# bf16 pack peephole extended with exact def-use checks: 1646 bit-trick packs now v_cvt_pk_bf16_f32 (+s_nop fill)
# speedup vs baseline: 1.0097x; 1.0044x over previous
; #define LAS __attribute__((address_space(3)))
; #define LDS_WAIT() asm volatile("s_waitcnt lgkmcnt(0)" ::: "memory")
; __device__ __forceinline__ unsigned pk2(float lo, float hi) { return f2bf(lo) | (f2bf(hi) << 16); }
;     ...
;         for (int i = 0; i < 16; ++i) { LAS float* d = scr + (4 * i + kr) * 65 + nq; d[0] = v[i].x; d[1] = v[i].y; d[2] = v[i].z; d[3] = v[i].w; }
;         LDS_WAIT(); asm volatile("" ::: "memory");
;         const int c8 = lane & 7; int d0 = n0;
;         if (ffnmap) { const int bj = n0 >= FFH ? 1 : 0, chn = n0 - FFH * bj; d0 = 256 * (chn >> 7) + 128 * bj + (chn & 127); }
; #pragma unroll
;         for (int j = 0; j < 8; ++j) { const int n = (lane >> 3) + 8 * j; const LAS float* sp = scr + (8 * c8) * 65 + n;
;             v4u o; o.x = pk2(sp[0 * 65], sp[1 * 65]); o.y = pk2(sp[2 * 65], sp[3 * 65]); o.z = pk2(sp[4 * 65], sp[5 * 65]); o.w = pk2(sp[6 * 65], sp[7 * 65]);
;             *(v4u*)(WT + (size_t)(d0 + n) * K + k0 + 8 * c8) = o; }
.LBB0_10:
	v_add_u32_e32 v3, 0x410, v81
	s_waitcnt vmcnt(0)
	ds_write2_b32 v81, v6, v7 offset1:1
	ds_write2_b32 v81, v8, v9 offset0:2 offset1:3
	ds_write2_b32 v3, v10, v11 offset1:1
	v_add_u32_e32 v3, 0x418, v81
	ds_write2_b32 v3, v12, v13 offset1:1
	v_add_u32_e32 v3, 0x820, v81
	ds_write2_b32 v3, v14, v15 offset1:1
	v_add_u32_e32 v3, 0x828, v81
	ds_write2_b32 v3, v16, v17 offset1:1
	v_add_u32_e32 v3, 0xc30, v81
	ds_write2_b32 v3, v18, v19 offset1:1
	v_add_u32_e32 v3, 0xc38, v81
	ds_write2_b32 v3, v20, v21 offset1:1
	v_add_u32_e32 v3, 0x1040, v81
	ds_write2_b32 v3, v22, v23 offset1:1
	v_add_u32_e32 v3, 0x1048, v81
	ds_write2_b32 v3, v24, v25 offset1:1
	v_add_u32_e32 v3, 0x1450, v81
	ds_write2_b32 v3, v26, v27 offset1:1
	v_add_u32_e32 v3, 0x1458, v81
	ds_write2_b32 v3, v28, v29 offset1:1
	v_add_u32_e32 v3, 0x1860, v81
	ds_write2_b32 v3, v30, v31 offset1:1
	v_add_u32_e32 v3, 0x1868, v81
	ds_write2_b32 v3, v32, v33 offset1:1
	v_add_u32_e32 v3, 0x1c70, v81
	ds_write2_b32 v3, v34, v35 offset1:1
	v_add_u32_e32 v3, 0x1c78, v81
	ds_write2_b32 v3, v36, v37 offset1:1
	v_add_u32_e32 v3, 0x2080, v81
	ds_write2_b32 v3, v38, v39 offset1:1
	v_add_u32_e32 v3, 0x2088, v81
	ds_write2_b32 v3, v40, v41 offset1:1
	v_add_u32_e32 v3, 0x2490, v81
	ds_write2_b32 v3, v42, v43 offset1:1
	v_add_u32_e32 v3, 0x2498, v81
	ds_write2_b32 v3, v44, v45 offset1:1
	v_add_u32_e32 v3, 0x28a0, v81
	ds_write2_b32 v3, v46, v47 offset1:1
	v_add_u32_e32 v3, 0x28a8, v81
	ds_write2_b32 v3, v48, v49 offset1:1
	v_add_u32_e32 v3, 0x2cb0, v81
	ds_write2_b32 v3, v50, v51 offset1:1
	v_add_u32_e32 v3, 0x2cb8, v81
	ds_write2_b32 v3, v52, v53 offset1:1
	v_add_u32_e32 v3, 0x30c0, v81
	ds_write2_b32 v3, v54, v55 offset1:1
	v_add_u32_e32 v3, 0x30c8, v81
	ds_write2_b32 v3, v56, v57 offset1:1
	v_add_u32_e32 v3, 0x34d0, v81
	ds_write2_b32 v3, v58, v59 offset1:1
	v_add_u32_e32 v3, 0x34d8, v81
	ds_write2_b32 v3, v60, v61 offset1:1
	v_add_u32_e32 v3, 0x38e0, v81
	ds_write2_b32 v3, v62, v63 offset1:1
	v_add_u32_e32 v3, 0x38e8, v81
	ds_write2_b32 v3, v64, v65 offset1:1
	v_add_u32_e32 v3, 0x3cf0, v81
	ds_write2_b32 v3, v66, v67 offset1:1
	v_add_u32_e32 v3, 0x3cf8, v81
	ds_write2_b32 v3, v68, v69 offset1:1
	s_waitcnt lgkmcnt(0)
	ds_read2_b32 v[12:13], v80 offset1:8
	ds_read2_b32 v[14:15], v80 offset0:65 offset1:73
	ds_read2_b32 v[16:17], v80 offset0:130 offset1:138
	ds_read2_b32 v[18:19], v80 offset0:195 offset1:203
	v_add_u32_e32 v30, 0x400, v80
	s_waitcnt lgkmcnt(3)
	s_nop 1
	s_waitcnt lgkmcnt(2)
	s_nop 0
	ds_read2_b32 v[20:21], v30 offset0:4 offset1:12
	s_nop 1
	ds_read2_b32 v[22:23], v30 offset0:69 offset1:77
	v_cvt_pk_bf16_f32 v8, v12, v14
	s_waitcnt lgkmcnt(3)
	s_nop 1
	s_waitcnt lgkmcnt(2)
	s_nop 0
	ds_read2_b32 v[24:25], v30 offset0:134 offset1:142
	s_nop 1
	ds_read2_b32 v[26:27], v30 offset0:199 offset1:207
	v_cvt_pk_bf16_f32 v9, v16, v18
	s_waitcnt lgkmcnt(3)
	s_nop 1
	s_waitcnt lgkmcnt(2)
	s_nop 2
	v_cvt_pk_bf16_f32 v10, v20, v22
	s_waitcnt lgkmcnt(1)
	s_nop 1
	s_waitcnt lgkmcnt(0)
	s_nop 2
	v_cvt_pk_bf16_f32 v11, v24, v26
	v_add_u32_e32 v6, s6, v79
	s_ashr_i32 s9, s8, 31
	v_ashrrev_i32_e32 v7, 31, v6
	v_bfe_u32 v3, v13, 16, 1
	v_lshl_add_u64 v[4:5], s[8:9], 1, v[72:73]
	v_lshlrev_b64 v[28:29], 12, v[6:7]
	v_add3_u32 v3, v13, v3, s13
	v_bfe_u32 v7, v15, 16, 1
	v_lshl_add_u64 v[28:29], v[4:5], 0, v[28:29]
	v_lshrrev_b32_e32 v3, 16, v3
	v_add3_u32 v7, v15, v7, s13
	global_store_dwordx4 v[28:29], v[8:11], off
	v_add_u32_e32 v12, 8, v6
	v_ashrrev_i32_e32 v13, 31, v12
	v_and_or_b32 v8, v7, s14, v3
	s_nop 4
	v_cvt_pk_bf16_f32 v9, v17, v19
	s_nop 4
	v_cvt_pk_bf16_f32 v10, v21, v23
	s_nop 4
	v_lshlrev_b64 v[12:13], 12, v[12:13]
	v_cvt_pk_bf16_f32 v11, v25, v27
	ds_read2_b32 v[14:15], v80 offset0:16 offset1:24
	v_lshl_add_u64 v[12:13], v[4:5], 0, v[12:13]
	global_store_dwordx4 v[12:13], v[8:11], off
	ds_read2_b32 v[12:13], v80 offset0:81 offset1:89
	ds_read2_b32 v[16:17], v80 offset0:146 offset1:154
	ds_read2_b32 v[18:19], v80 offset0:211 offset1:219
	s_waitcnt lgkmcnt(3)
	s_nop 1
	s_waitcnt lgkmcnt(2)
; #define LAS __attribute__((address_space(3)))
; #define LDS_WAIT() asm volatile("s_waitcnt lgkmcnt(0)" ::: "memory")
; __device__ __forceinline__ unsigned pk2(float lo, float hi) { return f2bf(lo) | (f2bf(hi) << 16); }
;     ...
;         for (int j = 0; j < 8; ++j) { const int n = (lane >> 3) + 8 * j; const LAS float* sp = scr + (8 * c8) * 65 + n;
;             v4u o; o.x = pk2(sp[0 * 65], sp[1 * 65]); o.y = pk2(sp[2 * 65], sp[3 * 65]); o.z = pk2(sp[4 * 65], sp[5 * 65]); o.w = pk2(sp[6 * 65], sp[7 * 65]);
;             *(v4u*)(WT + (size_t)(d0 + n) * K + k0 + 8 * c8) = o; }
;         LDS_WAIT(); asm volatile("" ::: "memory");
	s_nop 0
	ds_read2_b32 v[20:21], v30 offset0:20 offset1:28
	s_nop 1
	ds_read2_b32 v[22:23], v30 offset0:85 offset1:93
	v_cvt_pk_bf16_f32 v8, v14, v12
	s_waitcnt lgkmcnt(3)
	s_nop 1
	s_waitcnt lgkmcnt(2)
	s_nop 0
	ds_read2_b32 v[24:25], v30 offset0:150 offset1:158
	s_nop 1
	ds_read2_b32 v[26:27], v30 offset0:215 offset1:223
	v_cvt_pk_bf16_f32 v9, v16, v18
	s_waitcnt lgkmcnt(3)
	s_nop 1
	s_waitcnt lgkmcnt(2)
	s_nop 2
	v_cvt_pk_bf16_f32 v10, v20, v22
	s_waitcnt lgkmcnt(1)
	s_nop 1
	s_waitcnt lgkmcnt(0)
	s_nop 2
	v_add_u32_e32 v28, 16, v6
	v_cvt_pk_bf16_f32 v11, v24, v26
	v_ashrrev_i32_e32 v29, 31, v28
	v_bfe_u32 v3, v15, 16, 1
	v_lshlrev_b64 v[28:29], 12, v[28:29]
	v_add3_u32 v3, v15, v3, s13
	v_bfe_u32 v7, v13, 16, 1
	v_lshl_add_u64 v[28:29], v[4:5], 0, v[28:29]
	v_lshrrev_b32_e32 v3, 16, v3
	v_add3_u32 v7, v13, v7, s13
	global_store_dwordx4 v[28:29], v[8:11], off
	v_add_u32_e32 v12, 24, v6
	v_ashrrev_i32_e32 v13, 31, v12
	v_and_or_b32 v8, v7, s14, v3
	s_nop 4
	v_cvt_pk_bf16_f32 v9, v17, v19
	s_nop 4
	v_cvt_pk_bf16_f32 v10, v21, v23
	s_nop 4
	v_lshlrev_b64 v[12:13], 12, v[12:13]
	v_cvt_pk_bf16_f32 v11, v25, v27
	ds_read2_b32 v[14:15], v80 offset0:32 offset1:40
	v_lshl_add_u64 v[12:13], v[4:5], 0, v[12:13]
	global_store_dwordx4 v[12:13], v[8:11], off
	ds_read2_b32 v[12:13], v80 offset0:97 offset1:105
	ds_read2_b32 v[16:17], v80 offset0:162 offset1:170
	ds_read2_b32 v[18:19], v80 offset0:227 offset1:235
	s_waitcnt lgkmcnt(3)
	s_nop 1
	s_waitcnt lgkmcnt(2)
	s_nop 0
	ds_read2_b32 v[20:21], v30 offset0:36 offset1:44
	s_nop 1
	ds_read2_b32 v[22:23], v30 offset0:101 offset1:109
	v_cvt_pk_bf16_f32 v8, v14, v12
	s_waitcnt lgkmcnt(3)
	s_nop 1
	s_waitcnt lgkmcnt(2)
	s_nop 0
	ds_read2_b32 v[24:25], v30 offset0:166 offset1:174
	s_nop 1
	ds_read2_b32 v[26:27], v30 offset0:231 offset1:239
	v_cvt_pk_bf16_f32 v9, v16, v18
	s_waitcnt lgkmcnt(3)
	s_nop 1
	s_waitcnt lgkmcnt(2)
	s_nop 2
	v_cvt_pk_bf16_f32 v10, v20, v22
	s_waitcnt lgkmcnt(1)
	s_nop 1
	s_waitcnt lgkmcnt(0)
	s_nop 2
	v_add_u32_e32 v28, 32, v6
	v_cvt_pk_bf16_f32 v11, v24, v26
	v_ashrrev_i32_e32 v29, 31, v28
	v_bfe_u32 v3, v15, 16, 1
	v_lshlrev_b64 v[28:29], 12, v[28:29]
	v_add3_u32 v3, v15, v3, s13
	v_bfe_u32 v7, v13, 16, 1
	v_lshl_add_u64 v[28:29], v[4:5], 0, v[28:29]
	v_lshrrev_b32_e32 v3, 16, v3
	v_add3_u32 v7, v13, v7, s13
	global_store_dwordx4 v[28:29], v[8:11], off
	v_add_u32_e32 v12, 40, v6
	v_ashrrev_i32_e32 v13, 31, v12
	v_and_or_b32 v8, v7, s14, v3
	s_nop 4
	v_cvt_pk_bf16_f32 v9, v17, v19
	s_nop 4
	v_cvt_pk_bf16_f32 v10, v21, v23
	s_nop 4
	v_lshlrev_b64 v[12:13], 12, v[12:13]
	v_cvt_pk_bf16_f32 v11, v25, v27
	ds_read2_b32 v[14:15], v80 offset0:48 offset1:56
	v_lshl_add_u64 v[12:13], v[4:5], 0, v[12:13]
	global_store_dwordx4 v[12:13], v[8:11], off
	ds_read2_b32 v[12:13], v80 offset0:113 offset1:121
	ds_read2_b32 v[16:17], v80 offset0:178 offset1:186
	ds_read2_b32 v[18:19], v80 offset0:243 offset1:251
	s_waitcnt lgkmcnt(3)
	s_nop 1
	s_waitcnt lgkmcnt(2)
	s_nop 0
	ds_read2_b32 v[20:21], v30 offset0:52 offset1:60
	s_nop 1
	ds_read2_b32 v[22:23], v30 offset0:117 offset1:125
	v_cvt_pk_bf16_f32 v8, v14, v12
	s_waitcnt lgkmcnt(3)
	s_nop 1
	s_waitcnt lgkmcnt(2)
	s_nop 0
	ds_read2_b32 v[24:25], v30 offset0:182 offset1:190
	s_nop 1
	ds_read2_b32 v[26:27], v30 offset0:247 offset1:255
	v_cvt_pk_bf16_f32 v9, v16, v18
	s_waitcnt lgkmcnt(3)
	s_nop 1
	s_waitcnt lgkmcnt(2)
	s_nop 2
	v_cvt_pk_bf16_f32 v10, v20, v22
	s_waitcnt lgkmcnt(1)
	s_nop 1
	s_waitcnt lgkmcnt(0)
	s_nop 2
	v_add_u32_e32 v28, 48, v6
	v_cvt_pk_bf16_f32 v11, v24, v26
	v_ashrrev_i32_e32 v29, 31, v28
	s_nop 0
	v_lshlrev_b64 v[28:29], 12, v[28:29]
	s_nop 1
	v_lshl_add_u64 v[28:29], v[4:5], 0, v[28:29]
	s_nop 1
	global_store_dwordx4 v[28:29], v[8:11], off
	v_add_u32_e32 v6, 56, v6
	s_add_i32 s15, s15, s86
	v_cvt_pk_bf16_f32 v8, v15, v13
	s_nop 4
	v_cvt_pk_bf16_f32 v9, v17, v19
	s_nop 4
	v_cvt_pk_bf16_f32 v10, v21, v23
	s_nop 4
	v_cvt_pk_bf16_f32 v11, v25, v27
	v_ashrrev_i32_e32 v7, 31, v6
	v_lshlrev_b64 v[6:7], 12, v[6:7]
	v_lshl_add_u64 v[4:5], v[4:5], 0, v[6:7]
	global_store_dwordx4 v[4:5], v[8:11], off
	s_waitcnt lgkmcnt(0)
	s_add_i32 s0, s0, s1
	s_cmpk_lt_i32 s15, 0x1480
	s_cbranch_scc0 .LBB0_45

; #define LAS __attribute__((address_space(3)))
; #define LDS_WAIT() asm volatile("s_waitcnt lgkmcnt(0)" ::: "memory")
; __device__ __forceinline__ unsigned pk2(float lo, float hi) { return f2bf(lo) | (f2bf(hi) << 16); }
;     ...
;         for (int i = 0; i < 16; ++i) { LAS float* d = scr + (4 * i + kr) * 65 + nq; d[0] = v[i].x; d[1] = v[i].y; d[2] = v[i].z; d[3] = v[i].w; }
;         LDS_WAIT(); asm volatile("" ::: "memory");
;         const int c8 = lane & 7; int d0 = n0;
;         if (ffnmap) { const int bj = n0 >= FFH ? 1 : 0, chn = n0 - FFH * bj; d0 = 256 * (chn >> 7) + 128 * bj + (chn & 127); }
; #pragma unroll
;         for (int j = 0; j < 8; ++j) { const int n = (lane >> 3) + 8 * j; const LAS float* sp = scr + (8 * c8) * 65 + n;
;             v4u o; o.x = pk2(sp[0 * 65], sp[1 * 65]); o.y = pk2(sp[2 * 65], sp[3 * 65]); o.z = pk2(sp[4 * 65], sp[5 * 65]); o.w = pk2(sp[6 * 65], sp[7 * 65]);
;             *(v4u*)(WT + (size_t)(d0 + n) * K + k0 + 8 * c8) = o; }
.LBB0_47:
	s_or_b64 exec, exec, s[6:7]
	s_waitcnt vmcnt(0)
	ds_write2_b32 v77, v2, v3 offset1:1
	ds_write2_b32 v77, v4, v5 offset0:2 offset1:3
	v_add_u32_e32 v2, 0x410, v77
	ds_write2_b32 v2, v10, v11 offset1:1
	v_add_u32_e32 v2, 0x418, v77
	ds_write2_b32 v2, v12, v13 offset1:1
	v_add_u32_e32 v2, 0x820, v77
	ds_write2_b32 v2, v6, v7 offset1:1
	v_add_u32_e32 v2, 0x828, v77
	ds_write2_b32 v2, v8, v9 offset1:1
	v_add_u32_e32 v2, 0xc30, v77
	ds_write2_b32 v2, v18, v19 offset1:1
	v_add_u32_e32 v2, 0xc38, v77
	ds_write2_b32 v2, v20, v21 offset1:1
	v_add_u32_e32 v2, 0x1040, v77
	ds_write2_b32 v2, v14, v15 offset1:1
	v_add_u32_e32 v2, 0x1048, v77
	ds_write2_b32 v2, v16, v17 offset1:1
	v_add_u32_e32 v2, 0x1450, v77
	ds_write2_b32 v2, v26, v27 offset1:1
	v_add_u32_e32 v2, 0x1458, v77
	ds_write2_b32 v2, v28, v29 offset1:1
	v_add_u32_e32 v2, 0x1860, v77
	ds_write2_b32 v2, v22, v23 offset1:1
	v_add_u32_e32 v2, 0x1868, v77
	ds_write2_b32 v2, v24, v25 offset1:1
	v_add_u32_e32 v2, 0x1c70, v77
	ds_write2_b32 v2, v34, v35 offset1:1
	v_add_u32_e32 v2, 0x1c78, v77
	ds_write2_b32 v2, v36, v37 offset1:1
	v_add_u32_e32 v2, 0x2080, v77
	ds_write2_b32 v2, v30, v31 offset1:1
	v_add_u32_e32 v2, 0x2088, v77
	ds_write2_b32 v2, v32, v33 offset1:1
	v_add_u32_e32 v2, 0x2490, v77
	ds_write2_b32 v2, v42, v43 offset1:1
	v_add_u32_e32 v2, 0x2498, v77
	ds_write2_b32 v2, v44, v45 offset1:1
	v_add_u32_e32 v2, 0x28a0, v77
	ds_write2_b32 v2, v38, v39 offset1:1
	v_add_u32_e32 v2, 0x28a8, v77
	ds_write2_b32 v2, v40, v41 offset1:1
	v_add_u32_e32 v2, 0x2cb0, v77
	ds_write2_b32 v2, v50, v51 offset1:1
	v_add_u32_e32 v2, 0x2cb8, v77
	ds_write2_b32 v2, v52, v53 offset1:1
	v_add_u32_e32 v2, 0x30c0, v77
	ds_write2_b32 v2, v46, v47 offset1:1
	v_add_u32_e32 v2, 0x30c8, v77
	ds_write2_b32 v2, v48, v49 offset1:1
	v_add_u32_e32 v2, 0x34d0, v77
	ds_write2_b32 v2, v58, v59 offset1:1
	v_add_u32_e32 v2, 0x34d8, v77
	ds_write2_b32 v2, v60, v61 offset1:1
	v_add_u32_e32 v2, 0x38e0, v77
	ds_write2_b32 v2, v54, v55 offset1:1
	v_add_u32_e32 v2, 0x38e8, v77
	ds_write2_b32 v2, v56, v57 offset1:1
	v_add_u32_e32 v2, 0x3cf0, v77
	ds_write2_b32 v2, v62, v63 offset1:1
	v_add_u32_e32 v2, 0x3cf8, v77
	ds_write2_b32 v2, v64, v65 offset1:1
	s_waitcnt lgkmcnt(0)
	ds_read2_b32 v[10:11], v76 offset1:8
	ds_read2_b32 v[12:13], v76 offset0:65 offset1:73
	ds_read2_b32 v[14:15], v76 offset0:130 offset1:138
	ds_read2_b32 v[16:17], v76 offset0:195 offset1:203
	v_add_u32_e32 v28, 0x400, v76
	s_waitcnt lgkmcnt(3)
	s_nop 1
	s_waitcnt lgkmcnt(2)
	s_nop 0
	ds_read2_b32 v[18:19], v28 offset0:4 offset1:12
	s_nop 1
	ds_read2_b32 v[20:21], v28 offset0:69 offset1:77
	v_cvt_pk_bf16_f32 v6, v10, v12
	s_waitcnt lgkmcnt(3)
	s_nop 1
	s_waitcnt lgkmcnt(2)
	s_nop 0
	ds_read2_b32 v[22:23], v28 offset0:134 offset1:142
	s_nop 1
	ds_read2_b32 v[24:25], v28 offset0:199 offset1:207
	v_cvt_pk_bf16_f32 v7, v14, v16
	s_waitcnt lgkmcnt(3)
	s_nop 1
	s_waitcnt lgkmcnt(2)
	s_nop 2
	v_cvt_pk_bf16_f32 v8, v18, v20
	s_waitcnt lgkmcnt(1)
	s_nop 1
	s_waitcnt lgkmcnt(0)
	s_nop 2
	s_add_i32 s12, s12, s0
	v_cvt_pk_bf16_f32 v9, v22, v24
	v_add_u32_e32 v4, s12, v75
	s_ashr_i32 s3, s2, 31
	v_ashrrev_i32_e32 v5, 31, v4
	v_lshl_add_u64 v[2:3], s[2:3], 1, v[68:69]
	v_lshlrev_b64 v[26:27], 13, v[4:5]
	v_lshl_add_u64 v[26:27], v[2:3], 0, v[26:27]
	s_nop 0
	global_store_dwordx4 v[26:27], v[6:9], off
	s_nop 3
	v_cvt_pk_bf16_f32 v6, v11, v13
	s_nop 4
	v_cvt_pk_bf16_f32 v7, v15, v17
	s_nop 4
	v_cvt_pk_bf16_f32 v8, v19, v21
	s_nop 0
	v_add_u32_e32 v10, 8, v4
	s_nop 1
	v_ashrrev_i32_e32 v11, 31, v10
	s_nop 1
	v_lshlrev_b64 v[10:11], 13, v[10:11]
	v_cvt_pk_bf16_f32 v9, v23, v25
	ds_read2_b32 v[12:13], v76 offset0:16 offset1:24
	v_lshl_add_u64 v[10:11], v[2:3], 0, v[10:11]
	global_store_dwordx4 v[10:11], v[6:9], off
	ds_read2_b32 v[10:11], v76 offset0:81 offset1:89
	ds_read2_b32 v[14:15], v76 offset0:146 offset1:154
	ds_read2_b32 v[16:17], v76 offset0:211 offset1:219
	s_waitcnt lgkmcnt(3)
	s_nop 1
	s_waitcnt lgkmcnt(2)
; #define LAS __attribute__((address_space(3)))
; #define LDS_WAIT() asm volatile("s_waitcnt lgkmcnt(0)" ::: "memory")
; __device__ __forceinline__ unsigned pk2(float lo, float hi) { return f2bf(lo) | (f2bf(hi) << 16); }
;     ...
;         for (int j = 0; j < 8; ++j) { const int n = (lane >> 3) + 8 * j; const LAS float* sp = scr + (8 * c8) * 65 + n;
;             v4u o; o.x = pk2(sp[0 * 65], sp[1 * 65]); o.y = pk2(sp[2 * 65], sp[3 * 65]); o.z = pk2(sp[4 * 65], sp[5 * 65]); o.w = pk2(sp[6 * 65], sp[7 * 65]);
;             *(v4u*)(WT + (size_t)(d0 + n) * K + k0 + 8 * c8) = o; }
;         LDS_WAIT(); asm volatile("" ::: "memory");
	s_nop 0
	ds_read2_b32 v[18:19], v28 offset0:20 offset1:28
	s_nop 1
	ds_read2_b32 v[20:21], v28 offset0:85 offset1:93
	v_cvt_pk_bf16_f32 v6, v12, v10
	s_waitcnt lgkmcnt(3)
	s_nop 1
	s_waitcnt lgkmcnt(2)
	s_nop 0
	ds_read2_b32 v[22:23], v28 offset0:150 offset1:158
	s_nop 1
	ds_read2_b32 v[24:25], v28 offset0:215 offset1:223
	v_cvt_pk_bf16_f32 v7, v14, v16
	s_waitcnt lgkmcnt(3)
	s_nop 1
	s_waitcnt lgkmcnt(2)
	s_nop 2
	v_cvt_pk_bf16_f32 v8, v18, v20
	s_waitcnt lgkmcnt(1)
	s_nop 0
	v_add_u32_e32 v26, 16, v4
	s_nop 0
	s_waitcnt lgkmcnt(0)
	s_nop 0
	v_ashrrev_i32_e32 v27, 31, v26
	s_nop 1
	v_lshlrev_b64 v[26:27], 13, v[26:27]
	v_cvt_pk_bf16_f32 v9, v22, v24
	v_lshl_add_u64 v[26:27], v[2:3], 0, v[26:27]
	s_nop 0
	global_store_dwordx4 v[26:27], v[6:9], off
	s_nop 3
	v_cvt_pk_bf16_f32 v6, v13, v11
	s_nop 4
	v_cvt_pk_bf16_f32 v7, v15, v17
	s_nop 4
	v_cvt_pk_bf16_f32 v8, v19, v21
	s_nop 0
	v_add_u32_e32 v10, 24, v4
	s_nop 1
	v_ashrrev_i32_e32 v11, 31, v10
	s_nop 1
	v_lshlrev_b64 v[10:11], 13, v[10:11]
	v_cvt_pk_bf16_f32 v9, v23, v25
	ds_read2_b32 v[12:13], v76 offset0:32 offset1:40
	v_lshl_add_u64 v[10:11], v[2:3], 0, v[10:11]
	global_store_dwordx4 v[10:11], v[6:9], off
	ds_read2_b32 v[10:11], v76 offset0:97 offset1:105
	ds_read2_b32 v[14:15], v76 offset0:162 offset1:170
	ds_read2_b32 v[16:17], v76 offset0:227 offset1:235
	s_waitcnt lgkmcnt(3)
	s_nop 1
	s_waitcnt lgkmcnt(2)
	s_nop 0
	ds_read2_b32 v[18:19], v28 offset0:36 offset1:44
	s_nop 1
	ds_read2_b32 v[20:21], v28 offset0:101 offset1:109
	v_cvt_pk_bf16_f32 v6, v12, v10
	s_waitcnt lgkmcnt(3)
	s_nop 1
	s_waitcnt lgkmcnt(2)
	s_nop 0
	ds_read2_b32 v[22:23], v28 offset0:166 offset1:174
	s_nop 1
	ds_read2_b32 v[24:25], v28 offset0:231 offset1:239
	v_cvt_pk_bf16_f32 v7, v14, v16
	s_waitcnt lgkmcnt(3)
	s_nop 1
	s_waitcnt lgkmcnt(2)
	s_nop 2
	v_cvt_pk_bf16_f32 v8, v18, v20
	s_waitcnt lgkmcnt(1)
	s_nop 0
	v_add_u32_e32 v26, 32, v4
	s_nop 0
	s_waitcnt lgkmcnt(0)
	s_nop 0
	v_ashrrev_i32_e32 v27, 31, v26
	s_nop 1
	v_lshlrev_b64 v[26:27], 13, v[26:27]
	v_cvt_pk_bf16_f32 v9, v22, v24
	v_lshl_add_u64 v[26:27], v[2:3], 0, v[26:27]
	s_nop 0
	global_store_dwordx4 v[26:27], v[6:9], off
	s_nop 3
	v_cvt_pk_bf16_f32 v6, v13, v11
	s_nop 4
	v_cvt_pk_bf16_f32 v7, v15, v17
	s_nop 4
	v_cvt_pk_bf16_f32 v8, v19, v21
	s_nop 0
	v_add_u32_e32 v10, 40, v4
	s_nop 1
	v_ashrrev_i32_e32 v11, 31, v10
	s_nop 1
	v_lshlrev_b64 v[10:11], 13, v[10:11]
	v_cvt_pk_bf16_f32 v9, v23, v25
	ds_read2_b32 v[12:13], v76 offset0:48 offset1:56
	v_lshl_add_u64 v[10:11], v[2:3], 0, v[10:11]
	global_store_dwordx4 v[10:11], v[6:9], off
	ds_read2_b32 v[10:11], v76 offset0:113 offset1:121
	ds_read2_b32 v[14:15], v76 offset0:178 offset1:186
	ds_read2_b32 v[16:17], v76 offset0:243 offset1:251
	s_waitcnt lgkmcnt(3)
	s_nop 1
	s_waitcnt lgkmcnt(2)
	s_nop 0
	ds_read2_b32 v[18:19], v28 offset0:52 offset1:60
	s_nop 1
	ds_read2_b32 v[20:21], v28 offset0:117 offset1:125
	v_cvt_pk_bf16_f32 v6, v12, v10
	s_waitcnt lgkmcnt(3)
	s_nop 1
	s_waitcnt lgkmcnt(2)
	s_nop 0
	ds_read2_b32 v[22:23], v28 offset0:182 offset1:190
	s_nop 1
	ds_read2_b32 v[24:25], v28 offset0:247 offset1:255
	v_cvt_pk_bf16_f32 v7, v14, v16
	s_waitcnt lgkmcnt(3)
	s_nop 1
	s_waitcnt lgkmcnt(2)
	s_nop 2
	v_cvt_pk_bf16_f32 v8, v18, v20
	s_waitcnt lgkmcnt(1)
	s_nop 0
	v_add_u32_e32 v26, 48, v4
	s_nop 0
	s_waitcnt lgkmcnt(0)
	s_nop 0
	v_ashrrev_i32_e32 v27, 31, v26
	s_nop 1
	v_lshlrev_b64 v[26:27], 13, v[26:27]
	v_cvt_pk_bf16_f32 v9, v22, v24
	v_lshl_add_u64 v[26:27], v[2:3], 0, v[26:27]
	s_nop 0
	global_store_dwordx4 v[26:27], v[6:9], off
	s_nop 3
	v_cvt_pk_bf16_f32 v6, v13, v11
	s_nop 4
	v_cvt_pk_bf16_f32 v7, v15, v17
	s_nop 4
	v_cvt_pk_bf16_f32 v8, v19, v21
	s_nop 4
	v_add_u32_e32 v4, 56, v4
	v_cvt_pk_bf16_f32 v9, v23, v25
	v_ashrrev_i32_e32 v5, 31, v4
	v_lshlrev_b64 v[4:5], 13, v[4:5]
	v_lshl_add_u64 v[2:3], v[2:3], 0, v[4:5]
	global_store_dwordx4 v[2:3], v[6:9], off
	s_waitcnt lgkmcnt(0)
	s_add_i32 s11, s11, s86
	s_add_i32 s0, s0, s1
	s_cmpk_lt_i32 s11, 0x800
	s_cbranch_scc0 .LBB0_80

; #define LAS __attribute__((address_space(3)))
; #define LDS_WAIT() asm volatile("s_waitcnt lgkmcnt(0)" ::: "memory")
;     ...
;         if (gain) {
; #pragma unroll
;             for (int i = 0; i < 16; ++i) v[i] *= gain[k0 + 4 * i + kr]; }
; #pragma unroll
;         for (int i = 0; i < 16; ++i) { LAS float* d = scr + (4 * i + kr) * 65 + nq; d[0] = v[i].x; d[1] = v[i].y; d[2] = v[i].z; d[3] = v[i].w; }
;         LDS_WAIT(); asm volatile("" ::: "memory");
.LBB0_82:
	s_or_b64 exec, exec, s[8:9]
	v_lshl_add_u64 v[70:71], v[70:71], 2, s[2:3]
	global_load_dword v72, v[70:71], off
	global_load_dword v80, v[70:71], off offset:16
	global_load_dword v82, v[70:71], off offset:32
	global_load_dword v84, v[70:71], off offset:48
	global_load_dword v86, v[70:71], off offset:64
	global_load_dword v88, v[70:71], off offset:80
	global_load_dword v90, v[70:71], off offset:96
	global_load_dword v92, v[70:71], off offset:112
	global_load_dword v94, v[70:71], off offset:128
	global_load_dword v96, v[70:71], off offset:144
	global_load_dword v98, v[70:71], off offset:160
	global_load_dword v100, v[70:71], off offset:176
	global_load_dword v102, v[70:71], off offset:192
	global_load_dword v104, v[70:71], off offset:208
	s_nop 0
	global_load_dword v70, v[70:71], off offset:224
	v_lshl_add_u64 v[74:75], v[74:75], 2, s[2:3]
	global_load_dword v74, v[74:75], off
	v_add_u32_e32 v73, 0x418, v79
	v_add_u32_e32 v81, 0x828, v79
	v_add_u32_e32 v83, 0xc30, v79
	v_add_u32_e32 v85, 0xc38, v79
	v_add_u32_e32 v87, 0x1040, v79
	v_add_u32_e32 v89, 0x1048, v79
	v_add_u32_e32 v91, 0x1450, v79
	v_add_u32_e32 v93, 0x1458, v79
	v_add_u32_e32 v95, 0x1860, v79
	v_add_u32_e32 v97, 0x1868, v79
	v_add_u32_e32 v71, 0x410, v79
	v_add_u32_e32 v75, 0x820, v79
	v_add_u32_e32 v99, 0x1c70, v79
	v_add_u32_e32 v101, 0x1c78, v79
	v_add_u32_e32 v103, 0x2080, v79
	v_add_u32_e32 v105, 0x2088, v79
	s_add_i32 s14, s14, s0
	s_ashr_i32 s7, s6, 31
	s_add_i32 s13, s13, s86
	s_add_i32 s0, s0, s1
	s_cmpk_lt_i32 s13, 0x100
	s_waitcnt vmcnt(15)
	v_pk_mul_f32 v[2:3], v[2:3], v[72:73] op_sel_hi:[1,0]
	v_pk_mul_f32 v[4:5], v[4:5], v[72:73] op_sel_hi:[1,0]
	s_waitcnt vmcnt(14)
	v_pk_mul_f32 v[12:13], v[12:13], v[80:81] op_sel_hi:[1,0]
	v_pk_mul_f32 v[10:11], v[10:11], v[80:81] op_sel_hi:[1,0]
	s_waitcnt vmcnt(13)
	v_pk_mul_f32 v[8:9], v[8:9], v[82:83] op_sel_hi:[1,0]
	v_pk_mul_f32 v[6:7], v[6:7], v[82:83] op_sel_hi:[1,0]
	s_waitcnt vmcnt(12)
	v_pk_mul_f32 v[20:21], v[20:21], v[84:85] op_sel_hi:[1,0]
	v_pk_mul_f32 v[18:19], v[18:19], v[84:85] op_sel_hi:[1,0]
	s_waitcnt vmcnt(11)
	v_pk_mul_f32 v[16:17], v[16:17], v[86:87] op_sel_hi:[1,0]
	v_pk_mul_f32 v[14:15], v[14:15], v[86:87] op_sel_hi:[1,0]
	s_waitcnt vmcnt(10)
	v_pk_mul_f32 v[28:29], v[28:29], v[88:89] op_sel_hi:[1,0]
	v_pk_mul_f32 v[26:27], v[26:27], v[88:89] op_sel_hi:[1,0]
	s_waitcnt vmcnt(9)
	v_pk_mul_f32 v[24:25], v[24:25], v[90:91] op_sel_hi:[1,0]
	v_pk_mul_f32 v[22:23], v[22:23], v[90:91] op_sel_hi:[1,0]
	s_waitcnt vmcnt(8)
	v_pk_mul_f32 v[36:37], v[36:37], v[92:93] op_sel_hi:[1,0]
	v_pk_mul_f32 v[34:35], v[34:35], v[92:93] op_sel_hi:[1,0]
	s_waitcnt vmcnt(7)
	v_pk_mul_f32 v[32:33], v[32:33], v[94:95] op_sel_hi:[1,0]
	v_pk_mul_f32 v[30:31], v[30:31], v[94:95] op_sel_hi:[1,0]
	s_waitcnt vmcnt(6)
	v_pk_mul_f32 v[42:43], v[42:43], v[96:97] op_sel_hi:[1,0]
	ds_write2_b32 v79, v2, v3 offset1:1
	ds_write2_b32 v79, v4, v5 offset0:2 offset1:3
	ds_write2_b32 v71, v10, v11 offset1:1
	ds_write2_b32 v73, v12, v13 offset1:1
	ds_write2_b32 v75, v6, v7 offset1:1
	ds_write2_b32 v81, v8, v9 offset1:1
	ds_write2_b32 v83, v18, v19 offset1:1
	ds_write2_b32 v85, v20, v21 offset1:1
	ds_write2_b32 v87, v14, v15 offset1:1
	ds_write2_b32 v89, v16, v17 offset1:1
	ds_write2_b32 v91, v26, v27 offset1:1
	ds_write2_b32 v93, v28, v29 offset1:1
	ds_write2_b32 v95, v22, v23 offset1:1
	ds_write2_b32 v97, v24, v25 offset1:1
	ds_write2_b32 v99, v34, v35 offset1:1
	ds_write2_b32 v101, v36, v37 offset1:1
	ds_write2_b32 v103, v30, v31 offset1:1
	ds_write2_b32 v105, v32, v33 offset1:1
	v_add_u32_e32 v2, 0x2490, v79
	v_pk_mul_f32 v[44:45], v[44:45], v[96:97] op_sel_hi:[1,0]
	ds_write2_b32 v2, v42, v43 offset1:1
	v_add_u32_e32 v2, 0x2498, v79
	s_waitcnt vmcnt(5)
	v_pk_mul_f32 v[38:39], v[38:39], v[98:99] op_sel_hi:[1,0]
	ds_write2_b32 v2, v44, v45 offset1:1
	v_add_u32_e32 v2, 0x28a0, v79
	v_pk_mul_f32 v[40:41], v[40:41], v[98:99] op_sel_hi:[1,0]
	ds_write2_b32 v2, v38, v39 offset1:1
	v_add_u32_e32 v2, 0x28a8, v79
	s_waitcnt vmcnt(4)
	v_pk_mul_f32 v[50:51], v[50:51], v[100:101] op_sel_hi:[1,0]
	ds_write2_b32 v2, v40, v41 offset1:1
	v_add_u32_e32 v2, 0x2cb0, v79
	v_pk_mul_f32 v[52:53], v[52:53], v[100:101] op_sel_hi:[1,0]
	ds_write2_b32 v2, v50, v51 offset1:1
	v_add_u32_e32 v2, 0x2cb8, v79
	s_waitcnt vmcnt(3)
	v_pk_mul_f32 v[46:47], v[46:47], v[102:103] op_sel_hi:[1,0]
	ds_write2_b32 v2, v52, v53 offset1:1
	v_add_u32_e32 v2, 0x30c0, v79
	v_pk_mul_f32 v[48:49], v[48:49], v[102:103] op_sel_hi:[1,0]
	ds_write2_b32 v2, v46, v47 offset1:1
	v_add_u32_e32 v2, 0x30c8, v79
	s_waitcnt vmcnt(2)
	v_pk_mul_f32 v[58:59], v[58:59], v[104:105] op_sel_hi:[1,0]
	ds_write2_b32 v2, v48, v49 offset1:1
	v_add_u32_e32 v2, 0x34d0, v79
	v_pk_mul_f32 v[60:61], v[60:61], v[104:105] op_sel_hi:[1,0]
	ds_write2_b32 v2, v58, v59 offset1:1
	v_add_u32_e32 v2, 0x34d8, v79
	s_waitcnt vmcnt(1)
	v_pk_mul_f32 v[54:55], v[54:55], v[70:71] op_sel_hi:[1,0]
	ds_write2_b32 v2, v60, v61 offset1:1
	v_add_u32_e32 v2, 0x38e0, v79
	v_pk_mul_f32 v[56:57], v[56:57], v[70:71] op_sel_hi:[1,0]
	ds_write2_b32 v2, v54, v55 offset1:1
	v_add_u32_e32 v2, 0x38e8, v79
	s_waitcnt vmcnt(0)
	v_pk_mul_f32 v[62:63], v[62:63], v[74:75] op_sel_hi:[1,0]
	ds_write2_b32 v2, v56, v57 offset1:1
	v_add_u32_e32 v2, 0x3cf0, v79
	v_pk_mul_f32 v[64:65], v[64:65], v[74:75] op_sel_hi:[1,0]
	ds_write2_b32 v2, v62, v63 offset1:1
	v_add_u32_e32 v2, 0x3cf8, v79
	ds_write2_b32 v2, v64, v65 offset1:1
	s_waitcnt lgkmcnt(0)
; #define LAS __attribute__((address_space(3)))
; #define LDS_WAIT() asm volatile("s_waitcnt lgkmcnt(0)" ::: "memory")
; __device__ __forceinline__ unsigned pk2(float lo, float hi) { return f2bf(lo) | (f2bf(hi) << 16); }
;     ...
;         const int c8 = lane & 7; int d0 = n0;
;         if (ffnmap) { const int bj = n0 >= FFH ? 1 : 0, chn = n0 - FFH * bj; d0 = 256 * (chn >> 7) + 128 * bj + (chn & 127); }
; #pragma unroll
;         for (int j = 0; j < 8; ++j) { const int n = (lane >> 3) + 8 * j; const LAS float* sp = scr + (8 * c8) * 65 + n;
;             v4u o; o.x = pk2(sp[0 * 65], sp[1 * 65]); o.y = pk2(sp[2 * 65], sp[3 * 65]); o.z = pk2(sp[4 * 65], sp[5 * 65]); o.w = pk2(sp[6 * 65], sp[7 * 65]);
;             *(v4u*)(WT + (size_t)(d0 + n) * K + k0 + 8 * c8) = o; }
;         LDS_WAIT(); asm volatile("" ::: "memory");
	ds_read2_b32 v[10:11], v78 offset1:8
	ds_read2_b32 v[12:13], v78 offset0:65 offset1:73
	ds_read2_b32 v[14:15], v78 offset0:130 offset1:138
	ds_read2_b32 v[16:17], v78 offset0:195 offset1:203
	v_add_u32_e32 v28, 0x400, v78
	s_waitcnt lgkmcnt(3)
	s_nop 1
	s_waitcnt lgkmcnt(2)
	s_nop 0
	ds_read2_b32 v[18:19], v28 offset0:4 offset1:12
	s_nop 1
	ds_read2_b32 v[20:21], v28 offset0:69 offset1:77
	v_cvt_pk_bf16_f32 v6, v10, v12
	s_waitcnt lgkmcnt(3)
	s_nop 1
	s_waitcnt lgkmcnt(2)
	s_nop 0
	ds_read2_b32 v[22:23], v28 offset0:134 offset1:142
	s_nop 1
	ds_read2_b32 v[24:25], v28 offset0:199 offset1:207
	v_cvt_pk_bf16_f32 v7, v14, v16
	s_waitcnt lgkmcnt(3)
	s_nop 1
	s_waitcnt lgkmcnt(2)
	s_nop 2
	v_cvt_pk_bf16_f32 v8, v18, v20
	s_waitcnt lgkmcnt(1)
	s_nop 1
	s_waitcnt lgkmcnt(0)
	s_nop 2
	v_cvt_pk_bf16_f32 v9, v22, v24
	v_add_u32_e32 v4, s14, v77
	v_ashrrev_i32_e32 v5, 31, v4
	v_lshl_add_u64 v[2:3], s[6:7], 1, v[68:69]
	v_lshlrev_b64 v[26:27], 12, v[4:5]
	v_lshl_add_u64 v[26:27], v[2:3], 0, v[26:27]
	s_nop 0
	global_store_dwordx4 v[26:27], v[6:9], off
	s_nop 3
	v_cvt_pk_bf16_f32 v6, v11, v13
	s_nop 4
	v_cvt_pk_bf16_f32 v7, v15, v17
	s_nop 4
	v_cvt_pk_bf16_f32 v8, v19, v21
	s_nop 0
	v_add_u32_e32 v10, 8, v4
	s_nop 1
	v_ashrrev_i32_e32 v11, 31, v10
	s_nop 1
	v_lshlrev_b64 v[10:11], 12, v[10:11]
	v_cvt_pk_bf16_f32 v9, v23, v25
	ds_read2_b32 v[12:13], v78 offset0:16 offset1:24
	v_lshl_add_u64 v[10:11], v[2:3], 0, v[10:11]
	global_store_dwordx4 v[10:11], v[6:9], off
	ds_read2_b32 v[10:11], v78 offset0:81 offset1:89
	ds_read2_b32 v[14:15], v78 offset0:146 offset1:154
	ds_read2_b32 v[16:17], v78 offset0:211 offset1:219
	s_waitcnt lgkmcnt(3)
	s_nop 1
	s_waitcnt lgkmcnt(2)
	s_nop 0
	ds_read2_b32 v[18:19], v28 offset0:20 offset1:28
	s_nop 1
	ds_read2_b32 v[20:21], v28 offset0:85 offset1:93
	v_cvt_pk_bf16_f32 v6, v12, v10
	s_waitcnt lgkmcnt(3)
	s_nop 1
	s_waitcnt lgkmcnt(2)
	s_nop 0
	ds_read2_b32 v[22:23], v28 offset0:150 offset1:158
	s_nop 1
	ds_read2_b32 v[24:25], v28 offset0:215 offset1:223
	v_cvt_pk_bf16_f32 v7, v14, v16
	s_waitcnt lgkmcnt(3)
	s_nop 1
	s_waitcnt lgkmcnt(2)
	s_nop 2
	v_cvt_pk_bf16_f32 v8, v18, v20
	s_waitcnt lgkmcnt(1)
	s_nop 0
	v_add_u32_e32 v26, 16, v4
	s_nop 0
	s_waitcnt lgkmcnt(0)
	s_nop 0
	v_ashrrev_i32_e32 v27, 31, v26
	s_nop 1
	v_lshlrev_b64 v[26:27], 12, v[26:27]
	v_cvt_pk_bf16_f32 v9, v22, v24
	v_lshl_add_u64 v[26:27], v[2:3], 0, v[26:27]
	s_nop 0
	global_store_dwordx4 v[26:27], v[6:9], off
	s_nop 3
	v_cvt_pk_bf16_f32 v6, v13, v11
	s_nop 4
	v_cvt_pk_bf16_f32 v7, v15, v17
	s_nop 4
	v_cvt_pk_bf16_f32 v8, v19, v21
	s_nop 0
	v_add_u32_e32 v10, 24, v4
	s_nop 1
	v_ashrrev_i32_e32 v11, 31, v10
	s_nop 1
	v_lshlrev_b64 v[10:11], 12, v[10:11]
	v_cvt_pk_bf16_f32 v9, v23, v25
	ds_read2_b32 v[12:13], v78 offset0:32 offset1:40
	v_lshl_add_u64 v[10:11], v[2:3], 0, v[10:11]
	global_store_dwordx4 v[10:11], v[6:9], off
	ds_read2_b32 v[10:11], v78 offset0:97 offset1:105
	ds_read2_b32 v[14:15], v78 offset0:162 offset1:170
	ds_read2_b32 v[16:17], v78 offset0:227 offset1:235
	s_waitcnt lgkmcnt(3)
	s_nop 1
	s_waitcnt lgkmcnt(2)
	s_nop 0
	ds_read2_b32 v[18:19], v28 offset0:36 offset1:44
	s_nop 1
	ds_read2_b32 v[20:21], v28 offset0:101 offset1:109
	v_cvt_pk_bf16_f32 v6, v12, v10
	s_waitcnt lgkmcnt(3)
	s_nop 1
	s_waitcnt lgkmcnt(2)
	s_nop 0
	ds_read2_b32 v[22:23], v28 offset0:166 offset1:174
	s_nop 1
	ds_read2_b32 v[24:25], v28 offset0:231 offset1:239
	v_cvt_pk_bf16_f32 v7, v14, v16
	s_waitcnt lgkmcnt(3)
	s_nop 1
	s_waitcnt lgkmcnt(2)
	s_nop 2
	v_cvt_pk_bf16_f32 v8, v18, v20
	s_waitcnt lgkmcnt(1)
	s_nop 0
	v_add_u32_e32 v26, 32, v4
	s_nop 0
	s_waitcnt lgkmcnt(0)
	s_nop 0
	v_ashrrev_i32_e32 v27, 31, v26
	s_nop 1
	v_lshlrev_b64 v[26:27], 12, v[26:27]
	v_cvt_pk_bf16_f32 v9, v22, v24
	v_lshl_add_u64 v[26:27], v[2:3], 0, v[26:27]
	s_nop 0
	global_store_dwordx4 v[26:27], v[6:9], off
	s_nop 3
	v_cvt_pk_bf16_f32 v6, v13, v11
	s_nop 4
	v_cvt_pk_bf16_f32 v7, v15, v17
	s_nop 4
	v_cvt_pk_bf16_f32 v8, v19, v21
	s_nop 0
	v_add_u32_e32 v10, 40, v4
	s_nop 1
	v_ashrrev_i32_e32 v11, 31, v10
	s_nop 1
	v_lshlrev_b64 v[10:11], 12, v[10:11]
	v_cvt_pk_bf16_f32 v9, v23, v25
	ds_read2_b32 v[12:13], v78 offset0:48 offset1:56
	v_lshl_add_u64 v[10:11], v[2:3], 0, v[10:11]
	global_store_dwordx4 v[10:11], v[6:9], off
	ds_read2_b32 v[10:11], v78 offset0:113 offset1:121
	ds_read2_b32 v[14:15], v78 offset0:178 offset1:186
	ds_read2_b32 v[16:17], v78 offset0:243 offset1:251
	s_waitcnt lgkmcnt(3)
	s_nop 1
	s_waitcnt lgkmcnt(2)
	s_nop 0
	ds_read2_b32 v[18:19], v28 offset0:52 offset1:60
	s_nop 1
	ds_read2_b32 v[20:21], v28 offset0:117 offset1:125
	v_cvt_pk_bf16_f32 v6, v12, v10
	s_waitcnt lgkmcnt(3)
	s_nop 1
	s_waitcnt lgkmcnt(2)
	s_nop 0
	ds_read2_b32 v[22:23], v28 offset0:182 offset1:190
	s_nop 1
	ds_read2_b32 v[24:25], v28 offset0:247 offset1:255
	v_cvt_pk_bf16_f32 v7, v14, v16
	s_waitcnt lgkmcnt(3)
	s_nop 1
	s_waitcnt lgkmcnt(2)
	s_nop 2
	v_cvt_pk_bf16_f32 v8, v18, v20
	s_waitcnt lgkmcnt(1)
	s_nop 0
	v_add_u32_e32 v26, 48, v4
	s_nop 0
	s_waitcnt lgkmcnt(0)
	s_nop 0
	v_ashrrev_i32_e32 v27, 31, v26
	s_nop 1
	v_lshlrev_b64 v[26:27], 12, v[26:27]
	v_cvt_pk_bf16_f32 v9, v22, v24
	v_lshl_add_u64 v[26:27], v[2:3], 0, v[26:27]
	s_nop 0
	global_store_dwordx4 v[26:27], v[6:9], off
	s_nop 3
	v_cvt_pk_bf16_f32 v6, v13, v11
	s_nop 4
	v_cvt_pk_bf16_f32 v7, v15, v17
	s_nop 4
	v_cvt_pk_bf16_f32 v8, v19, v21
	s_nop 4
	v_add_u32_e32 v4, 56, v4
	v_cvt_pk_bf16_f32 v9, v23, v25
	v_ashrrev_i32_e32 v5, 31, v4
	v_lshlrev_b64 v[4:5], 12, v[4:5]
	v_lshl_add_u64 v[2:3], v[2:3], 0, v[4:5]
	global_store_dwordx4 v[2:3], v[6:9], off
	s_waitcnt lgkmcnt(0)
	s_cbranch_scc0 .LBB0_115

; #define LAS __attribute__((address_space(3)))
; #define LDS_WAIT() asm volatile("s_waitcnt lgkmcnt(0)" ::: "memory")
; __device__ __forceinline__ unsigned pk2(float lo, float hi) { return f2bf(lo) | (f2bf(hi) << 16); }
;     ...
;         for (int i = 0; i < 16; ++i) { LAS float* d = scr + (4 * i + kr) * 65 + nq; d[0] = v[i].x; d[1] = v[i].y; d[2] = v[i].z; d[3] = v[i].w; }
;         LDS_WAIT(); asm volatile("" ::: "memory");
;         const int c8 = lane & 7; int d0 = n0;
;         if (ffnmap) { const int bj = n0 >= FFH ? 1 : 0, chn = n0 - FFH * bj; d0 = 256 * (chn >> 7) + 128 * bj + (chn & 127); }
; #pragma unroll
;         for (int j = 0; j < 8; ++j) { const int n = (lane >> 3) + 8 * j; const LAS float* sp = scr + (8 * c8) * 65 + n;
;             v4u o; o.x = pk2(sp[0 * 65], sp[1 * 65]); o.y = pk2(sp[2 * 65], sp[3 * 65]); o.z = pk2(sp[4 * 65], sp[5 * 65]); o.w = pk2(sp[6 * 65], sp[7 * 65]);
;             *(v4u*)(WT + (size_t)(d0 + n) * K + k0 + 8 * c8) = o; }
.LBB0_117:
	s_or_b64 exec, exec, s[6:7]
	s_waitcnt vmcnt(0)
	ds_write2_b32 v77, v2, v3 offset1:1
	ds_write2_b32 v77, v4, v5 offset0:2 offset1:3
	v_add_u32_e32 v2, 0x410, v77
	ds_write2_b32 v2, v10, v11 offset1:1
	v_add_u32_e32 v2, 0x418, v77
	ds_write2_b32 v2, v12, v13 offset1:1
	v_add_u32_e32 v2, 0x820, v77
	ds_write2_b32 v2, v6, v7 offset1:1
	v_add_u32_e32 v2, 0x828, v77
	ds_write2_b32 v2, v8, v9 offset1:1
	v_add_u32_e32 v2, 0xc30, v77
	ds_write2_b32 v2, v18, v19 offset1:1
	v_add_u32_e32 v2, 0xc38, v77
	ds_write2_b32 v2, v20, v21 offset1:1
	v_add_u32_e32 v2, 0x1040, v77
	ds_write2_b32 v2, v14, v15 offset1:1
	v_add_u32_e32 v2, 0x1048, v77
	ds_write2_b32 v2, v16, v17 offset1:1
	v_add_u32_e32 v2, 0x1450, v77
	ds_write2_b32 v2, v26, v27 offset1:1
	v_add_u32_e32 v2, 0x1458, v77
	ds_write2_b32 v2, v28, v29 offset1:1
	v_add_u32_e32 v2, 0x1860, v77
	ds_write2_b32 v2, v22, v23 offset1:1
	v_add_u32_e32 v2, 0x1868, v77
	ds_write2_b32 v2, v24, v25 offset1:1
	v_add_u32_e32 v2, 0x1c70, v77
	ds_write2_b32 v2, v34, v35 offset1:1
	v_add_u32_e32 v2, 0x1c78, v77
	ds_write2_b32 v2, v36, v37 offset1:1
	v_add_u32_e32 v2, 0x2080, v77
	ds_write2_b32 v2, v30, v31 offset1:1
	v_add_u32_e32 v2, 0x2088, v77
	ds_write2_b32 v2, v32, v33 offset1:1
	v_add_u32_e32 v2, 0x2490, v77
	ds_write2_b32 v2, v42, v43 offset1:1
	v_add_u32_e32 v2, 0x2498, v77
	ds_write2_b32 v2, v44, v45 offset1:1
	v_add_u32_e32 v2, 0x28a0, v77
	ds_write2_b32 v2, v38, v39 offset1:1
	v_add_u32_e32 v2, 0x28a8, v77
	ds_write2_b32 v2, v40, v41 offset1:1
	v_add_u32_e32 v2, 0x2cb0, v77
	ds_write2_b32 v2, v50, v51 offset1:1
	v_add_u32_e32 v2, 0x2cb8, v77
	ds_write2_b32 v2, v52, v53 offset1:1
	v_add_u32_e32 v2, 0x30c0, v77
	ds_write2_b32 v2, v46, v47 offset1:1
	v_add_u32_e32 v2, 0x30c8, v77
	ds_write2_b32 v2, v48, v49 offset1:1
	v_add_u32_e32 v2, 0x34d0, v77
	ds_write2_b32 v2, v58, v59 offset1:1
	v_add_u32_e32 v2, 0x34d8, v77
	ds_write2_b32 v2, v60, v61 offset1:1
	v_add_u32_e32 v2, 0x38e0, v77
	ds_write2_b32 v2, v54, v55 offset1:1
	v_add_u32_e32 v2, 0x38e8, v77
	ds_write2_b32 v2, v56, v57 offset1:1
	v_add_u32_e32 v2, 0x3cf0, v77
	ds_write2_b32 v2, v62, v63 offset1:1
	v_add_u32_e32 v2, 0x3cf8, v77
	ds_write2_b32 v2, v64, v65 offset1:1
	s_waitcnt lgkmcnt(0)
	ds_read2_b32 v[10:11], v76 offset1:8
	ds_read2_b32 v[12:13], v76 offset0:65 offset1:73
	ds_read2_b32 v[14:15], v76 offset0:130 offset1:138
	ds_read2_b32 v[16:17], v76 offset0:195 offset1:203
	v_add_u32_e32 v28, 0x400, v76
	s_waitcnt lgkmcnt(3)
	s_nop 1
	s_waitcnt lgkmcnt(2)
	s_nop 0
	ds_read2_b32 v[18:19], v28 offset0:4 offset1:12
	s_nop 1
	ds_read2_b32 v[20:21], v28 offset0:69 offset1:77
	v_cvt_pk_bf16_f32 v6, v10, v12
	s_waitcnt lgkmcnt(3)
	s_nop 1
	s_waitcnt lgkmcnt(2)
	s_nop 0
	ds_read2_b32 v[22:23], v28 offset0:134 offset1:142
	s_nop 1
	ds_read2_b32 v[24:25], v28 offset0:199 offset1:207
	v_cvt_pk_bf16_f32 v7, v14, v16
	s_waitcnt lgkmcnt(3)
	s_nop 1
	s_waitcnt lgkmcnt(2)
	s_nop 2
	v_cvt_pk_bf16_f32 v8, v18, v20
	s_waitcnt lgkmcnt(1)
	s_nop 1
	s_waitcnt lgkmcnt(0)
	s_nop 2
	s_add_i32 s15, s15, s10
	v_cvt_pk_bf16_f32 v9, v22, v24
	v_add_u32_e32 v4, s15, v75
	s_ashr_i32 s3, s2, 31
	v_ashrrev_i32_e32 v5, 31, v4
	v_lshl_add_u64 v[2:3], s[2:3], 1, v[68:69]
	v_lshlrev_b64 v[26:27], 12, v[4:5]
	v_lshl_add_u64 v[26:27], v[2:3], 0, v[26:27]
	s_nop 0
	global_store_dwordx4 v[26:27], v[6:9], off
	s_nop 3
	v_cvt_pk_bf16_f32 v6, v11, v13
	s_nop 4
	v_cvt_pk_bf16_f32 v7, v15, v17
	s_nop 4
	v_cvt_pk_bf16_f32 v8, v19, v21
	s_nop 0
	v_add_u32_e32 v10, 8, v4
	s_nop 1
	v_ashrrev_i32_e32 v11, 31, v10
	s_nop 1
	v_lshlrev_b64 v[10:11], 12, v[10:11]
	v_cvt_pk_bf16_f32 v9, v23, v25
	ds_read2_b32 v[12:13], v76 offset0:16 offset1:24
	v_lshl_add_u64 v[10:11], v[2:3], 0, v[10:11]
	global_store_dwordx4 v[10:11], v[6:9], off
	ds_read2_b32 v[10:11], v76 offset0:81 offset1:89
	ds_read2_b32 v[14:15], v76 offset0:146 offset1:154
	ds_read2_b32 v[16:17], v76 offset0:211 offset1:219
	s_waitcnt lgkmcnt(3)
	s_nop 1
	s_waitcnt lgkmcnt(2)
; #define LAS __attribute__((address_space(3)))
; #define LDS_WAIT() asm volatile("s_waitcnt lgkmcnt(0)" ::: "memory")
; __device__ __forceinline__ unsigned pk2(float lo, float hi) { return f2bf(lo) | (f2bf(hi) << 16); }
;     ...
;         for (int j = 0; j < 8; ++j) { const int n = (lane >> 3) + 8 * j; const LAS float* sp = scr + (8 * c8) * 65 + n;
;             v4u o; o.x = pk2(sp[0 * 65], sp[1 * 65]); o.y = pk2(sp[2 * 65], sp[3 * 65]); o.z = pk2(sp[4 * 65], sp[5 * 65]); o.w = pk2(sp[6 * 65], sp[7 * 65]);
;             *(v4u*)(WT + (size_t)(d0 + n) * K + k0 + 8 * c8) = o; }
;         LDS_WAIT(); asm volatile("" ::: "memory");
	s_nop 0
	ds_read2_b32 v[18:19], v28 offset0:20 offset1:28
	s_nop 1
	ds_read2_b32 v[20:21], v28 offset0:85 offset1:93
	v_cvt_pk_bf16_f32 v6, v12, v10
	s_waitcnt lgkmcnt(3)
	s_nop 1
	s_waitcnt lgkmcnt(2)
	s_nop 0
	ds_read2_b32 v[22:23], v28 offset0:150 offset1:158
	s_nop 1
	ds_read2_b32 v[24:25], v28 offset0:215 offset1:223
	v_cvt_pk_bf16_f32 v7, v14, v16
	s_waitcnt lgkmcnt(3)
	s_nop 1
	s_waitcnt lgkmcnt(2)
	s_nop 2
	v_cvt_pk_bf16_f32 v8, v18, v20
	s_waitcnt lgkmcnt(1)
	s_nop 0
	v_add_u32_e32 v26, 16, v4
	s_nop 0
	s_waitcnt lgkmcnt(0)
	s_nop 0
	v_ashrrev_i32_e32 v27, 31, v26
	s_nop 1
	v_lshlrev_b64 v[26:27], 12, v[26:27]
	v_cvt_pk_bf16_f32 v9, v22, v24
	v_lshl_add_u64 v[26:27], v[2:3], 0, v[26:27]
	s_nop 0
	global_store_dwordx4 v[26:27], v[6:9], off
	s_nop 3
	v_cvt_pk_bf16_f32 v6, v13, v11
	s_nop 4
	v_cvt_pk_bf16_f32 v7, v15, v17
	s_nop 4
	v_cvt_pk_bf16_f32 v8, v19, v21
	s_nop 0
	v_add_u32_e32 v10, 24, v4
	s_nop 1
	v_ashrrev_i32_e32 v11, 31, v10
	s_nop 1
	v_lshlrev_b64 v[10:11], 12, v[10:11]
	v_cvt_pk_bf16_f32 v9, v23, v25
	ds_read2_b32 v[12:13], v76 offset0:32 offset1:40
	v_lshl_add_u64 v[10:11], v[2:3], 0, v[10:11]
	global_store_dwordx4 v[10:11], v[6:9], off
	ds_read2_b32 v[10:11], v76 offset0:97 offset1:105
	ds_read2_b32 v[14:15], v76 offset0:162 offset1:170
	ds_read2_b32 v[16:17], v76 offset0:227 offset1:235
	s_waitcnt lgkmcnt(3)
	s_nop 1
	s_waitcnt lgkmcnt(2)
	s_nop 0
	ds_read2_b32 v[18:19], v28 offset0:36 offset1:44
	s_nop 1
	ds_read2_b32 v[20:21], v28 offset0:101 offset1:109
	v_cvt_pk_bf16_f32 v6, v12, v10
	s_waitcnt lgkmcnt(3)
	s_nop 1
	s_waitcnt lgkmcnt(2)
	s_nop 0
	ds_read2_b32 v[22:23], v28 offset0:166 offset1:174
	s_nop 1
	ds_read2_b32 v[24:25], v28 offset0:231 offset1:239
	v_cvt_pk_bf16_f32 v7, v14, v16
	s_waitcnt lgkmcnt(3)
	s_nop 1
	s_waitcnt lgkmcnt(2)
	s_nop 2
	v_cvt_pk_bf16_f32 v8, v18, v20
	s_waitcnt lgkmcnt(1)
	s_nop 0
	v_add_u32_e32 v26, 32, v4
	s_nop 0
	s_waitcnt lgkmcnt(0)
	s_nop 0
	v_ashrrev_i32_e32 v27, 31, v26
	s_nop 1
	v_lshlrev_b64 v[26:27], 12, v[26:27]
	v_cvt_pk_bf16_f32 v9, v22, v24
	v_lshl_add_u64 v[26:27], v[2:3], 0, v[26:27]
	s_nop 0
	global_store_dwordx4 v[26:27], v[6:9], off
	s_nop 3
	v_cvt_pk_bf16_f32 v6, v13, v11
	s_nop 4
	v_cvt_pk_bf16_f32 v7, v15, v17
	s_nop 4
	v_cvt_pk_bf16_f32 v8, v19, v21
	s_nop 0
	v_add_u32_e32 v10, 40, v4
	s_nop 1
	v_ashrrev_i32_e32 v11, 31, v10
	s_nop 1
	v_lshlrev_b64 v[10:11], 12, v[10:11]
	v_cvt_pk_bf16_f32 v9, v23, v25
	ds_read2_b32 v[12:13], v76 offset0:48 offset1:56
	v_lshl_add_u64 v[10:11], v[2:3], 0, v[10:11]
	global_store_dwordx4 v[10:11], v[6:9], off
	ds_read2_b32 v[10:11], v76 offset0:113 offset1:121
	ds_read2_b32 v[14:15], v76 offset0:178 offset1:186
	ds_read2_b32 v[16:17], v76 offset0:243 offset1:251
	s_waitcnt lgkmcnt(3)
	s_nop 1
	s_waitcnt lgkmcnt(2)
	s_nop 0
	ds_read2_b32 v[18:19], v28 offset0:52 offset1:60
	s_nop 1
	ds_read2_b32 v[20:21], v28 offset0:117 offset1:125
	v_cvt_pk_bf16_f32 v6, v12, v10
	s_waitcnt lgkmcnt(3)
	s_nop 1
	s_waitcnt lgkmcnt(2)
	s_nop 0
	ds_read2_b32 v[22:23], v28 offset0:182 offset1:190
	s_nop 1
	ds_read2_b32 v[24:25], v28 offset0:247 offset1:255
	v_cvt_pk_bf16_f32 v7, v14, v16
	s_waitcnt lgkmcnt(3)
	s_nop 1
	s_waitcnt lgkmcnt(2)
	s_nop 2
	v_cvt_pk_bf16_f32 v8, v18, v20
	s_waitcnt lgkmcnt(1)
	s_nop 0
	v_add_u32_e32 v26, 48, v4
	s_nop 0
	s_waitcnt lgkmcnt(0)
	s_nop 0
	v_ashrrev_i32_e32 v27, 31, v26
	s_nop 1
	v_lshlrev_b64 v[26:27], 12, v[26:27]
	v_cvt_pk_bf16_f32 v9, v22, v24
	v_lshl_add_u64 v[26:27], v[2:3], 0, v[26:27]
	s_nop 0
	global_store_dwordx4 v[26:27], v[6:9], off
	s_nop 3
	v_cvt_pk_bf16_f32 v6, v13, v11
	s_nop 4
	v_cvt_pk_bf16_f32 v7, v15, v17
	s_nop 4
	v_cvt_pk_bf16_f32 v8, v19, v21
	s_nop 4
	v_add_u32_e32 v4, 56, v4
	v_cvt_pk_bf16_f32 v9, v23, v25
	v_ashrrev_i32_e32 v5, 31, v4
	v_lshlrev_b64 v[4:5], 12, v[4:5]
	v_lshl_add_u64 v[2:3], v[2:3], 0, v[4:5]
	global_store_dwordx4 v[2:3], v[6:9], off
	s_waitcnt lgkmcnt(0)
	s_add_i32 s9, s9, s86
	s_add_i32 s10, s10, s11
	s_cmpk_lt_i32 s9, 0x200
	s_cbranch_scc0 .LBB0_150

; #define LAS __attribute__((address_space(3)))
; #define LDS_WAIT() asm volatile("s_waitcnt lgkmcnt(0)" ::: "memory")
; __device__ __forceinline__ unsigned pk2(float lo, float hi) { return f2bf(lo) | (f2bf(hi) << 16); }
;     ...
;         for (int i = 0; i < 16; ++i) { LAS float* d = scr + (4 * i + kr) * 65 + nq; d[0] = v[i].x; d[1] = v[i].y; d[2] = v[i].z; d[3] = v[i].w; }
;         LDS_WAIT(); asm volatile("" ::: "memory");
;         const int c8 = lane & 7; int d0 = n0;
;         if (ffnmap) { const int bj = n0 >= FFH ? 1 : 0, chn = n0 - FFH * bj; d0 = 256 * (chn >> 7) + 128 * bj + (chn & 127); }
; #pragma unroll
;         for (int j = 0; j < 8; ++j) { const int n = (lane >> 3) + 8 * j; const LAS float* sp = scr + (8 * c8) * 65 + n;
;             v4u o; o.x = pk2(sp[0 * 65], sp[1 * 65]); o.y = pk2(sp[2 * 65], sp[3 * 65]); o.z = pk2(sp[4 * 65], sp[5 * 65]); o.w = pk2(sp[6 * 65], sp[7 * 65]);
;             *(v4u*)(WT + (size_t)(d0 + n) * K + k0 + 8 * c8) = o; }
.LBB0_152:
	s_or_b64 exec, exec, s[6:7]
	s_waitcnt vmcnt(0)
	ds_write2_b32 v77, v2, v3 offset1:1
	ds_write2_b32 v77, v4, v5 offset0:2 offset1:3
	v_add_u32_e32 v2, 0x410, v77
	ds_write2_b32 v2, v10, v11 offset1:1
	v_add_u32_e32 v2, 0x418, v77
	ds_write2_b32 v2, v12, v13 offset1:1
	v_add_u32_e32 v2, 0x820, v77
	ds_write2_b32 v2, v6, v7 offset1:1
	v_add_u32_e32 v2, 0x828, v77
	ds_write2_b32 v2, v8, v9 offset1:1
	v_add_u32_e32 v2, 0xc30, v77
	ds_write2_b32 v2, v18, v19 offset1:1
	v_add_u32_e32 v2, 0xc38, v77
	ds_write2_b32 v2, v20, v21 offset1:1
	v_add_u32_e32 v2, 0x1040, v77
	ds_write2_b32 v2, v14, v15 offset1:1
	v_add_u32_e32 v2, 0x1048, v77
	ds_write2_b32 v2, v16, v17 offset1:1
	v_add_u32_e32 v2, 0x1450, v77
	ds_write2_b32 v2, v26, v27 offset1:1
	v_add_u32_e32 v2, 0x1458, v77
	ds_write2_b32 v2, v28, v29 offset1:1
	v_add_u32_e32 v2, 0x1860, v77
	ds_write2_b32 v2, v22, v23 offset1:1
	v_add_u32_e32 v2, 0x1868, v77
	ds_write2_b32 v2, v24, v25 offset1:1
	v_add_u32_e32 v2, 0x1c70, v77
	ds_write2_b32 v2, v34, v35 offset1:1
	v_add_u32_e32 v2, 0x1c78, v77
	ds_write2_b32 v2, v36, v37 offset1:1
	v_add_u32_e32 v2, 0x2080, v77
	ds_write2_b32 v2, v30, v31 offset1:1
	v_add_u32_e32 v2, 0x2088, v77
	ds_write2_b32 v2, v32, v33 offset1:1
	v_add_u32_e32 v2, 0x2490, v77
	ds_write2_b32 v2, v42, v43 offset1:1
	v_add_u32_e32 v2, 0x2498, v77
	ds_write2_b32 v2, v44, v45 offset1:1
	v_add_u32_e32 v2, 0x28a0, v77
	ds_write2_b32 v2, v38, v39 offset1:1
	v_add_u32_e32 v2, 0x28a8, v77
	ds_write2_b32 v2, v40, v41 offset1:1
	v_add_u32_e32 v2, 0x2cb0, v77
	ds_write2_b32 v2, v50, v51 offset1:1
	v_add_u32_e32 v2, 0x2cb8, v77
	ds_write2_b32 v2, v52, v53 offset1:1
	v_add_u32_e32 v2, 0x30c0, v77
	ds_write2_b32 v2, v46, v47 offset1:1
	v_add_u32_e32 v2, 0x30c8, v77
	ds_write2_b32 v2, v48, v49 offset1:1
	v_add_u32_e32 v2, 0x34d0, v77
	ds_write2_b32 v2, v58, v59 offset1:1
	v_add_u32_e32 v2, 0x34d8, v77
	ds_write2_b32 v2, v60, v61 offset1:1
	v_add_u32_e32 v2, 0x38e0, v77
	ds_write2_b32 v2, v54, v55 offset1:1
	v_add_u32_e32 v2, 0x38e8, v77
	ds_write2_b32 v2, v56, v57 offset1:1
	v_add_u32_e32 v2, 0x3cf0, v77
	ds_write2_b32 v2, v62, v63 offset1:1
	v_add_u32_e32 v2, 0x3cf8, v77
	ds_write2_b32 v2, v64, v65 offset1:1
	s_waitcnt lgkmcnt(0)
	ds_read2_b32 v[10:11], v76 offset1:8
	ds_read2_b32 v[12:13], v76 offset0:65 offset1:73
	ds_read2_b32 v[14:15], v76 offset0:130 offset1:138
	ds_read2_b32 v[16:17], v76 offset0:195 offset1:203
	v_add_u32_e32 v28, 0x400, v76
	s_waitcnt lgkmcnt(3)
	s_nop 1
	s_waitcnt lgkmcnt(2)
	s_nop 0
	ds_read2_b32 v[18:19], v28 offset0:4 offset1:12
	s_nop 1
	ds_read2_b32 v[20:21], v28 offset0:69 offset1:77
	v_cvt_pk_bf16_f32 v6, v10, v12
	s_waitcnt lgkmcnt(3)
	s_nop 1
	s_waitcnt lgkmcnt(2)
	s_nop 0
	ds_read2_b32 v[22:23], v28 offset0:134 offset1:142
	s_nop 1
	ds_read2_b32 v[24:25], v28 offset0:199 offset1:207
	v_cvt_pk_bf16_f32 v7, v14, v16
	s_waitcnt lgkmcnt(3)
	s_nop 1
	s_waitcnt lgkmcnt(2)
	s_nop 2
	v_cvt_pk_bf16_f32 v8, v18, v20
	s_waitcnt lgkmcnt(1)
	s_nop 1
	s_waitcnt lgkmcnt(0)
	s_nop 2
	s_add_i32 s15, s15, s10
	v_cvt_pk_bf16_f32 v9, v22, v24
	v_add_u32_e32 v4, s15, v75
	s_ashr_i32 s3, s2, 31
	v_ashrrev_i32_e32 v5, 31, v4
	v_lshl_add_u64 v[2:3], s[2:3], 1, v[68:69]
	v_lshlrev_b64 v[26:27], 10, v[4:5]
	v_lshl_add_u64 v[26:27], v[2:3], 0, v[26:27]
	s_nop 0
	global_store_dwordx4 v[26:27], v[6:9], off
	s_nop 3
	v_cvt_pk_bf16_f32 v6, v11, v13
	s_nop 4
	v_cvt_pk_bf16_f32 v7, v15, v17
	s_nop 4
	v_cvt_pk_bf16_f32 v8, v19, v21
	s_nop 0
	v_add_u32_e32 v10, 8, v4
	s_nop 1
	v_ashrrev_i32_e32 v11, 31, v10
	s_nop 1
	v_lshlrev_b64 v[10:11], 10, v[10:11]
	v_cvt_pk_bf16_f32 v9, v23, v25
	ds_read2_b32 v[12:13], v76 offset0:16 offset1:24
	v_lshl_add_u64 v[10:11], v[2:3], 0, v[10:11]
	global_store_dwordx4 v[10:11], v[6:9], off
	ds_read2_b32 v[10:11], v76 offset0:81 offset1:89
	ds_read2_b32 v[14:15], v76 offset0:146 offset1:154
	ds_read2_b32 v[16:17], v76 offset0:211 offset1:219
	s_waitcnt lgkmcnt(3)
	s_nop 1
	s_waitcnt lgkmcnt(2)
; #define LAS __attribute__((address_space(3)))
; #define LDS_WAIT() asm volatile("s_waitcnt lgkmcnt(0)" ::: "memory")
; __device__ __forceinline__ unsigned pk2(float lo, float hi) { return f2bf(lo) | (f2bf(hi) << 16); }
;     ...
;         for (int j = 0; j < 8; ++j) { const int n = (lane >> 3) + 8 * j; const LAS float* sp = scr + (8 * c8) * 65 + n;
;             v4u o; o.x = pk2(sp[0 * 65], sp[1 * 65]); o.y = pk2(sp[2 * 65], sp[3 * 65]); o.z = pk2(sp[4 * 65], sp[5 * 65]); o.w = pk2(sp[6 * 65], sp[7 * 65]);
;             *(v4u*)(WT + (size_t)(d0 + n) * K + k0 + 8 * c8) = o; }
;         LDS_WAIT(); asm volatile("" ::: "memory");
	s_nop 0
	ds_read2_b32 v[18:19], v28 offset0:20 offset1:28
	s_nop 1
	ds_read2_b32 v[20:21], v28 offset0:85 offset1:93
	v_cvt_pk_bf16_f32 v6, v12, v10
	s_waitcnt lgkmcnt(3)
	s_nop 1
	s_waitcnt lgkmcnt(2)
	s_nop 0
	ds_read2_b32 v[22:23], v28 offset0:150 offset1:158
	s_nop 1
	ds_read2_b32 v[24:25], v28 offset0:215 offset1:223
	v_cvt_pk_bf16_f32 v7, v14, v16
	s_waitcnt lgkmcnt(3)
	s_nop 1
	s_waitcnt lgkmcnt(2)
	s_nop 2
	v_cvt_pk_bf16_f32 v8, v18, v20
	s_waitcnt lgkmcnt(1)
	s_nop 0
	v_add_u32_e32 v26, 16, v4
	s_nop 0
	s_waitcnt lgkmcnt(0)
	s_nop 0
	v_ashrrev_i32_e32 v27, 31, v26
	s_nop 1
	v_lshlrev_b64 v[26:27], 10, v[26:27]
	v_cvt_pk_bf16_f32 v9, v22, v24
	v_lshl_add_u64 v[26:27], v[2:3], 0, v[26:27]
	s_nop 0
	global_store_dwordx4 v[26:27], v[6:9], off
	s_nop 3
	v_cvt_pk_bf16_f32 v6, v13, v11
	s_nop 4
	v_cvt_pk_bf16_f32 v7, v15, v17
	s_nop 4
	v_cvt_pk_bf16_f32 v8, v19, v21
	s_nop 0
	v_add_u32_e32 v10, 24, v4
	s_nop 1
	v_ashrrev_i32_e32 v11, 31, v10
	s_nop 1
	v_lshlrev_b64 v[10:11], 10, v[10:11]
	v_cvt_pk_bf16_f32 v9, v23, v25
	ds_read2_b32 v[12:13], v76 offset0:32 offset1:40
	v_lshl_add_u64 v[10:11], v[2:3], 0, v[10:11]
	global_store_dwordx4 v[10:11], v[6:9], off
	ds_read2_b32 v[10:11], v76 offset0:97 offset1:105
	ds_read2_b32 v[14:15], v76 offset0:162 offset1:170
	ds_read2_b32 v[16:17], v76 offset0:227 offset1:235
	s_waitcnt lgkmcnt(3)
	s_nop 1
	s_waitcnt lgkmcnt(2)
	s_nop 0
	ds_read2_b32 v[18:19], v28 offset0:36 offset1:44
	s_nop 1
	ds_read2_b32 v[20:21], v28 offset0:101 offset1:109
	v_cvt_pk_bf16_f32 v6, v12, v10
	s_waitcnt lgkmcnt(3)
	s_nop 1
	s_waitcnt lgkmcnt(2)
	s_nop 0
	ds_read2_b32 v[22:23], v28 offset0:166 offset1:174
	s_nop 1
	ds_read2_b32 v[24:25], v28 offset0:231 offset1:239
	v_cvt_pk_bf16_f32 v7, v14, v16
	s_waitcnt lgkmcnt(3)
	s_nop 1
	s_waitcnt lgkmcnt(2)
	s_nop 2
	v_cvt_pk_bf16_f32 v8, v18, v20
	s_waitcnt lgkmcnt(1)
	s_nop 0
	v_add_u32_e32 v26, 32, v4
	s_nop 0
	s_waitcnt lgkmcnt(0)
	s_nop 0
	v_ashrrev_i32_e32 v27, 31, v26
	s_nop 1
	v_lshlrev_b64 v[26:27], 10, v[26:27]
	v_cvt_pk_bf16_f32 v9, v22, v24
	v_lshl_add_u64 v[26:27], v[2:3], 0, v[26:27]
	s_nop 0
	global_store_dwordx4 v[26:27], v[6:9], off
	s_nop 3
	v_cvt_pk_bf16_f32 v6, v13, v11
	s_nop 4
	v_cvt_pk_bf16_f32 v7, v15, v17
	s_nop 4
	v_cvt_pk_bf16_f32 v8, v19, v21
	s_nop 0
	v_add_u32_e32 v10, 40, v4
	s_nop 1
	v_ashrrev_i32_e32 v11, 31, v10
	s_nop 1
	v_lshlrev_b64 v[10:11], 10, v[10:11]
	v_cvt_pk_bf16_f32 v9, v23, v25
	ds_read2_b32 v[12:13], v76 offset0:48 offset1:56
	v_lshl_add_u64 v[10:11], v[2:3], 0, v[10:11]
	global_store_dwordx4 v[10:11], v[6:9], off
	ds_read2_b32 v[10:11], v76 offset0:113 offset1:121
	ds_read2_b32 v[14:15], v76 offset0:178 offset1:186
	ds_read2_b32 v[16:17], v76 offset0:243 offset1:251
	s_waitcnt lgkmcnt(3)
	s_nop 1
	s_waitcnt lgkmcnt(2)
	s_nop 0
	ds_read2_b32 v[18:19], v28 offset0:52 offset1:60
	s_nop 1
	ds_read2_b32 v[20:21], v28 offset0:117 offset1:125
	v_cvt_pk_bf16_f32 v6, v12, v10
	s_waitcnt lgkmcnt(3)
	s_nop 1
	s_waitcnt lgkmcnt(2)
	s_nop 0
	ds_read2_b32 v[22:23], v28 offset0:182 offset1:190
	s_nop 1
	ds_read2_b32 v[24:25], v28 offset0:247 offset1:255
	v_cvt_pk_bf16_f32 v7, v14, v16
	s_waitcnt lgkmcnt(3)
	s_nop 1
	s_waitcnt lgkmcnt(2)
	s_nop 2
	v_cvt_pk_bf16_f32 v8, v18, v20
	s_waitcnt lgkmcnt(1)
	s_nop 0
	v_add_u32_e32 v26, 48, v4
	s_nop 0
	s_waitcnt lgkmcnt(0)
	s_nop 0
	v_ashrrev_i32_e32 v27, 31, v26
	s_nop 1
	v_lshlrev_b64 v[26:27], 10, v[26:27]
	v_cvt_pk_bf16_f32 v9, v22, v24
	v_lshl_add_u64 v[26:27], v[2:3], 0, v[26:27]
	s_nop 0
	global_store_dwordx4 v[26:27], v[6:9], off
	s_nop 3
	v_cvt_pk_bf16_f32 v6, v13, v11
	s_nop 4
	v_cvt_pk_bf16_f32 v7, v15, v17
	s_nop 4
	v_cvt_pk_bf16_f32 v8, v19, v21
	s_nop 4
	v_add_u32_e32 v4, 56, v4
	v_cvt_pk_bf16_f32 v9, v23, v25
	v_ashrrev_i32_e32 v5, 31, v4
	v_lshlrev_b64 v[4:5], 10, v[4:5]
	v_lshl_add_u64 v[2:3], v[2:3], 0, v[4:5]
	global_store_dwordx4 v[2:3], v[6:9], off
	s_waitcnt lgkmcnt(0)
	s_add_i32 s9, s9, s86
	s_add_i32 s10, s10, s11
	s_cmpk_lt_i32 s9, 0x100
	s_cbranch_scc0 .LBB0_185

; __device__ __forceinline__ unsigned pk2(float lo, float hi) { return f2bf(lo) | (f2bf(hi) << 16); }
; __device__ __forceinline__ void x_to_xb(const Ctx& c, const float* X, bf16* XB, float* RS) {
;     for (int row = c.gw; row < MT; row += c.NGW) {
;         const f32x4* xr = (const f32x4*)(X + (size_t)row * DM) + c.lane; f32x4 v[8]; float s = 0.f;
; #pragma unroll
;         for (int j = 0; j < 8; ++j) { v[j] = xr[64 * j]; s += (v[j].x * v[j].x + v[j].y * v[j].y) + (v[j].z * v[j].z + v[j].w * v[j].w); }
;         const float rs = rsqrtf(wave_sum(s) * (1.f / DM) + EPS); if (c.lane == 0) RS[row] = rs;
;         v2u* o8 = (v2u*)(XB + (size_t)row * DM) + c.lane;
; #pragma unroll
;         for (int j = 0; j < 8; ++j) { v2u o; o.x = pk2(v[j].x, v[j].y); o.y = pk2(v[j].z, v[j].w); o8[64 * j] = o; }
;     }
.LBB0_190:
	s_or_b64 exec, exec, s[12:13]
	s_load_dwordx2 s[12:13], s[52:53], 0x120
	v_bfe_u32 v45, v30, 16, 1
	v_add3_u32 v30, v30, v45, s14
	v_bfe_u32 v45, v31, 16, 1
	v_lshrrev_b32_e32 v30, 16, v30
	v_add3_u32 v31, v31, v45, s14
	v_and_or_b32 v30, v31, s15, v30
	s_nop 2
	s_waitcnt lgkmcnt(0)
	v_lshl_add_u64 v[46:47], s[12:13], 0, v[38:39]
	s_nop 1
	v_cvt_pk_bf16_f32 v31, v32, v33
	v_add_co_u32_e32 v32, vcc, s16, v46
	s_add_i32 s17, s17, s86
	s_nop 0
	v_addc_co_u32_e32 v33, vcc, 0, v47, vcc
	global_store_dwordx2 v[32:33], v[30:31], off
	s_nop 4
	v_cvt_pk_bf16_f32 v26, v26, v27
	s_nop 4
	v_cvt_pk_bf16_f32 v27, v28, v29
	global_store_dwordx2 v[32:33], v[26:27], off offset:512
	s_nop 4
	v_cvt_pk_bf16_f32 v22, v22, v23
	s_nop 4
	v_cvt_pk_bf16_f32 v23, v24, v25
	global_store_dwordx2 v[32:33], v[22:23], off offset:1024
	s_nop 4
	v_cvt_pk_bf16_f32 v18, v18, v19
	s_nop 4
	v_cvt_pk_bf16_f32 v19, v20, v21
	global_store_dwordx2 v[32:33], v[18:19], off offset:1536
	s_nop 4
	v_cvt_pk_bf16_f32 v14, v14, v15
	s_nop 4
	v_cvt_pk_bf16_f32 v15, v16, v17
	global_store_dwordx2 v[32:33], v[14:15], off offset:2048
	s_nop 4
	v_cvt_pk_bf16_f32 v10, v10, v11
	s_nop 4
	v_cvt_pk_bf16_f32 v11, v12, v13
	global_store_dwordx2 v[32:33], v[10:11], off offset:2560
	v_bfe_u32 v10, v6, 16, 1
	v_add3_u32 v6, v6, v10, s14
	v_bfe_u32 v10, v7, 16, 1
	v_lshrrev_b32_e32 v6, 16, v6
	v_add3_u32 v7, v7, v10, s14
	v_and_or_b32 v6, v7, s15, v6
	v_bfe_u32 v7, v8, 16, 1
	v_add3_u32 v7, v8, v7, s14
	v_bfe_u32 v8, v9, 16, 1
	v_lshrrev_b32_e32 v7, 16, v7
	v_add3_u32 v8, v9, v8, s14
	v_and_or_b32 v7, v8, s15, v7
	global_store_dwordx2 v[32:33], v[6:7], off offset:3072
	v_bfe_u32 v6, v2, 16, 1
	v_add3_u32 v2, v2, v6, s14
	v_bfe_u32 v6, v3, 16, 1
	v_lshrrev_b32_e32 v2, 16, v2
	v_add3_u32 v3, v3, v6, s14
	v_and_or_b32 v2, v3, s15, v2
	v_bfe_u32 v3, v4, 16, 1
	v_add3_u32 v3, v4, v3, s14
	v_bfe_u32 v4, v5, 16, 1
	s_add_u32 s0, s0, s6
	v_lshrrev_b32_e32 v3, 16, v3
	v_add3_u32 v4, v5, v4, s14
	s_addc_u32 s1, s1, s7
	v_and_or_b32 v3, v4, s15, v3
	v_lshl_add_u64 v[36:37], v[36:37], 0, s[8:9]
	s_cmpk_gt_i32 s17, 0x3fff
	v_lshl_add_u64 v[38:39], v[38:39], 0, s[10:11]
	global_store_dwordx2 v[32:33], v[2:3], off offset:3584
	s_cbranch_scc1 .LBB0_193

; #define LAS __attribute__((address_space(3)))
; #define LDS_WAIT() asm volatile("s_waitcnt lgkmcnt(0)" ::: "memory")
; __device__ __forceinline__ unsigned pk2(float lo, float hi) { return f2bf(lo) | (f2bf(hi) << 16); }
;     ...
;         for (int i = 0; i < 16; ++i) { LAS float* d = scr + (4 * i + kr) * 65 + nq; d[0] = v[i].x; d[1] = v[i].y; d[2] = v[i].z; d[3] = v[i].w; }
;         LDS_WAIT(); asm volatile("" ::: "memory");
;         const int c8 = lane & 7; int d0 = n0;
;         if (ffnmap) { const int bj = n0 >= FFH ? 1 : 0, chn = n0 - FFH * bj; d0 = 256 * (chn >> 7) + 128 * bj + (chn & 127); }
; #pragma unroll
;         for (int j = 0; j < 8; ++j) { const int n = (lane >> 3) + 8 * j; const LAS float* sp = scr + (8 * c8) * 65 + n;
;             v4u o; o.x = pk2(sp[0 * 65], sp[1 * 65]); o.y = pk2(sp[2 * 65], sp[3 * 65]); o.z = pk2(sp[4 * 65], sp[5 * 65]); o.w = pk2(sp[6 * 65], sp[7 * 65]);
;             *(v4u*)(WT + (size_t)(d0 + n) * K + k0 + 8 * c8) = o; }
.LBB0_286:
	s_or_b64 exec, exec, s[10:11]
	s_waitcnt vmcnt(0)
	ds_write2_b32 v77, v2, v3 offset1:1
	ds_write2_b32 v77, v4, v5 offset0:2 offset1:3
	v_add_u32_e32 v2, 0x410, v77
	ds_write2_b32 v2, v10, v11 offset1:1
	v_add_u32_e32 v2, 0x418, v77
	ds_write2_b32 v2, v12, v13 offset1:1
	v_add_u32_e32 v2, 0x820, v77
	ds_write2_b32 v2, v6, v7 offset1:1
	v_add_u32_e32 v2, 0x828, v77
	ds_write2_b32 v2, v8, v9 offset1:1
	v_add_u32_e32 v2, 0xc30, v77
	ds_write2_b32 v2, v18, v19 offset1:1
	v_add_u32_e32 v2, 0xc38, v77
	ds_write2_b32 v2, v20, v21 offset1:1
	v_add_u32_e32 v2, 0x1040, v77
	ds_write2_b32 v2, v14, v15 offset1:1
	v_add_u32_e32 v2, 0x1048, v77
	ds_write2_b32 v2, v16, v17 offset1:1
	v_add_u32_e32 v2, 0x1450, v77
	ds_write2_b32 v2, v26, v27 offset1:1
	v_add_u32_e32 v2, 0x1458, v77
	ds_write2_b32 v2, v28, v29 offset1:1
	v_add_u32_e32 v2, 0x1860, v77
	ds_write2_b32 v2, v22, v23 offset1:1
	v_add_u32_e32 v2, 0x1868, v77
	ds_write2_b32 v2, v24, v25 offset1:1
	v_add_u32_e32 v2, 0x1c70, v77
	ds_write2_b32 v2, v34, v35 offset1:1
	v_add_u32_e32 v2, 0x1c78, v77
	ds_write2_b32 v2, v36, v37 offset1:1
	v_add_u32_e32 v2, 0x2080, v77
	ds_write2_b32 v2, v30, v31 offset1:1
	v_add_u32_e32 v2, 0x2088, v77
	ds_write2_b32 v2, v32, v33 offset1:1
	v_add_u32_e32 v2, 0x2490, v77
	ds_write2_b32 v2, v42, v43 offset1:1
	v_add_u32_e32 v2, 0x2498, v77
	ds_write2_b32 v2, v44, v45 offset1:1
	v_add_u32_e32 v2, 0x28a0, v77
	ds_write2_b32 v2, v38, v39 offset1:1
	v_add_u32_e32 v2, 0x28a8, v77
	ds_write2_b32 v2, v40, v41 offset1:1
	v_add_u32_e32 v2, 0x2cb0, v77
	ds_write2_b32 v2, v50, v51 offset1:1
	v_add_u32_e32 v2, 0x2cb8, v77
	ds_write2_b32 v2, v52, v53 offset1:1
	v_add_u32_e32 v2, 0x30c0, v77
	ds_write2_b32 v2, v46, v47 offset1:1
	v_add_u32_e32 v2, 0x30c8, v77
	ds_write2_b32 v2, v48, v49 offset1:1
	v_add_u32_e32 v2, 0x34d0, v77
	ds_write2_b32 v2, v58, v59 offset1:1
	v_add_u32_e32 v2, 0x34d8, v77
	ds_write2_b32 v2, v60, v61 offset1:1
	v_add_u32_e32 v2, 0x38e0, v77
	ds_write2_b32 v2, v54, v55 offset1:1
	v_add_u32_e32 v2, 0x38e8, v77
	ds_write2_b32 v2, v56, v57 offset1:1
	v_add_u32_e32 v2, 0x3cf0, v77
	ds_write2_b32 v2, v62, v63 offset1:1
	v_add_u32_e32 v2, 0x3cf8, v77
	ds_write2_b32 v2, v64, v65 offset1:1
	s_waitcnt lgkmcnt(0)
	ds_read2_b32 v[10:11], v75 offset1:8
	ds_read2_b32 v[12:13], v75 offset0:65 offset1:73
	ds_read2_b32 v[14:15], v75 offset0:130 offset1:138
	ds_read2_b32 v[16:17], v75 offset0:195 offset1:203
	v_add_u32_e32 v28, 0x400, v75
	s_waitcnt lgkmcnt(3)
	s_nop 1
	s_waitcnt lgkmcnt(2)
	s_nop 0
	ds_read2_b32 v[18:19], v28 offset0:4 offset1:12
	s_nop 1
	ds_read2_b32 v[20:21], v28 offset0:69 offset1:77
	v_cvt_pk_bf16_f32 v6, v10, v12
	s_waitcnt lgkmcnt(3)
	s_nop 1
	s_waitcnt lgkmcnt(2)
	s_nop 0
	ds_read2_b32 v[22:23], v28 offset0:134 offset1:142
	s_nop 1
	ds_read2_b32 v[24:25], v28 offset0:199 offset1:207
	v_cvt_pk_bf16_f32 v7, v14, v16
	s_waitcnt lgkmcnt(3)
	s_nop 1
	s_waitcnt lgkmcnt(2)
	s_nop 2
	v_cvt_pk_bf16_f32 v8, v18, v20
	s_waitcnt lgkmcnt(1)
	s_nop 1
	s_waitcnt lgkmcnt(0)
	s_nop 2
	s_mul_i32 s17, s17, 0xfea00000
	s_ashr_i32 s9, s8, 31
	v_cvt_pk_bf16_f32 v9, v22, v24
	v_add_u32_e32 v4, s17, v76
	v_lshl_add_u64 v[2:3], s[8:9], 1, v[68:69]
	v_ashrrev_i32_e32 v5, 31, v4
	v_lshl_add_u64 v[26:27], v[2:3], 0, v[4:5]
	s_nop 0
	global_store_dwordx4 v[26:27], v[6:9], off
	s_nop 3
	v_cvt_pk_bf16_f32 v6, v11, v13
	s_nop 4
	v_cvt_pk_bf16_f32 v7, v15, v17
	s_nop 4
	v_cvt_pk_bf16_f32 v8, v19, v21
	s_nop 2
	v_add_u32_e32 v10, 0x16000, v4
	s_nop 1
	v_ashrrev_i32_e32 v11, 31, v10
	v_cvt_pk_bf16_f32 v9, v23, v25
	ds_read2_b32 v[12:13], v75 offset0:16 offset1:24
	v_lshl_add_u64 v[10:11], v[2:3], 0, v[10:11]
	global_store_dwordx4 v[10:11], v[6:9], off
	ds_read2_b32 v[10:11], v75 offset0:81 offset1:89
	ds_read2_b32 v[14:15], v75 offset0:146 offset1:154
	ds_read2_b32 v[16:17], v75 offset0:211 offset1:219
	s_waitcnt lgkmcnt(3)
; #define LAS __attribute__((address_space(3)))
; #define LDS_WAIT() asm volatile("s_waitcnt lgkmcnt(0)" ::: "memory")
; __device__ __forceinline__ unsigned pk2(float lo, float hi) { return f2bf(lo) | (f2bf(hi) << 16); }
;     ...
;         for (int j = 0; j < 8; ++j) { const int n = (lane >> 3) + 8 * j; const LAS float* sp = scr + (8 * c8) * 65 + n;
;             v4u o; o.x = pk2(sp[0 * 65], sp[1 * 65]); o.y = pk2(sp[2 * 65], sp[3 * 65]); o.z = pk2(sp[4 * 65], sp[5 * 65]); o.w = pk2(sp[6 * 65], sp[7 * 65]);
;             *(v4u*)(WT + (size_t)(d0 + n) * K + k0 + 8 * c8) = o; }
;         LDS_WAIT(); asm volatile("" ::: "memory");
	s_nop 1
	s_waitcnt lgkmcnt(2)
	s_nop 0
	ds_read2_b32 v[18:19], v28 offset0:20 offset1:28
	s_nop 1
	ds_read2_b32 v[20:21], v28 offset0:85 offset1:93
	v_cvt_pk_bf16_f32 v6, v12, v10
	s_waitcnt lgkmcnt(3)
	s_nop 1
	s_waitcnt lgkmcnt(2)
	s_nop 0
	ds_read2_b32 v[22:23], v28 offset0:150 offset1:158
	s_nop 1
	ds_read2_b32 v[24:25], v28 offset0:215 offset1:223
	v_cvt_pk_bf16_f32 v7, v14, v16
	s_waitcnt lgkmcnt(3)
	s_nop 1
	s_waitcnt lgkmcnt(2)
	s_nop 2
	v_cvt_pk_bf16_f32 v8, v18, v20
	s_waitcnt lgkmcnt(1)
	s_nop 1
	s_waitcnt lgkmcnt(0)
	s_nop 0
	v_add_u32_e32 v26, 0x2c000, v4
	s_nop 1
	v_ashrrev_i32_e32 v27, 31, v26
	v_cvt_pk_bf16_f32 v9, v22, v24
	v_lshl_add_u64 v[26:27], v[2:3], 0, v[26:27]
	s_nop 0
	global_store_dwordx4 v[26:27], v[6:9], off
	s_nop 3
	v_cvt_pk_bf16_f32 v6, v13, v11
	s_nop 4
	v_cvt_pk_bf16_f32 v7, v15, v17
	s_nop 4
	v_cvt_pk_bf16_f32 v8, v19, v21
	s_nop 2
	v_add_u32_e32 v10, 0x42000, v4
	s_nop 1
	v_ashrrev_i32_e32 v11, 31, v10
	v_cvt_pk_bf16_f32 v9, v23, v25
	ds_read2_b32 v[12:13], v75 offset0:32 offset1:40
	v_lshl_add_u64 v[10:11], v[2:3], 0, v[10:11]
	global_store_dwordx4 v[10:11], v[6:9], off
	ds_read2_b32 v[10:11], v75 offset0:97 offset1:105
	ds_read2_b32 v[14:15], v75 offset0:162 offset1:170
	ds_read2_b32 v[16:17], v75 offset0:227 offset1:235
	s_waitcnt lgkmcnt(3)
	s_nop 1
	s_waitcnt lgkmcnt(2)
	s_nop 0
	ds_read2_b32 v[18:19], v28 offset0:36 offset1:44
	s_nop 1
	ds_read2_b32 v[20:21], v28 offset0:101 offset1:109
	v_cvt_pk_bf16_f32 v6, v12, v10
	s_waitcnt lgkmcnt(3)
	s_nop 1
	s_waitcnt lgkmcnt(2)
	s_nop 0
	ds_read2_b32 v[22:23], v28 offset0:166 offset1:174
	s_nop 1
	ds_read2_b32 v[24:25], v28 offset0:231 offset1:239
	v_cvt_pk_bf16_f32 v7, v14, v16
	s_waitcnt lgkmcnt(3)
	s_nop 1
	s_waitcnt lgkmcnt(2)
	s_nop 2
	v_cvt_pk_bf16_f32 v8, v18, v20
	s_waitcnt lgkmcnt(1)
	s_nop 1
	s_waitcnt lgkmcnt(0)
	s_nop 0
	v_add_u32_e32 v26, 0x58000, v4
	s_nop 1
	v_ashrrev_i32_e32 v27, 31, v26
	v_cvt_pk_bf16_f32 v9, v22, v24
	v_lshl_add_u64 v[26:27], v[2:3], 0, v[26:27]
	s_nop 0
	global_store_dwordx4 v[26:27], v[6:9], off
	s_nop 3
	v_cvt_pk_bf16_f32 v6, v13, v11
	s_nop 4
	v_cvt_pk_bf16_f32 v7, v15, v17
	s_nop 4
	v_cvt_pk_bf16_f32 v8, v19, v21
	s_nop 2
	v_add_u32_e32 v10, 0x6e000, v4
	s_nop 1
	v_ashrrev_i32_e32 v11, 31, v10
	v_cvt_pk_bf16_f32 v9, v23, v25
	ds_read2_b32 v[12:13], v75 offset0:48 offset1:56
	v_lshl_add_u64 v[10:11], v[2:3], 0, v[10:11]
	global_store_dwordx4 v[10:11], v[6:9], off
	ds_read2_b32 v[10:11], v75 offset0:113 offset1:121
	ds_read2_b32 v[14:15], v75 offset0:178 offset1:186
	ds_read2_b32 v[16:17], v75 offset0:243 offset1:251
	s_waitcnt lgkmcnt(3)
	s_nop 1
	s_waitcnt lgkmcnt(2)
	s_nop 0
	ds_read2_b32 v[18:19], v28 offset0:52 offset1:60
	s_nop 1
	ds_read2_b32 v[20:21], v28 offset0:117 offset1:125
	v_cvt_pk_bf16_f32 v6, v12, v10
	s_waitcnt lgkmcnt(3)
	s_nop 1
	s_waitcnt lgkmcnt(2)
	s_nop 0
	ds_read2_b32 v[22:23], v28 offset0:182 offset1:190
	s_nop 1
	ds_read2_b32 v[24:25], v28 offset0:247 offset1:255
	v_cvt_pk_bf16_f32 v7, v14, v16
	s_waitcnt lgkmcnt(3)
	s_nop 1
	s_waitcnt lgkmcnt(2)
	s_nop 2
	v_cvt_pk_bf16_f32 v8, v18, v20
	s_waitcnt lgkmcnt(1)
	s_nop 1
	s_waitcnt lgkmcnt(0)
	s_nop 0
	v_add_u32_e32 v26, 0x84000, v4
	s_nop 1
	v_ashrrev_i32_e32 v27, 31, v26
	v_cvt_pk_bf16_f32 v9, v22, v24
	v_lshl_add_u64 v[26:27], v[2:3], 0, v[26:27]
	s_nop 0
	global_store_dwordx4 v[26:27], v[6:9], off
	s_nop 3
	v_cvt_pk_bf16_f32 v6, v13, v11
	s_nop 4
	v_cvt_pk_bf16_f32 v7, v15, v17
	s_nop 4
	v_cvt_pk_bf16_f32 v8, v19, v21
	s_nop 4
	v_add_u32_e32 v4, 0x9a000, v4
	v_cvt_pk_bf16_f32 v9, v23, v25
	v_ashrrev_i32_e32 v5, 31, v4
	v_lshl_add_u64 v[2:3], v[2:3], 0, v[4:5]
	global_store_dwordx4 v[2:3], v[6:9], off
	s_waitcnt lgkmcnt(0)
	s_add_i32 s0, s0, s1
	s_add_i32 s12, s12, s13
	s_mul_i32 s8, s1, 0xb0000
	s_cmpk_lt_i32 s0, 0xb00
	v_add_u32_e32 v76, s8, v76
	s_cbranch_scc0 .LBB0_319

; __device__ __forceinline__ void ssd_conv(const Ctx& c, const bf16* P, const float* cw, const float* cb, const float* dtb, bf16* X2, float* DT) {
;     ...
;     for (int it = c.vcu * 512 + c.tid; it < items; it += c.G * 512) {
;         const int rb = it / NCG, cg = it % NCG, c0 = cg * 8, row0 = rb * 8, t0 = row0 & (SEQ - 1);
;         v4u xa[11];
; #pragma unroll
;         for (int i = 0; i < 11; ++i) { const bool ok = (i >= 3) || (t0 != 0); xa[i] = ok ? *(const v4u*)(P + (size_t)(row0 + i - 3) * SSD_NP + 4096 + c0) : (v4u){0u, 0u, 0u, 0u}; }
;         float w[4][8], bb[8];
; #pragma unroll
;         for (int k = 0; k < 4; ++k) { const f32x4 a0 = *(const f32x4*)(cw + k * NC + c0), a1 = *(const f32x4*)(cw + k * NC + c0 + 4);
; #pragma unroll
;             for (int j = 0; j < 4; ++j) { w[k][j] = a0[j]; w[k][4 + j] = a1[j]; } }
;         { const f32x4 a0 = *(const f32x4*)(cb + c0), a1 = *(const f32x4*)(cb + c0 + 4);
; #pragma unroll
;           for (int j = 0; j < 4; ++j) { bb[j] = a0[j]; bb[4 + j] = a1[j]; } }
.LBB0_390:
	s_or_b64 exec, exec, s[12:13]
	v_mad_i64_i32 v[2:3], s[2:3], v118, s14, v[88:89]
	v_lshlrev_b64 v[90:91], 1, v[6:7]
	v_lshl_add_u64 v[2:3], v[2:3], 0, v[90:91]
	v_add_co_u32_e32 v2, vcc, 0x2000, v2
	v_or_b32_e32 v117, 1, v118
	s_nop 0
	v_addc_co_u32_e32 v3, vcc, 0, v3, vcc
	global_load_dwordx4 v[74:77], v[2:3], off
	v_mad_i64_i32 v[2:3], s[2:3], v117, s14, v[88:89]
	v_lshl_add_u64 v[2:3], v[2:3], 0, v[90:91]
	v_add_co_u32_e32 v2, vcc, 0x2000, v2
	v_or_b32_e32 v116, 2, v118
	s_nop 0
	v_addc_co_u32_e32 v3, vcc, 0, v3, vcc
	global_load_dwordx4 v[66:69], v[2:3], off
	v_mad_i64_i32 v[2:3], s[2:3], v116, s14, v[88:89]
	v_lshl_add_u64 v[2:3], v[2:3], 0, v[90:91]
	v_add_co_u32_e32 v2, vcc, 0x2000, v2
	v_or_b32_e32 v115, 3, v118
	s_nop 0
	v_addc_co_u32_e32 v3, vcc, 0, v3, vcc
	global_load_dwordx4 v[62:65], v[2:3], off
	v_mad_i64_i32 v[2:3], s[2:3], v115, s14, v[88:89]
	v_lshl_add_u64 v[2:3], v[2:3], 0, v[90:91]
	v_add_co_u32_e32 v2, vcc, 0x2000, v2
	v_or_b32_e32 v114, 4, v118
	s_nop 0
	v_addc_co_u32_e32 v3, vcc, 0, v3, vcc
	global_load_dwordx4 v[58:61], v[2:3], off
	v_mad_i64_i32 v[2:3], s[2:3], v114, s14, v[88:89]
	v_lshl_add_u64 v[2:3], v[2:3], 0, v[90:91]
	v_add_co_u32_e32 v2, vcc, 0x2000, v2
	v_or_b32_e32 v113, 5, v118
	s_nop 0
	v_addc_co_u32_e32 v3, vcc, 0, v3, vcc
	global_load_dwordx4 v[54:57], v[2:3], off
	v_mad_i64_i32 v[2:3], s[2:3], v113, s14, v[88:89]
	v_lshl_add_u64 v[2:3], v[2:3], 0, v[90:91]
	v_add_co_u32_e32 v2, vcc, 0x2000, v2
	v_or_b32_e32 v112, 6, v118
	s_nop 0
	v_addc_co_u32_e32 v3, vcc, 0, v3, vcc
	global_load_dwordx4 v[50:53], v[2:3], off
	v_mad_i64_i32 v[2:3], s[2:3], v112, s14, v[88:89]
	s_load_dwordx16 s[52:67], s[68:69], 0x0
	v_lshl_add_u64 v[2:3], v[2:3], 0, v[90:91]
	v_add_co_u32_e32 v2, vcc, 0x2000, v2
	v_or_b32_e32 v111, 7, v118
	s_nop 0
	v_addc_co_u32_e32 v3, vcc, 0, v3, vcc
	global_load_dwordx4 v[42:45], v[2:3], off
	v_mad_i64_i32 v[2:3], s[2:3], v111, s14, v[88:89]
	v_lshl_add_u64 v[2:3], v[2:3], 0, v[90:91]
	v_lshlrev_b64 v[30:31], 2, v[6:7]
	s_waitcnt lgkmcnt(0)
	s_mov_b64 s[28:29], s[64:65]
	v_add_co_u32_e32 v2, vcc, 0x2000, v2
	v_lshl_add_u64 v[18:19], s[28:29], 0, v[30:31]
	s_mov_b64 s[2:3], 0x6000
	v_addc_co_u32_e32 v3, vcc, 0, v3, vcc
	v_lshl_add_u64 v[10:11], v[18:19], 0, s[2:3]
	s_movk_i32 s2, 0x6000
	v_add_co_u32_e32 v12, vcc, s2, v18
	s_mov_b64 s[2:3], 0xc000
	s_nop 0
	v_addc_co_u32_e32 v13, vcc, 0, v19, vcc
	v_lshl_add_u64 v[14:15], v[18:19], 0, s[2:3]
	s_mov_b32 s2, 0xc000
	v_add_co_u32_e32 v16, vcc, s2, v18
	s_mov_b64 s[2:3], 0x12000
	s_nop 0
	v_addc_co_u32_e32 v17, vcc, 0, v19, vcc
	v_lshl_add_u64 v[20:21], v[18:19], 0, s[2:3]
	s_mov_b32 s2, 0x12000
	global_load_dwordx4 v[2:5], v[2:3], off
	s_mov_b64 s[30:31], s[66:67]
	global_load_dwordx4 v[6:9], v[18:19], off offset:16
	global_load_dwordx4 v[22:25], v[18:19], off
	v_add_co_u32_e32 v18, vcc, s2, v18
	v_lshl_add_u64 v[46:47], s[30:31], 0, v[30:31]
	s_nop 0
	v_addc_co_u32_e32 v19, vcc, 0, v19, vcc
	global_load_dwordx4 v[26:29], v[12:13], off
	s_nop 0
	global_load_dwordx4 v[10:13], v[10:11], off offset:16
	s_nop 0
	global_load_dwordx4 v[34:37], v[16:17], off
	s_nop 0
	global_load_dwordx4 v[14:17], v[14:15], off offset:16
	s_nop 0
	global_load_dwordx4 v[38:41], v[18:19], off
	s_nop 0
	global_load_dwordx4 v[18:21], v[20:21], off offset:16
	s_nop 0
	global_load_dwordx4 v[30:33], v[46:47], off offset:16
	s_nop 0
	global_load_dwordx4 v[46:49], v[46:47], off
	s_waitcnt vmcnt(18)
	v_lshlrev_b32_e32 v108, 16, v78
	v_and_b32_e32 v106, 0xffff0000, v78
	v_lshlrev_b32_e32 v93, 16, v83
	v_lshlrev_b32_e32 v92, 16, v82
	v_lshlrev_b32_e32 v109, 16, v79
	v_and_b32_e32 v99, 0xffff0000, v83
	v_and_b32_e32 v98, 0xffff0000, v82
	v_and_b32_e32 v107, 0xffff0000, v79
	v_lshlrev_b32_e32 v104, 16, v80
	v_and_b32_e32 v102, 0xffff0000, v80
	v_lshlrev_b32_e32 v105, 16, v81
	v_and_b32_e32 v103, 0xffff0000, v81
	v_lshlrev_b32_e32 v101, 16, v85
	v_lshlrev_b32_e32 v100, 16, v84
	v_and_b32_e32 v121, 0xffff0000, v85
	v_and_b32_e32 v120, 0xffff0000, v84
	v_lshlrev_b32_e32 v97, 16, v71
	v_lshlrev_b32_e32 v96, 16, v70
	s_waitcnt vmcnt(17)
	v_lshlrev_b32_e32 v95, 16, v75
	v_lshlrev_b32_e32 v94, 16, v74
	v_lshl_add_u64 v[90:91], s[78:79], 0, v[90:91]
	v_add_u32_e32 v110, s0, v110
	v_add_u32_e32 v87, s1, v87
	s_waitcnt vmcnt(8)
	v_mov_b32_e32 v78, v22
	v_mov_b32_e32 v79, v24
	v_mov_b32_e32 v24, v23
	s_waitcnt vmcnt(7)
	v_mov_b32_e32 v82, v26
	v_mov_b32_e32 v83, v28
	v_mov_b32_e32 v28, v27
	s_waitcnt vmcnt(0)
; __device__ __forceinline__ unsigned pk2(float lo, float hi) { return f2bf(lo) | (f2bf(hi) << 16); }
; __device__ __forceinline__ float silu_fast(float x) { return x * __builtin_amdgcn_rcpf(1.f + __builtin_amdgcn_exp2f(-1.4426950408889634f * x)); }
; __device__ __forceinline__ void ssd_conv(const Ctx& c, const bf16* P, const float* cw, const float* cb, const float* dtb, bf16* X2, float* DT) {
;     ...
;         for (int i = 0; i < 8; ++i) {
;             float o[8];
; #pragma unroll
;             for (int j = 0; j < 8; ++j) { const int q = j >> 1; float y = bb[j];
; #pragma unroll
;                 for (int k = 0; k < 4; ++k) y += w[k][j] * ((j & 1) ? bfhi(xa[i + k][q]) : bflo(xa[i + k][q]));
;                 o[j] = silu_fast(y); }
;             v4u wv; wv.x = pk2(o[0], o[1]); wv.y = pk2(o[2], o[3]); wv.z = pk2(o[4], o[5]); wv.w = pk2(o[6], o[7]);
;             *(v4u*)(X2 + (size_t)(row0 + i) * NC + c0) = wv;
	v_mov_b32_e32 v80, v46
	v_mov_b32_e32 v81, v48
	v_mov_b32_e32 v48, v47
	v_pk_fma_f32 v[84:85], v[78:79], v[92:93], v[80:81]
	v_pk_fma_f32 v[46:47], v[24:25], v[98:99], v[48:49]
	v_pk_fma_f32 v[92:93], v[82:83], v[108:109], v[84:85]
	v_mov_b32_e32 v84, v34
	v_mov_b32_e32 v85, v36
	v_pk_fma_f32 v[26:27], v[28:29], v[106:107], v[46:47]
	v_and_b32_e32 v99, 0xffff0000, v71
	v_and_b32_e32 v98, 0xffff0000, v70
	v_mov_b32_e32 v36, v35
	v_pk_fma_f32 v[122:123], v[84:85], v[96:97], v[92:93]
	v_mov_b32_e32 v93, v40
	v_pk_fma_f32 v[26:27], v[36:37], v[98:99], v[26:27]
	v_and_b32_e32 v71, 0xffff0000, v75
	v_and_b32_e32 v70, 0xffff0000, v74
	v_mov_b32_e32 v40, v39
	v_pk_fma_f32 v[26:27], v[40:41], v[70:71], v[26:27]
	v_mov_b32_e32 v92, v38
	v_mul_f32_e32 v23, 0xbfb8aa3b, v26
	v_exp_f32_e32 v23, v23
	v_pk_fma_f32 v[122:123], v[92:93], v[94:95], v[122:123]
	v_lshlrev_b32_e32 v75, 16, v77
	v_mul_f32_e32 v22, 0xbfb8aa3b, v122
	v_add_f32_e32 v23, 1.0, v23
	v_rcp_f32_e32 v34, v23
	v_mul_f32_e32 v23, 0xbfb8aa3b, v123
	v_exp_f32_e32 v22, v22
	v_exp_f32_e32 v23, v23
	v_lshlrev_b32_e32 v74, 16, v76
	v_add_f32_e32 v22, 1.0, v22
	v_add_f32_e32 v23, 1.0, v23
	v_rcp_f32_e32 v22, v22
	v_rcp_f32_e32 v23, v23
	s_nop 0
	v_pk_mul_f32 v[122:123], v[122:123], v[22:23]
	v_mul_f32_e32 v22, 0xbfb8aa3b, v27
	v_exp_f32_e32 v22, v22
	v_mov_b32_e32 v23, v8
	v_mov_b32_e32 v8, v7
	v_add_f32_e32 v22, 1.0, v22
	v_rcp_f32_e32 v35, v22
	v_mov_b32_e32 v22, v6
	v_pk_mul_f32 v[124:125], v[26:27], v[34:35]
	v_mov_b32_e32 v26, v30
	v_mov_b32_e32 v27, v32
	v_pk_fma_f32 v[38:39], v[22:23], v[100:101], v[26:27]
	v_mov_b32_e32 v34, v10
	v_mov_b32_e32 v35, v12
	v_pk_fma_f32 v[46:47], v[34:35], v[104:105], v[38:39]
	v_lshlrev_b32_e32 v101, 16, v73
	v_lshlrev_b32_e32 v100, 16, v72
	v_mov_b32_e32 v38, v14
	v_mov_b32_e32 v39, v16
	v_pk_fma_f32 v[126:127], v[38:39], v[100:101], v[46:47]
	v_mov_b32_e32 v46, v18
	v_mov_b32_e32 v47, v20
	v_pk_fma_f32 v[126:127], v[46:47], v[74:75], v[126:127]
	v_mov_b32_e32 v32, v31
	v_mul_f32_e32 v6, 0xbfb8aa3b, v126
	v_exp_f32_e32 v6, v6
	v_mov_b32_e32 v12, v11
	v_and_b32_e32 v31, 0xffff0000, v73
	v_and_b32_e32 v30, 0xffff0000, v72
	v_add_f32_e32 v6, 1.0, v6
	v_rcp_f32_e32 v10, v6
	v_pk_fma_f32 v[6:7], v[8:9], v[120:121], v[32:33]
	v_mov_b32_e32 v16, v15
	v_pk_fma_f32 v[6:7], v[12:13], v[102:103], v[6:7]
	v_mov_b32_e32 v20, v19
	v_pk_fma_f32 v[14:15], v[16:17], v[30:31], v[6:7]
	v_and_b32_e32 v7, 0xffff0000, v77
	v_and_b32_e32 v6, 0xffff0000, v76
	v_pk_fma_f32 v[14:15], v[20:21], v[6:7], v[14:15]
	v_bfe_u32 v72, v125, 16, 1
	v_mul_f32_e32 v11, 0xbfb8aa3b, v14
	v_exp_f32_e32 v11, v11
	v_mul_f32_e32 v19, 0xbfb8aa3b, v15
	v_exp_f32_e32 v19, v19
	v_bfe_u32 v73, v124, 16, 1
	v_add_f32_e32 v11, 1.0, v11
	v_rcp_f32_e32 v18, v11
	v_mul_f32_e32 v11, 0xbfb8aa3b, v127
	v_exp_f32_e32 v11, v11
	v_add_f32_e32 v19, 1.0, v19
	v_rcp_f32_e32 v19, v19
	v_add3_u32 v73, v124, v73, s16
	v_add_f32_e32 v11, 1.0, v11
	v_rcp_f32_e32 v11, v11
	v_pk_mul_f32 v[14:15], v[14:15], v[18:19]
	v_add3_u32 v72, v125, v72, s16
	s_nop 0
	v_pk_mul_f32 v[10:11], v[126:127], v[10:11]
	s_nop 2
	v_bfe_u32 v18, v122, 16, 1
	v_bfe_u32 v19, v123, 16, 1
	s_nop 3
	v_add3_u32 v19, v123, v19, s16
	v_add3_u32 v18, v122, v18, s16
	v_lshrrev_b32_e32 v18, 16, v18
	v_lshrrev_b32_e32 v19, 16, v19
	s_nop 1
	v_cvt_pk_bf16_f32 v123, v11, v15
	v_cvt_pk_bf16_f32 v122, v10, v14
	v_and_or_b32 v121, v72, s15, v19
	v_and_or_b32 v120, v73, s15, v18
	v_mad_i64_i32 v[10:11], s[2:3], v118, s17, v[90:91]
	global_store_dwordx4 v[10:11], v[120:123], off
	v_pk_fma_f32 v[10:11], v[78:79], v[108:109], v[80:81]
	v_lshlrev_b32_e32 v77, 16, v67
	v_pk_fma_f32 v[10:11], v[82:83], v[96:97], v[10:11]
	v_lshlrev_b32_e32 v76, 16, v66
	v_pk_fma_f32 v[10:11], v[84:85], v[94:95], v[10:11]
	s_nop 0
	v_pk_fma_f32 v[14:15], v[92:93], v[76:77], v[10:11]
	s_nop 0
	v_mul_f32_e32 v10, 0xbfb8aa3b, v14
	v_exp_f32_e32 v10, v10
	s_nop 0
	v_add_f32_e32 v10, 1.0, v10
	v_rcp_f32_e32 v18, v10
	v_pk_fma_f32 v[10:11], v[24:25], v[106:107], v[48:49]
	s_nop 0
	v_pk_fma_f32 v[10:11], v[28:29], v[98:99], v[10:11]
	s_nop 0
	v_pk_fma_f32 v[72:73], v[36:37], v[70:71], v[10:11]
	v_and_b32_e32 v11, 0xffff0000, v67
	v_and_b32_e32 v10, 0xffff0000, v66
	v_pk_fma_f32 v[66:67], v[40:41], v[10:11], v[72:73]
	s_nop 0
	v_mul_f32_e32 v19, 0xbfb8aa3b, v66
	v_exp_f32_e32 v19, v19
	s_nop 0
	v_add_f32_e32 v19, 1.0, v19
	v_rcp_f32_e32 v72, v19
	v_mul_f32_e32 v19, 0xbfb8aa3b, v15
	v_exp_f32_e32 v19, v19
	s_nop 0
	v_add_f32_e32 v19, 1.0, v19
	v_rcp_f32_e32 v19, v19
	s_nop 0
	v_pk_mul_f32 v[18:19], v[14:15], v[18:19]
	v_mul_f32_e32 v14, 0xbfb8aa3b, v67
	v_exp_f32_e32 v14, v14
	s_nop 0
	v_add_f32_e32 v14, 1.0, v14
	v_rcp_f32_e32 v73, v14
	v_pk_fma_f32 v[14:15], v[22:23], v[104:105], v[26:27]
	v_pk_mul_f32 v[66:67], v[66:67], v[72:73]
	v_pk_fma_f32 v[14:15], v[34:35], v[100:101], v[14:15]
	v_lshlrev_b32_e32 v73, 16, v69
	v_pk_fma_f32 v[14:15], v[38:39], v[74:75], v[14:15]
	v_lshlrev_b32_e32 v72, 16, v68
	v_pk_fma_f32 v[104:105], v[46:47], v[72:73], v[14:15]
	s_nop 0
	v_mul_f32_e32 v14, 0xbfb8aa3b, v104
	v_exp_f32_e32 v14, v14
	s_nop 0
	v_add_f32_e32 v14, 1.0, v14
	v_rcp_f32_e32 v106, v14
	v_pk_fma_f32 v[14:15], v[8:9], v[102:103], v[32:33]
	s_nop 0
	v_pk_fma_f32 v[14:15], v[12:13], v[30:31], v[14:15]
	v_pk_fma_f32 v[30:31], v[8:9], v[30:31], v[32:33]
	v_pk_fma_f32 v[102:103], v[16:17], v[6:7], v[14:15]
	v_and_b32_e32 v15, 0xffff0000, v69
	v_and_b32_e32 v14, 0xffff0000, v68
	v_pk_fma_f32 v[68:69], v[20:21], v[14:15], v[102:103]
	v_mul_f32_e32 v103, 0xbfb8aa3b, v105
	v_exp_f32_e32 v103, v103
	v_mul_f32_e32 v102, 0xbfb8aa3b, v68
	v_exp_f32_e32 v102, v102
	v_pk_fma_f32 v[30:31], v[12:13], v[6:7], v[30:31]
; __device__ __forceinline__ unsigned pk2(float lo, float hi) { return f2bf(lo) | (f2bf(hi) << 16); }
; __device__ __forceinline__ float silu_fast(float x) { return x * __builtin_amdgcn_rcpf(1.f + __builtin_amdgcn_exp2f(-1.4426950408889634f * x)); }
; __device__ __forceinline__ void ssd_conv(const Ctx& c, const bf16* P, const float* cw, const float* cb, const float* dtb, bf16* X2, float* DT) {
;     ...
;         for (int i = 0; i < 8; ++i) {
;             float o[8];
; #pragma unroll
;             for (int j = 0; j < 8; ++j) { const int q = j >> 1; float y = bb[j];
; #pragma unroll
;                 for (int k = 0; k < 4; ++k) y += w[k][j] * ((j & 1) ? bfhi(xa[i + k][q]) : bflo(xa[i + k][q]));
;                 o[j] = silu_fast(y); }
;             v4u wv; wv.x = pk2(o[0], o[1]); wv.y = pk2(o[2], o[3]); wv.z = pk2(o[4], o[5]); wv.w = pk2(o[6], o[7]);
;             *(v4u*)(X2 + (size_t)(row0 + i) * NC + c0) = wv;
	v_add_f32_e32 v103, 1.0, v103
	v_rcp_f32_e32 v107, v103
	v_mul_f32_e32 v103, 0xbfb8aa3b, v69
	v_exp_f32_e32 v103, v103
	v_add_f32_e32 v102, 1.0, v102
	v_rcp_f32_e32 v102, v102
	v_pk_mul_f32 v[104:105], v[104:105], v[106:107]
	v_add_f32_e32 v103, 1.0, v103
	v_rcp_f32_e32 v103, v103
	s_nop 2
	v_pk_mul_f32 v[68:69], v[68:69], v[102:103]
	s_nop 0
	v_bfe_u32 v102, v69, 16, 1
	v_bfe_u32 v103, v68, 16, 1
	v_add3_u32 v68, v68, v103, s16
	v_add3_u32 v69, v69, v102, s16
	s_nop 1
	v_bfe_u32 v106, v104, 16, 1
	v_bfe_u32 v107, v105, 16, 1
	v_add3_u32 v105, v105, v107, s16
	v_add3_u32 v104, v104, v106, s16
	s_nop 3
	v_lshrrev_b32_e32 v102, 16, v104
	v_lshrrev_b32_e32 v103, 16, v105
	v_and_or_b32 v69, v69, s15, v103
	v_and_or_b32 v68, v68, s15, v102
	v_cvt_pk_bf16_f32 v67, v19, v67
	v_cvt_pk_bf16_f32 v66, v18, v66
	v_mad_i64_i32 v[18:19], s[2:3], v117, s17, v[90:91]
	global_store_dwordx4 v[18:19], v[66:69], off
	v_pk_fma_f32 v[18:19], v[78:79], v[96:97], v[80:81]
	v_pk_fma_f32 v[102:103], v[16:17], v[14:15], v[30:31]
	v_pk_fma_f32 v[18:19], v[82:83], v[94:95], v[18:19]
	v_lshlrev_b32_e32 v69, 16, v63
	v_pk_fma_f32 v[18:19], v[84:85], v[76:77], v[18:19]
	v_lshlrev_b32_e32 v68, 16, v62
	v_pk_fma_f32 v[66:67], v[92:93], v[68:69], v[18:19]
	v_and_b32_e32 v31, 0xffff0000, v65
	v_mul_f32_e32 v18, 0xbfb8aa3b, v66
	v_exp_f32_e32 v18, v18
	v_and_b32_e32 v30, 0xffff0000, v64
	v_pk_fma_f32 v[6:7], v[8:9], v[6:7], v[32:33]
	v_add_f32_e32 v18, 1.0, v18
	v_rcp_f32_e32 v96, v18
	v_pk_fma_f32 v[18:19], v[24:25], v[98:99], v[48:49]
	v_pk_fma_f32 v[6:7], v[12:13], v[14:15], v[6:7]
	v_pk_fma_f32 v[18:19], v[28:29], v[70:71], v[18:19]
	v_pk_fma_f32 v[70:71], v[24:25], v[70:71], v[48:49]
	v_pk_fma_f32 v[98:99], v[36:37], v[10:11], v[18:19]
	v_and_b32_e32 v19, 0xffff0000, v63
	v_and_b32_e32 v18, 0xffff0000, v62
	v_pk_fma_f32 v[62:63], v[40:41], v[18:19], v[98:99]
	v_pk_fma_f32 v[70:71], v[28:29], v[10:11], v[70:71]
	v_mul_f32_e32 v97, 0xbfb8aa3b, v62
	v_exp_f32_e32 v97, v97
	v_pk_fma_f32 v[70:71], v[36:37], v[18:19], v[70:71]
	v_pk_fma_f32 v[10:11], v[24:25], v[10:11], v[48:49]
	v_pk_fma_f32 v[14:15], v[8:9], v[14:15], v[32:33]
	v_add_f32_e32 v97, 1.0, v97
	v_rcp_f32_e32 v98, v97
	v_mul_f32_e32 v97, 0xbfb8aa3b, v67
	v_exp_f32_e32 v97, v97
	v_pk_fma_f32 v[10:11], v[28:29], v[18:19], v[10:11]
	v_pk_fma_f32 v[14:15], v[12:13], v[30:31], v[14:15]
	v_pk_fma_f32 v[18:19], v[24:25], v[18:19], v[48:49]
	v_add_f32_e32 v97, 1.0, v97
	v_rcp_f32_e32 v97, v97
	s_nop 0
	v_pk_mul_f32 v[96:97], v[66:67], v[96:97]
	v_mul_f32_e32 v66, 0xbfb8aa3b, v63
	v_exp_f32_e32 v66, v66
	s_nop 0
	v_add_f32_e32 v66, 1.0, v66
	v_rcp_f32_e32 v99, v66
	v_pk_fma_f32 v[66:67], v[22:23], v[100:101], v[26:27]
	v_pk_mul_f32 v[62:63], v[62:63], v[98:99]
	v_pk_fma_f32 v[66:67], v[34:35], v[74:75], v[66:67]
	s_nop 0
	v_pk_fma_f32 v[98:99], v[38:39], v[72:73], v[66:67]
	v_lshlrev_b32_e32 v67, 16, v65
	v_lshlrev_b32_e32 v66, 16, v64
	v_pk_fma_f32 v[64:65], v[20:21], v[30:31], v[102:103]
	v_pk_fma_f32 v[98:99], v[46:47], v[66:67], v[98:99]
	v_mul_f32_e32 v101, 0xbfb8aa3b, v64
	v_exp_f32_e32 v101, v101
	v_mul_f32_e32 v100, 0xbfb8aa3b, v98
	v_exp_f32_e32 v100, v100
	v_add_f32_e32 v101, 1.0, v101
	v_rcp_f32_e32 v102, v101
	v_mul_f32_e32 v101, 0xbfb8aa3b, v99
	v_exp_f32_e32 v101, v101
	v_add_f32_e32 v100, 1.0, v100
	v_rcp_f32_e32 v100, v100
	v_add_f32_e32 v101, 1.0, v101
	v_rcp_f32_e32 v101, v101
	s_nop 0
	v_pk_mul_f32 v[98:99], v[98:99], v[100:101]
	v_mul_f32_e32 v100, 0xbfb8aa3b, v65
	v_exp_f32_e32 v100, v100
	s_nop 0
	v_add_f32_e32 v100, 1.0, v100
	v_rcp_f32_e32 v103, v100
	s_nop 0
	v_pk_mul_f32 v[64:65], v[64:65], v[102:103]
	s_nop 0
	v_bfe_u32 v100, v65, 16, 1
	v_bfe_u32 v101, v64, 16, 1
	v_bfe_u32 v102, v63, 16, 1
	v_bfe_u32 v103, v62, 16, 1
	v_add3_u32 v62, v62, v103, s16
	v_add3_u32 v63, v63, v102, s16
	v_add3_u32 v64, v64, v101, s16
	v_add3_u32 v65, v65, v100, s16
	v_bfe_u32 v100, v96, 16, 1
	v_bfe_u32 v101, v97, 16, 1
	v_bfe_u32 v102, v98, 16, 1
	v_bfe_u32 v103, v99, 16, 1
	v_add3_u32 v99, v99, v103, s16
	v_add3_u32 v98, v98, v102, s16
	v_add3_u32 v97, v97, v101, s16
	v_add3_u32 v96, v96, v100, s16
	v_lshrrev_b32_e32 v96, 16, v96
	v_lshrrev_b32_e32 v97, 16, v97
	v_lshrrev_b32_e32 v98, 16, v98
	v_lshrrev_b32_e32 v99, 16, v99
	v_and_or_b32 v65, v65, s15, v99
	v_and_or_b32 v64, v64, s15, v98
	v_and_or_b32 v63, v63, s15, v97
	v_and_or_b32 v62, v62, s15, v96
	v_mad_i64_i32 v[96:97], s[2:3], v116, s17, v[90:91]
	global_store_dwordx4 v[96:97], v[62:65], off
	v_pk_fma_f32 v[98:99], v[16:17], v[30:31], v[6:7]
	v_and_b32_e32 v7, 0xffff0000, v61
	v_lshlrev_b32_e32 v65, 16, v59
	v_lshlrev_b32_e32 v64, 16, v58
	v_and_b32_e32 v59, 0xffff0000, v59
	v_and_b32_e32 v58, 0xffff0000, v58
	v_pk_fma_f32 v[70:71], v[40:41], v[58:59], v[70:71]
	v_pk_fma_f32 v[62:63], v[78:79], v[94:95], v[80:81]
	v_mul_f32_e32 v95, 0xbfb8aa3b, v70
	v_exp_f32_e32 v95, v95
	v_pk_fma_f32 v[62:63], v[82:83], v[76:77], v[62:63]
	v_and_b32_e32 v6, 0xffff0000, v60
	v_pk_fma_f32 v[62:63], v[84:85], v[68:69], v[62:63]
	v_add_f32_e32 v95, 1.0, v95
	v_pk_fma_f32 v[62:63], v[92:93], v[64:65], v[62:63]
	v_rcp_f32_e32 v96, v95
	v_mul_f32_e32 v94, 0xbfb8aa3b, v62
	v_mul_f32_e32 v95, 0xbfb8aa3b, v63
	v_exp_f32_e32 v94, v94
	v_exp_f32_e32 v95, v95
	v_pk_fma_f32 v[18:19], v[28:29], v[58:59], v[18:19]
	v_pk_fma_f32 v[30:31], v[8:9], v[30:31], v[32:33]
	v_add_f32_e32 v94, 1.0, v94
	v_add_f32_e32 v95, 1.0, v95
	v_rcp_f32_e32 v94, v94
	v_rcp_f32_e32 v95, v95
	v_pk_fma_f32 v[30:31], v[12:13], v[6:7], v[30:31]
	v_pk_mul_f32 v[94:95], v[62:63], v[94:95]
	v_mul_f32_e32 v62, 0xbfb8aa3b, v71
	v_exp_f32_e32 v62, v62
	s_nop 0
	v_add_f32_e32 v62, 1.0, v62
	v_rcp_f32_e32 v97, v62
; __device__ __forceinline__ unsigned pk2(float lo, float hi) { return f2bf(lo) | (f2bf(hi) << 16); }
; __device__ __forceinline__ float silu_fast(float x) { return x * __builtin_amdgcn_rcpf(1.f + __builtin_amdgcn_exp2f(-1.4426950408889634f * x)); }
; __device__ __forceinline__ void ssd_conv(const Ctx& c, const bf16* P, const float* cw, const float* cb, const float* dtb, bf16* X2, float* DT) {
;     ...
;         for (int i = 0; i < 8; ++i) {
;             float o[8];
; #pragma unroll
;             for (int j = 0; j < 8; ++j) { const int q = j >> 1; float y = bb[j];
; #pragma unroll
;                 for (int k = 0; k < 4; ++k) y += w[k][j] * ((j & 1) ? bfhi(xa[i + k][q]) : bflo(xa[i + k][q]));
;                 o[j] = silu_fast(y); }
;             v4u wv; wv.x = pk2(o[0], o[1]); wv.y = pk2(o[2], o[3]); wv.z = pk2(o[4], o[5]); wv.w = pk2(o[6], o[7]);
;             *(v4u*)(X2 + (size_t)(row0 + i) * NC + c0) = wv;
;         }
	v_pk_fma_f32 v[62:63], v[22:23], v[74:75], v[26:27]
	v_pk_mul_f32 v[70:71], v[70:71], v[96:97]
	v_pk_fma_f32 v[62:63], v[34:35], v[72:73], v[62:63]
	s_nop 0
	v_pk_fma_f32 v[74:75], v[38:39], v[66:67], v[62:63]
	v_lshlrev_b32_e32 v63, 16, v61
	v_lshlrev_b32_e32 v62, 16, v60
	v_pk_fma_f32 v[60:61], v[20:21], v[6:7], v[98:99]
	v_pk_fma_f32 v[74:75], v[46:47], v[62:63], v[74:75]
	v_mul_f32_e32 v97, 0xbfb8aa3b, v60
	v_exp_f32_e32 v97, v97
	v_mul_f32_e32 v96, 0xbfb8aa3b, v74
	v_exp_f32_e32 v96, v96
	v_add_f32_e32 v97, 1.0, v97
	v_rcp_f32_e32 v98, v97
	v_mul_f32_e32 v97, 0xbfb8aa3b, v75
	v_exp_f32_e32 v97, v97
	v_add_f32_e32 v96, 1.0, v96
	v_rcp_f32_e32 v96, v96
	v_add_f32_e32 v97, 1.0, v97
	v_rcp_f32_e32 v97, v97
	s_nop 0
	v_pk_mul_f32 v[74:75], v[74:75], v[96:97]
	v_mul_f32_e32 v96, 0xbfb8aa3b, v61
	v_exp_f32_e32 v96, v96
	s_nop 0
	v_add_f32_e32 v96, 1.0, v96
	v_rcp_f32_e32 v99, v96
	s_nop 0
	v_pk_mul_f32 v[60:61], v[60:61], v[98:99]
	s_nop 0
	v_bfe_u32 v96, v61, 16, 1
	v_bfe_u32 v97, v60, 16, 1
	s_nop 3
	v_add3_u32 v60, v60, v97, s16
	v_add3_u32 v61, v61, v96, s16
	s_nop 1
	v_bfe_u32 v98, v74, 16, 1
	v_bfe_u32 v99, v75, 16, 1
	v_add3_u32 v75, v75, v99, s16
	v_add3_u32 v74, v74, v98, s16
	s_nop 3
	v_lshrrev_b32_e32 v74, 16, v74
	v_lshrrev_b32_e32 v75, 16, v75
	v_and_or_b32 v97, v61, s15, v75
	v_and_or_b32 v96, v60, s15, v74
	v_cvt_pk_bf16_f32 v95, v95, v71
	v_cvt_pk_bf16_f32 v94, v94, v70
	v_mad_i64_i32 v[60:61], s[2:3], v115, s17, v[90:91]
	global_store_dwordx4 v[60:61], v[94:97], off
	v_pk_fma_f32 v[60:61], v[78:79], v[76:77], v[80:81]
	v_pk_fma_f32 v[76:77], v[36:37], v[58:59], v[10:11]
	v_pk_fma_f32 v[60:61], v[82:83], v[68:69], v[60:61]
	v_and_b32_e32 v11, 0xffff0000, v55
	v_and_b32_e32 v10, 0xffff0000, v54
	v_pk_fma_f32 v[70:71], v[84:85], v[64:65], v[60:61]
	v_lshlrev_b32_e32 v61, 16, v55
	v_lshlrev_b32_e32 v60, 16, v54
	v_pk_fma_f32 v[54:55], v[40:41], v[10:11], v[76:77]
	v_pk_fma_f32 v[70:71], v[92:93], v[60:61], v[70:71]
	v_mul_f32_e32 v75, 0xbfb8aa3b, v54
	v_exp_f32_e32 v75, v75
	v_mul_f32_e32 v74, 0xbfb8aa3b, v70
	v_exp_f32_e32 v74, v74
	v_pk_fma_f32 v[94:95], v[16:17], v[6:7], v[14:15]
	v_add_f32_e32 v75, 1.0, v75
	v_rcp_f32_e32 v76, v75
	v_mul_f32_e32 v75, 0xbfb8aa3b, v71
	v_exp_f32_e32 v75, v75
	v_add_f32_e32 v74, 1.0, v74
	v_rcp_f32_e32 v74, v74
	v_and_b32_e32 v15, 0xffff0000, v57
	v_add_f32_e32 v75, 1.0, v75
	v_rcp_f32_e32 v75, v75
	v_and_b32_e32 v14, 0xffff0000, v56
	v_pk_fma_f32 v[58:59], v[24:25], v[58:59], v[48:49]
	v_pk_fma_f32 v[6:7], v[8:9], v[6:7], v[32:33]
	v_pk_mul_f32 v[70:71], v[70:71], v[74:75]
	v_mul_f32_e32 v74, 0xbfb8aa3b, v55
	v_exp_f32_e32 v74, v74
	v_pk_fma_f32 v[58:59], v[28:29], v[10:11], v[58:59]
	v_pk_fma_f32 v[6:7], v[12:13], v[14:15], v[6:7]
	v_pk_fma_f32 v[8:9], v[8:9], v[14:15], v[32:33]
	v_add_f32_e32 v74, 1.0, v74
	v_rcp_f32_e32 v77, v74
	s_nop 0
	v_pk_mul_f32 v[74:75], v[54:55], v[76:77]
	v_pk_fma_f32 v[54:55], v[22:23], v[72:73], v[26:27]
	s_nop 0
	v_pk_fma_f32 v[54:55], v[34:35], v[66:67], v[54:55]
	s_nop 0
	v_pk_fma_f32 v[72:73], v[38:39], v[62:63], v[54:55]
	v_lshlrev_b32_e32 v55, 16, v57
	v_lshlrev_b32_e32 v54, 16, v56
	v_pk_fma_f32 v[56:57], v[20:21], v[14:15], v[94:95]
	v_pk_fma_f32 v[72:73], v[46:47], v[54:55], v[72:73]
	v_mul_f32_e32 v77, 0xbfb8aa3b, v56
	v_exp_f32_e32 v77, v77
	v_mul_f32_e32 v76, 0xbfb8aa3b, v72
	v_exp_f32_e32 v76, v76
	v_add_f32_e32 v77, 1.0, v77
	v_rcp_f32_e32 v94, v77
	v_mul_f32_e32 v77, 0xbfb8aa3b, v73
	v_exp_f32_e32 v77, v77
	v_add_f32_e32 v76, 1.0, v76
	v_rcp_f32_e32 v76, v76
	v_add_f32_e32 v77, 1.0, v77
	v_rcp_f32_e32 v77, v77
	s_nop 0
	v_pk_mul_f32 v[72:73], v[72:73], v[76:77]
	v_mul_f32_e32 v76, 0xbfb8aa3b, v57
	v_exp_f32_e32 v76, v76
	s_nop 0
	v_add_f32_e32 v76, 1.0, v76
	v_rcp_f32_e32 v95, v76
	s_nop 0
	v_pk_mul_f32 v[56:57], v[56:57], v[94:95]
	s_nop 0
	v_bfe_u32 v76, v57, 16, 1
	v_bfe_u32 v77, v56, 16, 1
	v_bfe_u32 v94, v75, 16, 1
	s_nop 1
	v_add3_u32 v75, v75, v94, s16
	v_add3_u32 v56, v56, v77, s16
	v_add3_u32 v57, v57, v76, s16
	s_nop 0
	v_bfe_u32 v77, v71, 16, 1
	v_bfe_u32 v94, v72, 16, 1
	v_bfe_u32 v95, v73, 16, 1
	v_add3_u32 v73, v73, v95, s16
	v_add3_u32 v72, v72, v94, s16
	v_add3_u32 v71, v71, v77, s16
	s_nop 1
	v_lshrrev_b32_e32 v71, 16, v71
	v_lshrrev_b32_e32 v72, 16, v72
	v_lshrrev_b32_e32 v73, 16, v73
	v_and_or_b32 v73, v57, s15, v73
	v_and_or_b32 v72, v56, s15, v72
	v_and_or_b32 v71, v75, s15, v71
	v_cvt_pk_bf16_f32 v70, v70, v74
	v_mad_i64_i32 v[56:57], s[2:3], v114, s17, v[90:91]
	global_store_dwordx4 v[56:57], v[70:73], off
	v_pk_fma_f32 v[56:57], v[78:79], v[68:69], v[80:81]
	v_pk_fma_f32 v[74:75], v[16:17], v[14:15], v[30:31]
	v_pk_fma_f32 v[56:57], v[82:83], v[64:65], v[56:57]
	v_pk_fma_f32 v[72:73], v[36:37], v[10:11], v[18:19]
	v_and_b32_e32 v19, 0xffff0000, v51
	v_and_b32_e32 v18, 0xffff0000, v50
	v_pk_fma_f32 v[68:69], v[84:85], v[60:61], v[56:57]
	v_lshlrev_b32_e32 v57, 16, v51
	v_lshlrev_b32_e32 v56, 16, v50
	v_pk_fma_f32 v[50:51], v[40:41], v[18:19], v[72:73]
	v_pk_fma_f32 v[68:69], v[92:93], v[56:57], v[68:69]
	v_mul_f32_e32 v71, 0xbfb8aa3b, v50
	v_exp_f32_e32 v71, v71
	v_mul_f32_e32 v70, 0xbfb8aa3b, v68
	v_exp_f32_e32 v70, v70
	v_and_b32_e32 v31, 0xffff0000, v53
	v_add_f32_e32 v71, 1.0, v71
	v_rcp_f32_e32 v72, v71
	v_mul_f32_e32 v71, 0xbfb8aa3b, v69
	v_exp_f32_e32 v71, v71
	v_add_f32_e32 v70, 1.0, v70
	v_rcp_f32_e32 v70, v70
	v_and_b32_e32 v30, 0xffff0000, v52
	v_add_f32_e32 v71, 1.0, v71
	v_rcp_f32_e32 v71, v71
	v_pk_fma_f32 v[58:59], v[36:37], v[18:19], v[58:59]
	v_pk_fma_f32 v[6:7], v[16:17], v[30:31], v[6:7]
	v_pk_fma_f32 v[10:11], v[24:25], v[10:11], v[48:49]
	v_pk_mul_f32 v[68:69], v[68:69], v[70:71]
	v_mul_f32_e32 v70, 0xbfb8aa3b, v51
; __device__ __forceinline__ unsigned pk2(float lo, float hi) { return f2bf(lo) | (f2bf(hi) << 16); }
; __device__ __forceinline__ float silu_fast(float x) { return x * __builtin_amdgcn_rcpf(1.f + __builtin_amdgcn_exp2f(-1.4426950408889634f * x)); }
; __device__ __forceinline__ void ssd_conv(const Ctx& c, const bf16* P, const float* cw, const float* cb, const float* dtb, bf16* X2, float* DT) {
;     ...
;     for (int it = c.vcu * 512 + c.tid; it < items; it += c.G * 512) {
;         const int rb = it / NCG, cg = it % NCG, c0 = cg * 8, row0 = rb * 8, t0 = row0 & (SEQ - 1);
;         v4u xa[11];
; #pragma unroll
;         for (int i = 0; i < 11; ++i) { const bool ok = (i >= 3) || (t0 != 0); xa[i] = ok ? *(const v4u*)(P + (size_t)(row0 + i - 3) * SSD_NP + 4096 + c0) : (v4u){0u, 0u, 0u, 0u}; }
;         float w[4][8], bb[8];
; #pragma unroll
;         for (int k = 0; k < 4; ++k) { const f32x4 a0 = *(const f32x4*)(cw + k * NC + c0), a1 = *(const f32x4*)(cw + k * NC + c0 + 4);
; #pragma unroll
;             for (int j = 0; j < 4; ++j) { w[k][j] = a0[j]; w[k][4 + j] = a1[j]; } }
;         { const f32x4 a0 = *(const f32x4*)(cb + c0), a1 = *(const f32x4*)(cb + c0 + 4);
; #pragma unroll
;           for (int j = 0; j < 4; ++j) { bb[j] = a0[j]; bb[4 + j] = a1[j]; } }
; #pragma unroll
;         for (int i = 0; i < 8; ++i) {
;             float o[8];
; #pragma unroll
;             for (int j = 0; j < 8; ++j) { const int q = j >> 1; float y = bb[j];
; #pragma unroll
;                 for (int k = 0; k < 4; ++k) y += w[k][j] * ((j & 1) ? bfhi(xa[i + k][q]) : bflo(xa[i + k][q]));
;                 o[j] = silu_fast(y); }
;             v4u wv; wv.x = pk2(o[0], o[1]); wv.y = pk2(o[2], o[3]); wv.z = pk2(o[4], o[5]); wv.w = pk2(o[6], o[7]);
;             *(v4u*)(X2 + (size_t)(row0 + i) * NC + c0) = wv;
;         }
	v_exp_f32_e32 v70, v70
	v_pk_fma_f32 v[10:11], v[28:29], v[18:19], v[10:11]
	v_lshlrev_b32_e32 v19, 16, v5
	v_lshlrev_b32_e32 v18, 16, v4
	v_add_f32_e32 v70, 1.0, v70
	v_rcp_f32_e32 v73, v70
	v_pk_fma_f32 v[8:9], v[12:13], v[30:31], v[8:9]
	v_and_b32_e32 v5, 0xffff0000, v5
	v_and_b32_e32 v4, 0xffff0000, v4
	v_pk_mul_f32 v[70:71], v[50:51], v[72:73]
	v_pk_fma_f32 v[50:51], v[22:23], v[66:67], v[26:27]
	s_nop 0
	v_pk_fma_f32 v[50:51], v[34:35], v[62:63], v[50:51]
	s_nop 0
	v_pk_fma_f32 v[66:67], v[38:39], v[54:55], v[50:51]
	v_lshlrev_b32_e32 v51, 16, v53
	v_lshlrev_b32_e32 v50, 16, v52
	v_pk_fma_f32 v[52:53], v[20:21], v[30:31], v[74:75]
	v_pk_fma_f32 v[66:67], v[46:47], v[50:51], v[66:67]
	v_mul_f32_e32 v73, 0xbfb8aa3b, v52
	v_exp_f32_e32 v73, v73
	v_mul_f32_e32 v72, 0xbfb8aa3b, v66
	v_exp_f32_e32 v72, v72
	v_add_f32_e32 v73, 1.0, v73
	v_rcp_f32_e32 v74, v73
	v_mul_f32_e32 v73, 0xbfb8aa3b, v67
	v_exp_f32_e32 v73, v73
	v_add_f32_e32 v72, 1.0, v72
	v_rcp_f32_e32 v72, v72
	v_add_f32_e32 v73, 1.0, v73
	v_rcp_f32_e32 v73, v73
	s_nop 0
	v_pk_mul_f32 v[66:67], v[66:67], v[72:73]
	v_mul_f32_e32 v72, 0xbfb8aa3b, v53
	v_exp_f32_e32 v72, v72
	s_nop 0
	v_add_f32_e32 v72, 1.0, v72
	v_rcp_f32_e32 v75, v72
	s_nop 0
	v_pk_mul_f32 v[52:53], v[52:53], v[74:75]
	s_nop 0
	v_bfe_u32 v72, v53, 16, 1
	s_nop 0
	v_bfe_u32 v74, v71, 16, 1
	v_bfe_u32 v75, v70, 16, 1
	v_add3_u32 v70, v70, v75, s16
	v_add3_u32 v71, v71, v74, s16
	s_nop 0
	v_add3_u32 v53, v53, v72, s16
	v_bfe_u32 v72, v68, 16, 1
	v_bfe_u32 v73, v69, 16, 1
	s_nop 0
	v_bfe_u32 v75, v67, 16, 1
	v_add3_u32 v67, v67, v75, s16
	s_nop 0
	v_add3_u32 v69, v69, v73, s16
	v_add3_u32 v68, v68, v72, s16
	v_lshrrev_b32_e32 v72, 16, v68
	v_lshrrev_b32_e32 v73, 16, v69
	s_nop 0
	v_lshrrev_b32_e32 v67, 16, v67
	v_and_or_b32 v69, v53, s15, v67
	v_cvt_pk_bf16_f32 v68, v66, v52
	v_and_or_b32 v67, v71, s15, v73
	v_and_or_b32 v66, v70, s15, v72
	v_mad_i64_i32 v[52:53], s[2:3], v113, s17, v[90:91]
	global_store_dwordx4 v[52:53], v[66:69], off
	v_pk_fma_f32 v[52:53], v[78:79], v[64:65], v[80:81]
	v_lshlrev_b32_e32 v65, 16, v43
	v_pk_fma_f32 v[52:53], v[82:83], v[60:61], v[52:53]
	v_lshlrev_b32_e32 v64, 16, v42
	v_pk_fma_f32 v[52:53], v[84:85], v[56:57], v[52:53]
	v_and_b32_e32 v69, 0xffff0000, v43
	v_pk_fma_f32 v[52:53], v[92:93], v[64:65], v[52:53]
	v_and_b32_e32 v68, 0xffff0000, v42
	v_pk_fma_f32 v[42:43], v[40:41], v[68:69], v[58:59]
	v_mul_f32_e32 v59, 0xbfb8aa3b, v53
	v_exp_f32_e32 v59, v59
	v_mul_f32_e32 v58, 0xbfb8aa3b, v42
	v_exp_f32_e32 v58, v58
	v_mul_f32_e32 v66, 0xbfb8aa3b, v52
	v_add_f32_e32 v59, 1.0, v59
	v_rcp_f32_e32 v67, v59
	v_mul_f32_e32 v59, 0xbfb8aa3b, v43
	v_exp_f32_e32 v59, v59
	v_add_f32_e32 v58, 1.0, v58
	v_rcp_f32_e32 v58, v58
	v_exp_f32_e32 v66, v66
	v_add_f32_e32 v59, 1.0, v59
	v_rcp_f32_e32 v59, v59
	v_and_b32_e32 v71, 0xffff0000, v45
	v_add_f32_e32 v66, 1.0, v66
	v_rcp_f32_e32 v66, v66
	v_pk_mul_f32 v[42:43], v[42:43], v[58:59]
	v_pk_fma_f32 v[58:59], v[22:23], v[62:63], v[26:27]
	v_lshlrev_b32_e32 v63, 16, v45
	v_pk_fma_f32 v[58:59], v[34:35], v[54:55], v[58:59]
	v_lshlrev_b32_e32 v62, 16, v44
	v_pk_fma_f32 v[58:59], v[38:39], v[50:51], v[58:59]
	v_and_b32_e32 v70, 0xffff0000, v44
	v_pk_fma_f32 v[58:59], v[46:47], v[62:63], v[58:59]
	v_pk_fma_f32 v[6:7], v[20:21], v[70:71], v[6:7]
	v_mul_f32_e32 v45, 0xbfb8aa3b, v59
	v_exp_f32_e32 v45, v45
	v_pk_mul_f32 v[52:53], v[52:53], v[66:67]
	v_mul_f32_e32 v44, 0xbfb8aa3b, v6
	v_mul_f32_e32 v66, 0xbfb8aa3b, v58
	v_add_f32_e32 v45, 1.0, v45
	v_rcp_f32_e32 v67, v45
	v_mul_f32_e32 v45, 0xbfb8aa3b, v7
	v_exp_f32_e32 v44, v44
	v_exp_f32_e32 v45, v45
	v_exp_f32_e32 v66, v66
	v_pk_fma_f32 v[10:11], v[36:37], v[68:69], v[10:11]
	v_add_f32_e32 v44, 1.0, v44
	v_add_f32_e32 v45, 1.0, v45
	v_add_f32_e32 v66, 1.0, v66
	v_rcp_f32_e32 v44, v44
	v_rcp_f32_e32 v45, v45
	v_rcp_f32_e32 v66, v66
	v_pk_fma_f32 v[8:9], v[16:17], v[70:71], v[8:9]
	v_pk_mul_f32 v[6:7], v[6:7], v[44:45]
	v_pk_mul_f32 v[58:59], v[58:59], v[66:67]
	s_nop 7
	s_nop 7
	s_nop 3
	v_cvt_pk_bf16_f32 v45, v59, v7
	v_cvt_pk_bf16_f32 v44, v58, v6
	v_cvt_pk_bf16_f32 v43, v53, v43
	v_cvt_pk_bf16_f32 v42, v52, v42
	v_mad_i64_i32 v[6:7], s[2:3], v112, s17, v[90:91]
	global_store_dwordx4 v[6:7], v[42:45], off
	v_pk_fma_f32 v[6:7], v[78:79], v[60:61], v[80:81]
	v_pk_fma_f32 v[4:5], v[20:21], v[4:5], v[8:9]
	v_pk_fma_f32 v[6:7], v[82:83], v[56:57], v[6:7]
	v_lshlrev_b32_e32 v43, 16, v3
	v_pk_fma_f32 v[6:7], v[84:85], v[64:65], v[6:7]
	v_lshlrev_b32_e32 v42, 16, v2
	v_pk_fma_f32 v[6:7], v[92:93], v[42:43], v[6:7]
	v_and_b32_e32 v3, 0xffff0000, v3
	v_and_b32_e32 v2, 0xffff0000, v2
	v_pk_fma_f32 v[2:3], v[40:41], v[2:3], v[10:11]
	v_mul_f32_e32 v11, 0xbfb8aa3b, v7
	v_exp_f32_e32 v11, v11
	v_mul_f32_e32 v10, 0xbfb8aa3b, v2
	v_exp_f32_e32 v10, v10
	v_mul_f32_e32 v8, 0xbfb8aa3b, v4
	v_add_f32_e32 v11, 1.0, v11
	v_rcp_f32_e32 v43, v11
	v_mul_f32_e32 v11, 0xbfb8aa3b, v3
	v_exp_f32_e32 v11, v11
	v_add_f32_e32 v10, 1.0, v10
	v_rcp_f32_e32 v10, v10
	v_mul_f32_e32 v42, 0xbfb8aa3b, v6
	v_add_f32_e32 v11, 1.0, v11
	v_rcp_f32_e32 v11, v11
	v_exp_f32_e32 v8, v8
	v_exp_f32_e32 v42, v42
	v_pk_mul_f32 v[2:3], v[2:3], v[10:11]
	v_pk_fma_f32 v[10:11], v[22:23], v[54:55], v[26:27]
	v_add_f32_e32 v8, 1.0, v8
	v_pk_fma_f32 v[10:11], v[34:35], v[50:51], v[10:11]
	v_add_f32_e32 v42, 1.0, v42
	v_pk_fma_f32 v[10:11], v[38:39], v[62:63], v[10:11]
	v_rcp_f32_e32 v8, v8
	v_pk_fma_f32 v[10:11], v[46:47], v[18:19], v[10:11]
	v_rcp_f32_e32 v42, v42
	v_mul_f32_e32 v9, 0xbfb8aa3b, v11
	v_exp_f32_e32 v9, v9
	v_mul_f32_e32 v18, 0xbfb8aa3b, v10
	v_exp_f32_e32 v18, v18
	v_pk_mul_f32 v[6:7], v[6:7], v[42:43]
	v_add_f32_e32 v9, 1.0, v9
	v_rcp_f32_e32 v19, v9
	v_mul_f32_e32 v9, 0xbfb8aa3b, v5
	v_exp_f32_e32 v9, v9
	v_add_f32_e32 v18, 1.0, v18
	v_rcp_f32_e32 v18, v18
	s_nop 0
	v_add_f32_e32 v9, 1.0, v9
	v_rcp_f32_e32 v9, v9
	s_nop 0
	v_pk_mul_f32 v[10:11], v[10:11], v[18:19]
	s_nop 0
	v_pk_mul_f32 v[4:5], v[4:5], v[8:9]
	s_nop 0
	v_bfe_u32 v8, v5, 16, 1
	v_bfe_u32 v9, v4, 16, 1
	v_add3_u32 v4, v4, v9, s16
	v_add3_u32 v5, v5, v8, s16
	s_nop 5
	v_bfe_u32 v12, v10, 16, 1
	v_bfe_u32 v13, v11, 16, 1
	v_cvt_pk_bf16_f32 v3, v7, v3
	v_cvt_pk_bf16_f32 v2, v6, v2
	v_mad_i64_i32 v[6:7], s[2:3], v111, s17, v[90:91]
	v_add3_u32 v11, v11, v13, s16
	v_add3_u32 v10, v10, v12, s16
	s_mov_b32 s2, 0x17ffff
	v_lshrrev_b32_e32 v8, 16, v10
	v_lshrrev_b32_e32 v9, 16, v11
	v_cmp_lt_i32_e32 vcc, s2, v110
	v_and_or_b32 v5, v5, s15, v9
	v_and_or_b32 v4, v4, s15, v8
	s_or_b64 s[10:11], vcc, s[10:11]
	global_store_dwordx4 v[6:7], v[2:5], off
	s_andn2_b64 exec, exec, s[10:11]
	s_cbranch_execz .LBB0_397

; #define LAS __attribute__((address_space(3)))
; __device__ __forceinline__ unsigned pk2(float lo, float hi) { return f2bf(lo) | (f2bf(hi) << 16); }
; #define SSD_LDT(t0_) do { if (w == 0) rdt = DT[((size_t)b * SEQ + (t0_) + lane) * 64 + h]; } while (0)
; __device__ __forceinline__ void ssd_scan_mfma(const Ctx& c, bf16* X2, const float* DT, const float* a_log, const float* dskip, bool do_store) {
;     ...
;             __syncthreads();
; #pragma unroll
;             for (int e = 0; e < 2; ++e) { const int cc = tid + 512 * e;
;                 *(LAS v4u*)(L + SS_B + (cc >> 4) * 272 + (cc & 15) * 16) = rB[e]; *(LAS v4u*)(L + SS_C + (cc >> 4) * 272 + (cc & 15) * 16) = rC[e]; }
;             *(LAS v4u*)(L + SS_XR + (tid >> 3) * 144 + (tid & 7) * 16) = rXR;
;             { const int sr = tid >> 3, p8 = tid & 7; const float fd = DTS[sr], fw = fd * __expf(CS[63] - CS[sr]);
;               float xv[8];
; #pragma unroll
;               for (int j = 0; j < 4; ++j) { xv[2 * j] = bflo(rXR[j]); xv[2 * j + 1] = bfhi(rXR[j]); }
;               v4u o1, o2; o1.x = pk2(xv[0] * fd, xv[1] * fd); o1.y = pk2(xv[2] * fd, xv[3] * fd); o1.z = pk2(xv[4] * fd, xv[5] * fd); o1.w = pk2(xv[6] * fd, xv[7] * fd);
;               o2.x = pk2(xv[0] * fw, xv[1] * fw); o2.y = pk2(xv[2] * fw, xv[3] * fw); o2.z = pk2(xv[4] * fw, xv[5] * fw); o2.w = pk2(xv[6] * fw, xv[7] * fw);
;               *(LAS v4u*)(L + SS_XD + sr * 144 + p8 * 16) = o1; *(LAS v4u*)(L + SS_XW + sr * 144 + p8 * 16) = o2; }
;             if (ch + 1 < SEQ / 64) { SSD_LOAD(t0 + 64); SSD_CS(cb ^ 1); if (ch + 2 < SEQ / 64) SSD_LDT(t0 + 128); }
;             __syncthreads();
;             {
;                 const float csl = CS[16 * lt + l15];
;                 bf16x8 Cf[4];
; #pragma unroll
;                 for (int ks = 0; ks < 4; ++ks) Cf[ks] = *(const LAS bf16x8*)(L + SS_C + (16 * lt + l15) * 272 + (32 * ks + 8 * lg) * 2);
;                 f32x4 GT[4];
; #pragma unroll
;                 for (int st = 0; st < 4; ++st) { GT[st] = (f32x4){0.f, 0.f, 0.f, 0.f};
;                     if (st <= lt) {
; #pragma unroll
;                         for (int ks = 0; ks < 4; ++ks) { const bf16x8 bf = *(const LAS bf16x8*)(L + SS_B + (16 * st + l15) * 272 + (32 * ks + 8 * lg) * 2); GT[st] = __builtin_amdgcn_mfma_f32_16x16x32_bf16(bf, Cf[ks], GT[st], 0, 0, 0); }
;                         const f32x4 css = *(const LAS f32x4*)(CS + 16 * st + 4 * lg);
.LBB0_483:
	s_waitcnt lgkmcnt(0)
	s_barrier
	s_waitcnt vmcnt(6)
	ds_write_b128 v130, v[30:33]
	s_waitcnt vmcnt(5)
	ds_write_b128 v130, v[26:29] offset:17408
	s_waitcnt vmcnt(4)
	ds_write_b128 v131, v[38:41]
	s_waitcnt vmcnt(3)
	ds_write_b128 v131, v[34:37] offset:17408
	s_waitcnt vmcnt(2)
	ds_write_b128 v132, v[22:25] offset:34816
	v_mov_b32_e32 v27, s89
	ds_read_b32 v26, v112 offset:256
	ds_read_b32 v27, v27
	ds_read_b32 v28, v122
	v_lshlrev_b32_e32 v31, 16, v23
	v_lshlrev_b32_e32 v30, 16, v22
	v_and_b32_e32 v23, 0xffff0000, v23
	v_and_b32_e32 v22, 0xffff0000, v22
	s_waitcnt lgkmcnt(0)
	v_sub_f32_e32 v27, v27, v28
	v_mul_f32_e32 v27, 0x3fb8aa3b, v27
	v_exp_f32_e32 v27, v27
	v_and_b32_e32 v41, 0xffff0000, v25
	v_and_b32_e32 v40, 0xffff0000, v24
	v_lshlrev_b32_e32 v39, 16, v25
	v_mul_f32_e32 v28, v26, v27
	v_pk_mul_f32 v[34:35], v[26:27], v[22:23] op_sel_hi:[0,1]
	v_lshlrev_b32_e32 v38, 16, v24
	v_pk_mul_f32 v[24:25], v[26:27], v[40:41] op_sel_hi:[0,1]
	v_pk_mul_f32 v[32:33], v[26:27], v[30:31] op_sel_hi:[0,1]
	v_pk_mul_f32 v[30:31], v[28:29], v[30:31] op_sel_hi:[0,1]
	v_pk_mul_f32 v[36:37], v[28:29], v[22:23] op_sel_hi:[0,1]
	v_pk_mul_f32 v[22:23], v[26:27], v[38:39] op_sel_hi:[0,1]
	s_nop 1
	v_bfe_u32 v29, v35, 16, 1
	s_nop 1
	v_add3_u32 v29, v35, v29, s88
	s_nop 2
	v_bfe_u32 v27, v33, 16, 1
	s_nop 3
	v_add3_u32 v27, v33, v27, s88
	s_nop 1
	v_lshrrev_b32_e32 v27, 16, v27
	s_nop 1
	v_cvt_pk_bf16_f32 v25, v23, v25
	v_cvt_pk_bf16_f32 v24, v22, v24
	v_and_or_b32 v23, v29, s87, v27
	v_cvt_pk_bf16_f32 v22, v32, v34
	v_pk_mul_f32 v[26:27], v[28:29], v[38:39] op_sel_hi:[0,1]
	v_pk_mul_f32 v[28:29], v[28:29], v[40:41] op_sel_hi:[0,1]
	s_nop 1
	v_bfe_u32 v34, v37, 16, 1
	v_bfe_u32 v35, v36, 16, 1
	v_add3_u32 v35, v36, v35, s88
	v_add3_u32 v34, v37, v34, s88
	s_nop 1
	v_bfe_u32 v32, v30, 16, 1
	v_bfe_u32 v33, v31, 16, 1
	s_nop 3
	v_add3_u32 v31, v31, v33, s88
	v_add3_u32 v30, v30, v32, s88
	v_lshrrev_b32_e32 v30, 16, v30
	v_lshrrev_b32_e32 v31, 16, v31
	s_nop 1
	v_cvt_pk_bf16_f32 v29, v27, v29
	v_cvt_pk_bf16_f32 v28, v26, v28
	v_and_or_b32 v27, v34, s87, v31
	v_and_or_b32 v26, v35, s87, v30
	ds_write_b128 v132, v[22:25] offset:44032
	ds_write_b128 v132, v[26:29] offset:53248
	s_waitcnt lgkmcnt(0)
	s_barrier
	ds_read_b32 v50, v123
	ds_read_b128 v[34:37], v139 offset:17408
	ds_read_b128 v[30:33], v139 offset:17472
	ds_read_b128 v[26:29], v139 offset:17536
	ds_read_b128 v[22:25], v139 offset:17600
	ds_read_b128 v[38:41], v133
	ds_read_b128 v[42:45], v133 offset:64
	s_waitcnt lgkmcnt(1)
	v_mfma_f32_16x16x32_bf16 v[38:41], v[38:41], v[34:37], 0
	v_mov_b32_e32 v46, 0
	s_and_b64 vcc, exec, s[54:55]
	v_mov_b32_e32 v47, 0
	s_waitcnt lgkmcnt(0)
	v_mfma_f32_16x16x32_bf16 v[38:41], v[42:45], v[30:33], v[38:41]
	ds_read_b128 v[42:45], v133 offset:128
	v_mov_b32_e32 v48, 0
	v_mov_b32_e32 v49, 0
	s_waitcnt lgkmcnt(0)
	v_mfma_f32_16x16x32_bf16 v[38:41], v[42:45], v[26:29], v[38:41]
	ds_read_b128 v[42:45], v133 offset:192
	v_mov_b32_e32 v51, 0
	s_waitcnt lgkmcnt(0)
	v_mfma_f32_16x16x32_bf16 v[38:41], v[42:45], v[22:25], v[38:41]
	ds_read_b128 v[42:45], v124
	s_cbranch_vccnz .LBB0_485
	ds_read_b128 v[56:59], v133 offset:4352
	ds_read_b128 v[60:63], v133 offset:4416
	s_waitcnt lgkmcnt(1)
	v_mfma_f32_16x16x32_bf16 v[56:59], v[56:59], v[34:37], 0
	s_waitcnt lgkmcnt(0)
	v_mfma_f32_16x16x32_bf16 v[56:59], v[60:63], v[30:33], v[56:59]
	ds_read_b128 v[60:63], v133 offset:4480
	s_waitcnt lgkmcnt(0)
	v_mfma_f32_16x16x32_bf16 v[56:59], v[60:63], v[26:29], v[56:59]
	ds_read_b128 v[60:63], v133 offset:4544
	s_waitcnt lgkmcnt(0)
	v_mfma_f32_16x16x32_bf16 v[56:59], v[60:63], v[22:25], v[56:59]
	ds_read_b128 v[60:63], v124 offset:64
	s_waitcnt lgkmcnt(0)
	v_sub_f32_e32 v47, v50, v60
	v_sub_f32_e32 v48, v50, v61
	v_sub_f32_e32 v49, v50, v62
	v_sub_f32_e32 v51, v50, v63
	v_mul_f32_e32 v47, 0x3fb8aa3b, v47
	v_mul_f32_e32 v48, 0x3fb8aa3b, v48
	v_mul_f32_e32 v49, 0x3fb8aa3b, v49
	v_mul_f32_e32 v51, 0x3fb8aa3b, v51
	v_exp_f32_e32 v47, v47
	v_exp_f32_e32 v48, v48
	v_exp_f32_e32 v49, v49
	v_exp_f32_e32 v51, v51
	v_mul_f32_e32 v47, v56, v47
	v_mul_f32_e32 v48, v57, v48
	v_mul_f32_e32 v49, v58, v49
	v_mul_f32_e32 v51, v59, v51
	v_cndmask_b32_e64 v47, v47, 0, s[24:25]
	v_cndmask_b32_e64 v48, v48, 0, s[26:27]
	v_cndmask_b32_e64 v49, v49, 0, s[28:29]
	v_cndmask_b32_e64 v51, v51, 0, s[30:31]

; __device__ __forceinline__ float siluf_(float x) { return x * sigmoidf_(x); }
; __device__ __forceinline__ void ssd_gnorm(const Ctx& c, bf16* X2, const bf16* P, const float* g) {
;     for (int row = c.gw; row < MT; row += c.NGW) {
;         v4u* yr = (v4u*)(X2 + (size_t)row * 6144) + c.lane; const v4u* zr = (const v4u*)(P + (size_t)row * SSD_NP) + c.lane;
;         float v[8][8]; float s = 0.f;
; #pragma unroll
;         for (int j = 0; j < 8; ++j) { const v4u y = yr[64 * j], z = zr[64 * j];
; #pragma unroll
;             for (int k = 0; k < 4; ++k) { const float a = bflo(y[k]) * siluf_(bflo(z[k])), b = bfhi(y[k]) * siluf_(bfhi(z[k])); v[j][2 * k] = a; v[j][2 * k + 1] = b; s += a * a + b * b; } }
.LBB0_550:
	s_nop 0
	v_lshl_add_u64 v[64:65], s[8:9], 0, v[130:131]
	v_add_co_u32_e32 v134, vcc, 0x23400000, v64
	v_lshl_add_u64 v[66:67], s[6:7], 0, v[130:131]
	s_nop 0
	v_addc_co_u32_e32 v135, vcc, 0, v65, vcc
	v_add_co_u32_e32 v68, vcc, 0xd400000, v66
	global_load_dwordx4 v[120:123], v[134:135], off
	s_nop 0
	v_addc_co_u32_e32 v69, vcc, 0, v67, vcc
	global_load_dwordx4 v[124:127], v[68:69], off
	global_load_dwordx4 v[112:115], v[134:135], off offset:1024
	global_load_dwordx4 v[116:119], v[68:69], off offset:1024
	global_load_dwordx4 v[104:107], v[134:135], off offset:2048
	global_load_dwordx4 v[108:111], v[68:69], off offset:2048
	global_load_dwordx4 v[96:99], v[134:135], off offset:3072
	global_load_dwordx4 v[100:103], v[68:69], off offset:3072
	v_add_co_u32_e32 v132, vcc, s14, v64
	s_add_i32 s19, s19, s86
	s_nop 0
	v_addc_co_u32_e32 v133, vcc, 0, v65, vcc
	v_add_co_u32_e32 v68, vcc, s15, v66
	global_load_dwordx4 v[88:91], v[132:133], off
	s_nop 0
	v_addc_co_u32_e32 v69, vcc, 0, v67, vcc
	global_load_dwordx4 v[92:95], v[68:69], off
	global_load_dwordx4 v[80:83], v[132:133], off offset:1024
	global_load_dwordx4 v[84:87], v[68:69], off offset:1024
	global_load_dwordx4 v[72:75], v[132:133], off offset:2048
	global_load_dwordx4 v[76:79], v[68:69], off offset:2048
	global_load_dwordx4 v[64:67], v[132:133], off offset:3072
	s_nop 0
	global_load_dwordx4 v[68:71], v[68:69], off offset:3072
	s_add_u32 s6, s6, s11
	s_addc_u32 s7, s7, s10
	s_add_u32 s8, s8, s13
	s_addc_u32 s9, s9, s12
	s_cmpk_lt_i32 s19, 0x4000
	s_waitcnt vmcnt(14)
	v_lshlrev_b32_e32 v137, 16, v125
	v_lshlrev_b32_e32 v136, 16, v124
	v_mul_f32_e32 v138, 0xbfb8aa3b, v136
	v_mul_f32_e32 v139, 0xbfb8aa3b, v137
	v_exp_f32_e32 v138, v138
	v_exp_f32_e32 v139, v139
	v_and_b32_e32 v140, 0xffff0000, v124
	v_mul_f32_e32 v124, 0xbfb8aa3b, v140
	v_and_b32_e32 v141, 0xffff0000, v125
	v_pk_add_f32 v[138:139], v[138:139], 1.0 op_sel_hi:[1,0]
	v_exp_f32_e32 v142, v124
	v_div_scale_f32 v143, s[0:1], v139, v139, 1.0
	v_rcp_f32_e32 v144, v143
	v_lshlrev_b32_e32 v125, 16, v121
	v_lshlrev_b32_e32 v124, 16, v120
	v_and_b32_e32 v121, 0xffff0000, v121
	v_fma_f32 v145, -v143, v144, 1.0
	v_fmac_f32_e32 v144, v145, v144
	v_div_scale_f32 v145, vcc, 1.0, v139, 1.0
	v_mul_f32_e32 v146, v145, v144
	v_fma_f32 v147, -v143, v146, v145
	v_fmac_f32_e32 v146, v147, v144
	v_fma_f32 v143, -v143, v146, v145
	v_div_fmas_f32 v143, v143, v144, v146
	v_div_fixup_f32 v139, v143, v139, 1.0
	v_div_scale_f32 v143, s[0:1], v138, v138, 1.0
	v_rcp_f32_e32 v144, v143
	v_and_b32_e32 v120, 0xffff0000, v120
	v_fma_f32 v145, -v143, v144, 1.0
	v_fmac_f32_e32 v144, v145, v144
	v_div_scale_f32 v145, vcc, 1.0, v138, 1.0
	v_mul_f32_e32 v146, v145, v144
	v_fma_f32 v147, -v143, v146, v145
	v_fmac_f32_e32 v146, v147, v144
	v_fma_f32 v143, -v143, v146, v145
	v_div_fmas_f32 v143, v143, v144, v146
	v_div_fixup_f32 v138, v143, v138, 1.0
	v_pk_mul_f32 v[136:137], v[138:139], v[136:137]
	s_nop 0
	v_pk_mul_f32 v[124:125], v[136:137], v[124:125]
	v_mul_f32_e32 v136, 0xbfb8aa3b, v141
	v_exp_f32_e32 v143, v136
	s_nop 0
	v_pk_add_f32 v[136:137], v[142:143], 1.0 op_sel_hi:[1,0]
	s_nop 0
	v_div_scale_f32 v138, s[0:1], v137, v137, 1.0
	v_rcp_f32_e32 v139, v138
	s_nop 0
	v_fma_f32 v142, -v138, v139, 1.0
	v_fmac_f32_e32 v139, v142, v139
	v_div_scale_f32 v142, vcc, 1.0, v137, 1.0
	v_mul_f32_e32 v143, v142, v139
	v_fma_f32 v144, -v138, v143, v142
	v_fmac_f32_e32 v143, v144, v139
	v_fma_f32 v138, -v138, v143, v142
	v_div_fmas_f32 v138, v138, v139, v143
	v_div_fixup_f32 v137, v138, v137, 1.0
	v_div_scale_f32 v138, s[0:1], v136, v136, 1.0
	v_rcp_f32_e32 v139, v138
	s_nop 0
	v_fma_f32 v142, -v138, v139, 1.0
	v_fmac_f32_e32 v139, v142, v139
	v_div_scale_f32 v142, vcc, 1.0, v136, 1.0
	v_mul_f32_e32 v143, v142, v139
	v_fma_f32 v144, -v138, v143, v142
	v_fmac_f32_e32 v143, v144, v139
	v_fma_f32 v138, -v138, v143, v142
	v_div_fmas_f32 v138, v138, v139, v143
	v_div_fixup_f32 v136, v138, v136, 1.0
	v_lshlrev_b32_e32 v143, 16, v127
	v_lshlrev_b32_e32 v142, 16, v126
	v_pk_mul_f32 v[136:137], v[136:137], v[140:141]
	v_mul_f32_e32 v138, 0xbfb8aa3b, v142
	v_mul_f32_e32 v141, 0xbfb8aa3b, v143
	v_exp_f32_e32 v144, v138
	v_exp_f32_e32 v145, v141
	v_and_b32_e32 v139, 0xffff0000, v127
	v_and_b32_e32 v138, 0xffff0000, v126
	v_mul_f32_e32 v126, 0xbfb8aa3b, v138
	v_pk_add_f32 v[144:145], v[144:145], 1.0 op_sel_hi:[1,0]
	v_exp_f32_e32 v140, v126
	v_div_scale_f32 v141, s[0:1], v145, v145, 1.0
	v_rcp_f32_e32 v146, v141
	v_lshlrev_b32_e32 v127, 16, v123
	v_lshlrev_b32_e32 v126, 16, v122
	v_pk_mul_f32 v[120:121], v[136:137], v[120:121]
	v_fma_f32 v147, -v141, v146, 1.0
	v_fmac_f32_e32 v146, v147, v146
	v_div_scale_f32 v147, vcc, 1.0, v145, 1.0
	v_mul_f32_e32 v148, v147, v146
	v_fma_f32 v149, -v141, v148, v147
	v_fmac_f32_e32 v148, v149, v146
	v_fma_f32 v141, -v141, v148, v147
	v_div_fmas_f32 v141, v141, v146, v148
	v_div_fixup_f32 v145, v141, v145, 1.0
	v_div_scale_f32 v141, s[0:1], v144, v144, 1.0
	v_rcp_f32_e32 v146, v141
	v_and_b32_e32 v123, 0xffff0000, v123
	v_and_b32_e32 v122, 0xffff0000, v122
	v_pk_mul_f32 v[136:137], v[120:121], v[120:121]
	v_fma_f32 v147, -v141, v146, 1.0
	v_fmac_f32_e32 v146, v147, v146
	v_div_scale_f32 v147, vcc, 1.0, v144, 1.0
	v_mul_f32_e32 v148, v147, v146
	v_fma_f32 v149, -v141, v148, v147
	v_fmac_f32_e32 v148, v149, v146
	v_fma_f32 v141, -v141, v148, v147
	v_div_fmas_f32 v141, v141, v146, v148
	v_div_fixup_f32 v144, v141, v144, 1.0
	v_mul_f32_e32 v141, 0xbfb8aa3b, v139
	v_exp_f32_e32 v141, v141
	v_pk_mul_f32 v[142:143], v[144:145], v[142:143]
	v_pk_fma_f32 v[136:137], v[124:125], v[124:125], v[136:137]
	v_pk_mul_f32 v[126:127], v[142:143], v[126:127]
	v_pk_add_f32 v[140:141], v[140:141], 1.0 op_sel_hi:[1,0]
	v_add_f32_e32 v136, v136, v137
	v_div_scale_f32 v142, s[0:1], v141, v141, 1.0
	v_rcp_f32_e32 v143, v142
	s_nop 0
	v_fma_f32 v144, -v142, v143, 1.0
	v_fmac_f32_e32 v143, v144, v143
	v_div_scale_f32 v144, vcc, 1.0, v141, 1.0
	v_mul_f32_e32 v145, v144, v143
	v_fma_f32 v146, -v142, v145, v144
	v_fmac_f32_e32 v145, v146, v143
	v_fma_f32 v142, -v142, v145, v144
	v_div_fmas_f32 v142, v142, v143, v145
	v_div_fixup_f32 v141, v142, v141, 1.0
	v_div_scale_f32 v142, s[0:1], v140, v140, 1.0
	v_rcp_f32_e32 v143, v142
	s_nop 0
	v_fma_f32 v144, -v142, v143, 1.0
	v_fmac_f32_e32 v143, v144, v143
	v_div_scale_f32 v144, vcc, 1.0, v140, 1.0
	v_mul_f32_e32 v145, v144, v143
	v_fma_f32 v146, -v142, v145, v144
	v_fmac_f32_e32 v145, v146, v143
	v_fma_f32 v142, -v142, v145, v144
	v_div_fmas_f32 v142, v142, v143, v145
	v_div_fixup_f32 v140, v142, v140, 1.0
	s_waitcnt vmcnt(12)
; __device__ __forceinline__ float siluf_(float x) { return x * sigmoidf_(x); }
; __device__ __forceinline__ void ssd_gnorm(const Ctx& c, bf16* X2, const bf16* P, const float* g) {
;     ...
;         for (int j = 0; j < 8; ++j) { const v4u y = yr[64 * j], z = zr[64 * j];
; #pragma unroll
;             for (int k = 0; k < 4; ++k) { const float a = bflo(y[k]) * siluf_(bflo(z[k])), b = bfhi(y[k]) * siluf_(bfhi(z[k])); v[j][2 * k] = a; v[j][2 * k + 1] = b; s += a * a + b * b; } }
	v_lshlrev_b32_e32 v145, 16, v117
	v_lshlrev_b32_e32 v144, 16, v116
	v_pk_mul_f32 v[138:139], v[140:141], v[138:139]
	v_mul_f32_e32 v140, 0xbfb8aa3b, v144
	v_mul_f32_e32 v143, 0xbfb8aa3b, v145
	v_exp_f32_e32 v146, v140
	v_exp_f32_e32 v147, v143
	v_and_b32_e32 v141, 0xffff0000, v117
	v_and_b32_e32 v140, 0xffff0000, v116
	v_mul_f32_e32 v116, 0xbfb8aa3b, v140
	v_pk_add_f32 v[146:147], v[146:147], 1.0 op_sel_hi:[1,0]
	v_exp_f32_e32 v142, v116
	v_div_scale_f32 v143, s[0:1], v147, v147, 1.0
	v_rcp_f32_e32 v148, v143
	v_lshlrev_b32_e32 v117, 16, v113
	v_lshlrev_b32_e32 v116, 16, v112
	v_pk_mul_f32 v[122:123], v[138:139], v[122:123]
	v_fma_f32 v149, -v143, v148, 1.0
	v_fmac_f32_e32 v148, v149, v148
	v_div_scale_f32 v149, vcc, 1.0, v147, 1.0
	v_mul_f32_e32 v150, v149, v148
	v_fma_f32 v151, -v143, v150, v149
	v_fmac_f32_e32 v150, v151, v148
	v_fma_f32 v143, -v143, v150, v149
	v_div_fmas_f32 v143, v143, v148, v150
	v_div_fixup_f32 v147, v143, v147, 1.0
	v_div_scale_f32 v143, s[0:1], v146, v146, 1.0
	v_rcp_f32_e32 v148, v143
	v_pk_mul_f32 v[138:139], v[122:123], v[122:123]
	v_and_b32_e32 v113, 0xffff0000, v113
	v_and_b32_e32 v112, 0xffff0000, v112
	v_fma_f32 v149, -v143, v148, 1.0
	v_fmac_f32_e32 v148, v149, v148
	v_div_scale_f32 v149, vcc, 1.0, v146, 1.0
	v_mul_f32_e32 v150, v149, v148
	v_fma_f32 v151, -v143, v150, v149
	v_fmac_f32_e32 v150, v151, v148
	v_fma_f32 v143, -v143, v150, v149
	v_div_fmas_f32 v143, v143, v148, v150
	v_div_fixup_f32 v146, v143, v146, 1.0
	v_mul_f32_e32 v143, 0xbfb8aa3b, v141
	v_exp_f32_e32 v143, v143
	v_pk_mul_f32 v[144:145], v[146:147], v[144:145]
	v_pk_fma_f32 v[138:139], v[126:127], v[126:127], v[138:139]
	v_pk_mul_f32 v[116:117], v[144:145], v[116:117]
	v_pk_add_f32 v[142:143], v[142:143], 1.0 op_sel_hi:[1,0]
	v_add_f32_e32 v136, v138, v136
	v_div_scale_f32 v144, s[0:1], v143, v143, 1.0
	v_rcp_f32_e32 v145, v144
	v_add_f32_e32 v136, v139, v136
	v_fma_f32 v146, -v144, v145, 1.0
	v_fmac_f32_e32 v145, v146, v145
	v_div_scale_f32 v146, vcc, 1.0, v143, 1.0
	v_mul_f32_e32 v147, v146, v145
	v_fma_f32 v148, -v144, v147, v146
	v_fmac_f32_e32 v147, v148, v145
	v_fma_f32 v144, -v144, v147, v146
	v_div_fmas_f32 v144, v144, v145, v147
	v_div_fixup_f32 v143, v144, v143, 1.0
	v_div_scale_f32 v144, s[0:1], v142, v142, 1.0
	v_rcp_f32_e32 v145, v144
	s_nop 0
	v_fma_f32 v146, -v144, v145, 1.0
	v_fmac_f32_e32 v145, v146, v145
	v_div_scale_f32 v146, vcc, 1.0, v142, 1.0
	v_mul_f32_e32 v147, v146, v145
	v_fma_f32 v148, -v144, v147, v146
	v_fmac_f32_e32 v147, v148, v145
	v_fma_f32 v144, -v144, v147, v146
	v_div_fmas_f32 v144, v144, v145, v147
	v_div_fixup_f32 v142, v144, v142, 1.0
	v_lshlrev_b32_e32 v147, 16, v119
	v_lshlrev_b32_e32 v146, 16, v118
	v_pk_mul_f32 v[140:141], v[142:143], v[140:141]
	v_mul_f32_e32 v142, 0xbfb8aa3b, v146
	v_mul_f32_e32 v145, 0xbfb8aa3b, v147
	v_exp_f32_e32 v148, v142
	v_exp_f32_e32 v149, v145
	v_and_b32_e32 v143, 0xffff0000, v119
	v_and_b32_e32 v142, 0xffff0000, v118
	v_mul_f32_e32 v118, 0xbfb8aa3b, v142
	v_pk_add_f32 v[148:149], v[148:149], 1.0 op_sel_hi:[1,0]
	v_exp_f32_e32 v144, v118
	v_div_scale_f32 v145, s[0:1], v149, v149, 1.0
	v_rcp_f32_e32 v150, v145
	v_lshlrev_b32_e32 v119, 16, v115
	v_lshlrev_b32_e32 v118, 16, v114
	v_pk_mul_f32 v[112:113], v[140:141], v[112:113]
	v_fma_f32 v151, -v145, v150, 1.0
	v_fmac_f32_e32 v150, v151, v150
	v_div_scale_f32 v151, vcc, 1.0, v149, 1.0
	v_mul_f32_e32 v152, v151, v150
	v_fma_f32 v153, -v145, v152, v151
	v_fmac_f32_e32 v152, v153, v150
	v_fma_f32 v145, -v145, v152, v151
	v_div_fmas_f32 v145, v145, v150, v152
	v_div_fixup_f32 v149, v145, v149, 1.0
	v_div_scale_f32 v145, s[0:1], v148, v148, 1.0
	v_rcp_f32_e32 v150, v145
	v_pk_mul_f32 v[140:141], v[112:113], v[112:113]
	v_and_b32_e32 v115, 0xffff0000, v115
	v_and_b32_e32 v114, 0xffff0000, v114
	v_fma_f32 v151, -v145, v150, 1.0
	v_fmac_f32_e32 v150, v151, v150
	v_div_scale_f32 v151, vcc, 1.0, v148, 1.0
	v_mul_f32_e32 v152, v151, v150
	v_fma_f32 v153, -v145, v152, v151
	v_fmac_f32_e32 v152, v153, v150
	v_fma_f32 v145, -v145, v152, v151
	v_div_fmas_f32 v145, v145, v150, v152
	v_div_fixup_f32 v148, v145, v148, 1.0
	v_mul_f32_e32 v145, 0xbfb8aa3b, v143
	v_exp_f32_e32 v145, v145
	v_pk_mul_f32 v[146:147], v[148:149], v[146:147]
	v_pk_fma_f32 v[140:141], v[116:117], v[116:117], v[140:141]
	v_pk_mul_f32 v[118:119], v[146:147], v[118:119]
	v_pk_add_f32 v[144:145], v[144:145], 1.0 op_sel_hi:[1,0]
	v_add_f32_e32 v136, v140, v136
	v_div_scale_f32 v146, s[0:1], v145, v145, 1.0
	v_rcp_f32_e32 v147, v146
	v_add_f32_e32 v136, v141, v136
	v_fma_f32 v148, -v146, v147, 1.0
	v_fmac_f32_e32 v147, v148, v147
	v_div_scale_f32 v148, vcc, 1.0, v145, 1.0
	v_mul_f32_e32 v149, v148, v147
	v_fma_f32 v150, -v146, v149, v148
	v_fmac_f32_e32 v149, v150, v147
	v_fma_f32 v146, -v146, v149, v148
	v_div_fmas_f32 v146, v146, v147, v149
	v_div_fixup_f32 v145, v146, v145, 1.0
	v_div_scale_f32 v146, s[0:1], v144, v144, 1.0
	v_rcp_f32_e32 v147, v146
	s_nop 0
	v_fma_f32 v148, -v146, v147, 1.0
	v_fmac_f32_e32 v147, v148, v147
	v_div_scale_f32 v148, vcc, 1.0, v144, 1.0
	v_mul_f32_e32 v149, v148, v147
	v_fma_f32 v150, -v146, v149, v148
	v_fmac_f32_e32 v149, v150, v147
	v_fma_f32 v146, -v146, v149, v148
	v_div_fmas_f32 v146, v146, v147, v149
	v_div_fixup_f32 v144, v146, v144, 1.0
	s_waitcnt vmcnt(10)
; __device__ __forceinline__ float siluf_(float x) { return x * sigmoidf_(x); }
; __device__ __forceinline__ void ssd_gnorm(const Ctx& c, bf16* X2, const bf16* P, const float* g) {
;     ...
;         for (int j = 0; j < 8; ++j) { const v4u y = yr[64 * j], z = zr[64 * j];
; #pragma unroll
;             for (int k = 0; k < 4; ++k) { const float a = bflo(y[k]) * siluf_(bflo(z[k])), b = bfhi(y[k]) * siluf_(bfhi(z[k])); v[j][2 * k] = a; v[j][2 * k + 1] = b; s += a * a + b * b; } }
	v_lshlrev_b32_e32 v149, 16, v109
	v_lshlrev_b32_e32 v148, 16, v108
	v_pk_mul_f32 v[142:143], v[144:145], v[142:143]
	v_mul_f32_e32 v144, 0xbfb8aa3b, v148
	v_mul_f32_e32 v147, 0xbfb8aa3b, v149
	v_exp_f32_e32 v150, v144
	v_exp_f32_e32 v151, v147
	v_and_b32_e32 v145, 0xffff0000, v109
	v_and_b32_e32 v144, 0xffff0000, v108
	v_mul_f32_e32 v108, 0xbfb8aa3b, v144
	v_pk_add_f32 v[150:151], v[150:151], 1.0 op_sel_hi:[1,0]
	v_exp_f32_e32 v146, v108
	v_div_scale_f32 v147, s[0:1], v151, v151, 1.0
	v_rcp_f32_e32 v152, v147
	v_lshlrev_b32_e32 v109, 16, v105
	v_lshlrev_b32_e32 v108, 16, v104
	v_pk_mul_f32 v[114:115], v[142:143], v[114:115]
	v_fma_f32 v153, -v147, v152, 1.0
	v_fmac_f32_e32 v152, v153, v152
	v_div_scale_f32 v153, vcc, 1.0, v151, 1.0
	v_mul_f32_e32 v154, v153, v152
	v_fma_f32 v155, -v147, v154, v153
	v_fmac_f32_e32 v154, v155, v152
	v_fma_f32 v147, -v147, v154, v153
	v_div_fmas_f32 v147, v147, v152, v154
	v_div_fixup_f32 v151, v147, v151, 1.0
	v_div_scale_f32 v147, s[0:1], v150, v150, 1.0
	v_rcp_f32_e32 v152, v147
	v_pk_mul_f32 v[142:143], v[114:115], v[114:115]
	v_and_b32_e32 v105, 0xffff0000, v105
	v_and_b32_e32 v104, 0xffff0000, v104
	v_fma_f32 v153, -v147, v152, 1.0
	v_fmac_f32_e32 v152, v153, v152
	v_div_scale_f32 v153, vcc, 1.0, v150, 1.0
	v_mul_f32_e32 v154, v153, v152
	v_fma_f32 v155, -v147, v154, v153
	v_fmac_f32_e32 v154, v155, v152
	v_fma_f32 v147, -v147, v154, v153
	v_div_fmas_f32 v147, v147, v152, v154
	v_div_fixup_f32 v150, v147, v150, 1.0
	v_mul_f32_e32 v147, 0xbfb8aa3b, v145
	v_exp_f32_e32 v147, v147
	v_pk_mul_f32 v[148:149], v[150:151], v[148:149]
	v_pk_fma_f32 v[142:143], v[118:119], v[118:119], v[142:143]
	v_pk_mul_f32 v[108:109], v[148:149], v[108:109]
	v_pk_add_f32 v[146:147], v[146:147], 1.0 op_sel_hi:[1,0]
	v_add_f32_e32 v136, v142, v136
	v_div_scale_f32 v148, s[0:1], v147, v147, 1.0
	v_rcp_f32_e32 v149, v148
	v_add_f32_e32 v136, v143, v136
	v_fma_f32 v150, -v148, v149, 1.0
	v_fmac_f32_e32 v149, v150, v149
	v_div_scale_f32 v150, vcc, 1.0, v147, 1.0
	v_mul_f32_e32 v151, v150, v149
	v_fma_f32 v152, -v148, v151, v150
	v_fmac_f32_e32 v151, v152, v149
	v_fma_f32 v148, -v148, v151, v150
	v_div_fmas_f32 v148, v148, v149, v151
	v_div_fixup_f32 v147, v148, v147, 1.0
	v_div_scale_f32 v148, s[0:1], v146, v146, 1.0
	v_rcp_f32_e32 v149, v148
	s_nop 0
	v_fma_f32 v150, -v148, v149, 1.0
	v_fmac_f32_e32 v149, v150, v149
	v_div_scale_f32 v150, vcc, 1.0, v146, 1.0
	v_mul_f32_e32 v151, v150, v149
	v_fma_f32 v152, -v148, v151, v150
	v_fmac_f32_e32 v151, v152, v149
	v_fma_f32 v148, -v148, v151, v150
	v_div_fmas_f32 v148, v148, v149, v151
	v_div_fixup_f32 v146, v148, v146, 1.0
	v_lshlrev_b32_e32 v151, 16, v111
	v_lshlrev_b32_e32 v150, 16, v110
	v_pk_mul_f32 v[144:145], v[146:147], v[144:145]
	v_mul_f32_e32 v146, 0xbfb8aa3b, v150
	v_mul_f32_e32 v149, 0xbfb8aa3b, v151
	v_exp_f32_e32 v152, v146
	v_exp_f32_e32 v153, v149
	v_and_b32_e32 v147, 0xffff0000, v111
	v_and_b32_e32 v146, 0xffff0000, v110
	v_mul_f32_e32 v110, 0xbfb8aa3b, v146
	v_pk_add_f32 v[152:153], v[152:153], 1.0 op_sel_hi:[1,0]
	v_exp_f32_e32 v148, v110
	v_div_scale_f32 v149, s[0:1], v153, v153, 1.0
	v_rcp_f32_e32 v154, v149
	v_lshlrev_b32_e32 v111, 16, v107
	v_lshlrev_b32_e32 v110, 16, v106
	v_pk_mul_f32 v[104:105], v[144:145], v[104:105]
	v_fma_f32 v155, -v149, v154, 1.0
	v_fmac_f32_e32 v154, v155, v154
	v_div_scale_f32 v155, vcc, 1.0, v153, 1.0
	v_mul_f32_e32 v156, v155, v154
	v_fma_f32 v157, -v149, v156, v155
	v_fmac_f32_e32 v156, v157, v154
	v_fma_f32 v149, -v149, v156, v155
	v_div_fmas_f32 v149, v149, v154, v156
	v_div_fixup_f32 v153, v149, v153, 1.0
	v_div_scale_f32 v149, s[0:1], v152, v152, 1.0
	v_rcp_f32_e32 v154, v149
	v_pk_mul_f32 v[144:145], v[104:105], v[104:105]
	v_and_b32_e32 v107, 0xffff0000, v107
	v_and_b32_e32 v106, 0xffff0000, v106
	v_fma_f32 v155, -v149, v154, 1.0
	v_fmac_f32_e32 v154, v155, v154
	v_div_scale_f32 v155, vcc, 1.0, v152, 1.0
	v_mul_f32_e32 v156, v155, v154
	v_fma_f32 v157, -v149, v156, v155
	v_fmac_f32_e32 v156, v157, v154
	v_fma_f32 v149, -v149, v156, v155
	v_div_fmas_f32 v149, v149, v154, v156
	v_div_fixup_f32 v152, v149, v152, 1.0
	v_mul_f32_e32 v149, 0xbfb8aa3b, v147
	v_exp_f32_e32 v149, v149
	v_pk_mul_f32 v[150:151], v[152:153], v[150:151]
	v_pk_fma_f32 v[144:145], v[108:109], v[108:109], v[144:145]
	v_pk_mul_f32 v[110:111], v[150:151], v[110:111]
	v_pk_add_f32 v[148:149], v[148:149], 1.0 op_sel_hi:[1,0]
	v_add_f32_e32 v136, v144, v136
	v_div_scale_f32 v150, s[0:1], v149, v149, 1.0
	v_rcp_f32_e32 v151, v150
	v_add_f32_e32 v136, v145, v136
	v_fma_f32 v152, -v150, v151, 1.0
	v_fmac_f32_e32 v151, v152, v151
	v_div_scale_f32 v152, vcc, 1.0, v149, 1.0
	v_mul_f32_e32 v153, v152, v151
	v_fma_f32 v154, -v150, v153, v152
	v_fmac_f32_e32 v153, v154, v151
	v_fma_f32 v150, -v150, v153, v152
	v_div_fmas_f32 v150, v150, v151, v153
	v_div_fixup_f32 v149, v150, v149, 1.0
	v_div_scale_f32 v150, s[0:1], v148, v148, 1.0
	v_rcp_f32_e32 v151, v150
	s_nop 0
	v_fma_f32 v152, -v150, v151, 1.0
	v_fmac_f32_e32 v151, v152, v151
	v_div_scale_f32 v152, vcc, 1.0, v148, 1.0
	v_mul_f32_e32 v153, v152, v151
	v_fma_f32 v154, -v150, v153, v152
	v_fmac_f32_e32 v153, v154, v151
	v_fma_f32 v150, -v150, v153, v152
	v_div_fmas_f32 v150, v150, v151, v153
	v_div_fixup_f32 v148, v150, v148, 1.0
	s_waitcnt vmcnt(8)
; __device__ __forceinline__ float siluf_(float x) { return x * sigmoidf_(x); }
; __device__ __forceinline__ void ssd_gnorm(const Ctx& c, bf16* X2, const bf16* P, const float* g) {
;     ...
;         for (int j = 0; j < 8; ++j) { const v4u y = yr[64 * j], z = zr[64 * j];
; #pragma unroll
;             for (int k = 0; k < 4; ++k) { const float a = bflo(y[k]) * siluf_(bflo(z[k])), b = bfhi(y[k]) * siluf_(bfhi(z[k])); v[j][2 * k] = a; v[j][2 * k + 1] = b; s += a * a + b * b; } }
	v_lshlrev_b32_e32 v153, 16, v101
	v_lshlrev_b32_e32 v152, 16, v100
	v_pk_mul_f32 v[146:147], v[148:149], v[146:147]
	v_mul_f32_e32 v148, 0xbfb8aa3b, v152
	v_mul_f32_e32 v151, 0xbfb8aa3b, v153
	v_exp_f32_e32 v154, v148
	v_exp_f32_e32 v155, v151
	v_and_b32_e32 v149, 0xffff0000, v101
	v_and_b32_e32 v148, 0xffff0000, v100
	v_mul_f32_e32 v100, 0xbfb8aa3b, v148
	v_pk_add_f32 v[154:155], v[154:155], 1.0 op_sel_hi:[1,0]
	v_exp_f32_e32 v150, v100
	v_div_scale_f32 v151, s[0:1], v155, v155, 1.0
	v_rcp_f32_e32 v156, v151
	v_lshlrev_b32_e32 v101, 16, v97
	v_lshlrev_b32_e32 v100, 16, v96
	v_pk_mul_f32 v[106:107], v[146:147], v[106:107]
	v_fma_f32 v157, -v151, v156, 1.0
	v_fmac_f32_e32 v156, v157, v156
	v_div_scale_f32 v157, vcc, 1.0, v155, 1.0
	v_mul_f32_e32 v158, v157, v156
	v_fma_f32 v159, -v151, v158, v157
	v_fmac_f32_e32 v158, v159, v156
	v_fma_f32 v151, -v151, v158, v157
	v_div_fmas_f32 v151, v151, v156, v158
	v_div_fixup_f32 v155, v151, v155, 1.0
	v_div_scale_f32 v151, s[0:1], v154, v154, 1.0
	v_rcp_f32_e32 v156, v151
	v_pk_mul_f32 v[146:147], v[106:107], v[106:107]
	v_and_b32_e32 v97, 0xffff0000, v97
	v_and_b32_e32 v96, 0xffff0000, v96
	v_fma_f32 v157, -v151, v156, 1.0
	v_fmac_f32_e32 v156, v157, v156
	v_div_scale_f32 v157, vcc, 1.0, v154, 1.0
	v_mul_f32_e32 v158, v157, v156
	v_fma_f32 v159, -v151, v158, v157
	v_fmac_f32_e32 v158, v159, v156
	v_fma_f32 v151, -v151, v158, v157
	v_div_fmas_f32 v151, v151, v156, v158
	v_div_fixup_f32 v154, v151, v154, 1.0
	v_mul_f32_e32 v151, 0xbfb8aa3b, v149
	v_exp_f32_e32 v151, v151
	v_pk_mul_f32 v[152:153], v[154:155], v[152:153]
	v_pk_fma_f32 v[146:147], v[110:111], v[110:111], v[146:147]
	v_pk_mul_f32 v[100:101], v[152:153], v[100:101]
	v_pk_add_f32 v[150:151], v[150:151], 1.0 op_sel_hi:[1,0]
	v_add_f32_e32 v136, v146, v136
	v_div_scale_f32 v152, s[0:1], v151, v151, 1.0
	v_rcp_f32_e32 v153, v152
	v_add_f32_e32 v136, v147, v136
	v_fma_f32 v154, -v152, v153, 1.0
	v_fmac_f32_e32 v153, v154, v153
	v_div_scale_f32 v154, vcc, 1.0, v151, 1.0
	v_mul_f32_e32 v155, v154, v153
	v_fma_f32 v156, -v152, v155, v154
	v_fmac_f32_e32 v155, v156, v153
	v_fma_f32 v152, -v152, v155, v154
	v_div_fmas_f32 v152, v152, v153, v155
	v_div_fixup_f32 v151, v152, v151, 1.0
	v_div_scale_f32 v152, s[0:1], v150, v150, 1.0
	v_rcp_f32_e32 v153, v152
	s_nop 0
	v_fma_f32 v154, -v152, v153, 1.0
	v_fmac_f32_e32 v153, v154, v153
	v_div_scale_f32 v154, vcc, 1.0, v150, 1.0
	v_mul_f32_e32 v155, v154, v153
	v_fma_f32 v156, -v152, v155, v154
	v_fmac_f32_e32 v155, v156, v153
	v_fma_f32 v152, -v152, v155, v154
	v_div_fmas_f32 v152, v152, v153, v155
	v_div_fixup_f32 v150, v152, v150, 1.0
	v_lshlrev_b32_e32 v155, 16, v103
	v_lshlrev_b32_e32 v154, 16, v102
	v_pk_mul_f32 v[148:149], v[150:151], v[148:149]
	v_mul_f32_e32 v150, 0xbfb8aa3b, v154
	v_mul_f32_e32 v153, 0xbfb8aa3b, v155
	v_exp_f32_e32 v156, v150
	v_exp_f32_e32 v157, v153
	v_and_b32_e32 v151, 0xffff0000, v103
	v_and_b32_e32 v150, 0xffff0000, v102
	v_mul_f32_e32 v102, 0xbfb8aa3b, v150
	v_pk_add_f32 v[156:157], v[156:157], 1.0 op_sel_hi:[1,0]
	v_exp_f32_e32 v152, v102
	v_div_scale_f32 v153, s[0:1], v157, v157, 1.0
	v_rcp_f32_e32 v158, v153
	v_lshlrev_b32_e32 v103, 16, v99
	v_lshlrev_b32_e32 v102, 16, v98
	v_pk_mul_f32 v[96:97], v[148:149], v[96:97]
	v_fma_f32 v159, -v153, v158, 1.0
	v_fmac_f32_e32 v158, v159, v158
	v_div_scale_f32 v159, vcc, 1.0, v157, 1.0
	v_mul_f32_e32 v160, v159, v158
	v_fma_f32 v161, -v153, v160, v159
	v_fmac_f32_e32 v160, v161, v158
	v_fma_f32 v153, -v153, v160, v159
	v_div_fmas_f32 v153, v153, v158, v160
	v_div_fixup_f32 v157, v153, v157, 1.0
	v_div_scale_f32 v153, s[0:1], v156, v156, 1.0
	v_rcp_f32_e32 v158, v153
	v_pk_mul_f32 v[148:149], v[96:97], v[96:97]
	v_and_b32_e32 v99, 0xffff0000, v99
	v_and_b32_e32 v98, 0xffff0000, v98
	v_fma_f32 v159, -v153, v158, 1.0
	v_fmac_f32_e32 v158, v159, v158
	v_div_scale_f32 v159, vcc, 1.0, v156, 1.0
	v_mul_f32_e32 v160, v159, v158
	v_fma_f32 v161, -v153, v160, v159
	v_fmac_f32_e32 v160, v161, v158
	v_fma_f32 v153, -v153, v160, v159
	v_div_fmas_f32 v153, v153, v158, v160
	v_div_fixup_f32 v156, v153, v156, 1.0
	v_mul_f32_e32 v153, 0xbfb8aa3b, v151
	v_exp_f32_e32 v153, v153
	v_pk_mul_f32 v[154:155], v[156:157], v[154:155]
	v_pk_fma_f32 v[148:149], v[100:101], v[100:101], v[148:149]
	v_pk_mul_f32 v[102:103], v[154:155], v[102:103]
	v_pk_add_f32 v[152:153], v[152:153], 1.0 op_sel_hi:[1,0]
	v_add_f32_e32 v136, v148, v136
	v_div_scale_f32 v154, s[0:1], v153, v153, 1.0
	v_rcp_f32_e32 v155, v154
	v_add_f32_e32 v136, v149, v136
	v_fma_f32 v156, -v154, v155, 1.0
	v_fmac_f32_e32 v155, v156, v155
	v_div_scale_f32 v156, vcc, 1.0, v153, 1.0
	v_mul_f32_e32 v157, v156, v155
	v_fma_f32 v158, -v154, v157, v156
	v_fmac_f32_e32 v157, v158, v155
	v_fma_f32 v154, -v154, v157, v156
	v_div_fmas_f32 v154, v154, v155, v157
	v_div_fixup_f32 v153, v154, v153, 1.0
	v_div_scale_f32 v154, s[0:1], v152, v152, 1.0
	v_rcp_f32_e32 v155, v154
	s_nop 0
	v_fma_f32 v156, -v154, v155, 1.0
	v_fmac_f32_e32 v155, v156, v155
	v_div_scale_f32 v156, vcc, 1.0, v152, 1.0
	v_mul_f32_e32 v157, v156, v155
	v_fma_f32 v158, -v154, v157, v156
	v_fmac_f32_e32 v157, v158, v155
	v_fma_f32 v154, -v154, v157, v156
	v_div_fmas_f32 v154, v154, v155, v157
	v_div_fixup_f32 v152, v154, v152, 1.0
	s_waitcnt vmcnt(6)
; __device__ __forceinline__ float siluf_(float x) { return x * sigmoidf_(x); }
; __device__ __forceinline__ void ssd_gnorm(const Ctx& c, bf16* X2, const bf16* P, const float* g) {
;     ...
;         for (int j = 0; j < 8; ++j) { const v4u y = yr[64 * j], z = zr[64 * j];
; #pragma unroll
;             for (int k = 0; k < 4; ++k) { const float a = bflo(y[k]) * siluf_(bflo(z[k])), b = bfhi(y[k]) * siluf_(bfhi(z[k])); v[j][2 * k] = a; v[j][2 * k + 1] = b; s += a * a + b * b; } }
	v_lshlrev_b32_e32 v157, 16, v93
	v_lshlrev_b32_e32 v156, 16, v92
	v_pk_mul_f32 v[150:151], v[152:153], v[150:151]
	v_mul_f32_e32 v152, 0xbfb8aa3b, v156
	v_mul_f32_e32 v155, 0xbfb8aa3b, v157
	v_exp_f32_e32 v158, v152
	v_exp_f32_e32 v159, v155
	v_and_b32_e32 v153, 0xffff0000, v93
	v_and_b32_e32 v152, 0xffff0000, v92
	v_mul_f32_e32 v92, 0xbfb8aa3b, v152
	v_pk_add_f32 v[158:159], v[158:159], 1.0 op_sel_hi:[1,0]
	v_exp_f32_e32 v154, v92
	v_div_scale_f32 v155, s[0:1], v159, v159, 1.0
	v_rcp_f32_e32 v160, v155
	v_lshlrev_b32_e32 v93, 16, v89
	v_lshlrev_b32_e32 v92, 16, v88
	v_pk_mul_f32 v[98:99], v[150:151], v[98:99]
	v_fma_f32 v161, -v155, v160, 1.0
	v_fmac_f32_e32 v160, v161, v160
	v_div_scale_f32 v161, vcc, 1.0, v159, 1.0
	v_mul_f32_e32 v162, v161, v160
	v_fma_f32 v163, -v155, v162, v161
	v_fmac_f32_e32 v162, v163, v160
	v_fma_f32 v155, -v155, v162, v161
	v_div_fmas_f32 v155, v155, v160, v162
	v_div_fixup_f32 v159, v155, v159, 1.0
	v_div_scale_f32 v155, s[0:1], v158, v158, 1.0
	v_rcp_f32_e32 v160, v155
	v_pk_mul_f32 v[150:151], v[98:99], v[98:99]
	v_and_b32_e32 v89, 0xffff0000, v89
	v_and_b32_e32 v88, 0xffff0000, v88
	v_fma_f32 v161, -v155, v160, 1.0
	v_fmac_f32_e32 v160, v161, v160
	v_div_scale_f32 v161, vcc, 1.0, v158, 1.0
	v_mul_f32_e32 v162, v161, v160
	v_fma_f32 v163, -v155, v162, v161
	v_fmac_f32_e32 v162, v163, v160
	v_fma_f32 v155, -v155, v162, v161
	v_div_fmas_f32 v155, v155, v160, v162
	v_div_fixup_f32 v158, v155, v158, 1.0
	v_mul_f32_e32 v155, 0xbfb8aa3b, v153
	v_exp_f32_e32 v155, v155
	v_pk_mul_f32 v[156:157], v[158:159], v[156:157]
	v_pk_fma_f32 v[150:151], v[102:103], v[102:103], v[150:151]
	v_pk_mul_f32 v[92:93], v[156:157], v[92:93]
	v_pk_add_f32 v[154:155], v[154:155], 1.0 op_sel_hi:[1,0]
	v_add_f32_e32 v136, v150, v136
	v_div_scale_f32 v156, s[0:1], v155, v155, 1.0
	v_rcp_f32_e32 v157, v156
	v_add_f32_e32 v136, v151, v136
	v_fma_f32 v158, -v156, v157, 1.0
	v_fmac_f32_e32 v157, v158, v157
	v_div_scale_f32 v158, vcc, 1.0, v155, 1.0
	v_mul_f32_e32 v159, v158, v157
	v_fma_f32 v160, -v156, v159, v158
	v_fmac_f32_e32 v159, v160, v157
	v_fma_f32 v156, -v156, v159, v158
	v_div_fmas_f32 v156, v156, v157, v159
	v_div_fixup_f32 v155, v156, v155, 1.0
	v_div_scale_f32 v156, s[0:1], v154, v154, 1.0
	v_rcp_f32_e32 v157, v156
	s_nop 0
	v_fma_f32 v158, -v156, v157, 1.0
	v_fmac_f32_e32 v157, v158, v157
	v_div_scale_f32 v158, vcc, 1.0, v154, 1.0
	v_mul_f32_e32 v159, v158, v157
	v_fma_f32 v160, -v156, v159, v158
	v_fmac_f32_e32 v159, v160, v157
	v_fma_f32 v156, -v156, v159, v158
	v_div_fmas_f32 v156, v156, v157, v159
	v_div_fixup_f32 v154, v156, v154, 1.0
	v_lshlrev_b32_e32 v159, 16, v95
	v_lshlrev_b32_e32 v158, 16, v94
	v_pk_mul_f32 v[152:153], v[154:155], v[152:153]
	v_mul_f32_e32 v154, 0xbfb8aa3b, v158
	v_mul_f32_e32 v157, 0xbfb8aa3b, v159
	v_exp_f32_e32 v160, v154
	v_exp_f32_e32 v161, v157
	v_and_b32_e32 v155, 0xffff0000, v95
	v_and_b32_e32 v154, 0xffff0000, v94
	v_mul_f32_e32 v94, 0xbfb8aa3b, v154
	v_pk_add_f32 v[160:161], v[160:161], 1.0 op_sel_hi:[1,0]
	v_exp_f32_e32 v156, v94
	v_div_scale_f32 v157, s[0:1], v161, v161, 1.0
	v_rcp_f32_e32 v162, v157
	v_lshlrev_b32_e32 v95, 16, v91
	v_lshlrev_b32_e32 v94, 16, v90
	v_pk_mul_f32 v[88:89], v[152:153], v[88:89]
	v_fma_f32 v163, -v157, v162, 1.0
	v_fmac_f32_e32 v162, v163, v162
	v_div_scale_f32 v163, vcc, 1.0, v161, 1.0
	v_mul_f32_e32 v165, v163, v162
	v_fma_f32 v166, -v157, v165, v163
	v_fmac_f32_e32 v165, v166, v162
	v_fma_f32 v157, -v157, v165, v163
	v_div_fmas_f32 v157, v157, v162, v165
	v_div_fixup_f32 v161, v157, v161, 1.0
	v_div_scale_f32 v157, s[0:1], v160, v160, 1.0
	v_rcp_f32_e32 v162, v157
	v_pk_mul_f32 v[152:153], v[88:89], v[88:89]
	v_and_b32_e32 v91, 0xffff0000, v91
	v_and_b32_e32 v90, 0xffff0000, v90
	v_fma_f32 v163, -v157, v162, 1.0
	v_fmac_f32_e32 v162, v163, v162
	v_div_scale_f32 v163, vcc, 1.0, v160, 1.0
	v_mul_f32_e32 v165, v163, v162
	v_fma_f32 v166, -v157, v165, v163
	v_fmac_f32_e32 v165, v166, v162
	v_fma_f32 v157, -v157, v165, v163
	v_div_fmas_f32 v157, v157, v162, v165
	v_div_fixup_f32 v160, v157, v160, 1.0
	v_mul_f32_e32 v157, 0xbfb8aa3b, v155
	v_exp_f32_e32 v157, v157
	v_pk_mul_f32 v[158:159], v[160:161], v[158:159]
	v_pk_fma_f32 v[152:153], v[92:93], v[92:93], v[152:153]
	v_pk_mul_f32 v[94:95], v[158:159], v[94:95]
	v_pk_add_f32 v[156:157], v[156:157], 1.0 op_sel_hi:[1,0]
	v_add_f32_e32 v136, v152, v136
	v_div_scale_f32 v158, s[0:1], v157, v157, 1.0
	v_rcp_f32_e32 v159, v158
	v_add_f32_e32 v136, v153, v136
	v_fma_f32 v160, -v158, v159, 1.0
	v_fmac_f32_e32 v159, v160, v159
	v_div_scale_f32 v160, vcc, 1.0, v157, 1.0
	v_mul_f32_e32 v161, v160, v159
	v_fma_f32 v162, -v158, v161, v160
	v_fmac_f32_e32 v161, v162, v159
	v_fma_f32 v158, -v158, v161, v160
	v_div_fmas_f32 v158, v158, v159, v161
	v_div_fixup_f32 v157, v158, v157, 1.0
	v_div_scale_f32 v158, s[0:1], v156, v156, 1.0
	v_rcp_f32_e32 v159, v158
	s_nop 0
	v_fma_f32 v160, -v158, v159, 1.0
	v_fmac_f32_e32 v159, v160, v159
	v_div_scale_f32 v160, vcc, 1.0, v156, 1.0
	v_mul_f32_e32 v161, v160, v159
	v_fma_f32 v162, -v158, v161, v160
	v_fmac_f32_e32 v161, v162, v159
	v_fma_f32 v158, -v158, v161, v160
	v_div_fmas_f32 v158, v158, v159, v161
	v_div_fixup_f32 v156, v158, v156, 1.0
	s_waitcnt vmcnt(4)
; __device__ __forceinline__ float siluf_(float x) { return x * sigmoidf_(x); }
; __device__ __forceinline__ void ssd_gnorm(const Ctx& c, bf16* X2, const bf16* P, const float* g) {
;     ...
;         for (int j = 0; j < 8; ++j) { const v4u y = yr[64 * j], z = zr[64 * j];
; #pragma unroll
;             for (int k = 0; k < 4; ++k) { const float a = bflo(y[k]) * siluf_(bflo(z[k])), b = bfhi(y[k]) * siluf_(bfhi(z[k])); v[j][2 * k] = a; v[j][2 * k + 1] = b; s += a * a + b * b; } }
	v_lshlrev_b32_e32 v161, 16, v85
	v_lshlrev_b32_e32 v160, 16, v84
	v_pk_mul_f32 v[154:155], v[156:157], v[154:155]
	v_mul_f32_e32 v156, 0xbfb8aa3b, v160
	v_mul_f32_e32 v159, 0xbfb8aa3b, v161
	v_exp_f32_e32 v162, v156
	v_exp_f32_e32 v163, v159
	v_and_b32_e32 v157, 0xffff0000, v85
	v_and_b32_e32 v156, 0xffff0000, v84
	v_mul_f32_e32 v84, 0xbfb8aa3b, v156
	v_pk_add_f32 v[162:163], v[162:163], 1.0 op_sel_hi:[1,0]
	v_exp_f32_e32 v158, v84
	v_div_scale_f32 v159, s[0:1], v163, v163, 1.0
	v_rcp_f32_e32 v165, v159
	v_lshlrev_b32_e32 v85, 16, v81
	v_lshlrev_b32_e32 v84, 16, v80
	v_pk_mul_f32 v[90:91], v[154:155], v[90:91]
	v_fma_f32 v166, -v159, v165, 1.0
	v_fmac_f32_e32 v165, v166, v165
	v_div_scale_f32 v166, vcc, 1.0, v163, 1.0
	v_mul_f32_e32 v168, v166, v165
	v_fma_f32 v169, -v159, v168, v166
	v_fmac_f32_e32 v168, v169, v165
	v_fma_f32 v159, -v159, v168, v166
	v_div_fmas_f32 v159, v159, v165, v168
	v_div_fixup_f32 v163, v159, v163, 1.0
	v_div_scale_f32 v159, s[0:1], v162, v162, 1.0
	v_rcp_f32_e32 v165, v159
	v_pk_mul_f32 v[154:155], v[90:91], v[90:91]
	v_and_b32_e32 v81, 0xffff0000, v81
	v_and_b32_e32 v80, 0xffff0000, v80
	v_fma_f32 v166, -v159, v165, 1.0
	v_fmac_f32_e32 v165, v166, v165
	v_div_scale_f32 v166, vcc, 1.0, v162, 1.0
	v_mul_f32_e32 v168, v166, v165
	v_fma_f32 v169, -v159, v168, v166
	v_fmac_f32_e32 v168, v169, v165
	v_fma_f32 v159, -v159, v168, v166
	v_div_fmas_f32 v159, v159, v165, v168
	v_div_fixup_f32 v162, v159, v162, 1.0
	v_mul_f32_e32 v159, 0xbfb8aa3b, v157
	v_exp_f32_e32 v159, v159
	v_pk_mul_f32 v[160:161], v[162:163], v[160:161]
	v_pk_fma_f32 v[154:155], v[94:95], v[94:95], v[154:155]
	v_pk_mul_f32 v[84:85], v[160:161], v[84:85]
	v_pk_add_f32 v[158:159], v[158:159], 1.0 op_sel_hi:[1,0]
	v_add_f32_e32 v136, v154, v136
	v_div_scale_f32 v160, s[0:1], v159, v159, 1.0
	v_rcp_f32_e32 v161, v160
	v_add_f32_e32 v136, v155, v136
	v_fma_f32 v162, -v160, v161, 1.0
	v_fmac_f32_e32 v161, v162, v161
	v_div_scale_f32 v162, vcc, 1.0, v159, 1.0
	v_mul_f32_e32 v163, v162, v161
	v_fma_f32 v165, -v160, v163, v162
	v_fmac_f32_e32 v163, v165, v161
	v_fma_f32 v160, -v160, v163, v162
	v_div_fmas_f32 v160, v160, v161, v163
	v_div_fixup_f32 v159, v160, v159, 1.0
	v_div_scale_f32 v160, s[0:1], v158, v158, 1.0
	v_rcp_f32_e32 v161, v160
	s_nop 0
	v_fma_f32 v162, -v160, v161, 1.0
	v_fmac_f32_e32 v161, v162, v161
	v_div_scale_f32 v162, vcc, 1.0, v158, 1.0
	v_mul_f32_e32 v163, v162, v161
	v_fma_f32 v165, -v160, v163, v162
	v_fmac_f32_e32 v163, v165, v161
	v_fma_f32 v160, -v160, v163, v162
	v_div_fmas_f32 v160, v160, v161, v163
	v_div_fixup_f32 v158, v160, v158, 1.0
	v_lshlrev_b32_e32 v163, 16, v87
	v_lshlrev_b32_e32 v162, 16, v86
	v_pk_mul_f32 v[156:157], v[158:159], v[156:157]
	v_mul_f32_e32 v158, 0xbfb8aa3b, v162
	v_mul_f32_e32 v161, 0xbfb8aa3b, v163
	v_exp_f32_e32 v168, v158
	v_exp_f32_e32 v169, v161
	v_and_b32_e32 v159, 0xffff0000, v87
	v_and_b32_e32 v158, 0xffff0000, v86
	v_mul_f32_e32 v86, 0xbfb8aa3b, v158
	v_pk_add_f32 v[168:169], v[168:169], 1.0 op_sel_hi:[1,0]
	v_exp_f32_e32 v160, v86
	v_div_scale_f32 v161, s[0:1], v169, v169, 1.0
	v_rcp_f32_e32 v165, v161
	v_lshlrev_b32_e32 v87, 16, v83
	v_lshlrev_b32_e32 v86, 16, v82
	v_pk_mul_f32 v[80:81], v[156:157], v[80:81]
	v_fma_f32 v166, -v161, v165, 1.0
	v_fmac_f32_e32 v165, v166, v165
	v_div_scale_f32 v166, vcc, 1.0, v169, 1.0
	v_mul_f32_e32 v170, v166, v165
	v_fma_f32 v171, -v161, v170, v166
	v_fmac_f32_e32 v170, v171, v165
	v_fma_f32 v161, -v161, v170, v166
	v_div_fmas_f32 v161, v161, v165, v170
	v_div_fixup_f32 v169, v161, v169, 1.0
	v_div_scale_f32 v161, s[0:1], v168, v168, 1.0
	v_rcp_f32_e32 v165, v161
	v_pk_mul_f32 v[156:157], v[80:81], v[80:81]
	v_and_b32_e32 v83, 0xffff0000, v83
	v_and_b32_e32 v82, 0xffff0000, v82
	v_fma_f32 v166, -v161, v165, 1.0
	v_fmac_f32_e32 v165, v166, v165
	v_div_scale_f32 v166, vcc, 1.0, v168, 1.0
	v_mul_f32_e32 v170, v166, v165
	v_fma_f32 v171, -v161, v170, v166
	v_fmac_f32_e32 v170, v171, v165
	v_fma_f32 v161, -v161, v170, v166
	v_div_fmas_f32 v161, v161, v165, v170
	v_div_fixup_f32 v168, v161, v168, 1.0
	v_mul_f32_e32 v161, 0xbfb8aa3b, v159
	v_exp_f32_e32 v161, v161
	v_pk_mul_f32 v[162:163], v[168:169], v[162:163]
	s_waitcnt vmcnt(2)
	v_lshlrev_b32_e32 v169, 16, v77
	v_pk_mul_f32 v[86:87], v[162:163], v[86:87]
	v_pk_add_f32 v[160:161], v[160:161], 1.0 op_sel_hi:[1,0]
	v_pk_fma_f32 v[156:157], v[84:85], v[84:85], v[156:157]
	v_div_scale_f32 v162, s[0:1], v161, v161, 1.0
	v_rcp_f32_e32 v163, v162
	v_add_f32_e32 v136, v156, v136
	v_add_f32_e32 v136, v157, v136
	v_fma_f32 v165, -v162, v163, 1.0
	v_fmac_f32_e32 v163, v165, v163
	v_div_scale_f32 v165, vcc, 1.0, v161, 1.0
	v_mul_f32_e32 v166, v165, v163
	v_fma_f32 v168, -v162, v166, v165
	v_fmac_f32_e32 v166, v168, v163
	v_fma_f32 v162, -v162, v166, v165
	v_div_fmas_f32 v162, v162, v163, v166
	v_div_fixup_f32 v161, v162, v161, 1.0
	v_div_scale_f32 v162, s[0:1], v160, v160, 1.0
	v_rcp_f32_e32 v163, v162
	s_nop 0
	v_fma_f32 v165, -v162, v163, 1.0
	v_fmac_f32_e32 v163, v165, v163
	v_div_scale_f32 v165, vcc, 1.0, v160, 1.0
	v_mul_f32_e32 v166, v165, v163
	v_fma_f32 v168, -v162, v166, v165
	v_fmac_f32_e32 v166, v168, v163
	v_fma_f32 v162, -v162, v166, v165
	v_div_fmas_f32 v162, v162, v163, v166
	v_div_fixup_f32 v160, v162, v160, 1.0
	v_lshlrev_b32_e32 v168, 16, v76
	v_pk_mul_f32 v[158:159], v[160:161], v[158:159]
	v_mul_f32_e32 v160, 0xbfb8aa3b, v168
	v_mul_f32_e32 v163, 0xbfb8aa3b, v169
	v_exp_f32_e32 v170, v160
	v_exp_f32_e32 v171, v163
	v_and_b32_e32 v161, 0xffff0000, v77
	v_and_b32_e32 v160, 0xffff0000, v76
	v_mul_f32_e32 v76, 0xbfb8aa3b, v160
	v_pk_add_f32 v[170:171], v[170:171], 1.0 op_sel_hi:[1,0]
	v_exp_f32_e32 v162, v76
; __device__ __forceinline__ float siluf_(float x) { return x * sigmoidf_(x); }
; __device__ __forceinline__ void ssd_gnorm(const Ctx& c, bf16* X2, const bf16* P, const float* g) {
;     ...
;         for (int j = 0; j < 8; ++j) { const v4u y = yr[64 * j], z = zr[64 * j];
; #pragma unroll
;             for (int k = 0; k < 4; ++k) { const float a = bflo(y[k]) * siluf_(bflo(z[k])), b = bfhi(y[k]) * siluf_(bfhi(z[k])); v[j][2 * k] = a; v[j][2 * k + 1] = b; s += a * a + b * b; } }
	v_div_scale_f32 v163, s[0:1], v171, v171, 1.0
	v_rcp_f32_e32 v165, v163
	v_lshlrev_b32_e32 v77, 16, v73
	v_lshlrev_b32_e32 v76, 16, v72
	v_pk_mul_f32 v[82:83], v[158:159], v[82:83]
	v_fma_f32 v166, -v163, v165, 1.0
	v_fmac_f32_e32 v165, v166, v165
	v_div_scale_f32 v166, vcc, 1.0, v171, 1.0
	v_mul_f32_e32 v172, v166, v165
	v_fma_f32 v173, -v163, v172, v166
	v_fmac_f32_e32 v172, v173, v165
	v_fma_f32 v163, -v163, v172, v166
	v_div_fmas_f32 v163, v163, v165, v172
	v_div_fixup_f32 v171, v163, v171, 1.0
	v_div_scale_f32 v163, s[0:1], v170, v170, 1.0
	v_rcp_f32_e32 v165, v163
	v_pk_mul_f32 v[158:159], v[82:83], v[82:83]
	v_and_b32_e32 v73, 0xffff0000, v73
	v_and_b32_e32 v72, 0xffff0000, v72
	v_fma_f32 v166, -v163, v165, 1.0
	v_fmac_f32_e32 v165, v166, v165
	v_div_scale_f32 v166, vcc, 1.0, v170, 1.0
	v_mul_f32_e32 v172, v166, v165
	v_fma_f32 v173, -v163, v172, v166
	v_fmac_f32_e32 v172, v173, v165
	v_fma_f32 v163, -v163, v172, v166
	v_div_fmas_f32 v163, v163, v165, v172
	v_div_fixup_f32 v170, v163, v170, 1.0
	v_mul_f32_e32 v163, 0xbfb8aa3b, v161
	v_exp_f32_e32 v163, v163
	v_pk_mul_f32 v[168:169], v[170:171], v[168:169]
	v_lshlrev_b32_e32 v171, 16, v79
	v_pk_mul_f32 v[76:77], v[168:169], v[76:77]
	v_pk_add_f32 v[162:163], v[162:163], 1.0 op_sel_hi:[1,0]
	v_pk_fma_f32 v[158:159], v[86:87], v[86:87], v[158:159]
	v_div_scale_f32 v165, s[0:1], v163, v163, 1.0
	v_rcp_f32_e32 v166, v165
	v_add_f32_e32 v136, v158, v136
	v_add_f32_e32 v136, v159, v136
	v_fma_f32 v168, -v165, v166, 1.0
	v_fmac_f32_e32 v166, v168, v166
	v_div_scale_f32 v168, vcc, 1.0, v163, 1.0
	v_mul_f32_e32 v169, v168, v166
	v_fma_f32 v170, -v165, v169, v168
	v_fmac_f32_e32 v169, v170, v166
	v_fma_f32 v165, -v165, v169, v168
	v_div_fmas_f32 v165, v165, v166, v169
	v_div_fixup_f32 v163, v165, v163, 1.0
	v_div_scale_f32 v165, s[0:1], v162, v162, 1.0
	v_rcp_f32_e32 v166, v165
	s_nop 0
	v_fma_f32 v168, -v165, v166, 1.0
	v_fmac_f32_e32 v166, v168, v166
	v_div_scale_f32 v168, vcc, 1.0, v162, 1.0
	v_mul_f32_e32 v169, v168, v166
	v_fma_f32 v170, -v165, v169, v168
	v_fmac_f32_e32 v169, v170, v166
	v_fma_f32 v165, -v165, v169, v168
	v_div_fmas_f32 v165, v165, v166, v169
	v_div_fixup_f32 v162, v165, v162, 1.0
	v_lshlrev_b32_e32 v170, 16, v78
	v_pk_mul_f32 v[160:161], v[162:163], v[160:161]
	v_mul_f32_e32 v162, 0xbfb8aa3b, v170
	v_mul_f32_e32 v165, 0xbfb8aa3b, v171
	v_exp_f32_e32 v172, v162
	v_exp_f32_e32 v173, v165
	v_and_b32_e32 v163, 0xffff0000, v79
	v_and_b32_e32 v162, 0xffff0000, v78
	v_mul_f32_e32 v78, 0xbfb8aa3b, v162
	v_pk_add_f32 v[172:173], v[172:173], 1.0 op_sel_hi:[1,0]
	v_exp_f32_e32 v168, v78
	v_div_scale_f32 v165, s[0:1], v173, v173, 1.0
	v_rcp_f32_e32 v166, v165
	v_lshlrev_b32_e32 v79, 16, v75
	v_lshlrev_b32_e32 v78, 16, v74
	v_pk_mul_f32 v[72:73], v[160:161], v[72:73]
	v_fma_f32 v169, -v165, v166, 1.0
	v_fmac_f32_e32 v166, v169, v166
	v_div_scale_f32 v169, vcc, 1.0, v173, 1.0
	v_mul_f32_e32 v180, v169, v166
	v_fma_f32 v181, -v165, v180, v169
	v_fmac_f32_e32 v180, v181, v166
	v_fma_f32 v165, -v165, v180, v169
	v_div_fmas_f32 v165, v165, v166, v180
	v_div_fixup_f32 v173, v165, v173, 1.0
	v_div_scale_f32 v165, s[0:1], v172, v172, 1.0
	v_rcp_f32_e32 v166, v165
	v_pk_mul_f32 v[160:161], v[72:73], v[72:73]
	v_and_b32_e32 v75, 0xffff0000, v75
	v_and_b32_e32 v74, 0xffff0000, v74
	v_fma_f32 v169, -v165, v166, 1.0
	v_fmac_f32_e32 v166, v169, v166
	v_div_scale_f32 v169, vcc, 1.0, v172, 1.0
	v_mul_f32_e32 v180, v169, v166
	v_fma_f32 v181, -v165, v180, v169
	v_fmac_f32_e32 v180, v181, v166
	v_fma_f32 v165, -v165, v180, v169
	v_div_fmas_f32 v165, v165, v166, v180
	v_div_fixup_f32 v172, v165, v172, 1.0
	v_mul_f32_e32 v165, 0xbfb8aa3b, v163
	v_exp_f32_e32 v169, v165
	v_pk_mul_f32 v[170:171], v[172:173], v[170:171]
	s_waitcnt vmcnt(0)
	v_lshlrev_b32_e32 v173, 16, v69
	v_pk_mul_f32 v[78:79], v[170:171], v[78:79]
	v_pk_add_f32 v[168:169], v[168:169], 1.0 op_sel_hi:[1,0]
	v_pk_fma_f32 v[160:161], v[76:77], v[76:77], v[160:161]
	v_div_scale_f32 v165, s[0:1], v169, v169, 1.0
	v_rcp_f32_e32 v166, v165
	v_add_f32_e32 v136, v160, v136
	v_add_f32_e32 v136, v161, v136
	v_fma_f32 v170, -v165, v166, 1.0
	v_fmac_f32_e32 v166, v170, v166
	v_div_scale_f32 v170, vcc, 1.0, v169, 1.0
	v_mul_f32_e32 v171, v170, v166
	v_fma_f32 v172, -v165, v171, v170
	v_fmac_f32_e32 v171, v172, v166
	v_fma_f32 v165, -v165, v171, v170
	v_div_fmas_f32 v165, v165, v166, v171
	v_div_fixup_f32 v169, v165, v169, 1.0
	v_div_scale_f32 v165, s[0:1], v168, v168, 1.0
	v_rcp_f32_e32 v166, v165
	s_nop 0
	v_fma_f32 v170, -v165, v166, 1.0
	v_fmac_f32_e32 v166, v170, v166
	v_div_scale_f32 v170, vcc, 1.0, v168, 1.0
	v_mul_f32_e32 v171, v170, v166
	v_fma_f32 v172, -v165, v171, v170
	v_fmac_f32_e32 v171, v172, v166
	v_fma_f32 v165, -v165, v171, v170
	v_div_fmas_f32 v165, v165, v166, v171
	v_lshlrev_b32_e32 v172, 16, v68
	v_div_fixup_f32 v168, v165, v168, 1.0
	v_mul_f32_e32 v165, 0xbfb8aa3b, v172
	v_exp_f32_e32 v180, v165
	v_mul_f32_e32 v165, 0xbfb8aa3b, v173
	v_exp_f32_e32 v181, v165
	v_pk_mul_f32 v[162:163], v[168:169], v[162:163]
	v_and_b32_e32 v169, 0xffff0000, v69
	v_and_b32_e32 v168, 0xffff0000, v68
	v_pk_add_f32 v[180:181], v[180:181], 1.0 op_sel_hi:[1,0]
	v_mul_f32_e32 v68, 0xbfb8aa3b, v168
	v_div_scale_f32 v165, s[0:1], v181, v181, 1.0
	v_rcp_f32_e32 v166, v165
	v_exp_f32_e32 v170, v68
	v_lshlrev_b32_e32 v69, 16, v65
	v_lshlrev_b32_e32 v68, 16, v64
	v_fma_f32 v171, -v165, v166, 1.0
	v_fmac_f32_e32 v166, v171, v166
	v_div_scale_f32 v171, vcc, 1.0, v181, 1.0
	v_mul_f32_e32 v182, v171, v166
	v_fma_f32 v183, -v165, v182, v171
	v_fmac_f32_e32 v182, v183, v166
	v_fma_f32 v165, -v165, v182, v171
	v_div_fmas_f32 v165, v165, v166, v182
; __device__ __forceinline__ float siluf_(float x) { return x * sigmoidf_(x); }
; __device__ __forceinline__ void ssd_gnorm(const Ctx& c, bf16* X2, const bf16* P, const float* g) {
;     ...
;         for (int j = 0; j < 8; ++j) { const v4u y = yr[64 * j], z = zr[64 * j];
; #pragma unroll
;             for (int k = 0; k < 4; ++k) { const float a = bflo(y[k]) * siluf_(bflo(z[k])), b = bfhi(y[k]) * siluf_(bfhi(z[k])); v[j][2 * k] = a; v[j][2 * k + 1] = b; s += a * a + b * b; } }
;         const float rs = rsqrtf(wave_sum(s) * (1.f / 4096.f) + EPS);
	v_div_fixup_f32 v181, v165, v181, 1.0
	v_div_scale_f32 v165, s[0:1], v180, v180, 1.0
	v_rcp_f32_e32 v166, v165
	v_pk_mul_f32 v[74:75], v[162:163], v[74:75]
	v_and_b32_e32 v65, 0xffff0000, v65
	v_pk_mul_f32 v[162:163], v[74:75], v[74:75]
	v_fma_f32 v171, -v165, v166, 1.0
	v_fmac_f32_e32 v166, v171, v166
	v_div_scale_f32 v171, vcc, 1.0, v180, 1.0
	v_mul_f32_e32 v182, v171, v166
	v_fma_f32 v183, -v165, v182, v171
	v_fmac_f32_e32 v182, v183, v166
	v_fma_f32 v165, -v165, v182, v171
	v_div_fmas_f32 v165, v165, v166, v182
	v_div_fixup_f32 v180, v165, v180, 1.0
	v_mul_f32_e32 v165, 0xbfb8aa3b, v169
	v_exp_f32_e32 v171, v165
	v_pk_mul_f32 v[172:173], v[180:181], v[172:173]
	v_lshlrev_b32_e32 v181, 16, v71
	v_pk_mul_f32 v[68:69], v[172:173], v[68:69]
	v_pk_add_f32 v[170:171], v[170:171], 1.0 op_sel_hi:[1,0]
	v_and_b32_e32 v64, 0xffff0000, v64
	v_div_scale_f32 v165, s[0:1], v171, v171, 1.0
	v_rcp_f32_e32 v166, v165
	v_pk_fma_f32 v[162:163], v[78:79], v[78:79], v[162:163]
	v_fma_f32 v172, -v165, v166, 1.0
	v_fmac_f32_e32 v166, v172, v166
	v_div_scale_f32 v172, vcc, 1.0, v171, 1.0
	v_mul_f32_e32 v173, v172, v166
	v_fma_f32 v180, -v165, v173, v172
	v_fmac_f32_e32 v173, v180, v166
	v_fma_f32 v165, -v165, v173, v172
	v_div_fmas_f32 v165, v165, v166, v173
	v_div_fixup_f32 v171, v165, v171, 1.0
	v_div_scale_f32 v165, s[0:1], v170, v170, 1.0
	v_rcp_f32_e32 v166, v165
	v_add_f32_e32 v136, v162, v136
	v_add_f32_e32 v136, v163, v136
	v_fma_f32 v172, -v165, v166, 1.0
	v_fmac_f32_e32 v166, v172, v166
	v_div_scale_f32 v172, vcc, 1.0, v170, 1.0
	v_mul_f32_e32 v173, v172, v166
	v_fma_f32 v180, -v165, v173, v172
	v_fmac_f32_e32 v173, v180, v166
	v_fma_f32 v165, -v165, v173, v172
	v_div_fmas_f32 v165, v165, v166, v173
	v_lshlrev_b32_e32 v180, 16, v70
	v_div_fixup_f32 v170, v165, v170, 1.0
	v_mul_f32_e32 v165, 0xbfb8aa3b, v180
	v_exp_f32_e32 v182, v165
	v_mul_f32_e32 v165, 0xbfb8aa3b, v181
	v_exp_f32_e32 v183, v165
	v_pk_mul_f32 v[168:169], v[170:171], v[168:169]
	v_and_b32_e32 v171, 0xffff0000, v71
	v_and_b32_e32 v170, 0xffff0000, v70
	v_pk_add_f32 v[182:183], v[182:183], 1.0 op_sel_hi:[1,0]
	v_mul_f32_e32 v70, 0xbfb8aa3b, v170
	v_div_scale_f32 v165, s[0:1], v183, v183, 1.0
	v_rcp_f32_e32 v166, v165
	v_exp_f32_e32 v172, v70
	v_lshlrev_b32_e32 v71, 16, v67
	v_lshlrev_b32_e32 v70, 16, v66
	v_fma_f32 v173, -v165, v166, 1.0
	v_fmac_f32_e32 v166, v173, v166
	v_div_scale_f32 v173, vcc, 1.0, v183, 1.0
	v_mul_f32_e32 v184, v173, v166
	v_fma_f32 v185, -v165, v184, v173
	v_fmac_f32_e32 v184, v185, v166
	v_fma_f32 v165, -v165, v184, v173
	v_div_fmas_f32 v165, v165, v166, v184
	v_div_fixup_f32 v183, v165, v183, 1.0
	v_div_scale_f32 v165, s[0:1], v182, v182, 1.0
	v_rcp_f32_e32 v166, v165
	v_pk_mul_f32 v[64:65], v[168:169], v[64:65]
	v_and_b32_e32 v67, 0xffff0000, v67
	v_pk_mul_f32 v[168:169], v[64:65], v[64:65]
	v_fma_f32 v173, -v165, v166, 1.0
	v_fmac_f32_e32 v166, v173, v166
	v_div_scale_f32 v173, vcc, 1.0, v182, 1.0
	v_mul_f32_e32 v184, v173, v166
	v_fma_f32 v185, -v165, v184, v173
	v_fmac_f32_e32 v184, v185, v166
	v_fma_f32 v165, -v165, v184, v173
	v_div_fmas_f32 v165, v165, v166, v184
	v_div_fixup_f32 v182, v165, v182, 1.0
	v_mul_f32_e32 v165, 0xbfb8aa3b, v171
	v_exp_f32_e32 v173, v165
	v_pk_mul_f32 v[180:181], v[182:183], v[180:181]
	v_and_b32_e32 v66, 0xffff0000, v66
	v_pk_mul_f32 v[70:71], v[180:181], v[70:71]
	v_pk_add_f32 v[172:173], v[172:173], 1.0 op_sel_hi:[1,0]
	v_pk_fma_f32 v[168:169], v[68:69], v[68:69], v[168:169]
	v_div_scale_f32 v165, s[0:1], v173, v173, 1.0
	v_rcp_f32_e32 v166, v165
	v_add_f32_e32 v136, v168, v136
	v_add_f32_e32 v136, v169, v136
	v_fma_f32 v180, -v165, v166, 1.0
	v_fmac_f32_e32 v166, v180, v166
	v_div_scale_f32 v180, vcc, 1.0, v173, 1.0
	v_mul_f32_e32 v181, v180, v166
	v_fma_f32 v182, -v165, v181, v180
	v_fmac_f32_e32 v181, v182, v166
	v_fma_f32 v165, -v165, v181, v180
	v_div_fmas_f32 v165, v165, v166, v181
	v_div_fixup_f32 v173, v165, v173, 1.0
	v_div_scale_f32 v165, s[0:1], v172, v172, 1.0
	v_rcp_f32_e32 v166, v165
	s_nop 0
	v_fma_f32 v180, -v165, v166, 1.0
	v_fmac_f32_e32 v166, v180, v166
	v_div_scale_f32 v180, vcc, 1.0, v172, 1.0
	v_mul_f32_e32 v181, v180, v166
	v_fma_f32 v182, -v165, v181, v180
	v_fmac_f32_e32 v181, v182, v166
	v_fma_f32 v165, -v165, v181, v180
	v_div_fmas_f32 v165, v165, v166, v181
	v_div_fixup_f32 v172, v165, v172, 1.0
	v_pk_mul_f32 v[170:171], v[172:173], v[170:171]
	s_nop 0
	v_pk_mul_f32 v[66:67], v[170:171], v[66:67]
	s_nop 0
	v_pk_mul_f32 v[170:171], v[66:67], v[66:67]
	s_nop 0
	v_pk_fma_f32 v[170:171], v[70:71], v[70:71], v[170:171]
	s_nop 0
	v_add_f32_e32 v136, v170, v136
	v_add_f32_e32 v136, v171, v136
	ds_bpermute_b32 v137, v174, v136
	s_waitcnt lgkmcnt(0)
	v_add_f32_e32 v136, v136, v137
	ds_bpermute_b32 v137, v175, v136
	s_waitcnt lgkmcnt(0)
	v_add_f32_e32 v136, v136, v137
	ds_bpermute_b32 v137, v176, v136
	s_waitcnt lgkmcnt(0)
	v_add_f32_e32 v136, v136, v137
	ds_bpermute_b32 v137, v177, v136
	s_waitcnt lgkmcnt(0)
	v_add_f32_e32 v136, v136, v137
	ds_bpermute_b32 v137, v178, v136
	s_waitcnt lgkmcnt(0)
	v_add_f32_e32 v136, v136, v137
	ds_bpermute_b32 v137, v179, v136
	s_waitcnt lgkmcnt(0)
; __device__ __forceinline__ unsigned pk2(float lo, float hi) { return f2bf(lo) | (f2bf(hi) << 16); }
; __device__ __forceinline__ void ssd_gnorm(const Ctx& c, bf16* X2, const bf16* P, const float* g) {
;     ...
;         const float rs = rsqrtf(wave_sum(s) * (1.f / 4096.f) + EPS);
; #pragma unroll
;         for (int j = 0; j < 8; ++j) { const float* gg = g + (c.lane + 64 * j) * 8; const f32x4 g0 = *(CF4)gg, g1 = *(CF4)(gg + 4);
;             v4u w; w.x = pk2(v[j][0] * rs * g0.x, v[j][1] * rs * g0.y); w.y = pk2(v[j][2] * rs * g0.z, v[j][3] * rs * g0.w); w.z = pk2(v[j][4] * rs * g1.x, v[j][5] * rs * g1.y); w.w = pk2(v[j][6] * rs * g1.z, v[j][7] * rs * g1.w);
;             yr[64 * j] = w; }
	v_add_f32_e32 v136, v136, v137
	v_fmamk_f32 v136, v136, 0x39800000, v167
	v_cmp_gt_f32_e32 vcc, s17, v136
	v_mul_f32_e32 v137, 0x4b800000, v136
	s_nop 0
	v_cndmask_b32_e32 v136, v136, v137, vcc
	v_rsq_f32_e32 v136, v136
	s_nop 0
	v_mul_f32_e32 v137, 0x45800000, v136
	v_cndmask_b32_e32 v136, v136, v137, vcc
	v_pk_mul_f32 v[120:121], v[120:121], v[136:137] op_sel_hi:[1,0]
	v_pk_mul_f32 v[122:123], v[122:123], v[136:137] op_sel_hi:[1,0]
	v_pk_mul_f32 v[124:125], v[124:125], v[136:137] op_sel_hi:[1,0]
	v_pk_mul_f32 v[120:121], v[128:129], v[120:121]
	v_pk_mul_f32 v[126:127], v[126:127], v[136:137] op_sel_hi:[1,0]
	v_pk_mul_f32 v[122:123], v[4:5], v[122:123]
	v_pk_mul_f32 v[124:125], v[2:3], v[124:125]
	v_pk_mul_f32 v[126:127], v[6:7], v[126:127]
	s_nop 2
	v_bfe_u32 v140, v120, 16, 1
	v_add3_u32 v120, v120, v140, s18
	s_nop 2
	v_bfe_u32 v137, v124, 16, 1
	s_nop 5
	v_add3_u32 v124, v124, v137, s18
	v_lshrrev_b32_e32 v124, 16, v124
	s_nop 2
	v_pk_mul_f32 v[112:113], v[112:113], v[136:137] op_sel_hi:[1,0]
	v_pk_mul_f32 v[114:115], v[114:115], v[136:137] op_sel_hi:[1,0]
	v_cvt_pk_bf16_f32 v123, v127, v123
	v_cvt_pk_bf16_f32 v122, v126, v122
	v_cvt_pk_bf16_f32 v121, v125, v121
	v_and_or_b32 v120, v120, s16, v124
	v_pk_mul_f32 v[116:117], v[116:117], v[136:137] op_sel_hi:[1,0]
	v_pk_mul_f32 v[112:113], v[8:9], v[112:113]
	v_pk_mul_f32 v[118:119], v[118:119], v[136:137] op_sel_hi:[1,0]
	v_pk_mul_f32 v[114:115], v[12:13], v[114:115]
	global_store_dwordx4 v[134:135], v[120:123], off
	v_pk_mul_f32 v[116:117], v[10:11], v[116:117]
	v_pk_mul_f32 v[118:119], v[14:15], v[118:119]
	v_bfe_u32 v120, v115, 16, 1
	v_bfe_u32 v121, v114, 16, 1
	v_bfe_u32 v122, v113, 16, 1
	v_bfe_u32 v123, v112, 16, 1
	v_add3_u32 v112, v112, v123, s18
	v_add3_u32 v113, v113, v122, s18
	v_add3_u32 v114, v114, v121, s18
	v_add3_u32 v115, v115, v120, s18
	v_bfe_u32 v120, v116, 16, 1
	v_bfe_u32 v121, v117, 16, 1
	v_bfe_u32 v122, v118, 16, 1
	v_bfe_u32 v123, v119, 16, 1
	v_add3_u32 v119, v119, v123, s18
	v_add3_u32 v118, v118, v122, s18
	v_add3_u32 v117, v117, v121, s18
	v_add3_u32 v116, v116, v120, s18
	v_lshrrev_b32_e32 v116, 16, v116
	v_lshrrev_b32_e32 v117, 16, v117
	v_lshrrev_b32_e32 v118, 16, v118
	v_lshrrev_b32_e32 v119, 16, v119
	v_pk_mul_f32 v[104:105], v[104:105], v[136:137] op_sel_hi:[1,0]
	v_pk_mul_f32 v[106:107], v[106:107], v[136:137] op_sel_hi:[1,0]
	v_and_or_b32 v115, v115, s16, v119
	v_and_or_b32 v114, v114, s16, v118
	v_and_or_b32 v113, v113, s16, v117
	v_and_or_b32 v112, v112, s16, v116
	v_pk_mul_f32 v[108:109], v[108:109], v[136:137] op_sel_hi:[1,0]
	v_pk_mul_f32 v[104:105], v[16:17], v[104:105]
	v_pk_mul_f32 v[110:111], v[110:111], v[136:137] op_sel_hi:[1,0]
	v_pk_mul_f32 v[106:107], v[20:21], v[106:107]
	global_store_dwordx4 v[134:135], v[112:115], off offset:1024
	v_pk_mul_f32 v[108:109], v[18:19], v[108:109]
	v_pk_mul_f32 v[110:111], v[22:23], v[110:111]
	v_bfe_u32 v112, v107, 16, 1
	v_bfe_u32 v113, v106, 16, 1
	v_bfe_u32 v114, v105, 16, 1
	v_bfe_u32 v115, v104, 16, 1
	v_add3_u32 v104, v104, v115, s18
	v_add3_u32 v105, v105, v114, s18
	v_add3_u32 v106, v106, v113, s18
	v_add3_u32 v107, v107, v112, s18
	v_bfe_u32 v112, v108, 16, 1
	v_bfe_u32 v113, v109, 16, 1
	v_bfe_u32 v114, v110, 16, 1
	v_bfe_u32 v115, v111, 16, 1
	v_add3_u32 v111, v111, v115, s18
	v_add3_u32 v110, v110, v114, s18
	v_add3_u32 v109, v109, v113, s18
	v_add3_u32 v108, v108, v112, s18
	v_lshrrev_b32_e32 v108, 16, v108
	v_lshrrev_b32_e32 v109, 16, v109
	v_lshrrev_b32_e32 v110, 16, v110
	v_lshrrev_b32_e32 v111, 16, v111
	v_pk_mul_f32 v[96:97], v[96:97], v[136:137] op_sel_hi:[1,0]
	v_pk_mul_f32 v[98:99], v[98:99], v[136:137] op_sel_hi:[1,0]
	v_and_or_b32 v107, v107, s16, v111
	v_and_or_b32 v106, v106, s16, v110
	v_and_or_b32 v105, v105, s16, v109
	v_and_or_b32 v104, v104, s16, v108
	v_pk_mul_f32 v[100:101], v[100:101], v[136:137] op_sel_hi:[1,0]
	v_pk_mul_f32 v[96:97], v[24:25], v[96:97]
	v_pk_mul_f32 v[102:103], v[102:103], v[136:137] op_sel_hi:[1,0]
	v_pk_mul_f32 v[98:99], v[28:29], v[98:99]
	global_store_dwordx4 v[134:135], v[104:107], off offset:2048
	v_pk_mul_f32 v[100:101], v[26:27], v[100:101]
	v_pk_mul_f32 v[102:103], v[30:31], v[102:103]
	v_bfe_u32 v104, v99, 16, 1
	v_bfe_u32 v105, v98, 16, 1
	v_bfe_u32 v106, v97, 16, 1
	v_bfe_u32 v107, v96, 16, 1
	v_add3_u32 v96, v96, v107, s18
	v_add3_u32 v97, v97, v106, s18
	v_add3_u32 v98, v98, v105, s18
; __device__ __forceinline__ unsigned pk2(float lo, float hi) { return f2bf(lo) | (f2bf(hi) << 16); }
; __device__ __forceinline__ void ssd_gnorm(const Ctx& c, bf16* X2, const bf16* P, const float* g) {
;     ...
;         for (int j = 0; j < 8; ++j) { const float* gg = g + (c.lane + 64 * j) * 8; const f32x4 g0 = *(CF4)gg, g1 = *(CF4)(gg + 4);
;             v4u w; w.x = pk2(v[j][0] * rs * g0.x, v[j][1] * rs * g0.y); w.y = pk2(v[j][2] * rs * g0.z, v[j][3] * rs * g0.w); w.z = pk2(v[j][4] * rs * g1.x, v[j][5] * rs * g1.y); w.w = pk2(v[j][6] * rs * g1.z, v[j][7] * rs * g1.w);
;             yr[64 * j] = w; }
;     }
	v_add3_u32 v99, v99, v104, s18
	v_bfe_u32 v104, v100, 16, 1
	v_bfe_u32 v105, v101, 16, 1
	v_bfe_u32 v106, v102, 16, 1
	v_bfe_u32 v107, v103, 16, 1
	v_add3_u32 v103, v103, v107, s18
	v_add3_u32 v102, v102, v106, s18
	v_add3_u32 v101, v101, v105, s18
	v_add3_u32 v100, v100, v104, s18
	v_lshrrev_b32_e32 v100, 16, v100
	v_lshrrev_b32_e32 v101, 16, v101
	v_lshrrev_b32_e32 v102, 16, v102
	v_lshrrev_b32_e32 v103, 16, v103
	v_pk_mul_f32 v[88:89], v[88:89], v[136:137] op_sel_hi:[1,0]
	v_pk_mul_f32 v[90:91], v[90:91], v[136:137] op_sel_hi:[1,0]
	v_and_or_b32 v99, v99, s16, v103
	v_and_or_b32 v98, v98, s16, v102
	v_and_or_b32 v97, v97, s16, v101
	v_and_or_b32 v96, v96, s16, v100
	v_pk_mul_f32 v[92:93], v[92:93], v[136:137] op_sel_hi:[1,0]
	v_pk_mul_f32 v[88:89], v[32:33], v[88:89]
	v_pk_mul_f32 v[94:95], v[94:95], v[136:137] op_sel_hi:[1,0]
	v_pk_mul_f32 v[90:91], v[36:37], v[90:91]
	global_store_dwordx4 v[134:135], v[96:99], off offset:3072
	v_pk_mul_f32 v[92:93], v[34:35], v[92:93]
	v_pk_mul_f32 v[94:95], v[38:39], v[94:95]
	v_bfe_u32 v96, v91, 16, 1
	v_bfe_u32 v97, v90, 16, 1
	v_bfe_u32 v98, v89, 16, 1
	v_bfe_u32 v99, v88, 16, 1
	v_add3_u32 v88, v88, v99, s18
	v_add3_u32 v89, v89, v98, s18
	v_add3_u32 v90, v90, v97, s18
	v_add3_u32 v91, v91, v96, s18
	v_bfe_u32 v96, v92, 16, 1
	v_bfe_u32 v97, v93, 16, 1
	v_bfe_u32 v98, v94, 16, 1
	v_bfe_u32 v99, v95, 16, 1
	v_add3_u32 v95, v95, v99, s18
	v_add3_u32 v94, v94, v98, s18
	v_add3_u32 v93, v93, v97, s18
	v_add3_u32 v92, v92, v96, s18
	v_lshrrev_b32_e32 v92, 16, v92
	v_lshrrev_b32_e32 v93, 16, v93
	v_lshrrev_b32_e32 v94, 16, v94
	v_lshrrev_b32_e32 v95, 16, v95
	v_pk_mul_f32 v[80:81], v[80:81], v[136:137] op_sel_hi:[1,0]
	v_pk_mul_f32 v[82:83], v[82:83], v[136:137] op_sel_hi:[1,0]
	v_and_or_b32 v91, v91, s16, v95
	v_and_or_b32 v90, v90, s16, v94
	v_and_or_b32 v89, v89, s16, v93
	v_and_or_b32 v88, v88, s16, v92
	v_pk_mul_f32 v[84:85], v[84:85], v[136:137] op_sel_hi:[1,0]
	v_pk_mul_f32 v[80:81], v[40:41], v[80:81]
	v_pk_mul_f32 v[86:87], v[86:87], v[136:137] op_sel_hi:[1,0]
	v_pk_mul_f32 v[82:83], v[48:49], v[82:83]
	global_store_dwordx4 v[132:133], v[88:91], off
	v_pk_mul_f32 v[84:85], v[46:47], v[84:85]
	v_pk_mul_f32 v[86:87], v[42:43], v[86:87]
	v_bfe_u32 v88, v83, 16, 1
	s_nop 0
	v_bfe_u32 v90, v81, 16, 1
	s_nop 1
	v_add3_u32 v81, v81, v90, s18
	s_nop 0
	v_add3_u32 v83, v83, v88, s18
	s_nop 0
	v_bfe_u32 v89, v85, 16, 1
	s_nop 0
	v_bfe_u32 v91, v87, 16, 1
	v_add3_u32 v87, v87, v91, s18
	s_nop 0
	v_add3_u32 v85, v85, v89, s18
	s_nop 1
	v_lshrrev_b32_e32 v85, 16, v85
	s_nop 0
	v_lshrrev_b32_e32 v87, 16, v87
	v_pk_mul_f32 v[72:73], v[72:73], v[136:137] op_sel_hi:[1,0]
	v_pk_mul_f32 v[74:75], v[74:75], v[136:137] op_sel_hi:[1,0]
	v_and_or_b32 v83, v83, s16, v87
	v_cvt_pk_bf16_f32 v82, v86, v82
	v_and_or_b32 v81, v81, s16, v85
	v_cvt_pk_bf16_f32 v80, v84, v80
	v_pk_mul_f32 v[76:77], v[76:77], v[136:137] op_sel_hi:[1,0]
	v_pk_mul_f32 v[72:73], v[44:45], v[72:73]
	v_pk_mul_f32 v[78:79], v[78:79], v[136:137] op_sel_hi:[1,0]
	v_pk_mul_f32 v[74:75], v[52:53], v[74:75]
	global_store_dwordx4 v[132:133], v[80:83], off offset:1024
	v_pk_mul_f32 v[76:77], v[50:51], v[76:77]
	v_pk_mul_f32 v[78:79], v[54:55], v[78:79]
	s_nop 1
	v_bfe_u32 v82, v73, 16, 1
	s_nop 1
	v_add3_u32 v73, v73, v82, s18
	s_nop 2
	v_bfe_u32 v81, v77, 16, 1
	s_nop 3
	v_add3_u32 v77, v77, v81, s18
	s_nop 1
	v_lshrrev_b32_e32 v77, 16, v77
	s_nop 1
	v_pk_mul_f32 v[64:65], v[64:65], v[136:137] op_sel_hi:[1,0]
	v_pk_mul_f32 v[66:67], v[66:67], v[136:137] op_sel_hi:[1,0]
	v_cvt_pk_bf16_f32 v75, v79, v75
	v_cvt_pk_bf16_f32 v74, v78, v74
	v_and_or_b32 v73, v73, s16, v77
	v_cvt_pk_bf16_f32 v72, v76, v72
	v_pk_mul_f32 v[68:69], v[68:69], v[136:137] op_sel_hi:[1,0]
	v_pk_mul_f32 v[64:65], v[56:57], v[64:65]
	v_pk_mul_f32 v[70:71], v[70:71], v[136:137] op_sel_hi:[1,0]
	v_pk_mul_f32 v[66:67], v[60:61], v[66:67]
	global_store_dwordx4 v[132:133], v[72:75], off offset:2048
	v_pk_mul_f32 v[68:69], v[58:59], v[68:69]
	v_pk_mul_f32 v[70:71], v[62:63], v[70:71]
	v_bfe_u32 v72, v67, 16, 1
	s_nop 5
	v_add3_u32 v67, v67, v72, s18
	s_nop 2
	v_bfe_u32 v75, v71, 16, 1
	v_add3_u32 v71, v71, v75, s18
	s_nop 5
	v_lshrrev_b32_e32 v71, 16, v71
	v_and_or_b32 v67, v67, s16, v71
	v_cvt_pk_bf16_f32 v66, v70, v66
	v_cvt_pk_bf16_f32 v65, v69, v65
	v_cvt_pk_bf16_f32 v64, v68, v64
	global_store_dwordx4 v[132:133], v[64:67], off offset:3072
	s_cbranch_scc1 .LBB0_550

; __device__ __forceinline__ void postnorm(const Ctx& c, const bf16* MF, bf16* XB, float* RS, const float* gpost, float* OUT) {
;     for (int row = c.gw; row < MT; row += c.NGW) {
;         const v4u* mr = (const v4u*)(MF + (size_t)row * DM) + c.lane; v4u* xr = (v4u*)(XB + (size_t)row * DM) + c.lane;
;         v4u mv[4], xv[4]; float v[4][8]; float s = 0.f;
; #pragma unroll
;         for (int j = 0; j < 4; ++j) { mv[j] = mr[64 * j]; xv[j] = xr[64 * j]; }
; #pragma unroll
;         for (int j = 0; j < 4; ++j)
; #pragma unroll
;             for (int k = 0; k < 4; ++k) { v[j][2 * k] = bflo(mv[j][k]); v[j][2 * k + 1] = bfhi(mv[j][k]); s += v[j][2 * k] * v[j][2 * k] + v[j][2 * k + 1] * v[j][2 * k + 1]; }
;         const float rs = rsqrtf(wave_sum(s) * (1.f / DM) + EPS);
.LBB0_685:
	s_load_dwordx2 s[4:5], s[52:53], 0x120
	s_waitcnt lgkmcnt(0)
	v_lshl_add_u64 v[32:33], s[4:5], 0, v[34:35]
	v_add_co_u32_e32 v58, vcc, 0xd400000, v32
	s_nop 1
	v_addc_co_u32_e32 v59, vcc, 0, v33, vcc
	global_load_dwordx4 v[46:49], v[58:59], off
	global_load_dwordx4 v[50:53], v[58:59], off offset:1024
	global_load_dwordx4 v[54:57], v[58:59], off offset:2048
	s_nop 0
	global_load_dwordx4 v[58:61], v[58:59], off offset:3072
	v_add_co_u32_e32 v32, vcc, 0x9400000, v32
	s_waitcnt vmcnt(3)
	v_lshlrev_b32_e32 v79, 16, v47
	v_addc_co_u32_e32 v33, vcc, 0, v33, vcc
	global_load_dwordx4 v[62:65], v[32:33], off
	global_load_dwordx4 v[66:69], v[32:33], off offset:1024
	global_load_dwordx4 v[70:73], v[32:33], off offset:2048
	global_load_dwordx4 v[74:77], v[32:33], off offset:3072
	v_lshlrev_b32_e32 v78, 16, v46
	v_and_b32_e32 v47, 0xffff0000, v47
	v_and_b32_e32 v46, 0xffff0000, v46
	v_lshlrev_b32_e32 v81, 16, v49
	v_lshlrev_b32_e32 v80, 16, v48
	v_and_b32_e32 v49, 0xffff0000, v49
	v_and_b32_e32 v48, 0xffff0000, v48
	v_pk_mul_f32 v[94:95], v[46:47], v[46:47]
	v_pk_mul_f32 v[98:99], v[48:49], v[48:49]
	v_pk_fma_f32 v[94:95], v[78:79], v[78:79], v[94:95]
	s_waitcnt vmcnt(6)
	v_lshlrev_b32_e32 v83, 16, v51
	v_lshlrev_b32_e32 v82, 16, v50
	v_and_b32_e32 v51, 0xffff0000, v51
	v_and_b32_e32 v50, 0xffff0000, v50
	v_pk_fma_f32 v[98:99], v[80:81], v[80:81], v[98:99]
	v_add_f32_e32 v45, v94, v95
	v_pk_mul_f32 v[102:103], v[50:51], v[50:51]
	v_add_f32_e32 v45, v98, v45
	v_lshlrev_b32_e32 v85, 16, v53
	v_lshlrev_b32_e32 v84, 16, v52
	v_and_b32_e32 v53, 0xffff0000, v53
	v_and_b32_e32 v52, 0xffff0000, v52
	v_pk_fma_f32 v[102:103], v[82:83], v[82:83], v[102:103]
	v_add_f32_e32 v45, v99, v45
	v_pk_mul_f32 v[104:105], v[52:53], v[52:53]
	v_add_f32_e32 v45, v102, v45
	s_waitcnt vmcnt(5)
	v_lshlrev_b32_e32 v87, 16, v55
	v_lshlrev_b32_e32 v86, 16, v54
	v_and_b32_e32 v55, 0xffff0000, v55
	v_and_b32_e32 v54, 0xffff0000, v54
	v_pk_fma_f32 v[104:105], v[84:85], v[84:85], v[104:105]
	v_add_f32_e32 v45, v103, v45
	v_pk_mul_f32 v[106:107], v[54:55], v[54:55]
	v_add_f32_e32 v45, v104, v45
	v_lshlrev_b32_e32 v89, 16, v57
	v_lshlrev_b32_e32 v88, 16, v56
	v_and_b32_e32 v57, 0xffff0000, v57
	v_and_b32_e32 v56, 0xffff0000, v56
	v_pk_fma_f32 v[106:107], v[86:87], v[86:87], v[106:107]
	v_add_f32_e32 v45, v105, v45
	v_pk_mul_f32 v[108:109], v[56:57], v[56:57]
	v_add_f32_e32 v45, v106, v45
	s_waitcnt vmcnt(4)
	v_lshlrev_b32_e32 v91, 16, v59
	v_lshlrev_b32_e32 v90, 16, v58
	v_and_b32_e32 v59, 0xffff0000, v59
	v_and_b32_e32 v58, 0xffff0000, v58
	v_pk_fma_f32 v[108:109], v[88:89], v[88:89], v[108:109]
	v_add_f32_e32 v45, v107, v45
	v_pk_mul_f32 v[110:111], v[58:59], v[58:59]
	v_add_f32_e32 v45, v108, v45
	v_lshlrev_b32_e32 v93, 16, v61
	v_lshlrev_b32_e32 v92, 16, v60
	v_and_b32_e32 v61, 0xffff0000, v61
	v_and_b32_e32 v60, 0xffff0000, v60
	v_pk_fma_f32 v[110:111], v[90:91], v[90:91], v[110:111]
	v_add_f32_e32 v45, v109, v45
	v_pk_mul_f32 v[112:113], v[60:61], v[60:61]
	v_add_f32_e32 v45, v110, v45
	v_pk_fma_f32 v[112:113], v[92:93], v[92:93], v[112:113]
	v_add_f32_e32 v45, v111, v45
	v_add_f32_e32 v45, v112, v45
	v_add_f32_e32 v45, v113, v45
	ds_bpermute_b32 v94, v39, v45
	s_waitcnt lgkmcnt(0)
	v_add_f32_e32 v45, v45, v94
	ds_bpermute_b32 v98, v40, v45
	s_waitcnt lgkmcnt(0)
	v_add_f32_e32 v45, v45, v98
	ds_bpermute_b32 v102, v41, v45
	s_waitcnt vmcnt(3)
	v_lshlrev_b32_e32 v97, 16, v63
	v_lshlrev_b32_e32 v96, 16, v62
	v_and_b32_e32 v63, 0xffff0000, v63
	s_waitcnt lgkmcnt(0)
	v_add_f32_e32 v45, v45, v102
	ds_bpermute_b32 v104, v42, v45
	v_and_b32_e32 v62, 0xffff0000, v62
	v_lshlrev_b32_e32 v101, 16, v65
	v_lshlrev_b32_e32 v100, 16, v64
	v_and_b32_e32 v65, 0xffff0000, v65
	s_waitcnt lgkmcnt(0)
	v_add_f32_e32 v45, v45, v104
	ds_bpermute_b32 v106, v43, v45
	v_and_b32_e32 v64, 0xffff0000, v64
	s_waitcnt vmcnt(0)
	v_lshlrev_b32_e32 v109, 16, v77
	v_and_b32_e32 v77, 0xffff0000, v77
	v_lshlrev_b32_e32 v95, 16, v67
	s_waitcnt lgkmcnt(0)
	v_add_f32_e32 v45, v45, v106
	ds_bpermute_b32 v108, v44, v45
	v_lshlrev_b32_e32 v94, 16, v66
	v_and_b32_e32 v67, 0xffff0000, v67
	v_and_b32_e32 v66, 0xffff0000, v66
	v_lshlrev_b32_e32 v99, 16, v69
	s_waitcnt lgkmcnt(0)
; __device__ __forceinline__ unsigned pk2(float lo, float hi) { return f2bf(lo) | (f2bf(hi) << 16); }
; __device__ __forceinline__ void postnorm(const Ctx& c, const bf16* MF, bf16* XB, float* RS, const float* gpost, float* OUT) {
;     ...
;         const float rs = rsqrtf(wave_sum(s) * (1.f / DM) + EPS);
;         float s2 = 0.f;
; #pragma unroll
;         for (int j = 0; j < 4; ++j) { const float* gp = gpost + (c.lane + 64 * j) * 8; const f32x4 g0 = *(CF4)gp, g1 = *(CF4)(gp + 4);
; #pragma unroll
;             for (int k = 0; k < 4; ++k) { const float ga = (k < 2) ? g0[2 * k] : g1[2 * k - 4], gb = (k < 2) ? g0[2 * k + 1] : g1[2 * k - 3];
;                 v[j][2 * k] = bflo(xv[j][k]) + v[j][2 * k] * rs * ga; v[j][2 * k + 1] = bfhi(xv[j][k]) + v[j][2 * k + 1] * rs * gb;
;                 s2 += v[j][2 * k] * v[j][2 * k] + v[j][2 * k + 1] * v[j][2 * k + 1]; } }
;         if (OUT) {
; #pragma unroll
;             for (int j = 0; j < 4; ++j) { float* op = OUT + (size_t)row * DM + (c.lane + 64 * j) * 8; *(f32x4*)op = (f32x4){v[j][0], v[j][1], v[j][2], v[j][3]}; *(f32x4*)(op + 4) = (f32x4){v[j][4], v[j][5], v[j][6], v[j][7]}; }
;         } else {
; #pragma unroll
;             for (int j = 0; j < 4; ++j) { v4u o; o.x = pk2(v[j][0], v[j][1]); o.y = pk2(v[j][2], v[j][3]); o.z = pk2(v[j][4], v[j][5]); o.w = pk2(v[j][6], v[j][7]); xr[64 * j] = o; }
;             const float rs2 = rsqrtf(wave_sum(s2) * (1.f / DM) + EPS); if (c.lane == 0) RS[row] = rs2;
;         }
	v_add_f32_e32 v45, v45, v108
	v_fmamk_f32 v45, v45, 0x3a000000, v38
	v_mul_f32_e32 v108, 0x4b800000, v45
	v_cmp_gt_f32_e32 vcc, s1, v45
	v_lshlrev_b32_e32 v98, 16, v68
	v_and_b32_e32 v69, 0xffff0000, v69
	v_cndmask_b32_e32 v45, v45, v108, vcc
	v_rsq_f32_e32 v45, v45
	v_lshlrev_b32_e32 v108, 16, v76
	v_and_b32_e32 v76, 0xffff0000, v76
	v_and_b32_e32 v68, 0xffff0000, v68
	v_mul_f32_e32 v110, 0x45800000, v45
	v_cndmask_b32_e32 v110, v45, v110, vcc
	v_pk_mul_f32 v[46:47], v[110:111], v[46:47] op_sel_hi:[0,1]
	v_pk_mul_f32 v[78:79], v[110:111], v[78:79] op_sel_hi:[0,1]
	v_pk_mul_f32 v[48:49], v[110:111], v[48:49] op_sel_hi:[0,1]
	v_pk_fma_f32 v[46:47], v[36:37], v[46:47], v[62:63]
	v_pk_mul_f32 v[60:61], v[110:111], v[60:61] op_sel_hi:[0,1]
	v_pk_mul_f32 v[80:81], v[110:111], v[80:81] op_sel_hi:[0,1]
	v_pk_fma_f32 v[78:79], v[2:3], v[78:79], v[96:97]
	v_pk_fma_f32 v[48:49], v[4:5], v[48:49], v[64:65]
	v_pk_fma_f32 v[60:61], v[28:29], v[60:61], v[76:77]
	v_pk_mul_f32 v[76:77], v[46:47], v[46:47]
	v_pk_fma_f32 v[62:63], v[6:7], v[80:81], v[100:101]
	v_pk_fma_f32 v[76:77], v[78:79], v[78:79], v[76:77]
	v_pk_mul_f32 v[80:81], v[48:49], v[48:49]
	v_add_f32_e32 v45, v76, v77
	v_pk_fma_f32 v[80:81], v[62:63], v[62:63], v[80:81]
	v_pk_mul_f32 v[50:51], v[110:111], v[50:51] op_sel_hi:[0,1]
	v_add_f32_e32 v45, v80, v45
	v_pk_mul_f32 v[82:83], v[110:111], v[82:83] op_sel_hi:[0,1]
	v_pk_fma_f32 v[50:51], v[8:9], v[50:51], v[66:67]
	v_add_f32_e32 v45, v81, v45
	s_nop 1
	v_bfe_u32 v80, v47, 16, 1
	s_nop 0
	v_pk_mul_f32 v[52:53], v[110:111], v[52:53] op_sel_hi:[0,1]
	v_pk_fma_f32 v[64:65], v[14:15], v[82:83], v[94:95]
	v_pk_mul_f32 v[82:83], v[50:51], v[50:51]
	s_nop 0
	v_add3_u32 v47, v47, v80, s14
	s_nop 2
	v_bfe_u32 v77, v79, 16, 1
	s_nop 1
	v_pk_mul_f32 v[84:85], v[110:111], v[84:85] op_sel_hi:[0,1]
	v_pk_fma_f32 v[52:53], v[16:17], v[52:53], v[68:69]
	v_pk_fma_f32 v[82:83], v[64:65], v[64:65], v[82:83]
	s_nop 1
	v_add3_u32 v77, v79, v77, s14
	s_nop 0
	v_lshlrev_b32_e32 v103, 16, v71
	v_lshlrev_b32_e32 v102, 16, v70
	v_and_b32_e32 v71, 0xffff0000, v71
	v_and_b32_e32 v70, 0xffff0000, v70
	v_pk_fma_f32 v[66:67], v[10:11], v[84:85], v[98:99]
	v_pk_mul_f32 v[54:55], v[110:111], v[54:55] op_sel_hi:[0,1]
	v_pk_mul_f32 v[84:85], v[52:53], v[52:53]
	v_add_f32_e32 v45, v82, v45
	s_nop 0
	v_lshrrev_b32_e32 v77, 16, v77
	s_nop 1
	v_pk_mul_f32 v[68:69], v[110:111], v[86:87] op_sel_hi:[0,1]
	v_pk_fma_f32 v[54:55], v[12:13], v[54:55], v[70:71]
	v_pk_fma_f32 v[84:85], v[66:67], v[66:67], v[84:85]
	v_add_f32_e32 v45, v83, v45
	v_cvt_pk_bf16_f32 v49, v63, v49
	v_cvt_pk_bf16_f32 v48, v62, v48
	v_and_or_b32 v47, v47, s0, v77
	v_cvt_pk_bf16_f32 v46, v78, v46
	v_lshlrev_b32_e32 v105, 16, v73
	v_lshlrev_b32_e32 v104, 16, v72
	v_and_b32_e32 v73, 0xffff0000, v73
	v_and_b32_e32 v72, 0xffff0000, v72
	v_pk_fma_f32 v[68:69], v[18:19], v[68:69], v[102:103]
	v_pk_mul_f32 v[56:57], v[110:111], v[56:57] op_sel_hi:[0,1]
	v_pk_mul_f32 v[86:87], v[54:55], v[54:55]
	v_add_f32_e32 v45, v84, v45
	global_store_dwordx4 v[32:33], v[46:49], off
	v_pk_mul_f32 v[70:71], v[110:111], v[88:89] op_sel_hi:[0,1]
	v_pk_fma_f32 v[56:57], v[20:21], v[56:57], v[72:73]
	s_nop 3
	v_pk_fma_f32 v[86:87], v[68:69], v[68:69], v[86:87]
	v_add_f32_e32 v45, v85, v45
	s_nop 7
	v_lshlrev_b32_e32 v107, 16, v75
	v_lshlrev_b32_e32 v106, 16, v74
	v_and_b32_e32 v75, 0xffff0000, v75
	v_and_b32_e32 v74, 0xffff0000, v74
	v_pk_fma_f32 v[70:71], v[22:23], v[70:71], v[104:105]
	v_pk_mul_f32 v[58:59], v[110:111], v[58:59] op_sel_hi:[0,1]
	v_pk_mul_f32 v[88:89], v[56:57], v[56:57]
	v_add_f32_e32 v45, v86, v45
	s_nop 3
	v_pk_mul_f32 v[72:73], v[110:111], v[90:91] op_sel_hi:[0,1]
	v_pk_fma_f32 v[58:59], v[24:25], v[58:59], v[74:75]
	v_pk_fma_f32 v[88:89], v[70:71], v[70:71], v[88:89]
	v_add_f32_e32 v45, v87, v45
	s_nop 3
	v_pk_fma_f32 v[72:73], v[26:27], v[72:73], v[106:107]
	v_pk_mul_f32 v[90:91], v[58:59], v[58:59]
	v_add_f32_e32 v45, v88, v45
	v_cvt_pk_bf16_f32 v49, v67, v53
	v_cvt_pk_bf16_f32 v48, v66, v52
	v_cvt_pk_bf16_f32 v47, v65, v51
	v_cvt_pk_bf16_f32 v46, v64, v50
	v_pk_mul_f32 v[74:75], v[110:111], v[92:93] op_sel_hi:[0,1]
	v_pk_fma_f32 v[90:91], v[72:73], v[72:73], v[90:91]
	v_add_f32_e32 v45, v89, v45
	global_store_dwordx4 v[32:33], v[46:49], off offset:1024
	v_pk_fma_f32 v[74:75], v[30:31], v[74:75], v[108:109]
	v_pk_mul_f32 v[92:93], v[60:61], v[60:61]
	s_nop 1
	v_add_f32_e32 v45, v90, v45
	s_nop 5
	v_pk_fma_f32 v[92:93], v[74:75], v[74:75], v[92:93]
	v_add_f32_e32 v45, v91, v45
	s_nop 5
	v_add_f32_e32 v45, v92, v45
	s_nop 5
	v_add_f32_e32 v45, v93, v45
	v_cvt_pk_bf16_f32 v49, v71, v57
	v_cvt_pk_bf16_f32 v48, v70, v56
	v_cvt_pk_bf16_f32 v47, v69, v55
	v_cvt_pk_bf16_f32 v46, v68, v54
	global_store_dwordx4 v[32:33], v[46:49], off offset:2048
	ds_bpermute_b32 v47, v39, v45
	s_nop 3
	s_waitcnt lgkmcnt(0)
	v_add_f32_e32 v45, v45, v47
	ds_bpermute_b32 v47, v40, v45
	s_nop 3
	s_waitcnt lgkmcnt(0)
	v_add_f32_e32 v45, v45, v47
	ds_bpermute_b32 v47, v41, v45
	s_nop 0
	v_cvt_pk_bf16_f32 v51, v75, v61
	s_nop 1
	s_waitcnt lgkmcnt(0)
	v_add_f32_e32 v45, v45, v47
	ds_bpermute_b32 v47, v42, v45
	s_nop 3
	s_waitcnt lgkmcnt(0)
	v_add_f32_e32 v45, v45, v47
	ds_bpermute_b32 v47, v43, v45
	s_nop 3
	s_waitcnt lgkmcnt(0)
	v_add_f32_e32 v45, v45, v47
	ds_bpermute_b32 v46, v44, v45
	s_nop 0
	v_cvt_pk_bf16_f32 v50, v74, v60
	v_cvt_pk_bf16_f32 v49, v73, v59
	v_cvt_pk_bf16_f32 v48, v72, v58
	global_store_dwordx4 v[32:33], v[48:51], off offset:3072
	s_and_saveexec_b64 s[12:13], s[2:3]
	s_cbranch_execz .LBB0_684
	s_waitcnt lgkmcnt(0)
	v_add_f32_e32 v32, v45, v46
	v_fmamk_f32 v32, v32, 0x3a000000, v38
	v_mul_f32_e32 v33, 0x4b800000, v32
	v_cmp_gt_f32_e32 vcc, s1, v32
	s_load_dwordx2 s[4:5], s[52:53], 0x120
	s_waitcnt lgkmcnt(0)
	s_add_u32 s18, s4, s15
	v_cndmask_b32_e32 v32, v32, v33, vcc
	v_rsq_f32_e32 v32, v32
	s_addc_u32 s19, s5, s16
	v_mul_f32_e32 v33, 0x45800000, v32
	v_cndmask_b32_e32 v32, v32, v33, vcc
	global_store_dword v251, v32, s[18:19]
	s_branch .LBB0_684

; #define LAS __attribute__((address_space(3)))
; #define LDS_WAIT() asm volatile("s_waitcnt lgkmcnt(0)" ::: "memory")
;     ...
;     for (int it = gw0; it < items; it += ngw) {
;         const int kb = it / nblk, nb = it % nblk, k0 = 64 * kb, n0 = 64 * nb, nq = (lane & 15) * 4, kr = lane >> 4; const bool ok = (n0 + nq) < N;
;         f32x4 v[16];
; #pragma unroll
;         for (int i = 0; i < 16; ++i) v[i] = ok ? __builtin_nontemporal_load((const f32x4*)(W + (size_t)(k0 + 4 * i + kr) * N + n0 + nq)) : (f32x4){0.f, 0.f, 0.f, 0.f};
;         if (gain) {
; #pragma unroll
;             for (int i = 0; i < 16; ++i) v[i] *= gain[k0 + 4 * i + kr]; }
; #pragma unroll
;         for (int i = 0; i < 16; ++i) { LAS float* d = scr + (4 * i + kr) * 65 + nq; d[0] = v[i].x; d[1] = v[i].y; d[2] = v[i].z; d[3] = v[i].w; }
;         LDS_WAIT(); asm volatile("" ::: "memory");
.LBB0_851:
	s_or_b64 exec, exec, s[10:11]
	v_ashrrev_i32_e32 v73, 31, v72
	v_lshl_add_u64 v[106:107], v[72:73], 2, s[0:1]
	global_load_dword v72, v[106:107], off
	s_ashr_i32 s9, s8, 31
	s_add_i32 s19, s19, s13
	s_add_i32 s14, s14, s15
	s_cmpk_lt_i32 s19, 0xa80
	s_waitcnt vmcnt(0)
	v_pk_mul_f32 v[100:101], v[2:3], v[72:73] op_sel_hi:[1,0]
	global_load_dword v2, v[106:107], off offset:16
	v_pk_mul_f32 v[98:99], v[4:5], v[72:73] op_sel_hi:[1,0]
	global_load_dword v4, v[106:107], off offset:128
	s_waitcnt vmcnt(0)
	v_pk_mul_f32 v[90:91], v[12:13], v[2:3] op_sel_hi:[1,0]
	v_pk_mul_f32 v[94:95], v[10:11], v[2:3] op_sel_hi:[1,0]
	global_load_dword v2, v[106:107], off offset:32
	global_load_dword v10, v[106:107], off offset:160
	s_waitcnt vmcnt(0)
	v_pk_mul_f32 v[86:87], v[8:9], v[2:3] op_sel_hi:[1,0]
	v_pk_mul_f32 v[92:93], v[6:7], v[2:3] op_sel_hi:[1,0]
	global_load_dword v2, v[106:107], off offset:48
	global_load_dword v6, v[106:107], off offset:144
	v_pk_mul_f32 v[8:9], v[44:45], v[10:11] op_sel_hi:[1,0]
	v_pk_mul_f32 v[10:11], v[42:43], v[10:11] op_sel_hi:[1,0]
	s_waitcnt vmcnt(0)
	v_pk_mul_f32 v[82:83], v[20:21], v[2:3] op_sel_hi:[1,0]
	v_pk_mul_f32 v[88:89], v[18:19], v[2:3] op_sel_hi:[1,0]
	global_load_dword v2, v[106:107], off offset:64
	global_load_dword v18, v[106:107], off offset:192
	s_waitcnt vmcnt(0)
	v_pk_mul_f32 v[78:79], v[16:17], v[2:3] op_sel_hi:[1,0]
	v_pk_mul_f32 v[84:85], v[14:15], v[2:3] op_sel_hi:[1,0]
	global_load_dword v2, v[106:107], off offset:80
	global_load_dword v14, v[106:107], off offset:176
	v_pk_mul_f32 v[16:17], v[52:53], v[18:19] op_sel_hi:[1,0]
	v_pk_mul_f32 v[18:19], v[50:51], v[18:19] op_sel_hi:[1,0]
	s_waitcnt vmcnt(0)
	v_pk_mul_f32 v[74:75], v[28:29], v[2:3] op_sel_hi:[1,0]
	v_pk_mul_f32 v[80:81], v[26:27], v[2:3] op_sel_hi:[1,0]
	global_load_dword v2, v[106:107], off offset:96
	global_load_dword v26, v[106:107], off offset:224
	v_lshl_add_u64 v[28:29], v[96:97], 2, s[0:1]
	v_pk_mul_f32 v[12:13], v[56:57], v[14:15] op_sel_hi:[1,0]
	v_pk_mul_f32 v[14:15], v[54:55], v[14:15] op_sel_hi:[1,0]
	s_waitcnt vmcnt(0)
	v_pk_mul_f32 v[72:73], v[24:25], v[2:3] op_sel_hi:[1,0]
	v_pk_mul_f32 v[76:77], v[22:23], v[2:3] op_sel_hi:[1,0]
	global_load_dword v2, v[106:107], off offset:112
	global_load_dword v22, v[106:107], off offset:208
	v_pk_mul_f32 v[24:25], v[60:61], v[26:27] op_sel_hi:[1,0]
	v_pk_mul_f32 v[26:27], v[58:59], v[26:27] op_sel_hi:[1,0]
	s_waitcnt vmcnt(0)
	v_pk_mul_f32 v[36:37], v[36:37], v[2:3] op_sel_hi:[1,0]
	v_pk_mul_f32 v[34:35], v[34:35], v[2:3] op_sel_hi:[1,0]
	v_pk_mul_f32 v[2:3], v[32:33], v[4:5] op_sel_hi:[1,0]
	v_pk_mul_f32 v[32:33], v[30:31], v[4:5] op_sel_hi:[1,0]
	global_load_dword v30, v[28:29], off
	ds_write2_b32 v104, v100, v101 offset1:1
	ds_write2_b32 v104, v98, v99 offset0:2 offset1:3
	v_pk_mul_f32 v[4:5], v[48:49], v[6:7] op_sel_hi:[1,0]
	v_pk_mul_f32 v[6:7], v[46:47], v[6:7] op_sel_hi:[1,0]
	v_pk_mul_f32 v[20:21], v[64:65], v[22:23] op_sel_hi:[1,0]
	v_pk_mul_f32 v[22:23], v[62:63], v[22:23] op_sel_hi:[1,0]
	s_waitcnt vmcnt(0)
	v_pk_mul_f32 v[28:29], v[40:41], v[30:31] op_sel_hi:[1,0]
	v_pk_mul_f32 v[30:31], v[38:39], v[30:31] op_sel_hi:[1,0]
	v_add_u32_e32 v38, 0x410, v104
	ds_write2_b32 v38, v94, v95 offset1:1
	v_add_u32_e32 v38, 0x418, v104
	ds_write2_b32 v38, v90, v91 offset1:1
	v_add_u32_e32 v38, 0x820, v104
	ds_write2_b32 v38, v92, v93 offset1:1
	v_add_u32_e32 v38, 0x828, v104
	ds_write2_b32 v38, v86, v87 offset1:1
	v_add_u32_e32 v38, 0xc30, v104
	ds_write2_b32 v38, v88, v89 offset1:1
	v_add_u32_e32 v38, 0xc38, v104
	ds_write2_b32 v38, v82, v83 offset1:1
	v_add_u32_e32 v38, 0x1040, v104
	ds_write2_b32 v38, v84, v85 offset1:1
	v_add_u32_e32 v38, 0x1048, v104
	ds_write2_b32 v38, v78, v79 offset1:1
	v_add_u32_e32 v38, 0x1450, v104
	ds_write2_b32 v38, v80, v81 offset1:1
	v_add_u32_e32 v38, 0x1458, v104
	ds_write2_b32 v38, v74, v75 offset1:1
	v_add_u32_e32 v38, 0x1860, v104
	ds_write2_b32 v38, v76, v77 offset1:1
	v_add_u32_e32 v38, 0x1868, v104
	ds_write2_b32 v38, v72, v73 offset1:1
	v_add_u32_e32 v38, 0x1c70, v104
	ds_write2_b32 v38, v34, v35 offset1:1
	v_add_u32_e32 v34, 0x1c78, v104
	ds_write2_b32 v34, v36, v37 offset1:1
	v_add_u32_e32 v34, 0x2080, v104
	ds_write2_b32 v34, v32, v33 offset1:1
	v_add_u32_e32 v32, 0x2088, v104
	ds_write2_b32 v32, v2, v3 offset1:1
	v_add_u32_e32 v2, 0x2490, v104
	ds_write2_b32 v2, v6, v7 offset1:1
	v_add_u32_e32 v2, 0x2498, v104
	ds_write2_b32 v2, v4, v5 offset1:1
	v_add_u32_e32 v2, 0x28a0, v104
	ds_write2_b32 v2, v10, v11 offset1:1
	v_add_u32_e32 v2, 0x28a8, v104
	ds_write2_b32 v2, v8, v9 offset1:1
	v_add_u32_e32 v2, 0x2cb0, v104
	ds_write2_b32 v2, v14, v15 offset1:1
	v_add_u32_e32 v2, 0x2cb8, v104
	ds_write2_b32 v2, v12, v13 offset1:1
	v_add_u32_e32 v2, 0x30c0, v104
	ds_write2_b32 v2, v18, v19 offset1:1
	v_add_u32_e32 v2, 0x30c8, v104
	ds_write2_b32 v2, v16, v17 offset1:1
	v_add_u32_e32 v2, 0x34d0, v104
	ds_write2_b32 v2, v22, v23 offset1:1
	v_add_u32_e32 v2, 0x34d8, v104
	ds_write2_b32 v2, v20, v21 offset1:1
	v_add_u32_e32 v2, 0x38e0, v104
	ds_write2_b32 v2, v26, v27 offset1:1
	v_add_u32_e32 v2, 0x38e8, v104
	ds_write2_b32 v2, v24, v25 offset1:1
	v_add_u32_e32 v2, 0x3cf0, v104
	ds_write2_b32 v2, v30, v31 offset1:1
	v_add_u32_e32 v2, 0x3cf8, v104
	ds_write2_b32 v2, v28, v29 offset1:1
	s_waitcnt lgkmcnt(0)
	ds_read2_b32 v[6:7], v103 offset0:65 offset1:73
	ds_read2_b32 v[12:13], v103 offset1:8
	ds_read2_b32 v[14:15], v103 offset0:130 offset1:138
	ds_read2_b32 v[16:17], v103 offset0:195 offset1:203
	v_lshl_add_u64 v[2:3], s[8:9], 1, v[70:71]
	s_waitcnt lgkmcnt(0)
; #define LAS __attribute__((address_space(3)))
; #define LDS_WAIT() asm volatile("s_waitcnt lgkmcnt(0)" ::: "memory")
; __device__ __forceinline__ unsigned pk2(float lo, float hi) { return f2bf(lo) | (f2bf(hi) << 16); }
;     ...
;         const int c8 = lane & 7; int d0 = n0;
;         if (ffnmap) { const int bj = n0 >= FFH ? 1 : 0, chn = n0 - FFH * bj; d0 = 256 * (chn >> 7) + 128 * bj + (chn & 127); }
; #pragma unroll
;         for (int j = 0; j < 8; ++j) { const int n = (lane >> 3) + 8 * j; const LAS float* sp = scr + (8 * c8) * 65 + n;
;             v4u o; o.x = pk2(sp[0 * 65], sp[1 * 65]); o.y = pk2(sp[2 * 65], sp[3 * 65]); o.z = pk2(sp[4 * 65], sp[5 * 65]); o.w = pk2(sp[6 * 65], sp[7 * 65]);
;             *(v4u*)(WT + (size_t)(d0 + n) * K + k0 + 8 * c8) = o; }
;         LDS_WAIT(); asm volatile("" ::: "memory");
	v_bfe_u32 v5, v6, 16, 1
	v_bfe_u32 v4, v12, 16, 1
	v_add3_u32 v4, v12, v4, s17
	v_add3_u32 v5, v6, v5, s17
	v_add_u32_e32 v6, 0x400, v103
	v_lshrrev_b32_e32 v4, 16, v4
	ds_read2_b32 v[18:19], v6 offset0:4 offset1:12
	ds_read2_b32 v[20:21], v6 offset0:69 offset1:77
	v_and_or_b32 v8, v5, s18, v4
	s_nop 4
	ds_read2_b32 v[22:23], v6 offset0:134 offset1:142
	ds_read2_b32 v[24:25], v6 offset0:199 offset1:207
	v_cvt_pk_bf16_f32 v9, v14, v16
	s_waitcnt lgkmcnt(3)
	s_nop 1
	s_waitcnt lgkmcnt(2)
	s_nop 2
	v_cvt_pk_bf16_f32 v10, v18, v20
	s_waitcnt lgkmcnt(1)
	s_nop 1
	s_waitcnt lgkmcnt(0)
	s_nop 2
	v_cvt_pk_bf16_f32 v11, v22, v24
	v_add_u32_e32 v4, s6, v102
	v_ashrrev_i32_e32 v5, 31, v4
	v_lshlrev_b64 v[26:27], 12, v[4:5]
	v_lshl_add_u64 v[26:27], v[2:3], 0, v[26:27]
	s_nop 0
	global_store_dwordx4 v[26:27], v[8:11], off
	s_nop 3
	v_cvt_pk_bf16_f32 v8, v13, v7
	s_nop 4
	v_cvt_pk_bf16_f32 v9, v15, v17
	s_nop 4
	v_cvt_pk_bf16_f32 v10, v19, v21
	s_nop 0
	v_add_u32_e32 v12, 8, v4
	s_nop 1
	v_ashrrev_i32_e32 v13, 31, v12
	s_nop 1
	v_lshlrev_b64 v[12:13], 12, v[12:13]
	v_cvt_pk_bf16_f32 v11, v23, v25
	v_lshl_add_u64 v[12:13], v[2:3], 0, v[12:13]
	global_store_dwordx4 v[12:13], v[8:11], off
	ds_read2_b32 v[12:13], v103 offset0:81 offset1:89
	ds_read2_b32 v[14:15], v103 offset0:16 offset1:24
	ds_read2_b32 v[16:17], v103 offset0:146 offset1:154
	ds_read2_b32 v[18:19], v103 offset0:211 offset1:219
	ds_read2_b32 v[20:21], v6 offset0:20 offset1:28
	ds_read2_b32 v[22:23], v6 offset0:85 offset1:93
	ds_read2_b32 v[24:25], v6 offset0:150 offset1:158
	ds_read2_b32 v[26:27], v6 offset0:215 offset1:223
	s_waitcnt lgkmcnt(7)
	s_nop 0
	s_waitcnt lgkmcnt(6)
	s_nop 3
	v_cvt_pk_bf16_f32 v8, v14, v12
	s_waitcnt lgkmcnt(5)
	s_nop 1
	s_waitcnt lgkmcnt(4)
	s_nop 2
	v_cvt_pk_bf16_f32 v9, v16, v18
	s_waitcnt lgkmcnt(3)
	s_nop 1
	s_waitcnt lgkmcnt(2)
	s_nop 2
	v_cvt_pk_bf16_f32 v10, v20, v22
	s_waitcnt lgkmcnt(1)
	s_nop 1
	s_waitcnt lgkmcnt(0)
	s_nop 2
	v_add_u32_e32 v28, 16, v4
	v_cvt_pk_bf16_f32 v11, v24, v26
	v_ashrrev_i32_e32 v29, 31, v28
	v_bfe_u32 v5, v15, 16, 1
	v_lshlrev_b64 v[28:29], 12, v[28:29]
	v_add3_u32 v5, v15, v5, s17
	v_bfe_u32 v7, v13, 16, 1
	v_lshl_add_u64 v[28:29], v[2:3], 0, v[28:29]
	v_lshrrev_b32_e32 v5, 16, v5
	v_add3_u32 v7, v13, v7, s17
	global_store_dwordx4 v[28:29], v[8:11], off
	v_add_u32_e32 v12, 24, v4
	v_ashrrev_i32_e32 v13, 31, v12
	v_and_or_b32 v8, v7, s18, v5
	s_nop 4
	v_cvt_pk_bf16_f32 v9, v17, v19
	s_nop 4
	v_cvt_pk_bf16_f32 v10, v21, v23
	s_nop 4
	v_lshlrev_b64 v[12:13], 12, v[12:13]
	v_cvt_pk_bf16_f32 v11, v25, v27
	v_lshl_add_u64 v[12:13], v[2:3], 0, v[12:13]
	global_store_dwordx4 v[12:13], v[8:11], off
	ds_read2_b32 v[12:13], v103 offset0:97 offset1:105
	ds_read2_b32 v[14:15], v103 offset0:32 offset1:40
	ds_read2_b32 v[16:17], v103 offset0:162 offset1:170
	ds_read2_b32 v[18:19], v103 offset0:227 offset1:235
	ds_read2_b32 v[20:21], v6 offset0:36 offset1:44
	ds_read2_b32 v[22:23], v6 offset0:101 offset1:109
	ds_read2_b32 v[24:25], v6 offset0:166 offset1:174
	ds_read2_b32 v[26:27], v6 offset0:231 offset1:239
	s_waitcnt lgkmcnt(7)
	s_nop 0
	s_waitcnt lgkmcnt(6)
	s_nop 3
	v_cvt_pk_bf16_f32 v8, v14, v12
	s_waitcnt lgkmcnt(5)
	s_nop 1
	s_waitcnt lgkmcnt(4)
	s_nop 2
	v_cvt_pk_bf16_f32 v9, v16, v18
	s_waitcnt lgkmcnt(3)
	s_nop 1
	s_waitcnt lgkmcnt(2)
	s_nop 2
	v_cvt_pk_bf16_f32 v10, v20, v22
	s_waitcnt lgkmcnt(1)
	s_nop 1
	s_waitcnt lgkmcnt(0)
	s_nop 2
	v_add_u32_e32 v28, 32, v4
	v_cvt_pk_bf16_f32 v11, v24, v26
	v_ashrrev_i32_e32 v29, 31, v28
	v_bfe_u32 v5, v15, 16, 1
	v_lshlrev_b64 v[28:29], 12, v[28:29]
	v_add3_u32 v5, v15, v5, s17
	v_bfe_u32 v7, v13, 16, 1
	v_lshl_add_u64 v[28:29], v[2:3], 0, v[28:29]
	v_lshrrev_b32_e32 v5, 16, v5
	v_add3_u32 v7, v13, v7, s17
	global_store_dwordx4 v[28:29], v[8:11], off
	v_add_u32_e32 v12, 40, v4
	v_ashrrev_i32_e32 v13, 31, v12
	v_and_or_b32 v8, v7, s18, v5
	s_nop 4
	v_cvt_pk_bf16_f32 v9, v17, v19
	s_nop 4
	v_cvt_pk_bf16_f32 v10, v21, v23
	s_nop 4
	v_lshlrev_b64 v[12:13], 12, v[12:13]
	v_cvt_pk_bf16_f32 v11, v25, v27
	v_lshl_add_u64 v[12:13], v[2:3], 0, v[12:13]
	global_store_dwordx4 v[12:13], v[8:11], off
	ds_read2_b32 v[12:13], v103 offset0:48 offset1:56
	ds_read2_b32 v[14:15], v103 offset0:113 offset1:121
	ds_read2_b32 v[16:17], v103 offset0:178 offset1:186
	ds_read2_b32 v[18:19], v103 offset0:243 offset1:251
	ds_read2_b32 v[20:21], v6 offset0:52 offset1:60
	ds_read2_b32 v[22:23], v6 offset0:117 offset1:125
	ds_read2_b32 v[24:25], v6 offset0:182 offset1:190
	ds_read2_b32 v[26:27], v6 offset0:247 offset1:255
	s_waitcnt lgkmcnt(7)
	s_nop 1
	s_waitcnt lgkmcnt(6)
	s_nop 2
	v_cvt_pk_bf16_f32 v8, v12, v14
	s_waitcnt lgkmcnt(5)
	s_nop 1
	s_waitcnt lgkmcnt(4)
	s_nop 2
	v_cvt_pk_bf16_f32 v9, v16, v18
	s_waitcnt lgkmcnt(3)
	s_nop 1
	s_waitcnt lgkmcnt(2)
	s_nop 2
	v_cvt_pk_bf16_f32 v10, v20, v22
	s_waitcnt lgkmcnt(1)
	s_nop 1
	s_waitcnt lgkmcnt(0)
	s_nop 2
	v_cvt_pk_bf16_f32 v11, v24, v26
	v_add_u32_e32 v6, 48, v4
	v_ashrrev_i32_e32 v7, 31, v6
	v_lshlrev_b64 v[6:7], 12, v[6:7]
	v_lshl_add_u64 v[6:7], v[2:3], 0, v[6:7]
	s_nop 0
	global_store_dwordx4 v[6:7], v[8:11], off
	s_nop 3
	v_cvt_pk_bf16_f32 v6, v13, v15
	s_nop 4
	v_cvt_pk_bf16_f32 v7, v17, v19
	s_nop 4
	v_cvt_pk_bf16_f32 v8, v21, v23
	s_nop 4
	v_add_u32_e32 v4, 56, v4
	v_cvt_pk_bf16_f32 v9, v25, v27
	v_ashrrev_i32_e32 v5, 31, v4
	v_lshlrev_b64 v[4:5], 12, v[4:5]
	v_lshl_add_u64 v[2:3], v[2:3], 0, v[4:5]
	global_store_dwordx4 v[2:3], v[6:9], off
	s_waitcnt lgkmcnt(0)
	s_cbranch_scc0 .LBB0_884

; #define LAS __attribute__((address_space(3)))
; #define LDS_WAIT() asm volatile("s_waitcnt lgkmcnt(0)" ::: "memory")
; __device__ __forceinline__ unsigned pk2(float lo, float hi) { return f2bf(lo) | (f2bf(hi) << 16); }
;     ...
; #pragma unroll
;         for (int i = 0; i < 16; ++i) { LAS float* d = scr + (4 * i + kr) * 65 + nq; d[0] = v[i].x; d[1] = v[i].y; d[2] = v[i].z; d[3] = v[i].w; }
;         LDS_WAIT(); asm volatile("" ::: "memory");
;         const int c8 = lane & 7; int d0 = n0;
;         if (ffnmap) { const int bj = n0 >= FFH ? 1 : 0, chn = n0 - FFH * bj; d0 = 256 * (chn >> 7) + 128 * bj + (chn & 127); }
; #pragma unroll
;         for (int j = 0; j < 8; ++j) { const int n = (lane >> 3) + 8 * j; const LAS float* sp = scr + (8 * c8) * 65 + n;
;             v4u o; o.x = pk2(sp[0 * 65], sp[1 * 65]); o.y = pk2(sp[2 * 65], sp[3 * 65]); o.z = pk2(sp[4 * 65], sp[5 * 65]); o.w = pk2(sp[6 * 65], sp[7 * 65]);
;             *(v4u*)(WT + (size_t)(d0 + n) * K + k0 + 8 * c8) = o; }
.LBB0_886:
	s_or_b64 exec, exec, s[6:7]
	s_waitcnt vmcnt(0)
	ds_write2_b32 v78, v2, v3 offset1:1
	ds_write2_b32 v78, v4, v5 offset0:2 offset1:3
	v_add_u32_e32 v2, 0x410, v78
	ds_write2_b32 v2, v10, v11 offset1:1
	v_add_u32_e32 v2, 0x418, v78
	ds_write2_b32 v2, v12, v13 offset1:1
	v_add_u32_e32 v2, 0x820, v78
	ds_write2_b32 v2, v6, v7 offset1:1
	v_add_u32_e32 v2, 0x828, v78
	ds_write2_b32 v2, v8, v9 offset1:1
	v_add_u32_e32 v2, 0xc30, v78
	ds_write2_b32 v2, v18, v19 offset1:1
	v_add_u32_e32 v2, 0xc38, v78
	ds_write2_b32 v2, v20, v21 offset1:1
	v_add_u32_e32 v2, 0x1040, v78
	ds_write2_b32 v2, v14, v15 offset1:1
	v_add_u32_e32 v2, 0x1048, v78
	ds_write2_b32 v2, v16, v17 offset1:1
	v_add_u32_e32 v2, 0x1450, v78
	ds_write2_b32 v2, v26, v27 offset1:1
	v_add_u32_e32 v2, 0x1458, v78
	ds_write2_b32 v2, v28, v29 offset1:1
	v_add_u32_e32 v2, 0x1860, v78
	ds_write2_b32 v2, v22, v23 offset1:1
	v_add_u32_e32 v2, 0x1868, v78
	ds_write2_b32 v2, v24, v25 offset1:1
	v_add_u32_e32 v2, 0x1c70, v78
	ds_write2_b32 v2, v34, v35 offset1:1
	v_add_u32_e32 v2, 0x1c78, v78
	ds_write2_b32 v2, v36, v37 offset1:1
	v_add_u32_e32 v2, 0x2080, v78
	ds_write2_b32 v2, v30, v31 offset1:1
	v_add_u32_e32 v2, 0x2088, v78
	ds_write2_b32 v2, v32, v33 offset1:1
	v_add_u32_e32 v2, 0x2490, v78
	ds_write2_b32 v2, v42, v43 offset1:1
	v_add_u32_e32 v2, 0x2498, v78
	ds_write2_b32 v2, v44, v45 offset1:1
	v_add_u32_e32 v2, 0x28a0, v78
	ds_write2_b32 v2, v38, v39 offset1:1
	v_add_u32_e32 v2, 0x28a8, v78
	ds_write2_b32 v2, v40, v41 offset1:1
	v_add_u32_e32 v2, 0x2cb0, v78
	ds_write2_b32 v2, v50, v51 offset1:1
	v_add_u32_e32 v2, 0x2cb8, v78
	ds_write2_b32 v2, v52, v53 offset1:1
	v_add_u32_e32 v2, 0x30c0, v78
	ds_write2_b32 v2, v46, v47 offset1:1
	v_add_u32_e32 v2, 0x30c8, v78
	ds_write2_b32 v2, v48, v49 offset1:1
	v_add_u32_e32 v2, 0x34d0, v78
	ds_write2_b32 v2, v58, v59 offset1:1
	v_add_u32_e32 v2, 0x34d8, v78
	ds_write2_b32 v2, v60, v61 offset1:1
	v_add_u32_e32 v2, 0x38e0, v78
	ds_write2_b32 v2, v54, v55 offset1:1
	v_add_u32_e32 v2, 0x38e8, v78
	ds_write2_b32 v2, v56, v57 offset1:1
	v_add_u32_e32 v2, 0x3cf0, v78
	ds_write2_b32 v2, v62, v63 offset1:1
	v_add_u32_e32 v2, 0x3cf8, v78
	ds_write2_b32 v2, v64, v65 offset1:1
	s_waitcnt lgkmcnt(0)
	ds_read2_b32 v[10:11], v77 offset1:8
	ds_read2_b32 v[12:13], v77 offset0:65 offset1:73
	ds_read2_b32 v[14:15], v77 offset0:130 offset1:138
	ds_read2_b32 v[16:17], v77 offset0:195 offset1:203
	v_add_u32_e32 v28, 0x400, v77
	s_waitcnt lgkmcnt(0)
	s_nop 2
	ds_read2_b32 v[18:19], v28 offset0:4 offset1:12
	s_nop 1
	ds_read2_b32 v[20:21], v28 offset0:69 offset1:77
	v_cvt_pk_bf16_f32 v6, v10, v12
	s_nop 2
	ds_read2_b32 v[22:23], v28 offset0:134 offset1:142
	s_nop 1
	ds_read2_b32 v[24:25], v28 offset0:199 offset1:207
	v_cvt_pk_bf16_f32 v7, v14, v16
	s_waitcnt lgkmcnt(3)
	s_nop 1
	s_waitcnt lgkmcnt(2)
	s_nop 2
	v_cvt_pk_bf16_f32 v8, v18, v20
	s_waitcnt lgkmcnt(1)
	s_nop 1
	s_waitcnt lgkmcnt(0)
	s_nop 2
	s_add_i32 s15, s15, s8
	v_cvt_pk_bf16_f32 v9, v22, v24
	v_add_u32_e32 v4, s15, v76
	s_ashr_i32 s1, s0, 31
	v_ashrrev_i32_e32 v5, 31, v4
	v_lshl_add_u64 v[2:3], s[0:1], 1, v[70:71]
	v_lshlrev_b64 v[26:27], 12, v[4:5]
	v_lshl_add_u64 v[26:27], v[2:3], 0, v[26:27]
	s_nop 0
	global_store_dwordx4 v[26:27], v[6:9], off
	s_nop 3
	v_cvt_pk_bf16_f32 v6, v11, v13
	s_nop 4
	v_cvt_pk_bf16_f32 v7, v15, v17
	s_nop 4
	v_cvt_pk_bf16_f32 v8, v19, v21
	s_nop 0
	v_add_u32_e32 v10, 8, v4
	s_nop 1
	v_ashrrev_i32_e32 v11, 31, v10
	s_nop 1
	v_lshlrev_b64 v[10:11], 12, v[10:11]
	v_cvt_pk_bf16_f32 v9, v23, v25
	ds_read2_b32 v[12:13], v77 offset0:16 offset1:24
	v_lshl_add_u64 v[10:11], v[2:3], 0, v[10:11]
	global_store_dwordx4 v[10:11], v[6:9], off
	ds_read2_b32 v[10:11], v77 offset0:81 offset1:89
	ds_read2_b32 v[14:15], v77 offset0:146 offset1:154
	ds_read2_b32 v[16:17], v77 offset0:211 offset1:219
	s_waitcnt lgkmcnt(3)
	s_nop 1
	s_waitcnt lgkmcnt(2)
; #define LAS __attribute__((address_space(3)))
; #define LDS_WAIT() asm volatile("s_waitcnt lgkmcnt(0)" ::: "memory")
; __device__ __forceinline__ unsigned pk2(float lo, float hi) { return f2bf(lo) | (f2bf(hi) << 16); }
;     ...
; #pragma unroll
;         for (int j = 0; j < 8; ++j) { const int n = (lane >> 3) + 8 * j; const LAS float* sp = scr + (8 * c8) * 65 + n;
;             v4u o; o.x = pk2(sp[0 * 65], sp[1 * 65]); o.y = pk2(sp[2 * 65], sp[3 * 65]); o.z = pk2(sp[4 * 65], sp[5 * 65]); o.w = pk2(sp[6 * 65], sp[7 * 65]);
;             *(v4u*)(WT + (size_t)(d0 + n) * K + k0 + 8 * c8) = o; }
;         LDS_WAIT(); asm volatile("" ::: "memory");
	s_nop 0
	ds_read2_b32 v[18:19], v28 offset0:20 offset1:28
	s_nop 1
	ds_read2_b32 v[20:21], v28 offset0:85 offset1:93
	v_cvt_pk_bf16_f32 v6, v12, v10
	s_waitcnt lgkmcnt(3)
	s_nop 1
	s_waitcnt lgkmcnt(2)
	s_nop 0
	ds_read2_b32 v[22:23], v28 offset0:150 offset1:158
	s_nop 1
	ds_read2_b32 v[24:25], v28 offset0:215 offset1:223
	v_cvt_pk_bf16_f32 v7, v14, v16
	s_waitcnt lgkmcnt(3)
	s_nop 1
	s_waitcnt lgkmcnt(2)
	s_nop 2
	v_cvt_pk_bf16_f32 v8, v18, v20
	s_waitcnt lgkmcnt(1)
	s_nop 0
	v_add_u32_e32 v26, 16, v4
	s_nop 0
	s_waitcnt lgkmcnt(0)
	s_nop 0
	v_ashrrev_i32_e32 v27, 31, v26
	s_nop 1
	v_lshlrev_b64 v[26:27], 12, v[26:27]
	v_cvt_pk_bf16_f32 v9, v22, v24
	v_lshl_add_u64 v[26:27], v[2:3], 0, v[26:27]
	s_nop 0
	global_store_dwordx4 v[26:27], v[6:9], off
	s_nop 3
	v_cvt_pk_bf16_f32 v6, v13, v11
	s_nop 4
	v_cvt_pk_bf16_f32 v7, v15, v17
	s_nop 4
	v_cvt_pk_bf16_f32 v8, v19, v21
	s_nop 0
	v_add_u32_e32 v10, 24, v4
	s_nop 1
	v_ashrrev_i32_e32 v11, 31, v10
	s_nop 1
	v_lshlrev_b64 v[10:11], 12, v[10:11]
	v_cvt_pk_bf16_f32 v9, v23, v25
	ds_read2_b32 v[12:13], v77 offset0:32 offset1:40
	v_lshl_add_u64 v[10:11], v[2:3], 0, v[10:11]
	global_store_dwordx4 v[10:11], v[6:9], off
	ds_read2_b32 v[10:11], v77 offset0:97 offset1:105
	ds_read2_b32 v[14:15], v77 offset0:162 offset1:170
	ds_read2_b32 v[16:17], v77 offset0:227 offset1:235
	s_waitcnt lgkmcnt(3)
	s_nop 1
	s_waitcnt lgkmcnt(2)
	s_nop 0
	ds_read2_b32 v[18:19], v28 offset0:36 offset1:44
	s_nop 1
	ds_read2_b32 v[20:21], v28 offset0:101 offset1:109
	v_cvt_pk_bf16_f32 v6, v12, v10
	s_waitcnt lgkmcnt(3)
	s_nop 1
	s_waitcnt lgkmcnt(2)
	s_nop 0
	ds_read2_b32 v[22:23], v28 offset0:166 offset1:174
	s_nop 1
	ds_read2_b32 v[24:25], v28 offset0:231 offset1:239
	v_cvt_pk_bf16_f32 v7, v14, v16
	s_waitcnt lgkmcnt(3)
	s_nop 1
	s_waitcnt lgkmcnt(2)
	s_nop 2
	v_cvt_pk_bf16_f32 v8, v18, v20
	s_waitcnt lgkmcnt(1)
	s_nop 0
	v_add_u32_e32 v26, 32, v4
	s_nop 0
	s_waitcnt lgkmcnt(0)
	s_nop 0
	v_ashrrev_i32_e32 v27, 31, v26
	s_nop 1
	v_lshlrev_b64 v[26:27], 12, v[26:27]
	v_cvt_pk_bf16_f32 v9, v22, v24
	v_lshl_add_u64 v[26:27], v[2:3], 0, v[26:27]
	s_nop 0
	global_store_dwordx4 v[26:27], v[6:9], off
	s_nop 3
	v_cvt_pk_bf16_f32 v6, v13, v11
	s_nop 4
	v_cvt_pk_bf16_f32 v7, v15, v17
	s_nop 4
	v_cvt_pk_bf16_f32 v8, v19, v21
	s_nop 0
	v_add_u32_e32 v10, 40, v4
	s_nop 1
	v_ashrrev_i32_e32 v11, 31, v10
	s_nop 1
	v_lshlrev_b64 v[10:11], 12, v[10:11]
	v_cvt_pk_bf16_f32 v9, v23, v25
	ds_read2_b32 v[12:13], v77 offset0:48 offset1:56
	v_lshl_add_u64 v[10:11], v[2:3], 0, v[10:11]
	global_store_dwordx4 v[10:11], v[6:9], off
	ds_read2_b32 v[10:11], v77 offset0:113 offset1:121
	ds_read2_b32 v[14:15], v77 offset0:178 offset1:186
	ds_read2_b32 v[16:17], v77 offset0:243 offset1:251
	s_waitcnt lgkmcnt(3)
	s_nop 1
	s_waitcnt lgkmcnt(2)
	s_nop 0
	ds_read2_b32 v[18:19], v28 offset0:52 offset1:60
	s_nop 1
	ds_read2_b32 v[20:21], v28 offset0:117 offset1:125
	v_cvt_pk_bf16_f32 v6, v12, v10
	s_waitcnt lgkmcnt(3)
	s_nop 1
	s_waitcnt lgkmcnt(2)
	s_nop 0
	ds_read2_b32 v[22:23], v28 offset0:182 offset1:190
	s_nop 1
	ds_read2_b32 v[24:25], v28 offset0:247 offset1:255
	v_cvt_pk_bf16_f32 v7, v14, v16
	s_waitcnt lgkmcnt(3)
	s_nop 1
	s_waitcnt lgkmcnt(2)
	s_nop 2
	v_cvt_pk_bf16_f32 v8, v18, v20
	s_waitcnt lgkmcnt(1)
	s_nop 0
	v_add_u32_e32 v26, 48, v4
	s_nop 0
	s_waitcnt lgkmcnt(0)
	s_nop 0
	v_ashrrev_i32_e32 v27, 31, v26
	s_nop 1
	v_lshlrev_b64 v[26:27], 12, v[26:27]
	v_cvt_pk_bf16_f32 v9, v22, v24
	v_lshl_add_u64 v[26:27], v[2:3], 0, v[26:27]
	s_nop 0
	global_store_dwordx4 v[26:27], v[6:9], off
	s_nop 3
	v_cvt_pk_bf16_f32 v6, v13, v11
	s_nop 4
	v_cvt_pk_bf16_f32 v7, v15, v17
	s_nop 4
	v_cvt_pk_bf16_f32 v8, v19, v21
	s_nop 4
	v_add_u32_e32 v4, 56, v4
	v_cvt_pk_bf16_f32 v9, v23, v25
	v_ashrrev_i32_e32 v5, 31, v4
	v_lshlrev_b64 v[4:5], 12, v[4:5]
	v_lshl_add_u64 v[2:3], v[2:3], 0, v[4:5]
	global_store_dwordx4 v[2:3], v[6:9], off
	s_waitcnt lgkmcnt(0)
	s_add_i32 s14, s14, s13
	s_add_i32 s8, s8, s9
	s_cmpk_lt_i32 s14, 0x400
	s_cbranch_scc0 .LBB0_919

; #define LAS __attribute__((address_space(3)))
; #define LDS_WAIT() asm volatile("s_waitcnt lgkmcnt(0)" ::: "memory")
; __device__ __forceinline__ unsigned pk2(float lo, float hi) { return f2bf(lo) | (f2bf(hi) << 16); }
;     ...
; #pragma unroll
;         for (int i = 0; i < 16; ++i) { LAS float* d = scr + (4 * i + kr) * 65 + nq; d[0] = v[i].x; d[1] = v[i].y; d[2] = v[i].z; d[3] = v[i].w; }
;         LDS_WAIT(); asm volatile("" ::: "memory");
;         const int c8 = lane & 7; int d0 = n0;
;         if (ffnmap) { const int bj = n0 >= FFH ? 1 : 0, chn = n0 - FFH * bj; d0 = 256 * (chn >> 7) + 128 * bj + (chn & 127); }
; #pragma unroll
;         for (int j = 0; j < 8; ++j) { const int n = (lane >> 3) + 8 * j; const LAS float* sp = scr + (8 * c8) * 65 + n;
;             v4u o; o.x = pk2(sp[0 * 65], sp[1 * 65]); o.y = pk2(sp[2 * 65], sp[3 * 65]); o.z = pk2(sp[4 * 65], sp[5 * 65]); o.w = pk2(sp[6 * 65], sp[7 * 65]);
;             *(v4u*)(WT + (size_t)(d0 + n) * K + k0 + 8 * c8) = o; }
.LBB0_921:
	s_or_b64 exec, exec, s[6:7]
	s_waitcnt vmcnt(0)
	ds_write2_b32 v80, v2, v3 offset1:1
	ds_write2_b32 v80, v4, v5 offset0:2 offset1:3
	v_add_u32_e32 v2, 0x410, v80
	ds_write2_b32 v2, v10, v11 offset1:1
	v_add_u32_e32 v2, 0x418, v80
	ds_write2_b32 v2, v12, v13 offset1:1
	v_add_u32_e32 v2, 0x820, v80
	ds_write2_b32 v2, v6, v7 offset1:1
	v_add_u32_e32 v2, 0x828, v80
	ds_write2_b32 v2, v8, v9 offset1:1
	v_add_u32_e32 v2, 0xc30, v80
	ds_write2_b32 v2, v18, v19 offset1:1
	v_add_u32_e32 v2, 0xc38, v80
	ds_write2_b32 v2, v20, v21 offset1:1
	v_add_u32_e32 v2, 0x1040, v80
	ds_write2_b32 v2, v14, v15 offset1:1
	v_add_u32_e32 v2, 0x1048, v80
	ds_write2_b32 v2, v16, v17 offset1:1
	v_add_u32_e32 v2, 0x1450, v80
	ds_write2_b32 v2, v26, v27 offset1:1
	v_add_u32_e32 v2, 0x1458, v80
	ds_write2_b32 v2, v28, v29 offset1:1
	v_add_u32_e32 v2, 0x1860, v80
	ds_write2_b32 v2, v22, v23 offset1:1
	v_add_u32_e32 v2, 0x1868, v80
	ds_write2_b32 v2, v24, v25 offset1:1
	v_add_u32_e32 v2, 0x1c70, v80
	ds_write2_b32 v2, v34, v35 offset1:1
	v_add_u32_e32 v2, 0x1c78, v80
	ds_write2_b32 v2, v36, v37 offset1:1
	v_add_u32_e32 v2, 0x2080, v80
	ds_write2_b32 v2, v30, v31 offset1:1
	v_add_u32_e32 v2, 0x2088, v80
	ds_write2_b32 v2, v32, v33 offset1:1
	v_add_u32_e32 v2, 0x2490, v80
	ds_write2_b32 v2, v42, v43 offset1:1
	v_add_u32_e32 v2, 0x2498, v80
	ds_write2_b32 v2, v44, v45 offset1:1
	v_add_u32_e32 v2, 0x28a0, v80
	ds_write2_b32 v2, v38, v39 offset1:1
	v_add_u32_e32 v2, 0x28a8, v80
	ds_write2_b32 v2, v40, v41 offset1:1
	v_add_u32_e32 v2, 0x2cb0, v80
	ds_write2_b32 v2, v50, v51 offset1:1
	v_add_u32_e32 v2, 0x2cb8, v80
	ds_write2_b32 v2, v52, v53 offset1:1
	v_add_u32_e32 v2, 0x30c0, v80
	ds_write2_b32 v2, v46, v47 offset1:1
	v_add_u32_e32 v2, 0x30c8, v80
	ds_write2_b32 v2, v48, v49 offset1:1
	v_add_u32_e32 v2, 0x34d0, v80
	ds_write2_b32 v2, v58, v59 offset1:1
	v_add_u32_e32 v2, 0x34d8, v80
	ds_write2_b32 v2, v60, v61 offset1:1
	v_add_u32_e32 v2, 0x38e0, v80
	ds_write2_b32 v2, v54, v55 offset1:1
	v_add_u32_e32 v2, 0x38e8, v80
	ds_write2_b32 v2, v56, v57 offset1:1
	v_add_u32_e32 v2, 0x3cf0, v80
	ds_write2_b32 v2, v62, v63 offset1:1
	v_add_u32_e32 v2, 0x3cf8, v80
	ds_write2_b32 v2, v64, v65 offset1:1
	s_waitcnt lgkmcnt(0)
	ds_read2_b32 v[10:11], v79 offset1:8
	ds_read2_b32 v[12:13], v79 offset0:65 offset1:73
	ds_read2_b32 v[14:15], v79 offset0:130 offset1:138
	ds_read2_b32 v[16:17], v79 offset0:195 offset1:203
	v_add_u32_e32 v28, 0x400, v79
	s_waitcnt lgkmcnt(0)
	s_nop 2
	ds_read2_b32 v[18:19], v28 offset0:4 offset1:12
	s_nop 1
	ds_read2_b32 v[20:21], v28 offset0:69 offset1:77
	v_cvt_pk_bf16_f32 v6, v10, v12
	s_nop 2
	ds_read2_b32 v[22:23], v28 offset0:134 offset1:142
	s_nop 1
	ds_read2_b32 v[24:25], v28 offset0:199 offset1:207
	v_cvt_pk_bf16_f32 v7, v14, v16
	s_waitcnt lgkmcnt(3)
	s_nop 1
	s_waitcnt lgkmcnt(2)
	s_nop 2
	v_cvt_pk_bf16_f32 v8, v18, v20
	s_waitcnt lgkmcnt(1)
	s_nop 1
	s_waitcnt lgkmcnt(0)
	s_nop 2
	s_add_i32 s16, s16, s14
	v_cvt_pk_bf16_f32 v9, v22, v24
	v_add_u32_e32 v4, s16, v78
	s_ashr_i32 s1, s0, 31
	v_ashrrev_i32_e32 v5, 31, v4
	v_lshl_add_u64 v[2:3], s[0:1], 1, v[72:73]
	v_lshlrev_b64 v[26:27], 13, v[4:5]
	v_lshl_add_u64 v[26:27], v[2:3], 0, v[26:27]
	s_nop 0
	global_store_dwordx4 v[26:27], v[6:9], off
	s_nop 3
	v_cvt_pk_bf16_f32 v6, v11, v13
	s_nop 4
	v_cvt_pk_bf16_f32 v7, v15, v17
	s_nop 4
	v_cvt_pk_bf16_f32 v8, v19, v21
	s_nop 0
	v_add_u32_e32 v10, 8, v4
	s_nop 1
	v_ashrrev_i32_e32 v11, 31, v10
	s_nop 1
	v_lshlrev_b64 v[10:11], 13, v[10:11]
	v_cvt_pk_bf16_f32 v9, v23, v25
	ds_read2_b32 v[12:13], v79 offset0:16 offset1:24
	v_lshl_add_u64 v[10:11], v[2:3], 0, v[10:11]
	global_store_dwordx4 v[10:11], v[6:9], off
	ds_read2_b32 v[10:11], v79 offset0:81 offset1:89
	ds_read2_b32 v[14:15], v79 offset0:146 offset1:154
	ds_read2_b32 v[16:17], v79 offset0:211 offset1:219
	s_waitcnt lgkmcnt(3)
	s_nop 1
	s_waitcnt lgkmcnt(2)
; #define LAS __attribute__((address_space(3)))
; #define LDS_WAIT() asm volatile("s_waitcnt lgkmcnt(0)" ::: "memory")
; __device__ __forceinline__ unsigned pk2(float lo, float hi) { return f2bf(lo) | (f2bf(hi) << 16); }
;     ...
; #pragma unroll
;         for (int j = 0; j < 8; ++j) { const int n = (lane >> 3) + 8 * j; const LAS float* sp = scr + (8 * c8) * 65 + n;
;             v4u o; o.x = pk2(sp[0 * 65], sp[1 * 65]); o.y = pk2(sp[2 * 65], sp[3 * 65]); o.z = pk2(sp[4 * 65], sp[5 * 65]); o.w = pk2(sp[6 * 65], sp[7 * 65]);
;             *(v4u*)(WT + (size_t)(d0 + n) * K + k0 + 8 * c8) = o; }
;         LDS_WAIT(); asm volatile("" ::: "memory");
	s_nop 0
	ds_read2_b32 v[18:19], v28 offset0:20 offset1:28
	s_nop 1
	ds_read2_b32 v[20:21], v28 offset0:85 offset1:93
	v_cvt_pk_bf16_f32 v6, v12, v10
	s_waitcnt lgkmcnt(3)
	s_nop 1
	s_waitcnt lgkmcnt(2)
	s_nop 0
	ds_read2_b32 v[22:23], v28 offset0:150 offset1:158
	s_nop 1
	ds_read2_b32 v[24:25], v28 offset0:215 offset1:223
	v_cvt_pk_bf16_f32 v7, v14, v16
	s_waitcnt lgkmcnt(3)
	s_nop 1
	s_waitcnt lgkmcnt(2)
	s_nop 2
	v_cvt_pk_bf16_f32 v8, v18, v20
	s_waitcnt lgkmcnt(1)
	s_nop 0
	v_add_u32_e32 v26, 16, v4
	s_nop 0
	s_waitcnt lgkmcnt(0)
	s_nop 0
	v_ashrrev_i32_e32 v27, 31, v26
	s_nop 1
	v_lshlrev_b64 v[26:27], 13, v[26:27]
	v_cvt_pk_bf16_f32 v9, v22, v24
	v_lshl_add_u64 v[26:27], v[2:3], 0, v[26:27]
	s_nop 0
	global_store_dwordx4 v[26:27], v[6:9], off
	s_nop 3
	v_cvt_pk_bf16_f32 v6, v13, v11
	s_nop 4
	v_cvt_pk_bf16_f32 v7, v15, v17
	s_nop 4
	v_cvt_pk_bf16_f32 v8, v19, v21
	s_nop 0
	v_add_u32_e32 v10, 24, v4
	s_nop 1
	v_ashrrev_i32_e32 v11, 31, v10
	s_nop 1
	v_lshlrev_b64 v[10:11], 13, v[10:11]
	v_cvt_pk_bf16_f32 v9, v23, v25
	ds_read2_b32 v[12:13], v79 offset0:32 offset1:40
	v_lshl_add_u64 v[10:11], v[2:3], 0, v[10:11]
	global_store_dwordx4 v[10:11], v[6:9], off
	ds_read2_b32 v[10:11], v79 offset0:97 offset1:105
	ds_read2_b32 v[14:15], v79 offset0:162 offset1:170
	ds_read2_b32 v[16:17], v79 offset0:227 offset1:235
	s_waitcnt lgkmcnt(3)
	s_nop 1
	s_waitcnt lgkmcnt(2)
	s_nop 0
	ds_read2_b32 v[18:19], v28 offset0:36 offset1:44
	s_nop 1
	ds_read2_b32 v[20:21], v28 offset0:101 offset1:109
	v_cvt_pk_bf16_f32 v6, v12, v10
	s_waitcnt lgkmcnt(3)
	s_nop 1
	s_waitcnt lgkmcnt(2)
	s_nop 0
	ds_read2_b32 v[22:23], v28 offset0:166 offset1:174
	s_nop 1
	ds_read2_b32 v[24:25], v28 offset0:231 offset1:239
	v_cvt_pk_bf16_f32 v7, v14, v16
	s_waitcnt lgkmcnt(3)
	s_nop 1
	s_waitcnt lgkmcnt(2)
	s_nop 2
	v_cvt_pk_bf16_f32 v8, v18, v20
	s_waitcnt lgkmcnt(1)
	s_nop 0
	v_add_u32_e32 v26, 32, v4
	s_nop 0
	s_waitcnt lgkmcnt(0)
	s_nop 0
	v_ashrrev_i32_e32 v27, 31, v26
	s_nop 1
	v_lshlrev_b64 v[26:27], 13, v[26:27]
	v_cvt_pk_bf16_f32 v9, v22, v24
	v_lshl_add_u64 v[26:27], v[2:3], 0, v[26:27]
	s_nop 0
	global_store_dwordx4 v[26:27], v[6:9], off
	s_nop 3
	v_cvt_pk_bf16_f32 v6, v13, v11
	s_nop 4
	v_cvt_pk_bf16_f32 v7, v15, v17
	s_nop 4
	v_cvt_pk_bf16_f32 v8, v19, v21
	s_nop 0
	v_add_u32_e32 v10, 40, v4
	s_nop 1
	v_ashrrev_i32_e32 v11, 31, v10
	s_nop 1
	v_lshlrev_b64 v[10:11], 13, v[10:11]
	v_cvt_pk_bf16_f32 v9, v23, v25
	ds_read2_b32 v[12:13], v79 offset0:48 offset1:56
	v_lshl_add_u64 v[10:11], v[2:3], 0, v[10:11]
	global_store_dwordx4 v[10:11], v[6:9], off
	ds_read2_b32 v[10:11], v79 offset0:113 offset1:121
	ds_read2_b32 v[14:15], v79 offset0:178 offset1:186
	ds_read2_b32 v[16:17], v79 offset0:243 offset1:251
	s_waitcnt lgkmcnt(3)
	s_nop 1
	s_waitcnt lgkmcnt(2)
	s_nop 0
	ds_read2_b32 v[18:19], v28 offset0:52 offset1:60
	s_nop 1
	ds_read2_b32 v[20:21], v28 offset0:117 offset1:125
	v_cvt_pk_bf16_f32 v6, v12, v10
	s_waitcnt lgkmcnt(3)
	s_nop 1
	s_waitcnt lgkmcnt(2)
	s_nop 0
	ds_read2_b32 v[22:23], v28 offset0:182 offset1:190
	s_nop 1
	ds_read2_b32 v[24:25], v28 offset0:247 offset1:255
	v_cvt_pk_bf16_f32 v7, v14, v16
	s_waitcnt lgkmcnt(3)
	s_nop 1
	s_waitcnt lgkmcnt(2)
	s_nop 2
	v_cvt_pk_bf16_f32 v8, v18, v20
	s_waitcnt lgkmcnt(1)
	s_nop 0
	v_add_u32_e32 v26, 48, v4
	s_nop 0
	s_waitcnt lgkmcnt(0)
	s_nop 0
	v_ashrrev_i32_e32 v27, 31, v26
	s_nop 1
	v_lshlrev_b64 v[26:27], 13, v[26:27]
	v_cvt_pk_bf16_f32 v9, v22, v24
	v_lshl_add_u64 v[26:27], v[2:3], 0, v[26:27]
	s_nop 0
	global_store_dwordx4 v[26:27], v[6:9], off
	s_nop 3
	v_cvt_pk_bf16_f32 v6, v13, v11
	s_nop 4
	v_cvt_pk_bf16_f32 v7, v15, v17
	s_nop 4
	v_cvt_pk_bf16_f32 v8, v19, v21
	s_nop 4
	v_add_u32_e32 v4, 56, v4
	v_cvt_pk_bf16_f32 v9, v23, v25
	v_ashrrev_i32_e32 v5, 31, v4
	v_lshlrev_b64 v[4:5], 13, v[4:5]
	v_lshl_add_u64 v[2:3], v[2:3], 0, v[4:5]
	global_store_dwordx4 v[2:3], v[6:9], off
	s_waitcnt lgkmcnt(0)
	s_add_i32 s15, s15, s13
	s_add_i32 s14, s14, s9
	s_cmpk_lt_i32 s15, 0x100
	s_cbranch_scc0 .LBB0_954

; #define LAS __attribute__((address_space(3)))
; #define LDS_WAIT() asm volatile("s_waitcnt lgkmcnt(0)" ::: "memory")
; __device__ __forceinline__ unsigned pk2(float lo, float hi) { return f2bf(lo) | (f2bf(hi) << 16); }
;     ...
; #pragma unroll
;         for (int i = 0; i < 16; ++i) { LAS float* d = scr + (4 * i + kr) * 65 + nq; d[0] = v[i].x; d[1] = v[i].y; d[2] = v[i].z; d[3] = v[i].w; }
;         LDS_WAIT(); asm volatile("" ::: "memory");
;         const int c8 = lane & 7; int d0 = n0;
;         if (ffnmap) { const int bj = n0 >= FFH ? 1 : 0, chn = n0 - FFH * bj; d0 = 256 * (chn >> 7) + 128 * bj + (chn & 127); }
; #pragma unroll
;         for (int j = 0; j < 8; ++j) { const int n = (lane >> 3) + 8 * j; const LAS float* sp = scr + (8 * c8) * 65 + n;
;             v4u o; o.x = pk2(sp[0 * 65], sp[1 * 65]); o.y = pk2(sp[2 * 65], sp[3 * 65]); o.z = pk2(sp[4 * 65], sp[5 * 65]); o.w = pk2(sp[6 * 65], sp[7 * 65]);
;             *(v4u*)(WT + (size_t)(d0 + n) * K + k0 + 8 * c8) = o; }
.LBB0_955:
	s_or_b64 exec, exec, s[6:7]
	s_waitcnt vmcnt(0)
	ds_write2_b32 v80, v2, v3 offset1:1
	ds_write2_b32 v80, v4, v5 offset0:2 offset1:3
	v_add_u32_e32 v2, 0x410, v80
	ds_write2_b32 v2, v10, v11 offset1:1
	v_add_u32_e32 v2, 0x418, v80
	ds_write2_b32 v2, v12, v13 offset1:1
	v_add_u32_e32 v2, 0x820, v80
	ds_write2_b32 v2, v6, v7 offset1:1
	v_add_u32_e32 v2, 0x828, v80
	ds_write2_b32 v2, v8, v9 offset1:1
	v_add_u32_e32 v2, 0xc30, v80
	ds_write2_b32 v2, v18, v19 offset1:1
	v_add_u32_e32 v2, 0xc38, v80
	ds_write2_b32 v2, v20, v21 offset1:1
	v_add_u32_e32 v2, 0x1040, v80
	ds_write2_b32 v2, v14, v15 offset1:1
	v_add_u32_e32 v2, 0x1048, v80
	ds_write2_b32 v2, v16, v17 offset1:1
	v_add_u32_e32 v2, 0x1450, v80
	ds_write2_b32 v2, v26, v27 offset1:1
	v_add_u32_e32 v2, 0x1458, v80
	ds_write2_b32 v2, v28, v29 offset1:1
	v_add_u32_e32 v2, 0x1860, v80
	ds_write2_b32 v2, v22, v23 offset1:1
	v_add_u32_e32 v2, 0x1868, v80
	ds_write2_b32 v2, v24, v25 offset1:1
	v_add_u32_e32 v2, 0x1c70, v80
	ds_write2_b32 v2, v34, v35 offset1:1
	v_add_u32_e32 v2, 0x1c78, v80
	ds_write2_b32 v2, v36, v37 offset1:1
	v_add_u32_e32 v2, 0x2080, v80
	ds_write2_b32 v2, v30, v31 offset1:1
	v_add_u32_e32 v2, 0x2088, v80
	ds_write2_b32 v2, v32, v33 offset1:1
	v_add_u32_e32 v2, 0x2490, v80
	ds_write2_b32 v2, v42, v43 offset1:1
	v_add_u32_e32 v2, 0x2498, v80
	ds_write2_b32 v2, v44, v45 offset1:1
	v_add_u32_e32 v2, 0x28a0, v80
	ds_write2_b32 v2, v38, v39 offset1:1
	v_add_u32_e32 v2, 0x28a8, v80
	ds_write2_b32 v2, v40, v41 offset1:1
	v_add_u32_e32 v2, 0x2cb0, v80
	ds_write2_b32 v2, v50, v51 offset1:1
	v_add_u32_e32 v2, 0x2cb8, v80
	ds_write2_b32 v2, v52, v53 offset1:1
	v_add_u32_e32 v2, 0x30c0, v80
	ds_write2_b32 v2, v46, v47 offset1:1
	v_add_u32_e32 v2, 0x30c8, v80
	ds_write2_b32 v2, v48, v49 offset1:1
	v_add_u32_e32 v2, 0x34d0, v80
	ds_write2_b32 v2, v58, v59 offset1:1
	v_add_u32_e32 v2, 0x34d8, v80
	ds_write2_b32 v2, v60, v61 offset1:1
	v_add_u32_e32 v2, 0x38e0, v80
	ds_write2_b32 v2, v54, v55 offset1:1
	v_add_u32_e32 v2, 0x38e8, v80
	ds_write2_b32 v2, v56, v57 offset1:1
	v_add_u32_e32 v2, 0x3cf0, v80
	ds_write2_b32 v2, v62, v63 offset1:1
	v_add_u32_e32 v2, 0x3cf8, v80
	ds_write2_b32 v2, v64, v65 offset1:1
	s_waitcnt lgkmcnt(0)
	ds_read2_b32 v[10:11], v79 offset1:8
	ds_read2_b32 v[12:13], v79 offset0:65 offset1:73
	ds_read2_b32 v[14:15], v79 offset0:130 offset1:138
	ds_read2_b32 v[16:17], v79 offset0:195 offset1:203
	v_add_u32_e32 v28, 0x400, v79
	s_waitcnt lgkmcnt(3)
	s_nop 1
	s_waitcnt lgkmcnt(2)
	s_nop 0
	ds_read2_b32 v[18:19], v28 offset0:4 offset1:12
	s_nop 1
	ds_read2_b32 v[20:21], v28 offset0:69 offset1:77
	v_cvt_pk_bf16_f32 v6, v10, v12
	s_waitcnt lgkmcnt(3)
	s_nop 1
	s_waitcnt lgkmcnt(2)
	s_nop 0
	ds_read2_b32 v[22:23], v28 offset0:134 offset1:142
	s_nop 1
	ds_read2_b32 v[24:25], v28 offset0:199 offset1:207
	v_cvt_pk_bf16_f32 v7, v14, v16
	s_waitcnt lgkmcnt(3)
	s_nop 1
	s_waitcnt lgkmcnt(2)
	s_nop 2
	v_cvt_pk_bf16_f32 v8, v18, v20
	s_waitcnt lgkmcnt(1)
	s_nop 1
	s_waitcnt lgkmcnt(0)
	s_nop 2
	s_add_i32 s14, s14, s8
	v_cvt_pk_bf16_f32 v9, v22, v24
	v_add_u32_e32 v4, s14, v78
	s_ashr_i32 s1, s0, 31
	v_ashrrev_i32_e32 v5, 31, v4
	v_lshl_add_u64 v[2:3], s[0:1], 1, v[68:69]
	v_lshlrev_b64 v[26:27], 13, v[4:5]
	v_lshl_add_u64 v[26:27], v[2:3], 0, v[26:27]
	s_nop 0
	global_store_dwordx4 v[26:27], v[6:9], off
	s_nop 3
	v_cvt_pk_bf16_f32 v6, v11, v13
	s_nop 4
	v_cvt_pk_bf16_f32 v7, v15, v17
	s_nop 4
	v_cvt_pk_bf16_f32 v8, v19, v21
	s_nop 0
	v_add_u32_e32 v10, 8, v4
	s_nop 1
	v_ashrrev_i32_e32 v11, 31, v10
	s_nop 1
	v_lshlrev_b64 v[10:11], 13, v[10:11]
	v_cvt_pk_bf16_f32 v9, v23, v25
	ds_read2_b32 v[12:13], v79 offset0:16 offset1:24
	v_lshl_add_u64 v[10:11], v[2:3], 0, v[10:11]
	global_store_dwordx4 v[10:11], v[6:9], off
	ds_read2_b32 v[10:11], v79 offset0:81 offset1:89
	ds_read2_b32 v[14:15], v79 offset0:146 offset1:154
	ds_read2_b32 v[16:17], v79 offset0:211 offset1:219
	s_waitcnt lgkmcnt(3)
	s_nop 1
	s_waitcnt lgkmcnt(2)
; #define LAS __attribute__((address_space(3)))
; #define LDS_WAIT() asm volatile("s_waitcnt lgkmcnt(0)" ::: "memory")
; __device__ __forceinline__ unsigned pk2(float lo, float hi) { return f2bf(lo) | (f2bf(hi) << 16); }
;     ...
;     for (int it = gw0; it < items; it += ngw) {
;         const int kb = it / nblk, nb = it % nblk, k0 = 64 * kb, n0 = 64 * nb, nq = (lane & 15) * 4, kr = lane >> 4; const bool ok = (n0 + nq) < N;
;         f32x4 v[16];
; #pragma unroll
;         for (int i = 0; i < 16; ++i) v[i] = ok ? __builtin_nontemporal_load((const f32x4*)(W + (size_t)(k0 + 4 * i + kr) * N + n0 + nq)) : (f32x4){0.f, 0.f, 0.f, 0.f};
;         if (gain) {
; #pragma unroll
;             for (int i = 0; i < 16; ++i) v[i] *= gain[k0 + 4 * i + kr]; }
; #pragma unroll
;         for (int i = 0; i < 16; ++i) { LAS float* d = scr + (4 * i + kr) * 65 + nq; d[0] = v[i].x; d[1] = v[i].y; d[2] = v[i].z; d[3] = v[i].w; }
;         LDS_WAIT(); asm volatile("" ::: "memory");
;         const int c8 = lane & 7; int d0 = n0;
;         if (ffnmap) { const int bj = n0 >= FFH ? 1 : 0, chn = n0 - FFH * bj; d0 = 256 * (chn >> 7) + 128 * bj + (chn & 127); }
; #pragma unroll
;         for (int j = 0; j < 8; ++j) { const int n = (lane >> 3) + 8 * j; const LAS float* sp = scr + (8 * c8) * 65 + n;
;             v4u o; o.x = pk2(sp[0 * 65], sp[1 * 65]); o.y = pk2(sp[2 * 65], sp[3 * 65]); o.z = pk2(sp[4 * 65], sp[5 * 65]); o.w = pk2(sp[6 * 65], sp[7 * 65]);
;             *(v4u*)(WT + (size_t)(d0 + n) * K + k0 + 8 * c8) = o; }
;         LDS_WAIT(); asm volatile("" ::: "memory");
	s_nop 0
	ds_read2_b32 v[18:19], v28 offset0:20 offset1:28
	s_nop 1
	ds_read2_b32 v[20:21], v28 offset0:85 offset1:93
	v_cvt_pk_bf16_f32 v6, v12, v10
	s_waitcnt lgkmcnt(3)
	s_nop 1
	s_waitcnt lgkmcnt(2)
	s_nop 0
	ds_read2_b32 v[22:23], v28 offset0:150 offset1:158
	s_nop 1
	ds_read2_b32 v[24:25], v28 offset0:215 offset1:223
	v_cvt_pk_bf16_f32 v7, v14, v16
	s_waitcnt lgkmcnt(3)
	s_nop 1
	s_waitcnt lgkmcnt(2)
	s_nop 2
	v_cvt_pk_bf16_f32 v8, v18, v20
	s_waitcnt lgkmcnt(1)
	s_nop 0
	v_add_u32_e32 v26, 16, v4
	s_nop 0
	s_waitcnt lgkmcnt(0)
	s_nop 0
	v_ashrrev_i32_e32 v27, 31, v26
	s_nop 1
	v_lshlrev_b64 v[26:27], 13, v[26:27]
	v_cvt_pk_bf16_f32 v9, v22, v24
	v_lshl_add_u64 v[26:27], v[2:3], 0, v[26:27]
	s_nop 0
	global_store_dwordx4 v[26:27], v[6:9], off
	s_nop 3
	v_cvt_pk_bf16_f32 v6, v13, v11
	s_nop 4
	v_cvt_pk_bf16_f32 v7, v15, v17
	s_nop 4
	v_cvt_pk_bf16_f32 v8, v19, v21
	s_nop 0
	v_add_u32_e32 v10, 24, v4
	s_nop 1
	v_ashrrev_i32_e32 v11, 31, v10
	s_nop 1
	v_lshlrev_b64 v[10:11], 13, v[10:11]
	v_cvt_pk_bf16_f32 v9, v23, v25
	ds_read2_b32 v[12:13], v79 offset0:32 offset1:40
	v_lshl_add_u64 v[10:11], v[2:3], 0, v[10:11]
	global_store_dwordx4 v[10:11], v[6:9], off
	ds_read2_b32 v[10:11], v79 offset0:97 offset1:105
	ds_read2_b32 v[14:15], v79 offset0:162 offset1:170
	ds_read2_b32 v[16:17], v79 offset0:227 offset1:235
	s_waitcnt lgkmcnt(3)
	s_nop 1
	s_waitcnt lgkmcnt(2)
	s_nop 0
	ds_read2_b32 v[18:19], v28 offset0:36 offset1:44
	s_nop 1
	ds_read2_b32 v[20:21], v28 offset0:101 offset1:109
	v_cvt_pk_bf16_f32 v6, v12, v10
	s_waitcnt lgkmcnt(3)
	s_nop 1
	s_waitcnt lgkmcnt(2)
	s_nop 0
	ds_read2_b32 v[22:23], v28 offset0:166 offset1:174
	s_nop 1
	ds_read2_b32 v[24:25], v28 offset0:231 offset1:239
	v_cvt_pk_bf16_f32 v7, v14, v16
	s_waitcnt lgkmcnt(3)
	s_nop 1
	s_waitcnt lgkmcnt(2)
	s_nop 2
	v_cvt_pk_bf16_f32 v8, v18, v20
	s_waitcnt lgkmcnt(1)
	s_nop 0
	v_add_u32_e32 v26, 32, v4
	s_nop 0
	s_waitcnt lgkmcnt(0)
	s_nop 0
	v_ashrrev_i32_e32 v27, 31, v26
	s_nop 1
	v_lshlrev_b64 v[26:27], 13, v[26:27]
	v_cvt_pk_bf16_f32 v9, v22, v24
	v_lshl_add_u64 v[26:27], v[2:3], 0, v[26:27]
	s_nop 0
	global_store_dwordx4 v[26:27], v[6:9], off
	s_nop 3
	v_cvt_pk_bf16_f32 v6, v13, v11
	s_nop 4
	v_cvt_pk_bf16_f32 v7, v15, v17
	s_nop 4
	v_cvt_pk_bf16_f32 v8, v19, v21
	s_nop 0
	v_add_u32_e32 v10, 40, v4
	s_nop 1
	v_ashrrev_i32_e32 v11, 31, v10
	s_nop 1
	v_lshlrev_b64 v[10:11], 13, v[10:11]
	v_cvt_pk_bf16_f32 v9, v23, v25
	ds_read2_b32 v[12:13], v79 offset0:48 offset1:56
	v_lshl_add_u64 v[10:11], v[2:3], 0, v[10:11]
	global_store_dwordx4 v[10:11], v[6:9], off
	ds_read2_b32 v[10:11], v79 offset0:113 offset1:121
	ds_read2_b32 v[14:15], v79 offset0:178 offset1:186
	ds_read2_b32 v[16:17], v79 offset0:243 offset1:251
	s_waitcnt lgkmcnt(3)
	s_nop 1
	s_waitcnt lgkmcnt(2)
	s_nop 0
	ds_read2_b32 v[18:19], v28 offset0:52 offset1:60
	s_nop 1
	ds_read2_b32 v[20:21], v28 offset0:117 offset1:125
	v_cvt_pk_bf16_f32 v6, v12, v10
	s_waitcnt lgkmcnt(3)
	s_nop 1
	s_waitcnt lgkmcnt(2)
	s_nop 0
	ds_read2_b32 v[22:23], v28 offset0:182 offset1:190
	s_nop 1
	ds_read2_b32 v[24:25], v28 offset0:247 offset1:255
	v_cvt_pk_bf16_f32 v7, v14, v16
	s_waitcnt lgkmcnt(3)
	s_nop 1
	s_waitcnt lgkmcnt(2)
	s_nop 2
	v_cvt_pk_bf16_f32 v8, v18, v20
	s_waitcnt lgkmcnt(1)
	s_nop 0
	v_add_u32_e32 v26, 48, v4
	s_nop 0
	s_waitcnt lgkmcnt(0)
	s_nop 0
	v_ashrrev_i32_e32 v27, 31, v26
	s_nop 1
	v_lshlrev_b64 v[26:27], 13, v[26:27]
	v_cvt_pk_bf16_f32 v9, v22, v24
	v_lshl_add_u64 v[26:27], v[2:3], 0, v[26:27]
	s_nop 0
	global_store_dwordx4 v[26:27], v[6:9], off
	s_nop 3
	v_cvt_pk_bf16_f32 v6, v13, v11
	s_nop 4
	v_cvt_pk_bf16_f32 v7, v15, v17
	s_nop 4
	v_cvt_pk_bf16_f32 v8, v19, v21
	s_nop 4
	v_add_u32_e32 v4, 56, v4
	v_cvt_pk_bf16_f32 v9, v23, v25
	v_ashrrev_i32_e32 v5, 31, v4
	v_lshlrev_b64 v[4:5], 13, v[4:5]
	v_lshl_add_u64 v[2:3], v[2:3], 0, v[4:5]
	global_store_dwordx4 v[2:3], v[6:9], off
	s_waitcnt lgkmcnt(0)
	s_add_i32 s12, s12, s13
	s_add_i32 s8, s8, s9
	s_cmpk_lt_i32 s12, 0x100
	s_cbranch_scc0 .LBB0_988

; __device__ __forceinline__ unsigned pk2(float lo, float hi) { return f2bf(lo) | (f2bf(hi) << 16); }
; __device__ __forceinline__ void xa_attn_fa(const Ctx& c, const bf16* Q, const bf16* KV, const bf16* XVT, bf16* Oo) {
;     ...
;         for (int mi = 0; mi < 2; ++mi) { float lt = l[mi]; lt += __shfl_xor(lt, 16); lt += __shfl_xor(lt, 32); const float il = 1.f / lt;
; #pragma unroll
;             for (int dt = 0; dt < 8; ++dt) { const f32x4 o = O[dt][mi] * il; v2u w; w.x = pk2(o[0], o[1]); w.y = pk2(o[2], o[3]);
;                 *(v2u*)(Oo + grow[mi] * 512 + hd * 128 + 16 * dt + 4 * lg) = w; } }
.LBB0_1044:
	v_mul_f32_e32 v4, 0x3e800000, v128
	ds_bpermute_b32 v4, v167, v4
	s_lshl_b32 s8, s21, 1
	v_lshl_add_u64 v[6:7], v[172:173], 0, s[8:9]
	v_lshl_add_u64 v[42:43], v[6:7], 0, v[188:189]
	v_mul_f32_e32 v48, 0x3e800000, v40
	s_waitcnt lgkmcnt(0)
	v_fmac_f32_e32 v4, 0x3e800000, v128
	ds_bpermute_b32 v41, v196, v4
	v_lshl_add_u64 v[6:7], v[6:7], 0, v[186:187]
	s_add_i32 s20, s20, s33
	s_cmpk_lt_i32 s20, 0x100
	s_waitcnt lgkmcnt(0)
	v_add_f32_e32 v4, v4, v41
	v_div_scale_f32 v41, s[10:11], v4, v4, 1.0
	v_rcp_f32_e32 v44, v41
	v_div_scale_f32 v45, vcc, 1.0, v4, 1.0
	v_fma_f32 v46, -v41, v44, 1.0
	v_fmac_f32_e32 v44, v46, v44
	v_mul_f32_e32 v46, v45, v44
	v_fma_f32 v47, -v41, v46, v45
	v_fmac_f32_e32 v46, v47, v44
	v_fma_f32 v41, -v41, v46, v45
	v_div_fmas_f32 v41, v41, v44, v46
	v_div_fixup_f32 v4, v41, v4, 1.0
	v_pk_mul_f32 v[46:47], v[104:105], v[4:5] op_sel_hi:[1,0]
	v_pk_mul_f32 v[44:45], v[106:107], v[4:5] op_sel_hi:[1,0]
	s_nop 4
	v_cvt_pk_bf16_f32 v46, v46, v47
	s_nop 4
	v_cvt_pk_bf16_f32 v47, v44, v45
	global_store_dwordx2 v[42:43], v[46:47], off
	v_pk_mul_f32 v[46:47], v[100:101], v[4:5] op_sel_hi:[1,0]
	v_pk_mul_f32 v[44:45], v[102:103], v[4:5] op_sel_hi:[1,0]
	s_nop 4
	v_cvt_pk_bf16_f32 v46, v46, v47
	s_nop 4
	v_cvt_pk_bf16_f32 v47, v44, v45
	global_store_dwordx2 v[42:43], v[46:47], off offset:32
	v_pk_mul_f32 v[46:47], v[96:97], v[4:5] op_sel_hi:[1,0]
	v_pk_mul_f32 v[44:45], v[98:99], v[4:5] op_sel_hi:[1,0]
	s_nop 4
	v_cvt_pk_bf16_f32 v46, v46, v47
	s_nop 4
	v_cvt_pk_bf16_f32 v47, v44, v45
	global_store_dwordx2 v[42:43], v[46:47], off offset:64
	v_pk_mul_f32 v[46:47], v[92:93], v[4:5] op_sel_hi:[1,0]
	v_pk_mul_f32 v[44:45], v[94:95], v[4:5] op_sel_hi:[1,0]
	s_nop 4
	v_cvt_pk_bf16_f32 v46, v46, v47
	s_nop 4
	v_cvt_pk_bf16_f32 v47, v44, v45
	global_store_dwordx2 v[42:43], v[46:47], off offset:96
	v_pk_mul_f32 v[46:47], v[88:89], v[4:5] op_sel_hi:[1,0]
	v_pk_mul_f32 v[44:45], v[90:91], v[4:5] op_sel_hi:[1,0]
	s_nop 4
	v_cvt_pk_bf16_f32 v46, v46, v47
	s_nop 4
	v_cvt_pk_bf16_f32 v47, v44, v45
	global_store_dwordx2 v[42:43], v[46:47], off offset:128
	v_pk_mul_f32 v[46:47], v[84:85], v[4:5] op_sel_hi:[1,0]
	v_pk_mul_f32 v[44:45], v[86:87], v[4:5] op_sel_hi:[1,0]
	s_nop 4
	v_cvt_pk_bf16_f32 v46, v46, v47
	s_nop 4
	v_cvt_pk_bf16_f32 v47, v44, v45
	global_store_dwordx2 v[42:43], v[46:47], off offset:160
	v_pk_mul_f32 v[46:47], v[80:81], v[4:5] op_sel_hi:[1,0]
	v_pk_mul_f32 v[44:45], v[82:83], v[4:5] op_sel_hi:[1,0]
	s_nop 4
	v_cvt_pk_bf16_f32 v46, v46, v47
	s_nop 4
	v_cvt_pk_bf16_f32 v47, v44, v45
	ds_bpermute_b32 v41, v167, v48
	global_store_dwordx2 v[42:43], v[46:47], off offset:192
	v_pk_mul_f32 v[46:47], v[76:77], v[4:5] op_sel_hi:[1,0]
	v_pk_mul_f32 v[44:45], v[78:79], v[4:5] op_sel_hi:[1,0]
	s_nop 4
	s_waitcnt lgkmcnt(0)
	v_fmac_f32_e32 v41, 0x3e800000, v40
	v_cvt_pk_bf16_f32 v46, v46, v47
	ds_bpermute_b32 v4, v196, v41
	s_nop 3
	s_waitcnt lgkmcnt(0)
	v_add_f32_e32 v4, v41, v4
	v_div_scale_f32 v41, s[10:11], v4, v4, 1.0
	v_rcp_f32_e32 v48, v41
	s_nop 0
	v_cvt_pk_bf16_f32 v47, v44, v45
	global_store_dwordx2 v[42:43], v[46:47], off offset:224
	v_fma_f32 v40, -v41, v48, 1.0
	v_fmac_f32_e32 v48, v40, v48
	v_div_scale_f32 v40, vcc, 1.0, v4, 1.0
	v_mul_f32_e32 v42, v40, v48
	v_fma_f32 v43, -v41, v42, v40
	v_fmac_f32_e32 v42, v43, v48
	v_fma_f32 v40, -v41, v42, v40
	v_div_fmas_f32 v40, v40, v48, v42
	v_div_fixup_f32 v4, v40, v4, 1.0
	v_pk_mul_f32 v[36:37], v[36:37], v[4:5] op_sel_hi:[1,0]
	v_pk_mul_f32 v[38:39], v[38:39], v[4:5] op_sel_hi:[1,0]
	s_nop 4
	v_cvt_pk_bf16_f32 v36, v36, v37
	s_nop 4
	v_cvt_pk_bf16_f32 v37, v38, v39
	v_pk_mul_f32 v[32:33], v[32:33], v[4:5] op_sel_hi:[1,0]
	global_store_dwordx2 v[6:7], v[36:37], off
	s_nop 2
	v_pk_mul_f32 v[34:35], v[34:35], v[4:5] op_sel_hi:[1,0]
	s_nop 1
	v_cvt_pk_bf16_f32 v32, v32, v33
	s_nop 4
	v_cvt_pk_bf16_f32 v33, v34, v35
	v_pk_mul_f32 v[28:29], v[28:29], v[4:5] op_sel_hi:[1,0]
	global_store_dwordx2 v[6:7], v[32:33], off offset:32
	s_nop 2
	v_pk_mul_f32 v[30:31], v[30:31], v[4:5] op_sel_hi:[1,0]
	s_nop 1
	v_cvt_pk_bf16_f32 v28, v28, v29
	s_nop 4
	v_cvt_pk_bf16_f32 v29, v30, v31
	v_pk_mul_f32 v[24:25], v[24:25], v[4:5] op_sel_hi:[1,0]
	global_store_dwordx2 v[6:7], v[28:29], off offset:64
	s_nop 2
	v_pk_mul_f32 v[26:27], v[26:27], v[4:5] op_sel_hi:[1,0]
	s_nop 1
	v_cvt_pk_bf16_f32 v24, v24, v25
	s_nop 4
	v_cvt_pk_bf16_f32 v25, v26, v27
	v_pk_mul_f32 v[20:21], v[20:21], v[4:5] op_sel_hi:[1,0]
	global_store_dwordx2 v[6:7], v[24:25], off offset:96
	s_nop 2
	v_pk_mul_f32 v[22:23], v[22:23], v[4:5] op_sel_hi:[1,0]
	s_nop 1
	v_cvt_pk_bf16_f32 v20, v20, v21
	s_nop 4
	v_cvt_pk_bf16_f32 v21, v22, v23
	v_pk_mul_f32 v[16:17], v[16:17], v[4:5] op_sel_hi:[1,0]
	global_store_dwordx2 v[6:7], v[20:21], off offset:128
	s_nop 2
	v_pk_mul_f32 v[18:19], v[18:19], v[4:5] op_sel_hi:[1,0]
	s_nop 1
	v_cvt_pk_bf16_f32 v16, v16, v17
	s_nop 4
	v_cvt_pk_bf16_f32 v17, v18, v19
	v_pk_mul_f32 v[12:13], v[12:13], v[4:5] op_sel_hi:[1,0]
	v_pk_mul_f32 v[8:9], v[8:9], v[4:5] op_sel_hi:[1,0]
	global_store_dwordx2 v[6:7], v[16:17], off offset:160
	v_pk_mul_f32 v[14:15], v[14:15], v[4:5] op_sel_hi:[1,0]
	s_nop 0
	v_pk_mul_f32 v[10:11], v[10:11], v[4:5] op_sel_hi:[1,0]
	s_nop 7
	s_nop 0
	v_cvt_pk_bf16_f32 v12, v12, v13
	s_nop 0
	v_cvt_pk_bf16_f32 v8, v8, v9
	v_bfe_u32 v4, v10, 16, 1
	s_nop 1
	v_add3_u32 v4, v10, v4, s18
	v_bfe_u32 v9, v11, 16, 1
	s_nop 1
	v_lshrrev_b32_e32 v4, 16, v4
	v_add3_u32 v9, v11, v9, s18
	v_cvt_pk_bf16_f32 v13, v14, v15
	v_and_or_b32 v9, v9, s19, v4
	global_store_dwordx2 v[6:7], v[12:13], off offset:192
	global_store_dwordx2 v[6:7], v[8:9], off offset:224
	s_cbranch_scc0 .LBB0_1056

; __device__ __forceinline__ void postnorm(const Ctx& c, const bf16* MF, bf16* XB, float* RS, const float* gpost, float* OUT) {
;     for (int row = c.gw; row < MT; row += c.NGW) {
;         const v4u* mr = (const v4u*)(MF + (size_t)row * DM) + c.lane; v4u* xr = (v4u*)(XB + (size_t)row * DM) + c.lane;
;         v4u mv[4], xv[4]; float v[4][8]; float s = 0.f;
; #pragma unroll
;         for (int j = 0; j < 4; ++j) { mv[j] = mr[64 * j]; xv[j] = xr[64 * j]; }
; #pragma unroll
;         for (int j = 0; j < 4; ++j)
; #pragma unroll
;             for (int k = 0; k < 4; ++k) { v[j][2 * k] = bflo(mv[j][k]); v[j][2 * k + 1] = bfhi(mv[j][k]); s += v[j][2 * k] * v[j][2 * k] + v[j][2 * k + 1] * v[j][2 * k + 1]; }
;         const float rs = rsqrtf(wave_sum(s) * (1.f / DM) + EPS);
.LBB0_1188:
	v_readlane_b32 s10, v253, 0
	v_readlane_b32 s11, v253, 1
	s_nop 1
	v_lshl_add_u64 v[38:39], s[10:11], 0, v[30:31]
	v_add_co_u32_e32 v58, vcc, 0xd400000, v38
	s_nop 1
	v_addc_co_u32_e32 v59, vcc, 0, v39, vcc
	s_waitcnt lgkmcnt(0)
	global_load_dwordx4 v[46:49], v[58:59], off
	global_load_dwordx4 v[50:53], v[58:59], off offset:1024
	global_load_dwordx4 v[54:57], v[58:59], off offset:2048
	s_nop 0
	global_load_dwordx4 v[58:61], v[58:59], off offset:3072
	v_add_co_u32_e32 v38, vcc, 0x9400000, v38
	s_waitcnt vmcnt(0)
	v_lshlrev_b32_e32 v79, 16, v47
	v_addc_co_u32_e32 v39, vcc, 0, v39, vcc
	global_load_dwordx4 v[62:65], v[38:39], off
	global_load_dwordx4 v[66:69], v[38:39], off offset:1024
	global_load_dwordx4 v[70:73], v[38:39], off offset:2048
	global_load_dwordx4 v[74:77], v[38:39], off offset:3072
	v_lshlrev_b32_e32 v78, 16, v46
	v_and_b32_e32 v47, 0xffff0000, v47
	v_and_b32_e32 v46, 0xffff0000, v46
	v_lshlrev_b32_e32 v81, 16, v49
	v_lshlrev_b32_e32 v80, 16, v48
	v_and_b32_e32 v49, 0xffff0000, v49
	v_and_b32_e32 v48, 0xffff0000, v48
	v_pk_mul_f32 v[94:95], v[46:47], v[46:47]
	v_pk_mul_f32 v[98:99], v[48:49], v[48:49]
	v_pk_fma_f32 v[94:95], v[78:79], v[78:79], v[94:95]
	v_lshlrev_b32_e32 v83, 16, v51
	v_lshlrev_b32_e32 v82, 16, v50
	v_and_b32_e32 v51, 0xffff0000, v51
	v_and_b32_e32 v50, 0xffff0000, v50
	v_pk_fma_f32 v[98:99], v[80:81], v[80:81], v[98:99]
	v_add_f32_e32 v94, v94, v95
	v_pk_mul_f32 v[102:103], v[50:51], v[50:51]
	v_add_f32_e32 v94, v98, v94
	v_lshlrev_b32_e32 v85, 16, v53
	v_lshlrev_b32_e32 v84, 16, v52
	v_and_b32_e32 v53, 0xffff0000, v53
	v_and_b32_e32 v52, 0xffff0000, v52
	v_pk_fma_f32 v[102:103], v[82:83], v[82:83], v[102:103]
	v_add_f32_e32 v94, v99, v94
	v_pk_mul_f32 v[104:105], v[52:53], v[52:53]
	v_add_f32_e32 v94, v102, v94
	v_lshlrev_b32_e32 v87, 16, v55
	v_lshlrev_b32_e32 v86, 16, v54
	v_and_b32_e32 v55, 0xffff0000, v55
	v_and_b32_e32 v54, 0xffff0000, v54
	v_pk_fma_f32 v[104:105], v[84:85], v[84:85], v[104:105]
	v_add_f32_e32 v94, v103, v94
	v_pk_mul_f32 v[106:107], v[54:55], v[54:55]
	v_add_f32_e32 v94, v104, v94
	v_lshlrev_b32_e32 v89, 16, v57
	v_lshlrev_b32_e32 v88, 16, v56
	v_and_b32_e32 v57, 0xffff0000, v57
	v_and_b32_e32 v56, 0xffff0000, v56
	v_pk_fma_f32 v[106:107], v[86:87], v[86:87], v[106:107]
	v_add_f32_e32 v94, v105, v94
	v_pk_mul_f32 v[108:109], v[56:57], v[56:57]
	v_add_f32_e32 v94, v106, v94
	v_lshlrev_b32_e32 v91, 16, v59
	v_lshlrev_b32_e32 v90, 16, v58
	v_and_b32_e32 v59, 0xffff0000, v59
	v_and_b32_e32 v58, 0xffff0000, v58
	v_pk_fma_f32 v[108:109], v[88:89], v[88:89], v[108:109]
	v_add_f32_e32 v94, v107, v94
	v_pk_mul_f32 v[110:111], v[58:59], v[58:59]
	v_add_f32_e32 v94, v108, v94
	v_lshlrev_b32_e32 v93, 16, v61
	v_lshlrev_b32_e32 v92, 16, v60
	v_and_b32_e32 v61, 0xffff0000, v61
	v_and_b32_e32 v60, 0xffff0000, v60
	v_pk_fma_f32 v[110:111], v[90:91], v[90:91], v[110:111]
	v_add_f32_e32 v94, v109, v94
	v_pk_mul_f32 v[112:113], v[60:61], v[60:61]
	v_add_f32_e32 v94, v110, v94
	v_pk_fma_f32 v[112:113], v[92:93], v[92:93], v[112:113]
	v_add_f32_e32 v94, v111, v94
	v_add_f32_e32 v94, v112, v94
	v_add_f32_e32 v94, v113, v94
	ds_bpermute_b32 v98, v3, v94
	s_waitcnt lgkmcnt(0)
	v_add_f32_e32 v98, v94, v98
	ds_bpermute_b32 v102, v40, v98
	s_waitcnt lgkmcnt(0)
	v_add_f32_e32 v102, v98, v102
	ds_bpermute_b32 v104, v41, v102
	s_waitcnt vmcnt(3)
	v_lshlrev_b32_e32 v97, 16, v63
	v_lshlrev_b32_e32 v96, 16, v62
	v_and_b32_e32 v63, 0xffff0000, v63
	s_waitcnt lgkmcnt(0)
	v_add_f32_e32 v104, v102, v104
	ds_bpermute_b32 v106, v42, v104
	v_and_b32_e32 v62, 0xffff0000, v62
	v_lshlrev_b32_e32 v101, 16, v65
	v_lshlrev_b32_e32 v100, 16, v64
	v_and_b32_e32 v65, 0xffff0000, v65
	s_waitcnt lgkmcnt(0)
	v_add_f32_e32 v106, v104, v106
	ds_bpermute_b32 v108, v43, v106
	v_and_b32_e32 v64, 0xffff0000, v64
	s_waitcnt vmcnt(0)
	v_lshlrev_b32_e32 v109, 16, v77
	v_and_b32_e32 v77, 0xffff0000, v77
	v_lshlrev_b32_e32 v95, 16, v67
	s_waitcnt lgkmcnt(0)
	v_add_f32_e32 v108, v106, v108
	ds_bpermute_b32 v110, v44, v108
	v_lshlrev_b32_e32 v94, 16, v66
	v_and_b32_e32 v67, 0xffff0000, v67
	v_and_b32_e32 v66, 0xffff0000, v66
	v_lshlrev_b32_e32 v99, 16, v69
	s_waitcnt lgkmcnt(0)
; __device__ __forceinline__ unsigned pk2(float lo, float hi) { return f2bf(lo) | (f2bf(hi) << 16); }
; __device__ __forceinline__ void postnorm(const Ctx& c, const bf16* MF, bf16* XB, float* RS, const float* gpost, float* OUT) {
;     ...
;         const float rs = rsqrtf(wave_sum(s) * (1.f / DM) + EPS);
;         float s2 = 0.f;
; #pragma unroll
;         for (int j = 0; j < 4; ++j) { const float* gp = gpost + (c.lane + 64 * j) * 8; const f32x4 g0 = *(CF4)gp, g1 = *(CF4)(gp + 4);
; #pragma unroll
;             for (int k = 0; k < 4; ++k) { const float ga = (k < 2) ? g0[2 * k] : g1[2 * k - 4], gb = (k < 2) ? g0[2 * k + 1] : g1[2 * k - 3];
;                 v[j][2 * k] = bflo(xv[j][k]) + v[j][2 * k] * rs * ga; v[j][2 * k + 1] = bfhi(xv[j][k]) + v[j][2 * k + 1] * rs * gb;
;                 s2 += v[j][2 * k] * v[j][2 * k] + v[j][2 * k + 1] * v[j][2 * k + 1]; } }
;         if (OUT) {
; #pragma unroll
;             for (int j = 0; j < 4; ++j) { float* op = OUT + (size_t)row * DM + (c.lane + 64 * j) * 8; *(f32x4*)op = (f32x4){v[j][0], v[j][1], v[j][2], v[j][3]}; *(f32x4*)(op + 4) = (f32x4){v[j][4], v[j][5], v[j][6], v[j][7]}; }
;         } else {
; #pragma unroll
;             for (int j = 0; j < 4; ++j) { v4u o; o.x = pk2(v[j][0], v[j][1]); o.y = pk2(v[j][2], v[j][3]); o.z = pk2(v[j][4], v[j][5]); o.w = pk2(v[j][6], v[j][7]); xr[64 * j] = o; }
;             const float rs2 = rsqrtf(wave_sum(s2) * (1.f / DM) + EPS); if (c.lane == 0) RS[row] = rs2;
	v_add_f32_e32 v108, v108, v110
	v_fmamk_f32 v108, v108, 0x3a000000, v45
	v_mul_f32_e32 v110, 0x4b800000, v108
	v_cmp_gt_f32_e32 vcc, s15, v108
	v_lshlrev_b32_e32 v98, 16, v68
	v_and_b32_e32 v69, 0xffff0000, v69
	v_cndmask_b32_e32 v108, v108, v110, vcc
	v_rsq_f32_e32 v110, v108
	v_lshlrev_b32_e32 v108, 16, v76
	v_and_b32_e32 v76, 0xffff0000, v76
	v_and_b32_e32 v68, 0xffff0000, v68
	v_mul_f32_e32 v111, 0x45800000, v110
	v_cndmask_b32_e32 v110, v110, v111, vcc
	v_pk_mul_f32 v[46:47], v[110:111], v[46:47] op_sel_hi:[0,1]
	v_pk_mul_f32 v[78:79], v[110:111], v[78:79] op_sel_hi:[0,1]
	v_pk_mul_f32 v[48:49], v[110:111], v[48:49] op_sel_hi:[0,1]
	v_pk_fma_f32 v[46:47], v[36:37], v[46:47], v[62:63]
	v_pk_mul_f32 v[60:61], v[110:111], v[60:61] op_sel_hi:[0,1]
	v_pk_mul_f32 v[80:81], v[110:111], v[80:81] op_sel_hi:[0,1]
	v_pk_fma_f32 v[78:79], v[8:9], v[78:79], v[96:97]
	v_pk_fma_f32 v[48:49], v[10:11], v[48:49], v[64:65]
	v_pk_fma_f32 v[60:61], v[34:35], v[60:61], v[76:77]
	v_pk_mul_f32 v[76:77], v[46:47], v[46:47]
	v_pk_mul_f32 v[50:51], v[110:111], v[50:51] op_sel_hi:[0,1]
	v_pk_fma_f32 v[62:63], v[4:5], v[80:81], v[100:101]
	v_pk_fma_f32 v[76:77], v[78:79], v[78:79], v[76:77]
	v_pk_mul_f32 v[80:81], v[48:49], v[48:49]
	v_pk_mul_f32 v[82:83], v[110:111], v[82:83] op_sel_hi:[0,1]
	v_pk_fma_f32 v[50:51], v[6:7], v[50:51], v[66:67]
	v_pk_fma_f32 v[80:81], v[62:63], v[62:63], v[80:81]
	v_add_f32_e32 v76, v76, v77
	v_pk_fma_f32 v[64:65], v[16:17], v[82:83], v[94:95]
	v_pk_mul_f32 v[82:83], v[50:51], v[50:51]
	v_add_f32_e32 v76, v80, v76
	v_pk_fma_f32 v[82:83], v[64:65], v[64:65], v[82:83]
	v_add_f32_e32 v76, v81, v76
	v_add_f32_e32 v76, v82, v76
	s_nop 2
	v_bfe_u32 v82, v46, 16, 1
	v_pk_mul_f32 v[52:53], v[110:111], v[52:53] op_sel_hi:[0,1]
	v_add3_u32 v46, v46, v82, s16
	s_nop 2
	v_bfe_u32 v77, v78, 16, 1
	s_nop 2
	v_pk_mul_f32 v[84:85], v[110:111], v[84:85] op_sel_hi:[0,1]
	v_pk_fma_f32 v[52:53], v[18:19], v[52:53], v[68:69]
	s_nop 2
	v_add3_u32 v77, v78, v77, s16
	v_lshlrev_b32_e32 v103, 16, v71
	v_lshlrev_b32_e32 v102, 16, v70
	v_and_b32_e32 v71, 0xffff0000, v71
	v_and_b32_e32 v70, 0xffff0000, v70
	v_pk_fma_f32 v[66:67], v[12:13], v[84:85], v[98:99]
	v_pk_mul_f32 v[54:55], v[110:111], v[54:55] op_sel_hi:[0,1]
	v_pk_mul_f32 v[84:85], v[52:53], v[52:53]
	v_lshrrev_b32_e32 v77, 16, v77
	s_nop 2
	v_pk_mul_f32 v[68:69], v[110:111], v[86:87] op_sel_hi:[0,1]
	v_pk_fma_f32 v[54:55], v[14:15], v[54:55], v[70:71]
	v_pk_fma_f32 v[84:85], v[66:67], v[66:67], v[84:85]
	v_add_f32_e32 v76, v83, v76
	v_cvt_pk_bf16_f32 v49, v63, v49
	v_cvt_pk_bf16_f32 v48, v62, v48
	v_cvt_pk_bf16_f32 v47, v79, v47
	v_and_or_b32 v46, v46, s14, v77
	v_lshlrev_b32_e32 v105, 16, v73
	v_lshlrev_b32_e32 v104, 16, v72
	v_and_b32_e32 v73, 0xffff0000, v73
	v_and_b32_e32 v72, 0xffff0000, v72
	v_pk_fma_f32 v[68:69], v[24:25], v[68:69], v[102:103]
	v_pk_mul_f32 v[56:57], v[110:111], v[56:57] op_sel_hi:[0,1]
	v_pk_mul_f32 v[86:87], v[54:55], v[54:55]
	v_add_f32_e32 v76, v84, v76
	global_store_dwordx4 v[38:39], v[46:49], off
	v_pk_mul_f32 v[70:71], v[110:111], v[88:89] op_sel_hi:[0,1]
	v_pk_fma_f32 v[56:57], v[26:27], v[56:57], v[72:73]
	s_nop 3
	v_pk_fma_f32 v[86:87], v[68:69], v[68:69], v[86:87]
	v_add_f32_e32 v76, v85, v76
	s_nop 7
	v_lshlrev_b32_e32 v107, 16, v75
	v_lshlrev_b32_e32 v106, 16, v74
	v_and_b32_e32 v75, 0xffff0000, v75
	v_and_b32_e32 v74, 0xffff0000, v74
	v_pk_fma_f32 v[70:71], v[20:21], v[70:71], v[104:105]
	v_pk_mul_f32 v[58:59], v[110:111], v[58:59] op_sel_hi:[0,1]
	v_pk_mul_f32 v[88:89], v[56:57], v[56:57]
	v_add_f32_e32 v76, v86, v76
	s_nop 3
	v_pk_mul_f32 v[72:73], v[110:111], v[90:91] op_sel_hi:[0,1]
	v_pk_fma_f32 v[58:59], v[22:23], v[58:59], v[74:75]
	v_pk_fma_f32 v[88:89], v[70:71], v[70:71], v[88:89]
	v_add_f32_e32 v76, v87, v76
	s_nop 3
	v_pk_fma_f32 v[72:73], v[32:33], v[72:73], v[106:107]
	v_pk_mul_f32 v[90:91], v[58:59], v[58:59]
	v_add_f32_e32 v76, v88, v76
	v_cvt_pk_bf16_f32 v49, v67, v53
	v_cvt_pk_bf16_f32 v48, v66, v52
	v_cvt_pk_bf16_f32 v47, v65, v51
	v_cvt_pk_bf16_f32 v46, v64, v50
	v_pk_mul_f32 v[74:75], v[110:111], v[92:93] op_sel_hi:[0,1]
	v_pk_fma_f32 v[90:91], v[72:73], v[72:73], v[90:91]
	v_add_f32_e32 v76, v89, v76
	global_store_dwordx4 v[38:39], v[46:49], off offset:1024
	v_pk_fma_f32 v[74:75], v[28:29], v[74:75], v[108:109]
	v_pk_mul_f32 v[92:93], v[60:61], v[60:61]
	s_nop 1
	v_add_f32_e32 v76, v90, v76
	s_nop 5
	v_pk_fma_f32 v[92:93], v[74:75], v[74:75], v[92:93]
	v_add_f32_e32 v76, v91, v76
	s_nop 5
	v_add_f32_e32 v76, v92, v76
	s_nop 5
	v_add_f32_e32 v76, v93, v76
	v_cvt_pk_bf16_f32 v49, v71, v57
	v_cvt_pk_bf16_f32 v48, v70, v56
	v_cvt_pk_bf16_f32 v47, v69, v55
	v_cvt_pk_bf16_f32 v46, v68, v54
	global_store_dwordx4 v[38:39], v[46:49], off offset:2048
	ds_bpermute_b32 v47, v3, v76
	s_nop 3
	s_waitcnt lgkmcnt(0)
	v_add_f32_e32 v47, v76, v47
	ds_bpermute_b32 v50, v40, v47
	s_nop 3
	s_waitcnt lgkmcnt(0)
	v_add_f32_e32 v47, v47, v50
	ds_bpermute_b32 v50, v41, v47
	s_nop 1
	v_cvt_pk_bf16_f32 v51, v75, v61
	s_nop 0
	s_waitcnt lgkmcnt(0)
	v_add_f32_e32 v47, v47, v50
	ds_bpermute_b32 v50, v42, v47
	s_nop 3
	s_waitcnt lgkmcnt(0)
	v_add_f32_e32 v47, v47, v50
	ds_bpermute_b32 v50, v43, v47
	s_nop 3
	s_waitcnt lgkmcnt(0)
	v_add_f32_e32 v46, v47, v50
	ds_bpermute_b32 v47, v44, v46
	s_nop 0
	v_cvt_pk_bf16_f32 v50, v74, v60
	v_cvt_pk_bf16_f32 v49, v73, v59
	v_cvt_pk_bf16_f32 v48, v72, v58
	global_store_dwordx4 v[38:39], v[48:51], off offset:3072
	s_and_saveexec_b64 s[10:11], s[0:1]
	s_cbranch_execz .LBB0_1187
	s_waitcnt lgkmcnt(0)
	v_add_f32_e32 v38, v46, v47
	v_fmamk_f32 v38, v38, 0x3a000000, v45
	v_mul_f32_e32 v39, 0x4b800000, v38
	v_cmp_gt_f32_e32 vcc, s15, v38
	v_readlane_b32 s18, v253, 0
	v_readlane_b32 s19, v253, 1
	v_cndmask_b32_e32 v38, v38, v39, vcc
	v_rsq_f32_e32 v38, v38
	s_add_u32 s18, s18, s12
	s_addc_u32 s19, s19, s13
	v_mul_f32_e32 v39, 0x45800000, v38
	v_cndmask_b32_e32 v38, v38, v39, vcc
	global_store_dword v251, v38, s[18:19]
	s_branch .LBB0_1187

; __device__ __forceinline__ unsigned pk2(float lo, float hi) { return f2bf(lo) | (f2bf(hi) << 16); }
; __device__ __forceinline__ float silu_fast(float x) { return x * __builtin_amdgcn_rcpf(1.f + __builtin_amdgcn_exp2f(-1.4426950408889634f * x)); }
; __device__ __forceinline__ float dpp_shr1(float x) { return __builtin_bit_cast(float, __builtin_amdgcn_update_dpp(0, __builtin_bit_cast(int, x), 0x111, 0xf, 0xf, true)); }
;     __device__ __forceinline__ void operator()(const f32x4 (&acc)[2][2][4][2], const pg8::Unit& u, int wr, int wc, int fr, int fq) const {
;     ...
;             const int cc = ch0 + 4 * n;
;             const f32x4 wg0 = *(CF4)(cw + cc), wg1 = *(CF4)(cw + FF2 + cc), wg2 = *(CF4)(cw + 2 * FF2 + cc), wv0 = *(CF4)(cw + FFH + cc), wv1 = *(CF4)(cw + FF2 + FFH + cc), wv2 = *(CF4)(cw + 2 * FF2 + FFH + cc);
;             const f32x4 bg = *(CF4)(cb + cc), bv = *(CF4)(cb + FFH + cc);
; #pragma unroll
;             for (int jj = 0; jj < 4; ++jj) {
;                 float g2 = dpp_shr1(g[6][jj]), g1 = dpp_shr1(g[7][jj]), v2 = dpp_shr1(v[6][jj]), v1 = dpp_shr1(v[7][jj]);
; #pragma unroll
;                 for (int e = 0; e < 8; ++e) { const float g0 = g[e][jj], v0 = v[e][jj];
;                     const float cg = bg[jj] + wg0[jj] * g2 + wg1[jj] * g1 + wg2[jj] * g0, cv = bv[jj] + wv0[jj] * v2 + wv1[jj] * v1 + wv2[jj] * v0;
;                     g[e][jj] = silu_fast(cg) * cv; g2 = g1; g1 = g0; v2 = v1; v1 = v0; } }
; #pragma unroll
;             for (int e = 0; e < 8; ++e) { v2u w; w.x = pk2(g[e][0], g[e][1]); w.y = pk2(g[e][2], g[e][3]); *(v2u*)(ACT + (size_t)(tok0 + e) * FFH + cc) = w; }
.LBB0_1249:
	s_or_b64 exec, exec, s[28:29]
	v_or_b32_e32 v38, 4, v132
	v_ashrrev_i32_e32 v39, 31, v38
	v_lshlrev_b64 v[64:65], 2, v[38:39]
	v_lshl_add_u64 v[38:39], s[8:9], 0, v[64:65]
	v_lshl_add_u64 v[44:45], s[14:15], 0, v[64:65]
	global_load_dwordx4 v[56:59], v[38:39], off
	global_load_dwordx4 v[52:55], v[138:139], off offset:16
	v_lshl_add_u64 v[48:49], s[16:17], 0, v[64:65]
	global_load_dwordx4 v[44:47], v[44:45], off
	v_lshl_add_u64 v[38:39], s[10:11], 0, v[64:65]
	global_load_dwordx4 v[60:63], v[38:39], off
	v_lshl_add_u64 v[38:39], s[12:13], 0, v[64:65]
	global_load_dwordx4 v[38:41], v[38:39], off
	s_nop 0
	global_load_dwordx4 v[48:51], v[48:49], off
	s_nop 0
	global_load_dwordx4 v[68:71], v[134:135], off offset:16
	v_lshl_add_u64 v[64:65], s[18:19], 0, v[64:65]
	global_load_dwordx4 v[64:67], v[64:65], off
	v_mov_b32_dpp v106, v88 row_shr:1 row_mask:0xf bank_mask:0xf bound_ctrl:1
	v_mov_b32_dpp v107, v89 row_shr:1 row_mask:0xf bank_mask:0xf bound_ctrl:1
	v_mov_b32_dpp v136, v94 row_shr:1 row_mask:0xf bank_mask:0xf bound_ctrl:1
	v_mov_b32_dpp v137, v95 row_shr:1 row_mask:0xf bank_mask:0xf bound_ctrl:1
	v_mov_b32_dpp v158, v86 row_shr:1 row_mask:0xf bank_mask:0xf bound_ctrl:1
	v_mov_b32_dpp v159, v87 row_shr:1 row_mask:0xf bank_mask:0xf bound_ctrl:1
	v_mov_b32_dpp v134, v90 row_shr:1 row_mask:0xf bank_mask:0xf bound_ctrl:1
	v_mov_b32_dpp v135, v91 row_shr:1 row_mask:0xf bank_mask:0xf bound_ctrl:1
	v_mov_b32_dpp v138, v82 row_shr:1 row_mask:0xf bank_mask:0xf bound_ctrl:1
	v_mov_b32_dpp v160, v72 row_shr:1 row_mask:0xf bank_mask:0xf bound_ctrl:1
	v_mov_b32_dpp v139, v83 row_shr:1 row_mask:0xf bank_mask:0xf bound_ctrl:1
	v_mov_b32_dpp v161, v73 row_shr:1 row_mask:0xf bank_mask:0xf bound_ctrl:1
	v_mov_b32_dpp v132, v84 row_shr:1 row_mask:0xf bank_mask:0xf bound_ctrl:1
	v_mov_b32_dpp v130, v74 row_shr:1 row_mask:0xf bank_mask:0xf bound_ctrl:1
	v_mov_b32_dpp v133, v85 row_shr:1 row_mask:0xf bank_mask:0xf bound_ctrl:1
	v_mov_b32_dpp v131, v75 row_shr:1 row_mask:0xf bank_mask:0xf bound_ctrl:1
	s_andn2_b64 vcc, exec, s[0:1]
	s_mov_b32 s57, s20
	s_mov_b32 s28, s22
	s_mov_b64 s[34:35], s[26:27]
	s_mov_b64 s[30:31], s[24:25]
	s_waitcnt vmcnt(0)
	v_mov_b32_e32 v98, v52
	v_mov_b32_e32 v99, v54
	v_mov_b32_e32 v54, v53
	v_mov_b32_e32 v102, v68
	v_mov_b32_e32 v103, v70
	v_pk_fma_f32 v[110:111], v[98:99], v[106:107], v[102:103]
	v_mov_b32_e32 v106, v56
	v_mov_b32_e32 v107, v58
	v_pk_fma_f32 v[162:163], v[106:107], v[136:137], v[110:111]
	v_mov_b32_e32 v110, v60
	v_mov_b32_e32 v111, v62
	v_pk_fma_f32 v[162:163], v[126:127], v[110:111], v[162:163]
	v_mov_b32_e32 v70, v69
	v_mul_f32_e32 v52, 0xbfb8aa3b, v162
	v_exp_f32_e32 v52, v52
	v_mov_b32_e32 v58, v57
	v_mov_b32_e32 v62, v61
	v_mov_b32_e32 v60, v44
	v_add_f32_e32 v52, 1.0, v52
	v_rcp_f32_e32 v168, v52
	v_pk_fma_f32 v[52:53], v[54:55], v[158:159], v[70:71]
	v_mov_b32_e32 v56, v64
	v_pk_fma_f32 v[52:53], v[58:59], v[134:135], v[52:53]
	v_mov_b32_e32 v57, v66
	v_pk_fma_f32 v[158:159], v[124:125], v[62:63], v[52:53]
	v_mov_b32_e32 v53, v40
	v_mul_f32_e32 v52, 0xbfb8aa3b, v158
	v_exp_f32_e32 v52, v52
	v_mul_f32_e32 v44, 0xbfb8aa3b, v159
	v_exp_f32_e32 v44, v44
	v_mov_b32_e32 v40, v39
	v_add_f32_e32 v52, 1.0, v52
	v_rcp_f32_e32 v172, v52
	v_mov_b32_e32 v52, v38
	v_mul_f32_e32 v38, 0xbfb8aa3b, v163
	v_exp_f32_e32 v38, v38
	v_add_f32_e32 v44, 1.0, v44
	v_rcp_f32_e32 v173, v44
	v_mov_b32_e32 v66, v65
	v_add_f32_e32 v38, 1.0, v38
	v_pk_fma_f32 v[68:69], v[52:53], v[138:139], v[56:57]
	v_mov_b32_e32 v61, v46
	v_rcp_f32_e32 v169, v38
	v_pk_fma_f32 v[38:39], v[40:41], v[160:161], v[66:67]
	v_mov_b32_e32 v46, v45
	v_pk_fma_f32 v[138:139], v[60:61], v[132:133], v[68:69]
	v_mov_b32_e32 v69, v50
	v_pk_fma_f32 v[38:39], v[46:47], v[130:131], v[38:39]
	v_mov_b32_e32 v50, v49
	v_pk_fma_f32 v[38:39], v[120:121], v[50:51], v[38:39]
	v_pk_mul_f32 v[44:45], v[158:159], v[172:173]
	v_mov_b32_e32 v68, v48
	v_pk_mul_f32 v[38:39], v[38:39], v[44:45]
	v_pk_fma_f32 v[138:139], v[122:123], v[68:69], v[138:139]
	v_pk_mul_f32 v[162:163], v[162:163], v[168:169]
	s_nop 1
	v_pk_mul_f32 v[138:139], v[138:139], v[162:163]
	s_nop 1
	v_pk_fma_f32 v[48:49], v[54:55], v[134:135], v[70:71]
	s_nop 0
	v_pk_fma_f32 v[48:49], v[124:125], v[58:59], v[48:49]
	s_nop 1
	v_pk_fma_f32 v[48:49], v[116:117], v[62:63], v[48:49]
	s_nop 0
	v_cvt_pk_bf16_f32 v38, v138, v38
	v_mul_f32_e32 v45, 0xbfb8aa3b, v48
	s_nop 1
	v_exp_f32_e32 v45, v45
	v_cvt_pk_bf16_f32 v39, v139, v39
	global_store_dwordx2 v[170:171], v[38:39], off offset:8
	v_pk_fma_f32 v[38:39], v[98:99], v[136:137], v[102:103]
	v_add_f32_e32 v45, 1.0, v45
	v_pk_fma_f32 v[38:39], v[126:127], v[106:107], v[38:39]
	v_rcp_f32_e32 v64, v45
	v_pk_fma_f32 v[38:39], v[112:113], v[110:111], v[38:39]
	v_mul_f32_e32 v65, 0xbfb8aa3b, v49
	v_mul_f32_e32 v44, 0xbfb8aa3b, v38
	v_mul_f32_e32 v45, 0xbfb8aa3b, v39
	v_exp_f32_e32 v44, v44
	v_exp_f32_e32 v45, v45
	v_exp_f32_e32 v65, v65
	v_pk_fma_f32 v[132:133], v[52:53], v[132:133], v[56:57]
	v_add_f32_e32 v44, 1.0, v44
	v_add_f32_e32 v45, 1.0, v45
	v_rcp_f32_e32 v44, v44
	v_rcp_f32_e32 v45, v45
	v_add_f32_e32 v65, 1.0, v65
	v_rcp_f32_e32 v65, v65
	v_pk_fma_f32 v[132:133], v[122:123], v[60:61], v[132:133]
	v_pk_mul_f32 v[38:39], v[38:39], v[44:45]
	v_pk_fma_f32 v[44:45], v[40:41], v[130:131], v[66:67]
	v_pk_fma_f32 v[132:133], v[114:115], v[68:69], v[132:133]
	v_pk_fma_f32 v[44:45], v[120:121], v[46:47], v[44:45]
	v_pk_mul_f32 v[38:39], v[132:133], v[38:39]
	v_pk_fma_f32 v[44:45], v[118:119], v[50:51], v[44:45]
	v_pk_mul_f32 v[48:49], v[48:49], v[64:65]
	s_nop 0
	v_pk_mul_f32 v[44:45], v[44:45], v[48:49]
	s_nop 7
	s_nop 1
	v_cvt_pk_bf16_f32 v39, v39, v45
; __device__ __forceinline__ unsigned pk2(float lo, float hi) { return f2bf(lo) | (f2bf(hi) << 16); }
; __device__ __forceinline__ float silu_fast(float x) { return x * __builtin_amdgcn_rcpf(1.f + __builtin_amdgcn_exp2f(-1.4426950408889634f * x)); }
; __device__ __forceinline__ float dpp_shr1(float x) { return __builtin_bit_cast(float, __builtin_amdgcn_update_dpp(0, __builtin_bit_cast(int, x), 0x111, 0xf, 0xf, true)); }
;     __device__ __forceinline__ void operator()(const f32x4 (&acc)[2][2][4][2], const pg8::Unit& u, int wr, int wc, int fr, int fq) const {
;     ...
;             for (int jj = 0; jj < 4; ++jj) {
;                 float g2 = dpp_shr1(g[6][jj]), g1 = dpp_shr1(g[7][jj]), v2 = dpp_shr1(v[6][jj]), v1 = dpp_shr1(v[7][jj]);
; #pragma unroll
;                 for (int e = 0; e < 8; ++e) { const float g0 = g[e][jj], v0 = v[e][jj];
;                     const float cg = bg[jj] + wg0[jj] * g2 + wg1[jj] * g1 + wg2[jj] * g0, cv = bv[jj] + wv0[jj] * v2 + wv1[jj] * v1 + wv2[jj] * v0;
;                     g[e][jj] = silu_fast(cg) * cv; g2 = g1; g1 = g0; v2 = v1; v1 = v0; } }
; #pragma unroll
;             for (int e = 0; e < 8; ++e) { v2u w; w.x = pk2(g[e][0], g[e][1]); w.y = pk2(g[e][2], g[e][3]); *(v2u*)(ACT + (size_t)(tok0 + e) * FFH + cc) = w; }
	v_cvt_pk_bf16_f32 v38, v38, v44
	v_mov_b32_e32 v44, v33
	v_mov_b32_e32 v45, v35
	v_mov_b32_e32 v33, v34
	v_pk_fma_f32 v[34:35], v[124:125], v[54:55], v[70:71]
	v_pk_mul_f32 v[44:45], v[44:45], v[128:129]
	v_pk_fma_f32 v[34:35], v[116:117], v[58:59], v[34:35]
	global_store_dwordx2 v[108:109], v[38:39], off offset:8
	v_pk_fma_f32 v[34:35], v[44:45], v[62:63], v[34:35]
	v_mov_b32_e32 v39, v31
	v_mul_f32_e32 v31, 0xbfb8aa3b, v34
	v_exp_f32_e32 v31, v31
	v_mov_b32_e32 v38, v29
	v_mov_b32_e32 v29, v30
	v_pk_mul_f32 v[48:49], v[28:29], v[128:129]
	v_pk_fma_f32 v[28:29], v[126:127], v[98:99], v[102:103]
	v_pk_mul_f32 v[32:33], v[32:33], v[128:129]
	v_pk_fma_f32 v[28:29], v[112:113], v[106:107], v[28:29]
	v_add_f32_e32 v31, 1.0, v31
	v_pk_fma_f32 v[28:29], v[32:33], v[110:111], v[28:29]
	v_rcp_f32_e32 v64, v31
	v_mul_f32_e32 v30, 0xbfb8aa3b, v28
	v_mul_f32_e32 v31, 0xbfb8aa3b, v29
	v_exp_f32_e32 v30, v30
	v_exp_f32_e32 v31, v31
	v_mul_f32_e32 v65, 0xbfb8aa3b, v35
	v_exp_f32_e32 v65, v65
	v_add_f32_e32 v30, 1.0, v30
	v_add_f32_e32 v31, 1.0, v31
	v_rcp_f32_e32 v30, v30
	v_rcp_f32_e32 v31, v31
	v_add_f32_e32 v65, 1.0, v65
	v_rcp_f32_e32 v65, v65
	v_pk_fma_f32 v[108:109], v[122:123], v[52:53], v[56:57]
	v_pk_mul_f32 v[28:29], v[28:29], v[30:31]
	v_pk_fma_f32 v[108:109], v[114:115], v[60:61], v[108:109]
	v_pk_fma_f32 v[30:31], v[120:121], v[40:41], v[66:67]
	v_pk_mul_f32 v[38:39], v[38:39], v[128:129]
	v_pk_fma_f32 v[108:109], v[48:49], v[68:69], v[108:109]
	v_pk_fma_f32 v[30:31], v[118:119], v[46:47], v[30:31]
	v_pk_mul_f32 v[28:29], v[108:109], v[28:29]
	v_pk_fma_f32 v[30:31], v[38:39], v[50:51], v[30:31]
	v_pk_mul_f32 v[34:35], v[34:35], v[64:65]
	s_nop 0
	v_pk_mul_f32 v[30:31], v[30:31], v[34:35]
	s_nop 7
	s_nop 1
	v_cvt_pk_bf16_f32 v29, v29, v31
	v_cvt_pk_bf16_f32 v28, v28, v30
	v_mov_b32_e32 v30, v25
	v_mov_b32_e32 v31, v27
	v_pk_fma_f32 v[34:35], v[116:117], v[54:55], v[70:71]
	v_pk_mul_f32 v[30:31], v[30:31], v[42:43]
	v_pk_fma_f32 v[34:35], v[44:45], v[58:59], v[34:35]
	v_mov_b32_e32 v25, v26
	v_pk_fma_f32 v[34:35], v[30:31], v[62:63], v[34:35]
	global_store_dwordx2 v[104:105], v[28:29], off offset:8
	v_mul_f32_e32 v65, 0xbfb8aa3b, v34
	v_exp_f32_e32 v65, v65
	v_mov_b32_e32 v28, v21
	v_mov_b32_e32 v29, v23
	v_mov_b32_e32 v21, v22
	v_pk_mul_f32 v[22:23], v[24:25], v[42:43]
	v_pk_fma_f32 v[24:25], v[112:113], v[98:99], v[102:103]
	v_add_f32_e32 v65, 1.0, v65
	v_pk_fma_f32 v[24:25], v[32:33], v[106:107], v[24:25]
	v_rcp_f32_e32 v104, v65
	v_pk_fma_f32 v[24:25], v[22:23], v[110:111], v[24:25]
	v_pk_fma_f32 v[26:27], v[114:115], v[52:53], v[56:57]
	v_mul_f32_e32 v64, 0xbfb8aa3b, v24
	v_mul_f32_e32 v65, 0xbfb8aa3b, v25
	v_exp_f32_e32 v64, v64
	v_exp_f32_e32 v65, v65
	v_pk_mul_f32 v[20:21], v[20:21], v[42:43]
	v_pk_fma_f32 v[26:27], v[48:49], v[60:61], v[26:27]
	v_add_f32_e32 v64, 1.0, v64
	v_add_f32_e32 v65, 1.0, v65
	v_rcp_f32_e32 v64, v64
	v_rcp_f32_e32 v65, v65
	v_pk_mul_f32 v[28:29], v[28:29], v[42:43]
	v_pk_fma_f32 v[42:43], v[118:119], v[40:41], v[66:67]
	v_pk_fma_f32 v[26:27], v[20:21], v[68:69], v[26:27]
	v_pk_mul_f32 v[24:25], v[24:25], v[64:65]
	s_nop 0
	v_pk_mul_f32 v[24:25], v[26:27], v[24:25]
	v_pk_fma_f32 v[26:27], v[38:39], v[46:47], v[42:43]
	v_mul_f32_e32 v42, 0xbfb8aa3b, v35
	v_exp_f32_e32 v42, v42
	v_pk_fma_f32 v[26:27], v[28:29], v[50:51], v[26:27]
	v_add_f32_e32 v42, 1.0, v42
	v_rcp_f32_e32 v105, v42
	s_nop 0
	v_pk_mul_f32 v[34:35], v[34:35], v[104:105]
	s_nop 0
	v_pk_mul_f32 v[26:27], v[26:27], v[34:35]
	s_nop 7
	s_nop 1
	v_cvt_pk_bf16_f32 v25, v25, v27
	v_cvt_pk_bf16_f32 v24, v24, v26
	v_mov_b32_e32 v26, v17
	v_mov_b32_e32 v27, v19
	v_mov_b32_e32 v17, v18
	v_pk_fma_f32 v[18:19], v[44:45], v[54:55], v[70:71]
	v_pk_mul_f32 v[26:27], v[26:27], v[92:93]
	v_pk_fma_f32 v[18:19], v[30:31], v[58:59], v[18:19]
	global_store_dwordx2 v[100:101], v[24:25], off offset:8
	v_mov_b32_e32 v24, v13
	v_mov_b32_e32 v13, v14
	v_pk_fma_f32 v[18:19], v[26:27], v[62:63], v[18:19]
	v_pk_mul_f32 v[34:35], v[12:13], v[92:93]
	v_pk_fma_f32 v[12:13], v[32:33], v[98:99], v[102:103]
	v_pk_fma_f32 v[32:33], v[38:39], v[40:41], v[66:67]
	v_mul_f32_e32 v39, 0xbfb8aa3b, v18
	v_exp_f32_e32 v39, v39
	v_pk_mul_f32 v[16:17], v[16:17], v[92:93]
	v_pk_fma_f32 v[12:13], v[22:23], v[106:107], v[12:13]
	v_mov_b32_e32 v25, v15
	v_pk_fma_f32 v[12:13], v[16:17], v[110:111], v[12:13]
	v_add_f32_e32 v39, 1.0, v39
	v_mul_f32_e32 v38, 0xbfb8aa3b, v12
	v_rcp_f32_e32 v42, v39
	v_mul_f32_e32 v39, 0xbfb8aa3b, v13
	v_exp_f32_e32 v38, v38
	v_exp_f32_e32 v39, v39
	v_pk_fma_f32 v[14:15], v[48:49], v[52:53], v[56:57]
	v_pk_mul_f32 v[24:25], v[24:25], v[92:93]
	v_add_f32_e32 v38, 1.0, v38
	v_add_f32_e32 v39, 1.0, v39
	v_rcp_f32_e32 v38, v38
	v_rcp_f32_e32 v39, v39
	v_pk_fma_f32 v[14:15], v[20:21], v[60:61], v[14:15]
	v_pk_mul_f32 v[12:13], v[12:13], v[38:39]
	v_pk_fma_f32 v[14:15], v[34:35], v[68:69], v[14:15]
	s_nop 0
	v_pk_mul_f32 v[12:13], v[14:15], v[12:13]
	v_pk_fma_f32 v[14:15], v[28:29], v[46:47], v[32:33]
	v_mul_f32_e32 v32, 0xbfb8aa3b, v19
	v_exp_f32_e32 v32, v32
	v_pk_fma_f32 v[14:15], v[24:25], v[50:51], v[14:15]
	v_add_f32_e32 v32, 1.0, v32
	v_rcp_f32_e32 v43, v32
	s_nop 0
	v_pk_mul_f32 v[18:19], v[18:19], v[42:43]
	s_nop 0
	v_pk_mul_f32 v[14:15], v[14:15], v[18:19]
	s_nop 7
	s_nop 1
; __device__ __forceinline__ unsigned pk2(float lo, float hi) { return f2bf(lo) | (f2bf(hi) << 16); }
; __device__ __forceinline__ float silu_fast(float x) { return x * __builtin_amdgcn_rcpf(1.f + __builtin_amdgcn_exp2f(-1.4426950408889634f * x)); }
; __device__ __forceinline__ float dpp_shr1(float x) { return __builtin_bit_cast(float, __builtin_amdgcn_update_dpp(0, __builtin_bit_cast(int, x), 0x111, 0xf, 0xf, true)); }
;     __device__ __forceinline__ void operator()(const f32x4 (&acc)[2][2][4][2], const pg8::Unit& u, int wr, int wc, int fr, int fq) const {
;     ...
;             for (int jj = 0; jj < 4; ++jj) {
;                 float g2 = dpp_shr1(g[6][jj]), g1 = dpp_shr1(g[7][jj]), v2 = dpp_shr1(v[6][jj]), v1 = dpp_shr1(v[7][jj]);
; #pragma unroll
;                 for (int e = 0; e < 8; ++e) { const float g0 = g[e][jj], v0 = v[e][jj];
;                     const float cg = bg[jj] + wg0[jj] * g2 + wg1[jj] * g1 + wg2[jj] * g0, cv = bv[jj] + wv0[jj] * v2 + wv1[jj] * v1 + wv2[jj] * v0;
;                     g[e][jj] = silu_fast(cg) * cv; g2 = g1; g1 = g0; v2 = v1; v1 = v0; } }
; #pragma unroll
;             for (int e = 0; e < 8; ++e) { v2u w; w.x = pk2(g[e][0], g[e][1]); w.y = pk2(g[e][2], g[e][3]); *(v2u*)(ACT + (size_t)(tok0 + e) * FFH + cc) = w; }
	v_cvt_pk_bf16_f32 v13, v13, v15
	v_cvt_pk_bf16_f32 v12, v12, v14
	v_mov_b32_e32 v14, v9
	v_mov_b32_e32 v15, v11
	v_pk_fma_f32 v[18:19], v[30:31], v[54:55], v[70:71]
	v_pk_mul_f32 v[14:15], v[14:15], v[36:37]
	v_pk_fma_f32 v[18:19], v[26:27], v[58:59], v[18:19]
	v_mov_b32_e32 v9, v10
	v_pk_fma_f32 v[18:19], v[14:15], v[62:63], v[18:19]
	global_store_dwordx2 v[96:97], v[12:13], off offset:8
	v_mov_b32_e32 v12, v5
	v_mov_b32_e32 v13, v7
	v_mov_b32_e32 v5, v6
	v_pk_mul_f32 v[6:7], v[8:9], v[36:37]
	v_pk_fma_f32 v[8:9], v[22:23], v[98:99], v[102:103]
	v_mul_f32_e32 v23, 0xbfb8aa3b, v18
	v_exp_f32_e32 v23, v23
	v_pk_fma_f32 v[8:9], v[16:17], v[106:107], v[8:9]
	v_pk_fma_f32 v[10:11], v[20:21], v[52:53], v[56:57]
	v_pk_fma_f32 v[8:9], v[6:7], v[110:111], v[8:9]
	v_add_f32_e32 v23, 1.0, v23
	v_pk_fma_f32 v[20:21], v[28:29], v[40:41], v[66:67]
	v_mul_f32_e32 v22, 0xbfb8aa3b, v8
	v_rcp_f32_e32 v28, v23
	v_mul_f32_e32 v23, 0xbfb8aa3b, v9
	v_exp_f32_e32 v22, v22
	v_exp_f32_e32 v23, v23
	v_pk_mul_f32 v[4:5], v[4:5], v[36:37]
	v_pk_fma_f32 v[10:11], v[34:35], v[60:61], v[10:11]
	v_add_f32_e32 v22, 1.0, v22
	v_add_f32_e32 v23, 1.0, v23
	v_rcp_f32_e32 v22, v22
	v_rcp_f32_e32 v23, v23
	v_pk_fma_f32 v[10:11], v[4:5], v[68:69], v[10:11]
	v_pk_mul_f32 v[12:13], v[12:13], v[36:37]
	v_pk_mul_f32 v[8:9], v[8:9], v[22:23]
	s_nop 0
	v_pk_mul_f32 v[8:9], v[10:11], v[8:9]
	v_pk_fma_f32 v[10:11], v[24:25], v[46:47], v[20:21]
	v_mul_f32_e32 v20, 0xbfb8aa3b, v19
	v_exp_f32_e32 v20, v20
	v_pk_fma_f32 v[10:11], v[12:13], v[50:51], v[10:11]
	v_add_f32_e32 v20, 1.0, v20
	v_rcp_f32_e32 v29, v20
	s_nop 0
	v_pk_mul_f32 v[18:19], v[18:19], v[28:29]
	s_nop 0
	v_pk_mul_f32 v[10:11], v[10:11], v[18:19]
	s_nop 7
	s_nop 1
	v_cvt_pk_bf16_f32 v9, v9, v11
	v_cvt_pk_bf16_f32 v8, v8, v10
	global_store_dwordx2 v[80:81], v[8:9], off offset:8
	v_pk_fma_f32 v[8:9], v[16:17], v[98:99], v[102:103]
	v_pk_fma_f32 v[16:17], v[26:27], v[54:55], v[70:71]
	v_pk_fma_f32 v[8:9], v[6:7], v[106:107], v[8:9]
	v_pk_fma_f32 v[16:17], v[14:15], v[58:59], v[16:17]
	v_pk_fma_f32 v[8:9], v[88:89], v[110:111], v[8:9]
	v_pk_fma_f32 v[16:17], v[86:87], v[62:63], v[16:17]
	v_mul_f32_e32 v20, 0xbfb8aa3b, v8
	v_mul_f32_e32 v21, 0xbfb8aa3b, v16
	v_exp_f32_e32 v21, v21
	v_exp_f32_e32 v20, v20
	v_pk_fma_f32 v[10:11], v[34:35], v[52:53], v[56:57]
	v_pk_fma_f32 v[18:19], v[24:25], v[40:41], v[66:67]
	v_add_f32_e32 v21, 1.0, v21
	v_rcp_f32_e32 v22, v21
	v_mul_f32_e32 v21, 0xbfb8aa3b, v9
	v_exp_f32_e32 v21, v21
	v_add_f32_e32 v20, 1.0, v20
	v_rcp_f32_e32 v20, v20
	v_pk_fma_f32 v[10:11], v[4:5], v[60:61], v[10:11]
	v_add_f32_e32 v21, 1.0, v21
	v_rcp_f32_e32 v21, v21
	v_pk_fma_f32 v[10:11], v[82:83], v[68:69], v[10:11]
	v_pk_fma_f32 v[6:7], v[6:7], v[98:99], v[102:103]
	v_pk_fma_f32 v[4:5], v[4:5], v[52:53], v[56:57]
	v_pk_mul_f32 v[8:9], v[8:9], v[20:21]
	v_pk_fma_f32 v[6:7], v[88:89], v[106:107], v[6:7]
	v_pk_mul_f32 v[8:9], v[10:11], v[8:9]
	v_pk_fma_f32 v[10:11], v[12:13], v[46:47], v[18:19]
	v_mul_f32_e32 v18, 0xbfb8aa3b, v17
	v_exp_f32_e32 v18, v18
	v_pk_fma_f32 v[10:11], v[72:73], v[50:51], v[10:11]
	v_pk_fma_f32 v[6:7], v[94:95], v[110:111], v[6:7]
	v_pk_fma_f32 v[4:5], v[82:83], v[60:61], v[4:5]
	v_add_f32_e32 v18, 1.0, v18
	v_rcp_f32_e32 v23, v18
	v_pk_fma_f32 v[4:5], v[84:85], v[68:69], v[4:5]
	v_pk_mul_f32 v[16:17], v[16:17], v[22:23]
	s_nop 0
	v_pk_mul_f32 v[10:11], v[10:11], v[16:17]
	s_nop 7
	s_nop 1
	v_cvt_pk_bf16_f32 v9, v9, v11
	v_cvt_pk_bf16_f32 v8, v8, v10
	v_pk_fma_f32 v[10:11], v[14:15], v[54:55], v[70:71]
	global_store_dwordx2 v[78:79], v[8:9], off offset:8
	v_pk_fma_f32 v[10:11], v[86:87], v[58:59], v[10:11]
	v_mul_f32_e32 v8, 0xbfb8aa3b, v6
	v_pk_fma_f32 v[10:11], v[90:91], v[62:63], v[10:11]
	v_exp_f32_e32 v8, v8
	v_mul_f32_e32 v9, 0xbfb8aa3b, v10
	v_exp_f32_e32 v9, v9
	v_add_f32_e32 v8, 1.0, v8
	v_rcp_f32_e32 v8, v8
	v_add_f32_e32 v9, 1.0, v9
	v_rcp_f32_e32 v14, v9
	v_mul_f32_e32 v9, 0xbfb8aa3b, v7
	v_exp_f32_e32 v9, v9
	s_nop 0
	v_add_f32_e32 v9, 1.0, v9
	v_rcp_f32_e32 v9, v9
	s_nop 0
	v_pk_mul_f32 v[6:7], v[6:7], v[8:9]
	v_mul_f32_e32 v8, 0xbfb8aa3b, v11
	v_exp_f32_e32 v8, v8
	v_pk_mul_f32 v[4:5], v[4:5], v[6:7]
	v_pk_fma_f32 v[6:7], v[12:13], v[40:41], v[66:67]
	v_add_f32_e32 v8, 1.0, v8
	v_rcp_f32_e32 v15, v8
	v_pk_fma_f32 v[6:7], v[72:73], v[46:47], v[6:7]
	v_pk_mul_f32 v[8:9], v[10:11], v[14:15]
	v_pk_fma_f32 v[6:7], v[74:75], v[50:51], v[6:7]
	s_nop 0
	v_pk_mul_f32 v[6:7], v[6:7], v[8:9]
	v_and_b32_sdwa v8, v5, v238 dst_sel:DWORD dst_unused:UNUSED_PAD src0_sel:WORD_1 src1_sel:DWORD
	v_and_b32_sdwa v9, v4, v238 dst_sel:DWORD dst_unused:UNUSED_PAD src0_sel:WORD_1 src1_sel:DWORD
	v_add3_u32 v4, v4, v9, s55
	v_add3_u32 v5, v5, v8, s55
	v_and_b32_sdwa v8, v7, v238 dst_sel:DWORD dst_unused:UNUSED_PAD src0_sel:WORD_1 src1_sel:DWORD
	v_and_b32_sdwa v9, v6, v238 dst_sel:DWORD dst_unused:UNUSED_PAD src0_sel:WORD_1 src1_sel:DWORD
	v_add3_u32 v7, v7, v8, s55
	v_add3_u32 v6, v6, v9, s55
	v_and_b32_e32 v7, 0xffff0000, v7
	v_and_b32_e32 v6, 0xffff0000, v6
	v_or_b32_sdwa v5, v7, v5 dst_sel:DWORD dst_unused:UNUSED_PAD src0_sel:DWORD src1_sel:WORD_1
	v_or_b32_sdwa v4, v6, v4 dst_sel:DWORD dst_unused:UNUSED_PAD src0_sel:DWORD src1_sel:WORD_1
	global_store_dwordx2 v[76:77], v[4:5], off offset:8
	s_cbranch_vccz .LBB0_1268

; #define PG8_STAGE(bufoff, gbase, voff) do { _Pragma("unroll") for (int _i = 0; _i < 2; ++_i) \
;         __builtin_amdgcn_global_load_lds((const unsigned*)((const char*)(gbase) + (voff)[_i]), (LAS unsigned*)(lds + (bufoff) + ldsw + _i * 8192), 16, 0, 0); } while (0)
; #define PG8_LDA(dst, b, h) do { _Pragma("unroll") for (int m = 0; m < 4; ++m) _Pragma("unroll") for (int k = 0; k < 2; ++k) dst[m][k] = *(const LAS bf16x8*)(lds + PG8_SA(b, h) + aoff + m * 2048 + k * 1024); } while (0)
; #define PG8_LDB(dst, b, h) do { _Pragma("unroll") for (int n = 0; n < 2; ++n) _Pragma("unroll") for (int k = 0; k < 2; ++k) dst[n][k] = *(const LAS bf16x8*)(lds + PG8_SB(b, h) + boff + n * 2048 + k * 1024); } while (0)
; #define PG8_MMA(ai, bj, At, Bt) do { __builtin_amdgcn_s_setprio(1); _Pragma("unroll") for (int m = 0; m < 4; ++m) _Pragma("unroll") for (int n = 0; n < 2; ++n) _Pragma("unroll") for (int k = 0; k < 2; ++k) \
;         acc[ai][bj][m][n] = __builtin_amdgcn_mfma_f32_16x16x32_bf16(Bt[n][k], At[m][k], acc[ai][bj][m][n], 0, 0, 0); __builtin_amdgcn_s_setprio(0); } while (0)
; #define PG8_WAIT_L(n) asm volatile("s_waitcnt lgkmcnt(" #n ")" ::: "memory")
; #define PG8_BAR __builtin_amdgcn_s_barrier()
; #define PG8_SCHED __builtin_amdgcn_sched_barrier(0)
; template <class PT, class Epi>
; __device__ __forceinline__ void gemm_phase_once(LAS unsigned char* lds, const PT& S, const Epi& E, bool epi_on) {
;     ...
;         for (int t = 0; t < nt; t += 2) {
;             const bool last = (t == nt - 2);
;             const char* a1 = cA + (size_t)(t + 1) * kstep;
;             const char* a2 = last ? nA : cA + (size_t)(t + 2) * kstep; const char* b2 = last ? nB : cB + (size_t)(t + 2) * kstep;
;             const char* a3 = a2 + kstep; const char* b3 = b2 + kstep;
;             PG8_LDB(B0, 0, 0); PG8_SCHED; PG8_LDA(At, 0, 0); PG8_STAGE(PG8_SA(1, 1), a1 + hstepA, voffA);
;             PG8_WAIT_L(8); PG8_BAR; PG8_WAIT_L(0); PG8_MMA(0, 0, At, B0); PG8_BAR; PG8_SCHED;
;             PG8_LDB(B1, 0, 1); PG8_STAGE(PG8_SB(0, 0), b2, voffB);
;             PG8_BAR; PG8_WAIT_L(0); PG8_MMA(0, 1, At, B1); PG8_BAR;
;             PG8_LDA(At, 0, 1); PG8_STAGE(PG8_SA(0, 0), a2, voffA);
;             PG8_BAR; PG8_WAIT_L(0); PG8_MMA(1, 0, At, B0); PG8_BAR; PG8_SCHED;
.LBB0_1253:
	ds_read_b128 v[36:39], v235
	ds_read_b128 v[40:43], v235 offset:1024
	ds_read_b128 v[158:161], v235 offset:2048
	ds_read_b128 v[168:171], v235 offset:3072
	s_add_u32 s34, s30, 0x100
	s_addc_u32 s35, s31, 0
	s_cmp_eq_u32 s61, 28
	s_cselect_b32 s39, s23, s35
	s_cselect_b32 s38, s29, s34
	s_cselect_b32 s37, s21, s60
	s_cselect_b32 s36, s58, s59
	v_lshl_add_u64 v[162:163], s[30:31], 0, v[150:151]
	s_add_i32 m0, s45, 0xc000
	ds_read_b128 v[172:175], v236
	ds_read_b128 v[176:179], v236 offset:1024
	ds_read_b128 v[180:183], v236 offset:2048
	ds_read_b128 v[184:187], v236 offset:3072
	ds_read_b128 v[188:191], v236 offset:4096
	ds_read_b128 v[192:195], v236 offset:5120
	ds_read_b128 v[196:199], v236 offset:6144
	ds_read_b128 v[200:203], v236 offset:7168
	global_load_lds_dwordx4 v[162:163], off
	v_lshl_add_u64 v[162:163], s[30:31], 0, v[152:153]
	s_add_i32 m0, s45, 0xe000
	s_nop 0
	global_load_lds_dwordx4 v[162:163], off
	s_waitcnt lgkmcnt(8)
	s_barrier
	s_waitcnt lgkmcnt(0)
	s_setprio 1
	s_waitcnt lgkmcnt(0)
	v_mfma_f32_16x16x32_bf16 v[132:135], v[36:39], v[172:175], v[132:135]
	v_mfma_f32_16x16x32_bf16 v[72:75], v[158:161], v[172:175], v[72:75]
	v_mfma_f32_16x16x32_bf16 v[124:127], v[36:39], v[180:183], v[124:127]
	v_mfma_f32_16x16x32_bf16 v[68:71], v[158:161], v[180:183], v[68:71]
	v_mfma_f32_16x16x32_bf16 v[104:107], v[36:39], v[188:191], v[104:107]
	v_mfma_f32_16x16x32_bf16 v[32:35], v[158:161], v[188:191], v[32:35]
	v_mfma_f32_16x16x32_bf16 v[100:103], v[36:39], v[196:199], v[100:103]
	v_mfma_f32_16x16x32_bf16 v[24:27], v[158:161], v[196:199], v[24:27]
	v_mfma_f32_16x16x32_bf16 v[132:135], v[40:43], v[176:179], v[132:135]
	v_mfma_f32_16x16x32_bf16 v[72:75], v[168:171], v[176:179], v[72:75]
	v_mfma_f32_16x16x32_bf16 v[124:127], v[40:43], v[184:187], v[124:127]
	v_mfma_f32_16x16x32_bf16 v[68:71], v[168:171], v[184:187], v[68:71]
	v_mfma_f32_16x16x32_bf16 v[104:107], v[40:43], v[192:195], v[104:107]
	v_mfma_f32_16x16x32_bf16 v[32:35], v[168:171], v[192:195], v[32:35]
	v_mfma_f32_16x16x32_bf16 v[100:103], v[40:43], v[200:203], v[100:103]
	v_mfma_f32_16x16x32_bf16 v[24:27], v[168:171], v[200:203], v[24:27]
	s_setprio 0
	s_barrier
	s_add_i32 s30, s53, s42
	v_lshl_add_u64 v[162:163], s[36:37], 0, v[146:147]
	s_mov_b32 m0, s30
	ds_read_b128 v[204:207], v237
	ds_read_b128 v[208:211], v237 offset:1024
	ds_read_b128 v[212:215], v237 offset:2048
	ds_read_b128 v[216:219], v237 offset:3072
	global_load_lds_dwordx4 v[162:163], off
	v_lshl_add_u64 v[220:221], s[36:37], 0, v[140:141]
	s_add_i32 m0, s30, 0x2000
	s_nop 0
	global_load_lds_dwordx4 v[220:221], off
	s_barrier
	s_waitcnt lgkmcnt(0)
	s_setprio 1
	s_waitcnt lgkmcnt(0)
	v_mfma_f32_16x16x32_bf16 v[120:123], v[204:207], v[172:175], v[120:123]
	v_mfma_f32_16x16x32_bf16 v[64:67], v[212:215], v[172:175], v[64:67]
	v_mfma_f32_16x16x32_bf16 v[116:119], v[204:207], v[180:183], v[116:119]
	v_mfma_f32_16x16x32_bf16 v[60:63], v[212:215], v[180:183], v[60:63]
	v_mfma_f32_16x16x32_bf16 v[96:99], v[204:207], v[188:191], v[96:99]
	v_mfma_f32_16x16x32_bf16 v[28:31], v[212:215], v[188:191], v[28:31]
	v_mfma_f32_16x16x32_bf16 v[92:95], v[204:207], v[196:199], v[92:95]
	v_mfma_f32_16x16x32_bf16 v[20:23], v[212:215], v[196:199], v[20:23]
	v_mfma_f32_16x16x32_bf16 v[120:123], v[208:211], v[176:179], v[120:123]
	v_mfma_f32_16x16x32_bf16 v[64:67], v[216:219], v[176:179], v[64:67]
	v_mfma_f32_16x16x32_bf16 v[116:119], v[208:211], v[184:187], v[116:119]
	v_mfma_f32_16x16x32_bf16 v[60:63], v[216:219], v[184:187], v[60:63]
	v_mfma_f32_16x16x32_bf16 v[96:99], v[208:211], v[192:195], v[96:99]
	v_mfma_f32_16x16x32_bf16 v[28:31], v[216:219], v[192:195], v[28:31]
	v_mfma_f32_16x16x32_bf16 v[92:95], v[208:211], v[200:203], v[92:95]
	v_mfma_f32_16x16x32_bf16 v[20:23], v[216:219], v[200:203], v[20:23]
	s_setprio 0
	s_mov_b32 m0, s45
	v_lshl_add_u64 v[222:223], s[38:39], 0, v[142:143]
	s_barrier
	ds_read_b128 v[172:175], v236 offset:16384
	ds_read_b128 v[176:179], v236 offset:17408
	ds_read_b128 v[180:183], v236 offset:18432
	ds_read_b128 v[184:187], v236 offset:19456
	ds_read_b128 v[188:191], v236 offset:20480
	ds_read_b128 v[192:195], v236 offset:21504
	ds_read_b128 v[196:199], v236 offset:22528
	ds_read_b128 v[200:203], v236 offset:23552
	global_load_lds_dwordx4 v[222:223], off
	v_lshl_add_u64 v[224:225], s[38:39], 0, v[144:145]
	s_mov_b32 m0, s46
	s_nop 0
	global_load_lds_dwordx4 v[224:225], off
	s_barrier
	s_waitcnt lgkmcnt(0)
	s_setprio 1
	s_waitcnt lgkmcnt(0)
	v_mfma_f32_16x16x32_bf16 v[88:91], v[36:39], v[172:175], v[88:91]
	v_mfma_f32_16x16x32_bf16 v[16:19], v[158:161], v[172:175], v[16:19]
	v_mfma_f32_16x16x32_bf16 v[84:87], v[36:39], v[180:183], v[84:87]
	v_mfma_f32_16x16x32_bf16 v[8:11], v[158:161], v[180:183], v[8:11]
	v_mfma_f32_16x16x32_bf16 v[136:139], v[36:39], v[188:191], v[136:139]
	v_mfma_f32_16x16x32_bf16 v[56:59], v[158:161], v[188:191], v[56:59]
	v_mfma_f32_16x16x32_bf16 v[36:39], v[36:39], v[196:199], v[112:115]
	v_mfma_f32_16x16x32_bf16 v[88:91], v[40:43], v[176:179], v[88:91]
	v_mfma_f32_16x16x32_bf16 v[16:19], v[168:171], v[176:179], v[16:19]
	v_mfma_f32_16x16x32_bf16 v[84:87], v[40:43], v[184:187], v[84:87]
	v_mfma_f32_16x16x32_bf16 v[8:11], v[168:171], v[184:187], v[8:11]
	v_mfma_f32_16x16x32_bf16 v[136:139], v[40:43], v[192:195], v[136:139]
	v_mfma_f32_16x16x32_bf16 v[56:59], v[168:171], v[192:195], v[56:59]
	v_mfma_f32_16x16x32_bf16 v[36:39], v[40:43], v[200:203], v[36:39]
	v_mfma_f32_16x16x32_bf16 v[40:43], v[158:161], v[196:199], v[52:55]
	v_mfma_f32_16x16x32_bf16 v[40:43], v[168:171], v[200:203], v[40:43]
	s_setprio 0
	s_barrier
; #define PG8_STAGE(bufoff, gbase, voff) do { _Pragma("unroll") for (int _i = 0; _i < 2; ++_i) \
;         __builtin_amdgcn_global_load_lds((const unsigned*)((const char*)(gbase) + (voff)[_i]), (LAS unsigned*)(lds + (bufoff) + ldsw + _i * 8192), 16, 0, 0); } while (0)
; #define PG8_LDA(dst, b, h) do { _Pragma("unroll") for (int m = 0; m < 4; ++m) _Pragma("unroll") for (int k = 0; k < 2; ++k) dst[m][k] = *(const LAS bf16x8*)(lds + PG8_SA(b, h) + aoff + m * 2048 + k * 1024); } while (0)
; #define PG8_LDB(dst, b, h) do { _Pragma("unroll") for (int n = 0; n < 2; ++n) _Pragma("unroll") for (int k = 0; k < 2; ++k) dst[n][k] = *(const LAS bf16x8*)(lds + PG8_SB(b, h) + boff + n * 2048 + k * 1024); } while (0)
; #define PG8_MMA(ai, bj, At, Bt) do { __builtin_amdgcn_s_setprio(1); _Pragma("unroll") for (int m = 0; m < 4; ++m) _Pragma("unroll") for (int n = 0; n < 2; ++n) _Pragma("unroll") for (int k = 0; k < 2; ++k) \
;         acc[ai][bj][m][n] = __builtin_amdgcn_mfma_f32_16x16x32_bf16(Bt[n][k], At[m][k], acc[ai][bj][m][n], 0, 0, 0); __builtin_amdgcn_s_setprio(0); } while (0)
; #define PG8_WAIT_V(n) asm volatile("s_waitcnt vmcnt(" #n ")" ::: "memory")
; #define PG8_WAIT_L(n) asm volatile("s_waitcnt lgkmcnt(" #n ")" ::: "memory")
; #define PG8_BAR __builtin_amdgcn_s_barrier()
; #define PG8_SCHED __builtin_amdgcn_sched_barrier(0)
; template <class PT, class Epi>
; __device__ __forceinline__ void gemm_phase_once(LAS unsigned char* lds, const PT& S, const Epi& E, bool epi_on) {
;     ...
;             PG8_STAGE(PG8_SB(0, 1), b2 + hstepB, voffB);
;             PG8_WAIT_V(6); PG8_BAR; PG8_MMA(1, 1, At, B1); PG8_BAR;
;             PG8_LDB(B0, 1, 0); PG8_SCHED; PG8_LDA(At, 1, 0); PG8_STAGE(PG8_SA(0, 1), a2 + hstepA, voffA);
;             PG8_WAIT_L(8); PG8_BAR; PG8_WAIT_L(0); PG8_MMA(0, 0, At, B0); PG8_BAR; PG8_SCHED;
;             PG8_LDB(B1, 1, 1); PG8_STAGE(PG8_SB(1, 0), b3, voffB);
;             PG8_BAR; PG8_WAIT_L(0); PG8_MMA(0, 1, At, B1); PG8_BAR;
;             PG8_LDA(At, 1, 1); PG8_STAGE(PG8_SA(1, 0), a3, voffA);
;             PG8_BAR; PG8_WAIT_L(0); PG8_MMA(1, 0, At, B0); PG8_BAR; PG8_SCHED;
	s_add_u32 s30, s36, 0x80000
	s_addc_u32 s31, s37, 0
	s_add_i32 s62, s54, s42
	v_lshl_add_u64 v[52:53], s[30:31], 0, v[146:147]
	s_mov_b32 m0, s62
	s_nop 0
	global_load_lds_dwordx4 v[52:53], off
	v_lshl_add_u64 v[52:53], s[30:31], 0, v[140:141]
	s_add_i32 m0, s62, 0x2000
	s_nop 0
	global_load_lds_dwordx4 v[52:53], off
	s_waitcnt vmcnt(6)
	s_barrier
	s_setprio 1
	v_mfma_f32_16x16x32_bf16 v[52:55], v[204:207], v[172:175], v[80:83]
	v_mfma_f32_16x16x32_bf16 v[80:83], v[208:211], v[176:179], v[52:55]
	v_mfma_f32_16x16x32_bf16 v[52:55], v[204:207], v[180:183], v[76:79]
	v_mfma_f32_16x16x32_bf16 v[76:79], v[208:211], v[184:187], v[52:55]
	v_mfma_f32_16x16x32_bf16 v[52:55], v[204:207], v[188:191], v[128:131]
	v_mfma_f32_16x16x32_bf16 v[12:15], v[212:215], v[172:175], v[12:15]
	v_mfma_f32_16x16x32_bf16 v[4:7], v[212:215], v[180:183], v[4:7]
	v_mfma_f32_16x16x32_bf16 v[128:131], v[208:211], v[192:195], v[52:55]
	v_mfma_f32_16x16x32_bf16 v[48:51], v[212:215], v[188:191], v[48:51]
	v_mfma_f32_16x16x32_bf16 v[52:55], v[204:207], v[196:199], v[108:111]
	v_mfma_f32_16x16x32_bf16 v[44:47], v[212:215], v[196:199], v[44:47]
	v_mfma_f32_16x16x32_bf16 v[12:15], v[216:219], v[176:179], v[12:15]
	v_mfma_f32_16x16x32_bf16 v[4:7], v[216:219], v[184:187], v[4:7]
	v_mfma_f32_16x16x32_bf16 v[48:51], v[216:219], v[192:195], v[48:51]
	v_mfma_f32_16x16x32_bf16 v[108:111], v[208:211], v[200:203], v[52:55]
	v_mfma_f32_16x16x32_bf16 v[44:47], v[216:219], v[200:203], v[44:47]
	s_setprio 0
	s_add_i32 s62, 0, 0x18000
	v_add_u32_e32 v165, s62, v167
	s_barrier
	ds_read_b128 v[52:55], v165
	ds_read_b128 v[112:115], v165 offset:1024
	ds_read_b128 v[158:161], v165 offset:2048
	ds_read_b128 v[168:171], v165 offset:3072
	s_add_u32 s30, s38, 0x4000
	s_addc_u32 s31, s39, 0
	s_mov_b32 m0, s47
	v_lshl_add_u64 v[204:205], s[30:31], 0, v[142:143]
	ds_read_b128 v[172:175], v236 offset:32768
	ds_read_b128 v[176:179], v236 offset:33792
	ds_read_b128 v[180:183], v236 offset:34816
	ds_read_b128 v[184:187], v236 offset:35840
	ds_read_b128 v[188:191], v236 offset:36864
	ds_read_b128 v[192:195], v236 offset:37888
	ds_read_b128 v[196:199], v236 offset:38912
	ds_read_b128 v[200:203], v236 offset:39936
	global_load_lds_dwordx4 v[204:205], off
	v_lshl_add_u64 v[204:205], s[30:31], 0, v[144:145]
	s_mov_b32 m0, s48
	s_nop 0
	global_load_lds_dwordx4 v[204:205], off
	s_waitcnt lgkmcnt(8)
	s_barrier
	s_waitcnt lgkmcnt(0)
	s_setprio 1
	s_waitcnt lgkmcnt(0)
	v_mfma_f32_16x16x32_bf16 v[132:135], v[52:55], v[172:175], v[132:135]
	v_mfma_f32_16x16x32_bf16 v[72:75], v[158:161], v[172:175], v[72:75]
	v_mfma_f32_16x16x32_bf16 v[124:127], v[52:55], v[180:183], v[124:127]
	v_mfma_f32_16x16x32_bf16 v[68:71], v[158:161], v[180:183], v[68:71]
	v_mfma_f32_16x16x32_bf16 v[104:107], v[52:55], v[188:191], v[104:107]
	v_mfma_f32_16x16x32_bf16 v[32:35], v[158:161], v[188:191], v[32:35]
	v_mfma_f32_16x16x32_bf16 v[100:103], v[52:55], v[196:199], v[100:103]
	v_mfma_f32_16x16x32_bf16 v[24:27], v[158:161], v[196:199], v[24:27]
	v_mfma_f32_16x16x32_bf16 v[132:135], v[112:115], v[176:179], v[132:135]
	v_mfma_f32_16x16x32_bf16 v[72:75], v[168:171], v[176:179], v[72:75]
	v_mfma_f32_16x16x32_bf16 v[124:127], v[112:115], v[184:187], v[124:127]
	v_mfma_f32_16x16x32_bf16 v[68:71], v[168:171], v[184:187], v[68:71]
	v_mfma_f32_16x16x32_bf16 v[104:107], v[112:115], v[192:195], v[104:107]
	v_mfma_f32_16x16x32_bf16 v[32:35], v[168:171], v[192:195], v[32:35]
	v_mfma_f32_16x16x32_bf16 v[100:103], v[112:115], v[200:203], v[100:103]
	v_mfma_f32_16x16x32_bf16 v[24:27], v[168:171], v[200:203], v[24:27]
	s_setprio 0
	s_barrier
	s_add_i32 s38, 0, 0x1c000
	s_add_i32 s30, s62, s42
	v_add_u32_e32 v165, s38, v167
	v_lshl_add_u64 v[162:163], v[162:163], 0, s[6:7]
	s_mov_b32 m0, s30
	ds_read_b128 v[204:207], v165
	ds_read_b128 v[208:211], v165 offset:1024
	ds_read_b128 v[212:215], v165 offset:2048
	ds_read_b128 v[216:219], v165 offset:3072
	global_load_lds_dwordx4 v[162:163], off
	v_lshl_add_u64 v[162:163], v[220:221], 0, s[6:7]
	s_add_i32 m0, s30, 0x2000
	s_nop 0
	global_load_lds_dwordx4 v[162:163], off
	s_barrier
	s_waitcnt lgkmcnt(0)
	s_setprio 1
	s_waitcnt lgkmcnt(0)
	v_mfma_f32_16x16x32_bf16 v[120:123], v[204:207], v[172:175], v[120:123]
	v_mfma_f32_16x16x32_bf16 v[64:67], v[212:215], v[172:175], v[64:67]
	v_mfma_f32_16x16x32_bf16 v[116:119], v[204:207], v[180:183], v[116:119]
	v_mfma_f32_16x16x32_bf16 v[60:63], v[212:215], v[180:183], v[60:63]
	v_mfma_f32_16x16x32_bf16 v[96:99], v[204:207], v[188:191], v[96:99]
	v_mfma_f32_16x16x32_bf16 v[28:31], v[212:215], v[188:191], v[28:31]
	v_mfma_f32_16x16x32_bf16 v[92:95], v[204:207], v[196:199], v[92:95]
	v_mfma_f32_16x16x32_bf16 v[20:23], v[212:215], v[196:199], v[20:23]
	v_mfma_f32_16x16x32_bf16 v[120:123], v[208:211], v[176:179], v[120:123]
	v_mfma_f32_16x16x32_bf16 v[64:67], v[216:219], v[176:179], v[64:67]
	v_mfma_f32_16x16x32_bf16 v[116:119], v[208:211], v[184:187], v[116:119]
	v_mfma_f32_16x16x32_bf16 v[60:63], v[216:219], v[184:187], v[60:63]
	v_mfma_f32_16x16x32_bf16 v[96:99], v[208:211], v[192:195], v[96:99]
	v_mfma_f32_16x16x32_bf16 v[28:31], v[216:219], v[192:195], v[28:31]
	v_mfma_f32_16x16x32_bf16 v[92:95], v[208:211], v[200:203], v[92:95]
	v_mfma_f32_16x16x32_bf16 v[20:23], v[216:219], v[200:203], v[20:23]
	s_setprio 0
	s_mov_b32 m0, s50
	v_lshl_add_u64 v[162:163], v[222:223], 0, s[6:7]
	s_barrier
	ds_read_b128 v[172:175], v236 offset:49152
	ds_read_b128 v[176:179], v236 offset:50176
	ds_read_b128 v[180:183], v236 offset:51200
	ds_read_b128 v[184:187], v236 offset:52224
	ds_read_b128 v[188:191], v236 offset:53248
	ds_read_b128 v[192:195], v236 offset:54272
	ds_read_b128 v[196:199], v236 offset:55296
	ds_read_b128 v[200:203], v236 offset:56320
	global_load_lds_dwordx4 v[162:163], off
	v_lshl_add_u64 v[162:163], v[224:225], 0, s[6:7]
	s_mov_b32 m0, s51
	s_nop 0
	global_load_lds_dwordx4 v[162:163], off
	s_barrier
; __device__ __forceinline__ unsigned pk2(float lo, float hi) { return f2bf(lo) | (f2bf(hi) << 16); }
; #define PG8_STAGE(bufoff, gbase, voff) do { _Pragma("unroll") for (int _i = 0; _i < 2; ++_i) \
;         __builtin_amdgcn_global_load_lds((const unsigned*)((const char*)(gbase) + (voff)[_i]), (LAS unsigned*)(lds + (bufoff) + ldsw + _i * 8192), 16, 0, 0); } while (0)
; #define PG8_WAIT_V(n) asm volatile("s_waitcnt vmcnt(" #n ")" ::: "memory")
; template <class PT, class Epi>
; __device__ __forceinline__ void gemm_phase_once(LAS unsigned char* lds, const PT& S, const Epi& E, bool epi_on) {
;     ...
;             PG8_LDA(At, 1, 1); PG8_STAGE(PG8_SA(1, 0), a3, voffA);
;             PG8_BAR; PG8_WAIT_L(0); PG8_MMA(1, 0, At, B0); PG8_BAR; PG8_SCHED;
;             PG8_STAGE(PG8_SB(1, 1), b3 + hstepB, voffB);
;             PG8_WAIT_V(6); PG8_BAR; PG8_MMA(1, 1, At, B1); PG8_BAR;
;     __device__ __forceinline__ void operator()(const f32x4 (&acc)[2][2][4][2], const pg8::Unit& u, int wr, int wc, int fr, int fq) const {
;         const int ch0 = 128 * u.pn + 32 * wc + 8 * fq, tok0 = 256 * u.pm + 128 * wr + 8 * fr;
;         const f32x4 r0 = *(const f32x4*)(RS + tok0), r1 = *(const f32x4*)(RS + tok0 + 4);
;         bf16* hb = HALO + ((size_t)((u.pm * 44 + u.pn) * 2 + wr) * 4) * 256 + 32 * wc + 8 * fq;
; #pragma unroll
;         for (int n = 0; n < 2; ++n) {
;             float g[8][4], v[8][4];
; #pragma unroll
;             for (int e = 0; e < 8; ++e) { const float rs = (e < 4) ? r0[e & 3] : r1[e & 3];
; #pragma unroll
;                 for (int jj = 0; jj < 4; ++jj) { g[e][jj] = acc[e >> 2][0][e & 3][n][jj] * rs; v[e][jj] = acc[e >> 2][1][e & 3][n][jj] * rs; } }
;             if (fr == 0) {
; #pragma unroll
;                 for (int q = 0; q < 2; ++q) { v2u a, b; a.x = pk2(g[q][0], g[q][1]); a.y = pk2(g[q][2], g[q][3]); b.x = pk2(v[q][0], v[q][1]); b.y = pk2(v[q][2], v[q][3]);
;                     *(v2u*)(hb + (size_t)q * 256 + 4 * n) = a; *(v2u*)(hb + (size_t)q * 256 + 128 + 4 * n) = b; } }
;             if (fr == 15) {
; #pragma unroll
;                 for (int q = 0; q < 2; ++q) { v2u a, b; a.x = pk2(g[6 + q][0], g[6 + q][1]); a.y = pk2(g[6 + q][2], g[6 + q][3]); b.x = pk2(v[6 + q][0], v[6 + q][1]); b.y = pk2(v[6 + q][2], v[6 + q][3]);
;                     *(v2u*)(hb + (size_t)(2 + q) * 256 + 4 * n) = a; *(v2u*)(hb + (size_t)(2 + q) * 256 + 128 + 4 * n) = b; } }
	s_waitcnt lgkmcnt(0)
	s_setprio 1
	s_waitcnt lgkmcnt(0)
	v_mfma_f32_16x16x32_bf16 v[88:91], v[52:55], v[172:175], v[88:91]
	v_mfma_f32_16x16x32_bf16 v[84:87], v[52:55], v[180:183], v[84:87]
	v_mfma_f32_16x16x32_bf16 v[136:139], v[52:55], v[188:191], v[136:139]
	v_mfma_f32_16x16x32_bf16 v[36:39], v[52:55], v[196:199], v[36:39]
	v_mfma_f32_16x16x32_bf16 v[88:91], v[112:115], v[176:179], v[88:91]
	v_mfma_f32_16x16x32_bf16 v[16:19], v[158:161], v[172:175], v[16:19]
	v_mfma_f32_16x16x32_bf16 v[84:87], v[112:115], v[184:187], v[84:87]
	v_mfma_f32_16x16x32_bf16 v[8:11], v[158:161], v[180:183], v[8:11]
	v_mfma_f32_16x16x32_bf16 v[136:139], v[112:115], v[192:195], v[136:139]
	v_mfma_f32_16x16x32_bf16 v[56:59], v[158:161], v[188:191], v[56:59]
	v_mfma_f32_16x16x32_bf16 v[112:115], v[112:115], v[200:203], v[36:39]
	v_mfma_f32_16x16x32_bf16 v[36:39], v[158:161], v[196:199], v[40:43]
	v_mfma_f32_16x16x32_bf16 v[16:19], v[168:171], v[176:179], v[16:19]
	v_mfma_f32_16x16x32_bf16 v[8:11], v[168:171], v[184:187], v[8:11]
	v_mfma_f32_16x16x32_bf16 v[56:59], v[168:171], v[192:195], v[56:59]
	v_mfma_f32_16x16x32_bf16 v[52:55], v[168:171], v[200:203], v[36:39]
	s_setprio 0
	s_barrier
	s_add_u32 s30, s36, 0x80080
	s_addc_u32 s31, s37, 0
	s_add_i32 s36, s38, s42
	v_lshl_add_u64 v[36:37], s[30:31], 0, v[146:147]
	s_mov_b32 m0, s36
	s_nop 0
	global_load_lds_dwordx4 v[36:37], off
	v_lshl_add_u64 v[36:37], s[30:31], 0, v[140:141]
	s_add_i32 m0, s36, 0x2000
	s_nop 0
	global_load_lds_dwordx4 v[36:37], off
	s_waitcnt vmcnt(6)
	s_barrier
	s_setprio 1
	v_mfma_f32_16x16x32_bf16 v[36:39], v[204:207], v[172:175], v[80:83]
	v_mfma_f32_16x16x32_bf16 v[80:83], v[208:211], v[176:179], v[36:39]
	v_mfma_f32_16x16x32_bf16 v[36:39], v[204:207], v[180:183], v[76:79]
	v_mfma_f32_16x16x32_bf16 v[76:79], v[208:211], v[184:187], v[36:39]
	v_mfma_f32_16x16x32_bf16 v[36:39], v[204:207], v[188:191], v[128:131]
	v_mfma_f32_16x16x32_bf16 v[128:131], v[208:211], v[192:195], v[36:39]
	v_mfma_f32_16x16x32_bf16 v[36:39], v[212:215], v[188:191], v[48:51]
	v_mfma_f32_16x16x32_bf16 v[48:51], v[216:219], v[192:195], v[36:39]
	v_mfma_f32_16x16x32_bf16 v[36:39], v[204:207], v[196:199], v[108:111]
	v_mfma_f32_16x16x32_bf16 v[12:15], v[212:215], v[172:175], v[12:15]
	v_mfma_f32_16x16x32_bf16 v[4:7], v[212:215], v[180:183], v[4:7]
	v_mfma_f32_16x16x32_bf16 v[108:111], v[208:211], v[200:203], v[36:39]
	v_mfma_f32_16x16x32_bf16 v[36:39], v[212:215], v[196:199], v[44:47]
	v_mfma_f32_16x16x32_bf16 v[12:15], v[216:219], v[176:179], v[12:15]
	v_mfma_f32_16x16x32_bf16 v[4:7], v[216:219], v[184:187], v[4:7]
	v_mfma_f32_16x16x32_bf16 v[44:47], v[216:219], v[200:203], v[36:39]
	s_setprio 0
	s_add_i32 s61, s61, 2
	s_add_u32 s59, s59, 0x100
	s_addc_u32 s60, s60, 0
	s_cmp_lt_u32 s61, 30
	s_mov_b64 s[30:31], s[34:35]
	s_barrier
	s_cbranch_scc1 .LBB0_1253
	v_lshl_add_u32 v160, s28, 8, v233
	v_ashrrev_i32_e32 v161, 31, v160
	v_lshl_add_u64 v[40:41], v[160:161], 2, s[90:91]
	global_load_dwordx4 v[36:39], v[40:41], off offset:16
	s_nop 0
	global_load_dwordx4 v[40:43], v[40:41], off
	s_mul_i32 s21, s28, 44
	s_add_i32 s21, s21, s57
	s_lshl_b32 s21, s21, 1
	s_add_i32 s28, s21, s41
	s_ashr_i32 s29, s28, 31
	v_mov_b32_e32 v162, v136
	v_mov_b32_e32 v163, v138
	s_lshl_b64 s[28:29], s[28:29], 11
	v_mov_b32_e32 v138, v137
	v_lshl_add_u64 v[158:159], v[148:149], 0, s[28:29]
	v_cmp_lt_i32_e32 vcc, 14, v3
	s_mov_b64 s[28:29], 0
	s_waitcnt vmcnt(0)
	v_pk_mul_f32 v[168:169], v[162:163], v[38:39] op_sel_hi:[1,0]
	v_mov_b32_e32 v162, v128
	v_mov_b32_e32 v163, v130
	v_mov_b32_e32 v130, v129
	v_pk_mul_f32 v[162:163], v[162:163], v[38:39] op_sel_hi:[1,0]
	v_pk_mul_f32 v[136:137], v[138:139], v[38:39] op_sel_hi:[1,0]
	v_pk_mul_f32 v[130:131], v[130:131], v[38:39] op_sel_hi:[1,0]
	s_and_saveexec_b64 s[30:31], vcc
	s_xor_b64 s[30:31], exec, s[30:31]
	s_cbranch_execz .LBB0_1256
	s_nop 7
	s_nop 1
	v_cvt_pk_bf16_f32 v139, v169, v137
	v_cvt_pk_bf16_f32 v138, v168, v136
	s_nop 7
	s_nop 1
	s_mov_b64 s[28:29], exec
	v_cvt_pk_bf16_f32 v129, v163, v131
	v_cvt_pk_bf16_f32 v128, v162, v130
	global_store_dwordx2 v[158:159], v[138:139], off offset:1024
.LBB0_1256:
	s_or_saveexec_b64 s[30:31], s[30:31]
	v_mov_b32_e32 v138, v132
	v_mov_b32_e32 v139, v134
	v_pk_mul_f32 v[196:197], v[138:139], v[40:41] op_sel_hi:[1,0]
	v_mov_b32_e32 v138, v120
	v_mov_b32_e32 v139, v122
	v_mov_b32_e32 v122, v121
	v_mov_b32_e32 v120, v124
	v_mov_b32_e32 v121, v126
	v_pk_mul_f32 v[188:189], v[120:121], v[40:41] op_sel:[0,1]
	v_mov_b32_e32 v120, v116
	v_mov_b32_e32 v121, v118
	v_mov_b32_e32 v118, v117
	v_mov_b32_e32 v116, v112
	v_mov_b32_e32 v117, v114
	v_mov_b32_e32 v112, v39
	v_pk_mul_f32 v[176:177], v[116:117], v[112:113] op_sel_hi:[1,0]
	v_mov_b32_e32 v116, v108
	v_mov_b32_e32 v117, v110
	v_mov_b32_e32 v114, v113
	v_mov_b32_e32 v110, v109
	v_mov_b32_e32 v134, v133
	v_mov_b32_e32 v126, v125
	v_pk_mul_f32 v[172:173], v[116:117], v[112:113] op_sel_hi:[1,0]
	v_pk_mul_f32 v[178:179], v[114:115], v[112:113] op_sel_hi:[1,0]
	v_pk_mul_f32 v[174:175], v[110:111], v[112:113] op_sel_hi:[1,0]
	v_pk_mul_f32 v[194:195], v[138:139], v[40:41] op_sel_hi:[1,0]
	v_pk_mul_f32 v[198:199], v[134:135], v[40:41] op_sel_hi:[1,0]
	v_pk_mul_f32 v[192:193], v[122:123], v[40:41] op_sel_hi:[1,0]
	v_pk_mul_f32 v[186:187], v[120:121], v[40:41] op_sel:[0,1]
	v_pk_mul_f32 v[190:191], v[126:127], v[40:41] op_sel:[0,1]
	v_pk_mul_f32 v[184:185], v[118:119], v[40:41] op_sel:[0,1]
	v_mov_b64_e32 v[116:117], 0x500
	v_mov_b64_e32 v[110:111], 0x600
	v_mov_b64_e32 v[108:109], 0x700
	v_mov_b64_e32 v[120:121], v[176:177]
	v_mov_b64_e32 v[118:119], v[178:179]
	v_mov_b64_e32 v[112:113], v[172:173]
	v_mov_b64_e32 v[114:115], v[174:175]
	s_xor_b64 exec, exec, s[30:31]
	s_cbranch_execz .LBB0_1260
	v_cmp_eq_u32_e32 vcc, 0, v3
	s_mov_b64 s[36:37], s[28:29]
	s_and_saveexec_b64 s[34:35], vcc
	s_cbranch_execz .LBB0_1259
	s_nop 7
	s_nop 3
	v_cvt_pk_bf16_f32 v109, v197, v199
	v_cvt_pk_bf16_f32 v108, v196, v198
	s_nop 7
	v_cvt_pk_bf16_f32 v129, v195, v193
	v_cvt_pk_bf16_f32 v128, v194, v192
	s_or_b64 s[36:37], s[28:29], exec
	global_store_dwordx2 v[158:159], v[108:109], off

; __device__ __forceinline__ unsigned pk2(float lo, float hi) { return f2bf(lo) | (f2bf(hi) << 16); }
; __device__ __forceinline__ float dpp_shr1(float x) { return __builtin_bit_cast(float, __builtin_amdgcn_update_dpp(0, __builtin_bit_cast(int, x), 0x111, 0xf, 0xf, true)); }
;     __device__ __forceinline__ void operator()(const f32x4 (&acc)[2][2][4][2], const pg8::Unit& u, int wr, int wc, int fr, int fq) const {
;     ...
;                     *(v2u*)(hb + (size_t)q * 256 + 4 * n) = a; *(v2u*)(hb + (size_t)q * 256 + 128 + 4 * n) = b; } }
;             if (fr == 15) {
; #pragma unroll
;                 for (int q = 0; q < 2; ++q) { v2u a, b; a.x = pk2(g[6 + q][0], g[6 + q][1]); a.y = pk2(g[6 + q][2], g[6 + q][3]); b.x = pk2(v[6 + q][0], v[6 + q][1]); b.y = pk2(v[6 + q][2], v[6 + q][3]);
;                     *(v2u*)(hb + (size_t)(2 + q) * 256 + 4 * n) = a; *(v2u*)(hb + (size_t)(2 + q) * 256 + 128 + 4 * n) = b; } }
;             const int cc = ch0 + 4 * n;
;             const f32x4 wg0 = *(CF4)(cw + cc), wg1 = *(CF4)(cw + FF2 + cc), wg2 = *(CF4)(cw + 2 * FF2 + cc), wv0 = *(CF4)(cw + FFH + cc), wv1 = *(CF4)(cw + FF2 + FFH + cc), wv2 = *(CF4)(cw + 2 * FF2 + FFH + cc);
;             const f32x4 bg = *(CF4)(cb + cc), bv = *(CF4)(cb + FFH + cc);
; #pragma unroll
;             for (int jj = 0; jj < 4; ++jj) {
;                 float g2 = dpp_shr1(g[6][jj]), g1 = dpp_shr1(g[7][jj]), v2 = dpp_shr1(v[6][jj]), v1 = dpp_shr1(v[7][jj]);
.LBB0_1260:
	s_or_b64 exec, exec, s[30:31]
	s_and_saveexec_b64 s[30:31], s[28:29]
	s_cbranch_execz .LBB0_1262
	v_lshl_add_u64 v[116:117], v[158:159], 0, v[116:117]
	global_store_dwordx2 v[116:117], v[128:129], off
	v_and_b32_sdwa v116, v121, v238 dst_sel:DWORD dst_unused:UNUSED_PAD src0_sel:WORD_1 src1_sel:DWORD
	s_nop 1
	v_add3_u32 v116, v121, v116, s55
	v_and_b32_sdwa v117, v119, v238 dst_sel:DWORD dst_unused:UNUSED_PAD src0_sel:WORD_1 src1_sel:DWORD
	s_nop 0
	v_add3_u32 v117, v119, v117, s55
	s_nop 0
	v_and_b32_e32 v117, 0xffff0000, v117
	s_nop 0
	v_or_b32_sdwa v117, v117, v116 dst_sel:DWORD dst_unused:UNUSED_PAD src0_sel:DWORD src1_sel:WORD_1
	v_cvt_pk_bf16_f32 v116, v120, v118
	s_nop 7
	s_nop 1
	v_cvt_pk_bf16_f32 v113, v113, v115
	v_cvt_pk_bf16_f32 v112, v112, v114
	v_lshl_add_u64 v[110:111], v[158:159], 0, v[110:111]
	v_lshl_add_u64 v[108:109], v[158:159], 0, v[108:109]
	global_store_dwordx2 v[110:111], v[116:117], off
	global_store_dwordx2 v[108:109], v[112:113], off
.LBB0_1262:
	s_or_b64 exec, exec, s[30:31]
	v_lshl_or_b32 v132, s57, 7, v234
	v_ashrrev_i32_e32 v133, 31, v132
	v_readlane_b32 s60, v253, 2
	v_lshlrev_b64 v[200:201], 2, v[132:133]
	v_readlane_b32 s61, v253, 3
	v_readlane_b32 s62, v253, 4
	v_readlane_b32 s63, v253, 5
	v_lshl_add_u64 v[138:139], s[60:61], 0, v[200:201]
	global_load_dwordx4 v[108:111], v[138:139], off
	v_lshl_add_u64 v[134:135], s[62:63], 0, v[200:201]
	global_load_dwordx4 v[116:119], v[134:135], off
	v_lshl_add_u64 v[112:113], s[8:9], 0, v[200:201]
	global_load_dwordx4 v[120:123], v[112:113], off
	v_lshl_add_u64 v[112:113], s[10:11], 0, v[200:201]
	global_load_dwordx4 v[124:127], v[112:113], off
	v_mov_b32_e32 v112, v104
	v_mov_b32_e32 v113, v106
	v_pk_mul_f32 v[228:229], v[112:113], v[42:43] op_sel_hi:[1,0]
	v_mov_b32_e32 v112, v96
	v_mov_b32_e32 v113, v98
	v_mov_b32_e32 v98, v97
	v_lshl_add_u64 v[96:97], s[12:13], 0, v[200:201]
	v_pk_mul_f32 v[222:223], v[98:99], v[42:43] op_sel_hi:[1,0]
	global_load_dwordx4 v[96:99], v[96:97], off
	v_pk_mul_f32 v[224:225], v[112:113], v[42:43] op_sel_hi:[1,0]
	v_mov_b32_e32 v106, v105
	v_mov_b32_e32 v112, v100
	v_mov_b32_e32 v113, v102
	v_mov_b32_e32 v166, v43
	v_lshl_add_u64 v[104:105], s[18:19], 0, v[200:201]
	v_pk_mul_f32 v[226:227], v[106:107], v[42:43] op_sel_hi:[1,0]
	global_load_dwordx4 v[104:107], v[104:105], off
	v_pk_mul_f32 v[218:219], v[112:113], v[166:167] op_sel_hi:[1,0]
	v_lshl_add_u64 v[112:113], s[14:15], 0, v[200:201]
	global_load_dwordx4 v[112:115], v[112:113], off
	v_mov_b32_e32 v102, v101
	v_lshl_add_u64 v[100:101], s[16:17], 0, v[200:201]
	v_pk_mul_f32 v[220:221], v[102:103], v[166:167] op_sel_hi:[1,0]
	global_load_dwordx4 v[100:103], v[100:101], off
	v_mov_b32_e32 v203, v94
	v_mov_b32_e32 v94, v93
	v_mov_b32_e32 v170, v36
	v_mov_b32_e32 v171, v37
	v_pk_mul_f32 v[212:213], v[94:95], v[166:167] op_sel_hi:[1,0]
	v_mov_b32_e32 v94, v88
	v_mov_b32_e32 v95, v90
	v_pk_mul_f32 v[208:209], v[94:95], v[170:171] op_sel_hi:[1,0]
	v_mov_b32_e32 v94, v80
	v_mov_b32_e32 v95, v82
	v_mov_b32_e32 v82, v81
	v_mov_b32_e32 v80, v84
	v_mov_b32_e32 v81, v86
	v_mov_b32_e32 v90, v89
	v_pk_mul_f32 v[88:89], v[80:81], v[170:171] op_sel:[0,1]
	v_mov_b32_e32 v81, v78
	v_mov_b32_e32 v86, v85
	v_mov_b32_e32 v78, v77
	v_mov_b32_e32 v202, v92
	v_pk_mul_f32 v[200:201], v[94:95], v[170:171] op_sel_hi:[1,0]
	v_mov_b32_e32 v80, v76
	v_pk_mul_f32 v[84:85], v[86:87], v[170:171] op_sel:[0,1]
	v_pk_mul_f32 v[76:77], v[78:79], v[170:171] op_sel:[0,1]
	v_mov_b32_dpp v78, v168 row_shr:1 row_mask:0xf bank_mask:0xf bound_ctrl:1
	v_mov_b32_dpp v79, v169 row_shr:1 row_mask:0xf bank_mask:0xf bound_ctrl:1
	v_pk_mul_f32 v[214:215], v[202:203], v[166:167] op_sel_hi:[1,0]
	v_pk_mul_f32 v[206:207], v[90:91], v[170:171] op_sel_hi:[1,0]
	v_pk_mul_f32 v[90:91], v[82:83], v[170:171] op_sel_hi:[1,0]
	v_pk_mul_f32 v[82:83], v[80:81], v[170:171] op_sel:[0,1]
	v_mov_b32_dpp v80, v176 row_shr:1 row_mask:0xf bank_mask:0xf bound_ctrl:1
	v_mov_b32_dpp v81, v177 row_shr:1 row_mask:0xf bank_mask:0xf bound_ctrl:1
	v_mov_b32_dpp v210, v136 row_shr:1 row_mask:0xf bank_mask:0xf bound_ctrl:1
	v_mov_b32_dpp v211, v137 row_shr:1 row_mask:0xf bank_mask:0xf bound_ctrl:1
	v_mov_b32_dpp v242, v178 row_shr:1 row_mask:0xf bank_mask:0xf bound_ctrl:1
	v_mov_b32_dpp v243, v179 row_shr:1 row_mask:0xf bank_mask:0xf bound_ctrl:1
	v_mov_b32_dpp v170, v162 row_shr:1 row_mask:0xf bank_mask:0xf bound_ctrl:1
	v_mov_b32_dpp v171, v163 row_shr:1 row_mask:0xf bank_mask:0xf bound_ctrl:1
	v_mov_b32_dpp v240, v172 row_shr:1 row_mask:0xf bank_mask:0xf bound_ctrl:1
	v_mov_b32_dpp v241, v173 row_shr:1 row_mask:0xf bank_mask:0xf bound_ctrl:1
	v_mov_b32_dpp v216, v130 row_shr:1 row_mask:0xf bank_mask:0xf bound_ctrl:1
	v_mov_b32_dpp v217, v131 row_shr:1 row_mask:0xf bank_mask:0xf bound_ctrl:1
	v_mov_b32_dpp v244, v174 row_shr:1 row_mask:0xf bank_mask:0xf bound_ctrl:1
	v_mov_b32_dpp v245, v175 row_shr:1 row_mask:0xf bank_mask:0xf bound_ctrl:1
	v_mov_b32_e32 v180, v40
	v_mov_b32_e32 v181, v40
	v_mov_b32_e32 v40, v41
	v_mov_b32_e32 v182, v38
	v_mov_b32_e32 v183, v38
	v_mov_b32_e32 v38, v39
	s_waitcnt vmcnt(0)
; __device__ __forceinline__ unsigned pk2(float lo, float hi) { return f2bf(lo) | (f2bf(hi) << 16); }
; __device__ __forceinline__ float silu_fast(float x) { return x * __builtin_amdgcn_rcpf(1.f + __builtin_amdgcn_exp2f(-1.4426950408889634f * x)); }
; __device__ __forceinline__ float dpp_shr1(float x) { return __builtin_bit_cast(float, __builtin_amdgcn_update_dpp(0, __builtin_bit_cast(int, x), 0x111, 0xf, 0xf, true)); }
;     __device__ __forceinline__ void operator()(const f32x4 (&acc)[2][2][4][2], const pg8::Unit& u, int wr, int wc, int fr, int fq) const {
;     ...
;             for (int jj = 0; jj < 4; ++jj) {
;                 float g2 = dpp_shr1(g[6][jj]), g1 = dpp_shr1(g[7][jj]), v2 = dpp_shr1(v[6][jj]), v1 = dpp_shr1(v[7][jj]);
; #pragma unroll
;                 for (int e = 0; e < 8; ++e) { const float g0 = g[e][jj], v0 = v[e][jj];
;                     const float cg = bg[jj] + wg0[jj] * g2 + wg1[jj] * g1 + wg2[jj] * g0, cv = bv[jj] + wv0[jj] * v2 + wv1[jj] * v1 + wv2[jj] * v0;
;                     g[e][jj] = silu_fast(cg) * cv; g2 = g1; g1 = g0; v2 = v1; v1 = v0; } }
; #pragma unroll
;             for (int e = 0; e < 8; ++e) { v2u w; w.x = pk2(g[e][0], g[e][1]); w.y = pk2(g[e][2], g[e][3]); *(v2u*)(ACT + (size_t)(tok0 + e) * FFH + cc) = w; }
	v_mov_b32_e32 v86, v108
	v_mov_b32_e32 v87, v110
	v_mov_b32_e32 v94, v116
	v_mov_b32_e32 v95, v118
	v_pk_fma_f32 v[78:79], v[86:87], v[78:79], v[94:95]
	v_mov_b32_e32 v202, v120
	v_mov_b32_e32 v203, v122
	v_pk_fma_f32 v[78:79], v[202:203], v[80:81], v[78:79]
	v_mov_b32_e32 v204, v124
	v_mov_b32_e32 v205, v126
	v_pk_fma_f32 v[78:79], v[196:197], v[204:205], v[78:79]
	v_mov_b32_e32 v110, v109
	v_mul_f32_e32 v108, 0xbfb8aa3b, v78
	v_mov_b32_e32 v118, v117
	v_exp_f32_e32 v116, v108
	v_pk_fma_f32 v[108:109], v[110:111], v[210:211], v[118:119]
	v_mov_b32_e32 v122, v121
	v_pk_fma_f32 v[108:109], v[122:123], v[242:243], v[108:109]
	v_mov_b32_e32 v126, v125
	v_pk_fma_f32 v[108:109], v[198:199], v[126:127], v[108:109]
	v_add_f32_e32 v116, 1.0, v116
	v_mul_f32_e32 v117, 0xbfb8aa3b, v108
	v_exp_f32_e32 v117, v117
	v_rcp_f32_e32 v246, v116
	v_mov_b32_e32 v120, v104
	v_mov_b32_e32 v121, v106
	v_add_f32_e32 v116, 1.0, v117
	v_rcp_f32_e32 v248, v116
	v_mov_b32_e32 v116, v96
	v_mul_f32_e32 v96, 0xbfb8aa3b, v79
	v_exp_f32_e32 v96, v96
	v_mov_b32_e32 v117, v98
	v_pk_fma_f32 v[124:125], v[116:117], v[170:171], v[120:121]
	v_mov_b32_e32 v210, v112
	v_add_f32_e32 v96, 1.0, v96
	v_mov_b32_e32 v211, v114
	v_rcp_f32_e32 v247, v96
	v_mul_f32_e32 v96, 0xbfb8aa3b, v109
	v_pk_fma_f32 v[170:171], v[210:211], v[240:241], v[124:125]
	v_mov_b32_e32 v124, v100
	v_exp_f32_e32 v100, v96
	v_mov_b32_e32 v98, v97
	v_mov_b32_e32 v106, v105
	v_mov_b32_e32 v125, v102
	v_add_f32_e32 v100, 1.0, v100
	v_rcp_f32_e32 v249, v100
	v_pk_fma_f32 v[96:97], v[98:99], v[216:217], v[106:107]
	v_mov_b32_e32 v114, v113
	v_pk_fma_f32 v[170:171], v[194:195], v[124:125], v[170:171]
	v_pk_mul_f32 v[78:79], v[78:79], v[246:247]
	v_pk_fma_f32 v[96:97], v[114:115], v[244:245], v[96:97]
	v_mov_b32_e32 v102, v101
	v_pk_mul_f32 v[78:79], v[170:171], v[78:79]
	v_pk_fma_f32 v[96:97], v[192:193], v[102:103], v[96:97]
	v_pk_mul_f32 v[100:101], v[108:109], v[248:249]
	v_pk_fma_f32 v[80:81], v[86:87], v[80:81], v[94:95]
	v_pk_mul_f32 v[96:97], v[96:97], v[100:101]
	s_nop 7
	s_nop 1
	v_mov_b64_e32 v[112:113], s[78:79]
	v_pk_fma_f32 v[80:81], v[196:197], v[202:203], v[80:81]
	v_cvt_pk_bf16_f32 v79, v79, v97
	v_cvt_pk_bf16_f32 v78, v78, v96
	v_mad_i64_i32 v[96:97], s[28:29], v160, s56, v[112:113]
	v_lshlrev_b64 v[216:217], 1, v[132:133]
	v_pk_fma_f32 v[80:81], v[188:189], v[204:205], v[80:81]
	v_lshl_add_u64 v[170:171], v[96:97], 0, v[216:217]
	v_mul_f32_e32 v96, 0xbfb8aa3b, v80
	v_exp_f32_e32 v100, v96
	v_pk_fma_f32 v[96:97], v[110:111], v[242:243], v[118:119]
	global_store_dwordx2 v[170:171], v[78:79], off
	v_pk_fma_f32 v[96:97], v[198:199], v[122:123], v[96:97]
	v_add_f32_e32 v78, 1.0, v100
	v_pk_fma_f32 v[96:97], v[190:191], v[126:127], v[96:97]
	v_mul_f32_e32 v100, 0xbfb8aa3b, v81
	v_mul_f32_e32 v101, 0xbfb8aa3b, v96
	v_exp_f32_e32 v101, v101
	v_rcp_f32_e32 v78, v78
	v_pk_fma_f32 v[104:105], v[116:117], v[240:241], v[120:121]
	v_mov_b32_e32 v128, v42
	v_add_f32_e32 v79, 1.0, v101
	v_exp_f32_e32 v101, v100
	v_rcp_f32_e32 v100, v79
	v_pk_fma_f32 v[104:105], v[194:195], v[210:211], v[104:105]
	v_mov_b32_e32 v129, v42
	v_add_f32_e32 v79, 1.0, v101
	v_mul_f32_e32 v101, 0xbfb8aa3b, v97
	v_rcp_f32_e32 v79, v79
	v_exp_f32_e32 v101, v101
	v_pk_fma_f32 v[104:105], v[186:187], v[124:125], v[104:105]
	v_mov_b32_e32 v42, v43
	v_pk_mul_f32 v[78:79], v[80:81], v[78:79]
	v_add_f32_e32 v80, 1.0, v101
	v_rcp_f32_e32 v101, v80
	v_pk_fma_f32 v[80:81], v[98:99], v[244:245], v[106:107]
	v_pk_mul_f32 v[78:79], v[104:105], v[78:79]
	v_pk_fma_f32 v[80:81], v[192:193], v[114:115], v[80:81]
	v_pk_mul_f32 v[96:97], v[96:97], v[100:101]
	v_pk_fma_f32 v[80:81], v[184:185], v[102:103], v[80:81]
	v_pk_fma_f32 v[104:105], v[194:195], v[116:117], v[120:121]
	v_pk_mul_f32 v[80:81], v[80:81], v[96:97]
	s_nop 7
	s_nop 1
	v_cvt_pk_bf16_f32 v78, v78, v80
	v_or_b32_e32 v80, 1, v160
	v_cvt_pk_bf16_f32 v79, v79, v81
	v_mad_i64_i32 v[80:81], s[28:29], v80, s56, v[112:113]
	v_lshl_add_u64 v[108:109], v[80:81], 0, v[216:217]
	v_pk_fma_f32 v[80:81], v[196:197], v[86:87], v[94:95]
	global_store_dwordx2 v[108:109], v[78:79], off
	v_pk_fma_f32 v[80:81], v[188:189], v[202:203], v[80:81]
	v_pk_fma_f32 v[104:105], v[186:187], v[210:211], v[104:105]
	v_pk_fma_f32 v[80:81], v[228:229], v[204:205], v[80:81]
	v_pk_fma_f32 v[104:105], v[224:225], v[124:125], v[104:105]
	v_mul_f32_e32 v96, 0xbfb8aa3b, v80
	v_exp_f32_e32 v100, v96
	v_pk_fma_f32 v[96:97], v[198:199], v[110:111], v[118:119]
	v_pk_fma_f32 v[186:187], v[186:187], v[116:117], v[120:121]
	v_pk_fma_f32 v[96:97], v[190:191], v[122:123], v[96:97]
	v_add_f32_e32 v78, 1.0, v100
	v_pk_fma_f32 v[96:97], v[226:227], v[126:127], v[96:97]
	v_mul_f32_e32 v100, 0xbfb8aa3b, v81
	v_mul_f32_e32 v101, 0xbfb8aa3b, v96
	v_exp_f32_e32 v101, v101
	v_rcp_f32_e32 v78, v78
	v_pk_fma_f32 v[186:187], v[224:225], v[210:211], v[186:187]
	v_mov_b32_e32 v92, v36
	v_add_f32_e32 v79, 1.0, v101
	v_exp_f32_e32 v101, v100
	v_rcp_f32_e32 v100, v79
	v_pk_fma_f32 v[186:187], v[214:215], v[124:125], v[186:187]
	v_mov_b32_e32 v93, v36
	v_add_f32_e32 v79, 1.0, v101
	v_mul_f32_e32 v101, 0xbfb8aa3b, v97
	v_rcp_f32_e32 v79, v79
	v_exp_f32_e32 v101, v101
	v_mov_b32_e32 v36, v37
	v_cmp_gt_i32_e32 vcc, 15, v3
	v_pk_mul_f32 v[78:79], v[80:81], v[78:79]
	v_add_f32_e32 v80, 1.0, v101
	v_rcp_f32_e32 v101, v80
	v_pk_fma_f32 v[80:81], v[192:193], v[98:99], v[106:107]
	v_pk_mul_f32 v[78:79], v[104:105], v[78:79]
	v_pk_fma_f32 v[80:81], v[184:185], v[114:115], v[80:81]
	v_pk_mul_f32 v[96:97], v[96:97], v[100:101]
	v_pk_fma_f32 v[80:81], v[222:223], v[102:103], v[80:81]
	s_mov_b64 s[30:31], -1
	v_pk_mul_f32 v[80:81], v[80:81], v[96:97]
	s_nop 7
	s_nop 1
; __device__ __forceinline__ unsigned pk2(float lo, float hi) { return f2bf(lo) | (f2bf(hi) << 16); }
; __device__ __forceinline__ float silu_fast(float x) { return x * __builtin_amdgcn_rcpf(1.f + __builtin_amdgcn_exp2f(-1.4426950408889634f * x)); }
; __device__ __forceinline__ float dpp_shr1(float x) { return __builtin_bit_cast(float, __builtin_amdgcn_update_dpp(0, __builtin_bit_cast(int, x), 0x111, 0xf, 0xf, true)); }
;     __device__ __forceinline__ void operator()(const f32x4 (&acc)[2][2][4][2], const pg8::Unit& u, int wr, int wc, int fr, int fq) const {
;     ...
;             for (int jj = 0; jj < 4; ++jj) {
;                 float g2 = dpp_shr1(g[6][jj]), g1 = dpp_shr1(g[7][jj]), v2 = dpp_shr1(v[6][jj]), v1 = dpp_shr1(v[7][jj]);
; #pragma unroll
;                 for (int e = 0; e < 8; ++e) { const float g0 = g[e][jj], v0 = v[e][jj];
;                     const float cg = bg[jj] + wg0[jj] * g2 + wg1[jj] * g1 + wg2[jj] * g0, cv = bv[jj] + wv0[jj] * v2 + wv1[jj] * v1 + wv2[jj] * v0;
;                     g[e][jj] = silu_fast(cg) * cv; g2 = g1; g1 = g0; v2 = v1; v1 = v0; } }
; #pragma unroll
;             for (int e = 0; e < 8; ++e) { v2u w; w.x = pk2(g[e][0], g[e][1]); w.y = pk2(g[e][2], g[e][3]); *(v2u*)(ACT + (size_t)(tok0 + e) * FFH + cc) = w; }
	v_cvt_pk_bf16_f32 v78, v78, v80
	v_or_b32_e32 v80, 2, v160
	v_cvt_pk_bf16_f32 v79, v79, v81
	v_mad_i64_i32 v[80:81], s[28:29], v80, s56, v[112:113]
	v_lshl_add_u64 v[104:105], v[80:81], 0, v[216:217]
	v_pk_fma_f32 v[80:81], v[188:189], v[86:87], v[94:95]
	global_store_dwordx2 v[104:105], v[78:79], off
	v_pk_fma_f32 v[80:81], v[228:229], v[202:203], v[80:81]
	v_pk_fma_f32 v[188:189], v[214:215], v[116:117], v[120:121]
	v_pk_fma_f32 v[80:81], v[218:219], v[204:205], v[80:81]
	v_pk_fma_f32 v[188:189], v[200:201], v[210:211], v[188:189]
	v_mul_f32_e32 v96, 0xbfb8aa3b, v80
	v_exp_f32_e32 v100, v96
	v_pk_fma_f32 v[96:97], v[190:191], v[110:111], v[118:119]
	v_pk_fma_f32 v[188:189], v[82:83], v[124:125], v[188:189]
	v_pk_fma_f32 v[96:97], v[226:227], v[122:123], v[96:97]
	v_add_f32_e32 v78, 1.0, v100
	v_pk_fma_f32 v[96:97], v[220:221], v[126:127], v[96:97]
	v_mul_f32_e32 v100, 0xbfb8aa3b, v81
	v_mul_f32_e32 v101, 0xbfb8aa3b, v96
	v_exp_f32_e32 v101, v101
	v_rcp_f32_e32 v78, v78
	v_pk_fma_f32 v[190:191], v[200:201], v[116:117], v[120:121]
	v_readlane_b32 s64, v253, 6
	v_add_f32_e32 v79, 1.0, v101
	v_exp_f32_e32 v101, v100
	v_rcp_f32_e32 v100, v79
	v_pk_fma_f32 v[190:191], v[82:83], v[210:211], v[190:191]
	v_pk_fma_f32 v[82:83], v[82:83], v[116:117], v[120:121]
	v_add_f32_e32 v79, 1.0, v101
	v_mul_f32_e32 v101, 0xbfb8aa3b, v97
	v_rcp_f32_e32 v79, v79
	v_exp_f32_e32 v101, v101
	v_pk_fma_f32 v[190:191], v[162:163], v[124:125], v[190:191]
	v_pk_fma_f32 v[82:83], v[162:163], v[210:211], v[82:83]
	v_pk_mul_f32 v[78:79], v[80:81], v[78:79]
	v_add_f32_e32 v80, 1.0, v101
	v_rcp_f32_e32 v101, v80
	v_pk_fma_f32 v[80:81], v[184:185], v[98:99], v[106:107]
	v_pk_mul_f32 v[78:79], v[186:187], v[78:79]
	v_pk_fma_f32 v[80:81], v[222:223], v[114:115], v[80:81]
	v_pk_mul_f32 v[96:97], v[96:97], v[100:101]
	v_pk_fma_f32 v[80:81], v[212:213], v[102:103], v[80:81]
	v_pk_fma_f32 v[186:187], v[224:225], v[116:117], v[120:121]
	v_pk_mul_f32 v[80:81], v[80:81], v[96:97]
	s_nop 7
	s_nop 1
	v_cvt_pk_bf16_f32 v78, v78, v80
	v_or_b32_e32 v80, 3, v160
	v_cvt_pk_bf16_f32 v79, v79, v81
	v_mad_i64_i32 v[80:81], s[28:29], v80, s56, v[112:113]
	v_lshl_add_u64 v[100:101], v[80:81], 0, v[216:217]
	v_pk_fma_f32 v[80:81], v[228:229], v[86:87], v[94:95]
	global_store_dwordx2 v[100:101], v[78:79], off
	v_pk_fma_f32 v[80:81], v[218:219], v[202:203], v[80:81]
	v_pk_fma_f32 v[186:187], v[214:215], v[210:211], v[186:187]
	v_pk_fma_f32 v[80:81], v[208:209], v[204:205], v[80:81]
	v_pk_fma_f32 v[186:187], v[200:201], v[124:125], v[186:187]
	v_mul_f32_e32 v96, 0xbfb8aa3b, v80
	v_exp_f32_e32 v133, v96
	v_pk_fma_f32 v[96:97], v[226:227], v[110:111], v[118:119]
	v_pk_fma_f32 v[82:83], v[172:173], v[124:125], v[82:83]
	v_pk_fma_f32 v[96:97], v[220:221], v[122:123], v[96:97]
	v_add_f32_e32 v78, 1.0, v133
	v_pk_fma_f32 v[96:97], v[206:207], v[126:127], v[96:97]
	v_mul_f32_e32 v133, 0xbfb8aa3b, v81
	v_mul_f32_e32 v161, 0xbfb8aa3b, v96
	v_exp_f32_e32 v161, v161
	v_exp_f32_e32 v133, v133
	v_rcp_f32_e32 v78, v78
	v_readlane_b32 s65, v253, 7
	v_add_f32_e32 v79, 1.0, v161
	v_rcp_f32_e32 v184, v79
	v_add_f32_e32 v79, 1.0, v133
	v_mul_f32_e32 v133, 0xbfb8aa3b, v97
	v_rcp_f32_e32 v79, v79
	v_exp_f32_e32 v133, v133
	v_readlane_b32 s66, v253, 8
	v_readlane_b32 s67, v253, 9
	v_pk_mul_f32 v[78:79], v[80:81], v[78:79]
	v_add_f32_e32 v80, 1.0, v133
	v_rcp_f32_e32 v185, v80
	v_pk_fma_f32 v[80:81], v[222:223], v[98:99], v[106:107]
	v_pk_mul_f32 v[78:79], v[186:187], v[78:79]
	v_pk_fma_f32 v[80:81], v[212:213], v[114:115], v[80:81]
	v_pk_mul_f32 v[96:97], v[96:97], v[184:185]
	v_pk_fma_f32 v[80:81], v[90:91], v[102:103], v[80:81]
	v_pk_fma_f32 v[184:185], v[220:221], v[110:111], v[118:119]
	v_pk_mul_f32 v[80:81], v[80:81], v[96:97]
	s_nop 7
	s_nop 1
	v_cvt_pk_bf16_f32 v78, v78, v80
	v_or_b32_e32 v80, 4, v160
	v_cvt_pk_bf16_f32 v79, v79, v81
	v_mad_i64_i32 v[80:81], s[28:29], v80, s56, v[112:113]
	v_lshl_add_u64 v[96:97], v[80:81], 0, v[216:217]
	v_pk_fma_f32 v[80:81], v[218:219], v[86:87], v[94:95]
	v_pk_fma_f32 v[184:185], v[206:207], v[122:123], v[184:185]
	v_pk_fma_f32 v[80:81], v[208:209], v[202:203], v[80:81]
	v_pk_fma_f32 v[184:185], v[84:85], v[126:127], v[184:185]
	v_pk_fma_f32 v[80:81], v[88:89], v[204:205], v[80:81]
	v_mul_f32_e32 v161, 0xbfb8aa3b, v184
	v_mul_f32_e32 v133, 0xbfb8aa3b, v80
	v_exp_f32_e32 v133, v133
	v_exp_f32_e32 v161, v161
	global_store_dwordx2 v[96:97], v[78:79], off
	v_add_f32_e32 v78, 1.0, v133
	v_mul_f32_e32 v133, 0xbfb8aa3b, v81
	v_exp_f32_e32 v133, v133
	v_add_f32_e32 v79, 1.0, v161
	v_rcp_f32_e32 v186, v79
	v_rcp_f32_e32 v78, v78
	v_add_f32_e32 v79, 1.0, v133
	v_mul_f32_e32 v133, 0xbfb8aa3b, v185
	v_rcp_f32_e32 v79, v79
	v_exp_f32_e32 v133, v133
	v_pk_mul_f32 v[78:79], v[80:81], v[78:79]
	v_add_f32_e32 v80, 1.0, v133
	v_rcp_f32_e32 v187, v80
	v_pk_fma_f32 v[80:81], v[212:213], v[98:99], v[106:107]
	v_pk_mul_f32 v[78:79], v[188:189], v[78:79]
	v_pk_fma_f32 v[80:81], v[90:91], v[114:115], v[80:81]
	v_pk_mul_f32 v[184:185], v[184:185], v[186:187]
	v_pk_fma_f32 v[80:81], v[76:77], v[102:103], v[80:81]
	s_nop 0
	v_pk_mul_f32 v[80:81], v[80:81], v[184:185]
	v_pk_fma_f32 v[184:185], v[208:209], v[86:87], v[94:95]
	s_nop 0
	v_pk_fma_f32 v[184:185], v[88:89], v[202:203], v[184:185]
	s_nop 3
	v_pk_fma_f32 v[184:185], v[168:169], v[204:205], v[184:185]
	s_nop 1
	v_mul_f32_e32 v133, 0xbfb8aa3b, v184
	s_nop 0
	v_exp_f32_e32 v133, v133
	v_pk_fma_f32 v[186:187], v[206:207], v[110:111], v[118:119]
	s_nop 0
	v_cvt_pk_bf16_f32 v78, v78, v80
	v_or_b32_e32 v80, 5, v160
	v_pk_fma_f32 v[186:187], v[84:85], v[122:123], v[186:187]
	v_cvt_pk_bf16_f32 v79, v79, v81
	v_mad_i64_i32 v[80:81], s[28:29], v80, s56, v[112:113]
; __device__ __forceinline__ unsigned pk2(float lo, float hi) { return f2bf(lo) | (f2bf(hi) << 16); }
; __device__ __forceinline__ float silu_fast(float x) { return x * __builtin_amdgcn_rcpf(1.f + __builtin_amdgcn_exp2f(-1.4426950408889634f * x)); }
;     __device__ __forceinline__ void operator()(const f32x4 (&acc)[2][2][4][2], const pg8::Unit& u, int wr, int wc, int fr, int fq) const {
;     ...
;         for (int n = 0; n < 2; ++n) {
;             float g[8][4], v[8][4];
; #pragma unroll
;             for (int e = 0; e < 8; ++e) { const float rs = (e < 4) ? r0[e & 3] : r1[e & 3];
; #pragma unroll
;                 for (int jj = 0; jj < 4; ++jj) { g[e][jj] = acc[e >> 2][0][e & 3][n][jj] * rs; v[e][jj] = acc[e >> 2][1][e & 3][n][jj] * rs; } }
;             if (fr == 0) {
; #pragma unroll
;                 for (int q = 0; q < 2; ++q) { v2u a, b; a.x = pk2(g[q][0], g[q][1]); a.y = pk2(g[q][2], g[q][3]); b.x = pk2(v[q][0], v[q][1]); b.y = pk2(v[q][2], v[q][3]);
;                     *(v2u*)(hb + (size_t)q * 256 + 4 * n) = a; *(v2u*)(hb + (size_t)q * 256 + 128 + 4 * n) = b; } }
;             if (fr == 15) {
; #pragma unroll
;                 for (int q = 0; q < 2; ++q) { v2u a, b; a.x = pk2(g[6 + q][0], g[6 + q][1]); a.y = pk2(g[6 + q][2], g[6 + q][3]); b.x = pk2(v[6 + q][0], v[6 + q][1]); b.y = pk2(v[6 + q][2], v[6 + q][3]);
;                     *(v2u*)(hb + (size_t)(2 + q) * 256 + 4 * n) = a; *(v2u*)(hb + (size_t)(2 + q) * 256 + 128 + 4 * n) = b; } }
;     ...
;                 for (int e = 0; e < 8; ++e) { const float g0 = g[e][jj], v0 = v[e][jj];
;                     const float cg = bg[jj] + wg0[jj] * g2 + wg1[jj] * g1 + wg2[jj] * g0, cv = bv[jj] + wv0[jj] * v2 + wv1[jj] * v1 + wv2[jj] * v0;
;                     g[e][jj] = silu_fast(cg) * cv; g2 = g1; g1 = g0; v2 = v1; v1 = v0; } }
; #pragma unroll
;             for (int e = 0; e < 8; ++e) { v2u w; w.x = pk2(g[e][0], g[e][1]); w.y = pk2(g[e][2], g[e][3]); *(v2u*)(ACT + (size_t)(tok0 + e) * FFH + cc) = w; }
	v_pk_fma_f32 v[186:187], v[136:137], v[126:127], v[186:187]
	v_lshl_add_u64 v[80:81], v[80:81], 0, v[216:217]
	v_mul_f32_e32 v161, 0xbfb8aa3b, v186
	v_exp_f32_e32 v161, v161
	global_store_dwordx2 v[80:81], v[78:79], off
	v_add_f32_e32 v78, 1.0, v133
	v_mul_f32_e32 v133, 0xbfb8aa3b, v185
	v_exp_f32_e32 v133, v133
	v_add_f32_e32 v79, 1.0, v161
	v_rcp_f32_e32 v188, v79
	v_rcp_f32_e32 v78, v78
	v_add_f32_e32 v79, 1.0, v133
	v_mul_f32_e32 v133, 0xbfb8aa3b, v187
	v_exp_f32_e32 v133, v133
	v_rcp_f32_e32 v79, v79
	v_pk_fma_f32 v[90:91], v[90:91], v[98:99], v[106:107]
	v_pk_fma_f32 v[84:85], v[84:85], v[110:111], v[118:119]
	v_add_f32_e32 v133, 1.0, v133
	v_rcp_f32_e32 v189, v133
	v_pk_mul_f32 v[78:79], v[184:185], v[78:79]
	v_pk_fma_f32 v[90:91], v[76:77], v[114:115], v[90:91]
	v_pk_mul_f32 v[78:79], v[190:191], v[78:79]
	v_pk_fma_f32 v[90:91], v[130:131], v[102:103], v[90:91]
	v_pk_mul_f32 v[184:185], v[186:187], v[188:189]
	s_nop 0
	v_pk_mul_f32 v[90:91], v[90:91], v[184:185]
	s_nop 7
	s_nop 0
	v_cvt_pk_bf16_f32 v90, v78, v90
	v_or_b32_e32 v78, 6, v160
	v_pk_fma_f32 v[86:87], v[88:89], v[86:87], v[94:95]
	v_pk_fma_f32 v[84:85], v[136:137], v[122:123], v[84:85]
	v_cvt_pk_bf16_f32 v91, v79, v91
	v_mad_i64_i32 v[78:79], s[28:29], v78, s56, v[112:113]
	v_pk_fma_f32 v[86:87], v[168:169], v[202:203], v[86:87]
	v_pk_fma_f32 v[84:85], v[178:179], v[126:127], v[84:85]
	v_lshl_add_u64 v[78:79], v[78:79], 0, v[216:217]
	v_pk_fma_f32 v[86:87], v[176:177], v[204:205], v[86:87]
	v_mul_f32_e32 v89, 0xbfb8aa3b, v84
	v_mul_f32_e32 v88, 0xbfb8aa3b, v86
	v_exp_f32_e32 v89, v89
	global_store_dwordx2 v[78:79], v[90:91], off
	v_mul_f32_e32 v90, 0xbfb8aa3b, v87
	v_exp_f32_e32 v88, v88
	v_exp_f32_e32 v91, v90
	v_add_f32_e32 v89, 1.0, v89
	v_rcp_f32_e32 v90, v89
	v_add_f32_e32 v88, 1.0, v88
	v_add_f32_e32 v89, 1.0, v91
	v_rcp_f32_e32 v88, v88
	v_rcp_f32_e32 v89, v89
	v_mul_f32_e32 v91, 0xbfb8aa3b, v85
	v_exp_f32_e32 v91, v91
	v_pk_fma_f32 v[76:77], v[76:77], v[98:99], v[106:107]
	v_pk_mul_f32 v[86:87], v[86:87], v[88:89]
	v_pk_fma_f32 v[76:77], v[130:131], v[114:115], v[76:77]
	v_pk_mul_f32 v[82:83], v[82:83], v[86:87]
	v_add_f32_e32 v86, 1.0, v91
	v_rcp_f32_e32 v91, v86
	v_pk_fma_f32 v[76:77], v[174:175], v[102:103], v[76:77]
	v_pk_mul_f32 v[84:85], v[84:85], v[90:91]
	s_nop 0
	v_pk_mul_f32 v[76:77], v[76:77], v[84:85]
	s_nop 7
	s_nop 1
	v_cvt_pk_bf16_f32 v82, v82, v76
	v_or_b32_e32 v76, 7, v160
	v_cvt_pk_bf16_f32 v83, v83, v77
	v_mad_i64_i32 v[76:77], s[28:29], v76, s56, v[112:113]
	v_lshl_add_u64 v[76:77], v[76:77], 0, v[216:217]
	global_store_dwordx2 v[76:77], v[82:83], off
	v_mov_b32_e32 v82, v72
	v_mov_b32_e32 v83, v74
	v_pk_mul_f32 v[126:127], v[82:83], v[180:181]
	v_mov_b32_e32 v82, v64
	v_mov_b32_e32 v83, v66
	v_mov_b32_e32 v66, v65
	v_mov_b32_e32 v64, v68
	v_mov_b32_e32 v65, v70
	v_pk_mul_f32 v[112:113], v[64:65], v[40:41]
	v_mov_b32_e32 v64, v60
	v_mov_b32_e32 v65, v62
	v_mov_b32_e32 v70, v69
	v_mov_b32_e32 v62, v61
	v_pk_mul_f32 v[114:115], v[64:65], v[40:41]
	v_pk_mul_f32 v[116:117], v[70:71], v[40:41]
	v_pk_mul_f32 v[118:119], v[62:63], v[40:41]
	v_mov_b32_e32 v40, v56
	v_mov_b32_e32 v41, v58
	v_pk_mul_f32 v[88:89], v[40:41], v[182:183]
	v_mov_b32_e32 v40, v48
	v_mov_b32_e32 v41, v50
	v_pk_mul_f32 v[122:123], v[82:83], v[180:181]
	v_pk_mul_f32 v[82:83], v[40:41], v[182:183]
	v_mov_b32_e32 v40, v52
	v_mov_b32_e32 v41, v54
	v_mov_b32_e32 v74, v73
	v_mov_b32_e32 v58, v57
	v_mov_b32_e32 v50, v49
	v_pk_mul_f32 v[94:95], v[40:41], v[38:39]
	v_mov_b32_e32 v40, v44
	v_mov_b32_e32 v41, v46
	v_mov_b32_e32 v54, v53
	v_mov_b32_e32 v46, v45
	v_pk_mul_f32 v[124:125], v[74:75], v[180:181]
	v_pk_mul_f32 v[86:87], v[58:59], v[182:183]
	v_pk_mul_f32 v[72:73], v[50:51], v[182:183]
	v_pk_mul_f32 v[84:85], v[40:41], v[38:39]
	v_pk_mul_f32 v[90:91], v[54:55], v[38:39]
	v_pk_mul_f32 v[74:75], v[46:47], v[38:39]
	v_pk_mul_f32 v[120:121], v[66:67], v[180:181]
	v_mov_b64_e32 v[44:45], 0x408
	v_mov_b64_e32 v[46:47], 0x508
	v_mov_b64_e32 v[38:39], 0x608
	v_mov_b64_e32 v[40:41], 0x708
	v_mov_b64_e32 v[54:55], v[94:95]
	v_mov_b64_e32 v[52:53], v[90:91]
	v_mov_b64_e32 v[50:51], v[84:85]
	v_mov_b64_e32 v[48:49], v[74:75]
	v_mov_b64_e32 v[62:63], v[88:89]
	v_mov_b64_e32 v[60:61], v[86:87]
	v_mov_b64_e32 v[58:59], v[82:83]
	v_mov_b64_e32 v[56:57], v[72:73]
	s_and_saveexec_b64 s[28:29], vcc
	s_cbranch_execz .LBB0_1266
	v_cmp_eq_u32_e32 vcc, 0, v3
	s_mov_b64 s[30:31], 0
	v_mov_b64_e32 v[44:45], 0x408
	v_mov_b64_e32 v[46:47], 0x508
	v_mov_b64_e32 v[38:39], 0x608
	v_mov_b64_e32 v[40:41], 0x708
	s_and_saveexec_b64 s[34:35], vcc
	s_mov_b64 s[30:31], exec
	v_mov_b64_e32 v[44:45], 8
	v_mov_b64_e32 v[46:47], 0x108
	v_mov_b64_e32 v[38:39], 0x208
	v_mov_b64_e32 v[40:41], 0x308
	s_or_b64 exec, exec, s[34:35]
	s_orn2_b64 s[30:31], s[30:31], exec
	v_mov_b64_e32 v[54:55], v[112:113]
	v_mov_b64_e32 v[52:53], v[116:117]
	v_mov_b64_e32 v[50:51], v[114:115]
	v_mov_b64_e32 v[48:49], v[118:119]
	v_mov_b64_e32 v[62:63], v[126:127]
	v_mov_b64_e32 v[60:61], v[124:125]
	v_mov_b64_e32 v[58:59], v[122:123]
	v_mov_b64_e32 v[56:57], v[120:121]
.LBB0_1266:
	s_or_b64 exec, exec, s[28:29]
	s_and_saveexec_b64 s[28:29], s[30:31]
	s_cbranch_execz .LBB0_1249
	s_nop 7
	s_nop 1
	v_cvt_pk_bf16_f32 v61, v63, v61
	v_cvt_pk_bf16_f32 v60, v62, v60
	s_nop 7
	s_nop 1
	v_lshl_add_u64 v[44:45], v[158:159], 0, v[44:45]
	v_cvt_pk_bf16_f32 v57, v59, v57
	v_cvt_pk_bf16_f32 v56, v58, v56
	global_store_dwordx2 v[44:45], v[60:61], off
	v_lshl_add_u64 v[44:45], v[158:159], 0, v[46:47]
	global_store_dwordx2 v[44:45], v[56:57], off
	s_nop 7
	s_nop 1
	v_cvt_pk_bf16_f32 v45, v55, v53
	v_cvt_pk_bf16_f32 v44, v54, v52
	v_and_b32_sdwa v46, v51, v238 dst_sel:DWORD dst_unused:UNUSED_PAD src0_sel:WORD_1 src1_sel:DWORD
	s_nop 1
	v_add3_u32 v46, v51, v46, s55
	v_and_b32_sdwa v47, v49, v238 dst_sel:DWORD dst_unused:UNUSED_PAD src0_sel:WORD_1 src1_sel:DWORD
	s_nop 0
	v_add3_u32 v47, v49, v47, s55
	s_nop 0
	v_and_b32_e32 v47, 0xffff0000, v47
	s_nop 0
	v_lshl_add_u64 v[38:39], v[158:159], 0, v[38:39]
	v_or_b32_sdwa v47, v47, v46 dst_sel:DWORD dst_unused:UNUSED_PAD src0_sel:DWORD src1_sel:WORD_1
	v_cvt_pk_bf16_f32 v46, v50, v48
	global_store_dwordx2 v[38:39], v[44:45], off
	v_lshl_add_u64 v[38:39], v[158:159], 0, v[40:41]
	global_store_dwordx2 v[38:39], v[46:47], off
	s_branch .LBB0_1249

; __device__ __forceinline__ float siluf_(float x) { return x * sigmoidf_(x); }
; __device__ __forceinline__ void ffn_fixup(const Ctx& c, const bf16* HALO, const float* cw, const float* cb, bf16* ACT) {
;     ...
;         const int cg8 = it & 15, wr = (it >> 4) & 1, tile = it >> 5, pm = tile / 44, pn = tile % 44, ch0 = 128 * pn + 8 * cg8;
;         const bf16* cur = HALO + ((size_t)(tile * 2 + wr) * 4) * 256 + 8 * cg8;
;         const bool hasprev = wr == 1 || (pm & 15) != 0; const bf16* prv = wr == 1 ? HALO + ((size_t)(tile * 2) * 4 + 2) * 256 + 8 * cg8 : HALO + ((size_t)((tile - 44) * 2 + 1) * 4 + 2) * 256 + 8 * cg8;
;         const v4u z4 = (v4u){0u, 0u, 0u, 0u};
;         const v4u cg0 = *(const v4u*)cur, cv0 = *(const v4u*)(cur + 128), cg1 = *(const v4u*)(cur + 256), cv1 = *(const v4u*)(cur + 256 + 128);
;         const v4u pg2 = hasprev ? *(const v4u*)prv : z4, pv2 = hasprev ? *(const v4u*)(prv + 128) : z4, pg3 = hasprev ? *(const v4u*)(prv + 256) : z4, pv3 = hasprev ? *(const v4u*)(prv + 256 + 128) : z4;
;         float oa[8], ob[8];
; #pragma unroll
;         for (int j = 0; j < 8; ++j) { const int q = j >> 1; const bool hi = j & 1;
;             const float wg0 = cw[ch0 + j], wg1 = cw[FF2 + ch0 + j], wg2 = cw[2 * FF2 + ch0 + j], wv0 = cw[FFH + ch0 + j], wv1 = cw[FF2 + FFH + ch0 + j], wv2 = cw[2 * FF2 + FFH + ch0 + j], bg = cb[ch0 + j], bv = cb[FFH + ch0 + j];
;             const float gA2 = hi ? bfhi(pg2[q]) : bflo(pg2[q]), gA1 = hi ? bfhi(pg3[q]) : bflo(pg3[q]), gA0 = hi ? bfhi(cg0[q]) : bflo(cg0[q]), gB0 = hi ? bfhi(cg1[q]) : bflo(cg1[q]);
;             const float vA2 = hi ? bfhi(pv2[q]) : bflo(pv2[q]), vA1 = hi ? bfhi(pv3[q]) : bflo(pv3[q]), vA0 = hi ? bfhi(cv0[q]) : bflo(cv0[q]), vB0 = hi ? bfhi(cv1[q]) : bflo(cv1[q]);
;             oa[j] = siluf_(bg + wg0 * gA2 + wg1 * gA1 + wg2 * gA0) * (bv + wv0 * vA2 + wv1 * vA1 + wv2 * vA0);
.LBB0_1328:
	s_or_b64 exec, exec, s[0:1]
	v_mul_lo_u32 v26, v24, 44
	v_sub_u32_e32 v25, v25, v26
	v_lshl_or_b32 v94, v25, 7, v28
	v_ashrrev_i32_e32 v95, 31, v94
	v_readlane_b32 s20, v253, 2
	v_lshlrev_b64 v[26:27], 2, v[94:95]
	v_readlane_b32 s21, v253, 3
	s_mov_b64 s[0:1], 0xb000
	v_readlane_b32 s22, v253, 4
	v_lshl_add_u64 v[42:43], s[20:21], 0, v[26:27]
	v_lshl_add_u64 v[28:29], v[42:43], 0, s[0:1]
	s_mov_b64 s[0:1], 0x16000
	v_readlane_b32 s23, v253, 5
	v_lshl_add_u64 v[36:37], v[42:43], 0, s[0:1]
	s_mov_b64 s[0:1], 0x5800
	v_lshl_add_u64 v[38:39], v[26:27], 0, s[0:1]
	v_lshl_add_u64 v[44:45], s[22:23], 0, v[26:27]
	v_ashrrev_i32_e32 v25, 31, v24
	v_lshl_add_u64 v[34:35], s[20:21], 0, v[38:39]
	v_lshl_add_u64 v[48:49], s[22:23], 0, v[38:39]
	s_waitcnt vmcnt(0)
	v_lshlrev_b32_e32 v39, 16, v13
	v_lshlrev_b32_e32 v38, 16, v12
	v_and_b32_e32 v131, 0xffff0000, v13
	v_and_b32_e32 v130, 0xffff0000, v12
	v_lshlrev_b32_e32 v123, 16, v15
	v_lshlrev_b32_e32 v122, 16, v14
	v_and_b32_e32 v121, 0xffff0000, v15
	v_and_b32_e32 v120, 0xffff0000, v14
	v_lshlrev_b64 v[102:103], 8, v[24:25]
	global_load_dwordx4 v[12:15], v[42:43], off offset:16
	global_load_dwordx4 v[60:63], v[42:43], off
	global_load_dwordx4 v[24:27], v[44:45], off offset:16
	global_load_dwordx4 v[64:67], v[44:45], off
	s_mov_b64 s[0:1], 0x10800
	v_lshl_add_u64 v[32:33], v[42:43], 0, s[0:1]
	s_mov_b64 s[0:1], 0x1b800
	v_lshl_add_u64 v[40:41], v[42:43], 0, s[0:1]
	s_mov_b32 s0, 0xb000
	v_lshlrev_b32_e32 v114, 16, v18
	v_and_b32_e32 v104, 0xffff0000, v18
	v_add_co_u32_e32 v18, vcc, s0, v42
	v_lshlrev_b32_e32 v115, 16, v19
	v_and_b32_e32 v105, 0xffff0000, v19
	v_addc_co_u32_e32 v19, vcc, 0, v43, vcc
	v_lshl_or_b32 v88, v30, 7, v102
	global_load_dwordx4 v[68:71], v[18:19], off
	s_nop 0
	global_load_dwordx4 v[28:31], v[28:29], off offset:16
	v_add_co_u32_e32 v18, vcc, s12, v42
	v_lshlrev_b32_e32 v126, 16, v16
	s_nop 0
	v_addc_co_u32_e32 v19, vcc, 0, v43, vcc
	v_and_b32_e32 v124, 0xffff0000, v16
	v_lshlrev_b32_e32 v127, 16, v17
	v_and_b32_e32 v125, 0xffff0000, v17
	v_lshlrev_b32_e32 v98, 16, v20
	v_lshlrev_b32_e32 v99, 16, v21
	v_lshlrev_b32_e32 v101, 16, v57
	v_lshlrev_b32_e32 v100, 16, v56
	s_mov_b32 s0, 0x10000
	v_and_b32_e32 v96, 0xffff0000, v20
	v_and_b32_e32 v97, 0xffff0000, v21
	v_lshlrev_b32_e32 v92, 16, v22
	v_and_b32_e32 v90, 0xffff0000, v22
	v_lshlrev_b32_e32 v93, 16, v23
	v_and_b32_e32 v91, 0xffff0000, v23
	v_and_b32_e32 v129, 0xffff0000, v57
	v_and_b32_e32 v128, 0xffff0000, v56
	v_lshlrev_b32_e32 v106, 16, v76
	v_lshlrev_b32_e32 v107, 16, v77
	v_lshlrev_b32_e32 v109, 16, v53
	v_lshlrev_b32_e32 v108, 16, v52
	v_and_b32_e32 v53, 0xffff0000, v53
	v_and_b32_e32 v52, 0xffff0000, v52
	v_add_u32_e32 v3, s13, v3
	v_add_u32_e32 v134, s14, v134
	v_readlane_b32 s24, v253, 6
	v_readlane_b32 s25, v253, 7
	v_readlane_b32 s26, v253, 8
	v_readlane_b32 s27, v253, 9
	s_waitcnt vmcnt(0)
	v_mov_b32_e32 v110, v60
	v_mov_b32_e32 v111, v62
	v_mov_b32_e32 v112, v64
	v_mov_b32_e32 v113, v66
	v_pk_fma_f32 v[16:17], v[110:111], v[38:39], v[112:113]
	global_load_dwordx4 v[80:83], v[18:19], off
	s_nop 0
	global_load_dwordx4 v[36:39], v[36:37], off offset:16
	v_mov_b32_e32 v62, v61
	v_mov_b32_e32 v66, v65
	v_pk_fma_f32 v[56:57], v[62:63], v[130:131], v[66:67]
	v_pk_fma_f32 v[62:63], v[62:63], v[96:97], v[66:67]
	v_mov_b32_e32 v116, v68
	v_mov_b32_e32 v117, v70
	v_pk_fma_f32 v[16:17], v[116:117], v[98:99], v[16:17]
	v_mov_b32_e32 v70, v69
	v_pk_fma_f32 v[56:57], v[70:71], v[96:97], v[56:57]
	v_pk_fma_f32 v[62:63], v[70:71], v[128:129], v[62:63]
	s_waitcnt vmcnt(0)
	v_mov_b32_e32 v118, v80
	v_mov_b32_e32 v119, v82
	v_pk_fma_f32 v[132:133], v[118:119], v[100:101], v[16:17]
	v_mov_b32_e32 v82, v81
	v_mul_f32_e32 v16, 0xbfb8aa3b, v132
	v_exp_f32_e32 v60, v16
	global_load_dwordx4 v[16:19], v[34:35], off offset:16
	s_waitcnt lgkmcnt(0)
	global_load_dwordx4 v[44:47], v[34:35], off
	global_load_dwordx4 v[20:23], v[48:49], off offset:16
	s_nop 0
	global_load_dwordx4 v[48:51], v[48:49], off
	v_add_co_u32_e32 v34, vcc, s0, v42
	s_mov_b32 s0, 0x1b000
	s_nop 0
	v_addc_co_u32_e32 v35, vcc, 0, v43, vcc
	v_add_co_u32_e32 v42, vcc, s0, v42
	global_load_dwordx4 v[72:75], v[34:35], off offset:2048
	s_nop 0
	global_load_dwordx4 v[32:35], v[32:33], off offset:16
	v_addc_co_u32_e32 v43, vcc, 0, v43, vcc
	global_load_dwordx4 v[84:87], v[42:43], off offset:2048
	s_nop 0
	global_load_dwordx4 v[40:43], v[40:41], off offset:16
	v_mul_f32_e32 v61, 0xbfb8aa3b, v133
	v_exp_f32_e32 v61, v61
	v_pk_fma_f32 v[68:69], v[82:83], v[128:129], v[56:57]
	v_and_b32_e32 v57, 0xffff0000, v77
	v_mul_f32_e32 v56, 0xbfb8aa3b, v68
	v_pk_add_f32 v[60:61], v[60:61], 1.0 op_sel_hi:[1,0]
	v_exp_f32_e32 v136, v56
	v_div_scale_f32 v64, s[0:1], v61, v61, 1.0
	v_rcp_f32_e32 v65, v64
	v_and_b32_e32 v56, 0xffff0000, v76
	v_fma_f32 v76, -v64, v65, 1.0
	v_fmac_f32_e32 v65, v76, v65
	v_div_scale_f32 v76, vcc, 1.0, v61, 1.0
	v_mul_f32_e32 v77, v76, v65
	v_fma_f32 v80, -v64, v77, v76
	v_fmac_f32_e32 v77, v80, v65
	v_fma_f32 v64, -v64, v77, v76
	v_div_fmas_f32 v64, v64, v65, v77
	v_div_fixup_f32 v61, v64, v61, 1.0
	v_div_scale_f32 v64, s[0:1], v60, v60, 1.0
	v_rcp_f32_e32 v65, v64
	s_waitcnt vmcnt(3)
	v_mov_b32_e32 v81, v74
	v_fma_f32 v76, -v64, v65, 1.0
	v_fmac_f32_e32 v65, v76, v65
	v_div_scale_f32 v76, vcc, 1.0, v60, 1.0
	v_mul_f32_e32 v77, v76, v65
	v_fma_f32 v80, -v64, v77, v76
	v_fmac_f32_e32 v77, v80, v65
	v_fma_f32 v64, -v64, v77, v76
	v_div_fmas_f32 v64, v64, v65, v77
	v_div_fixup_f32 v60, v64, v60, 1.0
	v_mov_b32_e32 v64, v44
	v_mul_f32_e32 v44, 0xbfb8aa3b, v69
	v_mov_b32_e32 v65, v46
	v_mov_b32_e32 v76, v48
	v_mov_b32_e32 v77, v50
	v_exp_f32_e32 v137, v44
	v_pk_fma_f32 v[126:127], v[64:65], v[126:127], v[76:77]
	v_mov_b32_e32 v80, v72
	v_pk_fma_f32 v[130:131], v[80:81], v[106:107], v[126:127]
	s_waitcnt vmcnt(1)
; __device__ __forceinline__ unsigned pk2(float lo, float hi) { return f2bf(lo) | (f2bf(hi) << 16); }
; __device__ __forceinline__ float siluf_(float x) { return x * sigmoidf_(x); }
; __device__ __forceinline__ void ffn_fixup(const Ctx& c, const bf16* HALO, const float* cw, const float* cb, bf16* ACT) {
;     ...
;             const float wg0 = cw[ch0 + j], wg1 = cw[FF2 + ch0 + j], wg2 = cw[2 * FF2 + ch0 + j], wv0 = cw[FFH + ch0 + j], wv1 = cw[FF2 + FFH + ch0 + j], wv2 = cw[2 * FF2 + FFH + ch0 + j], bg = cb[ch0 + j], bv = cb[FFH + ch0 + j];
;             const float gA2 = hi ? bfhi(pg2[q]) : bflo(pg2[q]), gA1 = hi ? bfhi(pg3[q]) : bflo(pg3[q]), gA0 = hi ? bfhi(cg0[q]) : bflo(cg0[q]), gB0 = hi ? bfhi(cg1[q]) : bflo(cg1[q]);
;             const float vA2 = hi ? bfhi(pv2[q]) : bflo(pv2[q]), vA1 = hi ? bfhi(pv3[q]) : bflo(pv3[q]), vA0 = hi ? bfhi(cv0[q]) : bflo(cv0[q]), vB0 = hi ? bfhi(cv1[q]) : bflo(cv1[q]);
;             oa[j] = siluf_(bg + wg0 * gA2 + wg1 * gA1 + wg2 * gA0) * (bv + wv0 * vA2 + wv1 * vA1 + wv2 * vA0);
;             ob[j] = siluf_(bg + wg0 * gA1 + wg1 * gA0 + wg2 * gB0) * (bv + wv0 * vA1 + wv1 * vA0 + wv2 * vB0); }
;         const size_t tok = (size_t)256 * pm + 128 * wr;
;         v4u w; w.x = pk2(oa[0], oa[1]); w.y = pk2(oa[2], oa[3]); w.z = pk2(oa[4], oa[5]); w.w = pk2(oa[6], oa[7]); *(v4u*)(ACT + tok * FFH + ch0) = w;
	v_mov_b32_e32 v126, v84
	v_mov_b32_e32 v127, v86
	v_pk_mul_f32 v[60:61], v[132:133], v[60:61]
	v_pk_fma_f32 v[130:131], v[126:127], v[108:109], v[130:131]
	v_mov_b32_e32 v74, v73
	v_pk_mul_f32 v[130:131], v[130:131], v[60:61]
	v_pk_add_f32 v[60:61], v[136:137], 1.0 op_sel_hi:[1,0]
	v_mov_b32_e32 v86, v85
	v_div_scale_f32 v44, s[0:1], v61, v61, 1.0
	v_rcp_f32_e32 v46, v44
	v_mov_b32_e32 v73, v26
	v_mov_b32_e32 v84, v28
	v_mov_b32_e32 v85, v30
	v_fma_f32 v48, -v44, v46, 1.0
	v_fmac_f32_e32 v46, v48, v46
	v_div_scale_f32 v48, vcc, 1.0, v61, 1.0
	v_mul_f32_e32 v50, v48, v46
	v_fma_f32 v72, -v44, v50, v48
	v_fmac_f32_e32 v50, v72, v46
	v_fma_f32 v44, -v44, v50, v48
	v_div_fmas_f32 v44, v44, v46, v50
	v_div_fixup_f32 v61, v44, v61, 1.0
	v_div_scale_f32 v44, s[0:1], v60, v60, 1.0
	v_rcp_f32_e32 v46, v44
	v_mov_b32_e32 v30, v29
	v_mov_b32_e32 v26, v25
	v_and_b32_e32 v25, 0xffff0000, v55
	v_fma_f32 v48, -v44, v46, 1.0
	v_fmac_f32_e32 v46, v48, v46
	v_div_scale_f32 v48, vcc, 1.0, v60, 1.0
	v_mul_f32_e32 v50, v48, v46
	v_fma_f32 v72, -v44, v50, v48
	v_fmac_f32_e32 v50, v72, v46
	v_fma_f32 v44, -v44, v50, v48
	v_div_fmas_f32 v44, v44, v46, v50
	v_mov_b32_e32 v46, v45
	v_mov_b32_e32 v50, v49
	v_div_fixup_f32 v60, v44, v60, 1.0
	v_pk_fma_f32 v[44:45], v[46:47], v[124:125], v[50:51]
	v_pk_mul_f32 v[60:61], v[68:69], v[60:61]
	v_pk_fma_f32 v[44:45], v[74:75], v[56:57], v[44:45]
	v_mov_b32_e32 v68, v12
	v_pk_fma_f32 v[44:45], v[86:87], v[52:53], v[44:45]
	v_mov_b32_e32 v69, v14
	v_mov_b32_e32 v72, v24
	v_pk_mul_f32 v[124:125], v[44:45], v[60:61]
	v_pk_fma_f32 v[44:45], v[68:69], v[122:123], v[72:73]
	v_lshlrev_b32_e32 v61, 16, v59
	v_lshlrev_b32_e32 v60, 16, v58
	v_pk_fma_f32 v[44:45], v[84:85], v[92:93], v[44:45]
	v_mov_b32_e32 v122, v36
	v_mov_b32_e32 v123, v38
	v_pk_fma_f32 v[132:133], v[122:123], v[60:61], v[44:45]
	v_mov_b32_e32 v38, v37
	v_mul_f32_e32 v12, 0xbfb8aa3b, v132
	v_mul_f32_e32 v29, 0xbfb8aa3b, v133
	v_exp_f32_e32 v28, v12
	v_exp_f32_e32 v29, v29
	v_mov_b32_e32 v14, v13
	v_pk_fma_f32 v[12:13], v[14:15], v[120:121], v[26:27]
	v_lshlrev_b32_e32 v48, 16, v54
	v_pk_add_f32 v[28:29], v[28:29], 1.0 op_sel_hi:[1,0]
	v_and_b32_e32 v59, 0xffff0000, v59
	v_div_scale_f32 v36, s[0:1], v29, v29, 1.0
	v_rcp_f32_e32 v37, v36
	v_and_b32_e32 v58, 0xffff0000, v58
	v_pk_fma_f32 v[12:13], v[30:31], v[90:91], v[12:13]
	v_and_b32_e32 v24, 0xffff0000, v54
	v_fma_f32 v54, -v36, v37, 1.0
	v_pk_fma_f32 v[120:121], v[38:39], v[58:59], v[12:13]
	v_fmac_f32_e32 v37, v54, v37
	v_div_scale_f32 v54, vcc, 1.0, v29, 1.0
	v_lshlrev_b32_e32 v49, 16, v55
	v_mul_f32_e32 v12, 0xbfb8aa3b, v120
	v_mul_f32_e32 v55, v54, v37
	v_lshlrev_b32_e32 v44, 16, v78
	v_exp_f32_e32 v136, v12
	v_and_b32_e32 v12, 0xffff0000, v78
	v_fma_f32 v78, -v36, v55, v54
	v_fmac_f32_e32 v55, v78, v37
	v_fma_f32 v36, -v36, v55, v54
	v_div_fmas_f32 v36, v36, v37, v55
	v_div_fixup_f32 v29, v36, v29, 1.0
	v_div_scale_f32 v36, s[0:1], v28, v28, 1.0
	v_rcp_f32_e32 v37, v36
	v_lshlrev_b32_e32 v45, 16, v79
	v_and_b32_e32 v13, 0xffff0000, v79
	v_pk_fma_f32 v[14:15], v[14:15], v[90:91], v[26:27]
	v_fma_f32 v54, -v36, v37, 1.0
	v_fmac_f32_e32 v37, v54, v37
	v_div_scale_f32 v54, vcc, 1.0, v28, 1.0
	v_mul_f32_e32 v55, v54, v37
	v_fma_f32 v78, -v36, v55, v54
	v_fmac_f32_e32 v55, v78, v37
	v_fma_f32 v36, -v36, v55, v54
	v_div_fmas_f32 v36, v36, v37, v55
	v_div_fixup_f32 v28, v36, v28, 1.0
	v_pk_mul_f32 v[132:133], v[132:133], v[28:29]
	v_mov_b32_e32 v28, v16
	v_mul_f32_e32 v16, 0xbfb8aa3b, v121
	v_mov_b32_e32 v29, v18
	v_mov_b32_e32 v36, v20
	v_mov_b32_e32 v37, v22
	v_exp_f32_e32 v137, v16
	v_pk_fma_f32 v[78:79], v[28:29], v[114:115], v[36:37]
	v_mov_b32_e32 v54, v32
	v_mov_b32_e32 v55, v34
	v_pk_fma_f32 v[114:115], v[54:55], v[44:45], v[78:79]
	s_waitcnt vmcnt(0)
	v_mov_b32_e32 v78, v40
	v_mov_b32_e32 v79, v42
	v_pk_fma_f32 v[114:115], v[78:79], v[48:49], v[114:115]
	v_mov_b32_e32 v34, v33
	v_pk_mul_f32 v[114:115], v[114:115], v[132:133]
	v_pk_add_f32 v[132:133], v[136:137], 1.0 op_sel_hi:[1,0]
	v_mov_b32_e32 v42, v41
	v_div_scale_f32 v16, s[0:1], v133, v133, 1.0
	v_rcp_f32_e32 v18, v16
	s_nop 2
	v_fma_f32 v20, -v16, v18, 1.0
	v_fmac_f32_e32 v18, v20, v18
	v_div_scale_f32 v20, vcc, 1.0, v133, 1.0
	v_mul_f32_e32 v22, v20, v18
	v_fma_f32 v32, -v16, v22, v20
	v_fmac_f32_e32 v22, v32, v18
	v_fma_f32 v16, -v16, v22, v20
	v_div_fmas_f32 v16, v16, v18, v22
	v_div_fixup_f32 v133, v16, v133, 1.0
	v_div_scale_f32 v16, s[0:1], v132, v132, 1.0
	v_rcp_f32_e32 v18, v16
	s_nop 2
	v_fma_f32 v20, -v16, v18, 1.0
	v_fmac_f32_e32 v18, v20, v18
	v_div_scale_f32 v20, vcc, 1.0, v132, 1.0
	v_mul_f32_e32 v22, v20, v18
	v_fma_f32 v32, -v16, v22, v20
	v_fmac_f32_e32 v22, v32, v18
	v_fma_f32 v16, -v16, v22, v20
	v_div_fmas_f32 v16, v16, v18, v22
	v_mov_b32_e32 v18, v17
	v_mov_b32_e32 v22, v21
	v_div_fixup_f32 v132, v16, v132, 1.0
	v_pk_fma_f32 v[16:17], v[18:19], v[104:105], v[22:23]
	v_pk_mul_f32 v[120:121], v[120:121], v[132:133]
	v_pk_fma_f32 v[16:17], v[34:35], v[12:13], v[16:17]
	s_nop 0
	v_pk_fma_f32 v[16:17], v[42:43], v[24:25], v[16:17]
	s_nop 0
	v_pk_mul_f32 v[16:17], v[16:17], v[120:121]
	s_nop 7
	s_nop 3
	v_cvt_pk_bf16_f32 v131, v131, v125
	v_cvt_pk_bf16_f32 v130, v130, v124
	v_cvt_pk_bf16_f32 v133, v115, v17
	v_cvt_pk_bf16_f32 v132, v114, v16
	v_lshlrev_b32_e32 v21, 16, v9
	v_lshlrev_b32_e32 v20, 16, v8
	v_lshlrev_b32_e32 v33, 16, v5
	v_lshlrev_b32_e32 v32, 16, v4
	v_and_b32_e32 v9, 0xffff0000, v9
	v_and_b32_e32 v8, 0xffff0000, v8
	v_and_b32_e32 v41, 0xffff0000, v5
	v_and_b32_e32 v40, 0xffff0000, v4
	v_pk_fma_f32 v[4:5], v[110:111], v[98:99], v[112:113]
	v_pk_fma_f32 v[8:9], v[82:83], v[8:9], v[62:63]
	v_pk_fma_f32 v[4:5], v[116:117], v[100:101], v[4:5]
; __device__ __forceinline__ unsigned pk2(float lo, float hi) { return f2bf(lo) | (f2bf(hi) << 16); }
; __device__ __forceinline__ float siluf_(float x) { return x * sigmoidf_(x); }
; __device__ __forceinline__ void ffn_fixup(const Ctx& c, const bf16* HALO, const float* cw, const float* cb, bf16* ACT) {
;     ...
;             oa[j] = siluf_(bg + wg0 * gA2 + wg1 * gA1 + wg2 * gA0) * (bv + wv0 * vA2 + wv1 * vA1 + wv2 * vA0);
;             ob[j] = siluf_(bg + wg0 * gA1 + wg1 * gA0 + wg2 * gB0) * (bv + wv0 * vA1 + wv1 * vA0 + wv2 * vB0); }
;         const size_t tok = (size_t)256 * pm + 128 * wr;
;         v4u w; w.x = pk2(oa[0], oa[1]); w.y = pk2(oa[2], oa[3]); w.z = pk2(oa[4], oa[5]); w.w = pk2(oa[6], oa[7]); *(v4u*)(ACT + tok * FFH + ch0) = w;
;         w.x = pk2(ob[0], ob[1]); w.y = pk2(ob[2], ob[3]); w.z = pk2(ob[4], ob[5]); w.w = pk2(ob[6], ob[7]); *(v4u*)(ACT + (tok + 1) * FFH + ch0) = w;
;     }
	v_pk_fma_f32 v[14:15], v[30:31], v[58:59], v[14:15]
	v_pk_fma_f32 v[4:5], v[118:119], v[20:21], v[4:5]
	v_mul_f32_e32 v21, 0xbfb8aa3b, v8
	v_mul_f32_e32 v20, 0xbfb8aa3b, v4
	v_exp_f32_e32 v62, v21
	v_mul_f32_e32 v21, 0xbfb8aa3b, v5
	v_exp_f32_e32 v20, v20
	v_exp_f32_e32 v21, v21
	v_pk_fma_f32 v[12:13], v[18:19], v[12:13], v[22:23]
	v_mov_b64_e32 v[16:17], s[78:79]
	v_pk_fma_f32 v[12:13], v[34:35], v[24:25], v[12:13]
	v_pk_add_f32 v[20:21], v[20:21], 1.0 op_sel_hi:[1,0]
	v_mad_u64_u32 v[16:17], s[0:1], v88, s17, v[16:17]
	v_div_scale_f32 v63, s[0:1], v21, v21, 1.0
	v_rcp_f32_e32 v66, v63
	v_mad_i32_i24 v17, v103, s17, v17
	v_lshl_add_u64 v[16:17], v[94:95], 1, v[16:17]
	global_store_dwordx4 v[16:17], v[130:133], off
	v_fma_f32 v67, -v63, v66, 1.0
	v_fmac_f32_e32 v66, v67, v66
	v_div_scale_f32 v67, vcc, 1.0, v21, 1.0
	v_mul_f32_e32 v70, v67, v66
	v_fma_f32 v71, -v63, v70, v67
	v_fmac_f32_e32 v70, v71, v66
	v_fma_f32 v63, -v63, v70, v67
	v_div_fmas_f32 v63, v63, v66, v70
	v_div_fixup_f32 v21, v63, v21, 1.0
	v_div_scale_f32 v63, s[0:1], v20, v20, 1.0
	v_rcp_f32_e32 v66, v63
	s_nop 0
	v_fma_f32 v67, -v63, v66, 1.0
	v_fmac_f32_e32 v66, v67, v66
	v_div_scale_f32 v67, vcc, 1.0, v20, 1.0
	v_mul_f32_e32 v70, v67, v66
	v_fma_f32 v71, -v63, v70, v67
	v_fmac_f32_e32 v70, v71, v66
	v_fma_f32 v63, -v63, v70, v67
	v_div_fmas_f32 v63, v63, v66, v70
	v_div_fixup_f32 v20, v63, v20, 1.0
	v_pk_mul_f32 v[4:5], v[4:5], v[20:21]
	v_pk_fma_f32 v[20:21], v[64:65], v[106:107], v[76:77]
	s_nop 0
	v_pk_fma_f32 v[20:21], v[80:81], v[108:109], v[20:21]
	s_nop 0
	v_pk_fma_f32 v[20:21], v[126:127], v[32:33], v[20:21]
	s_nop 0
	v_pk_mul_f32 v[4:5], v[20:21], v[4:5]
	v_mul_f32_e32 v20, 0xbfb8aa3b, v9
	v_exp_f32_e32 v63, v20
	s_nop 0
	v_pk_add_f32 v[20:21], v[62:63], 1.0 op_sel_hi:[1,0]
	s_nop 0
	v_div_scale_f32 v32, s[0:1], v21, v21, 1.0
	v_rcp_f32_e32 v33, v32
	s_nop 0
	v_fma_f32 v62, -v32, v33, 1.0
	v_fmac_f32_e32 v33, v62, v33
	v_div_scale_f32 v62, vcc, 1.0, v21, 1.0
	v_mul_f32_e32 v63, v62, v33
	v_fma_f32 v64, -v32, v63, v62
	v_fmac_f32_e32 v63, v64, v33
	v_fma_f32 v32, -v32, v63, v62
	v_div_fmas_f32 v32, v32, v33, v63
	v_div_fixup_f32 v21, v32, v21, 1.0
	v_div_scale_f32 v32, s[0:1], v20, v20, 1.0
	v_rcp_f32_e32 v33, v32
	s_nop 0
	v_fma_f32 v62, -v32, v33, 1.0
	v_fmac_f32_e32 v33, v62, v33
	v_div_scale_f32 v62, vcc, 1.0, v20, 1.0
	v_mul_f32_e32 v63, v62, v33
	v_fma_f32 v64, -v32, v63, v62
	v_fmac_f32_e32 v63, v64, v33
	v_fma_f32 v32, -v32, v63, v62
	v_div_fmas_f32 v32, v32, v33, v63
	v_div_fixup_f32 v20, v32, v20, 1.0
	v_pk_mul_f32 v[8:9], v[8:9], v[20:21]
	v_pk_fma_f32 v[20:21], v[46:47], v[56:57], v[50:51]
	v_lshlrev_b32_e32 v33, 16, v7
	v_pk_fma_f32 v[20:21], v[74:75], v[52:53], v[20:21]
	v_lshlrev_b32_e32 v32, 16, v6
	v_pk_fma_f32 v[20:21], v[86:87], v[40:41], v[20:21]
	v_pk_fma_f32 v[40:41], v[68:69], v[92:93], v[72:73]
	v_pk_mul_f32 v[8:9], v[20:21], v[8:9]
	v_lshlrev_b32_e32 v21, 16, v11
	v_lshlrev_b32_e32 v20, 16, v10
	v_pk_fma_f32 v[40:41], v[84:85], v[60:61], v[40:41]
	v_and_b32_e32 v11, 0xffff0000, v11
	v_and_b32_e32 v10, 0xffff0000, v10
	v_pk_fma_f32 v[20:21], v[122:123], v[20:21], v[40:41]
	v_pk_fma_f32 v[10:11], v[38:39], v[10:11], v[14:15]
	v_mul_f32_e32 v40, 0xbfb8aa3b, v20
	v_mul_f32_e32 v15, 0xbfb8aa3b, v21
	v_exp_f32_e32 v40, v40
	v_exp_f32_e32 v41, v15
	v_mul_f32_e32 v14, 0xbfb8aa3b, v10
	v_exp_f32_e32 v14, v14
	v_and_b32_e32 v7, 0xffff0000, v7
	v_pk_add_f32 v[26:27], v[40:41], 1.0 op_sel_hi:[1,0]
	v_and_b32_e32 v6, 0xffff0000, v6
	v_div_scale_f32 v15, s[0:1], v27, v27, 1.0
	v_rcp_f32_e32 v30, v15
	v_pk_fma_f32 v[6:7], v[42:43], v[6:7], v[12:13]
	v_fma_f32 v31, -v15, v30, 1.0
	v_fmac_f32_e32 v30, v31, v30
	v_div_scale_f32 v31, vcc, 1.0, v27, 1.0
	v_mul_f32_e32 v38, v31, v30
	v_fma_f32 v39, -v15, v38, v31
	v_fmac_f32_e32 v38, v39, v30
	v_fma_f32 v15, -v15, v38, v31
	v_div_fmas_f32 v15, v15, v30, v38
	v_div_fixup_f32 v27, v15, v27, 1.0
	v_div_scale_f32 v15, s[0:1], v26, v26, 1.0
	v_rcp_f32_e32 v30, v15
	s_nop 0
	v_fma_f32 v31, -v15, v30, 1.0
	v_fmac_f32_e32 v30, v31, v30
	v_div_scale_f32 v31, vcc, 1.0, v26, 1.0
	v_mul_f32_e32 v38, v31, v30
	v_fma_f32 v39, -v15, v38, v31
	v_fmac_f32_e32 v38, v39, v30
	v_fma_f32 v15, -v15, v38, v31
	v_div_fmas_f32 v15, v15, v30, v38
	v_div_fixup_f32 v26, v15, v26, 1.0
	v_mul_f32_e32 v15, 0xbfb8aa3b, v11
	v_exp_f32_e32 v15, v15
	v_pk_mul_f32 v[20:21], v[20:21], v[26:27]
	v_pk_fma_f32 v[26:27], v[28:29], v[44:45], v[36:37]
	v_pk_add_f32 v[14:15], v[14:15], 1.0 op_sel_hi:[1,0]
	v_pk_fma_f32 v[26:27], v[54:55], v[48:49], v[26:27]
	s_nop 0
	v_pk_fma_f32 v[26:27], v[78:79], v[32:33], v[26:27]
	s_nop 0
	v_pk_mul_f32 v[20:21], v[26:27], v[20:21]
	v_div_scale_f32 v26, s[0:1], v15, v15, 1.0
	v_rcp_f32_e32 v27, v26
	s_nop 0
	v_fma_f32 v28, -v26, v27, 1.0
	v_fmac_f32_e32 v27, v28, v27
	v_div_scale_f32 v28, vcc, 1.0, v15, 1.0
	v_mul_f32_e32 v29, v28, v27
	v_fma_f32 v30, -v26, v29, v28
	v_fmac_f32_e32 v29, v30, v27
	v_fma_f32 v26, -v26, v29, v28
	v_div_fmas_f32 v26, v26, v27, v29
	v_div_fixup_f32 v15, v26, v15, 1.0
	v_div_scale_f32 v26, s[0:1], v14, v14, 1.0
	v_rcp_f32_e32 v27, v26
	s_mov_b32 s0, 0x15fff
	v_fma_f32 v28, -v26, v27, 1.0
	v_fmac_f32_e32 v27, v28, v27
	v_div_scale_f32 v28, vcc, 1.0, v14, 1.0
	v_mul_f32_e32 v29, v28, v27
	v_fma_f32 v30, -v26, v29, v28
	v_fmac_f32_e32 v29, v30, v27
	v_fma_f32 v26, -v26, v29, v28
	v_div_fmas_f32 v26, v26, v27, v29
	v_div_fixup_f32 v14, v26, v14, 1.0
	v_pk_mul_f32 v[10:11], v[10:11], v[14:15]
	s_nop 0
	v_pk_mul_f32 v[6:7], v[6:7], v[10:11]
	s_nop 6
	v_bfe_u32 v12, v7, 16, 1
	v_bfe_u32 v13, v6, 16, 1
	s_nop 1
	v_add3_u32 v6, v6, v13, s16
	v_add3_u32 v7, v7, v12, s16
	v_bfe_u32 v12, v20, 16, 1
	v_bfe_u32 v13, v21, 16, 1
	s_nop 0
	v_cvt_pk_bf16_f32 v4, v4, v8
	v_add_co_u32_e32 v8, vcc, 0x2000, v16
	v_add3_u32 v10, v21, v13, s16
	v_add3_u32 v11, v20, v12, s16
	v_cvt_pk_bf16_f32 v5, v5, v9
	v_addc_co_u32_e32 v9, vcc, 0, v17, vcc
	v_lshrrev_b32_e32 v11, 16, v11
	v_lshrrev_b32_e32 v10, 16, v10
	v_cmp_lt_i32_e32 vcc, s0, v3
	v_and_or_b32 v7, v7, s15, v10
	v_and_or_b32 v6, v6, s15, v11
	s_or_b64 s[10:11], vcc, s[10:11]
	global_store_dwordx4 v[8:9], v[4:7], off offset:3072
	s_andn2_b64 exec, exec, s[10:11]
	s_cbranch_execz .LBB0_1337

; __device__ __forceinline__ void postnorm(const Ctx& c, const bf16* MF, bf16* XB, float* RS, const float* gpost, float* OUT) {
;     for (int row = c.gw; row < MT; row += c.NGW) {
;         const v4u* mr = (const v4u*)(MF + (size_t)row * DM) + c.lane; v4u* xr = (v4u*)(XB + (size_t)row * DM) + c.lane;
;         v4u mv[4], xv[4]; float v[4][8]; float s = 0.f;
; #pragma unroll
;         for (int j = 0; j < 4; ++j) { mv[j] = mr[64 * j]; xv[j] = xr[64 * j]; }
; #pragma unroll
;         for (int j = 0; j < 4; ++j)
; #pragma unroll
;             for (int k = 0; k < 4; ++k) { v[j][2 * k] = bflo(mv[j][k]); v[j][2 * k + 1] = bfhi(mv[j][k]); s += v[j][2 * k] * v[j][2 * k] + v[j][2 * k + 1] * v[j][2 * k + 1]; }
;         const float rs = rsqrtf(wave_sum(s) * (1.f / DM) + EPS);
.LBB0_1474:
	v_readlane_b32 s8, v253, 0
	v_readlane_b32 s9, v253, 1
	s_nop 1
	v_lshl_add_u64 v[38:39], s[8:9], 0, v[30:31]
	v_add_co_u32_e32 v58, vcc, 0xd400000, v38
	s_nop 1
	v_addc_co_u32_e32 v59, vcc, 0, v39, vcc
	s_waitcnt lgkmcnt(0)
	global_load_dwordx4 v[46:49], v[58:59], off
	global_load_dwordx4 v[50:53], v[58:59], off offset:1024
	global_load_dwordx4 v[54:57], v[58:59], off offset:2048
	s_nop 0
	global_load_dwordx4 v[58:61], v[58:59], off offset:3072
	v_add_co_u32_e32 v38, vcc, 0x9400000, v38
	s_waitcnt vmcnt(3)
	v_lshlrev_b32_e32 v79, 16, v47
	v_addc_co_u32_e32 v39, vcc, 0, v39, vcc
	global_load_dwordx4 v[62:65], v[38:39], off
	global_load_dwordx4 v[66:69], v[38:39], off offset:1024
	global_load_dwordx4 v[70:73], v[38:39], off offset:2048
	global_load_dwordx4 v[74:77], v[38:39], off offset:3072
	v_lshlrev_b32_e32 v78, 16, v46
	v_and_b32_e32 v47, 0xffff0000, v47
	v_and_b32_e32 v46, 0xffff0000, v46
	v_lshlrev_b32_e32 v81, 16, v49
	v_lshlrev_b32_e32 v80, 16, v48
	v_and_b32_e32 v49, 0xffff0000, v49
	v_and_b32_e32 v48, 0xffff0000, v48
	v_pk_mul_f32 v[94:95], v[46:47], v[46:47]
	v_pk_mul_f32 v[98:99], v[48:49], v[48:49]
	v_pk_fma_f32 v[94:95], v[78:79], v[78:79], v[94:95]
	s_waitcnt vmcnt(6)
	v_lshlrev_b32_e32 v83, 16, v51
	v_lshlrev_b32_e32 v82, 16, v50
	v_and_b32_e32 v51, 0xffff0000, v51
	v_and_b32_e32 v50, 0xffff0000, v50
	v_pk_fma_f32 v[98:99], v[80:81], v[80:81], v[98:99]
	v_add_f32_e32 v94, v94, v95
	v_pk_mul_f32 v[102:103], v[50:51], v[50:51]
	v_add_f32_e32 v94, v98, v94
	v_lshlrev_b32_e32 v85, 16, v53
	v_lshlrev_b32_e32 v84, 16, v52
	v_and_b32_e32 v53, 0xffff0000, v53
	v_and_b32_e32 v52, 0xffff0000, v52
	v_pk_fma_f32 v[102:103], v[82:83], v[82:83], v[102:103]
	v_add_f32_e32 v94, v99, v94
	v_pk_mul_f32 v[104:105], v[52:53], v[52:53]
	v_add_f32_e32 v94, v102, v94
	s_waitcnt vmcnt(5)
	v_lshlrev_b32_e32 v87, 16, v55
	v_lshlrev_b32_e32 v86, 16, v54
	v_and_b32_e32 v55, 0xffff0000, v55
	v_and_b32_e32 v54, 0xffff0000, v54
	v_pk_fma_f32 v[104:105], v[84:85], v[84:85], v[104:105]
	v_add_f32_e32 v94, v103, v94
	v_pk_mul_f32 v[106:107], v[54:55], v[54:55]
	v_add_f32_e32 v94, v104, v94
	v_lshlrev_b32_e32 v89, 16, v57
	v_lshlrev_b32_e32 v88, 16, v56
	v_and_b32_e32 v57, 0xffff0000, v57
	v_and_b32_e32 v56, 0xffff0000, v56
	v_pk_fma_f32 v[106:107], v[86:87], v[86:87], v[106:107]
	v_add_f32_e32 v94, v105, v94
	v_pk_mul_f32 v[108:109], v[56:57], v[56:57]
	v_add_f32_e32 v94, v106, v94
	s_waitcnt vmcnt(4)
	v_lshlrev_b32_e32 v91, 16, v59
	v_lshlrev_b32_e32 v90, 16, v58
	v_and_b32_e32 v59, 0xffff0000, v59
	v_and_b32_e32 v58, 0xffff0000, v58
	v_pk_fma_f32 v[108:109], v[88:89], v[88:89], v[108:109]
	v_add_f32_e32 v94, v107, v94
	v_pk_mul_f32 v[110:111], v[58:59], v[58:59]
	v_add_f32_e32 v94, v108, v94
	v_lshlrev_b32_e32 v93, 16, v61
	v_lshlrev_b32_e32 v92, 16, v60
	v_and_b32_e32 v61, 0xffff0000, v61
	v_and_b32_e32 v60, 0xffff0000, v60
	v_pk_fma_f32 v[110:111], v[90:91], v[90:91], v[110:111]
	v_add_f32_e32 v94, v109, v94
	v_pk_mul_f32 v[112:113], v[60:61], v[60:61]
	v_add_f32_e32 v94, v110, v94
	v_pk_fma_f32 v[112:113], v[92:93], v[92:93], v[112:113]
	v_add_f32_e32 v94, v111, v94
	v_add_f32_e32 v94, v112, v94
	v_add_f32_e32 v94, v113, v94
	ds_bpermute_b32 v98, v3, v94
	s_waitcnt lgkmcnt(0)
	v_add_f32_e32 v98, v94, v98
	ds_bpermute_b32 v102, v40, v98
	s_waitcnt lgkmcnt(0)
	v_add_f32_e32 v102, v98, v102
	ds_bpermute_b32 v104, v41, v102
	s_waitcnt vmcnt(3)
	v_lshlrev_b32_e32 v97, 16, v63
	v_lshlrev_b32_e32 v96, 16, v62
	v_and_b32_e32 v63, 0xffff0000, v63
	s_waitcnt lgkmcnt(0)
	v_add_f32_e32 v104, v102, v104
	ds_bpermute_b32 v106, v42, v104
	v_and_b32_e32 v62, 0xffff0000, v62
	v_lshlrev_b32_e32 v101, 16, v65
	v_lshlrev_b32_e32 v100, 16, v64
	v_and_b32_e32 v65, 0xffff0000, v65
	s_waitcnt lgkmcnt(0)
	v_add_f32_e32 v106, v104, v106
	ds_bpermute_b32 v108, v43, v106
	v_and_b32_e32 v64, 0xffff0000, v64
	s_waitcnt vmcnt(0)
	v_lshlrev_b32_e32 v109, 16, v77
	v_and_b32_e32 v77, 0xffff0000, v77
	v_lshlrev_b32_e32 v95, 16, v67
	s_waitcnt lgkmcnt(0)
	v_add_f32_e32 v108, v106, v108
	ds_bpermute_b32 v110, v44, v108
	v_lshlrev_b32_e32 v94, 16, v66
	v_and_b32_e32 v67, 0xffff0000, v67
	v_and_b32_e32 v66, 0xffff0000, v66
	v_lshlrev_b32_e32 v99, 16, v69
	s_waitcnt lgkmcnt(0)
; __device__ __forceinline__ unsigned pk2(float lo, float hi) { return f2bf(lo) | (f2bf(hi) << 16); }
; __device__ __forceinline__ void postnorm(const Ctx& c, const bf16* MF, bf16* XB, float* RS, const float* gpost, float* OUT) {
;     ...
;         const float rs = rsqrtf(wave_sum(s) * (1.f / DM) + EPS);
;         float s2 = 0.f;
; #pragma unroll
;         for (int j = 0; j < 4; ++j) { const float* gp = gpost + (c.lane + 64 * j) * 8; const f32x4 g0 = *(CF4)gp, g1 = *(CF4)(gp + 4);
; #pragma unroll
;             for (int k = 0; k < 4; ++k) { const float ga = (k < 2) ? g0[2 * k] : g1[2 * k - 4], gb = (k < 2) ? g0[2 * k + 1] : g1[2 * k - 3];
;                 v[j][2 * k] = bflo(xv[j][k]) + v[j][2 * k] * rs * ga; v[j][2 * k + 1] = bfhi(xv[j][k]) + v[j][2 * k + 1] * rs * gb;
;                 s2 += v[j][2 * k] * v[j][2 * k] + v[j][2 * k + 1] * v[j][2 * k + 1]; } }
;         if (OUT) {
; #pragma unroll
;             for (int j = 0; j < 4; ++j) { float* op = OUT + (size_t)row * DM + (c.lane + 64 * j) * 8; *(f32x4*)op = (f32x4){v[j][0], v[j][1], v[j][2], v[j][3]}; *(f32x4*)(op + 4) = (f32x4){v[j][4], v[j][5], v[j][6], v[j][7]}; }
;         } else {
; #pragma unroll
;             for (int j = 0; j < 4; ++j) { v4u o; o.x = pk2(v[j][0], v[j][1]); o.y = pk2(v[j][2], v[j][3]); o.z = pk2(v[j][4], v[j][5]); o.w = pk2(v[j][6], v[j][7]); xr[64 * j] = o; }
;             const float rs2 = rsqrtf(wave_sum(s2) * (1.f / DM) + EPS); if (c.lane == 0) RS[row] = rs2;
	v_add_f32_e32 v108, v108, v110
	v_fmamk_f32 v108, v108, 0x3a000000, v45
	v_mul_f32_e32 v110, 0x4b800000, v108
	v_cmp_gt_f32_e32 vcc, s13, v108
	v_lshlrev_b32_e32 v98, 16, v68
	v_and_b32_e32 v69, 0xffff0000, v69
	v_cndmask_b32_e32 v108, v108, v110, vcc
	v_rsq_f32_e32 v110, v108
	v_lshlrev_b32_e32 v108, 16, v76
	v_and_b32_e32 v76, 0xffff0000, v76
	v_and_b32_e32 v68, 0xffff0000, v68
	v_mul_f32_e32 v111, 0x45800000, v110
	v_cndmask_b32_e32 v110, v110, v111, vcc
	v_pk_mul_f32 v[46:47], v[110:111], v[46:47] op_sel_hi:[0,1]
	v_pk_mul_f32 v[78:79], v[110:111], v[78:79] op_sel_hi:[0,1]
	v_pk_mul_f32 v[48:49], v[110:111], v[48:49] op_sel_hi:[0,1]
	v_pk_fma_f32 v[46:47], v[36:37], v[46:47], v[62:63]
	v_pk_mul_f32 v[60:61], v[110:111], v[60:61] op_sel_hi:[0,1]
	v_pk_mul_f32 v[80:81], v[110:111], v[80:81] op_sel_hi:[0,1]
	v_pk_fma_f32 v[78:79], v[8:9], v[78:79], v[96:97]
	v_pk_fma_f32 v[48:49], v[10:11], v[48:49], v[64:65]
	v_pk_fma_f32 v[60:61], v[34:35], v[60:61], v[76:77]
	v_pk_mul_f32 v[76:77], v[46:47], v[46:47]
	v_pk_mul_f32 v[50:51], v[110:111], v[50:51] op_sel_hi:[0,1]
	v_pk_fma_f32 v[62:63], v[4:5], v[80:81], v[100:101]
	v_pk_fma_f32 v[76:77], v[78:79], v[78:79], v[76:77]
	v_pk_mul_f32 v[80:81], v[48:49], v[48:49]
	v_pk_mul_f32 v[82:83], v[110:111], v[82:83] op_sel_hi:[0,1]
	v_pk_fma_f32 v[50:51], v[6:7], v[50:51], v[66:67]
	v_pk_fma_f32 v[80:81], v[62:63], v[62:63], v[80:81]
	v_add_f32_e32 v76, v76, v77
	v_pk_fma_f32 v[64:65], v[16:17], v[82:83], v[94:95]
	v_pk_mul_f32 v[82:83], v[50:51], v[50:51]
	v_add_f32_e32 v76, v80, v76
	v_pk_fma_f32 v[82:83], v[64:65], v[64:65], v[82:83]
	v_add_f32_e32 v76, v81, v76
	v_add_f32_e32 v76, v82, v76
	s_nop 2
	v_bfe_u32 v82, v46, 16, 1
	v_pk_mul_f32 v[52:53], v[110:111], v[52:53] op_sel_hi:[0,1]
	v_add3_u32 v46, v46, v82, s14
	s_nop 2
	v_bfe_u32 v77, v78, 16, 1
	s_nop 2
	v_pk_mul_f32 v[84:85], v[110:111], v[84:85] op_sel_hi:[0,1]
	v_pk_fma_f32 v[52:53], v[18:19], v[52:53], v[68:69]
	s_nop 2
	v_add3_u32 v77, v78, v77, s14
	v_lshlrev_b32_e32 v103, 16, v71
	v_lshlrev_b32_e32 v102, 16, v70
	v_and_b32_e32 v71, 0xffff0000, v71
	v_and_b32_e32 v70, 0xffff0000, v70
	v_pk_fma_f32 v[66:67], v[12:13], v[84:85], v[98:99]
	v_pk_mul_f32 v[54:55], v[110:111], v[54:55] op_sel_hi:[0,1]
	v_pk_mul_f32 v[84:85], v[52:53], v[52:53]
	v_lshrrev_b32_e32 v77, 16, v77
	s_nop 2
	v_pk_mul_f32 v[68:69], v[110:111], v[86:87] op_sel_hi:[0,1]
	v_pk_fma_f32 v[54:55], v[14:15], v[54:55], v[70:71]
	v_pk_fma_f32 v[84:85], v[66:67], v[66:67], v[84:85]
	v_add_f32_e32 v76, v83, v76
	v_cvt_pk_bf16_f32 v49, v63, v49
	v_cvt_pk_bf16_f32 v48, v62, v48
	v_cvt_pk_bf16_f32 v47, v79, v47
	v_and_or_b32 v46, v46, s12, v77
	v_lshlrev_b32_e32 v105, 16, v73
	v_lshlrev_b32_e32 v104, 16, v72
	v_and_b32_e32 v73, 0xffff0000, v73
	v_and_b32_e32 v72, 0xffff0000, v72
	v_pk_fma_f32 v[68:69], v[24:25], v[68:69], v[102:103]
	v_pk_mul_f32 v[56:57], v[110:111], v[56:57] op_sel_hi:[0,1]
	v_pk_mul_f32 v[86:87], v[54:55], v[54:55]
	v_add_f32_e32 v76, v84, v76
	global_store_dwordx4 v[38:39], v[46:49], off
	v_pk_mul_f32 v[70:71], v[110:111], v[88:89] op_sel_hi:[0,1]
	v_pk_fma_f32 v[56:57], v[26:27], v[56:57], v[72:73]
	s_nop 3
	v_pk_fma_f32 v[86:87], v[68:69], v[68:69], v[86:87]
	v_add_f32_e32 v76, v85, v76
	s_nop 7
	v_lshlrev_b32_e32 v107, 16, v75
	v_lshlrev_b32_e32 v106, 16, v74
	v_and_b32_e32 v75, 0xffff0000, v75
	v_and_b32_e32 v74, 0xffff0000, v74
	v_pk_fma_f32 v[70:71], v[20:21], v[70:71], v[104:105]
	v_pk_mul_f32 v[58:59], v[110:111], v[58:59] op_sel_hi:[0,1]
	v_pk_mul_f32 v[88:89], v[56:57], v[56:57]
	v_add_f32_e32 v76, v86, v76
	s_nop 3
	v_pk_mul_f32 v[72:73], v[110:111], v[90:91] op_sel_hi:[0,1]
	v_pk_fma_f32 v[58:59], v[22:23], v[58:59], v[74:75]
	v_pk_fma_f32 v[88:89], v[70:71], v[70:71], v[88:89]
	v_add_f32_e32 v76, v87, v76
	s_nop 3
	v_pk_fma_f32 v[72:73], v[32:33], v[72:73], v[106:107]
	v_pk_mul_f32 v[90:91], v[58:59], v[58:59]
	v_add_f32_e32 v76, v88, v76
	v_cvt_pk_bf16_f32 v49, v67, v53
	v_cvt_pk_bf16_f32 v48, v66, v52
	v_cvt_pk_bf16_f32 v47, v65, v51
	v_cvt_pk_bf16_f32 v46, v64, v50
	v_pk_mul_f32 v[74:75], v[110:111], v[92:93] op_sel_hi:[0,1]
	v_pk_fma_f32 v[90:91], v[72:73], v[72:73], v[90:91]
	v_add_f32_e32 v76, v89, v76
	global_store_dwordx4 v[38:39], v[46:49], off offset:1024
	v_pk_fma_f32 v[74:75], v[28:29], v[74:75], v[108:109]
	v_pk_mul_f32 v[92:93], v[60:61], v[60:61]
	s_nop 1
	v_add_f32_e32 v76, v90, v76
	s_nop 5
	v_pk_fma_f32 v[92:93], v[74:75], v[74:75], v[92:93]
	v_add_f32_e32 v76, v91, v76
	s_nop 5
	v_add_f32_e32 v76, v92, v76
	s_nop 5
	v_add_f32_e32 v76, v93, v76
	v_cvt_pk_bf16_f32 v49, v71, v57
	v_cvt_pk_bf16_f32 v48, v70, v56
	v_cvt_pk_bf16_f32 v47, v69, v55
	v_cvt_pk_bf16_f32 v46, v68, v54
	global_store_dwordx4 v[38:39], v[46:49], off offset:2048
	ds_bpermute_b32 v47, v3, v76
	s_nop 3
	s_waitcnt lgkmcnt(0)
	v_add_f32_e32 v47, v76, v47
	ds_bpermute_b32 v50, v40, v47
	s_nop 3
	s_waitcnt lgkmcnt(0)
	v_add_f32_e32 v47, v47, v50
	ds_bpermute_b32 v50, v41, v47
	s_nop 1
	v_cvt_pk_bf16_f32 v51, v75, v61
	s_nop 0
	s_waitcnt lgkmcnt(0)
	v_add_f32_e32 v47, v47, v50
	ds_bpermute_b32 v50, v42, v47
	s_nop 3
	s_waitcnt lgkmcnt(0)
	v_add_f32_e32 v47, v47, v50
	ds_bpermute_b32 v50, v43, v47
	s_nop 3
	s_waitcnt lgkmcnt(0)
	v_add_f32_e32 v46, v47, v50
	ds_bpermute_b32 v47, v44, v46
	s_nop 0
	v_cvt_pk_bf16_f32 v50, v74, v60
	v_cvt_pk_bf16_f32 v49, v73, v59
	v_cvt_pk_bf16_f32 v48, v72, v58
	global_store_dwordx4 v[38:39], v[48:51], off offset:3072
	s_and_saveexec_b64 s[8:9], s[0:1]
	s_cbranch_execz .LBB0_1473
	s_waitcnt lgkmcnt(0)
	v_add_f32_e32 v38, v46, v47
	v_fmamk_f32 v38, v38, 0x3a000000, v45
	v_mul_f32_e32 v39, 0x4b800000, v38
	v_cmp_gt_f32_e32 vcc, s13, v38
	v_readlane_b32 s16, v253, 0
	v_readlane_b32 s17, v253, 1
	v_cndmask_b32_e32 v38, v38, v39, vcc
	v_rsq_f32_e32 v38, v38
	s_add_u32 s16, s16, s10
	s_addc_u32 s17, s17, s11
	v_mul_f32_e32 v39, 0x45800000, v38
	v_cndmask_b32_e32 v38, v38, v39, vcc
	global_store_dword v251, v38, s[16:17]
	s_branch .LBB0_1473

; #define LAS __attribute__((address_space(3)))
; #define LDS_WAIT() asm volatile("s_waitcnt lgkmcnt(0)" ::: "memory")
; __device__ __forceinline__ unsigned pk2(float lo, float hi) { return f2bf(lo) | (f2bf(hi) << 16); }
;     ...
;     for (int it = gw0; it < items; it += ngw) {
;         const int kb = it / nblk, nb = it % nblk, k0 = 64 * kb, n0 = 64 * nb, nq = (lane & 15) * 4, kr = lane >> 4; const bool ok = (n0 + nq) < N;
;         f32x4 v[16];
; #pragma unroll
;         for (int i = 0; i < 16; ++i) v[i] = ok ? __builtin_nontemporal_load((const f32x4*)(W + (size_t)(k0 + 4 * i + kr) * N + n0 + nq)) : (f32x4){0.f, 0.f, 0.f, 0.f};
;         if (gain) {
; #pragma unroll
;             for (int i = 0; i < 16; ++i) v[i] *= gain[k0 + 4 * i + kr]; }
; #pragma unroll
;         for (int i = 0; i < 16; ++i) { LAS float* d = scr + (4 * i + kr) * 65 + nq; d[0] = v[i].x; d[1] = v[i].y; d[2] = v[i].z; d[3] = v[i].w; }
;         LDS_WAIT(); asm volatile("" ::: "memory");
;         const int c8 = lane & 7; int d0 = n0;
;         if (ffnmap) { const int bj = n0 >= FFH ? 1 : 0, chn = n0 - FFH * bj; d0 = 256 * (chn >> 7) + 128 * bj + (chn & 127); }
; #pragma unroll
;         for (int j = 0; j < 8; ++j) { const int n = (lane >> 3) + 8 * j; const LAS float* sp = scr + (8 * c8) * 65 + n;
;             v4u o; o.x = pk2(sp[0 * 65], sp[1 * 65]); o.y = pk2(sp[2 * 65], sp[3 * 65]); o.z = pk2(sp[4 * 65], sp[5 * 65]); o.w = pk2(sp[6 * 65], sp[7 * 65]);
;             *(v4u*)(WT + (size_t)(d0 + n) * K + k0 + 8 * c8) = o; }
;         LDS_WAIT(); asm volatile("" ::: "memory");
;     }
.LBB0_1484:
	s_or_b64 exec, exec, s[8:9]
	v_lshl_add_u64 v[82:83], v[72:73], 2, s[2:3]
	global_load_dword v72, v[82:83], off
	s_add_i32 s15, s15, s10
	s_ashr_i32 s7, s6, 31
	s_add_i32 s14, s14, s86
	s_add_i32 s10, s10, s11
	s_cmpk_lt_i32 s14, 0x100
	s_waitcnt vmcnt(0)
	v_pk_mul_f32 v[86:87], v[8:9], v[72:73] op_sel_hi:[1,0]
	global_load_dword v8, v[82:83], off offset:16
	v_pk_mul_f32 v[84:85], v[10:11], v[72:73] op_sel_hi:[1,0]
	s_waitcnt vmcnt(0)
	v_pk_mul_f32 v[72:73], v[14:15], v[8:9] op_sel_hi:[1,0]
	v_pk_mul_f32 v[88:89], v[12:13], v[8:9] op_sel_hi:[1,0]
	global_load_dword v8, v[82:83], off offset:32
	global_load_dword v12, v[82:83], off offset:160
	s_waitcnt vmcnt(1)
	v_pk_mul_f32 v[90:91], v[4:5], v[8:9] op_sel_hi:[1,0]
	global_load_dword v4, v[82:83], off offset:48
	v_pk_mul_f32 v[74:75], v[6:7], v[8:9] op_sel_hi:[1,0]
	global_load_dword v6, v[82:83], off offset:128
	global_load_dword v8, v[82:83], off offset:144
	s_waitcnt vmcnt(3)
	v_pk_mul_f32 v[10:11], v[42:43], v[12:13] op_sel_hi:[1,0]
	v_pk_mul_f32 v[12:13], v[40:41], v[12:13] op_sel_hi:[1,0]
	v_add_u32_e32 v40, 0x410, v81
	s_waitcnt vmcnt(2)
	v_pk_mul_f32 v[92:93], v[22:23], v[4:5] op_sel_hi:[1,0]
	v_pk_mul_f32 v[94:95], v[20:21], v[4:5] op_sel_hi:[1,0]
	global_load_dword v4, v[82:83], off offset:64
	global_load_dword v20, v[82:83], off offset:192
	s_waitcnt vmcnt(1)
	v_pk_mul_f32 v[96:97], v[18:19], v[4:5] op_sel_hi:[1,0]
	v_pk_mul_f32 v[98:99], v[16:17], v[4:5] op_sel_hi:[1,0]
	global_load_dword v4, v[82:83], off offset:80
	global_load_dword v16, v[82:83], off offset:176
	s_waitcnt vmcnt(2)
	v_pk_mul_f32 v[18:19], v[50:51], v[20:21] op_sel_hi:[1,0]
	v_pk_mul_f32 v[20:21], v[48:49], v[20:21] op_sel_hi:[1,0]
	s_waitcnt vmcnt(1)
	v_pk_mul_f32 v[100:101], v[30:31], v[4:5] op_sel_hi:[1,0]
	v_pk_mul_f32 v[102:103], v[28:29], v[4:5] op_sel_hi:[1,0]
	global_load_dword v4, v[82:83], off offset:96
	global_load_dword v28, v[82:83], off offset:224
	v_lshl_add_u64 v[30:31], v[76:77], 2, s[2:3]
	s_waitcnt vmcnt(2)
	v_pk_mul_f32 v[14:15], v[54:55], v[16:17] op_sel_hi:[1,0]
	v_pk_mul_f32 v[16:17], v[52:53], v[16:17] op_sel_hi:[1,0]
	s_waitcnt vmcnt(1)
	v_pk_mul_f32 v[104:105], v[26:27], v[4:5] op_sel_hi:[1,0]
	v_pk_mul_f32 v[106:107], v[24:25], v[4:5] op_sel_hi:[1,0]
	global_load_dword v4, v[82:83], off offset:112
	global_load_dword v24, v[82:83], off offset:208
	s_waitcnt vmcnt(2)
	v_pk_mul_f32 v[26:27], v[58:59], v[28:29] op_sel_hi:[1,0]
	v_pk_mul_f32 v[28:29], v[56:57], v[28:29] op_sel_hi:[1,0]
	s_waitcnt vmcnt(1)
	v_pk_mul_f32 v[38:39], v[38:39], v[4:5] op_sel_hi:[1,0]
	v_pk_mul_f32 v[36:37], v[36:37], v[4:5] op_sel_hi:[1,0]
	v_pk_mul_f32 v[4:5], v[34:35], v[6:7] op_sel_hi:[1,0]
	v_pk_mul_f32 v[34:35], v[32:33], v[6:7] op_sel_hi:[1,0]
	global_load_dword v32, v[30:31], off
	ds_write2_b32 v81, v86, v87 offset1:1
	ds_write2_b32 v81, v84, v85 offset0:2 offset1:3
	ds_write2_b32 v40, v88, v89 offset1:1
	v_add_u32_e32 v40, 0x418, v81
	ds_write2_b32 v40, v72, v73 offset1:1
	v_add_u32_e32 v40, 0x820, v81
	ds_write2_b32 v40, v90, v91 offset1:1
	v_add_u32_e32 v40, 0x828, v81
	ds_write2_b32 v40, v74, v75 offset1:1
	v_add_u32_e32 v40, 0xc30, v81
	ds_write2_b32 v40, v94, v95 offset1:1
	v_add_u32_e32 v40, 0xc38, v81
	ds_write2_b32 v40, v92, v93 offset1:1
	v_add_u32_e32 v40, 0x1040, v81
	ds_write2_b32 v40, v98, v99 offset1:1
	v_add_u32_e32 v40, 0x1048, v81
	ds_write2_b32 v40, v96, v97 offset1:1
	v_add_u32_e32 v40, 0x1450, v81
	ds_write2_b32 v40, v102, v103 offset1:1
	v_add_u32_e32 v40, 0x1458, v81
	ds_write2_b32 v40, v100, v101 offset1:1
	v_add_u32_e32 v40, 0x1860, v81
	ds_write2_b32 v40, v106, v107 offset1:1
	v_add_u32_e32 v40, 0x1868, v81
	ds_write2_b32 v40, v104, v105 offset1:1
	v_add_u32_e32 v40, 0x1c70, v81
	ds_write2_b32 v40, v36, v37 offset1:1
	v_add_u32_e32 v36, 0x1c78, v81
	ds_write2_b32 v36, v38, v39 offset1:1
	v_add_u32_e32 v36, 0x2080, v81
	ds_write2_b32 v36, v34, v35 offset1:1
	v_add_u32_e32 v34, 0x2088, v81
	v_pk_mul_f32 v[6:7], v[46:47], v[8:9] op_sel_hi:[1,0]
	v_pk_mul_f32 v[8:9], v[44:45], v[8:9] op_sel_hi:[1,0]
	ds_write2_b32 v34, v4, v5 offset1:1
	v_add_u32_e32 v4, 0x2490, v81
	ds_write2_b32 v4, v8, v9 offset1:1
	v_add_u32_e32 v4, 0x2498, v81
	ds_write2_b32 v4, v6, v7 offset1:1
	v_add_u32_e32 v4, 0x28a0, v81
	ds_write2_b32 v4, v12, v13 offset1:1
	v_add_u32_e32 v4, 0x28a8, v81
	ds_write2_b32 v4, v10, v11 offset1:1
	v_add_u32_e32 v4, 0x2cb0, v81
	ds_write2_b32 v4, v16, v17 offset1:1
	v_add_u32_e32 v4, 0x2cb8, v81
	ds_write2_b32 v4, v14, v15 offset1:1
	v_add_u32_e32 v4, 0x30c0, v81
	ds_write2_b32 v4, v20, v21 offset1:1
	v_add_u32_e32 v4, 0x30c8, v81
	s_waitcnt vmcnt(1)
	v_pk_mul_f32 v[22:23], v[62:63], v[24:25] op_sel_hi:[1,0]
	v_pk_mul_f32 v[24:25], v[60:61], v[24:25] op_sel_hi:[1,0]
	ds_write2_b32 v4, v18, v19 offset1:1
	v_add_u32_e32 v4, 0x34d0, v81
	ds_write2_b32 v4, v24, v25 offset1:1
	v_add_u32_e32 v4, 0x34d8, v81
	ds_write2_b32 v4, v22, v23 offset1:1
	v_add_u32_e32 v4, 0x38e0, v81
	ds_write2_b32 v4, v28, v29 offset1:1
	v_add_u32_e32 v4, 0x38e8, v81
	ds_write2_b32 v4, v26, v27 offset1:1
	v_add_u32_e32 v4, 0x3cf0, v81
	s_waitcnt vmcnt(0)
	v_pk_mul_f32 v[30:31], v[66:67], v[32:33] op_sel_hi:[1,0]
	v_pk_mul_f32 v[32:33], v[64:65], v[32:33] op_sel_hi:[1,0]
	ds_write2_b32 v4, v32, v33 offset1:1
	v_add_u32_e32 v4, 0x3cf8, v81
	ds_write2_b32 v4, v30, v31 offset1:1
	s_waitcnt lgkmcnt(0)
	ds_read2_b32 v[8:9], v80 offset0:65 offset1:73
	ds_read2_b32 v[14:15], v80 offset1:8
	ds_read2_b32 v[16:17], v80 offset0:130 offset1:138
	ds_read2_b32 v[18:19], v80 offset0:195 offset1:203
	v_lshl_add_u64 v[4:5], s[6:7], 1, v[70:71]
	s_waitcnt lgkmcnt(3)
; #define LAS __attribute__((address_space(3)))
; #define LDS_WAIT() asm volatile("s_waitcnt lgkmcnt(0)" ::: "memory")
; __device__ __forceinline__ unsigned pk2(float lo, float hi) { return f2bf(lo) | (f2bf(hi) << 16); }
;     ...
;     for (int it = gw0; it < items; it += ngw) {
;         const int kb = it / nblk, nb = it % nblk, k0 = 64 * kb, n0 = 64 * nb, nq = (lane & 15) * 4, kr = lane >> 4; const bool ok = (n0 + nq) < N;
;         f32x4 v[16];
; #pragma unroll
;         for (int i = 0; i < 16; ++i) v[i] = ok ? __builtin_nontemporal_load((const f32x4*)(W + (size_t)(k0 + 4 * i + kr) * N + n0 + nq)) : (f32x4){0.f, 0.f, 0.f, 0.f};
;         if (gain) {
; #pragma unroll
;             for (int i = 0; i < 16; ++i) v[i] *= gain[k0 + 4 * i + kr]; }
; #pragma unroll
;         for (int i = 0; i < 16; ++i) { LAS float* d = scr + (4 * i + kr) * 65 + nq; d[0] = v[i].x; d[1] = v[i].y; d[2] = v[i].z; d[3] = v[i].w; }
;         LDS_WAIT(); asm volatile("" ::: "memory");
;         const int c8 = lane & 7; int d0 = n0;
;         if (ffnmap) { const int bj = n0 >= FFH ? 1 : 0, chn = n0 - FFH * bj; d0 = 256 * (chn >> 7) + 128 * bj + (chn & 127); }
; #pragma unroll
;         for (int j = 0; j < 8; ++j) { const int n = (lane >> 3) + 8 * j; const LAS float* sp = scr + (8 * c8) * 65 + n;
;             v4u o; o.x = pk2(sp[0 * 65], sp[1 * 65]); o.y = pk2(sp[2 * 65], sp[3 * 65]); o.z = pk2(sp[4 * 65], sp[5 * 65]); o.w = pk2(sp[6 * 65], sp[7 * 65]);
;             *(v4u*)(WT + (size_t)(d0 + n) * K + k0 + 8 * c8) = o; }
;         LDS_WAIT(); asm volatile("" ::: "memory");
;     }
	v_bfe_u32 v7, v8, 16, 1
	s_waitcnt lgkmcnt(2)
	v_bfe_u32 v6, v14, 16, 1
	v_add3_u32 v6, v14, v6, s12
	v_add3_u32 v7, v8, v7, s12
	v_add_u32_e32 v8, 0x400, v80
	v_lshrrev_b32_e32 v6, 16, v6
	ds_read2_b32 v[20:21], v8 offset0:4 offset1:12
	ds_read2_b32 v[22:23], v8 offset0:69 offset1:77
	v_and_or_b32 v10, v7, s13, v6
	s_waitcnt lgkmcnt(3)
	s_nop 1
	s_waitcnt lgkmcnt(2)
	s_nop 2
	ds_read2_b32 v[24:25], v8 offset0:134 offset1:142
	ds_read2_b32 v[26:27], v8 offset0:199 offset1:207
	v_cvt_pk_bf16_f32 v11, v16, v18
	s_waitcnt lgkmcnt(3)
	s_nop 1
	s_waitcnt lgkmcnt(2)
	s_nop 2
	v_cvt_pk_bf16_f32 v12, v20, v22
	s_waitcnt lgkmcnt(1)
	s_nop 1
	s_waitcnt lgkmcnt(0)
	s_nop 2
	v_cvt_pk_bf16_f32 v13, v24, v26
	v_add_u32_e32 v6, s15, v79
	v_ashrrev_i32_e32 v7, 31, v6
	v_lshlrev_b64 v[28:29], 12, v[6:7]
	v_lshl_add_u64 v[28:29], v[4:5], 0, v[28:29]
	s_nop 0
	global_store_dwordx4 v[28:29], v[10:13], off
	s_nop 3
	v_cvt_pk_bf16_f32 v10, v15, v9
	s_nop 4
	v_cvt_pk_bf16_f32 v11, v17, v19
	s_nop 4
	v_cvt_pk_bf16_f32 v12, v21, v23
	s_nop 0
	v_add_u32_e32 v14, 8, v6
	s_nop 1
	v_ashrrev_i32_e32 v15, 31, v14
	s_nop 1
	v_lshlrev_b64 v[14:15], 12, v[14:15]
	v_cvt_pk_bf16_f32 v13, v25, v27
	v_lshl_add_u64 v[14:15], v[4:5], 0, v[14:15]
	global_store_dwordx4 v[14:15], v[10:13], off
	ds_read2_b32 v[14:15], v80 offset0:81 offset1:89
	ds_read2_b32 v[16:17], v80 offset0:16 offset1:24
	ds_read2_b32 v[18:19], v80 offset0:146 offset1:154
	ds_read2_b32 v[20:21], v80 offset0:211 offset1:219
	ds_read2_b32 v[22:23], v8 offset0:20 offset1:28
	ds_read2_b32 v[24:25], v8 offset0:85 offset1:93
	ds_read2_b32 v[26:27], v8 offset0:150 offset1:158
	ds_read2_b32 v[28:29], v8 offset0:215 offset1:223
	s_waitcnt lgkmcnt(7)
	s_nop 0
	s_waitcnt lgkmcnt(6)
	s_nop 3
	v_cvt_pk_bf16_f32 v10, v16, v14
	s_waitcnt lgkmcnt(5)
	s_nop 1
	s_waitcnt lgkmcnt(4)
	s_nop 2
	v_cvt_pk_bf16_f32 v11, v18, v20
	s_waitcnt lgkmcnt(3)
	s_nop 1
	s_waitcnt lgkmcnt(2)
	s_nop 2
	v_cvt_pk_bf16_f32 v12, v22, v24
	s_waitcnt lgkmcnt(1)
	s_nop 1
	s_waitcnt lgkmcnt(0)
	s_nop 2
	v_add_u32_e32 v30, 16, v6
	v_cvt_pk_bf16_f32 v13, v26, v28
	v_ashrrev_i32_e32 v31, 31, v30
	v_bfe_u32 v7, v17, 16, 1
	v_lshlrev_b64 v[30:31], 12, v[30:31]
	v_add3_u32 v7, v17, v7, s12
	v_bfe_u32 v9, v15, 16, 1
	v_lshl_add_u64 v[30:31], v[4:5], 0, v[30:31]
	v_lshrrev_b32_e32 v7, 16, v7
	v_add3_u32 v9, v15, v9, s12
	global_store_dwordx4 v[30:31], v[10:13], off
	v_add_u32_e32 v14, 24, v6
	v_ashrrev_i32_e32 v15, 31, v14
	v_and_or_b32 v10, v9, s13, v7
	s_nop 4
	v_cvt_pk_bf16_f32 v11, v19, v21
	s_nop 4
	v_cvt_pk_bf16_f32 v12, v23, v25
	s_nop 4
	v_lshlrev_b64 v[14:15], 12, v[14:15]
	v_cvt_pk_bf16_f32 v13, v27, v29
	v_lshl_add_u64 v[14:15], v[4:5], 0, v[14:15]
	global_store_dwordx4 v[14:15], v[10:13], off
	ds_read2_b32 v[14:15], v80 offset0:97 offset1:105
	ds_read2_b32 v[16:17], v80 offset0:32 offset1:40
	ds_read2_b32 v[18:19], v80 offset0:162 offset1:170
	ds_read2_b32 v[20:21], v80 offset0:227 offset1:235
	ds_read2_b32 v[22:23], v8 offset0:36 offset1:44
	ds_read2_b32 v[24:25], v8 offset0:101 offset1:109
	ds_read2_b32 v[26:27], v8 offset0:166 offset1:174
	ds_read2_b32 v[28:29], v8 offset0:231 offset1:239
	s_waitcnt lgkmcnt(7)
	s_nop 0
	s_waitcnt lgkmcnt(6)
	s_nop 3
	v_cvt_pk_bf16_f32 v10, v16, v14
	s_waitcnt lgkmcnt(5)
	s_nop 1
	s_waitcnt lgkmcnt(4)
	s_nop 2
	v_cvt_pk_bf16_f32 v11, v18, v20
	s_waitcnt lgkmcnt(3)
	s_nop 1
	s_waitcnt lgkmcnt(2)
	s_nop 2
	v_cvt_pk_bf16_f32 v12, v22, v24
	s_waitcnt lgkmcnt(1)
	s_nop 1
	s_waitcnt lgkmcnt(0)
	s_nop 2
	v_add_u32_e32 v30, 32, v6
	v_cvt_pk_bf16_f32 v13, v26, v28
	v_ashrrev_i32_e32 v31, 31, v30
	v_bfe_u32 v7, v17, 16, 1
	v_lshlrev_b64 v[30:31], 12, v[30:31]
	v_add3_u32 v7, v17, v7, s12
	v_bfe_u32 v9, v15, 16, 1
	v_lshl_add_u64 v[30:31], v[4:5], 0, v[30:31]
	v_lshrrev_b32_e32 v7, 16, v7
	v_add3_u32 v9, v15, v9, s12
	global_store_dwordx4 v[30:31], v[10:13], off
	v_add_u32_e32 v14, 40, v6
	v_ashrrev_i32_e32 v15, 31, v14
	v_and_or_b32 v10, v9, s13, v7
	s_nop 4
	v_cvt_pk_bf16_f32 v11, v19, v21
	s_nop 4
	v_cvt_pk_bf16_f32 v12, v23, v25
	s_nop 4
	v_lshlrev_b64 v[14:15], 12, v[14:15]
	v_cvt_pk_bf16_f32 v13, v27, v29
	v_lshl_add_u64 v[14:15], v[4:5], 0, v[14:15]
	global_store_dwordx4 v[14:15], v[10:13], off
	ds_read2_b32 v[14:15], v80 offset0:48 offset1:56
	ds_read2_b32 v[16:17], v80 offset0:113 offset1:121
	ds_read2_b32 v[18:19], v80 offset0:178 offset1:186
	ds_read2_b32 v[20:21], v80 offset0:243 offset1:251
	ds_read2_b32 v[22:23], v8 offset0:52 offset1:60
	ds_read2_b32 v[24:25], v8 offset0:117 offset1:125
	ds_read2_b32 v[26:27], v8 offset0:182 offset1:190
	ds_read2_b32 v[28:29], v8 offset0:247 offset1:255
	s_waitcnt lgkmcnt(7)
	s_nop 1
	s_waitcnt lgkmcnt(6)
	s_nop 2
	v_cvt_pk_bf16_f32 v10, v14, v16
	s_waitcnt lgkmcnt(5)
	s_nop 1
	s_waitcnt lgkmcnt(4)
	s_nop 2
	v_cvt_pk_bf16_f32 v11, v18, v20
	s_waitcnt lgkmcnt(3)
	s_nop 1
	s_waitcnt lgkmcnt(2)
	s_nop 2
	v_cvt_pk_bf16_f32 v12, v22, v24
	s_waitcnt lgkmcnt(1)
	s_nop 1
	s_waitcnt lgkmcnt(0)
	s_nop 2
	v_cvt_pk_bf16_f32 v13, v26, v28
	v_add_u32_e32 v8, 48, v6
	v_ashrrev_i32_e32 v9, 31, v8
	v_lshlrev_b64 v[8:9], 12, v[8:9]
	v_lshl_add_u64 v[8:9], v[4:5], 0, v[8:9]
	s_nop 0
	global_store_dwordx4 v[8:9], v[10:13], off
	s_nop 3
	v_cvt_pk_bf16_f32 v8, v15, v17
	s_nop 4
	v_cvt_pk_bf16_f32 v9, v19, v21
	s_nop 4
	v_cvt_pk_bf16_f32 v10, v23, v25
	s_nop 4
	v_add_u32_e32 v6, 56, v6
	v_cvt_pk_bf16_f32 v11, v27, v29
	v_ashrrev_i32_e32 v7, 31, v6
	v_lshlrev_b64 v[6:7], 12, v[6:7]
	v_lshl_add_u64 v[4:5], v[4:5], 0, v[6:7]
	global_store_dwordx4 v[4:5], v[8:11], off
	s_waitcnt lgkmcnt(0)
	s_cbranch_scc0 .LBB0_1517

; #define LAS __attribute__((address_space(3)))
; #define LDS_WAIT() asm volatile("s_waitcnt lgkmcnt(0)" ::: "memory")
; __device__ __forceinline__ unsigned pk2(float lo, float hi) { return f2bf(lo) | (f2bf(hi) << 16); }
;     ...
;     for (int it = gw0; it < items; it += ngw) {
;         const int kb = it / nblk, nb = it % nblk, k0 = 64 * kb, n0 = 64 * nb, nq = (lane & 15) * 4, kr = lane >> 4; const bool ok = (n0 + nq) < N;
;         f32x4 v[16];
; #pragma unroll
;         for (int i = 0; i < 16; ++i) v[i] = ok ? __builtin_nontemporal_load((const f32x4*)(W + (size_t)(k0 + 4 * i + kr) * N + n0 + nq)) : (f32x4){0.f, 0.f, 0.f, 0.f};
;         if (gain) {
; #pragma unroll
;             for (int i = 0; i < 16; ++i) v[i] *= gain[k0 + 4 * i + kr]; }
; #pragma unroll
;         for (int i = 0; i < 16; ++i) { LAS float* d = scr + (4 * i + kr) * 65 + nq; d[0] = v[i].x; d[1] = v[i].y; d[2] = v[i].z; d[3] = v[i].w; }
;         LDS_WAIT(); asm volatile("" ::: "memory");
;         const int c8 = lane & 7; int d0 = n0;
;         if (ffnmap) { const int bj = n0 >= FFH ? 1 : 0, chn = n0 - FFH * bj; d0 = 256 * (chn >> 7) + 128 * bj + (chn & 127); }
; #pragma unroll
;         for (int j = 0; j < 8; ++j) { const int n = (lane >> 3) + 8 * j; const LAS float* sp = scr + (8 * c8) * 65 + n;
;             v4u o; o.x = pk2(sp[0 * 65], sp[1 * 65]); o.y = pk2(sp[2 * 65], sp[3 * 65]); o.z = pk2(sp[4 * 65], sp[5 * 65]); o.w = pk2(sp[6 * 65], sp[7 * 65]);
;             *(v4u*)(WT + (size_t)(d0 + n) * K + k0 + 8 * c8) = o; }
;         LDS_WAIT(); asm volatile("" ::: "memory");
;     }
.LBB0_1520:
	s_or_b64 exec, exec, s[6:7]
	s_waitcnt vmcnt(0)
	ds_write2_b32 v79, v4, v5 offset1:1
	ds_write2_b32 v79, v6, v7 offset0:2 offset1:3
	v_add_u32_e32 v4, 0x410, v79
	ds_write2_b32 v4, v12, v13 offset1:1
	v_add_u32_e32 v4, 0x418, v79
	ds_write2_b32 v4, v14, v15 offset1:1
	v_add_u32_e32 v4, 0x820, v79
	ds_write2_b32 v4, v8, v9 offset1:1
	v_add_u32_e32 v4, 0x828, v79
	ds_write2_b32 v4, v10, v11 offset1:1
	v_add_u32_e32 v4, 0xc30, v79
	ds_write2_b32 v4, v20, v21 offset1:1
	v_add_u32_e32 v4, 0xc38, v79
	ds_write2_b32 v4, v22, v23 offset1:1
	v_add_u32_e32 v4, 0x1040, v79
	ds_write2_b32 v4, v16, v17 offset1:1
	v_add_u32_e32 v4, 0x1048, v79
	ds_write2_b32 v4, v18, v19 offset1:1
	v_add_u32_e32 v4, 0x1450, v79
	ds_write2_b32 v4, v28, v29 offset1:1
	v_add_u32_e32 v4, 0x1458, v79
	ds_write2_b32 v4, v30, v31 offset1:1
	v_add_u32_e32 v4, 0x1860, v79
	ds_write2_b32 v4, v24, v25 offset1:1
	v_add_u32_e32 v4, 0x1868, v79
	ds_write2_b32 v4, v26, v27 offset1:1
	v_add_u32_e32 v4, 0x1c70, v79
	ds_write2_b32 v4, v36, v37 offset1:1
	v_add_u32_e32 v4, 0x1c78, v79
	ds_write2_b32 v4, v38, v39 offset1:1
	v_add_u32_e32 v4, 0x2080, v79
	ds_write2_b32 v4, v32, v33 offset1:1
	v_add_u32_e32 v4, 0x2088, v79
	ds_write2_b32 v4, v34, v35 offset1:1
	v_add_u32_e32 v4, 0x2490, v79
	ds_write2_b32 v4, v44, v45 offset1:1
	v_add_u32_e32 v4, 0x2498, v79
	ds_write2_b32 v4, v46, v47 offset1:1
	v_add_u32_e32 v4, 0x28a0, v79
	ds_write2_b32 v4, v40, v41 offset1:1
	v_add_u32_e32 v4, 0x28a8, v79
	ds_write2_b32 v4, v42, v43 offset1:1
	v_add_u32_e32 v4, 0x2cb0, v79
	ds_write2_b32 v4, v52, v53 offset1:1
	v_add_u32_e32 v4, 0x2cb8, v79
	ds_write2_b32 v4, v54, v55 offset1:1
	v_add_u32_e32 v4, 0x30c0, v79
	ds_write2_b32 v4, v48, v49 offset1:1
	v_add_u32_e32 v4, 0x30c8, v79
	ds_write2_b32 v4, v50, v51 offset1:1
	v_add_u32_e32 v4, 0x34d0, v79
	ds_write2_b32 v4, v60, v61 offset1:1
	v_add_u32_e32 v4, 0x34d8, v79
	ds_write2_b32 v4, v62, v63 offset1:1
	v_add_u32_e32 v4, 0x38e0, v79
	ds_write2_b32 v4, v56, v57 offset1:1
	v_add_u32_e32 v4, 0x38e8, v79
	ds_write2_b32 v4, v58, v59 offset1:1
	v_add_u32_e32 v4, 0x3cf0, v79
	ds_write2_b32 v4, v64, v65 offset1:1
	v_add_u32_e32 v4, 0x3cf8, v79
	ds_write2_b32 v4, v66, v67 offset1:1
	s_waitcnt lgkmcnt(0)
	ds_read2_b32 v[12:13], v78 offset1:8
	ds_read2_b32 v[14:15], v78 offset0:65 offset1:73
	ds_read2_b32 v[16:17], v78 offset0:130 offset1:138
	ds_read2_b32 v[18:19], v78 offset0:195 offset1:203
	v_add_u32_e32 v30, 0x400, v78
	s_waitcnt lgkmcnt(3)
	s_nop 1
	s_waitcnt lgkmcnt(2)
	s_nop 0
	ds_read2_b32 v[20:21], v30 offset0:4 offset1:12
	s_nop 1
	ds_read2_b32 v[22:23], v30 offset0:69 offset1:77
	v_cvt_pk_bf16_f32 v8, v12, v14
	s_waitcnt lgkmcnt(3)
	s_nop 1
	s_waitcnt lgkmcnt(2)
	s_nop 0
	ds_read2_b32 v[24:25], v30 offset0:134 offset1:142
	s_nop 1
	ds_read2_b32 v[26:27], v30 offset0:199 offset1:207
	v_cvt_pk_bf16_f32 v9, v16, v18
	s_waitcnt lgkmcnt(3)
	s_nop 1
	s_waitcnt lgkmcnt(2)
	s_nop 2
	v_cvt_pk_bf16_f32 v10, v20, v22
	s_waitcnt lgkmcnt(1)
	s_nop 1
	s_waitcnt lgkmcnt(0)
	s_nop 2
	s_add_i32 s16, s16, s12
	v_cvt_pk_bf16_f32 v11, v24, v26
	v_add_u32_e32 v6, s16, v77
	s_ashr_i32 s3, s2, 31
	v_ashrrev_i32_e32 v7, 31, v6
	v_lshl_add_u64 v[4:5], s[2:3], 1, v[70:71]
	v_lshlrev_b64 v[28:29], 12, v[6:7]
	v_lshl_add_u64 v[28:29], v[4:5], 0, v[28:29]
	s_nop 0
	global_store_dwordx4 v[28:29], v[8:11], off
	s_nop 3
	v_cvt_pk_bf16_f32 v8, v13, v15
	s_nop 4
	v_cvt_pk_bf16_f32 v9, v17, v19
	s_nop 4
	v_cvt_pk_bf16_f32 v10, v21, v23
	s_nop 0
	v_add_u32_e32 v12, 8, v6
	s_nop 1
	v_ashrrev_i32_e32 v13, 31, v12
	s_nop 1
	v_lshlrev_b64 v[12:13], 12, v[12:13]
	v_cvt_pk_bf16_f32 v11, v25, v27
	ds_read2_b32 v[14:15], v78 offset0:16 offset1:24
	v_lshl_add_u64 v[12:13], v[4:5], 0, v[12:13]
	global_store_dwordx4 v[12:13], v[8:11], off
	ds_read2_b32 v[12:13], v78 offset0:81 offset1:89
	ds_read2_b32 v[16:17], v78 offset0:146 offset1:154
	ds_read2_b32 v[18:19], v78 offset0:211 offset1:219
	s_waitcnt lgkmcnt(3)
	s_nop 1
	s_waitcnt lgkmcnt(2)
; #define LAS __attribute__((address_space(3)))
; #define LDS_WAIT() asm volatile("s_waitcnt lgkmcnt(0)" ::: "memory")
; __device__ __forceinline__ unsigned pk2(float lo, float hi) { return f2bf(lo) | (f2bf(hi) << 16); }
;     ...
;     for (int it = gw0; it < items; it += ngw) {
;         const int kb = it / nblk, nb = it % nblk, k0 = 64 * kb, n0 = 64 * nb, nq = (lane & 15) * 4, kr = lane >> 4; const bool ok = (n0 + nq) < N;
;         f32x4 v[16];
; #pragma unroll
;         for (int i = 0; i < 16; ++i) v[i] = ok ? __builtin_nontemporal_load((const f32x4*)(W + (size_t)(k0 + 4 * i + kr) * N + n0 + nq)) : (f32x4){0.f, 0.f, 0.f, 0.f};
;         if (gain) {
; #pragma unroll
;             for (int i = 0; i < 16; ++i) v[i] *= gain[k0 + 4 * i + kr]; }
; #pragma unroll
;         for (int i = 0; i < 16; ++i) { LAS float* d = scr + (4 * i + kr) * 65 + nq; d[0] = v[i].x; d[1] = v[i].y; d[2] = v[i].z; d[3] = v[i].w; }
;         LDS_WAIT(); asm volatile("" ::: "memory");
;         const int c8 = lane & 7; int d0 = n0;
;         if (ffnmap) { const int bj = n0 >= FFH ? 1 : 0, chn = n0 - FFH * bj; d0 = 256 * (chn >> 7) + 128 * bj + (chn & 127); }
; #pragma unroll
;         for (int j = 0; j < 8; ++j) { const int n = (lane >> 3) + 8 * j; const LAS float* sp = scr + (8 * c8) * 65 + n;
;             v4u o; o.x = pk2(sp[0 * 65], sp[1 * 65]); o.y = pk2(sp[2 * 65], sp[3 * 65]); o.z = pk2(sp[4 * 65], sp[5 * 65]); o.w = pk2(sp[6 * 65], sp[7 * 65]);
;             *(v4u*)(WT + (size_t)(d0 + n) * K + k0 + 8 * c8) = o; }
;         LDS_WAIT(); asm volatile("" ::: "memory");
;     }
	s_nop 0
	ds_read2_b32 v[20:21], v30 offset0:20 offset1:28
	s_nop 1
	ds_read2_b32 v[22:23], v30 offset0:85 offset1:93
	v_cvt_pk_bf16_f32 v8, v14, v12
	s_waitcnt lgkmcnt(3)
	s_nop 1
	s_waitcnt lgkmcnt(2)
	s_nop 0
	ds_read2_b32 v[24:25], v30 offset0:150 offset1:158
	s_nop 1
	ds_read2_b32 v[26:27], v30 offset0:215 offset1:223
	v_cvt_pk_bf16_f32 v9, v16, v18
	s_waitcnt lgkmcnt(3)
	s_nop 1
	s_waitcnt lgkmcnt(2)
	s_nop 2
	v_cvt_pk_bf16_f32 v10, v20, v22
	s_waitcnt lgkmcnt(1)
	s_nop 0
	v_add_u32_e32 v28, 16, v6
	s_nop 0
	s_waitcnt lgkmcnt(0)
	s_nop 0
	v_ashrrev_i32_e32 v29, 31, v28
	s_nop 1
	v_lshlrev_b64 v[28:29], 12, v[28:29]
	v_cvt_pk_bf16_f32 v11, v24, v26
	v_lshl_add_u64 v[28:29], v[4:5], 0, v[28:29]
	s_nop 0
	global_store_dwordx4 v[28:29], v[8:11], off
	s_nop 3
	v_cvt_pk_bf16_f32 v8, v15, v13
	s_nop 4
	v_cvt_pk_bf16_f32 v9, v17, v19
	s_nop 4
	v_cvt_pk_bf16_f32 v10, v21, v23
	s_nop 0
	v_add_u32_e32 v12, 24, v6
	s_nop 1
	v_ashrrev_i32_e32 v13, 31, v12
	s_nop 1
	v_lshlrev_b64 v[12:13], 12, v[12:13]
	v_cvt_pk_bf16_f32 v11, v25, v27
	ds_read2_b32 v[14:15], v78 offset0:32 offset1:40
	v_lshl_add_u64 v[12:13], v[4:5], 0, v[12:13]
	global_store_dwordx4 v[12:13], v[8:11], off
	ds_read2_b32 v[12:13], v78 offset0:97 offset1:105
	ds_read2_b32 v[16:17], v78 offset0:162 offset1:170
	ds_read2_b32 v[18:19], v78 offset0:227 offset1:235
	s_waitcnt lgkmcnt(3)
	s_nop 1
	s_waitcnt lgkmcnt(2)
	s_nop 0
	ds_read2_b32 v[20:21], v30 offset0:36 offset1:44
	s_nop 1
	ds_read2_b32 v[22:23], v30 offset0:101 offset1:109
	v_cvt_pk_bf16_f32 v8, v14, v12
	s_waitcnt lgkmcnt(3)
	s_nop 1
	s_waitcnt lgkmcnt(2)
	s_nop 0
	ds_read2_b32 v[24:25], v30 offset0:166 offset1:174
	s_nop 1
	ds_read2_b32 v[26:27], v30 offset0:231 offset1:239
	v_cvt_pk_bf16_f32 v9, v16, v18
	s_waitcnt lgkmcnt(3)
	s_nop 1
	s_waitcnt lgkmcnt(2)
	s_nop 2
	v_cvt_pk_bf16_f32 v10, v20, v22
	s_waitcnt lgkmcnt(1)
	s_nop 0
	v_add_u32_e32 v28, 32, v6
	s_nop 0
	s_waitcnt lgkmcnt(0)
	s_nop 0
	v_ashrrev_i32_e32 v29, 31, v28
	s_nop 1
	v_lshlrev_b64 v[28:29], 12, v[28:29]
	v_cvt_pk_bf16_f32 v11, v24, v26
	v_lshl_add_u64 v[28:29], v[4:5], 0, v[28:29]
	s_nop 0
	global_store_dwordx4 v[28:29], v[8:11], off
	s_nop 3
	v_cvt_pk_bf16_f32 v8, v15, v13
	s_nop 4
	v_cvt_pk_bf16_f32 v9, v17, v19
	s_nop 4
	v_cvt_pk_bf16_f32 v10, v21, v23
	s_nop 0
	v_add_u32_e32 v12, 40, v6
	s_nop 1
	v_ashrrev_i32_e32 v13, 31, v12
	s_nop 1
	v_lshlrev_b64 v[12:13], 12, v[12:13]
	v_cvt_pk_bf16_f32 v11, v25, v27
	ds_read2_b32 v[14:15], v78 offset0:48 offset1:56
	v_lshl_add_u64 v[12:13], v[4:5], 0, v[12:13]
	global_store_dwordx4 v[12:13], v[8:11], off
	ds_read2_b32 v[12:13], v78 offset0:113 offset1:121
	ds_read2_b32 v[16:17], v78 offset0:178 offset1:186
	ds_read2_b32 v[18:19], v78 offset0:243 offset1:251
	s_waitcnt lgkmcnt(3)
	s_nop 1
	s_waitcnt lgkmcnt(2)
	s_nop 0
	ds_read2_b32 v[20:21], v30 offset0:52 offset1:60
	s_nop 1
	ds_read2_b32 v[22:23], v30 offset0:117 offset1:125
	v_cvt_pk_bf16_f32 v8, v14, v12
	s_waitcnt lgkmcnt(3)
	s_nop 1
	s_waitcnt lgkmcnt(2)
	s_nop 0
	ds_read2_b32 v[24:25], v30 offset0:182 offset1:190
	s_nop 1
	ds_read2_b32 v[26:27], v30 offset0:247 offset1:255
	v_cvt_pk_bf16_f32 v9, v16, v18
	s_waitcnt lgkmcnt(3)
	s_nop 1
	s_waitcnt lgkmcnt(2)
	s_nop 2
	v_cvt_pk_bf16_f32 v10, v20, v22
	s_waitcnt lgkmcnt(1)
	s_nop 0
	v_add_u32_e32 v28, 48, v6
	s_nop 0
	s_waitcnt lgkmcnt(0)
	s_nop 0
	v_ashrrev_i32_e32 v29, 31, v28
	s_nop 1
	v_lshlrev_b64 v[28:29], 12, v[28:29]
	v_cvt_pk_bf16_f32 v11, v24, v26
	v_lshl_add_u64 v[28:29], v[4:5], 0, v[28:29]
	s_nop 0
	global_store_dwordx4 v[28:29], v[8:11], off
	s_nop 3
	v_cvt_pk_bf16_f32 v8, v15, v13
	s_nop 4
	v_cvt_pk_bf16_f32 v9, v17, v19
	s_nop 4
	v_cvt_pk_bf16_f32 v10, v21, v23
	s_nop 4
	v_add_u32_e32 v6, 56, v6
	v_cvt_pk_bf16_f32 v11, v25, v27
	v_ashrrev_i32_e32 v7, 31, v6
	v_lshlrev_b64 v[6:7], 12, v[6:7]
	v_lshl_add_u64 v[4:5], v[4:5], 0, v[6:7]
	global_store_dwordx4 v[4:5], v[8:11], off
	s_waitcnt lgkmcnt(0)
	s_add_i32 s11, s11, s86
	s_add_i32 s12, s12, s13
	s_cmpk_lt_i32 s11, 0x200
	s_cbranch_scc0 .LBB0_1553

; #define LAS __attribute__((address_space(3)))
; #define LDS_WAIT() asm volatile("s_waitcnt lgkmcnt(0)" ::: "memory")
; __device__ __forceinline__ unsigned pk2(float lo, float hi) { return f2bf(lo) | (f2bf(hi) << 16); }
;     ...
;     for (int it = gw0; it < items; it += ngw) {
;         const int kb = it / nblk, nb = it % nblk, k0 = 64 * kb, n0 = 64 * nb, nq = (lane & 15) * 4, kr = lane >> 4; const bool ok = (n0 + nq) < N;
;         f32x4 v[16];
; #pragma unroll
;         for (int i = 0; i < 16; ++i) v[i] = ok ? __builtin_nontemporal_load((const f32x4*)(W + (size_t)(k0 + 4 * i + kr) * N + n0 + nq)) : (f32x4){0.f, 0.f, 0.f, 0.f};
;         if (gain) {
; #pragma unroll
;             for (int i = 0; i < 16; ++i) v[i] *= gain[k0 + 4 * i + kr]; }
; #pragma unroll
;         for (int i = 0; i < 16; ++i) { LAS float* d = scr + (4 * i + kr) * 65 + nq; d[0] = v[i].x; d[1] = v[i].y; d[2] = v[i].z; d[3] = v[i].w; }
;         LDS_WAIT(); asm volatile("" ::: "memory");
;         const int c8 = lane & 7; int d0 = n0;
;         if (ffnmap) { const int bj = n0 >= FFH ? 1 : 0, chn = n0 - FFH * bj; d0 = 256 * (chn >> 7) + 128 * bj + (chn & 127); }
; #pragma unroll
;         for (int j = 0; j < 8; ++j) { const int n = (lane >> 3) + 8 * j; const LAS float* sp = scr + (8 * c8) * 65 + n;
;             v4u o; o.x = pk2(sp[0 * 65], sp[1 * 65]); o.y = pk2(sp[2 * 65], sp[3 * 65]); o.z = pk2(sp[4 * 65], sp[5 * 65]); o.w = pk2(sp[6 * 65], sp[7 * 65]);
;             *(v4u*)(WT + (size_t)(d0 + n) * K + k0 + 8 * c8) = o; }
;         LDS_WAIT(); asm volatile("" ::: "memory");
;     }
.LBB0_1555:
	s_or_b64 exec, exec, s[6:7]
	s_waitcnt vmcnt(0)
	ds_write2_b32 v79, v4, v5 offset1:1
	ds_write2_b32 v79, v6, v7 offset0:2 offset1:3
	v_add_u32_e32 v4, 0x410, v79
	ds_write2_b32 v4, v12, v13 offset1:1
	v_add_u32_e32 v4, 0x418, v79
	ds_write2_b32 v4, v14, v15 offset1:1
	v_add_u32_e32 v4, 0x820, v79
	ds_write2_b32 v4, v8, v9 offset1:1
	v_add_u32_e32 v4, 0x828, v79
	ds_write2_b32 v4, v10, v11 offset1:1
	v_add_u32_e32 v4, 0xc30, v79
	ds_write2_b32 v4, v20, v21 offset1:1
	v_add_u32_e32 v4, 0xc38, v79
	ds_write2_b32 v4, v22, v23 offset1:1
	v_add_u32_e32 v4, 0x1040, v79
	ds_write2_b32 v4, v16, v17 offset1:1
	v_add_u32_e32 v4, 0x1048, v79
	ds_write2_b32 v4, v18, v19 offset1:1
	v_add_u32_e32 v4, 0x1450, v79
	ds_write2_b32 v4, v28, v29 offset1:1
	v_add_u32_e32 v4, 0x1458, v79
	ds_write2_b32 v4, v30, v31 offset1:1
	v_add_u32_e32 v4, 0x1860, v79
	ds_write2_b32 v4, v24, v25 offset1:1
	v_add_u32_e32 v4, 0x1868, v79
	ds_write2_b32 v4, v26, v27 offset1:1
	v_add_u32_e32 v4, 0x1c70, v79
	ds_write2_b32 v4, v36, v37 offset1:1
	v_add_u32_e32 v4, 0x1c78, v79
	ds_write2_b32 v4, v38, v39 offset1:1
	v_add_u32_e32 v4, 0x2080, v79
	ds_write2_b32 v4, v32, v33 offset1:1
	v_add_u32_e32 v4, 0x2088, v79
	ds_write2_b32 v4, v34, v35 offset1:1
	v_add_u32_e32 v4, 0x2490, v79
	ds_write2_b32 v4, v44, v45 offset1:1
	v_add_u32_e32 v4, 0x2498, v79
	ds_write2_b32 v4, v46, v47 offset1:1
	v_add_u32_e32 v4, 0x28a0, v79
	ds_write2_b32 v4, v40, v41 offset1:1
	v_add_u32_e32 v4, 0x28a8, v79
	ds_write2_b32 v4, v42, v43 offset1:1
	v_add_u32_e32 v4, 0x2cb0, v79
	ds_write2_b32 v4, v52, v53 offset1:1
	v_add_u32_e32 v4, 0x2cb8, v79
	ds_write2_b32 v4, v54, v55 offset1:1
	v_add_u32_e32 v4, 0x30c0, v79
	ds_write2_b32 v4, v48, v49 offset1:1
	v_add_u32_e32 v4, 0x30c8, v79
	ds_write2_b32 v4, v50, v51 offset1:1
	v_add_u32_e32 v4, 0x34d0, v79
	ds_write2_b32 v4, v60, v61 offset1:1
	v_add_u32_e32 v4, 0x34d8, v79
	ds_write2_b32 v4, v62, v63 offset1:1
	v_add_u32_e32 v4, 0x38e0, v79
	ds_write2_b32 v4, v56, v57 offset1:1
	v_add_u32_e32 v4, 0x38e8, v79
	ds_write2_b32 v4, v58, v59 offset1:1
	v_add_u32_e32 v4, 0x3cf0, v79
	ds_write2_b32 v4, v64, v65 offset1:1
	v_add_u32_e32 v4, 0x3cf8, v79
	ds_write2_b32 v4, v66, v67 offset1:1
	s_waitcnt lgkmcnt(0)
	ds_read2_b32 v[12:13], v78 offset1:8
	ds_read2_b32 v[14:15], v78 offset0:65 offset1:73
	ds_read2_b32 v[16:17], v78 offset0:130 offset1:138
	ds_read2_b32 v[18:19], v78 offset0:195 offset1:203
	v_add_u32_e32 v30, 0x400, v78
	s_waitcnt lgkmcnt(3)
	s_nop 1
	s_waitcnt lgkmcnt(2)
	s_nop 0
	ds_read2_b32 v[20:21], v30 offset0:4 offset1:12
	s_nop 1
	ds_read2_b32 v[22:23], v30 offset0:69 offset1:77
	v_cvt_pk_bf16_f32 v8, v12, v14
	s_waitcnt lgkmcnt(3)
	s_nop 1
	s_waitcnt lgkmcnt(2)
	s_nop 0
	ds_read2_b32 v[24:25], v30 offset0:134 offset1:142
	s_nop 1
	ds_read2_b32 v[26:27], v30 offset0:199 offset1:207
	v_cvt_pk_bf16_f32 v9, v16, v18
	s_waitcnt lgkmcnt(3)
	s_nop 1
	s_waitcnt lgkmcnt(2)
	s_nop 2
	v_cvt_pk_bf16_f32 v10, v20, v22
	s_waitcnt lgkmcnt(1)
	s_nop 1
	s_waitcnt lgkmcnt(0)
	s_nop 2
	s_add_i32 s16, s16, s12
	v_cvt_pk_bf16_f32 v11, v24, v26
	v_add_u32_e32 v6, s16, v77
	s_ashr_i32 s3, s2, 31
	v_ashrrev_i32_e32 v7, 31, v6
	v_lshl_add_u64 v[4:5], s[2:3], 1, v[70:71]
	v_lshlrev_b64 v[28:29], 10, v[6:7]
	v_lshl_add_u64 v[28:29], v[4:5], 0, v[28:29]
	s_nop 0
	global_store_dwordx4 v[28:29], v[8:11], off
	s_nop 3
	v_cvt_pk_bf16_f32 v8, v13, v15
	s_nop 4
	v_cvt_pk_bf16_f32 v9, v17, v19
	s_nop 4
	v_cvt_pk_bf16_f32 v10, v21, v23
	s_nop 0
	v_add_u32_e32 v12, 8, v6
	s_nop 1
	v_ashrrev_i32_e32 v13, 31, v12
	s_nop 1
	v_lshlrev_b64 v[12:13], 10, v[12:13]
	v_cvt_pk_bf16_f32 v11, v25, v27
	ds_read2_b32 v[14:15], v78 offset0:16 offset1:24
	v_lshl_add_u64 v[12:13], v[4:5], 0, v[12:13]
	global_store_dwordx4 v[12:13], v[8:11], off
	ds_read2_b32 v[12:13], v78 offset0:81 offset1:89
	ds_read2_b32 v[16:17], v78 offset0:146 offset1:154
	ds_read2_b32 v[18:19], v78 offset0:211 offset1:219
	s_waitcnt lgkmcnt(3)
	s_nop 1
	s_waitcnt lgkmcnt(2)
; #define LAS __attribute__((address_space(3)))
; #define LDS_WAIT() asm volatile("s_waitcnt lgkmcnt(0)" ::: "memory")
; __device__ __forceinline__ unsigned pk2(float lo, float hi) { return f2bf(lo) | (f2bf(hi) << 16); }
;     ...
;     for (int it = gw0; it < items; it += ngw) {
;         const int kb = it / nblk, nb = it % nblk, k0 = 64 * kb, n0 = 64 * nb, nq = (lane & 15) * 4, kr = lane >> 4; const bool ok = (n0 + nq) < N;
;         f32x4 v[16];
; #pragma unroll
;         for (int i = 0; i < 16; ++i) v[i] = ok ? __builtin_nontemporal_load((const f32x4*)(W + (size_t)(k0 + 4 * i + kr) * N + n0 + nq)) : (f32x4){0.f, 0.f, 0.f, 0.f};
;         if (gain) {
; #pragma unroll
;             for (int i = 0; i < 16; ++i) v[i] *= gain[k0 + 4 * i + kr]; }
; #pragma unroll
;         for (int i = 0; i < 16; ++i) { LAS float* d = scr + (4 * i + kr) * 65 + nq; d[0] = v[i].x; d[1] = v[i].y; d[2] = v[i].z; d[3] = v[i].w; }
;         LDS_WAIT(); asm volatile("" ::: "memory");
;         const int c8 = lane & 7; int d0 = n0;
;         if (ffnmap) { const int bj = n0 >= FFH ? 1 : 0, chn = n0 - FFH * bj; d0 = 256 * (chn >> 7) + 128 * bj + (chn & 127); }
; #pragma unroll
;         for (int j = 0; j < 8; ++j) { const int n = (lane >> 3) + 8 * j; const LAS float* sp = scr + (8 * c8) * 65 + n;
;             v4u o; o.x = pk2(sp[0 * 65], sp[1 * 65]); o.y = pk2(sp[2 * 65], sp[3 * 65]); o.z = pk2(sp[4 * 65], sp[5 * 65]); o.w = pk2(sp[6 * 65], sp[7 * 65]);
;             *(v4u*)(WT + (size_t)(d0 + n) * K + k0 + 8 * c8) = o; }
;         LDS_WAIT(); asm volatile("" ::: "memory");
;     }
	s_nop 0
	ds_read2_b32 v[20:21], v30 offset0:20 offset1:28
	s_nop 1
	ds_read2_b32 v[22:23], v30 offset0:85 offset1:93
	v_cvt_pk_bf16_f32 v8, v14, v12
	s_waitcnt lgkmcnt(3)
	s_nop 1
	s_waitcnt lgkmcnt(2)
	s_nop 0
	ds_read2_b32 v[24:25], v30 offset0:150 offset1:158
	s_nop 1
	ds_read2_b32 v[26:27], v30 offset0:215 offset1:223
	v_cvt_pk_bf16_f32 v9, v16, v18
	s_waitcnt lgkmcnt(3)
	s_nop 1
	s_waitcnt lgkmcnt(2)
	s_nop 2
	v_cvt_pk_bf16_f32 v10, v20, v22
	s_waitcnt lgkmcnt(1)
	s_nop 0
	v_add_u32_e32 v28, 16, v6
	s_nop 0
	s_waitcnt lgkmcnt(0)
	s_nop 0
	v_ashrrev_i32_e32 v29, 31, v28
	s_nop 1
	v_lshlrev_b64 v[28:29], 10, v[28:29]
	v_cvt_pk_bf16_f32 v11, v24, v26
	v_lshl_add_u64 v[28:29], v[4:5], 0, v[28:29]
	s_nop 0
	global_store_dwordx4 v[28:29], v[8:11], off
	s_nop 3
	v_cvt_pk_bf16_f32 v8, v15, v13
	s_nop 4
	v_cvt_pk_bf16_f32 v9, v17, v19
	s_nop 4
	v_cvt_pk_bf16_f32 v10, v21, v23
	s_nop 0
	v_add_u32_e32 v12, 24, v6
	s_nop 1
	v_ashrrev_i32_e32 v13, 31, v12
	s_nop 1
	v_lshlrev_b64 v[12:13], 10, v[12:13]
	v_cvt_pk_bf16_f32 v11, v25, v27
	ds_read2_b32 v[14:15], v78 offset0:32 offset1:40
	v_lshl_add_u64 v[12:13], v[4:5], 0, v[12:13]
	global_store_dwordx4 v[12:13], v[8:11], off
	ds_read2_b32 v[12:13], v78 offset0:97 offset1:105
	ds_read2_b32 v[16:17], v78 offset0:162 offset1:170
	ds_read2_b32 v[18:19], v78 offset0:227 offset1:235
	s_waitcnt lgkmcnt(3)
	s_nop 1
	s_waitcnt lgkmcnt(2)
	s_nop 0
	ds_read2_b32 v[20:21], v30 offset0:36 offset1:44
	s_nop 1
	ds_read2_b32 v[22:23], v30 offset0:101 offset1:109
	v_cvt_pk_bf16_f32 v8, v14, v12
	s_waitcnt lgkmcnt(3)
	s_nop 1
	s_waitcnt lgkmcnt(2)
	s_nop 0
	ds_read2_b32 v[24:25], v30 offset0:166 offset1:174
	s_nop 1
	ds_read2_b32 v[26:27], v30 offset0:231 offset1:239
	v_cvt_pk_bf16_f32 v9, v16, v18
	s_waitcnt lgkmcnt(3)
	s_nop 1
	s_waitcnt lgkmcnt(2)
	s_nop 2
	v_cvt_pk_bf16_f32 v10, v20, v22
	s_waitcnt lgkmcnt(1)
	s_nop 0
	v_add_u32_e32 v28, 32, v6
	s_nop 0
	s_waitcnt lgkmcnt(0)
	s_nop 0
	v_ashrrev_i32_e32 v29, 31, v28
	s_nop 1
	v_lshlrev_b64 v[28:29], 10, v[28:29]
	v_cvt_pk_bf16_f32 v11, v24, v26
	v_lshl_add_u64 v[28:29], v[4:5], 0, v[28:29]
	s_nop 0
	global_store_dwordx4 v[28:29], v[8:11], off
	s_nop 3
	v_cvt_pk_bf16_f32 v8, v15, v13
	s_nop 4
	v_cvt_pk_bf16_f32 v9, v17, v19
	s_nop 4
	v_cvt_pk_bf16_f32 v10, v21, v23
	s_nop 0
	v_add_u32_e32 v12, 40, v6
	s_nop 1
	v_ashrrev_i32_e32 v13, 31, v12
	s_nop 1
	v_lshlrev_b64 v[12:13], 10, v[12:13]
	v_cvt_pk_bf16_f32 v11, v25, v27
	ds_read2_b32 v[14:15], v78 offset0:48 offset1:56
	v_lshl_add_u64 v[12:13], v[4:5], 0, v[12:13]
	global_store_dwordx4 v[12:13], v[8:11], off
	ds_read2_b32 v[12:13], v78 offset0:113 offset1:121
	ds_read2_b32 v[16:17], v78 offset0:178 offset1:186
	ds_read2_b32 v[18:19], v78 offset0:243 offset1:251
	s_waitcnt lgkmcnt(3)
	s_nop 1
	s_waitcnt lgkmcnt(2)
	s_nop 0
	ds_read2_b32 v[20:21], v30 offset0:52 offset1:60
	s_nop 1
	ds_read2_b32 v[22:23], v30 offset0:117 offset1:125
	v_cvt_pk_bf16_f32 v8, v14, v12
	s_waitcnt lgkmcnt(3)
	s_nop 1
	s_waitcnt lgkmcnt(2)
	s_nop 0
	ds_read2_b32 v[24:25], v30 offset0:182 offset1:190
	s_nop 1
	ds_read2_b32 v[26:27], v30 offset0:247 offset1:255
	v_cvt_pk_bf16_f32 v9, v16, v18
	s_waitcnt lgkmcnt(3)
	s_nop 1
	s_waitcnt lgkmcnt(2)
	s_nop 2
	v_cvt_pk_bf16_f32 v10, v20, v22
	s_waitcnt lgkmcnt(1)
	s_nop 0
	v_add_u32_e32 v28, 48, v6
	s_nop 0
	s_waitcnt lgkmcnt(0)
	s_nop 0
	v_ashrrev_i32_e32 v29, 31, v28
	s_nop 1
	v_lshlrev_b64 v[28:29], 10, v[28:29]
	v_cvt_pk_bf16_f32 v11, v24, v26
	v_lshl_add_u64 v[28:29], v[4:5], 0, v[28:29]
	s_nop 0
	global_store_dwordx4 v[28:29], v[8:11], off
	s_nop 3
	v_cvt_pk_bf16_f32 v8, v15, v13
	s_nop 4
	v_cvt_pk_bf16_f32 v9, v17, v19
	s_nop 4
	v_cvt_pk_bf16_f32 v10, v21, v23
	s_nop 4
	v_add_u32_e32 v6, 56, v6
	v_cvt_pk_bf16_f32 v11, v25, v27
	v_ashrrev_i32_e32 v7, 31, v6
	v_lshlrev_b64 v[6:7], 10, v[6:7]
	v_lshl_add_u64 v[4:5], v[4:5], 0, v[6:7]
	global_store_dwordx4 v[4:5], v[8:11], off
	s_waitcnt lgkmcnt(0)
	s_add_i32 s11, s11, s86
	s_add_i32 s12, s12, s13
	s_cmpk_lt_i32 s11, 0x100
	s_cbranch_scc0 .LBB0_1588

; #define LAS __attribute__((address_space(3)))
; #define LDS_WAIT() asm volatile("s_waitcnt lgkmcnt(0)" ::: "memory")
;     ...
;     for (int it = gw0; it < items; it += ngw) {
;         const int kb = it / nblk, nb = it % nblk, k0 = 64 * kb, n0 = 64 * nb, nq = (lane & 15) * 4, kr = lane >> 4; const bool ok = (n0 + nq) < N;
;         f32x4 v[16];
; #pragma unroll
;         for (int i = 0; i < 16; ++i) v[i] = ok ? __builtin_nontemporal_load((const f32x4*)(W + (size_t)(k0 + 4 * i + kr) * N + n0 + nq)) : (f32x4){0.f, 0.f, 0.f, 0.f};
;         if (gain) {
; #pragma unroll
;             for (int i = 0; i < 16; ++i) v[i] *= gain[k0 + 4 * i + kr]; }
; #pragma unroll
;         for (int i = 0; i < 16; ++i) { LAS float* d = scr + (4 * i + kr) * 65 + nq; d[0] = v[i].x; d[1] = v[i].y; d[2] = v[i].z; d[3] = v[i].w; }
;         LDS_WAIT(); asm volatile("" ::: "memory");
;         const int c8 = lane & 7; int d0 = n0;
;         if (ffnmap) { const int bj = n0 >= FFH ? 1 : 0, chn = n0 - FFH * bj; d0 = 256 * (chn >> 7) + 128 * bj + (chn & 127); }
.LBB0_1649:
	s_or_b64 exec, exec, s[14:15]
	v_ashrrev_i32_e32 v73, 31, v72
	v_lshl_add_u64 v[114:115], v[72:73], 2, s[2:3]
	global_load_dword v72, v[114:115], off
	s_mulk_i32 s28, 0xff50
	s_add_i32 s13, s27, s28
	s_cmpk_gt_i32 s13, 0x57
	s_cselect_b32 s13, 0xffffea00, 0
	s_cselect_b32 s14, 0x80, 0
	s_add_i32 s13, s13, s22
	s_add_i32 s13, s13, s11
	s_lshl_b32 s11, s13, 1
	s_and_b32 s12, s12, 64
	s_and_b32 s11, s11, 0xffffff00
	s_or_b32 s12, s12, s14
	s_or_b32 s12, s12, s11
	s_ashr_i32 s11, s10, 31
	s_add_i32 s27, s27, s21
	s_add_i32 s22, s22, s23
	s_cmpk_lt_i32 s27, 0x1600
	s_waitcnt vmcnt(0)
	v_pk_mul_f32 v[100:101], v[4:5], v[72:73] op_sel_hi:[1,0]
	global_load_dword v4, v[114:115], off offset:16
	v_pk_mul_f32 v[98:99], v[6:7], v[72:73] op_sel_hi:[1,0]
	global_load_dword v6, v[114:115], off offset:128
	s_waitcnt vmcnt(1)
	v_pk_mul_f32 v[90:91], v[14:15], v[4:5] op_sel_hi:[1,0]
	v_pk_mul_f32 v[96:97], v[12:13], v[4:5] op_sel_hi:[1,0]
	global_load_dword v4, v[114:115], off offset:32
	global_load_dword v14, v[114:115], off offset:160
	s_waitcnt vmcnt(1)
	v_pk_mul_f32 v[86:87], v[10:11], v[4:5] op_sel_hi:[1,0]
	v_pk_mul_f32 v[92:93], v[8:9], v[4:5] op_sel_hi:[1,0]
	global_load_dword v4, v[114:115], off offset:48
	global_load_dword v10, v[114:115], off offset:144
	s_waitcnt vmcnt(2)
	v_pk_mul_f32 v[12:13], v[46:47], v[14:15] op_sel_hi:[1,0]
	v_pk_mul_f32 v[14:15], v[44:45], v[14:15] op_sel_hi:[1,0]
	s_waitcnt vmcnt(1)
	v_pk_mul_f32 v[82:83], v[22:23], v[4:5] op_sel_hi:[1,0]
	v_pk_mul_f32 v[88:89], v[20:21], v[4:5] op_sel_hi:[1,0]
	global_load_dword v4, v[114:115], off offset:64
	global_load_dword v22, v[114:115], off offset:192
	s_waitcnt vmcnt(1)
	v_pk_mul_f32 v[78:79], v[18:19], v[4:5] op_sel_hi:[1,0]
	v_pk_mul_f32 v[84:85], v[16:17], v[4:5] op_sel_hi:[1,0]
	global_load_dword v4, v[114:115], off offset:80
	global_load_dword v18, v[114:115], off offset:176
	s_waitcnt vmcnt(2)
	v_pk_mul_f32 v[20:21], v[54:55], v[22:23] op_sel_hi:[1,0]
	v_pk_mul_f32 v[22:23], v[52:53], v[22:23] op_sel_hi:[1,0]
	s_waitcnt vmcnt(1)
	v_pk_mul_f32 v[74:75], v[30:31], v[4:5] op_sel_hi:[1,0]
	v_pk_mul_f32 v[80:81], v[28:29], v[4:5] op_sel_hi:[1,0]
	global_load_dword v4, v[114:115], off offset:96
	global_load_dword v30, v[114:115], off offset:224
	s_waitcnt vmcnt(2)
	v_pk_mul_f32 v[16:17], v[58:59], v[18:19] op_sel_hi:[1,0]
	v_pk_mul_f32 v[18:19], v[56:57], v[18:19] op_sel_hi:[1,0]
	s_waitcnt vmcnt(1)
	v_pk_mul_f32 v[72:73], v[26:27], v[4:5] op_sel_hi:[1,0]
	v_pk_mul_f32 v[76:77], v[24:25], v[4:5] op_sel_hi:[1,0]
	global_load_dword v4, v[114:115], off offset:112
	global_load_dword v26, v[114:115], off offset:208
	s_waitcnt vmcnt(2)
	v_pk_mul_f32 v[28:29], v[62:63], v[30:31] op_sel_hi:[1,0]
	v_pk_mul_f32 v[30:31], v[60:61], v[30:31] op_sel_hi:[1,0]
	s_waitcnt vmcnt(1)
	v_pk_mul_f32 v[38:39], v[38:39], v[4:5] op_sel_hi:[1,0]
	v_pk_mul_f32 v[36:37], v[36:37], v[4:5] op_sel_hi:[1,0]
	v_pk_mul_f32 v[4:5], v[34:35], v[6:7] op_sel_hi:[1,0]
	v_pk_mul_f32 v[6:7], v[32:33], v[6:7] op_sel_hi:[1,0]
	v_lshl_add_u64 v[32:33], v[94:95], 2, s[2:3]
	global_load_dword v34, v[32:33], off
	ds_write2_b32 v112, v100, v101 offset1:1
	ds_write2_b32 v112, v98, v99 offset0:2 offset1:3
	v_pk_mul_f32 v[8:9], v[50:51], v[10:11] op_sel_hi:[1,0]
	v_pk_mul_f32 v[10:11], v[48:49], v[10:11] op_sel_hi:[1,0]
	s_waitcnt vmcnt(1)
	v_pk_mul_f32 v[24:25], v[66:67], v[26:27] op_sel_hi:[1,0]
	v_pk_mul_f32 v[26:27], v[64:65], v[26:27] op_sel_hi:[1,0]
	s_waitcnt vmcnt(0)
	v_pk_mul_f32 v[32:33], v[42:43], v[34:35] op_sel_hi:[1,0]
	v_pk_mul_f32 v[34:35], v[40:41], v[34:35] op_sel_hi:[1,0]
	v_add_u32_e32 v40, 0x410, v112
	ds_write2_b32 v40, v96, v97 offset1:1
	v_add_u32_e32 v40, 0x418, v112
	ds_write2_b32 v40, v90, v91 offset1:1
	v_add_u32_e32 v40, 0x820, v112
	ds_write2_b32 v40, v92, v93 offset1:1
	v_add_u32_e32 v40, 0x828, v112
	ds_write2_b32 v40, v86, v87 offset1:1
	v_add_u32_e32 v40, 0xc30, v112
	ds_write2_b32 v40, v88, v89 offset1:1
	v_add_u32_e32 v40, 0xc38, v112
	ds_write2_b32 v40, v82, v83 offset1:1
	v_add_u32_e32 v40, 0x1040, v112
	ds_write2_b32 v40, v84, v85 offset1:1
	v_add_u32_e32 v40, 0x1048, v112
	ds_write2_b32 v40, v78, v79 offset1:1
	v_add_u32_e32 v40, 0x1450, v112
	ds_write2_b32 v40, v80, v81 offset1:1
	v_add_u32_e32 v40, 0x1458, v112
	ds_write2_b32 v40, v74, v75 offset1:1
	v_add_u32_e32 v40, 0x1860, v112
	ds_write2_b32 v40, v76, v77 offset1:1
	v_add_u32_e32 v40, 0x1868, v112
	ds_write2_b32 v40, v72, v73 offset1:1
	v_add_u32_e32 v40, 0x1c70, v112
	ds_write2_b32 v40, v36, v37 offset1:1
	v_add_u32_e32 v36, 0x1c78, v112
	ds_write2_b32 v36, v38, v39 offset1:1
	v_add_u32_e32 v36, 0x2080, v112
	ds_write2_b32 v36, v6, v7 offset1:1
	v_add_u32_e32 v6, 0x2088, v112
	ds_write2_b32 v6, v4, v5 offset1:1
	v_add_u32_e32 v4, 0x2490, v112
	ds_write2_b32 v4, v10, v11 offset1:1
	v_add_u32_e32 v4, 0x2498, v112
	ds_write2_b32 v4, v8, v9 offset1:1
	v_add_u32_e32 v4, 0x28a0, v112
	ds_write2_b32 v4, v14, v15 offset1:1
	v_add_u32_e32 v4, 0x28a8, v112
	ds_write2_b32 v4, v12, v13 offset1:1
	v_add_u32_e32 v4, 0x2cb0, v112
	ds_write2_b32 v4, v18, v19 offset1:1
	v_add_u32_e32 v4, 0x2cb8, v112
	ds_write2_b32 v4, v16, v17 offset1:1
	v_add_u32_e32 v4, 0x30c0, v112
	ds_write2_b32 v4, v22, v23 offset1:1
	v_add_u32_e32 v4, 0x30c8, v112
	ds_write2_b32 v4, v20, v21 offset1:1
	v_add_u32_e32 v4, 0x34d0, v112
	ds_write2_b32 v4, v26, v27 offset1:1
	v_add_u32_e32 v4, 0x34d8, v112
	ds_write2_b32 v4, v24, v25 offset1:1
	v_add_u32_e32 v4, 0x38e0, v112
	ds_write2_b32 v4, v30, v31 offset1:1
	v_add_u32_e32 v4, 0x38e8, v112
	ds_write2_b32 v4, v28, v29 offset1:1
	v_add_u32_e32 v4, 0x3cf0, v112
	ds_write2_b32 v4, v34, v35 offset1:1
	v_add_u32_e32 v4, 0x3cf8, v112
	ds_write2_b32 v4, v32, v33 offset1:1
	s_waitcnt lgkmcnt(0)
; #define LAS __attribute__((address_space(3)))
; #define LDS_WAIT() asm volatile("s_waitcnt lgkmcnt(0)" ::: "memory")
; __device__ __forceinline__ unsigned pk2(float lo, float hi) { return f2bf(lo) | (f2bf(hi) << 16); }
;     ...
;     for (int it = gw0; it < items; it += ngw) {
;         const int kb = it / nblk, nb = it % nblk, k0 = 64 * kb, n0 = 64 * nb, nq = (lane & 15) * 4, kr = lane >> 4; const bool ok = (n0 + nq) < N;
;         f32x4 v[16];
; #pragma unroll
;         for (int i = 0; i < 16; ++i) v[i] = ok ? __builtin_nontemporal_load((const f32x4*)(W + (size_t)(k0 + 4 * i + kr) * N + n0 + nq)) : (f32x4){0.f, 0.f, 0.f, 0.f};
;         if (gain) {
; #pragma unroll
;             for (int i = 0; i < 16; ++i) v[i] *= gain[k0 + 4 * i + kr]; }
; #pragma unroll
;         for (int i = 0; i < 16; ++i) { LAS float* d = scr + (4 * i + kr) * 65 + nq; d[0] = v[i].x; d[1] = v[i].y; d[2] = v[i].z; d[3] = v[i].w; }
;         LDS_WAIT(); asm volatile("" ::: "memory");
;         const int c8 = lane & 7; int d0 = n0;
;         if (ffnmap) { const int bj = n0 >= FFH ? 1 : 0, chn = n0 - FFH * bj; d0 = 256 * (chn >> 7) + 128 * bj + (chn & 127); }
; #pragma unroll
;         for (int j = 0; j < 8; ++j) { const int n = (lane >> 3) + 8 * j; const LAS float* sp = scr + (8 * c8) * 65 + n;
;             v4u o; o.x = pk2(sp[0 * 65], sp[1 * 65]); o.y = pk2(sp[2 * 65], sp[3 * 65]); o.z = pk2(sp[4 * 65], sp[5 * 65]); o.w = pk2(sp[6 * 65], sp[7 * 65]);
;             *(v4u*)(WT + (size_t)(d0 + n) * K + k0 + 8 * c8) = o; }
;         LDS_WAIT(); asm volatile("" ::: "memory");
;     }
	ds_read2_b32 v[6:7], v104 offset0:65 offset1:73
	ds_read2_b32 v[12:13], v104 offset1:8
	ds_read2_b32 v[14:15], v104 offset0:130 offset1:138
	ds_read2_b32 v[16:17], v104 offset0:195 offset1:203
	v_or_b32_e32 v26, s12, v103
	v_ashrrev_i32_e32 v27, 31, v26
	s_waitcnt lgkmcnt(3)
	s_nop 0
	s_waitcnt lgkmcnt(2)
	s_nop 3
	v_cvt_pk_bf16_f32 v8, v12, v6
	s_waitcnt lgkmcnt(1)
	s_nop 1
	s_waitcnt lgkmcnt(0)
	s_nop 2
	v_cvt_pk_bf16_f32 v9, v14, v16
	v_add_u32_e32 v6, 0x400, v104
	ds_read2_b32 v[18:19], v6 offset0:4 offset1:12
	ds_read2_b32 v[20:21], v6 offset0:69 offset1:77
	ds_read2_b32 v[22:23], v6 offset0:134 offset1:142
	ds_read2_b32 v[24:25], v6 offset0:199 offset1:207
	v_lshl_add_u64 v[4:5], s[10:11], 1, v[70:71]
	v_lshlrev_b64 v[26:27], 12, v[26:27]
	s_waitcnt lgkmcnt(3)
	s_nop 1
	s_waitcnt lgkmcnt(2)
	s_nop 2
	v_cvt_pk_bf16_f32 v10, v18, v20
	s_waitcnt lgkmcnt(1)
	s_nop 1
	s_waitcnt lgkmcnt(0)
	s_nop 2
	v_cvt_pk_bf16_f32 v11, v22, v24
	v_lshl_add_u64 v[26:27], v[4:5], 0, v[26:27]
	global_store_dwordx4 v[26:27], v[8:11], off
	v_or_b32_e32 v12, s12, v105
	v_or_b32_e32 v28, s12, v106
	s_nop 4
	v_cvt_pk_bf16_f32 v8, v13, v7
	s_nop 4
	v_cvt_pk_bf16_f32 v9, v15, v17
	s_nop 4
	v_cvt_pk_bf16_f32 v10, v19, v21
	s_nop 2
	v_ashrrev_i32_e32 v13, 31, v12
	s_nop 1
	v_lshlrev_b64 v[12:13], 12, v[12:13]
	v_cvt_pk_bf16_f32 v11, v23, v25
	v_lshl_add_u64 v[12:13], v[4:5], 0, v[12:13]
	global_store_dwordx4 v[12:13], v[8:11], off
	ds_read2_b32 v[12:13], v104 offset0:81 offset1:89
	ds_read2_b32 v[14:15], v104 offset0:16 offset1:24
	ds_read2_b32 v[16:17], v104 offset0:146 offset1:154
	ds_read2_b32 v[18:19], v104 offset0:211 offset1:219
	ds_read2_b32 v[20:21], v6 offset0:20 offset1:28
	ds_read2_b32 v[22:23], v6 offset0:85 offset1:93
	ds_read2_b32 v[24:25], v6 offset0:150 offset1:158
	ds_read2_b32 v[26:27], v6 offset0:215 offset1:223
	s_waitcnt lgkmcnt(7)
	s_nop 0
	s_waitcnt lgkmcnt(6)
	s_nop 3
	v_cvt_pk_bf16_f32 v8, v14, v12
	s_waitcnt lgkmcnt(5)
	s_nop 1
	s_waitcnt lgkmcnt(4)
	s_nop 2
	v_cvt_pk_bf16_f32 v9, v16, v18
	s_waitcnt lgkmcnt(3)
	s_nop 1
	s_waitcnt lgkmcnt(2)
	s_nop 2
	v_cvt_pk_bf16_f32 v10, v20, v22
	s_waitcnt lgkmcnt(1)
	s_nop 1
	s_waitcnt lgkmcnt(0)
	s_nop 0
	v_ashrrev_i32_e32 v29, 31, v28
	s_nop 1
	v_lshlrev_b64 v[28:29], 12, v[28:29]
	v_cvt_pk_bf16_f32 v11, v24, v26
	v_lshl_add_u64 v[28:29], v[4:5], 0, v[28:29]
	s_nop 0
	global_store_dwordx4 v[28:29], v[8:11], off
	s_nop 3
	v_cvt_pk_bf16_f32 v8, v15, v13
	s_nop 4
	v_cvt_pk_bf16_f32 v9, v17, v19
	s_nop 4
	v_cvt_pk_bf16_f32 v10, v21, v23
	s_nop 0
	v_or_b32_e32 v12, s12, v107
	s_nop 1
	v_ashrrev_i32_e32 v13, 31, v12
	s_nop 1
	v_lshlrev_b64 v[12:13], 12, v[12:13]
	v_cvt_pk_bf16_f32 v11, v25, v27
	v_lshl_add_u64 v[12:13], v[4:5], 0, v[12:13]
	global_store_dwordx4 v[12:13], v[8:11], off
	ds_read2_b32 v[12:13], v104 offset0:97 offset1:105
	ds_read2_b32 v[14:15], v104 offset0:32 offset1:40
	ds_read2_b32 v[16:17], v104 offset0:162 offset1:170
	ds_read2_b32 v[18:19], v104 offset0:227 offset1:235
	ds_read2_b32 v[20:21], v6 offset0:36 offset1:44
	ds_read2_b32 v[22:23], v6 offset0:101 offset1:109
	ds_read2_b32 v[24:25], v6 offset0:166 offset1:174
	ds_read2_b32 v[26:27], v6 offset0:231 offset1:239
	s_waitcnt lgkmcnt(7)
	s_nop 0
	s_waitcnt lgkmcnt(6)
	s_nop 3
	v_cvt_pk_bf16_f32 v8, v14, v12
	s_waitcnt lgkmcnt(5)
	s_nop 1
	s_waitcnt lgkmcnt(4)
	s_nop 2
	v_cvt_pk_bf16_f32 v9, v16, v18
	s_waitcnt lgkmcnt(3)
	s_nop 1
	s_waitcnt lgkmcnt(2)
	s_nop 2
	v_cvt_pk_bf16_f32 v10, v20, v22
	s_waitcnt lgkmcnt(1)
	s_nop 0
	v_or_b32_e32 v28, s12, v108
	s_nop 0
	s_waitcnt lgkmcnt(0)
	s_nop 0
	v_ashrrev_i32_e32 v29, 31, v28
	s_nop 1
	v_lshlrev_b64 v[28:29], 12, v[28:29]
	v_cvt_pk_bf16_f32 v11, v24, v26
	v_lshl_add_u64 v[28:29], v[4:5], 0, v[28:29]
	s_nop 0
	global_store_dwordx4 v[28:29], v[8:11], off
	s_nop 3
	v_cvt_pk_bf16_f32 v8, v15, v13
	s_nop 4
	v_cvt_pk_bf16_f32 v9, v17, v19
	s_nop 4
	v_cvt_pk_bf16_f32 v10, v21, v23
	s_nop 0
	v_or_b32_e32 v12, s12, v109
	s_nop 1
	v_ashrrev_i32_e32 v13, 31, v12
	s_nop 1
	v_lshlrev_b64 v[12:13], 12, v[12:13]
	v_cvt_pk_bf16_f32 v11, v25, v27
	v_lshl_add_u64 v[12:13], v[4:5], 0, v[12:13]
	global_store_dwordx4 v[12:13], v[8:11], off
	ds_read2_b32 v[12:13], v104 offset0:48 offset1:56
	ds_read2_b32 v[14:15], v104 offset0:113 offset1:121
	ds_read2_b32 v[16:17], v104 offset0:178 offset1:186
	ds_read2_b32 v[18:19], v104 offset0:243 offset1:251
	ds_read2_b32 v[20:21], v6 offset0:52 offset1:60
	ds_read2_b32 v[22:23], v6 offset0:117 offset1:125
	ds_read2_b32 v[24:25], v6 offset0:182 offset1:190
	ds_read2_b32 v[26:27], v6 offset0:247 offset1:255
	s_waitcnt lgkmcnt(7)
	s_nop 1
	s_waitcnt lgkmcnt(6)
	s_nop 2
	v_cvt_pk_bf16_f32 v8, v12, v14
	s_waitcnt lgkmcnt(5)
	s_nop 1
	s_waitcnt lgkmcnt(4)
	s_nop 2
	v_cvt_pk_bf16_f32 v9, v16, v18
	s_waitcnt lgkmcnt(3)
	s_nop 1
	s_waitcnt lgkmcnt(2)
	s_nop 2
	s_waitcnt lgkmcnt(1)
	s_nop 0
	v_cvt_pk_bf16_f32 v10, v20, v22
	s_nop 0
	s_waitcnt lgkmcnt(0)
	s_nop 2
	v_cvt_pk_bf16_f32 v11, v24, v26
	v_or_b32_e32 v6, s12, v110
	v_ashrrev_i32_e32 v7, 31, v6
	v_lshlrev_b64 v[6:7], 12, v[6:7]
	v_lshl_add_u64 v[6:7], v[4:5], 0, v[6:7]
	global_store_dwordx4 v[6:7], v[8:11], off
	s_nop 4
	v_cvt_pk_bf16_f32 v6, v13, v15
	s_nop 4
	v_cvt_pk_bf16_f32 v7, v17, v19
	s_nop 4
	v_cvt_pk_bf16_f32 v8, v21, v23
	s_nop 4
	v_cvt_pk_bf16_f32 v9, v25, v27
	v_or_b32_e32 v10, s12, v111
	v_ashrrev_i32_e32 v11, 31, v10
	v_lshlrev_b64 v[10:11], 12, v[10:11]
	v_lshl_add_u64 v[4:5], v[4:5], 0, v[10:11]
	global_store_dwordx4 v[4:5], v[6:9], off
	s_waitcnt lgkmcnt(0)
	s_cbranch_scc0 .LBB0_1682

; #define LAS __attribute__((address_space(3)))
; #define LDS_WAIT() asm volatile("s_waitcnt lgkmcnt(0)" ::: "memory")
; __device__ __forceinline__ unsigned pk2(float lo, float hi) { return f2bf(lo) | (f2bf(hi) << 16); }
;     ...
;     for (int it = gw0; it < items; it += ngw) {
;         const int kb = it / nblk, nb = it % nblk, k0 = 64 * kb, n0 = 64 * nb, nq = (lane & 15) * 4, kr = lane >> 4; const bool ok = (n0 + nq) < N;
;         f32x4 v[16];
; #pragma unroll
;         for (int i = 0; i < 16; ++i) v[i] = ok ? __builtin_nontemporal_load((const f32x4*)(W + (size_t)(k0 + 4 * i + kr) * N + n0 + nq)) : (f32x4){0.f, 0.f, 0.f, 0.f};
;         if (gain) {
; #pragma unroll
;             for (int i = 0; i < 16; ++i) v[i] *= gain[k0 + 4 * i + kr]; }
; #pragma unroll
;         for (int i = 0; i < 16; ++i) { LAS float* d = scr + (4 * i + kr) * 65 + nq; d[0] = v[i].x; d[1] = v[i].y; d[2] = v[i].z; d[3] = v[i].w; }
;         LDS_WAIT(); asm volatile("" ::: "memory");
;         const int c8 = lane & 7; int d0 = n0;
;         if (ffnmap) { const int bj = n0 >= FFH ? 1 : 0, chn = n0 - FFH * bj; d0 = 256 * (chn >> 7) + 128 * bj + (chn & 127); }
; #pragma unroll
;         for (int j = 0; j < 8; ++j) { const int n = (lane >> 3) + 8 * j; const LAS float* sp = scr + (8 * c8) * 65 + n;
;             v4u o; o.x = pk2(sp[0 * 65], sp[1 * 65]); o.y = pk2(sp[2 * 65], sp[3 * 65]); o.z = pk2(sp[4 * 65], sp[5 * 65]); o.w = pk2(sp[6 * 65], sp[7 * 65]);
;             *(v4u*)(WT + (size_t)(d0 + n) * K + k0 + 8 * c8) = o; }
;         LDS_WAIT(); asm volatile("" ::: "memory");
;     }
.LBB0_1684:
	s_or_b64 exec, exec, s[10:11]
	s_waitcnt vmcnt(0)
	ds_write2_b32 v79, v4, v5 offset1:1
	ds_write2_b32 v79, v6, v7 offset0:2 offset1:3
	v_add_u32_e32 v4, 0x410, v79
	ds_write2_b32 v4, v12, v13 offset1:1
	v_add_u32_e32 v4, 0x418, v79
	ds_write2_b32 v4, v14, v15 offset1:1
	v_add_u32_e32 v4, 0x820, v79
	ds_write2_b32 v4, v8, v9 offset1:1
	v_add_u32_e32 v4, 0x828, v79
	ds_write2_b32 v4, v10, v11 offset1:1
	v_add_u32_e32 v4, 0xc30, v79
	ds_write2_b32 v4, v20, v21 offset1:1
	v_add_u32_e32 v4, 0xc38, v79
	ds_write2_b32 v4, v22, v23 offset1:1
	v_add_u32_e32 v4, 0x1040, v79
	ds_write2_b32 v4, v16, v17 offset1:1
	v_add_u32_e32 v4, 0x1048, v79
	ds_write2_b32 v4, v18, v19 offset1:1
	v_add_u32_e32 v4, 0x1450, v79
	ds_write2_b32 v4, v28, v29 offset1:1
	v_add_u32_e32 v4, 0x1458, v79
	ds_write2_b32 v4, v30, v31 offset1:1
	v_add_u32_e32 v4, 0x1860, v79
	ds_write2_b32 v4, v24, v25 offset1:1
	v_add_u32_e32 v4, 0x1868, v79
	ds_write2_b32 v4, v26, v27 offset1:1
	v_add_u32_e32 v4, 0x1c70, v79
	ds_write2_b32 v4, v36, v37 offset1:1
	v_add_u32_e32 v4, 0x1c78, v79
	ds_write2_b32 v4, v38, v39 offset1:1
	v_add_u32_e32 v4, 0x2080, v79
	ds_write2_b32 v4, v32, v33 offset1:1
	v_add_u32_e32 v4, 0x2088, v79
	ds_write2_b32 v4, v34, v35 offset1:1
	v_add_u32_e32 v4, 0x2490, v79
	ds_write2_b32 v4, v44, v45 offset1:1
	v_add_u32_e32 v4, 0x2498, v79
	ds_write2_b32 v4, v46, v47 offset1:1
	v_add_u32_e32 v4, 0x28a0, v79
	ds_write2_b32 v4, v40, v41 offset1:1
	v_add_u32_e32 v4, 0x28a8, v79
	ds_write2_b32 v4, v42, v43 offset1:1
	v_add_u32_e32 v4, 0x2cb0, v79
	ds_write2_b32 v4, v52, v53 offset1:1
	v_add_u32_e32 v4, 0x2cb8, v79
	ds_write2_b32 v4, v54, v55 offset1:1
	v_add_u32_e32 v4, 0x30c0, v79
	ds_write2_b32 v4, v48, v49 offset1:1
	v_add_u32_e32 v4, 0x30c8, v79
	ds_write2_b32 v4, v50, v51 offset1:1
	v_add_u32_e32 v4, 0x34d0, v79
	ds_write2_b32 v4, v60, v61 offset1:1
	v_add_u32_e32 v4, 0x34d8, v79
	ds_write2_b32 v4, v62, v63 offset1:1
	v_add_u32_e32 v4, 0x38e0, v79
	ds_write2_b32 v4, v56, v57 offset1:1
	v_add_u32_e32 v4, 0x38e8, v79
	ds_write2_b32 v4, v58, v59 offset1:1
	v_add_u32_e32 v4, 0x3cf0, v79
	ds_write2_b32 v4, v64, v65 offset1:1
	v_add_u32_e32 v4, 0x3cf8, v79
	ds_write2_b32 v4, v66, v67 offset1:1
	s_waitcnt lgkmcnt(0)
	ds_read2_b32 v[12:13], v77 offset1:8
	ds_read2_b32 v[14:15], v77 offset0:65 offset1:73
	ds_read2_b32 v[16:17], v77 offset0:130 offset1:138
	ds_read2_b32 v[18:19], v77 offset0:195 offset1:203
	v_add_u32_e32 v30, 0x400, v77
	s_waitcnt lgkmcnt(3)
	s_nop 1
	s_waitcnt lgkmcnt(2)
	s_nop 0
	ds_read2_b32 v[20:21], v30 offset0:4 offset1:12
	s_nop 1
	ds_read2_b32 v[22:23], v30 offset0:69 offset1:77
	v_cvt_pk_bf16_f32 v8, v12, v14
	s_waitcnt lgkmcnt(3)
	s_nop 1
	s_waitcnt lgkmcnt(2)
	s_nop 0
	ds_read2_b32 v[24:25], v30 offset0:134 offset1:142
	s_nop 1
	ds_read2_b32 v[26:27], v30 offset0:199 offset1:207
	v_cvt_pk_bf16_f32 v9, v16, v18
	s_waitcnt lgkmcnt(3)
	s_nop 1
	s_waitcnt lgkmcnt(2)
	s_nop 2
	v_cvt_pk_bf16_f32 v10, v20, v22
	s_waitcnt lgkmcnt(1)
	s_nop 1
	s_waitcnt lgkmcnt(0)
	s_nop 2
	s_mul_i32 s22, s22, 0xfea00000
	s_ashr_i32 s3, s2, 31
	v_cvt_pk_bf16_f32 v11, v24, v26
	v_add_u32_e32 v6, s22, v78
	v_lshl_add_u64 v[4:5], s[2:3], 1, v[70:71]
	v_ashrrev_i32_e32 v7, 31, v6
	v_lshl_add_u64 v[28:29], v[4:5], 0, v[6:7]
	s_nop 0
	global_store_dwordx4 v[28:29], v[8:11], off
	s_nop 3
	v_cvt_pk_bf16_f32 v8, v13, v15
	s_nop 4
	v_cvt_pk_bf16_f32 v9, v17, v19
	s_nop 4
	v_cvt_pk_bf16_f32 v10, v21, v23
	s_nop 2
	v_add_u32_e32 v12, 0x16000, v6
	s_nop 1
	v_ashrrev_i32_e32 v13, 31, v12
	v_cvt_pk_bf16_f32 v11, v25, v27
	ds_read2_b32 v[14:15], v77 offset0:16 offset1:24
	v_lshl_add_u64 v[12:13], v[4:5], 0, v[12:13]
	global_store_dwordx4 v[12:13], v[8:11], off
	ds_read2_b32 v[12:13], v77 offset0:81 offset1:89
	ds_read2_b32 v[16:17], v77 offset0:146 offset1:154
	ds_read2_b32 v[18:19], v77 offset0:211 offset1:219
	s_waitcnt lgkmcnt(3)
; #define LAS __attribute__((address_space(3)))
; #define LDS_WAIT() asm volatile("s_waitcnt lgkmcnt(0)" ::: "memory")
; __device__ __forceinline__ unsigned pk2(float lo, float hi) { return f2bf(lo) | (f2bf(hi) << 16); }
;     ...
;     for (int it = gw0; it < items; it += ngw) {
;         const int kb = it / nblk, nb = it % nblk, k0 = 64 * kb, n0 = 64 * nb, nq = (lane & 15) * 4, kr = lane >> 4; const bool ok = (n0 + nq) < N;
;         f32x4 v[16];
; #pragma unroll
;         for (int i = 0; i < 16; ++i) v[i] = ok ? __builtin_nontemporal_load((const f32x4*)(W + (size_t)(k0 + 4 * i + kr) * N + n0 + nq)) : (f32x4){0.f, 0.f, 0.f, 0.f};
;         if (gain) {
; #pragma unroll
;             for (int i = 0; i < 16; ++i) v[i] *= gain[k0 + 4 * i + kr]; }
; #pragma unroll
;         for (int i = 0; i < 16; ++i) { LAS float* d = scr + (4 * i + kr) * 65 + nq; d[0] = v[i].x; d[1] = v[i].y; d[2] = v[i].z; d[3] = v[i].w; }
;         LDS_WAIT(); asm volatile("" ::: "memory");
;         const int c8 = lane & 7; int d0 = n0;
;         if (ffnmap) { const int bj = n0 >= FFH ? 1 : 0, chn = n0 - FFH * bj; d0 = 256 * (chn >> 7) + 128 * bj + (chn & 127); }
; #pragma unroll
;         for (int j = 0; j < 8; ++j) { const int n = (lane >> 3) + 8 * j; const LAS float* sp = scr + (8 * c8) * 65 + n;
;             v4u o; o.x = pk2(sp[0 * 65], sp[1 * 65]); o.y = pk2(sp[2 * 65], sp[3 * 65]); o.z = pk2(sp[4 * 65], sp[5 * 65]); o.w = pk2(sp[6 * 65], sp[7 * 65]);
;             *(v4u*)(WT + (size_t)(d0 + n) * K + k0 + 8 * c8) = o; }
;         LDS_WAIT(); asm volatile("" ::: "memory");
;     }
	s_nop 1
	s_waitcnt lgkmcnt(2)
	s_nop 0
	ds_read2_b32 v[20:21], v30 offset0:20 offset1:28
	s_nop 1
	ds_read2_b32 v[22:23], v30 offset0:85 offset1:93
	v_cvt_pk_bf16_f32 v8, v14, v12
	s_waitcnt lgkmcnt(3)
	s_nop 1
	s_waitcnt lgkmcnt(2)
	s_nop 0
	ds_read2_b32 v[24:25], v30 offset0:150 offset1:158
	s_nop 1
	ds_read2_b32 v[26:27], v30 offset0:215 offset1:223
	v_cvt_pk_bf16_f32 v9, v16, v18
	s_waitcnt lgkmcnt(3)
	s_nop 1
	s_waitcnt lgkmcnt(2)
	s_nop 2
	v_cvt_pk_bf16_f32 v10, v20, v22
	s_waitcnt lgkmcnt(1)
	s_nop 1
	s_waitcnt lgkmcnt(0)
	s_nop 0
	v_add_u32_e32 v28, 0x2c000, v6
	s_nop 1
	v_ashrrev_i32_e32 v29, 31, v28
	v_cvt_pk_bf16_f32 v11, v24, v26
	v_lshl_add_u64 v[28:29], v[4:5], 0, v[28:29]
	s_nop 0
	global_store_dwordx4 v[28:29], v[8:11], off
	s_nop 3
	v_cvt_pk_bf16_f32 v8, v15, v13
	s_nop 4
	v_cvt_pk_bf16_f32 v9, v17, v19
	s_nop 4
	v_cvt_pk_bf16_f32 v10, v21, v23
	s_nop 2
	v_add_u32_e32 v12, 0x42000, v6
	s_nop 1
	v_ashrrev_i32_e32 v13, 31, v12
	v_cvt_pk_bf16_f32 v11, v25, v27
	ds_read2_b32 v[14:15], v77 offset0:32 offset1:40
	v_lshl_add_u64 v[12:13], v[4:5], 0, v[12:13]
	global_store_dwordx4 v[12:13], v[8:11], off
	ds_read2_b32 v[12:13], v77 offset0:97 offset1:105
	ds_read2_b32 v[16:17], v77 offset0:162 offset1:170
	ds_read2_b32 v[18:19], v77 offset0:227 offset1:235
	s_waitcnt lgkmcnt(3)
	s_nop 1
	s_waitcnt lgkmcnt(2)
	s_nop 0
	ds_read2_b32 v[20:21], v30 offset0:36 offset1:44
	s_nop 1
	ds_read2_b32 v[22:23], v30 offset0:101 offset1:109
	v_cvt_pk_bf16_f32 v8, v14, v12
	s_waitcnt lgkmcnt(3)
	s_nop 1
	s_waitcnt lgkmcnt(2)
	s_nop 0
	ds_read2_b32 v[24:25], v30 offset0:166 offset1:174
	s_nop 1
	ds_read2_b32 v[26:27], v30 offset0:231 offset1:239
	v_cvt_pk_bf16_f32 v9, v16, v18
	s_waitcnt lgkmcnt(3)
	s_nop 1
	s_waitcnt lgkmcnt(2)
	s_nop 2
	v_cvt_pk_bf16_f32 v10, v20, v22
	s_waitcnt lgkmcnt(1)
	s_nop 1
	s_waitcnt lgkmcnt(0)
	s_nop 0
	v_add_u32_e32 v28, 0x58000, v6
	s_nop 1
	v_ashrrev_i32_e32 v29, 31, v28
	v_cvt_pk_bf16_f32 v11, v24, v26
	v_lshl_add_u64 v[28:29], v[4:5], 0, v[28:29]
	s_nop 0
	global_store_dwordx4 v[28:29], v[8:11], off
	s_nop 3
	v_cvt_pk_bf16_f32 v8, v15, v13
	s_nop 4
	v_cvt_pk_bf16_f32 v9, v17, v19
	s_nop 4
	v_cvt_pk_bf16_f32 v10, v21, v23
	s_nop 2
	v_add_u32_e32 v12, 0x6e000, v6
	s_nop 1
	v_ashrrev_i32_e32 v13, 31, v12
	v_cvt_pk_bf16_f32 v11, v25, v27
	ds_read2_b32 v[14:15], v77 offset0:48 offset1:56
	v_lshl_add_u64 v[12:13], v[4:5], 0, v[12:13]
	global_store_dwordx4 v[12:13], v[8:11], off
	ds_read2_b32 v[12:13], v77 offset0:113 offset1:121
	ds_read2_b32 v[16:17], v77 offset0:178 offset1:186
	ds_read2_b32 v[18:19], v77 offset0:243 offset1:251
	s_waitcnt lgkmcnt(3)
	s_nop 1
	s_waitcnt lgkmcnt(2)
	s_nop 0
	ds_read2_b32 v[20:21], v30 offset0:52 offset1:60
	s_nop 1
	ds_read2_b32 v[22:23], v30 offset0:117 offset1:125
	v_cvt_pk_bf16_f32 v8, v14, v12
	s_waitcnt lgkmcnt(3)
	s_nop 1
	s_waitcnt lgkmcnt(2)
	s_nop 0
	ds_read2_b32 v[24:25], v30 offset0:182 offset1:190
	s_nop 1
	ds_read2_b32 v[26:27], v30 offset0:247 offset1:255
	v_cvt_pk_bf16_f32 v9, v16, v18
	s_waitcnt lgkmcnt(3)
	s_nop 1
	s_waitcnt lgkmcnt(2)
	s_nop 2
	v_cvt_pk_bf16_f32 v10, v20, v22
	s_waitcnt lgkmcnt(1)
	s_nop 1
	s_waitcnt lgkmcnt(0)
	s_nop 0
	v_add_u32_e32 v28, 0x84000, v6
	s_nop 1
	v_ashrrev_i32_e32 v29, 31, v28
	v_cvt_pk_bf16_f32 v11, v24, v26
	v_lshl_add_u64 v[28:29], v[4:5], 0, v[28:29]
	s_nop 0
	global_store_dwordx4 v[28:29], v[8:11], off
	s_nop 3
	v_cvt_pk_bf16_f32 v8, v15, v13
	s_nop 4
	v_cvt_pk_bf16_f32 v9, v17, v19
	s_nop 4
	v_cvt_pk_bf16_f32 v10, v21, v23
	s_nop 4
	v_add_u32_e32 v6, 0x9a000, v6
	v_cvt_pk_bf16_f32 v11, v25, v27
	v_ashrrev_i32_e32 v7, 31, v6
	v_lshl_add_u64 v[4:5], v[4:5], 0, v[6:7]
	global_store_dwordx4 v[4:5], v[8:11], off
	s_waitcnt lgkmcnt(0)
	s_add_i32 s20, s20, s21
	s_add_i32 s12, s12, s13
	s_mul_i32 s2, s21, 0xb0000
	s_cmpk_lt_i32 s20, 0xb00
	v_add_u32_e32 v78, s2, v78
	s_cbranch_scc0 .LBB0_1717

; __device__ __forceinline__ unsigned pk2(float lo, float hi) { return f2bf(lo) | (f2bf(hi) << 16); }
; __device__ __forceinline__ float gelu_tanh(float x) { return x * __builtin_amdgcn_rcpf(1.f + __builtin_amdgcn_exp2f(x * __builtin_fmaf(-1.029432396e-01f, x * x, -2.302208198e+00f))); }
;     __device__ __forceinline__ const char* pb(const Unit& u) const { return (const char*)(Bt + (size_t)u.pn * b_tile_stride); }
; __device__ __forceinline__ void nsa_hidreduce(const Ctx& c, const float* HIDP, const float* pb, bf16* HID) {
;     for (int it = c.vcu * 512 + c.tid; it < 8192 * 32; it += c.G * 512) {
;         const int r = it >> 5, h0 = (it & 31) * 8, ten = r >> 12; const float* hrow = HIDP + (size_t)r * 2048 + h0;
;         f32x4 a0 = *(const f32x4*)(pb + ten * 256 + h0), a1 = *(const f32x4*)(pb + ten * 256 + h0 + 4);
; #pragma unroll
;         for (int sp = 0; sp < 8; ++sp) { a0 += *(const f32x4*)(hrow + sp * 256); a1 += *(const f32x4*)(hrow + sp * 256 + 4); }
;         v4u o; o.x = pk2(gelu_tanh(a0.x), gelu_tanh(a0.y)); o.y = pk2(gelu_tanh(a0.z), gelu_tanh(a0.w)); o.z = pk2(gelu_tanh(a1.x), gelu_tanh(a1.y)); o.w = pk2(gelu_tanh(a1.z), gelu_tanh(a1.w));
;         *(v4u*)(HID + (size_t)r * 256 + h0) = o;
;     }
.LBB0_2023:
	v_ashrrev_i32_e32 v26, 5, v8
	v_ashrrev_i32_e32 v27, 31, v26
	v_and_b32_e32 v9, 0xf8, v6
	v_lshlrev_b64 v[10:11], 13, v[26:27]
	v_lshl_add_u64 v[10:11], s[78:79], 0, v[10:11]
	v_lshlrev_b32_e32 v4, 2, v9
	v_lshl_add_u64 v[28:29], v[10:11], 0, v[4:5]
	v_ashrrev_i32_e32 v10, 9, v8
	v_and_b32_e32 v10, 0xffffff00, v10
	v_ashrrev_i32_e32 v11, 31, v10
	v_lshl_add_u64 v[10:11], v[10:11], 2, s[8:9]
	v_lshl_add_u64 v[14:15], v[10:11], 0, v[4:5]
	global_load_dwordx4 v[10:13], v[14:15], off offset:16
	s_nop 0
	global_load_dwordx4 v[14:17], v[14:15], off
	s_nop 0
	global_load_dwordx4 v[18:21], v[28:29], off offset:16
	global_load_dwordx4 v[22:25], v[28:29], off
	s_mov_b64 s[24:25], 0x1000
	v_add_u32_e32 v8, s12, v8
	v_add_u32_e32 v6, s13, v6
	s_waitcnt vmcnt(0)
	v_pk_add_f32 v[20:21], v[12:13], v[20:21]
	v_pk_add_f32 v[24:25], v[16:17], v[24:25]
	v_pk_add_f32 v[22:23], v[14:15], v[22:23]
	v_pk_add_f32 v[18:19], v[10:11], v[18:19]
	global_load_dwordx4 v[10:13], v[28:29], off offset:1040
	global_load_dwordx4 v[14:17], v[28:29], off offset:1024
	s_waitcnt vmcnt(0)
	v_pk_add_f32 v[20:21], v[20:21], v[12:13]
	v_pk_add_f32 v[24:25], v[24:25], v[16:17]
	v_pk_add_f32 v[22:23], v[22:23], v[14:15]
	v_pk_add_f32 v[18:19], v[18:19], v[10:11]
	global_load_dwordx4 v[10:13], v[28:29], off offset:2064
	global_load_dwordx4 v[14:17], v[28:29], off offset:2048
	s_waitcnt vmcnt(0)
	v_pk_add_f32 v[20:21], v[20:21], v[12:13]
	v_pk_add_f32 v[24:25], v[24:25], v[16:17]
	v_pk_add_f32 v[22:23], v[22:23], v[14:15]
	v_pk_add_f32 v[18:19], v[18:19], v[10:11]
	global_load_dwordx4 v[10:13], v[28:29], off offset:3088
	global_load_dwordx4 v[14:17], v[28:29], off offset:3072
	s_waitcnt vmcnt(0)
	v_pk_add_f32 v[20:21], v[20:21], v[12:13]
	v_pk_add_f32 v[22:23], v[22:23], v[14:15]
	v_lshl_add_u64 v[14:15], v[28:29], 0, s[24:25]
	s_movk_i32 s24, 0x1000
	v_add_co_u32_e32 v30, vcc, s24, v28
	v_pk_add_f32 v[24:25], v[24:25], v[16:17]
	s_nop 0
	v_addc_co_u32_e32 v31, vcc, 0, v29, vcc
	v_pk_add_f32 v[18:19], v[18:19], v[10:11]
	global_load_dwordx4 v[10:13], v[30:31], off
	s_nop 0
	global_load_dwordx4 v[14:17], v[14:15], off offset:16
	s_mov_b64 s[24:25], 0x1400
	s_waitcnt vmcnt(0)
	v_pk_add_f32 v[24:25], v[24:25], v[12:13]
	v_pk_add_f32 v[18:19], v[18:19], v[14:15]
	v_lshl_add_u64 v[14:15], v[28:29], 0, s[24:25]
	v_pk_add_f32 v[22:23], v[22:23], v[10:11]
	v_pk_add_f32 v[20:21], v[20:21], v[16:17]
	global_load_dwordx4 v[10:13], v[30:31], off offset:1024
	s_nop 0
	global_load_dwordx4 v[14:17], v[14:15], off offset:16
	s_mov_b64 s[24:25], 0x1800
	s_waitcnt vmcnt(0)
	v_pk_add_f32 v[24:25], v[24:25], v[12:13]
	v_pk_add_f32 v[18:19], v[18:19], v[14:15]
	v_lshl_add_u64 v[14:15], v[28:29], 0, s[24:25]
	v_pk_add_f32 v[22:23], v[22:23], v[10:11]
	v_pk_add_f32 v[20:21], v[20:21], v[16:17]
	global_load_dwordx4 v[10:13], v[30:31], off offset:2048
	s_nop 0
	global_load_dwordx4 v[14:17], v[14:15], off offset:16
	s_mov_b64 s[24:25], 0x1c00
	s_waitcnt vmcnt(0)
	v_pk_add_f32 v[24:25], v[24:25], v[12:13]
	v_pk_add_f32 v[18:19], v[18:19], v[14:15]
	v_lshl_add_u64 v[14:15], v[28:29], 0, s[24:25]
	v_pk_add_f32 v[22:23], v[22:23], v[10:11]
	v_pk_add_f32 v[20:21], v[20:21], v[16:17]
	global_load_dwordx4 v[10:13], v[30:31], off offset:3072
	s_nop 0
	global_load_dwordx4 v[14:17], v[14:15], off offset:16
	s_mov_b32 s24, 0x3ffff
	v_cmp_lt_i32_e32 vcc, s24, v8
	s_or_b64 s[10:11], vcc, s[10:11]
	s_waitcnt vmcnt(0)
	v_pk_add_f32 v[10:11], v[22:23], v[10:11]
	s_nop 0
	v_mul_f32_e32 v4, v10, v10
	v_fmamk_f32 v4, v4, 0xbdd2d3e8, v7
	v_mul_f32_e32 v4, v10, v4
	v_exp_f32_e32 v4, v4
	v_pk_add_f32 v[14:15], v[18:19], v[14:15]
	v_pk_add_f32 v[12:13], v[24:25], v[12:13]
	v_pk_add_f32 v[16:17], v[20:21], v[16:17]
	v_add_f32_e32 v4, 1.0, v4
	v_rcp_f32_e32 v18, v4
	v_mul_f32_e32 v4, v11, v11
	v_fmamk_f32 v4, v4, 0xbdd2d3e8, v7
	v_mul_f32_e32 v4, v11, v4
	v_exp_f32_e32 v4, v4
	v_mov_b32_e32 v23, v12
	v_mov_b32_e32 v22, v10
	v_add_f32_e32 v4, 1.0, v4
	v_rcp_f32_e32 v20, v4
	v_mul_f32_e32 v4, v12, v12
	v_fmamk_f32 v4, v4, 0xbdd2d3e8, v7
	v_mul_f32_e32 v4, v12, v4
	v_exp_f32_e32 v4, v4
	v_mov_b32_e32 v12, v11
	v_add_f32_e32 v4, 1.0, v4
	v_rcp_f32_e32 v19, v4
	v_mul_f32_e32 v4, v13, v13
	v_fmamk_f32 v4, v4, 0xbdd2d3e8, v7
	v_mul_f32_e32 v4, v13, v4
	v_exp_f32_e32 v4, v4
	v_pk_mul_f32 v[18:19], v[22:23], v[18:19]
	v_mov_b32_e32 v23, v16
	v_mov_b32_e32 v22, v14
	v_add_f32_e32 v4, 1.0, v4
	v_rcp_f32_e32 v21, v4
	v_mul_f32_e32 v4, v14, v14
	v_fmamk_f32 v4, v4, 0xbdd2d3e8, v7
	v_mul_f32_e32 v4, v14, v4
	v_exp_f32_e32 v4, v4
	v_pk_mul_f32 v[10:11], v[12:13], v[20:21]
	v_add_f32_e32 v4, 1.0, v4
	v_rcp_f32_e32 v12, v4
	v_mul_f32_e32 v4, v15, v15
	v_fmamk_f32 v4, v4, 0xbdd2d3e8, v7
	v_mul_f32_e32 v4, v15, v4
	v_exp_f32_e32 v4, v4
	s_nop 0
	v_add_f32_e32 v4, 1.0, v4
	v_rcp_f32_e32 v20, v4
	v_mul_f32_e32 v4, v16, v16
	v_fmamk_f32 v4, v4, 0xbdd2d3e8, v7
	v_mul_f32_e32 v4, v16, v4
	v_exp_f32_e32 v4, v4
	v_mov_b32_e32 v16, v15
	v_add_f32_e32 v4, 1.0, v4
	v_rcp_f32_e32 v13, v4
	v_mul_f32_e32 v4, v17, v17
	v_fmamk_f32 v4, v4, 0xbdd2d3e8, v7
	v_mul_f32_e32 v4, v17, v4
	v_exp_f32_e32 v4, v4
	v_pk_mul_f32 v[12:13], v[22:23], v[12:13]
	v_add_f32_e32 v4, 1.0, v4
	v_rcp_f32_e32 v21, v4
	v_bfe_u32 v4, v11, 16, 1
	v_add3_u32 v4, v11, v4, s14
	s_nop 0
	v_pk_mul_f32 v[14:15], v[16:17], v[20:21]
	s_nop 7
	v_bfe_u32 v16, v19, 16, 1
	s_nop 1
	v_add3_u32 v16, v19, v16, s14
	s_nop 3
	v_lshrrev_b32_e32 v11, 16, v16
	v_cvt_pk_bf16_f32 v13, v13, v15
	v_cvt_pk_bf16_f32 v12, v12, v14
	v_lshlrev_b64 v[14:15], 9, v[26:27]
	v_and_or_b32 v11, v4, s15, v11
	v_lshl_add_u64 v[14:15], s[6:7], 0, v[14:15]
	v_lshlrev_b32_e32 v4, 1, v9
	v_cvt_pk_bf16_f32 v10, v18, v10
	v_lshl_add_u64 v[14:15], v[14:15], 0, v[4:5]
	global_store_dwordx4 v[14:15], v[10:13], off
	s_andn2_b64 exec, exec, s[10:11]
	s_cbranch_execnz .LBB0_2023

; __device__ __forceinline__ unsigned pk2(float lo, float hi) { return f2bf(lo) | (f2bf(hi) << 16); }
; __device__ __forceinline__ float sigmoidf_(float x) { return 1.f / (1.f + __expf(-x)); }
; __device__ __forceinline__ void nsa_attn_sw(const Ctx& c, const bf16* Q, const bf16* T, const bf16* VT, const float* Gt, const float* NACC, float* NACC2, const unsigned long long* SMg, bf16* OUT) {
;     ...
;           for (int mi = 0; mi < 2; ++mi) { float lt = l[mi]; lt += __shfl_xor(lt, 16); lt += __shfl_xor(lt, 32); const float sc = sigmoidf_(Gt[(size_t)grow[mi] * 48 + (hcol[mi] >> 7) * 3 + 2]) / lt;
; #pragma unroll
;               for (int dt = 0; dt < 8; ++dt) { const f32x4 a = *(const f32x4*)(NACC2 + (size_t)grow[mi] * 2048 + hcol[mi] + 16 * dt + 4 * lg) + O[dt][mi] * sc; v2u w_; w_.x = pk2(a[0], a[1]); w_.y = pk2(a[2], a[3]);
;                   *(v2u*)(OUT + (size_t)grow[mi] * 2048 + hcol[mi] + 16 * dt + 4 * lg) = w_; } }
.LBB0_2308:
	ds_bpermute_b32 v4, v208, v11
	v_mov_b32_e32 v13, v5
	v_lshlrev_b32_e32 v14, 1, v200
	v_mov_b32_e32 v15, v5
	v_lshlrev_b32_e32 v16, 1, v170
	s_waitcnt lgkmcnt(0)
	v_add_f32_e32 v4, v11, v4
	ds_bpermute_b32 v6, v209, v4
	v_mov_b32_e32 v17, v5
	s_add_i32 s36, s36, s33
	s_cmpk_lt_i32 s36, 0x400
	s_waitcnt lgkmcnt(0)
	v_add_f32_e32 v4, v4, v6
	global_load_dword v6, v[194:195], off offset:8
	s_waitcnt vmcnt(0)
	v_mul_f32_e32 v6, 0xbfb8aa3b, v6
	v_exp_f32_e32 v6, v6
	s_nop 0
	v_add_f32_e32 v6, 1.0, v6
	v_div_scale_f32 v7, s[0:1], v6, v6, 1.0
	v_rcp_f32_e32 v8, v7
	s_nop 0
	v_fma_f32 v9, -v7, v8, 1.0
	v_fmac_f32_e32 v8, v9, v8
	v_div_scale_f32 v9, vcc, 1.0, v6, 1.0
	v_mul_f32_e32 v11, v9, v8
	v_fma_f32 v12, -v7, v11, v9
	v_fmac_f32_e32 v11, v12, v8
	v_fma_f32 v7, -v7, v11, v9
	v_div_fmas_f32 v7, v7, v8, v11
	v_div_fixup_f32 v6, v7, v6, 1.0
	v_div_scale_f32 v7, s[0:1], v4, v4, v6
	v_rcp_f32_e32 v8, v7
	s_nop 0
	v_fma_f32 v9, -v7, v8, 1.0
	v_fmac_f32_e32 v8, v9, v8
	v_div_scale_f32 v9, vcc, v6, v4, v6
	v_mul_f32_e32 v11, v9, v8
	v_fma_f32 v12, -v7, v11, v9
	v_fmac_f32_e32 v11, v12, v8
	v_fma_f32 v7, -v7, v11, v9
	v_div_fmas_f32 v7, v7, v8, v11
	v_div_fixup_f32 v18, v7, v4, v6
	v_lshl_add_u64 v[6:7], s[14:15], 0, v[196:197]
	v_lshlrev_b32_e32 v4, 2, v200
	v_lshl_add_u64 v[6:7], v[6:7], 0, v[4:5]
	v_lshlrev_b32_e32 v12, 2, v170
	v_lshl_add_u64 v[6:7], v[6:7], 0, v[12:13]
	global_load_dwordx4 v[124:127], v[6:7], off
	global_load_dwordx4 v[128:131], v[6:7], off offset:64
	global_load_dwordx4 v[132:135], v[6:7], off offset:128
	global_load_dwordx4 v[136:139], v[6:7], off offset:192
	global_load_dwordx4 v[140:143], v[6:7], off offset:256
	global_load_dwordx4 v[144:147], v[6:7], off offset:320
	global_load_dwordx4 v[148:151], v[6:7], off offset:384
	global_load_dwordx4 v[152:155], v[6:7], off offset:448
	v_lshl_add_u64 v[8:9], s[78:79], 0, v[184:185]
	v_lshl_add_u64 v[8:9], v[8:9], 0, v[14:15]
	v_lshl_add_u64 v[20:21], v[8:9], 0, v[16:17]
	s_waitcnt vmcnt(7)
	v_pk_fma_f32 v[22:23], v[100:101], v[18:19], v[124:125] op_sel_hi:[1,0,1]
	s_nop 0
	v_bfe_u32 v11, v22, 16, 1
	v_pk_fma_f32 v[8:9], v[102:103], v[18:19], v[126:127] op_sel_hi:[1,0,1]
	v_add3_u32 v11, v22, v11, s34
	v_bfe_u32 v19, v23, 16, 1
	v_lshrrev_b32_e32 v11, 16, v11
	v_add3_u32 v19, v23, v19, s34
	v_and_or_b32 v22, v19, s35, v11
	s_nop 4
	v_cvt_pk_bf16_f32 v23, v8, v9
	global_store_dwordx2 v[20:21], v[22:23], off
	s_waitcnt vmcnt(7)
	v_pk_fma_f32 v[22:23], v[96:97], v[18:19], v[128:129] op_sel_hi:[1,0,1]
	s_nop 0
	v_bfe_u32 v11, v22, 16, 1
	v_pk_fma_f32 v[8:9], v[98:99], v[18:19], v[130:131] op_sel_hi:[1,0,1]
	v_add3_u32 v11, v22, v11, s34
	v_bfe_u32 v19, v23, 16, 1
	v_lshrrev_b32_e32 v11, 16, v11
	v_add3_u32 v19, v23, v19, s34
	v_and_or_b32 v22, v19, s35, v11
	s_nop 4
	v_cvt_pk_bf16_f32 v23, v8, v9
	global_store_dwordx2 v[20:21], v[22:23], off offset:32
	s_waitcnt vmcnt(7)
	v_pk_fma_f32 v[22:23], v[92:93], v[18:19], v[132:133] op_sel_hi:[1,0,1]
	s_nop 0
	v_bfe_u32 v11, v22, 16, 1
	v_pk_fma_f32 v[8:9], v[94:95], v[18:19], v[134:135] op_sel_hi:[1,0,1]
	v_add3_u32 v11, v22, v11, s34
	v_bfe_u32 v19, v23, 16, 1
	v_lshrrev_b32_e32 v11, 16, v11
	v_add3_u32 v19, v23, v19, s34
	v_and_or_b32 v22, v19, s35, v11
	s_nop 4
	v_cvt_pk_bf16_f32 v23, v8, v9
	global_store_dwordx2 v[20:21], v[22:23], off offset:64
	s_waitcnt vmcnt(7)
	v_pk_fma_f32 v[22:23], v[88:89], v[18:19], v[136:137] op_sel_hi:[1,0,1]
	s_nop 0
	v_bfe_u32 v11, v22, 16, 1
	v_pk_fma_f32 v[8:9], v[90:91], v[18:19], v[138:139] op_sel_hi:[1,0,1]
	v_add3_u32 v11, v22, v11, s34
	v_bfe_u32 v19, v23, 16, 1
	v_lshrrev_b32_e32 v11, 16, v11
	v_add3_u32 v19, v23, v19, s34
	v_and_or_b32 v22, v19, s35, v11
	s_nop 4
	v_cvt_pk_bf16_f32 v23, v8, v9
	global_store_dwordx2 v[20:21], v[22:23], off offset:96
	s_waitcnt vmcnt(7)
	v_pk_fma_f32 v[22:23], v[84:85], v[18:19], v[140:141] op_sel_hi:[1,0,1]
	s_nop 0
	v_bfe_u32 v11, v22, 16, 1
	v_pk_fma_f32 v[8:9], v[86:87], v[18:19], v[142:143] op_sel_hi:[1,0,1]
	v_add3_u32 v11, v22, v11, s34
	v_bfe_u32 v19, v23, 16, 1
	v_lshrrev_b32_e32 v11, 16, v11
	v_add3_u32 v19, v23, v19, s34
	v_and_or_b32 v22, v19, s35, v11
	s_nop 4
	v_cvt_pk_bf16_f32 v23, v8, v9
	global_store_dwordx2 v[20:21], v[22:23], off offset:128
	s_waitcnt vmcnt(7)
	v_pk_fma_f32 v[22:23], v[80:81], v[18:19], v[144:145] op_sel_hi:[1,0,1]
	s_nop 0
	v_bfe_u32 v11, v22, 16, 1
	v_pk_fma_f32 v[8:9], v[82:83], v[18:19], v[146:147] op_sel_hi:[1,0,1]
	v_add3_u32 v11, v22, v11, s34
	v_bfe_u32 v19, v23, 16, 1
	v_lshrrev_b32_e32 v11, 16, v11
	v_add3_u32 v19, v23, v19, s34
	v_and_or_b32 v22, v19, s35, v11
	s_nop 4
	v_cvt_pk_bf16_f32 v23, v8, v9
	global_store_dwordx2 v[20:21], v[22:23], off offset:160
	s_waitcnt vmcnt(7)
	v_pk_fma_f32 v[22:23], v[76:77], v[18:19], v[148:149] op_sel_hi:[1,0,1]
	s_nop 0
	v_bfe_u32 v11, v22, 16, 1
	v_pk_fma_f32 v[8:9], v[78:79], v[18:19], v[150:151] op_sel_hi:[1,0,1]
	v_add3_u32 v11, v22, v11, s34
	v_bfe_u32 v19, v23, 16, 1
	v_lshrrev_b32_e32 v11, 16, v11
	v_add3_u32 v19, v23, v19, s34
	v_and_or_b32 v22, v19, s35, v11
	s_nop 4
	v_cvt_pk_bf16_f32 v23, v8, v9
	s_waitcnt vmcnt(6)
	v_pk_fma_f32 v[6:7], v[72:73], v[18:19], v[152:153] op_sel_hi:[1,0,1]
	s_nop 0
	s_nop 2
	v_pk_fma_f32 v[8:9], v[74:75], v[18:19], v[154:155] op_sel_hi:[1,0,1]
	s_nop 1
	v_cvt_pk_bf16_f32 v6, v6, v7
	s_nop 4
	v_cvt_pk_bf16_f32 v7, v8, v9
	global_store_dwordx2 v[20:21], v[6:7], off offset:224
	ds_bpermute_b32 v6, v208, v10
	global_store_dwordx2 v[20:21], v[22:23], off offset:192
	s_waitcnt lgkmcnt(0)
; __device__ __forceinline__ unsigned pk2(float lo, float hi) { return f2bf(lo) | (f2bf(hi) << 16); }
; __device__ __forceinline__ float sigmoidf_(float x) { return 1.f / (1.f + __expf(-x)); }
; __device__ __forceinline__ void nsa_attn_sw(const Ctx& c, const bf16* Q, const bf16* T, const bf16* VT, const float* Gt, const float* NACC, float* NACC2, const unsigned long long* SMg, bf16* OUT) {
;     ...
;           for (int mi = 0; mi < 2; ++mi) { float lt = l[mi]; lt += __shfl_xor(lt, 16); lt += __shfl_xor(lt, 32); const float sc = sigmoidf_(Gt[(size_t)grow[mi] * 48 + (hcol[mi] >> 7) * 3 + 2]) / lt;
; #pragma unroll
;               for (int dt = 0; dt < 8; ++dt) { const f32x4 a = *(const f32x4*)(NACC2 + (size_t)grow[mi] * 2048 + hcol[mi] + 16 * dt + 4 * lg) + O[dt][mi] * sc; v2u w_; w_.x = pk2(a[0], a[1]); w_.y = pk2(a[2], a[3]);
;                   *(v2u*)(OUT + (size_t)grow[mi] * 2048 + hcol[mi] + 16 * dt + 4 * lg) = w_; } }
	v_add_f32_e32 v6, v10, v6
	ds_bpermute_b32 v7, v209, v6
	s_waitcnt lgkmcnt(0)
	v_add_f32_e32 v6, v6, v7
	global_load_dword v7, v[186:187], off offset:8
	s_waitcnt vmcnt(0)
	v_mul_f32_e32 v7, 0xbfb8aa3b, v7
	v_exp_f32_e32 v7, v7
	s_nop 0
	v_add_f32_e32 v7, 1.0, v7
	v_div_scale_f32 v8, s[0:1], v7, v7, 1.0
	v_rcp_f32_e32 v9, v8
	s_nop 0
	v_fma_f32 v10, -v8, v9, 1.0
	v_fmac_f32_e32 v9, v10, v9
	v_div_scale_f32 v10, vcc, 1.0, v7, 1.0
	v_mul_f32_e32 v11, v10, v9
	v_fma_f32 v18, -v8, v11, v10
	v_fmac_f32_e32 v11, v18, v9
	v_fma_f32 v8, -v8, v11, v10
	v_div_fmas_f32 v8, v8, v9, v11
	v_div_fixup_f32 v7, v8, v7, 1.0
	v_div_scale_f32 v8, s[0:1], v6, v6, v7
	v_rcp_f32_e32 v9, v8
	s_nop 0
	v_fma_f32 v10, -v8, v9, 1.0
	v_fmac_f32_e32 v9, v10, v9
	v_div_scale_f32 v10, vcc, v7, v6, v7
	v_mul_f32_e32 v11, v10, v9
	v_fma_f32 v18, -v8, v11, v10
	v_fmac_f32_e32 v11, v18, v9
	v_fma_f32 v8, -v8, v11, v10
	v_div_fmas_f32 v8, v8, v9, v11
	v_div_fixup_f32 v6, v8, v6, v7
	v_lshl_add_u64 v[8:9], s[14:15], 0, v[188:189]
	v_lshl_add_u64 v[8:9], v[8:9], 0, v[4:5]
	v_lshl_add_u64 v[10:11], v[8:9], 0, v[12:13]
	v_lshl_add_u64 v[8:9], s[78:79], 0, v[182:183]
	v_lshl_add_u64 v[8:9], v[8:9], 0, v[14:15]
	global_load_dwordx4 v[124:127], v[10:11], off
	global_load_dwordx4 v[128:131], v[10:11], off offset:64
	global_load_dwordx4 v[132:135], v[10:11], off offset:128
	global_load_dwordx4 v[136:139], v[10:11], off offset:192
	global_load_dwordx4 v[140:143], v[10:11], off offset:256
	global_load_dwordx4 v[144:147], v[10:11], off offset:320
	global_load_dwordx4 v[148:151], v[10:11], off offset:384
	global_load_dwordx4 v[152:155], v[10:11], off offset:448
	v_lshl_add_u64 v[8:9], v[8:9], 0, v[16:17]
	s_waitcnt vmcnt(7)
	v_pk_fma_f32 v[12:13], v[68:69], v[6:7], v[124:125] op_sel_hi:[1,0,1]
	s_nop 0
	s_nop 0
	v_pk_fma_f32 v[14:15], v[70:71], v[6:7], v[126:127] op_sel_hi:[1,0,1]
	s_nop 3
	v_cvt_pk_bf16_f32 v12, v12, v13
	v_bfe_u32 v4, v14, 16, 1
	v_add3_u32 v4, v14, v4, s34
	v_bfe_u32 v7, v15, 16, 1
	v_lshrrev_b32_e32 v4, 16, v4
	v_add3_u32 v7, v15, v7, s34
	v_and_or_b32 v13, v7, s35, v4
	global_store_dwordx2 v[8:9], v[12:13], off
	s_waitcnt vmcnt(7)
	v_pk_fma_f32 v[12:13], v[64:65], v[6:7], v[128:129] op_sel_hi:[1,0,1]
	s_nop 0
	s_nop 0
	v_pk_fma_f32 v[14:15], v[66:67], v[6:7], v[130:131] op_sel_hi:[1,0,1]
	s_nop 3
	v_cvt_pk_bf16_f32 v12, v12, v13
	v_bfe_u32 v4, v14, 16, 1
	v_add3_u32 v4, v14, v4, s34
	v_bfe_u32 v7, v15, 16, 1
	v_lshrrev_b32_e32 v4, 16, v4
	v_add3_u32 v7, v15, v7, s34
	v_and_or_b32 v13, v7, s35, v4
	global_store_dwordx2 v[8:9], v[12:13], off offset:32
	s_waitcnt vmcnt(7)
	v_pk_fma_f32 v[12:13], v[60:61], v[6:7], v[132:133] op_sel_hi:[1,0,1]
	s_nop 0
	s_nop 0
	v_pk_fma_f32 v[14:15], v[62:63], v[6:7], v[134:135] op_sel_hi:[1,0,1]
	s_nop 3
	v_cvt_pk_bf16_f32 v12, v12, v13
	v_bfe_u32 v4, v14, 16, 1
	v_add3_u32 v4, v14, v4, s34
	v_bfe_u32 v7, v15, 16, 1
	v_lshrrev_b32_e32 v4, 16, v4
	v_add3_u32 v7, v15, v7, s34
	v_and_or_b32 v13, v7, s35, v4
	global_store_dwordx2 v[8:9], v[12:13], off offset:64
	s_waitcnt vmcnt(7)
	v_pk_fma_f32 v[12:13], v[56:57], v[6:7], v[136:137] op_sel_hi:[1,0,1]
	s_nop 0
	s_nop 0
	v_pk_fma_f32 v[14:15], v[58:59], v[6:7], v[138:139] op_sel_hi:[1,0,1]
	s_nop 3
	v_cvt_pk_bf16_f32 v12, v12, v13
	v_bfe_u32 v4, v14, 16, 1
	v_add3_u32 v4, v14, v4, s34
	v_bfe_u32 v7, v15, 16, 1
	v_lshrrev_b32_e32 v4, 16, v4
	v_add3_u32 v7, v15, v7, s34
	v_and_or_b32 v13, v7, s35, v4
	global_store_dwordx2 v[8:9], v[12:13], off offset:96
	s_waitcnt vmcnt(7)
	v_pk_fma_f32 v[12:13], v[52:53], v[6:7], v[140:141] op_sel_hi:[1,0,1]
	s_nop 0
	s_nop 0
	v_pk_fma_f32 v[14:15], v[54:55], v[6:7], v[142:143] op_sel_hi:[1,0,1]
	s_nop 3
	v_cvt_pk_bf16_f32 v12, v12, v13
	v_bfe_u32 v4, v14, 16, 1
	v_add3_u32 v4, v14, v4, s34
	v_bfe_u32 v7, v15, 16, 1
	v_lshrrev_b32_e32 v4, 16, v4
	v_add3_u32 v7, v15, v7, s34
	v_and_or_b32 v13, v7, s35, v4
	global_store_dwordx2 v[8:9], v[12:13], off offset:128
	s_waitcnt vmcnt(7)
	v_pk_fma_f32 v[12:13], v[48:49], v[6:7], v[144:145] op_sel_hi:[1,0,1]
	s_nop 0
	s_nop 0
	v_pk_fma_f32 v[14:15], v[50:51], v[6:7], v[146:147] op_sel_hi:[1,0,1]
	s_nop 3
	v_cvt_pk_bf16_f32 v12, v12, v13
	v_bfe_u32 v4, v14, 16, 1
	v_add3_u32 v4, v14, v4, s34
	v_bfe_u32 v7, v15, 16, 1
	v_lshrrev_b32_e32 v4, 16, v4
	v_add3_u32 v7, v15, v7, s34
	v_and_or_b32 v13, v7, s35, v4
	global_store_dwordx2 v[8:9], v[12:13], off offset:160
	s_waitcnt vmcnt(7)
	v_pk_fma_f32 v[12:13], v[44:45], v[6:7], v[148:149] op_sel_hi:[1,0,1]
	s_nop 0
	s_nop 0
	v_pk_fma_f32 v[14:15], v[46:47], v[6:7], v[150:151] op_sel_hi:[1,0,1]
	s_nop 3
	v_cvt_pk_bf16_f32 v12, v12, v13
	v_bfe_u32 v4, v14, 16, 1
	v_add3_u32 v4, v14, v4, s34
	v_bfe_u32 v7, v15, 16, 1
	v_lshrrev_b32_e32 v4, 16, v4
	v_add3_u32 v7, v15, v7, s34
	v_and_or_b32 v13, v7, s35, v4
	global_store_dwordx2 v[8:9], v[12:13], off offset:192
	s_waitcnt vmcnt(7)
	v_pk_fma_f32 v[12:13], v[42:43], v[6:7], v[154:155] op_sel_hi:[1,0,1]
	v_pk_fma_f32 v[6:7], v[40:41], v[6:7], v[152:153] op_sel_hi:[1,0,1]
	s_nop 0
	s_nop 4
	v_cvt_pk_bf16_f32 v6, v6, v7
	v_bfe_u32 v4, v12, 16, 1
	v_add3_u32 v4, v12, v4, s34
	v_bfe_u32 v7, v13, 16, 1
	v_lshrrev_b32_e32 v4, 16, v4
	v_add3_u32 v7, v13, v7, s34
	v_and_or_b32 v7, v7, s35, v4
	global_store_dwordx2 v[8:9], v[6:7], off offset:224
	s_cbranch_scc0 .LBB0_2352

; __device__ __forceinline__ void postnorm(const Ctx& c, const bf16* MF, bf16* XB, float* RS, const float* gpost, float* OUT) {
;     for (int row = c.gw; row < MT; row += c.NGW) {
;         const v4u* mr = (const v4u*)(MF + (size_t)row * DM) + c.lane; v4u* xr = (v4u*)(XB + (size_t)row * DM) + c.lane;
;         v4u mv[4], xv[4]; float v[4][8]; float s = 0.f;
; #pragma unroll
;         for (int j = 0; j < 4; ++j) { mv[j] = mr[64 * j]; xv[j] = xr[64 * j]; }
; #pragma unroll
;         for (int j = 0; j < 4; ++j)
; #pragma unroll
;             for (int k = 0; k < 4; ++k) { v[j][2 * k] = bflo(mv[j][k]); v[j][2 * k + 1] = bfhi(mv[j][k]); s += v[j][2 * k] * v[j][2 * k] + v[j][2 * k + 1] * v[j][2 * k + 1]; }
;         const float rs = rsqrtf(wave_sum(s) * (1.f / DM) + EPS);
.LBB0_2484:
	v_readlane_b32 s12, v253, 0
	v_readlane_b32 s13, v253, 1
	s_nop 1
	v_lshl_add_u64 v[38:39], s[12:13], 0, v[30:31]
	v_add_co_u32_e32 v58, vcc, 0xd400000, v38
	s_nop 1
	v_addc_co_u32_e32 v59, vcc, 0, v39, vcc
	s_waitcnt lgkmcnt(0)
	global_load_dwordx4 v[46:49], v[58:59], off
	global_load_dwordx4 v[50:53], v[58:59], off offset:1024
	global_load_dwordx4 v[54:57], v[58:59], off offset:2048
	s_nop 0
	global_load_dwordx4 v[58:61], v[58:59], off offset:3072
	v_add_co_u32_e32 v38, vcc, 0x9400000, v38
	s_waitcnt vmcnt(3)
	v_lshlrev_b32_e32 v79, 16, v47
	v_addc_co_u32_e32 v39, vcc, 0, v39, vcc
	global_load_dwordx4 v[62:65], v[38:39], off
	global_load_dwordx4 v[66:69], v[38:39], off offset:1024
	global_load_dwordx4 v[70:73], v[38:39], off offset:2048
	global_load_dwordx4 v[74:77], v[38:39], off offset:3072
	v_lshlrev_b32_e32 v78, 16, v46
	v_and_b32_e32 v47, 0xffff0000, v47
	v_and_b32_e32 v46, 0xffff0000, v46
	v_lshlrev_b32_e32 v81, 16, v49
	v_lshlrev_b32_e32 v80, 16, v48
	v_and_b32_e32 v49, 0xffff0000, v49
	v_and_b32_e32 v48, 0xffff0000, v48
	v_pk_mul_f32 v[94:95], v[46:47], v[46:47]
	v_pk_mul_f32 v[98:99], v[48:49], v[48:49]
	v_pk_fma_f32 v[94:95], v[78:79], v[78:79], v[94:95]
	s_waitcnt vmcnt(6)
	v_lshlrev_b32_e32 v83, 16, v51
	v_lshlrev_b32_e32 v82, 16, v50
	v_and_b32_e32 v51, 0xffff0000, v51
	v_and_b32_e32 v50, 0xffff0000, v50
	v_pk_fma_f32 v[98:99], v[80:81], v[80:81], v[98:99]
	v_add_f32_e32 v94, v94, v95
	v_pk_mul_f32 v[102:103], v[50:51], v[50:51]
	v_add_f32_e32 v94, v98, v94
	v_lshlrev_b32_e32 v85, 16, v53
	v_lshlrev_b32_e32 v84, 16, v52
	v_and_b32_e32 v53, 0xffff0000, v53
	v_and_b32_e32 v52, 0xffff0000, v52
	v_pk_fma_f32 v[102:103], v[82:83], v[82:83], v[102:103]
	v_add_f32_e32 v94, v99, v94
	v_pk_mul_f32 v[104:105], v[52:53], v[52:53]
	v_add_f32_e32 v94, v102, v94
	s_waitcnt vmcnt(5)
	v_lshlrev_b32_e32 v87, 16, v55
	v_lshlrev_b32_e32 v86, 16, v54
	v_and_b32_e32 v55, 0xffff0000, v55
	v_and_b32_e32 v54, 0xffff0000, v54
	v_pk_fma_f32 v[104:105], v[84:85], v[84:85], v[104:105]
	v_add_f32_e32 v94, v103, v94
	v_pk_mul_f32 v[106:107], v[54:55], v[54:55]
	v_add_f32_e32 v94, v104, v94
	v_lshlrev_b32_e32 v89, 16, v57
	v_lshlrev_b32_e32 v88, 16, v56
	v_and_b32_e32 v57, 0xffff0000, v57
	v_and_b32_e32 v56, 0xffff0000, v56
	v_pk_fma_f32 v[106:107], v[86:87], v[86:87], v[106:107]
	v_add_f32_e32 v94, v105, v94
	v_pk_mul_f32 v[108:109], v[56:57], v[56:57]
	v_add_f32_e32 v94, v106, v94
	s_waitcnt vmcnt(4)
	v_lshlrev_b32_e32 v91, 16, v59
	v_lshlrev_b32_e32 v90, 16, v58
	v_and_b32_e32 v59, 0xffff0000, v59
	v_and_b32_e32 v58, 0xffff0000, v58
	v_pk_fma_f32 v[108:109], v[88:89], v[88:89], v[108:109]
	v_add_f32_e32 v94, v107, v94
	v_pk_mul_f32 v[110:111], v[58:59], v[58:59]
	v_add_f32_e32 v94, v108, v94
	v_lshlrev_b32_e32 v93, 16, v61
	v_lshlrev_b32_e32 v92, 16, v60
	v_and_b32_e32 v61, 0xffff0000, v61
	v_and_b32_e32 v60, 0xffff0000, v60
	v_pk_fma_f32 v[110:111], v[90:91], v[90:91], v[110:111]
	v_add_f32_e32 v94, v109, v94
	v_pk_mul_f32 v[112:113], v[60:61], v[60:61]
	v_add_f32_e32 v94, v110, v94
	v_pk_fma_f32 v[112:113], v[92:93], v[92:93], v[112:113]
	v_add_f32_e32 v94, v111, v94
	v_add_f32_e32 v94, v112, v94
	v_add_f32_e32 v94, v113, v94
	ds_bpermute_b32 v98, v3, v94
	s_waitcnt lgkmcnt(0)
	v_add_f32_e32 v98, v94, v98
	ds_bpermute_b32 v102, v40, v98
	s_waitcnt lgkmcnt(0)
	v_add_f32_e32 v102, v98, v102
	ds_bpermute_b32 v104, v41, v102
	s_waitcnt vmcnt(3)
	v_lshlrev_b32_e32 v97, 16, v63
	v_lshlrev_b32_e32 v96, 16, v62
	v_and_b32_e32 v63, 0xffff0000, v63
	s_waitcnt lgkmcnt(0)
	v_add_f32_e32 v104, v102, v104
	ds_bpermute_b32 v106, v42, v104
	v_and_b32_e32 v62, 0xffff0000, v62
	v_lshlrev_b32_e32 v101, 16, v65
	v_lshlrev_b32_e32 v100, 16, v64
	v_and_b32_e32 v65, 0xffff0000, v65
	s_waitcnt lgkmcnt(0)
	v_add_f32_e32 v106, v104, v106
	ds_bpermute_b32 v108, v43, v106
	v_and_b32_e32 v64, 0xffff0000, v64
	s_waitcnt vmcnt(0)
	v_lshlrev_b32_e32 v109, 16, v77
	v_and_b32_e32 v77, 0xffff0000, v77
	v_lshlrev_b32_e32 v95, 16, v67
	s_waitcnt lgkmcnt(0)
	v_add_f32_e32 v108, v106, v108
	ds_bpermute_b32 v110, v44, v108
	v_lshlrev_b32_e32 v94, 16, v66
	v_and_b32_e32 v67, 0xffff0000, v67
	v_and_b32_e32 v66, 0xffff0000, v66
	v_lshlrev_b32_e32 v99, 16, v69
	s_waitcnt lgkmcnt(0)
; __device__ __forceinline__ unsigned pk2(float lo, float hi) { return f2bf(lo) | (f2bf(hi) << 16); }
; __device__ __forceinline__ void postnorm(const Ctx& c, const bf16* MF, bf16* XB, float* RS, const float* gpost, float* OUT) {
;     ...
;         const float rs = rsqrtf(wave_sum(s) * (1.f / DM) + EPS);
;         float s2 = 0.f;
; #pragma unroll
;         for (int j = 0; j < 4; ++j) { const float* gp = gpost + (c.lane + 64 * j) * 8; const f32x4 g0 = *(CF4)gp, g1 = *(CF4)(gp + 4);
; #pragma unroll
;             for (int k = 0; k < 4; ++k) { const float ga = (k < 2) ? g0[2 * k] : g1[2 * k - 4], gb = (k < 2) ? g0[2 * k + 1] : g1[2 * k - 3];
;                 v[j][2 * k] = bflo(xv[j][k]) + v[j][2 * k] * rs * ga; v[j][2 * k + 1] = bfhi(xv[j][k]) + v[j][2 * k + 1] * rs * gb;
;                 s2 += v[j][2 * k] * v[j][2 * k] + v[j][2 * k + 1] * v[j][2 * k + 1]; } }
;         if (OUT) {
; #pragma unroll
;             for (int j = 0; j < 4; ++j) { float* op = OUT + (size_t)row * DM + (c.lane + 64 * j) * 8; *(f32x4*)op = (f32x4){v[j][0], v[j][1], v[j][2], v[j][3]}; *(f32x4*)(op + 4) = (f32x4){v[j][4], v[j][5], v[j][6], v[j][7]}; }
;         } else {
; #pragma unroll
;             for (int j = 0; j < 4; ++j) { v4u o; o.x = pk2(v[j][0], v[j][1]); o.y = pk2(v[j][2], v[j][3]); o.z = pk2(v[j][4], v[j][5]); o.w = pk2(v[j][6], v[j][7]); xr[64 * j] = o; }
;             const float rs2 = rsqrtf(wave_sum(s2) * (1.f / DM) + EPS); if (c.lane == 0) RS[row] = rs2;
	v_add_f32_e32 v108, v108, v110
	v_fmamk_f32 v108, v108, 0x3a000000, v45
	v_mul_f32_e32 v110, 0x4b800000, v108
	v_cmp_gt_f32_e32 vcc, s17, v108
	v_lshlrev_b32_e32 v98, 16, v68
	v_and_b32_e32 v69, 0xffff0000, v69
	v_cndmask_b32_e32 v108, v108, v110, vcc
	v_rsq_f32_e32 v110, v108
	v_lshlrev_b32_e32 v108, 16, v76
	v_and_b32_e32 v76, 0xffff0000, v76
	v_and_b32_e32 v68, 0xffff0000, v68
	v_mul_f32_e32 v111, 0x45800000, v110
	v_cndmask_b32_e32 v110, v110, v111, vcc
	v_pk_mul_f32 v[46:47], v[110:111], v[46:47] op_sel_hi:[0,1]
	v_pk_mul_f32 v[78:79], v[110:111], v[78:79] op_sel_hi:[0,1]
	v_pk_mul_f32 v[48:49], v[110:111], v[48:49] op_sel_hi:[0,1]
	v_pk_fma_f32 v[46:47], v[36:37], v[46:47], v[62:63]
	v_pk_mul_f32 v[60:61], v[110:111], v[60:61] op_sel_hi:[0,1]
	v_pk_mul_f32 v[80:81], v[110:111], v[80:81] op_sel_hi:[0,1]
	v_pk_fma_f32 v[78:79], v[8:9], v[78:79], v[96:97]
	v_pk_fma_f32 v[48:49], v[10:11], v[48:49], v[64:65]
	v_pk_fma_f32 v[60:61], v[34:35], v[60:61], v[76:77]
	v_pk_mul_f32 v[76:77], v[46:47], v[46:47]
	v_pk_mul_f32 v[50:51], v[110:111], v[50:51] op_sel_hi:[0,1]
	v_pk_fma_f32 v[62:63], v[4:5], v[80:81], v[100:101]
	v_pk_fma_f32 v[76:77], v[78:79], v[78:79], v[76:77]
	v_pk_mul_f32 v[80:81], v[48:49], v[48:49]
	v_pk_mul_f32 v[82:83], v[110:111], v[82:83] op_sel_hi:[0,1]
	v_pk_fma_f32 v[50:51], v[6:7], v[50:51], v[66:67]
	v_pk_fma_f32 v[80:81], v[62:63], v[62:63], v[80:81]
	v_add_f32_e32 v76, v76, v77
	v_pk_fma_f32 v[64:65], v[16:17], v[82:83], v[94:95]
	v_pk_mul_f32 v[82:83], v[50:51], v[50:51]
	v_add_f32_e32 v76, v80, v76
	v_pk_fma_f32 v[82:83], v[64:65], v[64:65], v[82:83]
	v_add_f32_e32 v76, v81, v76
	v_add_f32_e32 v76, v82, v76
	s_nop 2
	v_bfe_u32 v82, v46, 16, 1
	v_pk_mul_f32 v[52:53], v[110:111], v[52:53] op_sel_hi:[0,1]
	v_add3_u32 v46, v46, v82, s18
	s_nop 2
	v_bfe_u32 v77, v78, 16, 1
	s_nop 2
	v_pk_mul_f32 v[84:85], v[110:111], v[84:85] op_sel_hi:[0,1]
	v_pk_fma_f32 v[52:53], v[18:19], v[52:53], v[68:69]
	s_nop 2
	v_add3_u32 v77, v78, v77, s18
	v_lshlrev_b32_e32 v103, 16, v71
	v_lshlrev_b32_e32 v102, 16, v70
	v_and_b32_e32 v71, 0xffff0000, v71
	v_and_b32_e32 v70, 0xffff0000, v70
	v_pk_fma_f32 v[66:67], v[12:13], v[84:85], v[98:99]
	v_pk_mul_f32 v[54:55], v[110:111], v[54:55] op_sel_hi:[0,1]
	v_pk_mul_f32 v[84:85], v[52:53], v[52:53]
	v_lshrrev_b32_e32 v77, 16, v77
	s_nop 2
	v_pk_mul_f32 v[68:69], v[110:111], v[86:87] op_sel_hi:[0,1]
	v_pk_fma_f32 v[54:55], v[14:15], v[54:55], v[70:71]
	v_pk_fma_f32 v[84:85], v[66:67], v[66:67], v[84:85]
	v_add_f32_e32 v76, v83, v76
	v_cvt_pk_bf16_f32 v49, v63, v49
	v_cvt_pk_bf16_f32 v48, v62, v48
	v_cvt_pk_bf16_f32 v47, v79, v47
	v_and_or_b32 v46, v46, s16, v77
	v_lshlrev_b32_e32 v105, 16, v73
	v_lshlrev_b32_e32 v104, 16, v72
	v_and_b32_e32 v73, 0xffff0000, v73
	v_and_b32_e32 v72, 0xffff0000, v72
	v_pk_fma_f32 v[68:69], v[24:25], v[68:69], v[102:103]
	v_pk_mul_f32 v[56:57], v[110:111], v[56:57] op_sel_hi:[0,1]
	v_pk_mul_f32 v[86:87], v[54:55], v[54:55]
	v_add_f32_e32 v76, v84, v76
	global_store_dwordx4 v[38:39], v[46:49], off
	v_pk_mul_f32 v[70:71], v[110:111], v[88:89] op_sel_hi:[0,1]
	v_pk_fma_f32 v[56:57], v[26:27], v[56:57], v[72:73]
	s_nop 3
	v_pk_fma_f32 v[86:87], v[68:69], v[68:69], v[86:87]
	v_add_f32_e32 v76, v85, v76
	s_nop 7
	v_lshlrev_b32_e32 v107, 16, v75
	v_lshlrev_b32_e32 v106, 16, v74
	v_and_b32_e32 v75, 0xffff0000, v75
	v_and_b32_e32 v74, 0xffff0000, v74
	v_pk_fma_f32 v[70:71], v[20:21], v[70:71], v[104:105]
	v_pk_mul_f32 v[58:59], v[110:111], v[58:59] op_sel_hi:[0,1]
	v_pk_mul_f32 v[88:89], v[56:57], v[56:57]
	v_add_f32_e32 v76, v86, v76
	s_nop 3
	v_pk_mul_f32 v[72:73], v[110:111], v[90:91] op_sel_hi:[0,1]
	v_pk_fma_f32 v[58:59], v[22:23], v[58:59], v[74:75]
	v_pk_fma_f32 v[88:89], v[70:71], v[70:71], v[88:89]
	v_add_f32_e32 v76, v87, v76
	s_nop 3
	v_pk_fma_f32 v[72:73], v[32:33], v[72:73], v[106:107]
	v_pk_mul_f32 v[90:91], v[58:59], v[58:59]
	v_add_f32_e32 v76, v88, v76
	v_cvt_pk_bf16_f32 v49, v67, v53
	v_cvt_pk_bf16_f32 v48, v66, v52
	v_cvt_pk_bf16_f32 v47, v65, v51
	v_cvt_pk_bf16_f32 v46, v64, v50
	v_pk_mul_f32 v[74:75], v[110:111], v[92:93] op_sel_hi:[0,1]
	v_pk_fma_f32 v[90:91], v[72:73], v[72:73], v[90:91]
	v_add_f32_e32 v76, v89, v76
	global_store_dwordx4 v[38:39], v[46:49], off offset:1024
	v_pk_fma_f32 v[74:75], v[28:29], v[74:75], v[108:109]
	v_pk_mul_f32 v[92:93], v[60:61], v[60:61]
	s_nop 1
	v_add_f32_e32 v76, v90, v76
	s_nop 5
	v_pk_fma_f32 v[92:93], v[74:75], v[74:75], v[92:93]
	v_add_f32_e32 v76, v91, v76
	s_nop 5
	v_add_f32_e32 v76, v92, v76
	s_nop 5
	v_add_f32_e32 v76, v93, v76
	v_cvt_pk_bf16_f32 v49, v71, v57
	v_cvt_pk_bf16_f32 v48, v70, v56
	v_cvt_pk_bf16_f32 v47, v69, v55
	v_cvt_pk_bf16_f32 v46, v68, v54
	global_store_dwordx4 v[38:39], v[46:49], off offset:2048
	ds_bpermute_b32 v47, v3, v76
	s_nop 3
	s_waitcnt lgkmcnt(0)
	v_add_f32_e32 v47, v76, v47
	ds_bpermute_b32 v50, v40, v47
	s_nop 3
	s_waitcnt lgkmcnt(0)
	v_add_f32_e32 v47, v47, v50
	ds_bpermute_b32 v50, v41, v47
	s_nop 1
	v_cvt_pk_bf16_f32 v51, v75, v61
	s_nop 0
	s_waitcnt lgkmcnt(0)
	v_add_f32_e32 v47, v47, v50
	ds_bpermute_b32 v50, v42, v47
	s_nop 3
	s_waitcnt lgkmcnt(0)
	v_add_f32_e32 v47, v47, v50
	ds_bpermute_b32 v50, v43, v47
	s_nop 3
	s_waitcnt lgkmcnt(0)
	v_add_f32_e32 v46, v47, v50
	ds_bpermute_b32 v47, v44, v46
	s_nop 0
	v_cvt_pk_bf16_f32 v50, v74, v60
	v_cvt_pk_bf16_f32 v49, v73, v59
	v_cvt_pk_bf16_f32 v48, v72, v58
	global_store_dwordx4 v[38:39], v[48:51], off offset:3072
	s_and_saveexec_b64 s[12:13], s[0:1]
	s_cbranch_execz .LBB0_2483
	s_waitcnt lgkmcnt(0)
	v_add_f32_e32 v38, v46, v47
	v_fmamk_f32 v38, v38, 0x3a000000, v45
	v_mul_f32_e32 v39, 0x4b800000, v38
	v_cmp_gt_f32_e32 vcc, s17, v38
	v_readlane_b32 s20, v253, 0
	v_readlane_b32 s21, v253, 1
	v_cndmask_b32_e32 v38, v38, v39, vcc
	v_rsq_f32_e32 v38, v38
	s_add_u32 s20, s20, s14
	s_addc_u32 s21, s21, s15
	v_mul_f32_e32 v39, 0x45800000, v38
	v_cndmask_b32_e32 v38, v38, v39, vcc
	global_store_dword v251, v38, s[20:21]
	s_branch .LBB0_2483

; #define LAS __attribute__((address_space(3)))
; #define LDS_WAIT() asm volatile("s_waitcnt lgkmcnt(0)" ::: "memory")
; __device__ __forceinline__ unsigned pk2(float lo, float hi) { return f2bf(lo) | (f2bf(hi) << 16); }
;     ...
;     for (int it = gw0; it < items; it += ngw) {
;         const int kb = it / nblk, nb = it % nblk, k0 = 64 * kb, n0 = 64 * nb, nq = (lane & 15) * 4, kr = lane >> 4; const bool ok = (n0 + nq) < N;
;         f32x4 v[16];
; #pragma unroll
;         for (int i = 0; i < 16; ++i) v[i] = ok ? __builtin_nontemporal_load((const f32x4*)(W + (size_t)(k0 + 4 * i + kr) * N + n0 + nq)) : (f32x4){0.f, 0.f, 0.f, 0.f};
;         if (gain) {
; #pragma unroll
;             for (int i = 0; i < 16; ++i) v[i] *= gain[k0 + 4 * i + kr]; }
; #pragma unroll
;         for (int i = 0; i < 16; ++i) { LAS float* d = scr + (4 * i + kr) * 65 + nq; d[0] = v[i].x; d[1] = v[i].y; d[2] = v[i].z; d[3] = v[i].w; }
;         LDS_WAIT(); asm volatile("" ::: "memory");
;         const int c8 = lane & 7; int d0 = n0;
;         if (ffnmap) { const int bj = n0 >= FFH ? 1 : 0, chn = n0 - FFH * bj; d0 = 256 * (chn >> 7) + 128 * bj + (chn & 127); }
; #pragma unroll
;         for (int j = 0; j < 8; ++j) { const int n = (lane >> 3) + 8 * j; const LAS float* sp = scr + (8 * c8) * 65 + n;
;             v4u o; o.x = pk2(sp[0 * 65], sp[1 * 65]); o.y = pk2(sp[2 * 65], sp[3 * 65]); o.z = pk2(sp[4 * 65], sp[5 * 65]); o.w = pk2(sp[6 * 65], sp[7 * 65]);
;             *(v4u*)(WT + (size_t)(d0 + n) * K + k0 + 8 * c8) = o; }
;         LDS_WAIT(); asm volatile("" ::: "memory");
;     }
.LBB0_2650:
	s_or_b64 exec, exec, s[10:11]
	v_lshl_add_u64 v[82:83], v[72:73], 2, s[0:1]
	global_load_dword v72, v[82:83], off
	s_add_i32 s19, s19, s14
	s_ashr_i32 s9, s8, 31
	s_add_i32 s18, s18, s13
	s_add_i32 s14, s14, s15
	s_cmpk_lt_i32 s18, 0x1000
	s_waitcnt vmcnt(0)
	v_pk_mul_f32 v[86:87], v[8:9], v[72:73] op_sel_hi:[1,0]
	global_load_dword v8, v[82:83], off offset:16
	v_pk_mul_f32 v[84:85], v[10:11], v[72:73] op_sel_hi:[1,0]
	s_waitcnt vmcnt(0)
	v_pk_mul_f32 v[72:73], v[14:15], v[8:9] op_sel_hi:[1,0]
	v_pk_mul_f32 v[88:89], v[12:13], v[8:9] op_sel_hi:[1,0]
	global_load_dword v8, v[82:83], off offset:32
	global_load_dword v12, v[82:83], off offset:160
	s_waitcnt vmcnt(1)
	v_pk_mul_f32 v[90:91], v[4:5], v[8:9] op_sel_hi:[1,0]
	global_load_dword v4, v[82:83], off offset:48
	v_pk_mul_f32 v[74:75], v[6:7], v[8:9] op_sel_hi:[1,0]
	global_load_dword v6, v[82:83], off offset:128
	global_load_dword v8, v[82:83], off offset:144
	s_waitcnt vmcnt(3)
	v_pk_mul_f32 v[10:11], v[42:43], v[12:13] op_sel_hi:[1,0]
	v_pk_mul_f32 v[12:13], v[40:41], v[12:13] op_sel_hi:[1,0]
	v_add_u32_e32 v40, 0x410, v81
	s_waitcnt vmcnt(2)
	v_pk_mul_f32 v[92:93], v[22:23], v[4:5] op_sel_hi:[1,0]
	v_pk_mul_f32 v[94:95], v[20:21], v[4:5] op_sel_hi:[1,0]
	global_load_dword v4, v[82:83], off offset:64
	global_load_dword v20, v[82:83], off offset:192
	s_waitcnt vmcnt(1)
	v_pk_mul_f32 v[96:97], v[18:19], v[4:5] op_sel_hi:[1,0]
	v_pk_mul_f32 v[98:99], v[16:17], v[4:5] op_sel_hi:[1,0]
	global_load_dword v4, v[82:83], off offset:80
	global_load_dword v16, v[82:83], off offset:176
	s_waitcnt vmcnt(2)
	v_pk_mul_f32 v[18:19], v[50:51], v[20:21] op_sel_hi:[1,0]
	v_pk_mul_f32 v[20:21], v[48:49], v[20:21] op_sel_hi:[1,0]
	s_waitcnt vmcnt(1)
	v_pk_mul_f32 v[100:101], v[30:31], v[4:5] op_sel_hi:[1,0]
	v_pk_mul_f32 v[102:103], v[28:29], v[4:5] op_sel_hi:[1,0]
	global_load_dword v4, v[82:83], off offset:96
	global_load_dword v28, v[82:83], off offset:224
	v_lshl_add_u64 v[30:31], v[76:77], 2, s[0:1]
	s_waitcnt vmcnt(2)
	v_pk_mul_f32 v[14:15], v[54:55], v[16:17] op_sel_hi:[1,0]
	v_pk_mul_f32 v[16:17], v[52:53], v[16:17] op_sel_hi:[1,0]
	s_waitcnt vmcnt(1)
	v_pk_mul_f32 v[104:105], v[26:27], v[4:5] op_sel_hi:[1,0]
	v_pk_mul_f32 v[106:107], v[24:25], v[4:5] op_sel_hi:[1,0]
	global_load_dword v4, v[82:83], off offset:112
	global_load_dword v24, v[82:83], off offset:208
	s_waitcnt vmcnt(2)
	v_pk_mul_f32 v[26:27], v[58:59], v[28:29] op_sel_hi:[1,0]
	v_pk_mul_f32 v[28:29], v[56:57], v[28:29] op_sel_hi:[1,0]
	s_waitcnt vmcnt(1)
	v_pk_mul_f32 v[38:39], v[38:39], v[4:5] op_sel_hi:[1,0]
	v_pk_mul_f32 v[36:37], v[36:37], v[4:5] op_sel_hi:[1,0]
	v_pk_mul_f32 v[4:5], v[34:35], v[6:7] op_sel_hi:[1,0]
	v_pk_mul_f32 v[34:35], v[32:33], v[6:7] op_sel_hi:[1,0]
	global_load_dword v32, v[30:31], off
	ds_write2_b32 v81, v86, v87 offset1:1
	ds_write2_b32 v81, v84, v85 offset0:2 offset1:3
	ds_write2_b32 v40, v88, v89 offset1:1
	v_add_u32_e32 v40, 0x418, v81
	ds_write2_b32 v40, v72, v73 offset1:1
	v_add_u32_e32 v40, 0x820, v81
	ds_write2_b32 v40, v90, v91 offset1:1
	v_add_u32_e32 v40, 0x828, v81
	ds_write2_b32 v40, v74, v75 offset1:1
	v_add_u32_e32 v40, 0xc30, v81
	ds_write2_b32 v40, v94, v95 offset1:1
	v_add_u32_e32 v40, 0xc38, v81
	ds_write2_b32 v40, v92, v93 offset1:1
	v_add_u32_e32 v40, 0x1040, v81
	ds_write2_b32 v40, v98, v99 offset1:1
	v_add_u32_e32 v40, 0x1048, v81
	ds_write2_b32 v40, v96, v97 offset1:1
	v_add_u32_e32 v40, 0x1450, v81
	ds_write2_b32 v40, v102, v103 offset1:1
	v_add_u32_e32 v40, 0x1458, v81
	ds_write2_b32 v40, v100, v101 offset1:1
	v_add_u32_e32 v40, 0x1860, v81
	ds_write2_b32 v40, v106, v107 offset1:1
	v_add_u32_e32 v40, 0x1868, v81
	ds_write2_b32 v40, v104, v105 offset1:1
	v_add_u32_e32 v40, 0x1c70, v81
	ds_write2_b32 v40, v36, v37 offset1:1
	v_add_u32_e32 v36, 0x1c78, v81
	ds_write2_b32 v36, v38, v39 offset1:1
	v_add_u32_e32 v36, 0x2080, v81
	ds_write2_b32 v36, v34, v35 offset1:1
	v_add_u32_e32 v34, 0x2088, v81
	v_pk_mul_f32 v[6:7], v[46:47], v[8:9] op_sel_hi:[1,0]
	v_pk_mul_f32 v[8:9], v[44:45], v[8:9] op_sel_hi:[1,0]
	ds_write2_b32 v34, v4, v5 offset1:1
	v_add_u32_e32 v4, 0x2490, v81
	ds_write2_b32 v4, v8, v9 offset1:1
	v_add_u32_e32 v4, 0x2498, v81
	ds_write2_b32 v4, v6, v7 offset1:1
	v_add_u32_e32 v4, 0x28a0, v81
	ds_write2_b32 v4, v12, v13 offset1:1
	v_add_u32_e32 v4, 0x28a8, v81
	ds_write2_b32 v4, v10, v11 offset1:1
	v_add_u32_e32 v4, 0x2cb0, v81
	ds_write2_b32 v4, v16, v17 offset1:1
	v_add_u32_e32 v4, 0x2cb8, v81
	ds_write2_b32 v4, v14, v15 offset1:1
	v_add_u32_e32 v4, 0x30c0, v81
	ds_write2_b32 v4, v20, v21 offset1:1
	v_add_u32_e32 v4, 0x30c8, v81
	s_waitcnt vmcnt(1)
	v_pk_mul_f32 v[22:23], v[62:63], v[24:25] op_sel_hi:[1,0]
	v_pk_mul_f32 v[24:25], v[60:61], v[24:25] op_sel_hi:[1,0]
	ds_write2_b32 v4, v18, v19 offset1:1
	v_add_u32_e32 v4, 0x34d0, v81
	ds_write2_b32 v4, v24, v25 offset1:1
	v_add_u32_e32 v4, 0x34d8, v81
	ds_write2_b32 v4, v22, v23 offset1:1
	v_add_u32_e32 v4, 0x38e0, v81
	ds_write2_b32 v4, v28, v29 offset1:1
	v_add_u32_e32 v4, 0x38e8, v81
	ds_write2_b32 v4, v26, v27 offset1:1
	v_add_u32_e32 v4, 0x3cf0, v81
	s_waitcnt vmcnt(0)
	v_pk_mul_f32 v[30:31], v[66:67], v[32:33] op_sel_hi:[1,0]
	v_pk_mul_f32 v[32:33], v[64:65], v[32:33] op_sel_hi:[1,0]
	ds_write2_b32 v4, v32, v33 offset1:1
	v_add_u32_e32 v4, 0x3cf8, v81
	ds_write2_b32 v4, v30, v31 offset1:1
	s_waitcnt lgkmcnt(0)
	ds_read2_b32 v[8:9], v80 offset0:65 offset1:73
	ds_read2_b32 v[14:15], v80 offset1:8
	ds_read2_b32 v[16:17], v80 offset0:130 offset1:138
	ds_read2_b32 v[18:19], v80 offset0:195 offset1:203
	v_lshl_add_u64 v[4:5], s[8:9], 1, v[70:71]
	s_waitcnt lgkmcnt(3)
; #define LAS __attribute__((address_space(3)))
; #define LDS_WAIT() asm volatile("s_waitcnt lgkmcnt(0)" ::: "memory")
; __device__ __forceinline__ unsigned pk2(float lo, float hi) { return f2bf(lo) | (f2bf(hi) << 16); }
;     ...
;     for (int it = gw0; it < items; it += ngw) {
;         const int kb = it / nblk, nb = it % nblk, k0 = 64 * kb, n0 = 64 * nb, nq = (lane & 15) * 4, kr = lane >> 4; const bool ok = (n0 + nq) < N;
;         f32x4 v[16];
; #pragma unroll
;         for (int i = 0; i < 16; ++i) v[i] = ok ? __builtin_nontemporal_load((const f32x4*)(W + (size_t)(k0 + 4 * i + kr) * N + n0 + nq)) : (f32x4){0.f, 0.f, 0.f, 0.f};
;         if (gain) {
; #pragma unroll
;             for (int i = 0; i < 16; ++i) v[i] *= gain[k0 + 4 * i + kr]; }
; #pragma unroll
;         for (int i = 0; i < 16; ++i) { LAS float* d = scr + (4 * i + kr) * 65 + nq; d[0] = v[i].x; d[1] = v[i].y; d[2] = v[i].z; d[3] = v[i].w; }
;         LDS_WAIT(); asm volatile("" ::: "memory");
;         const int c8 = lane & 7; int d0 = n0;
;         if (ffnmap) { const int bj = n0 >= FFH ? 1 : 0, chn = n0 - FFH * bj; d0 = 256 * (chn >> 7) + 128 * bj + (chn & 127); }
; #pragma unroll
;         for (int j = 0; j < 8; ++j) { const int n = (lane >> 3) + 8 * j; const LAS float* sp = scr + (8 * c8) * 65 + n;
;             v4u o; o.x = pk2(sp[0 * 65], sp[1 * 65]); o.y = pk2(sp[2 * 65], sp[3 * 65]); o.z = pk2(sp[4 * 65], sp[5 * 65]); o.w = pk2(sp[6 * 65], sp[7 * 65]);
;             *(v4u*)(WT + (size_t)(d0 + n) * K + k0 + 8 * c8) = o; }
;         LDS_WAIT(); asm volatile("" ::: "memory");
;     }
	v_bfe_u32 v7, v8, 16, 1
	s_waitcnt lgkmcnt(2)
	v_bfe_u32 v6, v14, 16, 1
	v_add3_u32 v6, v14, v6, s16
	v_add3_u32 v7, v8, v7, s16
	v_add_u32_e32 v8, 0x400, v80
	v_lshrrev_b32_e32 v6, 16, v6
	ds_read2_b32 v[20:21], v8 offset0:4 offset1:12
	ds_read2_b32 v[22:23], v8 offset0:69 offset1:77
	v_and_or_b32 v10, v7, s17, v6
	s_waitcnt lgkmcnt(3)
	s_nop 1
	s_waitcnt lgkmcnt(2)
	s_nop 2
	ds_read2_b32 v[24:25], v8 offset0:134 offset1:142
	ds_read2_b32 v[26:27], v8 offset0:199 offset1:207
	v_cvt_pk_bf16_f32 v11, v16, v18
	s_waitcnt lgkmcnt(3)
	s_nop 1
	s_waitcnt lgkmcnt(2)
	s_nop 2
	v_cvt_pk_bf16_f32 v12, v20, v22
	s_waitcnt lgkmcnt(1)
	s_nop 1
	s_waitcnt lgkmcnt(0)
	s_nop 2
	v_cvt_pk_bf16_f32 v13, v24, v26
	v_add_u32_e32 v6, s19, v79
	v_ashrrev_i32_e32 v7, 31, v6
	v_lshlrev_b64 v[28:29], 12, v[6:7]
	v_lshl_add_u64 v[28:29], v[4:5], 0, v[28:29]
	s_nop 0
	global_store_dwordx4 v[28:29], v[10:13], off
	s_nop 3
	v_cvt_pk_bf16_f32 v10, v15, v9
	s_nop 4
	v_cvt_pk_bf16_f32 v11, v17, v19
	s_nop 4
	v_cvt_pk_bf16_f32 v12, v21, v23
	s_nop 0
	v_add_u32_e32 v14, 8, v6
	s_nop 1
	v_ashrrev_i32_e32 v15, 31, v14
	s_nop 1
	v_lshlrev_b64 v[14:15], 12, v[14:15]
	v_cvt_pk_bf16_f32 v13, v25, v27
	v_lshl_add_u64 v[14:15], v[4:5], 0, v[14:15]
	global_store_dwordx4 v[14:15], v[10:13], off
	ds_read2_b32 v[14:15], v80 offset0:81 offset1:89
	ds_read2_b32 v[16:17], v80 offset0:16 offset1:24
	ds_read2_b32 v[18:19], v80 offset0:146 offset1:154
	ds_read2_b32 v[20:21], v80 offset0:211 offset1:219
	ds_read2_b32 v[22:23], v8 offset0:20 offset1:28
	ds_read2_b32 v[24:25], v8 offset0:85 offset1:93
	ds_read2_b32 v[26:27], v8 offset0:150 offset1:158
	ds_read2_b32 v[28:29], v8 offset0:215 offset1:223
	s_waitcnt lgkmcnt(7)
	s_nop 0
	s_waitcnt lgkmcnt(6)
	s_nop 3
	v_cvt_pk_bf16_f32 v10, v16, v14
	s_waitcnt lgkmcnt(5)
	s_nop 1
	s_waitcnt lgkmcnt(4)
	s_nop 2
	v_cvt_pk_bf16_f32 v11, v18, v20
	s_waitcnt lgkmcnt(3)
	s_nop 1
	s_waitcnt lgkmcnt(2)
	s_nop 2
	v_cvt_pk_bf16_f32 v12, v22, v24
	s_waitcnt lgkmcnt(1)
	s_nop 1
	s_waitcnt lgkmcnt(0)
	s_nop 2
	v_add_u32_e32 v30, 16, v6
	v_cvt_pk_bf16_f32 v13, v26, v28
	v_ashrrev_i32_e32 v31, 31, v30
	v_bfe_u32 v7, v17, 16, 1
	v_lshlrev_b64 v[30:31], 12, v[30:31]
	v_add3_u32 v7, v17, v7, s16
	v_bfe_u32 v9, v15, 16, 1
	v_lshl_add_u64 v[30:31], v[4:5], 0, v[30:31]
	v_lshrrev_b32_e32 v7, 16, v7
	v_add3_u32 v9, v15, v9, s16
	global_store_dwordx4 v[30:31], v[10:13], off
	v_add_u32_e32 v14, 24, v6
	v_ashrrev_i32_e32 v15, 31, v14
	v_and_or_b32 v10, v9, s17, v7
	s_nop 4
	v_cvt_pk_bf16_f32 v11, v19, v21
	s_nop 4
	v_cvt_pk_bf16_f32 v12, v23, v25
	s_nop 4
	v_lshlrev_b64 v[14:15], 12, v[14:15]
	v_cvt_pk_bf16_f32 v13, v27, v29
	v_lshl_add_u64 v[14:15], v[4:5], 0, v[14:15]
	global_store_dwordx4 v[14:15], v[10:13], off
	ds_read2_b32 v[14:15], v80 offset0:97 offset1:105
	ds_read2_b32 v[16:17], v80 offset0:32 offset1:40
	ds_read2_b32 v[18:19], v80 offset0:162 offset1:170
	ds_read2_b32 v[20:21], v80 offset0:227 offset1:235
	ds_read2_b32 v[22:23], v8 offset0:36 offset1:44
	ds_read2_b32 v[24:25], v8 offset0:101 offset1:109
	ds_read2_b32 v[26:27], v8 offset0:166 offset1:174
	ds_read2_b32 v[28:29], v8 offset0:231 offset1:239
	s_waitcnt lgkmcnt(7)
	s_nop 0
	s_waitcnt lgkmcnt(6)
	s_nop 3
	v_cvt_pk_bf16_f32 v10, v16, v14
	s_waitcnt lgkmcnt(5)
	s_nop 1
	s_waitcnt lgkmcnt(4)
	s_nop 2
	v_cvt_pk_bf16_f32 v11, v18, v20
	s_waitcnt lgkmcnt(3)
	s_nop 1
	s_waitcnt lgkmcnt(2)
	s_nop 2
	v_cvt_pk_bf16_f32 v12, v22, v24
	s_waitcnt lgkmcnt(1)
	s_nop 1
	s_waitcnt lgkmcnt(0)
	s_nop 2
	v_add_u32_e32 v30, 32, v6
	v_cvt_pk_bf16_f32 v13, v26, v28
	v_ashrrev_i32_e32 v31, 31, v30
	v_bfe_u32 v7, v17, 16, 1
	v_lshlrev_b64 v[30:31], 12, v[30:31]
	v_add3_u32 v7, v17, v7, s16
	v_bfe_u32 v9, v15, 16, 1
	v_lshl_add_u64 v[30:31], v[4:5], 0, v[30:31]
	v_lshrrev_b32_e32 v7, 16, v7
	v_add3_u32 v9, v15, v9, s16
	global_store_dwordx4 v[30:31], v[10:13], off
	v_add_u32_e32 v14, 40, v6
	v_ashrrev_i32_e32 v15, 31, v14
	v_and_or_b32 v10, v9, s17, v7
	s_nop 4
	v_cvt_pk_bf16_f32 v11, v19, v21
	s_nop 4
	v_cvt_pk_bf16_f32 v12, v23, v25
	s_nop 4
	v_lshlrev_b64 v[14:15], 12, v[14:15]
	v_cvt_pk_bf16_f32 v13, v27, v29
	v_lshl_add_u64 v[14:15], v[4:5], 0, v[14:15]
	global_store_dwordx4 v[14:15], v[10:13], off
	ds_read2_b32 v[14:15], v80 offset0:48 offset1:56
	ds_read2_b32 v[16:17], v80 offset0:113 offset1:121
	ds_read2_b32 v[18:19], v80 offset0:178 offset1:186
	ds_read2_b32 v[20:21], v80 offset0:243 offset1:251
	ds_read2_b32 v[22:23], v8 offset0:52 offset1:60
	ds_read2_b32 v[24:25], v8 offset0:117 offset1:125
	ds_read2_b32 v[26:27], v8 offset0:182 offset1:190
	ds_read2_b32 v[28:29], v8 offset0:247 offset1:255
	s_waitcnt lgkmcnt(7)
	s_nop 1
	s_waitcnt lgkmcnt(6)
	s_nop 2
	v_cvt_pk_bf16_f32 v10, v14, v16
	s_waitcnt lgkmcnt(5)
	s_nop 1
	s_waitcnt lgkmcnt(4)
	s_nop 2
	v_cvt_pk_bf16_f32 v11, v18, v20
	s_waitcnt lgkmcnt(3)
	s_nop 1
	s_waitcnt lgkmcnt(2)
	s_nop 2
	v_cvt_pk_bf16_f32 v12, v22, v24
	s_waitcnt lgkmcnt(1)
	s_nop 1
	s_waitcnt lgkmcnt(0)
	s_nop 2
	v_cvt_pk_bf16_f32 v13, v26, v28
	v_add_u32_e32 v8, 48, v6
	v_ashrrev_i32_e32 v9, 31, v8
	v_lshlrev_b64 v[8:9], 12, v[8:9]
	v_lshl_add_u64 v[8:9], v[4:5], 0, v[8:9]
	s_nop 0
	global_store_dwordx4 v[8:9], v[10:13], off
	s_nop 3
	v_cvt_pk_bf16_f32 v8, v15, v17
	s_nop 4
	v_cvt_pk_bf16_f32 v9, v19, v21
	s_nop 4
	v_cvt_pk_bf16_f32 v10, v23, v25
	s_nop 4
	v_add_u32_e32 v6, 56, v6
	v_cvt_pk_bf16_f32 v11, v27, v29
	v_ashrrev_i32_e32 v7, 31, v6
	v_lshlrev_b64 v[6:7], 12, v[6:7]
	v_lshl_add_u64 v[4:5], v[4:5], 0, v[6:7]
	global_store_dwordx4 v[4:5], v[8:11], off
	s_waitcnt lgkmcnt(0)
	s_cbranch_scc0 .LBB0_2683

; #define LAS __attribute__((address_space(3)))
; #define LDS_WAIT() asm volatile("s_waitcnt lgkmcnt(0)" ::: "memory")
; __device__ __forceinline__ unsigned pk2(float lo, float hi) { return f2bf(lo) | (f2bf(hi) << 16); }
;     ...
;     for (int it = gw0; it < items; it += ngw) {
;         const int kb = it / nblk, nb = it % nblk, k0 = 64 * kb, n0 = 64 * nb, nq = (lane & 15) * 4, kr = lane >> 4; const bool ok = (n0 + nq) < N;
;         f32x4 v[16];
; #pragma unroll
;         for (int i = 0; i < 16; ++i) v[i] = ok ? __builtin_nontemporal_load((const f32x4*)(W + (size_t)(k0 + 4 * i + kr) * N + n0 + nq)) : (f32x4){0.f, 0.f, 0.f, 0.f};
;         if (gain) {
; #pragma unroll
;             for (int i = 0; i < 16; ++i) v[i] *= gain[k0 + 4 * i + kr]; }
; #pragma unroll
;         for (int i = 0; i < 16; ++i) { LAS float* d = scr + (4 * i + kr) * 65 + nq; d[0] = v[i].x; d[1] = v[i].y; d[2] = v[i].z; d[3] = v[i].w; }
;         LDS_WAIT(); asm volatile("" ::: "memory");
;         const int c8 = lane & 7; int d0 = n0;
;         if (ffnmap) { const int bj = n0 >= FFH ? 1 : 0, chn = n0 - FFH * bj; d0 = 256 * (chn >> 7) + 128 * bj + (chn & 127); }
; #pragma unroll
;         for (int j = 0; j < 8; ++j) { const int n = (lane >> 3) + 8 * j; const LAS float* sp = scr + (8 * c8) * 65 + n;
;             v4u o; o.x = pk2(sp[0 * 65], sp[1 * 65]); o.y = pk2(sp[2 * 65], sp[3 * 65]); o.z = pk2(sp[4 * 65], sp[5 * 65]); o.w = pk2(sp[6 * 65], sp[7 * 65]);
;             *(v4u*)(WT + (size_t)(d0 + n) * K + k0 + 8 * c8) = o; }
;         LDS_WAIT(); asm volatile("" ::: "memory");
;     }
.LBB0_2685:
	s_or_b64 exec, exec, s[8:9]
	s_waitcnt vmcnt(0)
	ds_write2_b32 v79, v4, v5 offset1:1
	ds_write2_b32 v79, v6, v7 offset0:2 offset1:3
	v_add_u32_e32 v4, 0x410, v79
	ds_write2_b32 v4, v12, v13 offset1:1
	v_add_u32_e32 v4, 0x418, v79
	ds_write2_b32 v4, v14, v15 offset1:1
	v_add_u32_e32 v4, 0x820, v79
	ds_write2_b32 v4, v8, v9 offset1:1
	v_add_u32_e32 v4, 0x828, v79
	ds_write2_b32 v4, v10, v11 offset1:1
	v_add_u32_e32 v4, 0xc30, v79
	ds_write2_b32 v4, v20, v21 offset1:1
	v_add_u32_e32 v4, 0xc38, v79
	ds_write2_b32 v4, v22, v23 offset1:1
	v_add_u32_e32 v4, 0x1040, v79
	ds_write2_b32 v4, v16, v17 offset1:1
	v_add_u32_e32 v4, 0x1048, v79
	ds_write2_b32 v4, v18, v19 offset1:1
	v_add_u32_e32 v4, 0x1450, v79
	ds_write2_b32 v4, v28, v29 offset1:1
	v_add_u32_e32 v4, 0x1458, v79
	ds_write2_b32 v4, v30, v31 offset1:1
	v_add_u32_e32 v4, 0x1860, v79
	ds_write2_b32 v4, v24, v25 offset1:1
	v_add_u32_e32 v4, 0x1868, v79
	ds_write2_b32 v4, v26, v27 offset1:1
	v_add_u32_e32 v4, 0x1c70, v79
	ds_write2_b32 v4, v36, v37 offset1:1
	v_add_u32_e32 v4, 0x1c78, v79
	ds_write2_b32 v4, v38, v39 offset1:1
	v_add_u32_e32 v4, 0x2080, v79
	ds_write2_b32 v4, v32, v33 offset1:1
	v_add_u32_e32 v4, 0x2088, v79
	ds_write2_b32 v4, v34, v35 offset1:1
	v_add_u32_e32 v4, 0x2490, v79
	ds_write2_b32 v4, v44, v45 offset1:1
	v_add_u32_e32 v4, 0x2498, v79
	ds_write2_b32 v4, v46, v47 offset1:1
	v_add_u32_e32 v4, 0x28a0, v79
	ds_write2_b32 v4, v40, v41 offset1:1
	v_add_u32_e32 v4, 0x28a8, v79
	ds_write2_b32 v4, v42, v43 offset1:1
	v_add_u32_e32 v4, 0x2cb0, v79
	ds_write2_b32 v4, v52, v53 offset1:1
	v_add_u32_e32 v4, 0x2cb8, v79
	ds_write2_b32 v4, v54, v55 offset1:1
	v_add_u32_e32 v4, 0x30c0, v79
	ds_write2_b32 v4, v48, v49 offset1:1
	v_add_u32_e32 v4, 0x30c8, v79
	ds_write2_b32 v4, v50, v51 offset1:1
	v_add_u32_e32 v4, 0x34d0, v79
	ds_write2_b32 v4, v60, v61 offset1:1
	v_add_u32_e32 v4, 0x34d8, v79
	ds_write2_b32 v4, v62, v63 offset1:1
	v_add_u32_e32 v4, 0x38e0, v79
	ds_write2_b32 v4, v56, v57 offset1:1
	v_add_u32_e32 v4, 0x38e8, v79
	ds_write2_b32 v4, v58, v59 offset1:1
	v_add_u32_e32 v4, 0x3cf0, v79
	ds_write2_b32 v4, v64, v65 offset1:1
	v_add_u32_e32 v4, 0x3cf8, v79
	ds_write2_b32 v4, v66, v67 offset1:1
	s_waitcnt lgkmcnt(0)
	ds_read2_b32 v[12:13], v78 offset1:8
	ds_read2_b32 v[14:15], v78 offset0:65 offset1:73
	ds_read2_b32 v[16:17], v78 offset0:130 offset1:138
	ds_read2_b32 v[18:19], v78 offset0:195 offset1:203
	v_add_u32_e32 v30, 0x400, v78
	s_waitcnt lgkmcnt(3)
	s_nop 1
	s_waitcnt lgkmcnt(2)
	s_nop 0
	ds_read2_b32 v[20:21], v30 offset0:4 offset1:12
	s_nop 1
	ds_read2_b32 v[22:23], v30 offset0:69 offset1:77
	v_cvt_pk_bf16_f32 v8, v12, v14
	s_waitcnt lgkmcnt(3)
	s_nop 1
	s_waitcnt lgkmcnt(2)
	s_nop 0
	ds_read2_b32 v[24:25], v30 offset0:134 offset1:142
	s_nop 1
	ds_read2_b32 v[26:27], v30 offset0:199 offset1:207
	v_cvt_pk_bf16_f32 v9, v16, v18
	s_waitcnt lgkmcnt(3)
	s_nop 1
	s_waitcnt lgkmcnt(2)
	s_nop 2
	v_cvt_pk_bf16_f32 v10, v20, v22
	s_waitcnt lgkmcnt(1)
	s_nop 1
	s_waitcnt lgkmcnt(0)
	s_nop 2
	s_add_i32 s16, s16, s10
	v_cvt_pk_bf16_f32 v11, v24, v26
	v_add_u32_e32 v6, s16, v77
	s_ashr_i32 s1, s0, 31
	v_ashrrev_i32_e32 v7, 31, v6
	v_lshl_add_u64 v[4:5], s[0:1], 1, v[70:71]
	v_lshlrev_b64 v[28:29], 13, v[6:7]
	v_lshl_add_u64 v[28:29], v[4:5], 0, v[28:29]
	s_nop 0
	global_store_dwordx4 v[28:29], v[8:11], off
	s_nop 3
	v_cvt_pk_bf16_f32 v8, v13, v15
	s_nop 4
	v_cvt_pk_bf16_f32 v9, v17, v19
	s_nop 4
	v_cvt_pk_bf16_f32 v10, v21, v23
	s_nop 0
	v_add_u32_e32 v12, 8, v6
	s_nop 1
	v_ashrrev_i32_e32 v13, 31, v12
	s_nop 1
	v_lshlrev_b64 v[12:13], 13, v[12:13]
	v_cvt_pk_bf16_f32 v11, v25, v27
	ds_read2_b32 v[14:15], v78 offset0:16 offset1:24
	v_lshl_add_u64 v[12:13], v[4:5], 0, v[12:13]
	global_store_dwordx4 v[12:13], v[8:11], off
	ds_read2_b32 v[12:13], v78 offset0:81 offset1:89
	ds_read2_b32 v[16:17], v78 offset0:146 offset1:154
	ds_read2_b32 v[18:19], v78 offset0:211 offset1:219
	s_waitcnt lgkmcnt(3)
	s_nop 1
	s_waitcnt lgkmcnt(2)
; #define LAS __attribute__((address_space(3)))
; #define LDS_WAIT() asm volatile("s_waitcnt lgkmcnt(0)" ::: "memory")
; __device__ __forceinline__ unsigned pk2(float lo, float hi) { return f2bf(lo) | (f2bf(hi) << 16); }
;     ...
;     for (int it = gw0; it < items; it += ngw) {
;         const int kb = it / nblk, nb = it % nblk, k0 = 64 * kb, n0 = 64 * nb, nq = (lane & 15) * 4, kr = lane >> 4; const bool ok = (n0 + nq) < N;
;         f32x4 v[16];
; #pragma unroll
;         for (int i = 0; i < 16; ++i) v[i] = ok ? __builtin_nontemporal_load((const f32x4*)(W + (size_t)(k0 + 4 * i + kr) * N + n0 + nq)) : (f32x4){0.f, 0.f, 0.f, 0.f};
;         if (gain) {
; #pragma unroll
;             for (int i = 0; i < 16; ++i) v[i] *= gain[k0 + 4 * i + kr]; }
; #pragma unroll
;         for (int i = 0; i < 16; ++i) { LAS float* d = scr + (4 * i + kr) * 65 + nq; d[0] = v[i].x; d[1] = v[i].y; d[2] = v[i].z; d[3] = v[i].w; }
;         LDS_WAIT(); asm volatile("" ::: "memory");
;         const int c8 = lane & 7; int d0 = n0;
;         if (ffnmap) { const int bj = n0 >= FFH ? 1 : 0, chn = n0 - FFH * bj; d0 = 256 * (chn >> 7) + 128 * bj + (chn & 127); }
; #pragma unroll
;         for (int j = 0; j < 8; ++j) { const int n = (lane >> 3) + 8 * j; const LAS float* sp = scr + (8 * c8) * 65 + n;
;             v4u o; o.x = pk2(sp[0 * 65], sp[1 * 65]); o.y = pk2(sp[2 * 65], sp[3 * 65]); o.z = pk2(sp[4 * 65], sp[5 * 65]); o.w = pk2(sp[6 * 65], sp[7 * 65]);
;             *(v4u*)(WT + (size_t)(d0 + n) * K + k0 + 8 * c8) = o; }
;         LDS_WAIT(); asm volatile("" ::: "memory");
;     }
	s_nop 0
	ds_read2_b32 v[20:21], v30 offset0:20 offset1:28
	s_nop 1
	ds_read2_b32 v[22:23], v30 offset0:85 offset1:93
	v_cvt_pk_bf16_f32 v8, v14, v12
	s_waitcnt lgkmcnt(3)
	s_nop 1
	s_waitcnt lgkmcnt(2)
	s_nop 0
	ds_read2_b32 v[24:25], v30 offset0:150 offset1:158
	s_nop 1
	ds_read2_b32 v[26:27], v30 offset0:215 offset1:223
	v_cvt_pk_bf16_f32 v9, v16, v18
	s_waitcnt lgkmcnt(3)
	s_nop 1
	s_waitcnt lgkmcnt(2)
	s_nop 2
	v_cvt_pk_bf16_f32 v10, v20, v22
	s_waitcnt lgkmcnt(1)
	s_nop 0
	v_add_u32_e32 v28, 16, v6
	s_nop 0
	s_waitcnt lgkmcnt(0)
	s_nop 0
	v_ashrrev_i32_e32 v29, 31, v28
	s_nop 1
	v_lshlrev_b64 v[28:29], 13, v[28:29]
	v_cvt_pk_bf16_f32 v11, v24, v26
	v_lshl_add_u64 v[28:29], v[4:5], 0, v[28:29]
	s_nop 0
	global_store_dwordx4 v[28:29], v[8:11], off
	s_nop 3
	v_cvt_pk_bf16_f32 v8, v15, v13
	s_nop 4
	v_cvt_pk_bf16_f32 v9, v17, v19
	s_nop 4
	v_cvt_pk_bf16_f32 v10, v21, v23
	s_nop 0
	v_add_u32_e32 v12, 24, v6
	s_nop 1
	v_ashrrev_i32_e32 v13, 31, v12
	s_nop 1
	v_lshlrev_b64 v[12:13], 13, v[12:13]
	v_cvt_pk_bf16_f32 v11, v25, v27
	ds_read2_b32 v[14:15], v78 offset0:32 offset1:40
	v_lshl_add_u64 v[12:13], v[4:5], 0, v[12:13]
	global_store_dwordx4 v[12:13], v[8:11], off
	ds_read2_b32 v[12:13], v78 offset0:97 offset1:105
	ds_read2_b32 v[16:17], v78 offset0:162 offset1:170
	ds_read2_b32 v[18:19], v78 offset0:227 offset1:235
	s_waitcnt lgkmcnt(3)
	s_nop 1
	s_waitcnt lgkmcnt(2)
	s_nop 0
	ds_read2_b32 v[20:21], v30 offset0:36 offset1:44
	s_nop 1
	ds_read2_b32 v[22:23], v30 offset0:101 offset1:109
	v_cvt_pk_bf16_f32 v8, v14, v12
	s_waitcnt lgkmcnt(3)
	s_nop 1
	s_waitcnt lgkmcnt(2)
	s_nop 0
	ds_read2_b32 v[24:25], v30 offset0:166 offset1:174
	s_nop 1
	ds_read2_b32 v[26:27], v30 offset0:231 offset1:239
	v_cvt_pk_bf16_f32 v9, v16, v18
	s_waitcnt lgkmcnt(3)
	s_nop 1
	s_waitcnt lgkmcnt(2)
	s_nop 2
	v_cvt_pk_bf16_f32 v10, v20, v22
	s_waitcnt lgkmcnt(1)
	s_nop 0
	v_add_u32_e32 v28, 32, v6
	s_nop 0
	s_waitcnt lgkmcnt(0)
	s_nop 0
	v_ashrrev_i32_e32 v29, 31, v28
	s_nop 1
	v_lshlrev_b64 v[28:29], 13, v[28:29]
	v_cvt_pk_bf16_f32 v11, v24, v26
	v_lshl_add_u64 v[28:29], v[4:5], 0, v[28:29]
	s_nop 0
	global_store_dwordx4 v[28:29], v[8:11], off
	s_nop 3
	v_cvt_pk_bf16_f32 v8, v15, v13
	s_nop 4
	v_cvt_pk_bf16_f32 v9, v17, v19
	s_nop 4
	v_cvt_pk_bf16_f32 v10, v21, v23
	s_nop 0
	v_add_u32_e32 v12, 40, v6
	s_nop 1
	v_ashrrev_i32_e32 v13, 31, v12
	s_nop 1
	v_lshlrev_b64 v[12:13], 13, v[12:13]
	v_cvt_pk_bf16_f32 v11, v25, v27
	ds_read2_b32 v[14:15], v78 offset0:48 offset1:56
	v_lshl_add_u64 v[12:13], v[4:5], 0, v[12:13]
	global_store_dwordx4 v[12:13], v[8:11], off
	ds_read2_b32 v[12:13], v78 offset0:113 offset1:121
	ds_read2_b32 v[16:17], v78 offset0:178 offset1:186
	ds_read2_b32 v[18:19], v78 offset0:243 offset1:251
	s_waitcnt lgkmcnt(3)
	s_nop 1
	s_waitcnt lgkmcnt(2)
	s_nop 0
	ds_read2_b32 v[20:21], v30 offset0:52 offset1:60
	s_nop 1
	ds_read2_b32 v[22:23], v30 offset0:117 offset1:125
	v_cvt_pk_bf16_f32 v8, v14, v12
	s_waitcnt lgkmcnt(3)
	s_nop 1
	s_waitcnt lgkmcnt(2)
	s_nop 0
	ds_read2_b32 v[24:25], v30 offset0:182 offset1:190
	s_nop 1
	ds_read2_b32 v[26:27], v30 offset0:247 offset1:255
	v_cvt_pk_bf16_f32 v9, v16, v18
	s_waitcnt lgkmcnt(3)
	s_nop 1
	s_waitcnt lgkmcnt(2)
	s_nop 2
	v_cvt_pk_bf16_f32 v10, v20, v22
	s_waitcnt lgkmcnt(1)
	s_nop 0
	v_add_u32_e32 v28, 48, v6
	s_nop 0
	s_waitcnt lgkmcnt(0)
	s_nop 0
	v_ashrrev_i32_e32 v29, 31, v28
	s_nop 1
	v_lshlrev_b64 v[28:29], 13, v[28:29]
	v_cvt_pk_bf16_f32 v11, v24, v26
	v_lshl_add_u64 v[28:29], v[4:5], 0, v[28:29]
	s_nop 0
	global_store_dwordx4 v[28:29], v[8:11], off
	s_nop 3
	v_cvt_pk_bf16_f32 v8, v15, v13
	s_nop 4
	v_cvt_pk_bf16_f32 v9, v17, v19
	s_nop 4
	v_cvt_pk_bf16_f32 v10, v21, v23
	s_nop 4
	v_add_u32_e32 v6, 56, v6
	v_cvt_pk_bf16_f32 v11, v25, v27
	v_ashrrev_i32_e32 v7, 31, v6
	v_lshlrev_b64 v[6:7], 13, v[6:7]
	v_lshl_add_u64 v[4:5], v[4:5], 0, v[6:7]
	global_store_dwordx4 v[4:5], v[8:11], off
	s_waitcnt lgkmcnt(0)
	s_add_i32 s12, s12, s13
	s_add_i32 s10, s10, s11
	s_cmpk_lt_i32 s12, 0x800
	s_cbranch_scc0 .LBB0_2718

; __device__ __forceinline__ unsigned pk2(float lo, float hi) { return f2bf(lo) | (f2bf(hi) << 16); }
; __device__ __forceinline__ void xa_attn_fa(const Ctx& c, const bf16* Q, const bf16* KV, const bf16* XVT, bf16* Oo) {
;     ...
;         for (int mi = 0; mi < 2; ++mi) { float lt = l[mi]; lt += __shfl_xor(lt, 16); lt += __shfl_xor(lt, 32); const float il = 1.f / lt;
; #pragma unroll
;             for (int dt = 0; dt < 8; ++dt) { const f32x4 o = O[dt][mi] * il; v2u w; w.x = pk2(o[0], o[1]); w.y = pk2(o[2], o[3]);
;                 *(v2u*)(Oo + grow[mi] * 512 + hd * 128 + 16 * dt + 4 * lg) = w; } }
.LBB0_2774:
	v_mul_f32_e32 v4, 0x3e800000, v128
	ds_bpermute_b32 v4, v167, v4
	s_lshl_b32 s6, s23, 1
	v_lshl_add_u64 v[6:7], v[172:173], 0, s[6:7]
	v_lshl_add_u64 v[42:43], v[6:7], 0, v[188:189]
	v_mul_f32_e32 v48, 0x3e800000, v40
	s_waitcnt lgkmcnt(0)
	v_fmac_f32_e32 v4, 0x3e800000, v128
	ds_bpermute_b32 v41, v196, v4
	v_lshl_add_u64 v[6:7], v[6:7], 0, v[186:187]
	s_add_i32 s22, s22, s33
	s_cmpk_lt_i32 s22, 0x100
	s_waitcnt lgkmcnt(0)
	v_add_f32_e32 v4, v4, v41
	v_div_scale_f32 v41, s[12:13], v4, v4, 1.0
	v_rcp_f32_e32 v44, v41
	v_div_scale_f32 v45, vcc, 1.0, v4, 1.0
	v_fma_f32 v46, -v41, v44, 1.0
	v_fmac_f32_e32 v44, v46, v44
	v_mul_f32_e32 v46, v45, v44
	v_fma_f32 v47, -v41, v46, v45
	v_fmac_f32_e32 v46, v47, v44
	v_fma_f32 v41, -v41, v46, v45
	v_div_fmas_f32 v41, v41, v44, v46
	v_div_fixup_f32 v4, v41, v4, 1.0
	v_pk_mul_f32 v[46:47], v[104:105], v[4:5] op_sel_hi:[1,0]
	v_pk_mul_f32 v[44:45], v[106:107], v[4:5] op_sel_hi:[1,0]
	s_nop 4
	v_cvt_pk_bf16_f32 v46, v46, v47
	s_nop 4
	v_cvt_pk_bf16_f32 v47, v44, v45
	global_store_dwordx2 v[42:43], v[46:47], off
	v_pk_mul_f32 v[46:47], v[100:101], v[4:5] op_sel_hi:[1,0]
	v_pk_mul_f32 v[44:45], v[102:103], v[4:5] op_sel_hi:[1,0]
	s_nop 4
	v_cvt_pk_bf16_f32 v46, v46, v47
	s_nop 4
	v_cvt_pk_bf16_f32 v47, v44, v45
	global_store_dwordx2 v[42:43], v[46:47], off offset:32
	v_pk_mul_f32 v[46:47], v[96:97], v[4:5] op_sel_hi:[1,0]
	v_pk_mul_f32 v[44:45], v[98:99], v[4:5] op_sel_hi:[1,0]
	s_nop 4
	v_cvt_pk_bf16_f32 v46, v46, v47
	s_nop 4
	v_cvt_pk_bf16_f32 v47, v44, v45
	global_store_dwordx2 v[42:43], v[46:47], off offset:64
	v_pk_mul_f32 v[46:47], v[92:93], v[4:5] op_sel_hi:[1,0]
	v_pk_mul_f32 v[44:45], v[94:95], v[4:5] op_sel_hi:[1,0]
	s_nop 4
	v_cvt_pk_bf16_f32 v46, v46, v47
	s_nop 4
	v_cvt_pk_bf16_f32 v47, v44, v45
	global_store_dwordx2 v[42:43], v[46:47], off offset:96
	v_pk_mul_f32 v[46:47], v[88:89], v[4:5] op_sel_hi:[1,0]
	v_pk_mul_f32 v[44:45], v[90:91], v[4:5] op_sel_hi:[1,0]
	s_nop 4
	v_cvt_pk_bf16_f32 v46, v46, v47
	s_nop 4
	v_cvt_pk_bf16_f32 v47, v44, v45
	global_store_dwordx2 v[42:43], v[46:47], off offset:128
	v_pk_mul_f32 v[46:47], v[84:85], v[4:5] op_sel_hi:[1,0]
	v_pk_mul_f32 v[44:45], v[86:87], v[4:5] op_sel_hi:[1,0]
	s_nop 4
	v_cvt_pk_bf16_f32 v46, v46, v47
	s_nop 4
	v_cvt_pk_bf16_f32 v47, v44, v45
	global_store_dwordx2 v[42:43], v[46:47], off offset:160
	v_pk_mul_f32 v[46:47], v[80:81], v[4:5] op_sel_hi:[1,0]
	v_pk_mul_f32 v[44:45], v[82:83], v[4:5] op_sel_hi:[1,0]
	s_nop 4
	v_cvt_pk_bf16_f32 v46, v46, v47
	s_nop 4
	v_cvt_pk_bf16_f32 v47, v44, v45
	ds_bpermute_b32 v41, v167, v48
	global_store_dwordx2 v[42:43], v[46:47], off offset:192
	v_pk_mul_f32 v[46:47], v[76:77], v[4:5] op_sel_hi:[1,0]
	v_pk_mul_f32 v[44:45], v[78:79], v[4:5] op_sel_hi:[1,0]
	s_nop 4
	s_waitcnt lgkmcnt(0)
	v_fmac_f32_e32 v41, 0x3e800000, v40
	v_cvt_pk_bf16_f32 v46, v46, v47
	ds_bpermute_b32 v4, v196, v41
	s_nop 3
	s_waitcnt lgkmcnt(0)
	v_add_f32_e32 v4, v41, v4
	v_div_scale_f32 v41, s[12:13], v4, v4, 1.0
	v_rcp_f32_e32 v48, v41
	s_nop 0
	v_cvt_pk_bf16_f32 v47, v44, v45
	global_store_dwordx2 v[42:43], v[46:47], off offset:224
	v_fma_f32 v40, -v41, v48, 1.0
	v_fmac_f32_e32 v48, v40, v48
	v_div_scale_f32 v40, vcc, 1.0, v4, 1.0
	v_mul_f32_e32 v42, v40, v48
	v_fma_f32 v43, -v41, v42, v40
	v_fmac_f32_e32 v42, v43, v48
	v_fma_f32 v40, -v41, v42, v40
	v_div_fmas_f32 v40, v40, v48, v42
	v_div_fixup_f32 v4, v40, v4, 1.0
	v_pk_mul_f32 v[36:37], v[36:37], v[4:5] op_sel_hi:[1,0]
	v_pk_mul_f32 v[38:39], v[38:39], v[4:5] op_sel_hi:[1,0]
	s_nop 4
	v_cvt_pk_bf16_f32 v36, v36, v37
	s_nop 4
	v_cvt_pk_bf16_f32 v37, v38, v39
	v_pk_mul_f32 v[32:33], v[32:33], v[4:5] op_sel_hi:[1,0]
	global_store_dwordx2 v[6:7], v[36:37], off
	s_nop 2
	v_pk_mul_f32 v[34:35], v[34:35], v[4:5] op_sel_hi:[1,0]
	s_nop 1
	v_cvt_pk_bf16_f32 v32, v32, v33
	s_nop 4
	v_cvt_pk_bf16_f32 v33, v34, v35
	v_pk_mul_f32 v[28:29], v[28:29], v[4:5] op_sel_hi:[1,0]
	global_store_dwordx2 v[6:7], v[32:33], off offset:32
	s_nop 2
	v_pk_mul_f32 v[30:31], v[30:31], v[4:5] op_sel_hi:[1,0]
	s_nop 1
	v_cvt_pk_bf16_f32 v28, v28, v29
	s_nop 4
	v_cvt_pk_bf16_f32 v29, v30, v31
	v_pk_mul_f32 v[24:25], v[24:25], v[4:5] op_sel_hi:[1,0]
	global_store_dwordx2 v[6:7], v[28:29], off offset:64
	s_nop 2
	v_pk_mul_f32 v[26:27], v[26:27], v[4:5] op_sel_hi:[1,0]
	s_nop 1
	v_cvt_pk_bf16_f32 v24, v24, v25
	s_nop 4
	v_cvt_pk_bf16_f32 v25, v26, v27
	v_pk_mul_f32 v[20:21], v[20:21], v[4:5] op_sel_hi:[1,0]
	global_store_dwordx2 v[6:7], v[24:25], off offset:96
	s_nop 2
	v_pk_mul_f32 v[22:23], v[22:23], v[4:5] op_sel_hi:[1,0]
	s_nop 1
	v_cvt_pk_bf16_f32 v20, v20, v21
	s_nop 4
	v_cvt_pk_bf16_f32 v21, v22, v23
	v_pk_mul_f32 v[16:17], v[16:17], v[4:5] op_sel_hi:[1,0]
	global_store_dwordx2 v[6:7], v[20:21], off offset:128
	s_nop 2
	v_pk_mul_f32 v[18:19], v[18:19], v[4:5] op_sel_hi:[1,0]
	s_nop 1
	v_cvt_pk_bf16_f32 v16, v16, v17
	s_nop 4
	v_cvt_pk_bf16_f32 v17, v18, v19
	v_pk_mul_f32 v[12:13], v[12:13], v[4:5] op_sel_hi:[1,0]
	v_pk_mul_f32 v[8:9], v[8:9], v[4:5] op_sel_hi:[1,0]
	global_store_dwordx2 v[6:7], v[16:17], off offset:160
	v_pk_mul_f32 v[14:15], v[14:15], v[4:5] op_sel_hi:[1,0]
	s_nop 0
	v_pk_mul_f32 v[10:11], v[10:11], v[4:5] op_sel_hi:[1,0]
	s_nop 7
	s_nop 0
	v_cvt_pk_bf16_f32 v12, v12, v13
	s_nop 0
	v_cvt_pk_bf16_f32 v8, v8, v9
	v_bfe_u32 v4, v10, 16, 1
	s_nop 1
	v_add3_u32 v4, v10, v4, s20
	v_bfe_u32 v9, v11, 16, 1
	s_nop 1
	v_lshrrev_b32_e32 v4, 16, v4
	v_add3_u32 v9, v11, v9, s20
	v_cvt_pk_bf16_f32 v13, v14, v15
	v_and_or_b32 v9, v9, s21, v4
	global_store_dwordx2 v[6:7], v[12:13], off offset:192
	global_store_dwordx2 v[6:7], v[8:9], off offset:224
	s_cbranch_scc0 .LBB0_2786

; __device__ __forceinline__ unsigned pk2(float lo, float hi) { return f2bf(lo) | (f2bf(hi) << 16); }
; __device__ __forceinline__ float silu_fast(float x) { return x * __builtin_amdgcn_rcpf(1.f + __builtin_amdgcn_exp2f(-1.4426950408889634f * x)); }
; __device__ __forceinline__ float dpp_shr1(float x) { return __builtin_bit_cast(float, __builtin_amdgcn_update_dpp(0, __builtin_bit_cast(int, x), 0x111, 0xf, 0xf, true)); }
;     __device__ __forceinline__ void operator()(const f32x4 (&acc)[2][2][4][2], const pg8::Unit& u, int wr, int wc, int fr, int fq) const {
;     ...
;             const int cc = ch0 + 4 * n;
;             const f32x4 wg0 = *(CF4)(cw + cc), wg1 = *(CF4)(cw + FF2 + cc), wg2 = *(CF4)(cw + 2 * FF2 + cc), wv0 = *(CF4)(cw + FFH + cc), wv1 = *(CF4)(cw + FF2 + FFH + cc), wv2 = *(CF4)(cw + 2 * FF2 + FFH + cc);
;             const f32x4 bg = *(CF4)(cb + cc), bv = *(CF4)(cb + FFH + cc);
; #pragma unroll
;             for (int jj = 0; jj < 4; ++jj) {
;                 float g2 = dpp_shr1(g[6][jj]), g1 = dpp_shr1(g[7][jj]), v2 = dpp_shr1(v[6][jj]), v1 = dpp_shr1(v[7][jj]);
; #pragma unroll
;                 for (int e = 0; e < 8; ++e) { const float g0 = g[e][jj], v0 = v[e][jj];
;                     const float cg = bg[jj] + wg0[jj] * g2 + wg1[jj] * g1 + wg2[jj] * g0, cv = bv[jj] + wv0[jj] * v2 + wv1[jj] * v1 + wv2[jj] * v0;
;                     g[e][jj] = silu_fast(cg) * cv; g2 = g1; g1 = g0; v2 = v1; v1 = v0; } }
; #pragma unroll
;             for (int e = 0; e < 8; ++e) { v2u w; w.x = pk2(g[e][0], g[e][1]); w.y = pk2(g[e][2], g[e][3]); *(v2u*)(ACT + (size_t)(tok0 + e) * FFH + cc) = w; }
.LBB0_2979:
	s_or_b64 exec, exec, s[36:37]
	v_or_b32_e32 v38, 4, v132
	v_ashrrev_i32_e32 v39, 31, v38
	v_lshlrev_b64 v[64:65], 2, v[38:39]
	v_lshl_add_u64 v[38:39], s[8:9], 0, v[64:65]
	v_lshl_add_u64 v[44:45], s[20:21], 0, v[64:65]
	v_lshl_add_u64 v[66:67], s[10:11], 0, v[64:65]
	global_load_dwordx4 v[52:55], v[38:39], off
	v_lshl_add_u64 v[48:49], s[22:23], 0, v[64:65]
	global_load_dwordx4 v[44:47], v[44:45], off
	v_lshl_add_u64 v[38:39], s[14:15], 0, v[64:65]
	global_load_dwordx4 v[68:71], v[66:67], off
	global_load_dwordx4 v[56:59], v[38:39], off
	v_mov_b32_dpp v106, v88 row_shr:1 row_mask:0xf bank_mask:0xf bound_ctrl:1
	global_load_dwordx4 v[48:51], v[48:49], off
	v_lshl_add_u64 v[38:39], s[16:17], 0, v[64:65]
	global_load_dwordx4 v[60:63], v[38:39], off
	v_lshl_add_u64 v[38:39], s[18:19], 0, v[64:65]
	global_load_dwordx4 v[38:41], v[38:39], off
	v_lshl_add_u64 v[64:65], s[24:25], 0, v[64:65]
	global_load_dwordx4 v[64:67], v[64:65], off
	v_mov_b32_dpp v107, v89 row_shr:1 row_mask:0xf bank_mask:0xf bound_ctrl:1
	v_mov_b32_dpp v138, v94 row_shr:1 row_mask:0xf bank_mask:0xf bound_ctrl:1
	v_mov_b32_dpp v139, v95 row_shr:1 row_mask:0xf bank_mask:0xf bound_ctrl:1
	v_mov_b32_dpp v160, v86 row_shr:1 row_mask:0xf bank_mask:0xf bound_ctrl:1
	v_mov_b32_dpp v161, v87 row_shr:1 row_mask:0xf bank_mask:0xf bound_ctrl:1
	v_mov_b32_dpp v136, v90 row_shr:1 row_mask:0xf bank_mask:0xf bound_ctrl:1
	v_mov_b32_dpp v137, v91 row_shr:1 row_mask:0xf bank_mask:0xf bound_ctrl:1
	v_mov_b32_dpp v158, v82 row_shr:1 row_mask:0xf bank_mask:0xf bound_ctrl:1
	v_mov_b32_dpp v162, v72 row_shr:1 row_mask:0xf bank_mask:0xf bound_ctrl:1
	v_mov_b32_dpp v159, v83 row_shr:1 row_mask:0xf bank_mask:0xf bound_ctrl:1
	v_mov_b32_dpp v163, v73 row_shr:1 row_mask:0xf bank_mask:0xf bound_ctrl:1
	v_mov_b32_dpp v134, v84 row_shr:1 row_mask:0xf bank_mask:0xf bound_ctrl:1
	v_mov_b32_dpp v132, v74 row_shr:1 row_mask:0xf bank_mask:0xf bound_ctrl:1
	v_mov_b32_dpp v135, v85 row_shr:1 row_mask:0xf bank_mask:0xf bound_ctrl:1
	v_mov_b32_dpp v133, v75 row_shr:1 row_mask:0xf bank_mask:0xf bound_ctrl:1
	s_andn2_b64 vcc, exec, s[0:1]
	s_mov_b32 s63, s26
	s_mov_b32 s36, s28
	s_mov_b64 s[40:41], s[34:35]
	s_mov_b64 s[38:39], s[30:31]
	s_waitcnt vmcnt(0)
	v_mov_b32_e32 v98, v52
	v_mov_b32_e32 v99, v54
	v_mov_b32_e32 v54, v53
	v_mov_b32_e32 v102, v68
	v_mov_b32_e32 v103, v70
	v_pk_fma_f32 v[110:111], v[98:99], v[106:107], v[102:103]
	v_mov_b32_e32 v106, v56
	v_mov_b32_e32 v107, v58
	v_pk_fma_f32 v[168:169], v[106:107], v[138:139], v[110:111]
	v_mov_b32_e32 v110, v60
	v_mov_b32_e32 v111, v62
	v_pk_fma_f32 v[168:169], v[130:131], v[110:111], v[168:169]
	v_mov_b32_e32 v70, v69
	v_mul_f32_e32 v52, 0xbfb8aa3b, v168
	v_exp_f32_e32 v52, v52
	v_mov_b32_e32 v58, v57
	v_mov_b32_e32 v62, v61
	v_mov_b32_e32 v60, v44
	v_add_f32_e32 v52, 1.0, v52
	v_rcp_f32_e32 v170, v52
	v_pk_fma_f32 v[52:53], v[54:55], v[160:161], v[70:71]
	v_mov_b32_e32 v56, v64
	v_pk_fma_f32 v[52:53], v[58:59], v[136:137], v[52:53]
	v_mov_b32_e32 v57, v66
	v_pk_fma_f32 v[160:161], v[126:127], v[62:63], v[52:53]
	v_mov_b32_e32 v53, v40
	v_mul_f32_e32 v52, 0xbfb8aa3b, v160
	v_exp_f32_e32 v52, v52
	v_mul_f32_e32 v44, 0xbfb8aa3b, v161
	v_exp_f32_e32 v44, v44
	v_mov_b32_e32 v40, v39
	v_add_f32_e32 v52, 1.0, v52
	v_rcp_f32_e32 v172, v52
	v_mov_b32_e32 v52, v38
	v_mul_f32_e32 v38, 0xbfb8aa3b, v169
	v_exp_f32_e32 v38, v38
	v_add_f32_e32 v44, 1.0, v44
	v_rcp_f32_e32 v173, v44
	v_mov_b32_e32 v66, v65
	v_add_f32_e32 v38, 1.0, v38
	v_pk_fma_f32 v[68:69], v[52:53], v[158:159], v[56:57]
	v_mov_b32_e32 v61, v46
	v_rcp_f32_e32 v171, v38
	v_pk_fma_f32 v[38:39], v[40:41], v[162:163], v[66:67]
	v_mov_b32_e32 v46, v45
	v_pk_fma_f32 v[158:159], v[60:61], v[134:135], v[68:69]
	v_mov_b32_e32 v69, v50
	v_pk_fma_f32 v[38:39], v[46:47], v[132:133], v[38:39]
	v_mov_b32_e32 v50, v49
	v_pk_fma_f32 v[38:39], v[122:123], v[50:51], v[38:39]
	v_pk_mul_f32 v[44:45], v[160:161], v[172:173]
	v_mov_b32_e32 v68, v48
	v_pk_mul_f32 v[38:39], v[38:39], v[44:45]
	v_pk_fma_f32 v[158:159], v[124:125], v[68:69], v[158:159]
	v_pk_mul_f32 v[168:169], v[168:169], v[170:171]
	s_nop 1
	v_pk_mul_f32 v[158:159], v[158:159], v[168:169]
	s_nop 1
	v_pk_fma_f32 v[48:49], v[54:55], v[136:137], v[70:71]
	s_nop 0
	v_pk_fma_f32 v[48:49], v[126:127], v[58:59], v[48:49]
	s_nop 1
	v_pk_fma_f32 v[48:49], v[118:119], v[62:63], v[48:49]
	s_nop 0
	v_cvt_pk_bf16_f32 v38, v158, v38
	v_mul_f32_e32 v45, 0xbfb8aa3b, v48
	s_nop 1
	v_exp_f32_e32 v45, v45
	v_cvt_pk_bf16_f32 v39, v159, v39
	global_store_dwordx2 v[112:113], v[38:39], off offset:8
	v_pk_fma_f32 v[38:39], v[98:99], v[138:139], v[102:103]
	v_add_f32_e32 v45, 1.0, v45
	v_pk_fma_f32 v[38:39], v[130:131], v[106:107], v[38:39]
	v_rcp_f32_e32 v64, v45
	v_pk_fma_f32 v[38:39], v[114:115], v[110:111], v[38:39]
	v_mul_f32_e32 v65, 0xbfb8aa3b, v49
	v_mul_f32_e32 v44, 0xbfb8aa3b, v38
	v_mul_f32_e32 v45, 0xbfb8aa3b, v39
	v_exp_f32_e32 v44, v44
	v_exp_f32_e32 v45, v45
	v_exp_f32_e32 v65, v65
	v_pk_fma_f32 v[112:113], v[52:53], v[134:135], v[56:57]
	v_add_f32_e32 v44, 1.0, v44
	v_add_f32_e32 v45, 1.0, v45
	v_rcp_f32_e32 v44, v44
	v_rcp_f32_e32 v45, v45
	v_add_f32_e32 v65, 1.0, v65
	v_rcp_f32_e32 v65, v65
	v_pk_fma_f32 v[112:113], v[124:125], v[60:61], v[112:113]
	v_pk_mul_f32 v[38:39], v[38:39], v[44:45]
	v_pk_fma_f32 v[44:45], v[40:41], v[132:133], v[66:67]
	v_pk_fma_f32 v[112:113], v[116:117], v[68:69], v[112:113]
	v_pk_fma_f32 v[44:45], v[122:123], v[46:47], v[44:45]
	v_pk_mul_f32 v[38:39], v[112:113], v[38:39]
	v_pk_fma_f32 v[44:45], v[120:121], v[50:51], v[44:45]
	v_pk_mul_f32 v[48:49], v[48:49], v[64:65]
	s_nop 0
	v_pk_mul_f32 v[44:45], v[44:45], v[48:49]
; __device__ __forceinline__ unsigned pk2(float lo, float hi) { return f2bf(lo) | (f2bf(hi) << 16); }
; __device__ __forceinline__ float silu_fast(float x) { return x * __builtin_amdgcn_rcpf(1.f + __builtin_amdgcn_exp2f(-1.4426950408889634f * x)); }
; __device__ __forceinline__ float dpp_shr1(float x) { return __builtin_bit_cast(float, __builtin_amdgcn_update_dpp(0, __builtin_bit_cast(int, x), 0x111, 0xf, 0xf, true)); }
;     __device__ __forceinline__ void operator()(const f32x4 (&acc)[2][2][4][2], const pg8::Unit& u, int wr, int wc, int fr, int fq) const {
;     ...
;             const int cc = ch0 + 4 * n;
;             const f32x4 wg0 = *(CF4)(cw + cc), wg1 = *(CF4)(cw + FF2 + cc), wg2 = *(CF4)(cw + 2 * FF2 + cc), wv0 = *(CF4)(cw + FFH + cc), wv1 = *(CF4)(cw + FF2 + FFH + cc), wv2 = *(CF4)(cw + 2 * FF2 + FFH + cc);
;             const f32x4 bg = *(CF4)(cb + cc), bv = *(CF4)(cb + FFH + cc);
; #pragma unroll
;             for (int jj = 0; jj < 4; ++jj) {
;                 float g2 = dpp_shr1(g[6][jj]), g1 = dpp_shr1(g[7][jj]), v2 = dpp_shr1(v[6][jj]), v1 = dpp_shr1(v[7][jj]);
; #pragma unroll
;                 for (int e = 0; e < 8; ++e) { const float g0 = g[e][jj], v0 = v[e][jj];
;                     const float cg = bg[jj] + wg0[jj] * g2 + wg1[jj] * g1 + wg2[jj] * g0, cv = bv[jj] + wv0[jj] * v2 + wv1[jj] * v1 + wv2[jj] * v0;
;                     g[e][jj] = silu_fast(cg) * cv; g2 = g1; g1 = g0; v2 = v1; v1 = v0; } }
; #pragma unroll
;             for (int e = 0; e < 8; ++e) { v2u w; w.x = pk2(g[e][0], g[e][1]); w.y = pk2(g[e][2], g[e][3]); *(v2u*)(ACT + (size_t)(tok0 + e) * FFH + cc) = w; }
	s_nop 7
	s_nop 1
	v_cvt_pk_bf16_f32 v39, v39, v45
	v_cvt_pk_bf16_f32 v38, v38, v44
	v_mov_b32_e32 v44, v33
	v_mov_b32_e32 v45, v35
	v_mov_b32_e32 v33, v34
	v_pk_fma_f32 v[34:35], v[126:127], v[54:55], v[70:71]
	v_pk_mul_f32 v[44:45], v[44:45], v[128:129]
	v_pk_fma_f32 v[34:35], v[118:119], v[58:59], v[34:35]
	global_store_dwordx2 v[108:109], v[38:39], off offset:8
	v_pk_fma_f32 v[34:35], v[44:45], v[62:63], v[34:35]
	v_mov_b32_e32 v39, v31
	v_mul_f32_e32 v31, 0xbfb8aa3b, v34
	v_exp_f32_e32 v31, v31
	v_mov_b32_e32 v38, v29
	v_mov_b32_e32 v29, v30
	v_pk_mul_f32 v[48:49], v[28:29], v[128:129]
	v_pk_fma_f32 v[28:29], v[130:131], v[98:99], v[102:103]
	v_pk_mul_f32 v[32:33], v[32:33], v[128:129]
	v_pk_fma_f32 v[28:29], v[114:115], v[106:107], v[28:29]
	v_add_f32_e32 v31, 1.0, v31
	v_pk_fma_f32 v[28:29], v[32:33], v[110:111], v[28:29]
	v_rcp_f32_e32 v64, v31
	v_mul_f32_e32 v30, 0xbfb8aa3b, v28
	v_mul_f32_e32 v31, 0xbfb8aa3b, v29
	v_exp_f32_e32 v30, v30
	v_exp_f32_e32 v31, v31
	v_mul_f32_e32 v65, 0xbfb8aa3b, v35
	v_exp_f32_e32 v65, v65
	v_add_f32_e32 v30, 1.0, v30
	v_add_f32_e32 v31, 1.0, v31
	v_rcp_f32_e32 v30, v30
	v_rcp_f32_e32 v31, v31
	v_add_f32_e32 v65, 1.0, v65
	v_rcp_f32_e32 v65, v65
	v_pk_fma_f32 v[108:109], v[124:125], v[52:53], v[56:57]
	v_pk_mul_f32 v[28:29], v[28:29], v[30:31]
	v_pk_fma_f32 v[108:109], v[116:117], v[60:61], v[108:109]
	v_pk_fma_f32 v[30:31], v[122:123], v[40:41], v[66:67]
	v_pk_mul_f32 v[38:39], v[38:39], v[128:129]
	v_pk_fma_f32 v[108:109], v[48:49], v[68:69], v[108:109]
	v_pk_fma_f32 v[30:31], v[120:121], v[46:47], v[30:31]
	v_pk_mul_f32 v[28:29], v[108:109], v[28:29]
	v_pk_fma_f32 v[30:31], v[38:39], v[50:51], v[30:31]
	v_pk_mul_f32 v[34:35], v[34:35], v[64:65]
	s_nop 0
	v_pk_mul_f32 v[30:31], v[30:31], v[34:35]
	s_nop 7
	s_nop 1
	v_cvt_pk_bf16_f32 v29, v29, v31
	v_cvt_pk_bf16_f32 v28, v28, v30
	v_mov_b32_e32 v30, v25
	v_mov_b32_e32 v31, v27
	v_pk_fma_f32 v[34:35], v[118:119], v[54:55], v[70:71]
	v_pk_mul_f32 v[30:31], v[30:31], v[42:43]
	v_pk_fma_f32 v[34:35], v[44:45], v[58:59], v[34:35]
	v_mov_b32_e32 v25, v26
	v_pk_fma_f32 v[34:35], v[30:31], v[62:63], v[34:35]
	global_store_dwordx2 v[104:105], v[28:29], off offset:8
	v_mul_f32_e32 v65, 0xbfb8aa3b, v34
	v_exp_f32_e32 v65, v65
	v_mov_b32_e32 v28, v21
	v_mov_b32_e32 v29, v23
	v_mov_b32_e32 v21, v22
	v_pk_mul_f32 v[22:23], v[24:25], v[42:43]
	v_pk_fma_f32 v[24:25], v[114:115], v[98:99], v[102:103]
	v_add_f32_e32 v65, 1.0, v65
	v_pk_fma_f32 v[24:25], v[32:33], v[106:107], v[24:25]
	v_rcp_f32_e32 v104, v65
	v_pk_fma_f32 v[24:25], v[22:23], v[110:111], v[24:25]
	v_pk_fma_f32 v[26:27], v[116:117], v[52:53], v[56:57]
	v_mul_f32_e32 v64, 0xbfb8aa3b, v24
	v_mul_f32_e32 v65, 0xbfb8aa3b, v25
	v_exp_f32_e32 v64, v64
	v_exp_f32_e32 v65, v65
	v_pk_mul_f32 v[20:21], v[20:21], v[42:43]
	v_pk_fma_f32 v[26:27], v[48:49], v[60:61], v[26:27]
	v_add_f32_e32 v64, 1.0, v64
	v_add_f32_e32 v65, 1.0, v65
	v_rcp_f32_e32 v64, v64
	v_rcp_f32_e32 v65, v65
	v_pk_mul_f32 v[28:29], v[28:29], v[42:43]
	v_pk_fma_f32 v[42:43], v[120:121], v[40:41], v[66:67]
	v_pk_fma_f32 v[26:27], v[20:21], v[68:69], v[26:27]
	v_pk_mul_f32 v[24:25], v[24:25], v[64:65]
	s_nop 0
	v_pk_mul_f32 v[24:25], v[26:27], v[24:25]
	v_pk_fma_f32 v[26:27], v[38:39], v[46:47], v[42:43]
	v_mul_f32_e32 v42, 0xbfb8aa3b, v35
	v_exp_f32_e32 v42, v42
	v_pk_fma_f32 v[26:27], v[28:29], v[50:51], v[26:27]
	v_add_f32_e32 v42, 1.0, v42
	v_rcp_f32_e32 v105, v42
	s_nop 0
	v_pk_mul_f32 v[34:35], v[34:35], v[104:105]
	s_nop 0
	v_pk_mul_f32 v[26:27], v[26:27], v[34:35]
	s_nop 7
	s_nop 1
	v_cvt_pk_bf16_f32 v25, v25, v27
	v_cvt_pk_bf16_f32 v24, v24, v26
	v_mov_b32_e32 v26, v17
	v_mov_b32_e32 v27, v19
	v_mov_b32_e32 v17, v18
	v_pk_fma_f32 v[18:19], v[44:45], v[54:55], v[70:71]
	v_pk_mul_f32 v[26:27], v[26:27], v[92:93]
	v_pk_fma_f32 v[18:19], v[30:31], v[58:59], v[18:19]
	global_store_dwordx2 v[100:101], v[24:25], off offset:8
	v_mov_b32_e32 v24, v13
	v_mov_b32_e32 v13, v14
	v_pk_fma_f32 v[18:19], v[26:27], v[62:63], v[18:19]
	v_pk_mul_f32 v[34:35], v[12:13], v[92:93]
	v_pk_fma_f32 v[12:13], v[32:33], v[98:99], v[102:103]
	v_pk_fma_f32 v[32:33], v[38:39], v[40:41], v[66:67]
	v_mul_f32_e32 v39, 0xbfb8aa3b, v18
	v_exp_f32_e32 v39, v39
	v_pk_mul_f32 v[16:17], v[16:17], v[92:93]
	v_pk_fma_f32 v[12:13], v[22:23], v[106:107], v[12:13]
	v_mov_b32_e32 v25, v15
	v_pk_fma_f32 v[12:13], v[16:17], v[110:111], v[12:13]
	v_add_f32_e32 v39, 1.0, v39
	v_mul_f32_e32 v38, 0xbfb8aa3b, v12
	v_rcp_f32_e32 v42, v39
	v_mul_f32_e32 v39, 0xbfb8aa3b, v13
	v_exp_f32_e32 v38, v38
	v_exp_f32_e32 v39, v39
	v_pk_fma_f32 v[14:15], v[48:49], v[52:53], v[56:57]
	v_pk_mul_f32 v[24:25], v[24:25], v[92:93]
	v_add_f32_e32 v38, 1.0, v38
	v_add_f32_e32 v39, 1.0, v39
	v_rcp_f32_e32 v38, v38
	v_rcp_f32_e32 v39, v39
	v_pk_fma_f32 v[14:15], v[20:21], v[60:61], v[14:15]
	v_pk_mul_f32 v[12:13], v[12:13], v[38:39]
	v_pk_fma_f32 v[14:15], v[34:35], v[68:69], v[14:15]
	s_nop 0
	v_pk_mul_f32 v[12:13], v[14:15], v[12:13]
	v_pk_fma_f32 v[14:15], v[28:29], v[46:47], v[32:33]
	v_mul_f32_e32 v32, 0xbfb8aa3b, v19
	v_exp_f32_e32 v32, v32
	v_pk_fma_f32 v[14:15], v[24:25], v[50:51], v[14:15]
	v_add_f32_e32 v32, 1.0, v32
	v_rcp_f32_e32 v43, v32
	s_nop 0
	v_pk_mul_f32 v[18:19], v[18:19], v[42:43]
	s_nop 0
	v_pk_mul_f32 v[14:15], v[14:15], v[18:19]
; __device__ __forceinline__ unsigned pk2(float lo, float hi) { return f2bf(lo) | (f2bf(hi) << 16); }
; __device__ __forceinline__ float silu_fast(float x) { return x * __builtin_amdgcn_rcpf(1.f + __builtin_amdgcn_exp2f(-1.4426950408889634f * x)); }
; __device__ __forceinline__ float dpp_shr1(float x) { return __builtin_bit_cast(float, __builtin_amdgcn_update_dpp(0, __builtin_bit_cast(int, x), 0x111, 0xf, 0xf, true)); }
;     __device__ __forceinline__ void operator()(const f32x4 (&acc)[2][2][4][2], const pg8::Unit& u, int wr, int wc, int fr, int fq) const {
;     ...
;             const int cc = ch0 + 4 * n;
;             const f32x4 wg0 = *(CF4)(cw + cc), wg1 = *(CF4)(cw + FF2 + cc), wg2 = *(CF4)(cw + 2 * FF2 + cc), wv0 = *(CF4)(cw + FFH + cc), wv1 = *(CF4)(cw + FF2 + FFH + cc), wv2 = *(CF4)(cw + 2 * FF2 + FFH + cc);
;             const f32x4 bg = *(CF4)(cb + cc), bv = *(CF4)(cb + FFH + cc);
; #pragma unroll
;             for (int jj = 0; jj < 4; ++jj) {
;                 float g2 = dpp_shr1(g[6][jj]), g1 = dpp_shr1(g[7][jj]), v2 = dpp_shr1(v[6][jj]), v1 = dpp_shr1(v[7][jj]);
; #pragma unroll
;                 for (int e = 0; e < 8; ++e) { const float g0 = g[e][jj], v0 = v[e][jj];
;                     const float cg = bg[jj] + wg0[jj] * g2 + wg1[jj] * g1 + wg2[jj] * g0, cv = bv[jj] + wv0[jj] * v2 + wv1[jj] * v1 + wv2[jj] * v0;
;                     g[e][jj] = silu_fast(cg) * cv; g2 = g1; g1 = g0; v2 = v1; v1 = v0; } }
; #pragma unroll
;             for (int e = 0; e < 8; ++e) { v2u w; w.x = pk2(g[e][0], g[e][1]); w.y = pk2(g[e][2], g[e][3]); *(v2u*)(ACT + (size_t)(tok0 + e) * FFH + cc) = w; }
	s_nop 7
	s_nop 1
	v_cvt_pk_bf16_f32 v13, v13, v15
	v_cvt_pk_bf16_f32 v12, v12, v14
	v_mov_b32_e32 v14, v9
	v_mov_b32_e32 v15, v11
	v_pk_fma_f32 v[18:19], v[30:31], v[54:55], v[70:71]
	v_pk_mul_f32 v[14:15], v[14:15], v[36:37]
	v_pk_fma_f32 v[18:19], v[26:27], v[58:59], v[18:19]
	v_mov_b32_e32 v9, v10
	v_pk_fma_f32 v[18:19], v[14:15], v[62:63], v[18:19]
	global_store_dwordx2 v[96:97], v[12:13], off offset:8
	v_mov_b32_e32 v12, v5
	v_mov_b32_e32 v13, v7
	v_mov_b32_e32 v5, v6
	v_pk_mul_f32 v[6:7], v[8:9], v[36:37]
	v_pk_fma_f32 v[8:9], v[22:23], v[98:99], v[102:103]
	v_mul_f32_e32 v23, 0xbfb8aa3b, v18
	v_exp_f32_e32 v23, v23
	v_pk_fma_f32 v[8:9], v[16:17], v[106:107], v[8:9]
	v_pk_fma_f32 v[10:11], v[20:21], v[52:53], v[56:57]
	v_pk_fma_f32 v[8:9], v[6:7], v[110:111], v[8:9]
	v_add_f32_e32 v23, 1.0, v23
	v_pk_fma_f32 v[20:21], v[28:29], v[40:41], v[66:67]
	v_mul_f32_e32 v22, 0xbfb8aa3b, v8
	v_rcp_f32_e32 v28, v23
	v_mul_f32_e32 v23, 0xbfb8aa3b, v9
	v_exp_f32_e32 v22, v22
	v_exp_f32_e32 v23, v23
	v_pk_mul_f32 v[4:5], v[4:5], v[36:37]
	v_pk_fma_f32 v[10:11], v[34:35], v[60:61], v[10:11]
	v_add_f32_e32 v22, 1.0, v22
	v_add_f32_e32 v23, 1.0, v23
	v_rcp_f32_e32 v22, v22
	v_rcp_f32_e32 v23, v23
	v_pk_fma_f32 v[10:11], v[4:5], v[68:69], v[10:11]
	v_pk_mul_f32 v[12:13], v[12:13], v[36:37]
	v_pk_mul_f32 v[8:9], v[8:9], v[22:23]
	s_nop 0
	v_pk_mul_f32 v[8:9], v[10:11], v[8:9]
	v_pk_fma_f32 v[10:11], v[24:25], v[46:47], v[20:21]
	v_mul_f32_e32 v20, 0xbfb8aa3b, v19
	v_exp_f32_e32 v20, v20
	v_pk_fma_f32 v[10:11], v[12:13], v[50:51], v[10:11]
	v_add_f32_e32 v20, 1.0, v20
	v_rcp_f32_e32 v29, v20
	s_nop 0
	v_pk_mul_f32 v[18:19], v[18:19], v[28:29]
	s_nop 0
	v_pk_mul_f32 v[10:11], v[10:11], v[18:19]
	s_nop 7
	s_nop 1
	v_cvt_pk_bf16_f32 v9, v9, v11
	v_cvt_pk_bf16_f32 v8, v8, v10
	global_store_dwordx2 v[80:81], v[8:9], off offset:8
	v_pk_fma_f32 v[8:9], v[16:17], v[98:99], v[102:103]
	v_pk_fma_f32 v[16:17], v[26:27], v[54:55], v[70:71]
	v_pk_fma_f32 v[8:9], v[6:7], v[106:107], v[8:9]
	v_pk_fma_f32 v[16:17], v[14:15], v[58:59], v[16:17]
	v_pk_fma_f32 v[8:9], v[88:89], v[110:111], v[8:9]
	v_pk_fma_f32 v[16:17], v[86:87], v[62:63], v[16:17]
	v_mul_f32_e32 v20, 0xbfb8aa3b, v8
	v_mul_f32_e32 v21, 0xbfb8aa3b, v16
	v_exp_f32_e32 v21, v21
	v_exp_f32_e32 v20, v20
	v_pk_fma_f32 v[10:11], v[34:35], v[52:53], v[56:57]
	v_pk_fma_f32 v[18:19], v[24:25], v[40:41], v[66:67]
	v_add_f32_e32 v21, 1.0, v21
	v_rcp_f32_e32 v22, v21
	v_mul_f32_e32 v21, 0xbfb8aa3b, v9
	v_exp_f32_e32 v21, v21
	v_add_f32_e32 v20, 1.0, v20
	v_rcp_f32_e32 v20, v20
	v_pk_fma_f32 v[10:11], v[4:5], v[60:61], v[10:11]
	v_add_f32_e32 v21, 1.0, v21
	v_rcp_f32_e32 v21, v21
	v_pk_fma_f32 v[10:11], v[82:83], v[68:69], v[10:11]
	v_pk_fma_f32 v[6:7], v[6:7], v[98:99], v[102:103]
	v_pk_fma_f32 v[4:5], v[4:5], v[52:53], v[56:57]
	v_pk_mul_f32 v[8:9], v[8:9], v[20:21]
	v_pk_fma_f32 v[6:7], v[88:89], v[106:107], v[6:7]
	v_pk_mul_f32 v[8:9], v[10:11], v[8:9]
	v_pk_fma_f32 v[10:11], v[12:13], v[46:47], v[18:19]
	v_mul_f32_e32 v18, 0xbfb8aa3b, v17
	v_exp_f32_e32 v18, v18
	v_pk_fma_f32 v[10:11], v[72:73], v[50:51], v[10:11]
	v_pk_fma_f32 v[6:7], v[94:95], v[110:111], v[6:7]
	v_pk_fma_f32 v[4:5], v[82:83], v[60:61], v[4:5]
	v_add_f32_e32 v18, 1.0, v18
	v_rcp_f32_e32 v23, v18
	v_pk_fma_f32 v[4:5], v[84:85], v[68:69], v[4:5]
	v_pk_mul_f32 v[16:17], v[16:17], v[22:23]
	s_nop 0
	v_pk_mul_f32 v[10:11], v[10:11], v[16:17]
	s_nop 7
	s_nop 1
	v_cvt_pk_bf16_f32 v9, v9, v11
	v_cvt_pk_bf16_f32 v8, v8, v10
	v_pk_fma_f32 v[10:11], v[14:15], v[54:55], v[70:71]
	global_store_dwordx2 v[78:79], v[8:9], off offset:8
	v_pk_fma_f32 v[10:11], v[86:87], v[58:59], v[10:11]
	v_mul_f32_e32 v8, 0xbfb8aa3b, v6
	v_pk_fma_f32 v[10:11], v[90:91], v[62:63], v[10:11]
	v_exp_f32_e32 v8, v8
	v_mul_f32_e32 v9, 0xbfb8aa3b, v10
	v_exp_f32_e32 v9, v9
	v_add_f32_e32 v8, 1.0, v8
	v_rcp_f32_e32 v8, v8
	v_add_f32_e32 v9, 1.0, v9
	v_rcp_f32_e32 v14, v9
	v_mul_f32_e32 v9, 0xbfb8aa3b, v7
	v_exp_f32_e32 v9, v9
	s_nop 0
	v_add_f32_e32 v9, 1.0, v9
	v_rcp_f32_e32 v9, v9
	s_nop 0
	v_pk_mul_f32 v[6:7], v[6:7], v[8:9]
	v_mul_f32_e32 v8, 0xbfb8aa3b, v11
	v_exp_f32_e32 v8, v8
	v_pk_mul_f32 v[4:5], v[4:5], v[6:7]
	v_pk_fma_f32 v[6:7], v[12:13], v[40:41], v[66:67]
	v_add_f32_e32 v8, 1.0, v8
	v_rcp_f32_e32 v15, v8
	v_pk_fma_f32 v[6:7], v[72:73], v[46:47], v[6:7]
	v_pk_mul_f32 v[8:9], v[10:11], v[14:15]
	v_pk_fma_f32 v[6:7], v[74:75], v[50:51], v[6:7]
	s_nop 0
	v_pk_mul_f32 v[6:7], v[6:7], v[8:9]
	v_and_b32_sdwa v8, v5, v234 dst_sel:DWORD dst_unused:UNUSED_PAD src0_sel:WORD_1 src1_sel:DWORD
	v_and_b32_sdwa v9, v4, v234 dst_sel:DWORD dst_unused:UNUSED_PAD src0_sel:WORD_1 src1_sel:DWORD
	v_add3_u32 v4, v4, v9, s61
	v_add3_u32 v5, v5, v8, s61
	v_and_b32_sdwa v8, v7, v234 dst_sel:DWORD dst_unused:UNUSED_PAD src0_sel:WORD_1 src1_sel:DWORD
	v_and_b32_sdwa v9, v6, v234 dst_sel:DWORD dst_unused:UNUSED_PAD src0_sel:WORD_1 src1_sel:DWORD
	v_add3_u32 v7, v7, v8, s61
	v_add3_u32 v6, v6, v9, s61
	v_and_b32_e32 v7, 0xffff0000, v7
	v_and_b32_e32 v6, 0xffff0000, v6
	v_or_b32_sdwa v5, v7, v5 dst_sel:DWORD dst_unused:UNUSED_PAD src0_sel:DWORD src1_sel:WORD_1
	v_or_b32_sdwa v4, v6, v4 dst_sel:DWORD dst_unused:UNUSED_PAD src0_sel:DWORD src1_sel:WORD_1
	global_store_dwordx2 v[76:77], v[4:5], off offset:8
	s_cbranch_vccz .LBB0_2998

; #define PG8_STAGE(bufoff, gbase, voff) do { _Pragma("unroll") for (int _i = 0; _i < 2; ++_i) \
;         __builtin_amdgcn_global_load_lds((const unsigned*)((const char*)(gbase) + (voff)[_i]), (LAS unsigned*)(lds + (bufoff) + ldsw + _i * 8192), 16, 0, 0); } while (0)
; #define PG8_LDA(dst, b, h) do { _Pragma("unroll") for (int m = 0; m < 4; ++m) _Pragma("unroll") for (int k = 0; k < 2; ++k) dst[m][k] = *(const LAS bf16x8*)(lds + PG8_SA(b, h) + aoff + m * 2048 + k * 1024); } while (0)
; #define PG8_LDB(dst, b, h) do { _Pragma("unroll") for (int n = 0; n < 2; ++n) _Pragma("unroll") for (int k = 0; k < 2; ++k) dst[n][k] = *(const LAS bf16x8*)(lds + PG8_SB(b, h) + boff + n * 2048 + k * 1024); } while (0)
; #define PG8_MMA(ai, bj, At, Bt) do { __builtin_amdgcn_s_setprio(1); _Pragma("unroll") for (int m = 0; m < 4; ++m) _Pragma("unroll") for (int n = 0; n < 2; ++n) _Pragma("unroll") for (int k = 0; k < 2; ++k) \
;         acc[ai][bj][m][n] = __builtin_amdgcn_mfma_f32_16x16x32_bf16(Bt[n][k], At[m][k], acc[ai][bj][m][n], 0, 0, 0); __builtin_amdgcn_s_setprio(0); } while (0)
; #define PG8_WAIT_V(n) asm volatile("s_waitcnt vmcnt(" #n ")" ::: "memory")
; template <class PT, class Epi>
; __device__ __forceinline__ void gemm_phase_once(LAS unsigned char* lds, const PT& S, const Epi& E, bool epi_on) {
;     ...
;             const char* a1 = cA + (size_t)(t + 1) * kstep;
;             const char* a2 = last ? nA : cA + (size_t)(t + 2) * kstep; const char* b2 = last ? nB : cB + (size_t)(t + 2) * kstep;
;             const char* a3 = a2 + kstep; const char* b3 = b2 + kstep;
;             PG8_LDB(B0, 0, 0); PG8_SCHED; PG8_LDA(At, 0, 0); PG8_STAGE(PG8_SA(1, 1), a1 + hstepA, voffA);
;             PG8_WAIT_L(8); PG8_BAR; PG8_WAIT_L(0); PG8_MMA(0, 0, At, B0); PG8_BAR; PG8_SCHED;
;             PG8_LDB(B1, 0, 1); PG8_STAGE(PG8_SB(0, 0), b2, voffB);
;             PG8_BAR; PG8_WAIT_L(0); PG8_MMA(0, 1, At, B1); PG8_BAR;
;             PG8_LDA(At, 0, 1); PG8_STAGE(PG8_SA(0, 0), a2, voffA);
;             PG8_BAR; PG8_WAIT_L(0); PG8_MMA(1, 0, At, B0); PG8_BAR; PG8_SCHED;
;             PG8_STAGE(PG8_SB(0, 1), b2 + hstepB, voffB);
;             PG8_WAIT_V(6); PG8_BAR; PG8_MMA(1, 1, At, B1); PG8_BAR;
;             PG8_LDB(B0, 1, 0); PG8_SCHED; PG8_LDA(At, 1, 0); PG8_STAGE(PG8_SA(0, 1), a2 + hstepA, voffA);
;             PG8_WAIT_L(8); PG8_BAR; PG8_WAIT_L(0); PG8_MMA(0, 0, At, B0); PG8_BAR; PG8_SCHED;
.LBB0_2983:
	ds_read_b128 v[36:39], v228
	ds_read_b128 v[40:43], v228 offset:1024
	ds_read_b128 v[158:161], v228 offset:2048
	ds_read_b128 v[168:171], v228 offset:3072
	s_add_u32 s40, s38, 0x100
	s_addc_u32 s41, s39, 0
	s_cmp_eq_u32 s67, 28
	s_cselect_b32 s45, s29, s41
	s_cselect_b32 s44, s37, s40
	s_cselect_b32 s43, s27, s66
	s_cselect_b32 s42, s64, s65
	v_lshl_add_u64 v[162:163], s[38:39], 0, v[150:151]
	s_add_i32 m0, s51, 0xc000
	ds_read_b128 v[172:175], v229
	ds_read_b128 v[176:179], v229 offset:1024
	ds_read_b128 v[180:183], v229 offset:2048
	ds_read_b128 v[184:187], v229 offset:3072
	ds_read_b128 v[188:191], v229 offset:4096
	ds_read_b128 v[192:195], v229 offset:5120
	ds_read_b128 v[196:199], v229 offset:6144
	ds_read_b128 v[200:203], v229 offset:7168
	global_load_lds_dwordx4 v[162:163], off
	v_lshl_add_u64 v[162:163], s[38:39], 0, v[152:153]
	s_add_i32 m0, s51, 0xe000
	s_nop 0
	global_load_lds_dwordx4 v[162:163], off
	s_waitcnt lgkmcnt(8)
	s_barrier
	s_waitcnt lgkmcnt(0)
	s_setprio 1
	s_waitcnt lgkmcnt(0)
	v_mfma_f32_16x16x32_bf16 v[132:135], v[36:39], v[172:175], v[132:135]
	v_mfma_f32_16x16x32_bf16 v[72:75], v[158:161], v[172:175], v[72:75]
	v_mfma_f32_16x16x32_bf16 v[124:127], v[36:39], v[180:183], v[124:127]
	v_mfma_f32_16x16x32_bf16 v[68:71], v[158:161], v[180:183], v[68:71]
	v_mfma_f32_16x16x32_bf16 v[104:107], v[36:39], v[188:191], v[104:107]
	v_mfma_f32_16x16x32_bf16 v[32:35], v[158:161], v[188:191], v[32:35]
	v_mfma_f32_16x16x32_bf16 v[100:103], v[36:39], v[196:199], v[100:103]
	v_mfma_f32_16x16x32_bf16 v[24:27], v[158:161], v[196:199], v[24:27]
	v_mfma_f32_16x16x32_bf16 v[132:135], v[40:43], v[176:179], v[132:135]
	v_mfma_f32_16x16x32_bf16 v[72:75], v[168:171], v[176:179], v[72:75]
	v_mfma_f32_16x16x32_bf16 v[124:127], v[40:43], v[184:187], v[124:127]
	v_mfma_f32_16x16x32_bf16 v[68:71], v[168:171], v[184:187], v[68:71]
	v_mfma_f32_16x16x32_bf16 v[104:107], v[40:43], v[192:195], v[104:107]
	v_mfma_f32_16x16x32_bf16 v[32:35], v[168:171], v[192:195], v[32:35]
	v_mfma_f32_16x16x32_bf16 v[100:103], v[40:43], v[200:203], v[100:103]
	v_mfma_f32_16x16x32_bf16 v[24:27], v[168:171], v[200:203], v[24:27]
	s_setprio 0
	s_barrier
	s_add_i32 s38, s59, s48
	v_lshl_add_u64 v[162:163], s[42:43], 0, v[146:147]
	s_mov_b32 m0, s38
	ds_read_b128 v[204:207], v233
	ds_read_b128 v[208:211], v233 offset:1024
	ds_read_b128 v[212:215], v233 offset:2048
	ds_read_b128 v[216:219], v233 offset:3072
	global_load_lds_dwordx4 v[162:163], off
	v_lshl_add_u64 v[220:221], s[42:43], 0, v[140:141]
	s_add_i32 m0, s38, 0x2000
	s_nop 0
	global_load_lds_dwordx4 v[220:221], off
	s_barrier
	s_waitcnt lgkmcnt(0)
	s_setprio 1
	s_waitcnt lgkmcnt(0)
	v_mfma_f32_16x16x32_bf16 v[120:123], v[204:207], v[172:175], v[120:123]
	v_mfma_f32_16x16x32_bf16 v[64:67], v[212:215], v[172:175], v[64:67]
	v_mfma_f32_16x16x32_bf16 v[116:119], v[204:207], v[180:183], v[116:119]
	v_mfma_f32_16x16x32_bf16 v[60:63], v[212:215], v[180:183], v[60:63]
	v_mfma_f32_16x16x32_bf16 v[96:99], v[204:207], v[188:191], v[96:99]
	v_mfma_f32_16x16x32_bf16 v[28:31], v[212:215], v[188:191], v[28:31]
	v_mfma_f32_16x16x32_bf16 v[92:95], v[204:207], v[196:199], v[92:95]
	v_mfma_f32_16x16x32_bf16 v[20:23], v[212:215], v[196:199], v[20:23]
	v_mfma_f32_16x16x32_bf16 v[120:123], v[208:211], v[176:179], v[120:123]
	v_mfma_f32_16x16x32_bf16 v[64:67], v[216:219], v[176:179], v[64:67]
	v_mfma_f32_16x16x32_bf16 v[116:119], v[208:211], v[184:187], v[116:119]
	v_mfma_f32_16x16x32_bf16 v[60:63], v[216:219], v[184:187], v[60:63]
	v_mfma_f32_16x16x32_bf16 v[96:99], v[208:211], v[192:195], v[96:99]
	v_mfma_f32_16x16x32_bf16 v[28:31], v[216:219], v[192:195], v[28:31]
	v_mfma_f32_16x16x32_bf16 v[92:95], v[208:211], v[200:203], v[92:95]
	v_mfma_f32_16x16x32_bf16 v[20:23], v[216:219], v[200:203], v[20:23]
	s_setprio 0
	s_mov_b32 m0, s51
	v_lshl_add_u64 v[222:223], s[44:45], 0, v[142:143]
	s_barrier
	ds_read_b128 v[172:175], v229 offset:16384
	ds_read_b128 v[176:179], v229 offset:17408
	ds_read_b128 v[180:183], v229 offset:18432
	ds_read_b128 v[184:187], v229 offset:19456
	ds_read_b128 v[188:191], v229 offset:20480
	ds_read_b128 v[192:195], v229 offset:21504
	ds_read_b128 v[196:199], v229 offset:22528
	ds_read_b128 v[200:203], v229 offset:23552
	global_load_lds_dwordx4 v[222:223], off
	v_lshl_add_u64 v[224:225], s[44:45], 0, v[144:145]
	s_mov_b32 m0, s52
	s_nop 0
	global_load_lds_dwordx4 v[224:225], off
	s_barrier
	s_waitcnt lgkmcnt(0)
	s_setprio 1
	s_waitcnt lgkmcnt(0)
	v_mfma_f32_16x16x32_bf16 v[88:91], v[36:39], v[172:175], v[88:91]
	v_mfma_f32_16x16x32_bf16 v[16:19], v[158:161], v[172:175], v[16:19]
	v_mfma_f32_16x16x32_bf16 v[84:87], v[36:39], v[180:183], v[84:87]
	v_mfma_f32_16x16x32_bf16 v[8:11], v[158:161], v[180:183], v[8:11]
	v_mfma_f32_16x16x32_bf16 v[136:139], v[36:39], v[188:191], v[136:139]
	v_mfma_f32_16x16x32_bf16 v[56:59], v[158:161], v[188:191], v[56:59]
	v_mfma_f32_16x16x32_bf16 v[36:39], v[36:39], v[196:199], v[112:115]
	v_mfma_f32_16x16x32_bf16 v[88:91], v[40:43], v[176:179], v[88:91]
	v_mfma_f32_16x16x32_bf16 v[16:19], v[168:171], v[176:179], v[16:19]
	v_mfma_f32_16x16x32_bf16 v[84:87], v[40:43], v[184:187], v[84:87]
	v_mfma_f32_16x16x32_bf16 v[8:11], v[168:171], v[184:187], v[8:11]
	v_mfma_f32_16x16x32_bf16 v[136:139], v[40:43], v[192:195], v[136:139]
	v_mfma_f32_16x16x32_bf16 v[56:59], v[168:171], v[192:195], v[56:59]
	v_mfma_f32_16x16x32_bf16 v[36:39], v[40:43], v[200:203], v[36:39]
	v_mfma_f32_16x16x32_bf16 v[40:43], v[158:161], v[196:199], v[52:55]
	v_mfma_f32_16x16x32_bf16 v[40:43], v[168:171], v[200:203], v[40:43]
	s_setprio 0
	s_barrier
; #define PG8_STAGE(bufoff, gbase, voff) do { _Pragma("unroll") for (int _i = 0; _i < 2; ++_i) \
;         __builtin_amdgcn_global_load_lds((const unsigned*)((const char*)(gbase) + (voff)[_i]), (LAS unsigned*)(lds + (bufoff) + ldsw + _i * 8192), 16, 0, 0); } while (0)
; #define PG8_LDA(dst, b, h) do { _Pragma("unroll") for (int m = 0; m < 4; ++m) _Pragma("unroll") for (int k = 0; k < 2; ++k) dst[m][k] = *(const LAS bf16x8*)(lds + PG8_SA(b, h) + aoff + m * 2048 + k * 1024); } while (0)
; #define PG8_LDB(dst, b, h) do { _Pragma("unroll") for (int n = 0; n < 2; ++n) _Pragma("unroll") for (int k = 0; k < 2; ++k) dst[n][k] = *(const LAS bf16x8*)(lds + PG8_SB(b, h) + boff + n * 2048 + k * 1024); } while (0)
; #define PG8_MMA(ai, bj, At, Bt) do { __builtin_amdgcn_s_setprio(1); _Pragma("unroll") for (int m = 0; m < 4; ++m) _Pragma("unroll") for (int n = 0; n < 2; ++n) _Pragma("unroll") for (int k = 0; k < 2; ++k) \
;         acc[ai][bj][m][n] = __builtin_amdgcn_mfma_f32_16x16x32_bf16(Bt[n][k], At[m][k], acc[ai][bj][m][n], 0, 0, 0); __builtin_amdgcn_s_setprio(0); } while (0)
; #define PG8_WAIT_V(n) asm volatile("s_waitcnt vmcnt(" #n ")" ::: "memory")
; #define PG8_WAIT_L(n) asm volatile("s_waitcnt lgkmcnt(" #n ")" ::: "memory")
; #define PG8_BAR __builtin_amdgcn_s_barrier()
; #define PG8_SCHED __builtin_amdgcn_sched_barrier(0)
; template <class PT, class Epi>
; __device__ __forceinline__ void gemm_phase_once(LAS unsigned char* lds, const PT& S, const Epi& E, bool epi_on) {
;     ...
;             PG8_BAR; PG8_WAIT_L(0); PG8_MMA(1, 0, At, B0); PG8_BAR; PG8_SCHED;
;             PG8_STAGE(PG8_SB(0, 1), b2 + hstepB, voffB);
;             PG8_WAIT_V(6); PG8_BAR; PG8_MMA(1, 1, At, B1); PG8_BAR;
;             PG8_LDB(B0, 1, 0); PG8_SCHED; PG8_LDA(At, 1, 0); PG8_STAGE(PG8_SA(0, 1), a2 + hstepA, voffA);
;             PG8_WAIT_L(8); PG8_BAR; PG8_WAIT_L(0); PG8_MMA(0, 0, At, B0); PG8_BAR; PG8_SCHED;
;             PG8_LDB(B1, 1, 1); PG8_STAGE(PG8_SB(1, 0), b3, voffB);
;             PG8_BAR; PG8_WAIT_L(0); PG8_MMA(0, 1, At, B1); PG8_BAR;
;             PG8_LDA(At, 1, 1); PG8_STAGE(PG8_SA(1, 0), a3, voffA);
;             PG8_BAR; PG8_WAIT_L(0); PG8_MMA(1, 0, At, B0); PG8_BAR; PG8_SCHED;
	s_add_u32 s38, s42, 0x80000
	s_addc_u32 s39, s43, 0
	s_add_i32 s68, s60, s48
	v_lshl_add_u64 v[52:53], s[38:39], 0, v[146:147]
	s_mov_b32 m0, s68
	s_nop 0
	global_load_lds_dwordx4 v[52:53], off
	v_lshl_add_u64 v[52:53], s[38:39], 0, v[140:141]
	s_add_i32 m0, s68, 0x2000
	s_nop 0
	global_load_lds_dwordx4 v[52:53], off
	s_waitcnt vmcnt(6)
	s_barrier
	s_setprio 1
	v_mfma_f32_16x16x32_bf16 v[52:55], v[204:207], v[172:175], v[80:83]
	v_mfma_f32_16x16x32_bf16 v[80:83], v[208:211], v[176:179], v[52:55]
	v_mfma_f32_16x16x32_bf16 v[52:55], v[204:207], v[180:183], v[76:79]
	v_mfma_f32_16x16x32_bf16 v[76:79], v[208:211], v[184:187], v[52:55]
	v_mfma_f32_16x16x32_bf16 v[52:55], v[204:207], v[188:191], v[128:131]
	v_mfma_f32_16x16x32_bf16 v[12:15], v[212:215], v[172:175], v[12:15]
	v_mfma_f32_16x16x32_bf16 v[4:7], v[212:215], v[180:183], v[4:7]
	v_mfma_f32_16x16x32_bf16 v[128:131], v[208:211], v[192:195], v[52:55]
	v_mfma_f32_16x16x32_bf16 v[48:51], v[212:215], v[188:191], v[48:51]
	v_mfma_f32_16x16x32_bf16 v[52:55], v[204:207], v[196:199], v[108:111]
	v_mfma_f32_16x16x32_bf16 v[44:47], v[212:215], v[196:199], v[44:47]
	v_mfma_f32_16x16x32_bf16 v[12:15], v[216:219], v[176:179], v[12:15]
	v_mfma_f32_16x16x32_bf16 v[4:7], v[216:219], v[184:187], v[4:7]
	v_mfma_f32_16x16x32_bf16 v[48:51], v[216:219], v[192:195], v[48:51]
	v_mfma_f32_16x16x32_bf16 v[108:111], v[208:211], v[200:203], v[52:55]
	v_mfma_f32_16x16x32_bf16 v[44:47], v[216:219], v[200:203], v[44:47]
	s_setprio 0
	s_add_i32 s68, 0, 0x18000
	v_add_u32_e32 v165, s68, v167
	s_barrier
	ds_read_b128 v[52:55], v165
	ds_read_b128 v[112:115], v165 offset:1024
	ds_read_b128 v[158:161], v165 offset:2048
	ds_read_b128 v[168:171], v165 offset:3072
	s_add_u32 s38, s44, 0x4000
	s_addc_u32 s39, s45, 0
	s_mov_b32 m0, s53
	v_lshl_add_u64 v[204:205], s[38:39], 0, v[142:143]
	ds_read_b128 v[172:175], v229 offset:32768
	ds_read_b128 v[176:179], v229 offset:33792
	ds_read_b128 v[180:183], v229 offset:34816
	ds_read_b128 v[184:187], v229 offset:35840
	ds_read_b128 v[188:191], v229 offset:36864
	ds_read_b128 v[192:195], v229 offset:37888
	ds_read_b128 v[196:199], v229 offset:38912
	ds_read_b128 v[200:203], v229 offset:39936
	global_load_lds_dwordx4 v[204:205], off
	v_lshl_add_u64 v[204:205], s[38:39], 0, v[144:145]
	s_mov_b32 m0, s54
	s_nop 0
	global_load_lds_dwordx4 v[204:205], off
	s_waitcnt lgkmcnt(8)
	s_barrier
	s_waitcnt lgkmcnt(0)
	s_setprio 1
	s_waitcnt lgkmcnt(0)
	v_mfma_f32_16x16x32_bf16 v[132:135], v[52:55], v[172:175], v[132:135]
	v_mfma_f32_16x16x32_bf16 v[72:75], v[158:161], v[172:175], v[72:75]
	v_mfma_f32_16x16x32_bf16 v[124:127], v[52:55], v[180:183], v[124:127]
	v_mfma_f32_16x16x32_bf16 v[68:71], v[158:161], v[180:183], v[68:71]
	v_mfma_f32_16x16x32_bf16 v[104:107], v[52:55], v[188:191], v[104:107]
	v_mfma_f32_16x16x32_bf16 v[32:35], v[158:161], v[188:191], v[32:35]
	v_mfma_f32_16x16x32_bf16 v[100:103], v[52:55], v[196:199], v[100:103]
	v_mfma_f32_16x16x32_bf16 v[24:27], v[158:161], v[196:199], v[24:27]
	v_mfma_f32_16x16x32_bf16 v[132:135], v[112:115], v[176:179], v[132:135]
	v_mfma_f32_16x16x32_bf16 v[72:75], v[168:171], v[176:179], v[72:75]
	v_mfma_f32_16x16x32_bf16 v[124:127], v[112:115], v[184:187], v[124:127]
	v_mfma_f32_16x16x32_bf16 v[68:71], v[168:171], v[184:187], v[68:71]
	v_mfma_f32_16x16x32_bf16 v[104:107], v[112:115], v[192:195], v[104:107]
	v_mfma_f32_16x16x32_bf16 v[32:35], v[168:171], v[192:195], v[32:35]
	v_mfma_f32_16x16x32_bf16 v[100:103], v[112:115], v[200:203], v[100:103]
	v_mfma_f32_16x16x32_bf16 v[24:27], v[168:171], v[200:203], v[24:27]
	s_setprio 0
	s_barrier
	s_add_i32 s44, 0, 0x1c000
	s_add_i32 s38, s68, s48
	v_add_u32_e32 v165, s44, v167
	v_lshl_add_u64 v[162:163], v[162:163], 0, s[12:13]
	s_mov_b32 m0, s38
	ds_read_b128 v[204:207], v165
	ds_read_b128 v[208:211], v165 offset:1024
	ds_read_b128 v[212:215], v165 offset:2048
	ds_read_b128 v[216:219], v165 offset:3072
	global_load_lds_dwordx4 v[162:163], off
	v_lshl_add_u64 v[162:163], v[220:221], 0, s[12:13]
	s_add_i32 m0, s38, 0x2000
	s_nop 0
	global_load_lds_dwordx4 v[162:163], off
	s_barrier
	s_waitcnt lgkmcnt(0)
	s_setprio 1
	s_waitcnt lgkmcnt(0)
	v_mfma_f32_16x16x32_bf16 v[120:123], v[204:207], v[172:175], v[120:123]
	v_mfma_f32_16x16x32_bf16 v[64:67], v[212:215], v[172:175], v[64:67]
	v_mfma_f32_16x16x32_bf16 v[116:119], v[204:207], v[180:183], v[116:119]
	v_mfma_f32_16x16x32_bf16 v[60:63], v[212:215], v[180:183], v[60:63]
	v_mfma_f32_16x16x32_bf16 v[96:99], v[204:207], v[188:191], v[96:99]
	v_mfma_f32_16x16x32_bf16 v[28:31], v[212:215], v[188:191], v[28:31]
	v_mfma_f32_16x16x32_bf16 v[92:95], v[204:207], v[196:199], v[92:95]
	v_mfma_f32_16x16x32_bf16 v[20:23], v[212:215], v[196:199], v[20:23]
	v_mfma_f32_16x16x32_bf16 v[120:123], v[208:211], v[176:179], v[120:123]
	v_mfma_f32_16x16x32_bf16 v[64:67], v[216:219], v[176:179], v[64:67]
	v_mfma_f32_16x16x32_bf16 v[116:119], v[208:211], v[184:187], v[116:119]
	v_mfma_f32_16x16x32_bf16 v[60:63], v[216:219], v[184:187], v[60:63]
	v_mfma_f32_16x16x32_bf16 v[96:99], v[208:211], v[192:195], v[96:99]
	v_mfma_f32_16x16x32_bf16 v[28:31], v[216:219], v[192:195], v[28:31]
	v_mfma_f32_16x16x32_bf16 v[92:95], v[208:211], v[200:203], v[92:95]
	v_mfma_f32_16x16x32_bf16 v[20:23], v[216:219], v[200:203], v[20:23]
	s_setprio 0
	s_mov_b32 m0, s56
	v_lshl_add_u64 v[162:163], v[222:223], 0, s[12:13]
	s_barrier
	ds_read_b128 v[172:175], v229 offset:49152
	ds_read_b128 v[176:179], v229 offset:50176
	ds_read_b128 v[180:183], v229 offset:51200
	ds_read_b128 v[184:187], v229 offset:52224
	ds_read_b128 v[188:191], v229 offset:53248
	ds_read_b128 v[192:195], v229 offset:54272
	ds_read_b128 v[196:199], v229 offset:55296
	ds_read_b128 v[200:203], v229 offset:56320
	global_load_lds_dwordx4 v[162:163], off
	v_lshl_add_u64 v[162:163], v[224:225], 0, s[12:13]
	s_mov_b32 m0, s57
	s_nop 0
	global_load_lds_dwordx4 v[162:163], off
	s_barrier
; __device__ __forceinline__ unsigned pk2(float lo, float hi) { return f2bf(lo) | (f2bf(hi) << 16); }
; #define PG8_STAGE(bufoff, gbase, voff) do { _Pragma("unroll") for (int _i = 0; _i < 2; ++_i) \
;         __builtin_amdgcn_global_load_lds((const unsigned*)((const char*)(gbase) + (voff)[_i]), (LAS unsigned*)(lds + (bufoff) + ldsw + _i * 8192), 16, 0, 0); } while (0)
; template <class PT, class Epi>
; __device__ __forceinline__ void gemm_phase_once(LAS unsigned char* lds, const PT& S, const Epi& E, bool epi_on) {
;     ...
;             PG8_BAR; PG8_WAIT_L(0); PG8_MMA(0, 1, At, B1); PG8_BAR;
;             PG8_LDA(At, 1, 1); PG8_STAGE(PG8_SA(1, 0), a3, voffA);
;             PG8_BAR; PG8_WAIT_L(0); PG8_MMA(1, 0, At, B0); PG8_BAR; PG8_SCHED;
;             PG8_STAGE(PG8_SB(1, 1), b3 + hstepB, voffB);
;             PG8_WAIT_V(6); PG8_BAR; PG8_MMA(1, 1, At, B1); PG8_BAR;
;     __device__ __forceinline__ void operator()(const f32x4 (&acc)[2][2][4][2], const pg8::Unit& u, int wr, int wc, int fr, int fq) const {
;         const int ch0 = 128 * u.pn + 32 * wc + 8 * fq, tok0 = 256 * u.pm + 128 * wr + 8 * fr;
;         const f32x4 r0 = *(const f32x4*)(RS + tok0), r1 = *(const f32x4*)(RS + tok0 + 4);
;         bf16* hb = HALO + ((size_t)((u.pm * 44 + u.pn) * 2 + wr) * 4) * 256 + 32 * wc + 8 * fq;
; #pragma unroll
;         for (int n = 0; n < 2; ++n) {
;             float g[8][4], v[8][4];
; #pragma unroll
;             for (int e = 0; e < 8; ++e) { const float rs = (e < 4) ? r0[e & 3] : r1[e & 3];
; #pragma unroll
;                 for (int jj = 0; jj < 4; ++jj) { g[e][jj] = acc[e >> 2][0][e & 3][n][jj] * rs; v[e][jj] = acc[e >> 2][1][e & 3][n][jj] * rs; } }
;             if (fr == 0) {
; #pragma unroll
;                 for (int q = 0; q < 2; ++q) { v2u a, b; a.x = pk2(g[q][0], g[q][1]); a.y = pk2(g[q][2], g[q][3]); b.x = pk2(v[q][0], v[q][1]); b.y = pk2(v[q][2], v[q][3]);
;                     *(v2u*)(hb + (size_t)q * 256 + 4 * n) = a; *(v2u*)(hb + (size_t)q * 256 + 128 + 4 * n) = b; } }
;             if (fr == 15) {
; #pragma unroll
;                 for (int q = 0; q < 2; ++q) { v2u a, b; a.x = pk2(g[6 + q][0], g[6 + q][1]); a.y = pk2(g[6 + q][2], g[6 + q][3]); b.x = pk2(v[6 + q][0], v[6 + q][1]); b.y = pk2(v[6 + q][2], v[6 + q][3]);
;                     *(v2u*)(hb + (size_t)(2 + q) * 256 + 4 * n) = a; *(v2u*)(hb + (size_t)(2 + q) * 256 + 128 + 4 * n) = b; } }
	s_waitcnt lgkmcnt(0)
	s_setprio 1
	s_waitcnt lgkmcnt(0)
	v_mfma_f32_16x16x32_bf16 v[88:91], v[52:55], v[172:175], v[88:91]
	v_mfma_f32_16x16x32_bf16 v[84:87], v[52:55], v[180:183], v[84:87]
	v_mfma_f32_16x16x32_bf16 v[136:139], v[52:55], v[188:191], v[136:139]
	v_mfma_f32_16x16x32_bf16 v[36:39], v[52:55], v[196:199], v[36:39]
	v_mfma_f32_16x16x32_bf16 v[88:91], v[112:115], v[176:179], v[88:91]
	v_mfma_f32_16x16x32_bf16 v[16:19], v[158:161], v[172:175], v[16:19]
	v_mfma_f32_16x16x32_bf16 v[84:87], v[112:115], v[184:187], v[84:87]
	v_mfma_f32_16x16x32_bf16 v[8:11], v[158:161], v[180:183], v[8:11]
	v_mfma_f32_16x16x32_bf16 v[136:139], v[112:115], v[192:195], v[136:139]
	v_mfma_f32_16x16x32_bf16 v[56:59], v[158:161], v[188:191], v[56:59]
	v_mfma_f32_16x16x32_bf16 v[112:115], v[112:115], v[200:203], v[36:39]
	v_mfma_f32_16x16x32_bf16 v[36:39], v[158:161], v[196:199], v[40:43]
	v_mfma_f32_16x16x32_bf16 v[16:19], v[168:171], v[176:179], v[16:19]
	v_mfma_f32_16x16x32_bf16 v[8:11], v[168:171], v[184:187], v[8:11]
	v_mfma_f32_16x16x32_bf16 v[56:59], v[168:171], v[192:195], v[56:59]
	v_mfma_f32_16x16x32_bf16 v[52:55], v[168:171], v[200:203], v[36:39]
	s_setprio 0
	s_barrier
	s_add_u32 s38, s42, 0x80080
	s_addc_u32 s39, s43, 0
	s_add_i32 s42, s44, s48
	v_lshl_add_u64 v[36:37], s[38:39], 0, v[146:147]
	s_mov_b32 m0, s42
	s_nop 0
	global_load_lds_dwordx4 v[36:37], off
	v_lshl_add_u64 v[36:37], s[38:39], 0, v[140:141]
	s_add_i32 m0, s42, 0x2000
	s_nop 0
	global_load_lds_dwordx4 v[36:37], off
	s_waitcnt vmcnt(6)
	s_barrier
	s_setprio 1
	v_mfma_f32_16x16x32_bf16 v[36:39], v[204:207], v[172:175], v[80:83]
	v_mfma_f32_16x16x32_bf16 v[80:83], v[208:211], v[176:179], v[36:39]
	v_mfma_f32_16x16x32_bf16 v[36:39], v[204:207], v[180:183], v[76:79]
	v_mfma_f32_16x16x32_bf16 v[76:79], v[208:211], v[184:187], v[36:39]
	v_mfma_f32_16x16x32_bf16 v[36:39], v[204:207], v[188:191], v[128:131]
	v_mfma_f32_16x16x32_bf16 v[128:131], v[208:211], v[192:195], v[36:39]
	v_mfma_f32_16x16x32_bf16 v[36:39], v[212:215], v[188:191], v[48:51]
	v_mfma_f32_16x16x32_bf16 v[48:51], v[216:219], v[192:195], v[36:39]
	v_mfma_f32_16x16x32_bf16 v[36:39], v[204:207], v[196:199], v[108:111]
	v_mfma_f32_16x16x32_bf16 v[12:15], v[212:215], v[172:175], v[12:15]
	v_mfma_f32_16x16x32_bf16 v[4:7], v[212:215], v[180:183], v[4:7]
	v_mfma_f32_16x16x32_bf16 v[108:111], v[208:211], v[200:203], v[36:39]
	v_mfma_f32_16x16x32_bf16 v[36:39], v[212:215], v[196:199], v[44:47]
	v_mfma_f32_16x16x32_bf16 v[12:15], v[216:219], v[176:179], v[12:15]
	v_mfma_f32_16x16x32_bf16 v[4:7], v[216:219], v[184:187], v[4:7]
	v_mfma_f32_16x16x32_bf16 v[44:47], v[216:219], v[200:203], v[36:39]
	s_setprio 0
	s_add_i32 s67, s67, 2
	s_add_u32 s65, s65, 0x100
	s_addc_u32 s66, s66, 0
	s_cmp_lt_u32 s67, 30
	s_mov_b64 s[38:39], s[40:41]
	s_barrier
	s_cbranch_scc1 .LBB0_2983
	v_lshl_add_u32 v160, s36, 8, v226
	v_ashrrev_i32_e32 v161, 31, v160
	v_lshl_add_u64 v[40:41], v[160:161], 2, s[90:91]
	global_load_dwordx4 v[36:39], v[40:41], off offset:16
	s_nop 0
	global_load_dwordx4 v[40:43], v[40:41], off
	s_mul_i32 s27, s36, 44
	s_add_i32 s27, s27, s63
	s_lshl_b32 s27, s27, 1
	s_add_i32 s36, s27, s47
	s_ashr_i32 s37, s36, 31
	v_mov_b32_e32 v162, v136
	v_mov_b32_e32 v163, v138
	s_lshl_b64 s[36:37], s[36:37], 11
	v_mov_b32_e32 v138, v137
	v_lshl_add_u64 v[158:159], v[148:149], 0, s[36:37]
	v_cmp_lt_i32_e32 vcc, 14, v3
	s_mov_b64 s[36:37], 0
	s_waitcnt vmcnt(0)
	v_pk_mul_f32 v[168:169], v[162:163], v[38:39] op_sel_hi:[1,0]
	v_mov_b32_e32 v162, v128
	v_mov_b32_e32 v163, v130
	v_mov_b32_e32 v130, v129
	v_pk_mul_f32 v[162:163], v[162:163], v[38:39] op_sel_hi:[1,0]
	v_pk_mul_f32 v[136:137], v[138:139], v[38:39] op_sel_hi:[1,0]
	v_pk_mul_f32 v[130:131], v[130:131], v[38:39] op_sel_hi:[1,0]
	s_and_saveexec_b64 s[38:39], vcc
	s_xor_b64 s[38:39], exec, s[38:39]
	s_cbranch_execz .LBB0_2986
	s_nop 7
	s_nop 1
	v_cvt_pk_bf16_f32 v139, v169, v137
	v_cvt_pk_bf16_f32 v138, v168, v136
	s_nop 7
	s_nop 1
	s_mov_b64 s[36:37], exec
	v_cvt_pk_bf16_f32 v129, v163, v131
	v_cvt_pk_bf16_f32 v128, v162, v130
	global_store_dwordx2 v[158:159], v[138:139], off offset:1024
.LBB0_2986:
	s_or_saveexec_b64 s[38:39], s[38:39]
	v_mov_b32_e32 v138, v132
	v_mov_b32_e32 v139, v134
	v_pk_mul_f32 v[190:191], v[138:139], v[40:41] op_sel_hi:[1,0]
	v_mov_b32_e32 v138, v120
	v_mov_b32_e32 v139, v122
	v_mov_b32_e32 v122, v121
	v_mov_b32_e32 v120, v124
	v_mov_b32_e32 v121, v126
	v_pk_mul_f32 v[182:183], v[120:121], v[40:41] op_sel:[0,1]
	v_mov_b32_e32 v120, v116
	v_mov_b32_e32 v121, v118
	v_mov_b32_e32 v118, v117
	v_mov_b32_e32 v116, v112
	v_mov_b32_e32 v117, v114
	v_mov_b32_e32 v112, v39
	v_mov_b32_e32 v134, v133
	v_pk_mul_f32 v[170:171], v[116:117], v[112:113] op_sel_hi:[1,0]
	v_mov_b32_e32 v116, v108
	v_mov_b32_e32 v117, v110
	v_mov_b32_e32 v114, v113
	v_mov_b32_e32 v110, v109
	v_pk_mul_f32 v[188:189], v[138:139], v[40:41] op_sel_hi:[1,0]
	v_pk_mul_f32 v[192:193], v[134:135], v[40:41] op_sel_hi:[1,0]
	v_mov_b32_e32 v126, v125
	v_pk_mul_f32 v[134:135], v[116:117], v[112:113] op_sel_hi:[1,0]
	v_pk_mul_f32 v[172:173], v[114:115], v[112:113] op_sel_hi:[1,0]
	v_pk_mul_f32 v[138:139], v[110:111], v[112:113] op_sel_hi:[1,0]
	v_pk_mul_f32 v[186:187], v[122:123], v[40:41] op_sel_hi:[1,0]
	v_pk_mul_f32 v[180:181], v[120:121], v[40:41] op_sel:[0,1]
	v_pk_mul_f32 v[184:185], v[126:127], v[40:41] op_sel:[0,1]
	v_pk_mul_f32 v[178:179], v[118:119], v[40:41] op_sel:[0,1]
	v_mov_b64_e32 v[116:117], 0x500
	v_mov_b64_e32 v[110:111], 0x600
	v_mov_b64_e32 v[108:109], 0x700
	v_mov_b64_e32 v[120:121], v[170:171]
	v_mov_b64_e32 v[118:119], v[172:173]
	v_mov_b64_e32 v[112:113], v[134:135]
	v_mov_b64_e32 v[114:115], v[138:139]
	s_xor_b64 exec, exec, s[38:39]
	s_cbranch_execz .LBB0_2990
	v_cmp_eq_u32_e32 vcc, 0, v3
	s_mov_b64 s[42:43], s[36:37]
	s_and_saveexec_b64 s[40:41], vcc
	s_cbranch_execz .LBB0_2989
	s_nop 7
	s_nop 3
	v_cvt_pk_bf16_f32 v109, v191, v193
	v_cvt_pk_bf16_f32 v108, v190, v192
	s_nop 7
	v_cvt_pk_bf16_f32 v129, v189, v187
	v_cvt_pk_bf16_f32 v128, v188, v186
	s_or_b64 s[42:43], s[36:37], exec
	global_store_dwordx2 v[158:159], v[108:109], off

; __device__ __forceinline__ unsigned pk2(float lo, float hi) { return f2bf(lo) | (f2bf(hi) << 16); }
; __device__ __forceinline__ float dpp_shr1(float x) { return __builtin_bit_cast(float, __builtin_amdgcn_update_dpp(0, __builtin_bit_cast(int, x), 0x111, 0xf, 0xf, true)); }
;     __device__ __forceinline__ void operator()(const f32x4 (&acc)[2][2][4][2], const pg8::Unit& u, int wr, int wc, int fr, int fq) const {
;     ...
;             if (fr == 0) {
; #pragma unroll
;                 for (int q = 0; q < 2; ++q) { v2u a, b; a.x = pk2(g[q][0], g[q][1]); a.y = pk2(g[q][2], g[q][3]); b.x = pk2(v[q][0], v[q][1]); b.y = pk2(v[q][2], v[q][3]);
;                     *(v2u*)(hb + (size_t)q * 256 + 4 * n) = a; *(v2u*)(hb + (size_t)q * 256 + 128 + 4 * n) = b; } }
;             if (fr == 15) {
; #pragma unroll
;                 for (int q = 0; q < 2; ++q) { v2u a, b; a.x = pk2(g[6 + q][0], g[6 + q][1]); a.y = pk2(g[6 + q][2], g[6 + q][3]); b.x = pk2(v[6 + q][0], v[6 + q][1]); b.y = pk2(v[6 + q][2], v[6 + q][3]);
;                     *(v2u*)(hb + (size_t)(2 + q) * 256 + 4 * n) = a; *(v2u*)(hb + (size_t)(2 + q) * 256 + 128 + 4 * n) = b; } }
;             const int cc = ch0 + 4 * n;
;             const f32x4 wg0 = *(CF4)(cw + cc), wg1 = *(CF4)(cw + FF2 + cc), wg2 = *(CF4)(cw + 2 * FF2 + cc), wv0 = *(CF4)(cw + FFH + cc), wv1 = *(CF4)(cw + FF2 + FFH + cc), wv2 = *(CF4)(cw + 2 * FF2 + FFH + cc);
;             const f32x4 bg = *(CF4)(cb + cc), bv = *(CF4)(cb + FFH + cc);
; #pragma unroll
;             for (int jj = 0; jj < 4; ++jj) {
;                 float g2 = dpp_shr1(g[6][jj]), g1 = dpp_shr1(g[7][jj]), v2 = dpp_shr1(v[6][jj]), v1 = dpp_shr1(v[7][jj]);
.LBB0_2990:
	s_or_b64 exec, exec, s[38:39]
	s_and_saveexec_b64 s[38:39], s[36:37]
	s_cbranch_execz .LBB0_2992
	v_lshl_add_u64 v[116:117], v[158:159], 0, v[116:117]
	global_store_dwordx2 v[116:117], v[128:129], off
	v_and_b32_sdwa v116, v121, v234 dst_sel:DWORD dst_unused:UNUSED_PAD src0_sel:WORD_1 src1_sel:DWORD
	s_nop 1
	v_add3_u32 v116, v121, v116, s61
	v_and_b32_sdwa v117, v119, v234 dst_sel:DWORD dst_unused:UNUSED_PAD src0_sel:WORD_1 src1_sel:DWORD
	s_nop 0
	v_add3_u32 v117, v119, v117, s61
	s_nop 0
	v_and_b32_e32 v117, 0xffff0000, v117
	s_nop 0
	v_or_b32_sdwa v117, v117, v116 dst_sel:DWORD dst_unused:UNUSED_PAD src0_sel:DWORD src1_sel:WORD_1
	v_cvt_pk_bf16_f32 v116, v120, v118
	s_nop 7
	s_nop 1
	v_cvt_pk_bf16_f32 v113, v113, v115
	v_cvt_pk_bf16_f32 v112, v112, v114
	v_lshl_add_u64 v[110:111], v[158:159], 0, v[110:111]
	v_lshl_add_u64 v[108:109], v[158:159], 0, v[108:109]
	global_store_dwordx2 v[110:111], v[116:117], off
	global_store_dwordx2 v[108:109], v[112:113], off
.LBB0_2992:
	s_or_b64 exec, exec, s[38:39]
	v_lshl_or_b32 v132, s63, 7, v227
	v_ashrrev_i32_e32 v133, 31, v132
	v_lshlrev_b64 v[194:195], 2, v[132:133]
	v_lshl_add_u64 v[108:109], s[8:9], 0, v[194:195]
	v_lshl_add_u64 v[112:113], s[10:11], 0, v[194:195]
	global_load_dwordx4 v[108:111], v[108:109], off
	v_mov_b32_e32 v166, v43
	global_load_dwordx4 v[116:119], v[112:113], off
	v_lshl_add_u64 v[112:113], s[14:15], 0, v[194:195]
	global_load_dwordx4 v[120:123], v[112:113], off
	v_lshl_add_u64 v[112:113], s[16:17], 0, v[194:195]
	global_load_dwordx4 v[124:127], v[112:113], off
	v_mov_b32_e32 v112, v104
	v_mov_b32_e32 v113, v106
	v_pk_mul_f32 v[224:225], v[112:113], v[42:43] op_sel_hi:[1,0]
	v_mov_b32_e32 v112, v96
	v_mov_b32_e32 v113, v98
	v_mov_b32_e32 v98, v97
	v_lshl_add_u64 v[96:97], s[18:19], 0, v[194:195]
	v_pk_mul_f32 v[218:219], v[98:99], v[42:43] op_sel_hi:[1,0]
	global_load_dwordx4 v[96:99], v[96:97], off
	v_pk_mul_f32 v[220:221], v[112:113], v[42:43] op_sel_hi:[1,0]
	v_mov_b32_e32 v106, v105
	v_mov_b32_e32 v112, v100
	v_mov_b32_e32 v113, v102
	v_lshl_add_u64 v[104:105], s[24:25], 0, v[194:195]
	v_pk_mul_f32 v[222:223], v[106:107], v[42:43] op_sel_hi:[1,0]
	global_load_dwordx4 v[104:107], v[104:105], off
	v_pk_mul_f32 v[214:215], v[112:113], v[166:167] op_sel_hi:[1,0]
	v_lshl_add_u64 v[112:113], s[20:21], 0, v[194:195]
	global_load_dwordx4 v[112:115], v[112:113], off
	v_mov_b32_e32 v102, v101
	v_lshl_add_u64 v[100:101], s[22:23], 0, v[194:195]
	v_pk_mul_f32 v[216:217], v[102:103], v[166:167] op_sel_hi:[1,0]
	global_load_dwordx4 v[100:103], v[100:101], off
	v_mov_b32_e32 v199, v94
	v_mov_b32_e32 v94, v93
	v_mov_b32_e32 v196, v36
	v_mov_b32_e32 v197, v37
	v_pk_mul_f32 v[206:207], v[94:95], v[166:167] op_sel_hi:[1,0]
	v_mov_b32_e32 v94, v88
	v_mov_b32_e32 v95, v90
	v_pk_mul_f32 v[202:203], v[94:95], v[196:197] op_sel_hi:[1,0]
	v_mov_b32_e32 v94, v80
	v_mov_b32_e32 v95, v82
	v_mov_b32_e32 v82, v81
	v_mov_b32_e32 v80, v84
	v_mov_b32_e32 v81, v86
	v_mov_b32_e32 v90, v89
	v_pk_mul_f32 v[88:89], v[80:81], v[196:197] op_sel:[0,1]
	v_mov_b32_e32 v81, v78
	v_mov_b32_e32 v86, v85
	v_mov_b32_e32 v78, v77
	v_pk_mul_f32 v[194:195], v[94:95], v[196:197] op_sel_hi:[1,0]
	v_mov_b32_e32 v80, v76
	v_pk_mul_f32 v[84:85], v[86:87], v[196:197] op_sel:[0,1]
	v_pk_mul_f32 v[76:77], v[78:79], v[196:197] op_sel:[0,1]
	v_mov_b32_dpp v78, v168 row_shr:1 row_mask:0xf bank_mask:0xf bound_ctrl:1
	v_mov_b32_dpp v79, v169 row_shr:1 row_mask:0xf bank_mask:0xf bound_ctrl:1
	v_mov_b32_e32 v198, v92
	v_pk_mul_f32 v[200:201], v[90:91], v[196:197] op_sel_hi:[1,0]
	v_pk_mul_f32 v[90:91], v[82:83], v[196:197] op_sel_hi:[1,0]
	v_pk_mul_f32 v[82:83], v[80:81], v[196:197] op_sel:[0,1]
	v_mov_b32_dpp v80, v170 row_shr:1 row_mask:0xf bank_mask:0xf bound_ctrl:1
	v_mov_b32_dpp v81, v171 row_shr:1 row_mask:0xf bank_mask:0xf bound_ctrl:1
	v_pk_mul_f32 v[208:209], v[198:199], v[166:167] op_sel_hi:[1,0]
	v_mov_b32_dpp v210, v136 row_shr:1 row_mask:0xf bank_mask:0xf bound_ctrl:1
	v_mov_b32_dpp v211, v137 row_shr:1 row_mask:0xf bank_mask:0xf bound_ctrl:1
	v_mov_b32_dpp v238, v172 row_shr:1 row_mask:0xf bank_mask:0xf bound_ctrl:1
	v_mov_b32_dpp v239, v173 row_shr:1 row_mask:0xf bank_mask:0xf bound_ctrl:1
	v_mov_b32_dpp v204, v162 row_shr:1 row_mask:0xf bank_mask:0xf bound_ctrl:1
	v_mov_b32_dpp v205, v163 row_shr:1 row_mask:0xf bank_mask:0xf bound_ctrl:1
	v_mov_b32_dpp v236, v134 row_shr:1 row_mask:0xf bank_mask:0xf bound_ctrl:1
	v_mov_b32_dpp v237, v135 row_shr:1 row_mask:0xf bank_mask:0xf bound_ctrl:1
	v_mov_b32_dpp v212, v130 row_shr:1 row_mask:0xf bank_mask:0xf bound_ctrl:1
	v_mov_b32_dpp v213, v131 row_shr:1 row_mask:0xf bank_mask:0xf bound_ctrl:1
	v_mov_b32_dpp v240, v138 row_shr:1 row_mask:0xf bank_mask:0xf bound_ctrl:1
	v_mov_b32_dpp v241, v139 row_shr:1 row_mask:0xf bank_mask:0xf bound_ctrl:1
	v_mov_b32_e32 v174, v40
	v_mov_b32_e32 v175, v40
	v_mov_b32_e32 v40, v41
	v_mov_b32_e32 v176, v38
	v_mov_b32_e32 v177, v38
	v_mov_b32_e32 v38, v39
	v_mov_b32_e32 v128, v42
	s_waitcnt vmcnt(0)
; __device__ __forceinline__ unsigned pk2(float lo, float hi) { return f2bf(lo) | (f2bf(hi) << 16); }
; __device__ __forceinline__ float silu_fast(float x) { return x * __builtin_amdgcn_rcpf(1.f + __builtin_amdgcn_exp2f(-1.4426950408889634f * x)); }
; __device__ __forceinline__ float dpp_shr1(float x) { return __builtin_bit_cast(float, __builtin_amdgcn_update_dpp(0, __builtin_bit_cast(int, x), 0x111, 0xf, 0xf, true)); }
;     __device__ __forceinline__ void operator()(const f32x4 (&acc)[2][2][4][2], const pg8::Unit& u, int wr, int wc, int fr, int fq) const {
;     ...
;             for (int jj = 0; jj < 4; ++jj) {
;                 float g2 = dpp_shr1(g[6][jj]), g1 = dpp_shr1(g[7][jj]), v2 = dpp_shr1(v[6][jj]), v1 = dpp_shr1(v[7][jj]);
; #pragma unroll
;                 for (int e = 0; e < 8; ++e) { const float g0 = g[e][jj], v0 = v[e][jj];
;                     const float cg = bg[jj] + wg0[jj] * g2 + wg1[jj] * g1 + wg2[jj] * g0, cv = bv[jj] + wv0[jj] * v2 + wv1[jj] * v1 + wv2[jj] * v0;
;                     g[e][jj] = silu_fast(cg) * cv; g2 = g1; g1 = g0; v2 = v1; v1 = v0; } }
; #pragma unroll
;             for (int e = 0; e < 8; ++e) { v2u w; w.x = pk2(g[e][0], g[e][1]); w.y = pk2(g[e][2], g[e][3]); *(v2u*)(ACT + (size_t)(tok0 + e) * FFH + cc) = w; }
	v_mov_b32_e32 v86, v108
	v_mov_b32_e32 v87, v110
	v_mov_b32_e32 v94, v116
	v_mov_b32_e32 v95, v118
	v_pk_fma_f32 v[78:79], v[86:87], v[78:79], v[94:95]
	v_mov_b32_e32 v196, v120
	v_mov_b32_e32 v197, v122
	v_pk_fma_f32 v[78:79], v[196:197], v[80:81], v[78:79]
	v_mov_b32_e32 v198, v124
	v_mov_b32_e32 v199, v126
	v_pk_fma_f32 v[78:79], v[190:191], v[198:199], v[78:79]
	v_mov_b32_e32 v110, v109
	v_mul_f32_e32 v108, 0xbfb8aa3b, v78
	v_mov_b32_e32 v118, v117
	v_exp_f32_e32 v116, v108
	v_pk_fma_f32 v[108:109], v[110:111], v[210:211], v[118:119]
	v_mov_b32_e32 v122, v121
	v_pk_fma_f32 v[108:109], v[122:123], v[238:239], v[108:109]
	v_mov_b32_e32 v126, v125
	v_pk_fma_f32 v[108:109], v[192:193], v[126:127], v[108:109]
	v_add_f32_e32 v116, 1.0, v116
	v_mul_f32_e32 v117, 0xbfb8aa3b, v108
	v_exp_f32_e32 v117, v117
	v_rcp_f32_e32 v210, v116
	v_mov_b32_e32 v120, v104
	v_mov_b32_e32 v121, v106
	v_add_f32_e32 v116, 1.0, v117
	v_rcp_f32_e32 v242, v116
	v_mov_b32_e32 v116, v96
	v_mul_f32_e32 v96, 0xbfb8aa3b, v79
	v_exp_f32_e32 v96, v96
	v_mov_b32_e32 v117, v98
	v_pk_fma_f32 v[124:125], v[116:117], v[204:205], v[120:121]
	v_mov_b32_e32 v204, v112
	v_add_f32_e32 v96, 1.0, v96
	v_mov_b32_e32 v205, v114
	v_rcp_f32_e32 v211, v96
	v_mul_f32_e32 v96, 0xbfb8aa3b, v109
	v_pk_fma_f32 v[244:245], v[204:205], v[236:237], v[124:125]
	v_mov_b32_e32 v124, v100
	v_exp_f32_e32 v100, v96
	v_mov_b32_e32 v98, v97
	v_mov_b32_e32 v106, v105
	v_mov_b32_e32 v125, v102
	v_add_f32_e32 v100, 1.0, v100
	v_rcp_f32_e32 v243, v100
	v_pk_fma_f32 v[96:97], v[98:99], v[212:213], v[106:107]
	v_mov_b32_e32 v114, v113
	v_pk_fma_f32 v[244:245], v[188:189], v[124:125], v[244:245]
	v_pk_mul_f32 v[78:79], v[78:79], v[210:211]
	v_pk_fma_f32 v[96:97], v[114:115], v[240:241], v[96:97]
	v_mov_b32_e32 v102, v101
	v_pk_mul_f32 v[78:79], v[244:245], v[78:79]
	v_pk_fma_f32 v[96:97], v[186:187], v[102:103], v[96:97]
	v_pk_mul_f32 v[100:101], v[108:109], v[242:243]
	v_pk_fma_f32 v[80:81], v[86:87], v[80:81], v[94:95]
	v_pk_mul_f32 v[96:97], v[96:97], v[100:101]
	s_nop 7
	s_nop 1
	v_mov_b64_e32 v[210:211], s[78:79]
	v_pk_fma_f32 v[80:81], v[190:191], v[196:197], v[80:81]
	v_cvt_pk_bf16_f32 v79, v79, v97
	v_cvt_pk_bf16_f32 v78, v78, v96
	v_mad_i64_i32 v[96:97], s[36:37], v160, s62, v[210:211]
	v_lshlrev_b64 v[212:213], 1, v[132:133]
	v_pk_fma_f32 v[80:81], v[182:183], v[198:199], v[80:81]
	v_lshl_add_u64 v[112:113], v[96:97], 0, v[212:213]
	v_mul_f32_e32 v96, 0xbfb8aa3b, v80
	v_exp_f32_e32 v100, v96
	v_pk_fma_f32 v[96:97], v[110:111], v[238:239], v[118:119]
	global_store_dwordx2 v[112:113], v[78:79], off
	v_pk_fma_f32 v[96:97], v[192:193], v[122:123], v[96:97]
	v_add_f32_e32 v78, 1.0, v100
	v_pk_fma_f32 v[96:97], v[184:185], v[126:127], v[96:97]
	v_mul_f32_e32 v100, 0xbfb8aa3b, v81
	v_mul_f32_e32 v101, 0xbfb8aa3b, v96
	v_exp_f32_e32 v101, v101
	v_rcp_f32_e32 v78, v78
	v_pk_fma_f32 v[104:105], v[116:117], v[236:237], v[120:121]
	v_mov_b32_e32 v129, v42
	v_add_f32_e32 v79, 1.0, v101
	v_exp_f32_e32 v101, v100
	v_rcp_f32_e32 v100, v79
	v_pk_fma_f32 v[104:105], v[188:189], v[204:205], v[104:105]
	v_mov_b32_e32 v42, v43
	v_add_f32_e32 v79, 1.0, v101
	v_mul_f32_e32 v101, 0xbfb8aa3b, v97
	v_rcp_f32_e32 v79, v79
	v_exp_f32_e32 v101, v101
	v_pk_fma_f32 v[104:105], v[180:181], v[124:125], v[104:105]
	v_mov_b32_e32 v92, v36
	v_pk_mul_f32 v[78:79], v[80:81], v[78:79]
	v_add_f32_e32 v80, 1.0, v101
	v_rcp_f32_e32 v101, v80
	v_pk_fma_f32 v[80:81], v[98:99], v[240:241], v[106:107]
	v_pk_mul_f32 v[78:79], v[104:105], v[78:79]
	v_pk_fma_f32 v[80:81], v[186:187], v[114:115], v[80:81]
	v_pk_mul_f32 v[96:97], v[96:97], v[100:101]
	v_pk_fma_f32 v[80:81], v[178:179], v[102:103], v[80:81]
	v_pk_fma_f32 v[104:105], v[188:189], v[116:117], v[120:121]
	v_pk_mul_f32 v[80:81], v[80:81], v[96:97]
	s_nop 7
	s_nop 1
	v_cvt_pk_bf16_f32 v78, v78, v80
	v_or_b32_e32 v80, 1, v160
	v_cvt_pk_bf16_f32 v79, v79, v81
	v_mad_i64_i32 v[80:81], s[36:37], v80, s62, v[210:211]
	v_lshl_add_u64 v[108:109], v[80:81], 0, v[212:213]
	v_pk_fma_f32 v[80:81], v[190:191], v[86:87], v[94:95]
	global_store_dwordx2 v[108:109], v[78:79], off
	v_pk_fma_f32 v[80:81], v[182:183], v[196:197], v[80:81]
	v_pk_fma_f32 v[104:105], v[180:181], v[204:205], v[104:105]
	v_pk_fma_f32 v[80:81], v[224:225], v[198:199], v[80:81]
	v_pk_fma_f32 v[104:105], v[220:221], v[124:125], v[104:105]
	v_mul_f32_e32 v96, 0xbfb8aa3b, v80
	v_exp_f32_e32 v100, v96
	v_pk_fma_f32 v[96:97], v[192:193], v[110:111], v[118:119]
	v_pk_fma_f32 v[180:181], v[180:181], v[116:117], v[120:121]
	v_pk_fma_f32 v[96:97], v[184:185], v[122:123], v[96:97]
	v_add_f32_e32 v78, 1.0, v100
	v_pk_fma_f32 v[96:97], v[222:223], v[126:127], v[96:97]
	v_mul_f32_e32 v100, 0xbfb8aa3b, v81
	v_mul_f32_e32 v101, 0xbfb8aa3b, v96
	v_exp_f32_e32 v101, v101
	v_rcp_f32_e32 v78, v78
	v_pk_fma_f32 v[180:181], v[220:221], v[204:205], v[180:181]
	v_mov_b32_e32 v93, v36
	v_add_f32_e32 v79, 1.0, v101
	v_exp_f32_e32 v101, v100
	v_rcp_f32_e32 v100, v79
	v_pk_fma_f32 v[180:181], v[208:209], v[124:125], v[180:181]
	v_mov_b32_e32 v36, v37
	v_add_f32_e32 v79, 1.0, v101
	v_mul_f32_e32 v101, 0xbfb8aa3b, v97
	v_rcp_f32_e32 v79, v79
	v_exp_f32_e32 v101, v101
	v_cmp_gt_i32_e32 vcc, 15, v3
	s_mov_b64 s[38:39], -1
	v_pk_mul_f32 v[78:79], v[80:81], v[78:79]
	v_add_f32_e32 v80, 1.0, v101
	v_rcp_f32_e32 v101, v80
	v_pk_fma_f32 v[80:81], v[186:187], v[98:99], v[106:107]
	v_pk_mul_f32 v[78:79], v[104:105], v[78:79]
	v_pk_fma_f32 v[80:81], v[178:179], v[114:115], v[80:81]
	v_pk_mul_f32 v[96:97], v[96:97], v[100:101]
	v_pk_fma_f32 v[80:81], v[218:219], v[102:103], v[80:81]
	s_nop 0
	v_pk_mul_f32 v[80:81], v[80:81], v[96:97]
	s_nop 7
	s_nop 1
; __device__ __forceinline__ unsigned pk2(float lo, float hi) { return f2bf(lo) | (f2bf(hi) << 16); }
; __device__ __forceinline__ float silu_fast(float x) { return x * __builtin_amdgcn_rcpf(1.f + __builtin_amdgcn_exp2f(-1.4426950408889634f * x)); }
; __device__ __forceinline__ float dpp_shr1(float x) { return __builtin_bit_cast(float, __builtin_amdgcn_update_dpp(0, __builtin_bit_cast(int, x), 0x111, 0xf, 0xf, true)); }
;     __device__ __forceinline__ void operator()(const f32x4 (&acc)[2][2][4][2], const pg8::Unit& u, int wr, int wc, int fr, int fq) const {
;     ...
;             for (int jj = 0; jj < 4; ++jj) {
;                 float g2 = dpp_shr1(g[6][jj]), g1 = dpp_shr1(g[7][jj]), v2 = dpp_shr1(v[6][jj]), v1 = dpp_shr1(v[7][jj]);
; #pragma unroll
;                 for (int e = 0; e < 8; ++e) { const float g0 = g[e][jj], v0 = v[e][jj];
;                     const float cg = bg[jj] + wg0[jj] * g2 + wg1[jj] * g1 + wg2[jj] * g0, cv = bv[jj] + wv0[jj] * v2 + wv1[jj] * v1 + wv2[jj] * v0;
;                     g[e][jj] = silu_fast(cg) * cv; g2 = g1; g1 = g0; v2 = v1; v1 = v0; } }
; #pragma unroll
;             for (int e = 0; e < 8; ++e) { v2u w; w.x = pk2(g[e][0], g[e][1]); w.y = pk2(g[e][2], g[e][3]); *(v2u*)(ACT + (size_t)(tok0 + e) * FFH + cc) = w; }
	v_cvt_pk_bf16_f32 v78, v78, v80
	v_or_b32_e32 v80, 2, v160
	v_cvt_pk_bf16_f32 v79, v79, v81
	v_mad_i64_i32 v[80:81], s[36:37], v80, s62, v[210:211]
	v_lshl_add_u64 v[104:105], v[80:81], 0, v[212:213]
	v_pk_fma_f32 v[80:81], v[182:183], v[86:87], v[94:95]
	global_store_dwordx2 v[104:105], v[78:79], off
	v_pk_fma_f32 v[80:81], v[224:225], v[196:197], v[80:81]
	v_pk_fma_f32 v[182:183], v[208:209], v[116:117], v[120:121]
	v_pk_fma_f32 v[80:81], v[214:215], v[198:199], v[80:81]
	v_pk_fma_f32 v[182:183], v[194:195], v[204:205], v[182:183]
	v_mul_f32_e32 v96, 0xbfb8aa3b, v80
	v_exp_f32_e32 v100, v96
	v_pk_fma_f32 v[96:97], v[184:185], v[110:111], v[118:119]
	v_pk_fma_f32 v[182:183], v[82:83], v[124:125], v[182:183]
	v_pk_fma_f32 v[96:97], v[222:223], v[122:123], v[96:97]
	v_add_f32_e32 v78, 1.0, v100
	v_pk_fma_f32 v[96:97], v[216:217], v[126:127], v[96:97]
	v_mul_f32_e32 v100, 0xbfb8aa3b, v81
	v_mul_f32_e32 v101, 0xbfb8aa3b, v96
	v_exp_f32_e32 v101, v101
	v_rcp_f32_e32 v78, v78
	v_pk_fma_f32 v[184:185], v[194:195], v[116:117], v[120:121]
	v_add_f32_e32 v79, 1.0, v101
	v_exp_f32_e32 v101, v100
	v_rcp_f32_e32 v100, v79
	v_pk_fma_f32 v[184:185], v[82:83], v[204:205], v[184:185]
	v_pk_fma_f32 v[82:83], v[82:83], v[116:117], v[120:121]
	v_add_f32_e32 v79, 1.0, v101
	v_mul_f32_e32 v101, 0xbfb8aa3b, v97
	v_rcp_f32_e32 v79, v79
	v_exp_f32_e32 v101, v101
	v_pk_fma_f32 v[184:185], v[162:163], v[124:125], v[184:185]
	v_pk_fma_f32 v[82:83], v[162:163], v[204:205], v[82:83]
	v_pk_mul_f32 v[78:79], v[80:81], v[78:79]
	v_add_f32_e32 v80, 1.0, v101
	v_rcp_f32_e32 v101, v80
	v_pk_fma_f32 v[80:81], v[178:179], v[98:99], v[106:107]
	v_pk_mul_f32 v[78:79], v[180:181], v[78:79]
	v_pk_fma_f32 v[80:81], v[218:219], v[114:115], v[80:81]
	v_pk_mul_f32 v[96:97], v[96:97], v[100:101]
	v_pk_fma_f32 v[80:81], v[206:207], v[102:103], v[80:81]
	v_pk_fma_f32 v[180:181], v[220:221], v[116:117], v[120:121]
	v_pk_mul_f32 v[80:81], v[80:81], v[96:97]
	s_nop 7
	s_nop 1
	v_cvt_pk_bf16_f32 v78, v78, v80
	v_or_b32_e32 v80, 3, v160
	v_cvt_pk_bf16_f32 v79, v79, v81
	v_mad_i64_i32 v[80:81], s[36:37], v80, s62, v[210:211]
	v_lshl_add_u64 v[100:101], v[80:81], 0, v[212:213]
	v_pk_fma_f32 v[80:81], v[224:225], v[86:87], v[94:95]
	global_store_dwordx2 v[100:101], v[78:79], off
	v_pk_fma_f32 v[80:81], v[214:215], v[196:197], v[80:81]
	v_pk_fma_f32 v[180:181], v[208:209], v[204:205], v[180:181]
	v_pk_fma_f32 v[80:81], v[202:203], v[198:199], v[80:81]
	v_pk_fma_f32 v[180:181], v[194:195], v[124:125], v[180:181]
	v_mul_f32_e32 v96, 0xbfb8aa3b, v80
	v_exp_f32_e32 v133, v96
	v_pk_fma_f32 v[96:97], v[222:223], v[110:111], v[118:119]
	v_pk_fma_f32 v[82:83], v[134:135], v[124:125], v[82:83]
	v_pk_fma_f32 v[96:97], v[216:217], v[122:123], v[96:97]
	v_add_f32_e32 v78, 1.0, v133
	v_pk_fma_f32 v[96:97], v[200:201], v[126:127], v[96:97]
	v_mul_f32_e32 v133, 0xbfb8aa3b, v81
	v_mul_f32_e32 v161, 0xbfb8aa3b, v96
	v_exp_f32_e32 v161, v161
	v_exp_f32_e32 v133, v133
	v_rcp_f32_e32 v78, v78
	v_add_f32_e32 v79, 1.0, v161
	v_rcp_f32_e32 v178, v79
	v_add_f32_e32 v79, 1.0, v133
	v_mul_f32_e32 v133, 0xbfb8aa3b, v97
	v_rcp_f32_e32 v79, v79
	v_exp_f32_e32 v133, v133
	v_pk_mul_f32 v[78:79], v[80:81], v[78:79]
	v_add_f32_e32 v80, 1.0, v133
	v_rcp_f32_e32 v179, v80
	v_pk_fma_f32 v[80:81], v[218:219], v[98:99], v[106:107]
	v_pk_mul_f32 v[78:79], v[180:181], v[78:79]
	v_pk_fma_f32 v[80:81], v[206:207], v[114:115], v[80:81]
	v_pk_mul_f32 v[96:97], v[96:97], v[178:179]
	v_pk_fma_f32 v[80:81], v[90:91], v[102:103], v[80:81]
	v_pk_fma_f32 v[178:179], v[216:217], v[110:111], v[118:119]
	v_pk_mul_f32 v[80:81], v[80:81], v[96:97]
	s_nop 7
	s_nop 1
	v_cvt_pk_bf16_f32 v78, v78, v80
	v_or_b32_e32 v80, 4, v160
	v_cvt_pk_bf16_f32 v79, v79, v81
	v_mad_i64_i32 v[80:81], s[36:37], v80, s62, v[210:211]
	v_lshl_add_u64 v[96:97], v[80:81], 0, v[212:213]
	v_pk_fma_f32 v[80:81], v[214:215], v[86:87], v[94:95]
	v_pk_fma_f32 v[178:179], v[200:201], v[122:123], v[178:179]
	v_pk_fma_f32 v[80:81], v[202:203], v[196:197], v[80:81]
	v_pk_fma_f32 v[178:179], v[84:85], v[126:127], v[178:179]
	v_pk_fma_f32 v[80:81], v[88:89], v[198:199], v[80:81]
	v_mul_f32_e32 v161, 0xbfb8aa3b, v178
	v_mul_f32_e32 v133, 0xbfb8aa3b, v80
	v_exp_f32_e32 v133, v133
	v_exp_f32_e32 v161, v161
	global_store_dwordx2 v[96:97], v[78:79], off
	v_add_f32_e32 v78, 1.0, v133
	v_mul_f32_e32 v133, 0xbfb8aa3b, v81
	v_exp_f32_e32 v133, v133
	v_add_f32_e32 v79, 1.0, v161
	v_rcp_f32_e32 v180, v79
	v_rcp_f32_e32 v78, v78
	v_add_f32_e32 v79, 1.0, v133
	v_mul_f32_e32 v133, 0xbfb8aa3b, v179
	v_rcp_f32_e32 v79, v79
	v_exp_f32_e32 v133, v133
	v_pk_mul_f32 v[78:79], v[80:81], v[78:79]
	v_add_f32_e32 v80, 1.0, v133
	v_rcp_f32_e32 v181, v80
	v_pk_fma_f32 v[80:81], v[206:207], v[98:99], v[106:107]
	v_pk_mul_f32 v[78:79], v[182:183], v[78:79]
	v_pk_fma_f32 v[80:81], v[90:91], v[114:115], v[80:81]
	v_pk_mul_f32 v[178:179], v[178:179], v[180:181]
	v_pk_fma_f32 v[80:81], v[76:77], v[102:103], v[80:81]
	s_nop 0
	v_pk_mul_f32 v[80:81], v[80:81], v[178:179]
	v_pk_fma_f32 v[178:179], v[202:203], v[86:87], v[94:95]
	s_nop 0
	v_pk_fma_f32 v[178:179], v[88:89], v[196:197], v[178:179]
	s_nop 3
	v_pk_fma_f32 v[178:179], v[168:169], v[198:199], v[178:179]
	s_nop 1
	v_mul_f32_e32 v133, 0xbfb8aa3b, v178
	s_nop 0
	v_exp_f32_e32 v133, v133
	v_pk_fma_f32 v[180:181], v[200:201], v[110:111], v[118:119]
	s_nop 0
	v_cvt_pk_bf16_f32 v78, v78, v80
	v_or_b32_e32 v80, 5, v160
	v_pk_fma_f32 v[180:181], v[84:85], v[122:123], v[180:181]
	v_cvt_pk_bf16_f32 v79, v79, v81
	v_mad_i64_i32 v[80:81], s[36:37], v80, s62, v[210:211]
	v_pk_fma_f32 v[180:181], v[136:137], v[126:127], v[180:181]
	v_lshl_add_u64 v[80:81], v[80:81], 0, v[212:213]
; __device__ __forceinline__ unsigned pk2(float lo, float hi) { return f2bf(lo) | (f2bf(hi) << 16); }
; __device__ __forceinline__ float silu_fast(float x) { return x * __builtin_amdgcn_rcpf(1.f + __builtin_amdgcn_exp2f(-1.4426950408889634f * x)); }
; __device__ __forceinline__ float dpp_shr1(float x) { return __builtin_bit_cast(float, __builtin_amdgcn_update_dpp(0, __builtin_bit_cast(int, x), 0x111, 0xf, 0xf, true)); }
;     __device__ __forceinline__ void operator()(const f32x4 (&acc)[2][2][4][2], const pg8::Unit& u, int wr, int wc, int fr, int fq) const {
;     ...
;             for (int e = 0; e < 8; ++e) { const float rs = (e < 4) ? r0[e & 3] : r1[e & 3];
; #pragma unroll
;                 for (int jj = 0; jj < 4; ++jj) { g[e][jj] = acc[e >> 2][0][e & 3][n][jj] * rs; v[e][jj] = acc[e >> 2][1][e & 3][n][jj] * rs; } }
;             if (fr == 0) {
; #pragma unroll
;                 for (int q = 0; q < 2; ++q) { v2u a, b; a.x = pk2(g[q][0], g[q][1]); a.y = pk2(g[q][2], g[q][3]); b.x = pk2(v[q][0], v[q][1]); b.y = pk2(v[q][2], v[q][3]);
;                     *(v2u*)(hb + (size_t)q * 256 + 4 * n) = a; *(v2u*)(hb + (size_t)q * 256 + 128 + 4 * n) = b; } }
;             if (fr == 15) {
; #pragma unroll
;                 for (int q = 0; q < 2; ++q) { v2u a, b; a.x = pk2(g[6 + q][0], g[6 + q][1]); a.y = pk2(g[6 + q][2], g[6 + q][3]); b.x = pk2(v[6 + q][0], v[6 + q][1]); b.y = pk2(v[6 + q][2], v[6 + q][3]);
;                     *(v2u*)(hb + (size_t)(2 + q) * 256 + 4 * n) = a; *(v2u*)(hb + (size_t)(2 + q) * 256 + 128 + 4 * n) = b; } }
;     ...
;             for (int jj = 0; jj < 4; ++jj) {
;                 float g2 = dpp_shr1(g[6][jj]), g1 = dpp_shr1(g[7][jj]), v2 = dpp_shr1(v[6][jj]), v1 = dpp_shr1(v[7][jj]);
; #pragma unroll
;                 for (int e = 0; e < 8; ++e) { const float g0 = g[e][jj], v0 = v[e][jj];
;                     const float cg = bg[jj] + wg0[jj] * g2 + wg1[jj] * g1 + wg2[jj] * g0, cv = bv[jj] + wv0[jj] * v2 + wv1[jj] * v1 + wv2[jj] * v0;
;                     g[e][jj] = silu_fast(cg) * cv; g2 = g1; g1 = g0; v2 = v1; v1 = v0; } }
; #pragma unroll
;             for (int e = 0; e < 8; ++e) { v2u w; w.x = pk2(g[e][0], g[e][1]); w.y = pk2(g[e][2], g[e][3]); *(v2u*)(ACT + (size_t)(tok0 + e) * FFH + cc) = w; }
	v_mul_f32_e32 v161, 0xbfb8aa3b, v180
	v_exp_f32_e32 v161, v161
	global_store_dwordx2 v[80:81], v[78:79], off
	v_add_f32_e32 v78, 1.0, v133
	v_mul_f32_e32 v133, 0xbfb8aa3b, v179
	v_exp_f32_e32 v133, v133
	v_add_f32_e32 v79, 1.0, v161
	v_rcp_f32_e32 v182, v79
	v_rcp_f32_e32 v78, v78
	v_add_f32_e32 v79, 1.0, v133
	v_mul_f32_e32 v133, 0xbfb8aa3b, v181
	v_exp_f32_e32 v133, v133
	v_rcp_f32_e32 v79, v79
	v_pk_fma_f32 v[90:91], v[90:91], v[98:99], v[106:107]
	v_pk_fma_f32 v[84:85], v[84:85], v[110:111], v[118:119]
	v_add_f32_e32 v133, 1.0, v133
	v_rcp_f32_e32 v183, v133
	v_pk_mul_f32 v[78:79], v[178:179], v[78:79]
	v_pk_fma_f32 v[90:91], v[76:77], v[114:115], v[90:91]
	v_pk_mul_f32 v[78:79], v[184:185], v[78:79]
	v_pk_fma_f32 v[90:91], v[130:131], v[102:103], v[90:91]
	v_pk_mul_f32 v[178:179], v[180:181], v[182:183]
	s_nop 0
	v_pk_mul_f32 v[90:91], v[90:91], v[178:179]
	s_nop 7
	s_nop 0
	v_cvt_pk_bf16_f32 v90, v78, v90
	v_or_b32_e32 v78, 6, v160
	v_pk_fma_f32 v[86:87], v[88:89], v[86:87], v[94:95]
	v_pk_fma_f32 v[84:85], v[136:137], v[122:123], v[84:85]
	v_cvt_pk_bf16_f32 v91, v79, v91
	v_mad_i64_i32 v[78:79], s[36:37], v78, s62, v[210:211]
	v_pk_fma_f32 v[86:87], v[168:169], v[196:197], v[86:87]
	v_pk_fma_f32 v[84:85], v[172:173], v[126:127], v[84:85]
	v_lshl_add_u64 v[78:79], v[78:79], 0, v[212:213]
	v_pk_fma_f32 v[86:87], v[170:171], v[198:199], v[86:87]
	v_mul_f32_e32 v89, 0xbfb8aa3b, v84
	v_mul_f32_e32 v88, 0xbfb8aa3b, v86
	v_exp_f32_e32 v89, v89
	global_store_dwordx2 v[78:79], v[90:91], off
	v_mul_f32_e32 v90, 0xbfb8aa3b, v87
	v_exp_f32_e32 v88, v88
	v_exp_f32_e32 v91, v90
	v_add_f32_e32 v89, 1.0, v89
	v_rcp_f32_e32 v90, v89
	v_add_f32_e32 v88, 1.0, v88
	v_add_f32_e32 v89, 1.0, v91
	v_rcp_f32_e32 v88, v88
	v_rcp_f32_e32 v89, v89
	v_mul_f32_e32 v91, 0xbfb8aa3b, v85
	v_exp_f32_e32 v91, v91
	v_pk_fma_f32 v[76:77], v[76:77], v[98:99], v[106:107]
	v_pk_mul_f32 v[86:87], v[86:87], v[88:89]
	v_pk_fma_f32 v[76:77], v[130:131], v[114:115], v[76:77]
	v_pk_mul_f32 v[82:83], v[82:83], v[86:87]
	v_add_f32_e32 v86, 1.0, v91
	v_rcp_f32_e32 v91, v86
	v_pk_fma_f32 v[76:77], v[138:139], v[102:103], v[76:77]
	v_pk_mul_f32 v[84:85], v[84:85], v[90:91]
	s_nop 0
	v_pk_mul_f32 v[76:77], v[76:77], v[84:85]
	s_nop 7
	s_nop 1
	v_cvt_pk_bf16_f32 v82, v82, v76
	v_or_b32_e32 v76, 7, v160
	v_cvt_pk_bf16_f32 v83, v83, v77
	v_mad_i64_i32 v[76:77], s[36:37], v76, s62, v[210:211]
	v_lshl_add_u64 v[76:77], v[76:77], 0, v[212:213]
	global_store_dwordx2 v[76:77], v[82:83], off
	v_mov_b32_e32 v82, v72
	v_mov_b32_e32 v83, v74
	v_pk_mul_f32 v[130:131], v[82:83], v[174:175]
	v_mov_b32_e32 v82, v64
	v_mov_b32_e32 v83, v66
	v_mov_b32_e32 v66, v65
	v_mov_b32_e32 v64, v68
	v_mov_b32_e32 v65, v70
	v_pk_mul_f32 v[114:115], v[64:65], v[40:41]
	v_mov_b32_e32 v64, v60
	v_mov_b32_e32 v65, v62
	v_mov_b32_e32 v70, v69
	v_mov_b32_e32 v62, v61
	v_pk_mul_f32 v[116:117], v[64:65], v[40:41]
	v_pk_mul_f32 v[118:119], v[70:71], v[40:41]
	v_pk_mul_f32 v[120:121], v[62:63], v[40:41]
	v_mov_b32_e32 v40, v56
	v_mov_b32_e32 v41, v58
	v_pk_mul_f32 v[88:89], v[40:41], v[176:177]
	v_mov_b32_e32 v40, v48
	v_mov_b32_e32 v41, v50
	v_pk_mul_f32 v[124:125], v[82:83], v[174:175]
	v_pk_mul_f32 v[82:83], v[40:41], v[176:177]
	v_mov_b32_e32 v40, v52
	v_mov_b32_e32 v41, v54
	v_mov_b32_e32 v74, v73
	v_mov_b32_e32 v58, v57
	v_mov_b32_e32 v50, v49
	v_pk_mul_f32 v[94:95], v[40:41], v[38:39]
	v_mov_b32_e32 v40, v44
	v_mov_b32_e32 v41, v46
	v_mov_b32_e32 v54, v53
	v_mov_b32_e32 v46, v45
	v_pk_mul_f32 v[126:127], v[74:75], v[174:175]
	v_pk_mul_f32 v[86:87], v[58:59], v[176:177]
	v_pk_mul_f32 v[72:73], v[50:51], v[176:177]
	v_pk_mul_f32 v[84:85], v[40:41], v[38:39]
	v_pk_mul_f32 v[90:91], v[54:55], v[38:39]
	v_pk_mul_f32 v[74:75], v[46:47], v[38:39]
	v_pk_mul_f32 v[122:123], v[66:67], v[174:175]
	v_mov_b64_e32 v[44:45], 0x408
	v_mov_b64_e32 v[46:47], 0x508
	v_mov_b64_e32 v[38:39], 0x608
	v_mov_b64_e32 v[40:41], 0x708
	v_mov_b64_e32 v[54:55], v[94:95]
	v_mov_b64_e32 v[52:53], v[90:91]
	v_mov_b64_e32 v[50:51], v[84:85]
	v_mov_b64_e32 v[48:49], v[74:75]
	v_mov_b64_e32 v[62:63], v[88:89]
	v_mov_b64_e32 v[60:61], v[86:87]
	v_mov_b64_e32 v[58:59], v[82:83]
	v_mov_b64_e32 v[56:57], v[72:73]
	s_and_saveexec_b64 s[36:37], vcc
	s_cbranch_execz .LBB0_2996
	v_cmp_eq_u32_e32 vcc, 0, v3
	s_mov_b64 s[38:39], 0
	v_mov_b64_e32 v[44:45], 0x408
	v_mov_b64_e32 v[46:47], 0x508
	v_mov_b64_e32 v[38:39], 0x608
	v_mov_b64_e32 v[40:41], 0x708
	s_and_saveexec_b64 s[40:41], vcc
	s_mov_b64 s[38:39], exec
	v_mov_b64_e32 v[44:45], 8
	v_mov_b64_e32 v[46:47], 0x108
	v_mov_b64_e32 v[38:39], 0x208
	v_mov_b64_e32 v[40:41], 0x308
	s_or_b64 exec, exec, s[40:41]
	s_orn2_b64 s[38:39], s[38:39], exec
	v_mov_b64_e32 v[54:55], v[114:115]
	v_mov_b64_e32 v[52:53], v[118:119]
	v_mov_b64_e32 v[50:51], v[116:117]
	v_mov_b64_e32 v[48:49], v[120:121]
	v_mov_b64_e32 v[62:63], v[130:131]
	v_mov_b64_e32 v[60:61], v[126:127]
	v_mov_b64_e32 v[58:59], v[124:125]
	v_mov_b64_e32 v[56:57], v[122:123]
.LBB0_2996:
	s_or_b64 exec, exec, s[36:37]
	s_and_saveexec_b64 s[36:37], s[38:39]
	s_cbranch_execz .LBB0_2979
	s_nop 7
	s_nop 1
	v_cvt_pk_bf16_f32 v61, v63, v61
	v_cvt_pk_bf16_f32 v60, v62, v60
	s_nop 7
	s_nop 1
	v_lshl_add_u64 v[44:45], v[158:159], 0, v[44:45]
	v_cvt_pk_bf16_f32 v57, v59, v57
	v_cvt_pk_bf16_f32 v56, v58, v56
	global_store_dwordx2 v[44:45], v[60:61], off
	v_lshl_add_u64 v[44:45], v[158:159], 0, v[46:47]
	global_store_dwordx2 v[44:45], v[56:57], off
	s_nop 7
	s_nop 1
	v_cvt_pk_bf16_f32 v45, v55, v53
	v_cvt_pk_bf16_f32 v44, v54, v52
	v_and_b32_sdwa v46, v51, v234 dst_sel:DWORD dst_unused:UNUSED_PAD src0_sel:WORD_1 src1_sel:DWORD
	s_nop 1
	v_add3_u32 v46, v51, v46, s61
	v_and_b32_sdwa v47, v49, v234 dst_sel:DWORD dst_unused:UNUSED_PAD src0_sel:WORD_1 src1_sel:DWORD
	s_nop 0
	v_add3_u32 v47, v49, v47, s61
	s_nop 0
	v_and_b32_e32 v47, 0xffff0000, v47
	s_nop 0
	v_lshl_add_u64 v[38:39], v[158:159], 0, v[38:39]
	v_or_b32_sdwa v47, v47, v46 dst_sel:DWORD dst_unused:UNUSED_PAD src0_sel:DWORD src1_sel:WORD_1
	v_cvt_pk_bf16_f32 v46, v50, v48
	global_store_dwordx2 v[38:39], v[44:45], off
	v_lshl_add_u64 v[38:39], v[158:159], 0, v[40:41]
	global_store_dwordx2 v[38:39], v[46:47], off
	s_branch .LBB0_2979

; __device__ __forceinline__ float siluf_(float x) { return x * sigmoidf_(x); }
; __device__ __forceinline__ void ffn_fixup(const Ctx& c, const bf16* HALO, const float* cw, const float* cb, bf16* ACT) {
;     ...
;         const int cg8 = it & 15, wr = (it >> 4) & 1, tile = it >> 5, pm = tile / 44, pn = tile % 44, ch0 = 128 * pn + 8 * cg8;
;         const bf16* cur = HALO + ((size_t)(tile * 2 + wr) * 4) * 256 + 8 * cg8;
;         const bool hasprev = wr == 1 || (pm & 15) != 0; const bf16* prv = wr == 1 ? HALO + ((size_t)(tile * 2) * 4 + 2) * 256 + 8 * cg8 : HALO + ((size_t)((tile - 44) * 2 + 1) * 4 + 2) * 256 + 8 * cg8;
;         const v4u z4 = (v4u){0u, 0u, 0u, 0u};
;         const v4u cg0 = *(const v4u*)cur, cv0 = *(const v4u*)(cur + 128), cg1 = *(const v4u*)(cur + 256), cv1 = *(const v4u*)(cur + 256 + 128);
;         const v4u pg2 = hasprev ? *(const v4u*)prv : z4, pv2 = hasprev ? *(const v4u*)(prv + 128) : z4, pg3 = hasprev ? *(const v4u*)(prv + 256) : z4, pv3 = hasprev ? *(const v4u*)(prv + 256 + 128) : z4;
;         float oa[8], ob[8];
; #pragma unroll
;         for (int j = 0; j < 8; ++j) { const int q = j >> 1; const bool hi = j & 1;
;             const float wg0 = cw[ch0 + j], wg1 = cw[FF2 + ch0 + j], wg2 = cw[2 * FF2 + ch0 + j], wv0 = cw[FFH + ch0 + j], wv1 = cw[FF2 + FFH + ch0 + j], wv2 = cw[2 * FF2 + FFH + ch0 + j], bg = cb[ch0 + j], bv = cb[FFH + ch0 + j];
;             const float gA2 = hi ? bfhi(pg2[q]) : bflo(pg2[q]), gA1 = hi ? bfhi(pg3[q]) : bflo(pg3[q]), gA0 = hi ? bfhi(cg0[q]) : bflo(cg0[q]), gB0 = hi ? bfhi(cg1[q]) : bflo(cg1[q]);
;             const float vA2 = hi ? bfhi(pv2[q]) : bflo(pv2[q]), vA1 = hi ? bfhi(pv3[q]) : bflo(pv3[q]), vA0 = hi ? bfhi(cv0[q]) : bflo(cv0[q]), vB0 = hi ? bfhi(cv1[q]) : bflo(cv1[q]);
;             oa[j] = siluf_(bg + wg0 * gA2 + wg1 * gA1 + wg2 * gA0) * (bv + wv0 * vA2 + wv1 * vA1 + wv2 * vA0);
;             ob[j] = siluf_(bg + wg0 * gA1 + wg1 * gA0 + wg2 * gB0) * (bv + wv0 * vA1 + wv1 * vA0 + wv2 * vB0); }
.LBB0_3058:
	s_or_b64 exec, exec, s[0:1]
	v_mul_lo_u32 v26, v24, 44
	v_sub_u32_e32 v25, v25, v26
	v_lshl_or_b32 v94, v25, 7, v28
	v_ashrrev_i32_e32 v95, 31, v94
	v_lshlrev_b64 v[26:27], 2, v[94:95]
	v_lshl_add_u64 v[42:43], s[12:13], 0, v[26:27]
	s_mov_b64 s[0:1], 0xb000
	v_lshl_add_u64 v[28:29], v[42:43], 0, s[0:1]
	s_mov_b64 s[0:1], 0x16000
	v_lshl_add_u64 v[36:37], v[42:43], 0, s[0:1]
	s_mov_b64 s[0:1], 0x5800
	v_lshl_add_u64 v[38:39], v[26:27], 0, s[0:1]
	v_lshl_add_u64 v[44:45], s[14:15], 0, v[26:27]
	v_ashrrev_i32_e32 v25, 31, v24
	v_lshl_add_u64 v[34:35], s[12:13], 0, v[38:39]
	v_lshl_add_u64 v[48:49], s[14:15], 0, v[38:39]
	s_waitcnt vmcnt(0)
	v_lshlrev_b32_e32 v39, 16, v13
	v_lshlrev_b32_e32 v38, 16, v12
	v_and_b32_e32 v131, 0xffff0000, v13
	v_and_b32_e32 v130, 0xffff0000, v12
	v_lshlrev_b32_e32 v123, 16, v15
	v_lshlrev_b32_e32 v122, 16, v14
	v_and_b32_e32 v121, 0xffff0000, v15
	v_and_b32_e32 v120, 0xffff0000, v14
	v_lshlrev_b64 v[102:103], 8, v[24:25]
	global_load_dwordx4 v[12:15], v[42:43], off offset:16
	global_load_dwordx4 v[60:63], v[42:43], off
	global_load_dwordx4 v[24:27], v[44:45], off offset:16
	global_load_dwordx4 v[64:67], v[44:45], off
	s_mov_b64 s[0:1], 0x10800
	v_lshl_add_u64 v[32:33], v[42:43], 0, s[0:1]
	s_mov_b64 s[0:1], 0x1b800
	v_lshl_add_u64 v[40:41], v[42:43], 0, s[0:1]
	s_mov_b32 s0, 0xb000
	v_lshlrev_b32_e32 v114, 16, v18
	v_and_b32_e32 v104, 0xffff0000, v18
	v_add_co_u32_e32 v18, vcc, s0, v42
	v_lshlrev_b32_e32 v115, 16, v19
	v_and_b32_e32 v105, 0xffff0000, v19
	v_addc_co_u32_e32 v19, vcc, 0, v43, vcc
	v_lshl_or_b32 v88, v30, 7, v102
	global_load_dwordx4 v[68:71], v[18:19], off
	s_nop 0
	global_load_dwordx4 v[28:31], v[28:29], off offset:16
	v_add_co_u32_e32 v18, vcc, s18, v42
	v_lshlrev_b32_e32 v126, 16, v16
	s_nop 0
	v_addc_co_u32_e32 v19, vcc, 0, v43, vcc
	v_and_b32_e32 v124, 0xffff0000, v16
	v_lshlrev_b32_e32 v127, 16, v17
	v_and_b32_e32 v125, 0xffff0000, v17
	v_lshlrev_b32_e32 v98, 16, v20
	v_lshlrev_b32_e32 v99, 16, v21
	v_lshlrev_b32_e32 v101, 16, v57
	v_lshlrev_b32_e32 v100, 16, v56
	s_mov_b32 s0, 0x10000
	v_and_b32_e32 v96, 0xffff0000, v20
	v_and_b32_e32 v97, 0xffff0000, v21
	v_lshlrev_b32_e32 v92, 16, v22
	v_and_b32_e32 v90, 0xffff0000, v22
	v_lshlrev_b32_e32 v93, 16, v23
	v_and_b32_e32 v91, 0xffff0000, v23
	v_and_b32_e32 v129, 0xffff0000, v57
	v_and_b32_e32 v128, 0xffff0000, v56
	v_lshlrev_b32_e32 v106, 16, v76
	v_lshlrev_b32_e32 v107, 16, v77
	v_lshlrev_b32_e32 v109, 16, v53
	v_lshlrev_b32_e32 v108, 16, v52
	v_and_b32_e32 v53, 0xffff0000, v53
	v_and_b32_e32 v52, 0xffff0000, v52
	v_add_u32_e32 v3, s19, v3
	v_add_u32_e32 v134, s20, v134
	s_waitcnt vmcnt(0)
	v_mov_b32_e32 v110, v60
	v_mov_b32_e32 v111, v62
	v_mov_b32_e32 v112, v64
	v_mov_b32_e32 v113, v66
	v_pk_fma_f32 v[16:17], v[110:111], v[38:39], v[112:113]
	global_load_dwordx4 v[80:83], v[18:19], off
	s_nop 0
	global_load_dwordx4 v[36:39], v[36:37], off offset:16
	v_mov_b32_e32 v62, v61
	v_mov_b32_e32 v66, v65
	v_pk_fma_f32 v[56:57], v[62:63], v[130:131], v[66:67]
	v_pk_fma_f32 v[62:63], v[62:63], v[96:97], v[66:67]
	v_mov_b32_e32 v116, v68
	v_mov_b32_e32 v117, v70
	v_pk_fma_f32 v[16:17], v[116:117], v[98:99], v[16:17]
	v_mov_b32_e32 v70, v69
	v_pk_fma_f32 v[56:57], v[70:71], v[96:97], v[56:57]
	v_pk_fma_f32 v[62:63], v[70:71], v[128:129], v[62:63]
	s_waitcnt vmcnt(0)
	v_mov_b32_e32 v118, v80
	v_mov_b32_e32 v119, v82
	v_pk_fma_f32 v[132:133], v[118:119], v[100:101], v[16:17]
	v_mov_b32_e32 v82, v81
	v_mul_f32_e32 v16, 0xbfb8aa3b, v132
	v_exp_f32_e32 v60, v16
	global_load_dwordx4 v[16:19], v[34:35], off offset:16
	s_waitcnt lgkmcnt(0)
	global_load_dwordx4 v[44:47], v[34:35], off
	global_load_dwordx4 v[20:23], v[48:49], off offset:16
	s_nop 0
	global_load_dwordx4 v[48:51], v[48:49], off
	v_add_co_u32_e32 v34, vcc, s0, v42
	s_mov_b32 s0, 0x1b000
	s_nop 0
	v_addc_co_u32_e32 v35, vcc, 0, v43, vcc
	v_add_co_u32_e32 v42, vcc, s0, v42
	global_load_dwordx4 v[72:75], v[34:35], off offset:2048
	s_nop 0
	global_load_dwordx4 v[32:35], v[32:33], off offset:16
	v_addc_co_u32_e32 v43, vcc, 0, v43, vcc
	global_load_dwordx4 v[84:87], v[42:43], off offset:2048
	s_nop 0
	global_load_dwordx4 v[40:43], v[40:41], off offset:16
	v_mul_f32_e32 v61, 0xbfb8aa3b, v133
	v_exp_f32_e32 v61, v61
	v_pk_fma_f32 v[68:69], v[82:83], v[128:129], v[56:57]
	v_and_b32_e32 v57, 0xffff0000, v77
	v_mul_f32_e32 v56, 0xbfb8aa3b, v68
	v_pk_add_f32 v[60:61], v[60:61], 1.0 op_sel_hi:[1,0]
	v_exp_f32_e32 v136, v56
	v_div_scale_f32 v64, s[0:1], v61, v61, 1.0
	v_rcp_f32_e32 v65, v64
	v_and_b32_e32 v56, 0xffff0000, v76
	v_fma_f32 v76, -v64, v65, 1.0
	v_fmac_f32_e32 v65, v76, v65
	v_div_scale_f32 v76, vcc, 1.0, v61, 1.0
	v_mul_f32_e32 v77, v76, v65
	v_fma_f32 v80, -v64, v77, v76
	v_fmac_f32_e32 v77, v80, v65
	v_fma_f32 v64, -v64, v77, v76
	v_div_fmas_f32 v64, v64, v65, v77
	v_div_fixup_f32 v61, v64, v61, 1.0
	v_div_scale_f32 v64, s[0:1], v60, v60, 1.0
	v_rcp_f32_e32 v65, v64
	s_waitcnt vmcnt(3)
	v_mov_b32_e32 v81, v74
	v_fma_f32 v76, -v64, v65, 1.0
	v_fmac_f32_e32 v65, v76, v65
	v_div_scale_f32 v76, vcc, 1.0, v60, 1.0
	v_mul_f32_e32 v77, v76, v65
	v_fma_f32 v80, -v64, v77, v76
	v_fmac_f32_e32 v77, v80, v65
	v_fma_f32 v64, -v64, v77, v76
	v_div_fmas_f32 v64, v64, v65, v77
	v_div_fixup_f32 v60, v64, v60, 1.0
	v_mov_b32_e32 v64, v44
	v_mul_f32_e32 v44, 0xbfb8aa3b, v69
	v_mov_b32_e32 v65, v46
	v_mov_b32_e32 v76, v48
	v_mov_b32_e32 v77, v50
	v_exp_f32_e32 v137, v44
	v_pk_fma_f32 v[126:127], v[64:65], v[126:127], v[76:77]
	v_mov_b32_e32 v80, v72
	v_pk_fma_f32 v[130:131], v[80:81], v[106:107], v[126:127]
	s_waitcnt vmcnt(1)
; __device__ __forceinline__ unsigned pk2(float lo, float hi) { return f2bf(lo) | (f2bf(hi) << 16); }
; __device__ __forceinline__ float siluf_(float x) { return x * sigmoidf_(x); }
; __device__ __forceinline__ void ffn_fixup(const Ctx& c, const bf16* HALO, const float* cw, const float* cb, bf16* ACT) {
;     ...
;             const float gA2 = hi ? bfhi(pg2[q]) : bflo(pg2[q]), gA1 = hi ? bfhi(pg3[q]) : bflo(pg3[q]), gA0 = hi ? bfhi(cg0[q]) : bflo(cg0[q]), gB0 = hi ? bfhi(cg1[q]) : bflo(cg1[q]);
;             const float vA2 = hi ? bfhi(pv2[q]) : bflo(pv2[q]), vA1 = hi ? bfhi(pv3[q]) : bflo(pv3[q]), vA0 = hi ? bfhi(cv0[q]) : bflo(cv0[q]), vB0 = hi ? bfhi(cv1[q]) : bflo(cv1[q]);
;             oa[j] = siluf_(bg + wg0 * gA2 + wg1 * gA1 + wg2 * gA0) * (bv + wv0 * vA2 + wv1 * vA1 + wv2 * vA0);
;             ob[j] = siluf_(bg + wg0 * gA1 + wg1 * gA0 + wg2 * gB0) * (bv + wv0 * vA1 + wv1 * vA0 + wv2 * vB0); }
;         const size_t tok = (size_t)256 * pm + 128 * wr;
;         v4u w; w.x = pk2(oa[0], oa[1]); w.y = pk2(oa[2], oa[3]); w.z = pk2(oa[4], oa[5]); w.w = pk2(oa[6], oa[7]); *(v4u*)(ACT + tok * FFH + ch0) = w;
	v_mov_b32_e32 v126, v84
	v_mov_b32_e32 v127, v86
	v_pk_mul_f32 v[60:61], v[132:133], v[60:61]
	v_pk_fma_f32 v[130:131], v[126:127], v[108:109], v[130:131]
	v_mov_b32_e32 v74, v73
	v_pk_mul_f32 v[130:131], v[130:131], v[60:61]
	v_pk_add_f32 v[60:61], v[136:137], 1.0 op_sel_hi:[1,0]
	v_mov_b32_e32 v86, v85
	v_div_scale_f32 v44, s[0:1], v61, v61, 1.0
	v_rcp_f32_e32 v46, v44
	v_mov_b32_e32 v73, v26
	v_mov_b32_e32 v84, v28
	v_mov_b32_e32 v85, v30
	v_fma_f32 v48, -v44, v46, 1.0
	v_fmac_f32_e32 v46, v48, v46
	v_div_scale_f32 v48, vcc, 1.0, v61, 1.0
	v_mul_f32_e32 v50, v48, v46
	v_fma_f32 v72, -v44, v50, v48
	v_fmac_f32_e32 v50, v72, v46
	v_fma_f32 v44, -v44, v50, v48
	v_div_fmas_f32 v44, v44, v46, v50
	v_div_fixup_f32 v61, v44, v61, 1.0
	v_div_scale_f32 v44, s[0:1], v60, v60, 1.0
	v_rcp_f32_e32 v46, v44
	v_mov_b32_e32 v30, v29
	v_mov_b32_e32 v26, v25
	v_and_b32_e32 v25, 0xffff0000, v55
	v_fma_f32 v48, -v44, v46, 1.0
	v_fmac_f32_e32 v46, v48, v46
	v_div_scale_f32 v48, vcc, 1.0, v60, 1.0
	v_mul_f32_e32 v50, v48, v46
	v_fma_f32 v72, -v44, v50, v48
	v_fmac_f32_e32 v50, v72, v46
	v_fma_f32 v44, -v44, v50, v48
	v_div_fmas_f32 v44, v44, v46, v50
	v_mov_b32_e32 v46, v45
	v_mov_b32_e32 v50, v49
	v_div_fixup_f32 v60, v44, v60, 1.0
	v_pk_fma_f32 v[44:45], v[46:47], v[124:125], v[50:51]
	v_pk_mul_f32 v[60:61], v[68:69], v[60:61]
	v_pk_fma_f32 v[44:45], v[74:75], v[56:57], v[44:45]
	v_mov_b32_e32 v68, v12
	v_pk_fma_f32 v[44:45], v[86:87], v[52:53], v[44:45]
	v_mov_b32_e32 v69, v14
	v_mov_b32_e32 v72, v24
	v_pk_mul_f32 v[124:125], v[44:45], v[60:61]
	v_pk_fma_f32 v[44:45], v[68:69], v[122:123], v[72:73]
	v_lshlrev_b32_e32 v61, 16, v59
	v_lshlrev_b32_e32 v60, 16, v58
	v_pk_fma_f32 v[44:45], v[84:85], v[92:93], v[44:45]
	v_mov_b32_e32 v122, v36
	v_mov_b32_e32 v123, v38
	v_pk_fma_f32 v[132:133], v[122:123], v[60:61], v[44:45]
	v_mov_b32_e32 v38, v37
	v_mul_f32_e32 v12, 0xbfb8aa3b, v132
	v_mul_f32_e32 v29, 0xbfb8aa3b, v133
	v_exp_f32_e32 v28, v12
	v_exp_f32_e32 v29, v29
	v_mov_b32_e32 v14, v13
	v_pk_fma_f32 v[12:13], v[14:15], v[120:121], v[26:27]
	v_lshlrev_b32_e32 v48, 16, v54
	v_pk_add_f32 v[28:29], v[28:29], 1.0 op_sel_hi:[1,0]
	v_and_b32_e32 v59, 0xffff0000, v59
	v_div_scale_f32 v36, s[0:1], v29, v29, 1.0
	v_rcp_f32_e32 v37, v36
	v_and_b32_e32 v58, 0xffff0000, v58
	v_pk_fma_f32 v[12:13], v[30:31], v[90:91], v[12:13]
	v_and_b32_e32 v24, 0xffff0000, v54
	v_fma_f32 v54, -v36, v37, 1.0
	v_pk_fma_f32 v[120:121], v[38:39], v[58:59], v[12:13]
	v_fmac_f32_e32 v37, v54, v37
	v_div_scale_f32 v54, vcc, 1.0, v29, 1.0
	v_lshlrev_b32_e32 v49, 16, v55
	v_mul_f32_e32 v12, 0xbfb8aa3b, v120
	v_mul_f32_e32 v55, v54, v37
	v_lshlrev_b32_e32 v44, 16, v78
	v_exp_f32_e32 v136, v12
	v_and_b32_e32 v12, 0xffff0000, v78
	v_fma_f32 v78, -v36, v55, v54
	v_fmac_f32_e32 v55, v78, v37
	v_fma_f32 v36, -v36, v55, v54
	v_div_fmas_f32 v36, v36, v37, v55
	v_div_fixup_f32 v29, v36, v29, 1.0
	v_div_scale_f32 v36, s[0:1], v28, v28, 1.0
	v_rcp_f32_e32 v37, v36
	v_lshlrev_b32_e32 v45, 16, v79
	v_and_b32_e32 v13, 0xffff0000, v79
	v_pk_fma_f32 v[14:15], v[14:15], v[90:91], v[26:27]
	v_fma_f32 v54, -v36, v37, 1.0
	v_fmac_f32_e32 v37, v54, v37
	v_div_scale_f32 v54, vcc, 1.0, v28, 1.0
	v_mul_f32_e32 v55, v54, v37
	v_fma_f32 v78, -v36, v55, v54
	v_fmac_f32_e32 v55, v78, v37
	v_fma_f32 v36, -v36, v55, v54
	v_div_fmas_f32 v36, v36, v37, v55
	v_div_fixup_f32 v28, v36, v28, 1.0
	v_pk_mul_f32 v[132:133], v[132:133], v[28:29]
	v_mov_b32_e32 v28, v16
	v_mul_f32_e32 v16, 0xbfb8aa3b, v121
	v_mov_b32_e32 v29, v18
	v_mov_b32_e32 v36, v20
	v_mov_b32_e32 v37, v22
	v_exp_f32_e32 v137, v16
	v_pk_fma_f32 v[78:79], v[28:29], v[114:115], v[36:37]
	v_mov_b32_e32 v54, v32
	v_mov_b32_e32 v55, v34
	v_pk_fma_f32 v[114:115], v[54:55], v[44:45], v[78:79]
	s_waitcnt vmcnt(0)
	v_mov_b32_e32 v78, v40
	v_mov_b32_e32 v79, v42
	v_pk_fma_f32 v[114:115], v[78:79], v[48:49], v[114:115]
	v_mov_b32_e32 v34, v33
	v_pk_mul_f32 v[114:115], v[114:115], v[132:133]
	v_pk_add_f32 v[132:133], v[136:137], 1.0 op_sel_hi:[1,0]
	v_mov_b32_e32 v42, v41
	v_div_scale_f32 v16, s[0:1], v133, v133, 1.0
	v_rcp_f32_e32 v18, v16
	s_nop 2
	v_fma_f32 v20, -v16, v18, 1.0
	v_fmac_f32_e32 v18, v20, v18
	v_div_scale_f32 v20, vcc, 1.0, v133, 1.0
	v_mul_f32_e32 v22, v20, v18
	v_fma_f32 v32, -v16, v22, v20
	v_fmac_f32_e32 v22, v32, v18
	v_fma_f32 v16, -v16, v22, v20
	v_div_fmas_f32 v16, v16, v18, v22
	v_div_fixup_f32 v133, v16, v133, 1.0
	v_div_scale_f32 v16, s[0:1], v132, v132, 1.0
	v_rcp_f32_e32 v18, v16
	s_nop 2
	v_fma_f32 v20, -v16, v18, 1.0
	v_fmac_f32_e32 v18, v20, v18
	v_div_scale_f32 v20, vcc, 1.0, v132, 1.0
	v_mul_f32_e32 v22, v20, v18
	v_fma_f32 v32, -v16, v22, v20
	v_fmac_f32_e32 v22, v32, v18
	v_fma_f32 v16, -v16, v22, v20
	v_div_fmas_f32 v16, v16, v18, v22
	v_mov_b32_e32 v18, v17
	v_mov_b32_e32 v22, v21
	v_div_fixup_f32 v132, v16, v132, 1.0
	v_pk_fma_f32 v[16:17], v[18:19], v[104:105], v[22:23]
	v_pk_mul_f32 v[120:121], v[120:121], v[132:133]
	v_pk_fma_f32 v[16:17], v[34:35], v[12:13], v[16:17]
	s_nop 0
	v_pk_fma_f32 v[16:17], v[42:43], v[24:25], v[16:17]
	s_nop 0
	v_pk_mul_f32 v[16:17], v[16:17], v[120:121]
	s_nop 7
	s_nop 3
	v_cvt_pk_bf16_f32 v131, v131, v125
	v_cvt_pk_bf16_f32 v130, v130, v124
	v_cvt_pk_bf16_f32 v133, v115, v17
	v_cvt_pk_bf16_f32 v132, v114, v16
	v_lshlrev_b32_e32 v21, 16, v9
	v_lshlrev_b32_e32 v20, 16, v8
	v_lshlrev_b32_e32 v33, 16, v5
	v_lshlrev_b32_e32 v32, 16, v4
	v_and_b32_e32 v9, 0xffff0000, v9
	v_and_b32_e32 v8, 0xffff0000, v8
	v_and_b32_e32 v41, 0xffff0000, v5
	v_and_b32_e32 v40, 0xffff0000, v4
	v_pk_fma_f32 v[4:5], v[110:111], v[98:99], v[112:113]
	v_pk_fma_f32 v[8:9], v[82:83], v[8:9], v[62:63]
	v_pk_fma_f32 v[4:5], v[116:117], v[100:101], v[4:5]
; __device__ __forceinline__ unsigned pk2(float lo, float hi) { return f2bf(lo) | (f2bf(hi) << 16); }
; __device__ __forceinline__ float siluf_(float x) { return x * sigmoidf_(x); }
; __device__ __forceinline__ void ffn_fixup(const Ctx& c, const bf16* HALO, const float* cw, const float* cb, bf16* ACT) {
;     ...
;             ob[j] = siluf_(bg + wg0 * gA1 + wg1 * gA0 + wg2 * gB0) * (bv + wv0 * vA1 + wv1 * vA0 + wv2 * vB0); }
;         const size_t tok = (size_t)256 * pm + 128 * wr;
;         v4u w; w.x = pk2(oa[0], oa[1]); w.y = pk2(oa[2], oa[3]); w.z = pk2(oa[4], oa[5]); w.w = pk2(oa[6], oa[7]); *(v4u*)(ACT + tok * FFH + ch0) = w;
;         w.x = pk2(ob[0], ob[1]); w.y = pk2(ob[2], ob[3]); w.z = pk2(ob[4], ob[5]); w.w = pk2(ob[6], ob[7]); *(v4u*)(ACT + (tok + 1) * FFH + ch0) = w;
	v_pk_fma_f32 v[14:15], v[30:31], v[58:59], v[14:15]
	v_pk_fma_f32 v[4:5], v[118:119], v[20:21], v[4:5]
	v_mul_f32_e32 v21, 0xbfb8aa3b, v8
	v_mul_f32_e32 v20, 0xbfb8aa3b, v4
	v_exp_f32_e32 v62, v21
	v_mul_f32_e32 v21, 0xbfb8aa3b, v5
	v_exp_f32_e32 v20, v20
	v_exp_f32_e32 v21, v21
	v_pk_fma_f32 v[12:13], v[18:19], v[12:13], v[22:23]
	v_mov_b64_e32 v[16:17], s[78:79]
	v_pk_fma_f32 v[12:13], v[34:35], v[24:25], v[12:13]
	v_pk_add_f32 v[20:21], v[20:21], 1.0 op_sel_hi:[1,0]
	v_mad_u64_u32 v[16:17], s[0:1], v88, s23, v[16:17]
	v_div_scale_f32 v63, s[0:1], v21, v21, 1.0
	v_rcp_f32_e32 v66, v63
	v_mad_i32_i24 v17, v103, s23, v17
	v_lshl_add_u64 v[16:17], v[94:95], 1, v[16:17]
	global_store_dwordx4 v[16:17], v[130:133], off
	v_fma_f32 v67, -v63, v66, 1.0
	v_fmac_f32_e32 v66, v67, v66
	v_div_scale_f32 v67, vcc, 1.0, v21, 1.0
	v_mul_f32_e32 v70, v67, v66
	v_fma_f32 v71, -v63, v70, v67
	v_fmac_f32_e32 v70, v71, v66
	v_fma_f32 v63, -v63, v70, v67
	v_div_fmas_f32 v63, v63, v66, v70
	v_div_fixup_f32 v21, v63, v21, 1.0
	v_div_scale_f32 v63, s[0:1], v20, v20, 1.0
	v_rcp_f32_e32 v66, v63
	s_nop 0
	v_fma_f32 v67, -v63, v66, 1.0
	v_fmac_f32_e32 v66, v67, v66
	v_div_scale_f32 v67, vcc, 1.0, v20, 1.0
	v_mul_f32_e32 v70, v67, v66
	v_fma_f32 v71, -v63, v70, v67
	v_fmac_f32_e32 v70, v71, v66
	v_fma_f32 v63, -v63, v70, v67
	v_div_fmas_f32 v63, v63, v66, v70
	v_div_fixup_f32 v20, v63, v20, 1.0
	v_pk_mul_f32 v[4:5], v[4:5], v[20:21]
	v_pk_fma_f32 v[20:21], v[64:65], v[106:107], v[76:77]
	s_nop 0
	v_pk_fma_f32 v[20:21], v[80:81], v[108:109], v[20:21]
	s_nop 0
	v_pk_fma_f32 v[20:21], v[126:127], v[32:33], v[20:21]
	s_nop 0
	v_pk_mul_f32 v[4:5], v[20:21], v[4:5]
	v_mul_f32_e32 v20, 0xbfb8aa3b, v9
	v_exp_f32_e32 v63, v20
	s_nop 0
	v_pk_add_f32 v[20:21], v[62:63], 1.0 op_sel_hi:[1,0]
	s_nop 0
	v_div_scale_f32 v32, s[0:1], v21, v21, 1.0
	v_rcp_f32_e32 v33, v32
	s_nop 0
	v_fma_f32 v62, -v32, v33, 1.0
	v_fmac_f32_e32 v33, v62, v33
	v_div_scale_f32 v62, vcc, 1.0, v21, 1.0
	v_mul_f32_e32 v63, v62, v33
	v_fma_f32 v64, -v32, v63, v62
	v_fmac_f32_e32 v63, v64, v33
	v_fma_f32 v32, -v32, v63, v62
	v_div_fmas_f32 v32, v32, v33, v63
	v_div_fixup_f32 v21, v32, v21, 1.0
	v_div_scale_f32 v32, s[0:1], v20, v20, 1.0
	v_rcp_f32_e32 v33, v32
	s_nop 0
	v_fma_f32 v62, -v32, v33, 1.0
	v_fmac_f32_e32 v33, v62, v33
	v_div_scale_f32 v62, vcc, 1.0, v20, 1.0
	v_mul_f32_e32 v63, v62, v33
	v_fma_f32 v64, -v32, v63, v62
	v_fmac_f32_e32 v63, v64, v33
	v_fma_f32 v32, -v32, v63, v62
	v_div_fmas_f32 v32, v32, v33, v63
	v_div_fixup_f32 v20, v32, v20, 1.0
	v_pk_mul_f32 v[8:9], v[8:9], v[20:21]
	v_pk_fma_f32 v[20:21], v[46:47], v[56:57], v[50:51]
	v_lshlrev_b32_e32 v33, 16, v7
	v_pk_fma_f32 v[20:21], v[74:75], v[52:53], v[20:21]
	v_lshlrev_b32_e32 v32, 16, v6
	v_pk_fma_f32 v[20:21], v[86:87], v[40:41], v[20:21]
	v_pk_fma_f32 v[40:41], v[68:69], v[92:93], v[72:73]
	v_pk_mul_f32 v[8:9], v[20:21], v[8:9]
	v_lshlrev_b32_e32 v21, 16, v11
	v_lshlrev_b32_e32 v20, 16, v10
	v_pk_fma_f32 v[40:41], v[84:85], v[60:61], v[40:41]
	v_and_b32_e32 v11, 0xffff0000, v11
	v_and_b32_e32 v10, 0xffff0000, v10
	v_pk_fma_f32 v[20:21], v[122:123], v[20:21], v[40:41]
	v_pk_fma_f32 v[10:11], v[38:39], v[10:11], v[14:15]
	v_mul_f32_e32 v40, 0xbfb8aa3b, v20
	v_mul_f32_e32 v15, 0xbfb8aa3b, v21
	v_exp_f32_e32 v40, v40
	v_exp_f32_e32 v41, v15
	v_mul_f32_e32 v14, 0xbfb8aa3b, v10
	v_exp_f32_e32 v14, v14
	v_and_b32_e32 v7, 0xffff0000, v7
	v_pk_add_f32 v[26:27], v[40:41], 1.0 op_sel_hi:[1,0]
	v_and_b32_e32 v6, 0xffff0000, v6
	v_div_scale_f32 v15, s[0:1], v27, v27, 1.0
	v_rcp_f32_e32 v30, v15
	v_pk_fma_f32 v[6:7], v[42:43], v[6:7], v[12:13]
	v_fma_f32 v31, -v15, v30, 1.0
	v_fmac_f32_e32 v30, v31, v30
	v_div_scale_f32 v31, vcc, 1.0, v27, 1.0
	v_mul_f32_e32 v38, v31, v30
	v_fma_f32 v39, -v15, v38, v31
	v_fmac_f32_e32 v38, v39, v30
	v_fma_f32 v15, -v15, v38, v31
	v_div_fmas_f32 v15, v15, v30, v38
	v_div_fixup_f32 v27, v15, v27, 1.0
	v_div_scale_f32 v15, s[0:1], v26, v26, 1.0
	v_rcp_f32_e32 v30, v15
	s_nop 0
	v_fma_f32 v31, -v15, v30, 1.0
	v_fmac_f32_e32 v30, v31, v30
	v_div_scale_f32 v31, vcc, 1.0, v26, 1.0
	v_mul_f32_e32 v38, v31, v30
	v_fma_f32 v39, -v15, v38, v31
	v_fmac_f32_e32 v38, v39, v30
	v_fma_f32 v15, -v15, v38, v31
	v_div_fmas_f32 v15, v15, v30, v38
	v_div_fixup_f32 v26, v15, v26, 1.0
	v_mul_f32_e32 v15, 0xbfb8aa3b, v11
	v_exp_f32_e32 v15, v15
	v_pk_mul_f32 v[20:21], v[20:21], v[26:27]
	v_pk_fma_f32 v[26:27], v[28:29], v[44:45], v[36:37]
	v_pk_add_f32 v[14:15], v[14:15], 1.0 op_sel_hi:[1,0]
	v_pk_fma_f32 v[26:27], v[54:55], v[48:49], v[26:27]
	s_nop 0
	v_pk_fma_f32 v[26:27], v[78:79], v[32:33], v[26:27]
	s_nop 0
	v_pk_mul_f32 v[20:21], v[26:27], v[20:21]
	v_div_scale_f32 v26, s[0:1], v15, v15, 1.0
	v_rcp_f32_e32 v27, v26
	s_nop 0
	v_fma_f32 v28, -v26, v27, 1.0
	v_fmac_f32_e32 v27, v28, v27
	v_div_scale_f32 v28, vcc, 1.0, v15, 1.0
	v_mul_f32_e32 v29, v28, v27
	v_fma_f32 v30, -v26, v29, v28
	v_fmac_f32_e32 v29, v30, v27
	v_fma_f32 v26, -v26, v29, v28
	v_div_fmas_f32 v26, v26, v27, v29
	v_div_fixup_f32 v15, v26, v15, 1.0
	v_div_scale_f32 v26, s[0:1], v14, v14, 1.0
	v_rcp_f32_e32 v27, v26
	s_mov_b32 s0, 0x15fff
	v_fma_f32 v28, -v26, v27, 1.0
	v_fmac_f32_e32 v27, v28, v27
	v_div_scale_f32 v28, vcc, 1.0, v14, 1.0
	v_mul_f32_e32 v29, v28, v27
	v_fma_f32 v30, -v26, v29, v28
	v_fmac_f32_e32 v29, v30, v27
	v_fma_f32 v26, -v26, v29, v28
	v_div_fmas_f32 v26, v26, v27, v29
	v_div_fixup_f32 v14, v26, v14, 1.0
	v_pk_mul_f32 v[10:11], v[10:11], v[14:15]
	s_nop 0
	v_pk_mul_f32 v[6:7], v[6:7], v[10:11]
	s_nop 6
	v_bfe_u32 v12, v7, 16, 1
	v_bfe_u32 v13, v6, 16, 1
	s_nop 1
	v_add3_u32 v6, v6, v13, s22
	v_add3_u32 v7, v7, v12, s22
	v_bfe_u32 v12, v20, 16, 1
	v_bfe_u32 v13, v21, 16, 1
	s_nop 0
	v_cvt_pk_bf16_f32 v4, v4, v8
	v_add_co_u32_e32 v8, vcc, 0x2000, v16
	v_add3_u32 v10, v21, v13, s22
	v_add3_u32 v11, v20, v12, s22
	v_cvt_pk_bf16_f32 v5, v5, v9
	v_addc_co_u32_e32 v9, vcc, 0, v17, vcc
	v_lshrrev_b32_e32 v11, 16, v11
	v_lshrrev_b32_e32 v10, 16, v10
	v_cmp_lt_i32_e32 vcc, s0, v3
	v_and_or_b32 v7, v7, s21, v10
	v_and_or_b32 v6, v6, s21, v11
	s_or_b64 s[16:17], vcc, s[16:17]
	global_store_dwordx4 v[8:9], v[4:7], off offset:3072
	s_andn2_b64 exec, exec, s[16:17]
	s_cbranch_execz .LBB0_3067

; __device__ __forceinline__ void postnorm(const Ctx& c, const bf16* MF, bf16* XB, float* RS, const float* gpost, float* OUT) {
;     for (int row = c.gw; row < MT; row += c.NGW) {
;         const v4u* mr = (const v4u*)(MF + (size_t)row * DM) + c.lane; v4u* xr = (v4u*)(XB + (size_t)row * DM) + c.lane;
;         v4u mv[4], xv[4]; float v[4][8]; float s = 0.f;
; #pragma unroll
;         for (int j = 0; j < 4; ++j) { mv[j] = mr[64 * j]; xv[j] = xr[64 * j]; }
; #pragma unroll
;         for (int j = 0; j < 4; ++j)
; #pragma unroll
;             for (int k = 0; k < 4; ++k) { v[j][2 * k] = bflo(mv[j][k]); v[j][2 * k + 1] = bfhi(mv[j][k]); s += v[j][2 * k] * v[j][2 * k] + v[j][2 * k + 1] * v[j][2 * k + 1]; }
;         const float rs = rsqrtf(wave_sum(s) * (1.f / DM) + EPS);
.LBB0_3204:
	v_readlane_b32 s10, v253, 0
	v_readlane_b32 s11, v253, 1
	s_nop 1
	v_lshl_add_u64 v[38:39], s[10:11], 0, v[30:31]
	v_add_co_u32_e32 v58, vcc, 0xd400000, v38
	s_nop 1
	v_addc_co_u32_e32 v59, vcc, 0, v39, vcc
	s_waitcnt lgkmcnt(0)
	global_load_dwordx4 v[46:49], v[58:59], off
	global_load_dwordx4 v[50:53], v[58:59], off offset:1024
	global_load_dwordx4 v[54:57], v[58:59], off offset:2048
	s_nop 0
	global_load_dwordx4 v[58:61], v[58:59], off offset:3072
	v_add_co_u32_e32 v38, vcc, 0x9400000, v38
	s_waitcnt vmcnt(3)
	v_lshlrev_b32_e32 v79, 16, v47
	v_addc_co_u32_e32 v39, vcc, 0, v39, vcc
	global_load_dwordx4 v[62:65], v[38:39], off
	global_load_dwordx4 v[66:69], v[38:39], off offset:1024
	global_load_dwordx4 v[70:73], v[38:39], off offset:2048
	global_load_dwordx4 v[74:77], v[38:39], off offset:3072
	v_lshlrev_b32_e32 v78, 16, v46
	v_and_b32_e32 v47, 0xffff0000, v47
	v_and_b32_e32 v46, 0xffff0000, v46
	v_lshlrev_b32_e32 v81, 16, v49
	v_lshlrev_b32_e32 v80, 16, v48
	v_and_b32_e32 v49, 0xffff0000, v49
	v_and_b32_e32 v48, 0xffff0000, v48
	v_pk_mul_f32 v[94:95], v[46:47], v[46:47]
	v_pk_mul_f32 v[98:99], v[48:49], v[48:49]
	v_pk_fma_f32 v[94:95], v[78:79], v[78:79], v[94:95]
	s_waitcnt vmcnt(6)
	v_lshlrev_b32_e32 v83, 16, v51
	v_lshlrev_b32_e32 v82, 16, v50
	v_and_b32_e32 v51, 0xffff0000, v51
	v_and_b32_e32 v50, 0xffff0000, v50
	v_pk_fma_f32 v[98:99], v[80:81], v[80:81], v[98:99]
	v_add_f32_e32 v94, v94, v95
	v_pk_mul_f32 v[102:103], v[50:51], v[50:51]
	v_add_f32_e32 v94, v98, v94
	v_lshlrev_b32_e32 v85, 16, v53
	v_lshlrev_b32_e32 v84, 16, v52
	v_and_b32_e32 v53, 0xffff0000, v53
	v_and_b32_e32 v52, 0xffff0000, v52
	v_pk_fma_f32 v[102:103], v[82:83], v[82:83], v[102:103]
	v_add_f32_e32 v94, v99, v94
	v_pk_mul_f32 v[104:105], v[52:53], v[52:53]
	v_add_f32_e32 v94, v102, v94
	s_waitcnt vmcnt(5)
	v_lshlrev_b32_e32 v87, 16, v55
	v_lshlrev_b32_e32 v86, 16, v54
	v_and_b32_e32 v55, 0xffff0000, v55
	v_and_b32_e32 v54, 0xffff0000, v54
	v_pk_fma_f32 v[104:105], v[84:85], v[84:85], v[104:105]
	v_add_f32_e32 v94, v103, v94
	v_pk_mul_f32 v[106:107], v[54:55], v[54:55]
	v_add_f32_e32 v94, v104, v94
	v_lshlrev_b32_e32 v89, 16, v57
	v_lshlrev_b32_e32 v88, 16, v56
	v_and_b32_e32 v57, 0xffff0000, v57
	v_and_b32_e32 v56, 0xffff0000, v56
	v_pk_fma_f32 v[106:107], v[86:87], v[86:87], v[106:107]
	v_add_f32_e32 v94, v105, v94
	v_pk_mul_f32 v[108:109], v[56:57], v[56:57]
	v_add_f32_e32 v94, v106, v94
	s_waitcnt vmcnt(4)
	v_lshlrev_b32_e32 v91, 16, v59
	v_lshlrev_b32_e32 v90, 16, v58
	v_and_b32_e32 v59, 0xffff0000, v59
	v_and_b32_e32 v58, 0xffff0000, v58
	v_pk_fma_f32 v[108:109], v[88:89], v[88:89], v[108:109]
	v_add_f32_e32 v94, v107, v94
	v_pk_mul_f32 v[110:111], v[58:59], v[58:59]
	v_add_f32_e32 v94, v108, v94
	v_lshlrev_b32_e32 v93, 16, v61
	v_lshlrev_b32_e32 v92, 16, v60
	v_and_b32_e32 v61, 0xffff0000, v61
	v_and_b32_e32 v60, 0xffff0000, v60
	v_pk_fma_f32 v[110:111], v[90:91], v[90:91], v[110:111]
	v_add_f32_e32 v94, v109, v94
	v_pk_mul_f32 v[112:113], v[60:61], v[60:61]
	v_add_f32_e32 v94, v110, v94
	v_pk_fma_f32 v[112:113], v[92:93], v[92:93], v[112:113]
	v_add_f32_e32 v94, v111, v94
	v_add_f32_e32 v94, v112, v94
	v_add_f32_e32 v94, v113, v94
	ds_bpermute_b32 v98, v3, v94
	s_waitcnt lgkmcnt(0)
	v_add_f32_e32 v98, v94, v98
	ds_bpermute_b32 v102, v40, v98
	s_waitcnt lgkmcnt(0)
	v_add_f32_e32 v102, v98, v102
	ds_bpermute_b32 v104, v41, v102
	s_waitcnt vmcnt(3)
	v_lshlrev_b32_e32 v97, 16, v63
	v_lshlrev_b32_e32 v96, 16, v62
	v_and_b32_e32 v63, 0xffff0000, v63
	s_waitcnt lgkmcnt(0)
	v_add_f32_e32 v104, v102, v104
	ds_bpermute_b32 v106, v42, v104
	v_and_b32_e32 v62, 0xffff0000, v62
	v_lshlrev_b32_e32 v101, 16, v65
	v_lshlrev_b32_e32 v100, 16, v64
	v_and_b32_e32 v65, 0xffff0000, v65
	s_waitcnt lgkmcnt(0)
	v_add_f32_e32 v106, v104, v106
	ds_bpermute_b32 v108, v43, v106
	v_and_b32_e32 v64, 0xffff0000, v64
	s_waitcnt vmcnt(0)
	v_lshlrev_b32_e32 v109, 16, v77
	v_and_b32_e32 v77, 0xffff0000, v77
	v_lshlrev_b32_e32 v95, 16, v67
	s_waitcnt lgkmcnt(0)
	v_add_f32_e32 v108, v106, v108
	ds_bpermute_b32 v110, v44, v108
	v_lshlrev_b32_e32 v94, 16, v66
	v_and_b32_e32 v67, 0xffff0000, v67
	v_and_b32_e32 v66, 0xffff0000, v66
	v_lshlrev_b32_e32 v99, 16, v69
	s_waitcnt lgkmcnt(0)
; __device__ __forceinline__ unsigned pk2(float lo, float hi) { return f2bf(lo) | (f2bf(hi) << 16); }
; __device__ __forceinline__ void postnorm(const Ctx& c, const bf16* MF, bf16* XB, float* RS, const float* gpost, float* OUT) {
;     ...
;         const float rs = rsqrtf(wave_sum(s) * (1.f / DM) + EPS);
;         float s2 = 0.f;
; #pragma unroll
;         for (int j = 0; j < 4; ++j) { const float* gp = gpost + (c.lane + 64 * j) * 8; const f32x4 g0 = *(CF4)gp, g1 = *(CF4)(gp + 4);
; #pragma unroll
;             for (int k = 0; k < 4; ++k) { const float ga = (k < 2) ? g0[2 * k] : g1[2 * k - 4], gb = (k < 2) ? g0[2 * k + 1] : g1[2 * k - 3];
;                 v[j][2 * k] = bflo(xv[j][k]) + v[j][2 * k] * rs * ga; v[j][2 * k + 1] = bfhi(xv[j][k]) + v[j][2 * k + 1] * rs * gb;
;                 s2 += v[j][2 * k] * v[j][2 * k] + v[j][2 * k + 1] * v[j][2 * k + 1]; } }
;         if (OUT) {
; #pragma unroll
;             for (int j = 0; j < 4; ++j) { float* op = OUT + (size_t)row * DM + (c.lane + 64 * j) * 8; *(f32x4*)op = (f32x4){v[j][0], v[j][1], v[j][2], v[j][3]}; *(f32x4*)(op + 4) = (f32x4){v[j][4], v[j][5], v[j][6], v[j][7]}; }
;         } else {
; #pragma unroll
;             for (int j = 0; j < 4; ++j) { v4u o; o.x = pk2(v[j][0], v[j][1]); o.y = pk2(v[j][2], v[j][3]); o.z = pk2(v[j][4], v[j][5]); o.w = pk2(v[j][6], v[j][7]); xr[64 * j] = o; }
;             const float rs2 = rsqrtf(wave_sum(s2) * (1.f / DM) + EPS); if (c.lane == 0) RS[row] = rs2;
	v_add_f32_e32 v108, v108, v110
	v_fmamk_f32 v108, v108, 0x3a000000, v45
	v_mul_f32_e32 v110, 0x4b800000, v108
	v_cmp_gt_f32_e32 vcc, s15, v108
	v_lshlrev_b32_e32 v98, 16, v68
	v_and_b32_e32 v69, 0xffff0000, v69
	v_cndmask_b32_e32 v108, v108, v110, vcc
	v_rsq_f32_e32 v110, v108
	v_lshlrev_b32_e32 v108, 16, v76
	v_and_b32_e32 v76, 0xffff0000, v76
	v_and_b32_e32 v68, 0xffff0000, v68
	v_mul_f32_e32 v111, 0x45800000, v110
	v_cndmask_b32_e32 v110, v110, v111, vcc
	v_pk_mul_f32 v[46:47], v[110:111], v[46:47] op_sel_hi:[0,1]
	v_pk_mul_f32 v[78:79], v[110:111], v[78:79] op_sel_hi:[0,1]
	v_pk_mul_f32 v[48:49], v[110:111], v[48:49] op_sel_hi:[0,1]
	v_pk_fma_f32 v[46:47], v[36:37], v[46:47], v[62:63]
	v_pk_mul_f32 v[60:61], v[110:111], v[60:61] op_sel_hi:[0,1]
	v_pk_mul_f32 v[80:81], v[110:111], v[80:81] op_sel_hi:[0,1]
	v_pk_fma_f32 v[78:79], v[8:9], v[78:79], v[96:97]
	v_pk_fma_f32 v[48:49], v[10:11], v[48:49], v[64:65]
	v_pk_fma_f32 v[60:61], v[34:35], v[60:61], v[76:77]
	v_pk_mul_f32 v[76:77], v[46:47], v[46:47]
	v_pk_mul_f32 v[50:51], v[110:111], v[50:51] op_sel_hi:[0,1]
	v_pk_fma_f32 v[62:63], v[4:5], v[80:81], v[100:101]
	v_pk_fma_f32 v[76:77], v[78:79], v[78:79], v[76:77]
	v_pk_mul_f32 v[80:81], v[48:49], v[48:49]
	v_pk_mul_f32 v[82:83], v[110:111], v[82:83] op_sel_hi:[0,1]
	v_pk_fma_f32 v[50:51], v[6:7], v[50:51], v[66:67]
	v_pk_fma_f32 v[80:81], v[62:63], v[62:63], v[80:81]
	v_add_f32_e32 v76, v76, v77
	v_pk_fma_f32 v[64:65], v[16:17], v[82:83], v[94:95]
	v_pk_mul_f32 v[82:83], v[50:51], v[50:51]
	v_add_f32_e32 v76, v80, v76
	v_pk_fma_f32 v[82:83], v[64:65], v[64:65], v[82:83]
	v_add_f32_e32 v76, v81, v76
	v_add_f32_e32 v76, v82, v76
	s_nop 2
	v_bfe_u32 v82, v46, 16, 1
	v_pk_mul_f32 v[52:53], v[110:111], v[52:53] op_sel_hi:[0,1]
	v_add3_u32 v46, v46, v82, s16
	s_nop 2
	v_bfe_u32 v77, v78, 16, 1
	s_nop 2
	v_pk_mul_f32 v[84:85], v[110:111], v[84:85] op_sel_hi:[0,1]
	v_pk_fma_f32 v[52:53], v[18:19], v[52:53], v[68:69]
	s_nop 2
	v_add3_u32 v77, v78, v77, s16
	v_lshlrev_b32_e32 v103, 16, v71
	v_lshlrev_b32_e32 v102, 16, v70
	v_and_b32_e32 v71, 0xffff0000, v71
	v_and_b32_e32 v70, 0xffff0000, v70
	v_pk_fma_f32 v[66:67], v[12:13], v[84:85], v[98:99]
	v_pk_mul_f32 v[54:55], v[110:111], v[54:55] op_sel_hi:[0,1]
	v_pk_mul_f32 v[84:85], v[52:53], v[52:53]
	v_lshrrev_b32_e32 v77, 16, v77
	s_nop 2
	v_pk_mul_f32 v[68:69], v[110:111], v[86:87] op_sel_hi:[0,1]
	v_pk_fma_f32 v[54:55], v[14:15], v[54:55], v[70:71]
	v_pk_fma_f32 v[84:85], v[66:67], v[66:67], v[84:85]
	v_add_f32_e32 v76, v83, v76
	v_cvt_pk_bf16_f32 v49, v63, v49
	v_cvt_pk_bf16_f32 v48, v62, v48
	v_cvt_pk_bf16_f32 v47, v79, v47
	v_and_or_b32 v46, v46, s14, v77
	v_lshlrev_b32_e32 v105, 16, v73
	v_lshlrev_b32_e32 v104, 16, v72
	v_and_b32_e32 v73, 0xffff0000, v73
	v_and_b32_e32 v72, 0xffff0000, v72
	v_pk_fma_f32 v[68:69], v[24:25], v[68:69], v[102:103]
	v_pk_mul_f32 v[56:57], v[110:111], v[56:57] op_sel_hi:[0,1]
	v_pk_mul_f32 v[86:87], v[54:55], v[54:55]
	v_add_f32_e32 v76, v84, v76
	global_store_dwordx4 v[38:39], v[46:49], off
	v_pk_mul_f32 v[70:71], v[110:111], v[88:89] op_sel_hi:[0,1]
	v_pk_fma_f32 v[56:57], v[26:27], v[56:57], v[72:73]
	s_nop 3
	v_pk_fma_f32 v[86:87], v[68:69], v[68:69], v[86:87]
	v_add_f32_e32 v76, v85, v76
	s_nop 7
	v_lshlrev_b32_e32 v107, 16, v75
	v_lshlrev_b32_e32 v106, 16, v74
	v_and_b32_e32 v75, 0xffff0000, v75
	v_and_b32_e32 v74, 0xffff0000, v74
	v_pk_fma_f32 v[70:71], v[20:21], v[70:71], v[104:105]
	v_pk_mul_f32 v[58:59], v[110:111], v[58:59] op_sel_hi:[0,1]
	v_pk_mul_f32 v[88:89], v[56:57], v[56:57]
	v_add_f32_e32 v76, v86, v76
	s_nop 3
	v_pk_mul_f32 v[72:73], v[110:111], v[90:91] op_sel_hi:[0,1]
	v_pk_fma_f32 v[58:59], v[22:23], v[58:59], v[74:75]
	v_pk_fma_f32 v[88:89], v[70:71], v[70:71], v[88:89]
	v_add_f32_e32 v76, v87, v76
	s_nop 3
	v_pk_fma_f32 v[72:73], v[32:33], v[72:73], v[106:107]
	v_pk_mul_f32 v[90:91], v[58:59], v[58:59]
	v_add_f32_e32 v76, v88, v76
	v_cvt_pk_bf16_f32 v49, v67, v53
	v_cvt_pk_bf16_f32 v48, v66, v52
	v_cvt_pk_bf16_f32 v47, v65, v51
	v_cvt_pk_bf16_f32 v46, v64, v50
	v_pk_mul_f32 v[74:75], v[110:111], v[92:93] op_sel_hi:[0,1]
	v_pk_fma_f32 v[90:91], v[72:73], v[72:73], v[90:91]
	v_add_f32_e32 v76, v89, v76
	global_store_dwordx4 v[38:39], v[46:49], off offset:1024
	v_pk_fma_f32 v[74:75], v[28:29], v[74:75], v[108:109]
	v_pk_mul_f32 v[92:93], v[60:61], v[60:61]
	s_nop 1
	v_add_f32_e32 v76, v90, v76
	s_nop 5
	v_pk_fma_f32 v[92:93], v[74:75], v[74:75], v[92:93]
	v_add_f32_e32 v76, v91, v76
	s_nop 5
	v_add_f32_e32 v76, v92, v76
	s_nop 5
	v_add_f32_e32 v76, v93, v76
	v_cvt_pk_bf16_f32 v49, v71, v57
	v_cvt_pk_bf16_f32 v48, v70, v56
	v_cvt_pk_bf16_f32 v47, v69, v55
	v_cvt_pk_bf16_f32 v46, v68, v54
	global_store_dwordx4 v[38:39], v[46:49], off offset:2048
	ds_bpermute_b32 v47, v3, v76
	s_nop 3
	s_waitcnt lgkmcnt(0)
	v_add_f32_e32 v47, v76, v47
	ds_bpermute_b32 v50, v40, v47
	s_nop 3
	s_waitcnt lgkmcnt(0)
	v_add_f32_e32 v47, v47, v50
	ds_bpermute_b32 v50, v41, v47
	s_nop 1
	v_cvt_pk_bf16_f32 v51, v75, v61
	s_nop 0
	s_waitcnt lgkmcnt(0)
	v_add_f32_e32 v47, v47, v50
	ds_bpermute_b32 v50, v42, v47
	s_nop 3
	s_waitcnt lgkmcnt(0)
	v_add_f32_e32 v47, v47, v50
	ds_bpermute_b32 v50, v43, v47
	s_nop 3
	s_waitcnt lgkmcnt(0)
	v_add_f32_e32 v46, v47, v50
	ds_bpermute_b32 v47, v44, v46
	s_nop 0
	v_cvt_pk_bf16_f32 v50, v74, v60
	v_cvt_pk_bf16_f32 v49, v73, v59
	v_cvt_pk_bf16_f32 v48, v72, v58
	global_store_dwordx4 v[38:39], v[48:51], off offset:3072
	s_and_saveexec_b64 s[10:11], s[0:1]
	s_cbranch_execz .LBB0_3203
	s_waitcnt lgkmcnt(0)
	v_add_f32_e32 v38, v46, v47
	v_fmamk_f32 v38, v38, 0x3a000000, v45
	v_mul_f32_e32 v39, 0x4b800000, v38
	v_cmp_gt_f32_e32 vcc, s15, v38
	v_readlane_b32 s18, v253, 0
	v_readlane_b32 s19, v253, 1
	v_cndmask_b32_e32 v38, v38, v39, vcc
	v_rsq_f32_e32 v38, v38
	s_add_u32 s18, s18, s12
	s_addc_u32 s19, s19, s13
	v_mul_f32_e32 v39, 0x45800000, v38
	v_cndmask_b32_e32 v38, v38, v39, vcc
	global_store_dword v251, v38, s[18:19]
	s_branch .LBB0_3203

; #define LAS __attribute__((address_space(3)))
;     ...
;         const int kb = it / nblk, nb = it % nblk, k0 = 64 * kb, n0 = 64 * nb, nq = (lane & 15) * 4, kr = lane >> 4; const bool ok = (n0 + nq) < N;
;         f32x4 v[16];
; #pragma unroll
;         for (int i = 0; i < 16; ++i) v[i] = ok ? __builtin_nontemporal_load((const f32x4*)(W + (size_t)(k0 + 4 * i + kr) * N + n0 + nq)) : (f32x4){0.f, 0.f, 0.f, 0.f};
;         if (gain) {
; #pragma unroll
;             for (int i = 0; i < 16; ++i) v[i] *= gain[k0 + 4 * i + kr]; }
; #pragma unroll
;         for (int i = 0; i < 16; ++i) { LAS float* d = scr + (4 * i + kr) * 65 + nq; d[0] = v[i].x; d[1] = v[i].y; d[2] = v[i].z; d[3] = v[i].w; }
.LBB0_3209:
	s_or_b64 exec, exec, s[10:11]
	v_lshl_add_u64 v[82:83], v[72:73], 2, s[6:7]
	global_load_dword v72, v[82:83], off
	s_add_i32 s17, s17, s12
	s_ashr_i32 s9, s8, 31
	s_add_i32 s16, s16, s86
	s_add_i32 s12, s12, s13
	s_cmpk_lt_i32 s16, 0x100
	s_waitcnt vmcnt(0)
	v_pk_mul_f32 v[86:87], v[8:9], v[72:73] op_sel_hi:[1,0]
	global_load_dword v8, v[82:83], off offset:16
	v_pk_mul_f32 v[84:85], v[10:11], v[72:73] op_sel_hi:[1,0]
	s_waitcnt vmcnt(0)
	v_pk_mul_f32 v[72:73], v[14:15], v[8:9] op_sel_hi:[1,0]
	v_pk_mul_f32 v[88:89], v[12:13], v[8:9] op_sel_hi:[1,0]
	global_load_dword v8, v[82:83], off offset:32
	global_load_dword v12, v[82:83], off offset:160
	s_waitcnt vmcnt(1)
	v_pk_mul_f32 v[90:91], v[4:5], v[8:9] op_sel_hi:[1,0]
	global_load_dword v4, v[82:83], off offset:48
	v_pk_mul_f32 v[74:75], v[6:7], v[8:9] op_sel_hi:[1,0]
	global_load_dword v6, v[82:83], off offset:128
	global_load_dword v8, v[82:83], off offset:144
	s_waitcnt vmcnt(3)
	v_pk_mul_f32 v[10:11], v[42:43], v[12:13] op_sel_hi:[1,0]
	v_pk_mul_f32 v[12:13], v[40:41], v[12:13] op_sel_hi:[1,0]
	v_add_u32_e32 v40, 0x410, v81
	s_waitcnt vmcnt(2)
	v_pk_mul_f32 v[92:93], v[22:23], v[4:5] op_sel_hi:[1,0]
	v_pk_mul_f32 v[94:95], v[20:21], v[4:5] op_sel_hi:[1,0]
	global_load_dword v4, v[82:83], off offset:64
	global_load_dword v20, v[82:83], off offset:192
	s_waitcnt vmcnt(1)
	v_pk_mul_f32 v[96:97], v[18:19], v[4:5] op_sel_hi:[1,0]
	v_pk_mul_f32 v[98:99], v[16:17], v[4:5] op_sel_hi:[1,0]
	global_load_dword v4, v[82:83], off offset:80
	global_load_dword v16, v[82:83], off offset:176
	s_waitcnt vmcnt(2)
	v_pk_mul_f32 v[18:19], v[50:51], v[20:21] op_sel_hi:[1,0]
	v_pk_mul_f32 v[20:21], v[48:49], v[20:21] op_sel_hi:[1,0]
	s_waitcnt vmcnt(1)
	v_pk_mul_f32 v[100:101], v[30:31], v[4:5] op_sel_hi:[1,0]
	v_pk_mul_f32 v[102:103], v[28:29], v[4:5] op_sel_hi:[1,0]
	global_load_dword v4, v[82:83], off offset:96
	global_load_dword v28, v[82:83], off offset:224
	v_lshl_add_u64 v[30:31], v[76:77], 2, s[6:7]
	s_waitcnt vmcnt(2)
	v_pk_mul_f32 v[14:15], v[54:55], v[16:17] op_sel_hi:[1,0]
	v_pk_mul_f32 v[16:17], v[52:53], v[16:17] op_sel_hi:[1,0]
	s_waitcnt vmcnt(1)
	v_pk_mul_f32 v[104:105], v[26:27], v[4:5] op_sel_hi:[1,0]
	v_pk_mul_f32 v[106:107], v[24:25], v[4:5] op_sel_hi:[1,0]
	global_load_dword v4, v[82:83], off offset:112
	global_load_dword v24, v[82:83], off offset:208
	s_waitcnt vmcnt(2)
	v_pk_mul_f32 v[26:27], v[58:59], v[28:29] op_sel_hi:[1,0]
	v_pk_mul_f32 v[28:29], v[56:57], v[28:29] op_sel_hi:[1,0]
	s_waitcnt vmcnt(1)
	v_pk_mul_f32 v[38:39], v[38:39], v[4:5] op_sel_hi:[1,0]
	v_pk_mul_f32 v[36:37], v[36:37], v[4:5] op_sel_hi:[1,0]
	v_pk_mul_f32 v[4:5], v[34:35], v[6:7] op_sel_hi:[1,0]
	v_pk_mul_f32 v[34:35], v[32:33], v[6:7] op_sel_hi:[1,0]
	global_load_dword v32, v[30:31], off
	ds_write2_b32 v81, v86, v87 offset1:1
	ds_write2_b32 v81, v84, v85 offset0:2 offset1:3
	ds_write2_b32 v40, v88, v89 offset1:1
	v_add_u32_e32 v40, 0x418, v81
	ds_write2_b32 v40, v72, v73 offset1:1
	v_add_u32_e32 v40, 0x820, v81
	ds_write2_b32 v40, v90, v91 offset1:1
	v_add_u32_e32 v40, 0x828, v81
	ds_write2_b32 v40, v74, v75 offset1:1
	v_add_u32_e32 v40, 0xc30, v81
	ds_write2_b32 v40, v94, v95 offset1:1
	v_add_u32_e32 v40, 0xc38, v81
	ds_write2_b32 v40, v92, v93 offset1:1
	v_add_u32_e32 v40, 0x1040, v81
	ds_write2_b32 v40, v98, v99 offset1:1
	v_add_u32_e32 v40, 0x1048, v81
	ds_write2_b32 v40, v96, v97 offset1:1
	v_add_u32_e32 v40, 0x1450, v81
	ds_write2_b32 v40, v102, v103 offset1:1
	v_add_u32_e32 v40, 0x1458, v81
	ds_write2_b32 v40, v100, v101 offset1:1
	v_add_u32_e32 v40, 0x1860, v81
	ds_write2_b32 v40, v106, v107 offset1:1
	v_add_u32_e32 v40, 0x1868, v81
	ds_write2_b32 v40, v104, v105 offset1:1
	v_add_u32_e32 v40, 0x1c70, v81
	ds_write2_b32 v40, v36, v37 offset1:1
	v_add_u32_e32 v36, 0x1c78, v81
	ds_write2_b32 v36, v38, v39 offset1:1
	v_add_u32_e32 v36, 0x2080, v81
	ds_write2_b32 v36, v34, v35 offset1:1
	v_add_u32_e32 v34, 0x2088, v81
	v_pk_mul_f32 v[6:7], v[46:47], v[8:9] op_sel_hi:[1,0]
	v_pk_mul_f32 v[8:9], v[44:45], v[8:9] op_sel_hi:[1,0]
	ds_write2_b32 v34, v4, v5 offset1:1
	v_add_u32_e32 v4, 0x2490, v81
	ds_write2_b32 v4, v8, v9 offset1:1
	v_add_u32_e32 v4, 0x2498, v81
	ds_write2_b32 v4, v6, v7 offset1:1
	v_add_u32_e32 v4, 0x28a0, v81
	ds_write2_b32 v4, v12, v13 offset1:1
	v_add_u32_e32 v4, 0x28a8, v81
	ds_write2_b32 v4, v10, v11 offset1:1
	v_add_u32_e32 v4, 0x2cb0, v81
	ds_write2_b32 v4, v16, v17 offset1:1
	v_add_u32_e32 v4, 0x2cb8, v81
	ds_write2_b32 v4, v14, v15 offset1:1
	v_add_u32_e32 v4, 0x30c0, v81
	ds_write2_b32 v4, v20, v21 offset1:1
	v_add_u32_e32 v4, 0x30c8, v81
	s_waitcnt vmcnt(1)
	v_pk_mul_f32 v[22:23], v[62:63], v[24:25] op_sel_hi:[1,0]
	v_pk_mul_f32 v[24:25], v[60:61], v[24:25] op_sel_hi:[1,0]
	ds_write2_b32 v4, v18, v19 offset1:1
	v_add_u32_e32 v4, 0x34d0, v81
	ds_write2_b32 v4, v24, v25 offset1:1
	v_add_u32_e32 v4, 0x34d8, v81
	ds_write2_b32 v4, v22, v23 offset1:1
	v_add_u32_e32 v4, 0x38e0, v81
	ds_write2_b32 v4, v28, v29 offset1:1
	v_add_u32_e32 v4, 0x38e8, v81
	ds_write2_b32 v4, v26, v27 offset1:1
	v_add_u32_e32 v4, 0x3cf0, v81
	s_waitcnt vmcnt(0)
	v_pk_mul_f32 v[30:31], v[66:67], v[32:33] op_sel_hi:[1,0]
	v_pk_mul_f32 v[32:33], v[64:65], v[32:33] op_sel_hi:[1,0]
	ds_write2_b32 v4, v32, v33 offset1:1
	v_add_u32_e32 v4, 0x3cf8, v81
	ds_write2_b32 v4, v30, v31 offset1:1
	s_waitcnt lgkmcnt(0)
	ds_read2_b32 v[8:9], v80 offset0:65 offset1:73
	ds_read2_b32 v[14:15], v80 offset1:8
	ds_read2_b32 v[16:17], v80 offset0:130 offset1:138
	ds_read2_b32 v[18:19], v80 offset0:195 offset1:203
	v_lshl_add_u64 v[4:5], s[8:9], 1, v[70:71]
	s_waitcnt lgkmcnt(3)
; #define LAS __attribute__((address_space(3)))
; __device__ __forceinline__ unsigned pk2(float lo, float hi) { return f2bf(lo) | (f2bf(hi) << 16); }
;     ...
; #pragma unroll
;         for (int j = 0; j < 8; ++j) { const int n = (lane >> 3) + 8 * j; const LAS float* sp = scr + (8 * c8) * 65 + n;
;             v4u o; o.x = pk2(sp[0 * 65], sp[1 * 65]); o.y = pk2(sp[2 * 65], sp[3 * 65]); o.z = pk2(sp[4 * 65], sp[5 * 65]); o.w = pk2(sp[6 * 65], sp[7 * 65]);
;             *(v4u*)(WT + (size_t)(d0 + n) * K + k0 + 8 * c8) = o; }
	v_bfe_u32 v7, v8, 16, 1
	s_waitcnt lgkmcnt(2)
	v_bfe_u32 v6, v14, 16, 1
	v_add3_u32 v6, v14, v6, s14
	v_add3_u32 v7, v8, v7, s14
	v_add_u32_e32 v8, 0x400, v80
	v_lshrrev_b32_e32 v6, 16, v6
	ds_read2_b32 v[20:21], v8 offset0:4 offset1:12
	ds_read2_b32 v[22:23], v8 offset0:69 offset1:77
	v_and_or_b32 v10, v7, s15, v6
	s_waitcnt lgkmcnt(3)
	s_nop 1
	s_waitcnt lgkmcnt(2)
	s_nop 2
	ds_read2_b32 v[24:25], v8 offset0:134 offset1:142
	ds_read2_b32 v[26:27], v8 offset0:199 offset1:207
	v_cvt_pk_bf16_f32 v11, v16, v18
	s_waitcnt lgkmcnt(3)
	s_nop 1
	s_waitcnt lgkmcnt(2)
	s_nop 2
	v_cvt_pk_bf16_f32 v12, v20, v22
	s_waitcnt lgkmcnt(1)
	s_nop 1
	s_waitcnt lgkmcnt(0)
	s_nop 2
	v_cvt_pk_bf16_f32 v13, v24, v26
	v_add_u32_e32 v6, s17, v79
	v_ashrrev_i32_e32 v7, 31, v6
	v_lshlrev_b64 v[28:29], 12, v[6:7]
	v_lshl_add_u64 v[28:29], v[4:5], 0, v[28:29]
	s_nop 0
	global_store_dwordx4 v[28:29], v[10:13], off
	s_nop 3
	v_cvt_pk_bf16_f32 v10, v15, v9
	s_nop 4
	v_cvt_pk_bf16_f32 v11, v17, v19
	s_nop 4
	v_cvt_pk_bf16_f32 v12, v21, v23
	s_nop 0
	v_add_u32_e32 v14, 8, v6
	s_nop 1
	v_ashrrev_i32_e32 v15, 31, v14
	s_nop 1
	v_lshlrev_b64 v[14:15], 12, v[14:15]
	v_cvt_pk_bf16_f32 v13, v25, v27
	v_lshl_add_u64 v[14:15], v[4:5], 0, v[14:15]
	global_store_dwordx4 v[14:15], v[10:13], off
	ds_read2_b32 v[14:15], v80 offset0:81 offset1:89
	ds_read2_b32 v[16:17], v80 offset0:16 offset1:24
	ds_read2_b32 v[18:19], v80 offset0:146 offset1:154
	ds_read2_b32 v[20:21], v80 offset0:211 offset1:219
	ds_read2_b32 v[22:23], v8 offset0:20 offset1:28
	ds_read2_b32 v[24:25], v8 offset0:85 offset1:93
	ds_read2_b32 v[26:27], v8 offset0:150 offset1:158
	ds_read2_b32 v[28:29], v8 offset0:215 offset1:223
	s_waitcnt lgkmcnt(7)
	s_nop 0
	s_waitcnt lgkmcnt(6)
	s_nop 3
	v_cvt_pk_bf16_f32 v10, v16, v14
	s_waitcnt lgkmcnt(5)
	s_nop 1
	s_waitcnt lgkmcnt(4)
	s_nop 2
	v_cvt_pk_bf16_f32 v11, v18, v20
	s_waitcnt lgkmcnt(3)
	s_nop 1
	s_waitcnt lgkmcnt(2)
	s_nop 2
	v_cvt_pk_bf16_f32 v12, v22, v24
	s_waitcnt lgkmcnt(1)
	s_nop 1
	s_waitcnt lgkmcnt(0)
	s_nop 2
	v_add_u32_e32 v30, 16, v6
	v_cvt_pk_bf16_f32 v13, v26, v28
	v_ashrrev_i32_e32 v31, 31, v30
	v_bfe_u32 v7, v17, 16, 1
	v_lshlrev_b64 v[30:31], 12, v[30:31]
	v_add3_u32 v7, v17, v7, s14
	v_bfe_u32 v9, v15, 16, 1
	v_lshl_add_u64 v[30:31], v[4:5], 0, v[30:31]
	v_lshrrev_b32_e32 v7, 16, v7
	v_add3_u32 v9, v15, v9, s14
	global_store_dwordx4 v[30:31], v[10:13], off
	v_add_u32_e32 v14, 24, v6
	v_ashrrev_i32_e32 v15, 31, v14
	v_and_or_b32 v10, v9, s15, v7
	s_nop 4
	v_cvt_pk_bf16_f32 v11, v19, v21
	s_nop 4
	v_cvt_pk_bf16_f32 v12, v23, v25
	s_nop 4
	v_lshlrev_b64 v[14:15], 12, v[14:15]
	v_cvt_pk_bf16_f32 v13, v27, v29
	v_lshl_add_u64 v[14:15], v[4:5], 0, v[14:15]
	global_store_dwordx4 v[14:15], v[10:13], off
	ds_read2_b32 v[14:15], v80 offset0:97 offset1:105
	ds_read2_b32 v[16:17], v80 offset0:32 offset1:40
	ds_read2_b32 v[18:19], v80 offset0:162 offset1:170
	ds_read2_b32 v[20:21], v80 offset0:227 offset1:235
	ds_read2_b32 v[22:23], v8 offset0:36 offset1:44
	ds_read2_b32 v[24:25], v8 offset0:101 offset1:109
	ds_read2_b32 v[26:27], v8 offset0:166 offset1:174
	ds_read2_b32 v[28:29], v8 offset0:231 offset1:239
	s_waitcnt lgkmcnt(7)
	s_nop 0
	s_waitcnt lgkmcnt(6)
	s_nop 3
	v_cvt_pk_bf16_f32 v10, v16, v14
	s_waitcnt lgkmcnt(5)
	s_nop 1
	s_waitcnt lgkmcnt(4)
	s_nop 2
	v_cvt_pk_bf16_f32 v11, v18, v20
	s_waitcnt lgkmcnt(3)
	s_nop 1
	s_waitcnt lgkmcnt(2)
	s_nop 2
	v_cvt_pk_bf16_f32 v12, v22, v24
	s_waitcnt lgkmcnt(1)
	s_nop 1
	s_waitcnt lgkmcnt(0)
	s_nop 2
	v_add_u32_e32 v30, 32, v6
	v_cvt_pk_bf16_f32 v13, v26, v28
	v_ashrrev_i32_e32 v31, 31, v30
	v_bfe_u32 v7, v17, 16, 1
	v_lshlrev_b64 v[30:31], 12, v[30:31]
	v_add3_u32 v7, v17, v7, s14
	v_bfe_u32 v9, v15, 16, 1
	v_lshl_add_u64 v[30:31], v[4:5], 0, v[30:31]
	v_lshrrev_b32_e32 v7, 16, v7
	v_add3_u32 v9, v15, v9, s14
	global_store_dwordx4 v[30:31], v[10:13], off
	v_add_u32_e32 v14, 40, v6
	v_ashrrev_i32_e32 v15, 31, v14
	v_and_or_b32 v10, v9, s15, v7
	s_nop 4
	v_cvt_pk_bf16_f32 v11, v19, v21
	s_nop 4
	v_cvt_pk_bf16_f32 v12, v23, v25
	s_nop 4
	v_lshlrev_b64 v[14:15], 12, v[14:15]
	v_cvt_pk_bf16_f32 v13, v27, v29
	v_lshl_add_u64 v[14:15], v[4:5], 0, v[14:15]
	global_store_dwordx4 v[14:15], v[10:13], off
	ds_read2_b32 v[14:15], v80 offset0:48 offset1:56
	ds_read2_b32 v[16:17], v80 offset0:113 offset1:121
	ds_read2_b32 v[18:19], v80 offset0:178 offset1:186
	ds_read2_b32 v[20:21], v80 offset0:243 offset1:251
	ds_read2_b32 v[22:23], v8 offset0:52 offset1:60
	ds_read2_b32 v[24:25], v8 offset0:117 offset1:125
	ds_read2_b32 v[26:27], v8 offset0:182 offset1:190
	ds_read2_b32 v[28:29], v8 offset0:247 offset1:255
	s_waitcnt lgkmcnt(7)
	s_nop 1
	s_waitcnt lgkmcnt(6)
	s_nop 2
	v_cvt_pk_bf16_f32 v10, v14, v16
	s_waitcnt lgkmcnt(5)
	s_nop 1
	s_waitcnt lgkmcnt(4)
	s_nop 2
	v_cvt_pk_bf16_f32 v11, v18, v20
	s_waitcnt lgkmcnt(3)
	s_nop 1
	s_waitcnt lgkmcnt(2)
	s_nop 2
	v_cvt_pk_bf16_f32 v12, v22, v24
	s_waitcnt lgkmcnt(1)
	s_nop 1
	s_waitcnt lgkmcnt(0)
	s_nop 2
	v_cvt_pk_bf16_f32 v13, v26, v28
	v_add_u32_e32 v8, 48, v6
	v_ashrrev_i32_e32 v9, 31, v8
	v_lshlrev_b64 v[8:9], 12, v[8:9]
	v_lshl_add_u64 v[8:9], v[4:5], 0, v[8:9]
	s_nop 0
	global_store_dwordx4 v[8:9], v[10:13], off
	s_nop 3
	v_cvt_pk_bf16_f32 v8, v15, v17
	s_nop 4
	v_cvt_pk_bf16_f32 v9, v19, v21
	s_nop 4
	v_cvt_pk_bf16_f32 v10, v23, v25
	s_nop 4
	v_add_u32_e32 v6, 56, v6
	v_cvt_pk_bf16_f32 v11, v27, v29
	v_ashrrev_i32_e32 v7, 31, v6
	v_lshlrev_b64 v[6:7], 12, v[6:7]
	v_lshl_add_u64 v[4:5], v[4:5], 0, v[6:7]
	global_store_dwordx4 v[4:5], v[8:11], off
	s_waitcnt lgkmcnt(0)
	s_cbranch_scc0 .LBB0_3242

; #define LAS __attribute__((address_space(3)))
; #define LDS_WAIT() asm volatile("s_waitcnt lgkmcnt(0)" ::: "memory")
; __device__ __forceinline__ unsigned pk2(float lo, float hi) { return f2bf(lo) | (f2bf(hi) << 16); }
;     ...
;         for (int i = 0; i < 16; ++i) { LAS float* d = scr + (4 * i + kr) * 65 + nq; d[0] = v[i].x; d[1] = v[i].y; d[2] = v[i].z; d[3] = v[i].w; }
;         LDS_WAIT(); asm volatile("" ::: "memory");
;         const int c8 = lane & 7; int d0 = n0;
;         if (ffnmap) { const int bj = n0 >= FFH ? 1 : 0, chn = n0 - FFH * bj; d0 = 256 * (chn >> 7) + 128 * bj + (chn & 127); }
; #pragma unroll
;         for (int j = 0; j < 8; ++j) { const int n = (lane >> 3) + 8 * j; const LAS float* sp = scr + (8 * c8) * 65 + n;
;             v4u o; o.x = pk2(sp[0 * 65], sp[1 * 65]); o.y = pk2(sp[2 * 65], sp[3 * 65]); o.z = pk2(sp[4 * 65], sp[5 * 65]); o.w = pk2(sp[6 * 65], sp[7 * 65]);
;             *(v4u*)(WT + (size_t)(d0 + n) * K + k0 + 8 * c8) = o; }
.LBB0_3244:
	s_or_b64 exec, exec, s[8:9]
	s_waitcnt vmcnt(0)
	ds_write2_b32 v79, v4, v5 offset1:1
	ds_write2_b32 v79, v6, v7 offset0:2 offset1:3
	v_add_u32_e32 v4, 0x410, v79
	ds_write2_b32 v4, v12, v13 offset1:1
	v_add_u32_e32 v4, 0x418, v79
	ds_write2_b32 v4, v14, v15 offset1:1
	v_add_u32_e32 v4, 0x820, v79
	ds_write2_b32 v4, v8, v9 offset1:1
	v_add_u32_e32 v4, 0x828, v79
	ds_write2_b32 v4, v10, v11 offset1:1
	v_add_u32_e32 v4, 0xc30, v79
	ds_write2_b32 v4, v20, v21 offset1:1
	v_add_u32_e32 v4, 0xc38, v79
	ds_write2_b32 v4, v22, v23 offset1:1
	v_add_u32_e32 v4, 0x1040, v79
	ds_write2_b32 v4, v16, v17 offset1:1
	v_add_u32_e32 v4, 0x1048, v79
	ds_write2_b32 v4, v18, v19 offset1:1
	v_add_u32_e32 v4, 0x1450, v79
	ds_write2_b32 v4, v28, v29 offset1:1
	v_add_u32_e32 v4, 0x1458, v79
	ds_write2_b32 v4, v30, v31 offset1:1
	v_add_u32_e32 v4, 0x1860, v79
	ds_write2_b32 v4, v24, v25 offset1:1
	v_add_u32_e32 v4, 0x1868, v79
	ds_write2_b32 v4, v26, v27 offset1:1
	v_add_u32_e32 v4, 0x1c70, v79
	ds_write2_b32 v4, v36, v37 offset1:1
	v_add_u32_e32 v4, 0x1c78, v79
	ds_write2_b32 v4, v38, v39 offset1:1
	v_add_u32_e32 v4, 0x2080, v79
	ds_write2_b32 v4, v32, v33 offset1:1
	v_add_u32_e32 v4, 0x2088, v79
	ds_write2_b32 v4, v34, v35 offset1:1
	v_add_u32_e32 v4, 0x2490, v79
	ds_write2_b32 v4, v44, v45 offset1:1
	v_add_u32_e32 v4, 0x2498, v79
	ds_write2_b32 v4, v46, v47 offset1:1
	v_add_u32_e32 v4, 0x28a0, v79
	ds_write2_b32 v4, v40, v41 offset1:1
	v_add_u32_e32 v4, 0x28a8, v79
	ds_write2_b32 v4, v42, v43 offset1:1
	v_add_u32_e32 v4, 0x2cb0, v79
	ds_write2_b32 v4, v52, v53 offset1:1
	v_add_u32_e32 v4, 0x2cb8, v79
	ds_write2_b32 v4, v54, v55 offset1:1
	v_add_u32_e32 v4, 0x30c0, v79
	ds_write2_b32 v4, v48, v49 offset1:1
	v_add_u32_e32 v4, 0x30c8, v79
	ds_write2_b32 v4, v50, v51 offset1:1
	v_add_u32_e32 v4, 0x34d0, v79
	ds_write2_b32 v4, v60, v61 offset1:1
	v_add_u32_e32 v4, 0x34d8, v79
	ds_write2_b32 v4, v62, v63 offset1:1
	v_add_u32_e32 v4, 0x38e0, v79
	ds_write2_b32 v4, v56, v57 offset1:1
	v_add_u32_e32 v4, 0x38e8, v79
	ds_write2_b32 v4, v58, v59 offset1:1
	v_add_u32_e32 v4, 0x3cf0, v79
	ds_write2_b32 v4, v64, v65 offset1:1
	v_add_u32_e32 v4, 0x3cf8, v79
	ds_write2_b32 v4, v66, v67 offset1:1
	s_waitcnt lgkmcnt(0)
	ds_read2_b32 v[12:13], v78 offset1:8
	ds_read2_b32 v[14:15], v78 offset0:65 offset1:73
	ds_read2_b32 v[16:17], v78 offset0:130 offset1:138
	ds_read2_b32 v[18:19], v78 offset0:195 offset1:203
	v_add_u32_e32 v30, 0x400, v78
	s_waitcnt lgkmcnt(3)
	s_nop 1
	s_waitcnt lgkmcnt(2)
	s_nop 0
	ds_read2_b32 v[20:21], v30 offset0:4 offset1:12
	s_nop 1
	ds_read2_b32 v[22:23], v30 offset0:69 offset1:77
	v_cvt_pk_bf16_f32 v8, v12, v14
	s_waitcnt lgkmcnt(3)
	s_nop 1
	s_waitcnt lgkmcnt(2)
	s_nop 0
	ds_read2_b32 v[24:25], v30 offset0:134 offset1:142
	s_nop 1
	ds_read2_b32 v[26:27], v30 offset0:199 offset1:207
	v_cvt_pk_bf16_f32 v9, v16, v18
	s_waitcnt lgkmcnt(3)
	s_nop 1
	s_waitcnt lgkmcnt(2)
	s_nop 2
	v_cvt_pk_bf16_f32 v10, v20, v22
	s_waitcnt lgkmcnt(1)
	s_nop 1
	s_waitcnt lgkmcnt(0)
	s_nop 2
	s_add_i32 s18, s18, s14
	v_cvt_pk_bf16_f32 v11, v24, v26
	v_add_u32_e32 v6, s18, v77
	s_ashr_i32 s7, s6, 31
	v_ashrrev_i32_e32 v7, 31, v6
	v_lshl_add_u64 v[4:5], s[6:7], 1, v[70:71]
	v_lshlrev_b64 v[28:29], 12, v[6:7]
	v_lshl_add_u64 v[28:29], v[4:5], 0, v[28:29]
	s_nop 0
	global_store_dwordx4 v[28:29], v[8:11], off
	s_nop 3
	v_cvt_pk_bf16_f32 v8, v13, v15
	s_nop 4
	v_cvt_pk_bf16_f32 v9, v17, v19
	s_nop 4
	v_cvt_pk_bf16_f32 v10, v21, v23
	s_nop 0
	v_add_u32_e32 v12, 8, v6
	s_nop 1
	v_ashrrev_i32_e32 v13, 31, v12
	s_nop 1
	v_lshlrev_b64 v[12:13], 12, v[12:13]
	v_cvt_pk_bf16_f32 v11, v25, v27
	ds_read2_b32 v[14:15], v78 offset0:16 offset1:24
	v_lshl_add_u64 v[12:13], v[4:5], 0, v[12:13]
	global_store_dwordx4 v[12:13], v[8:11], off
	ds_read2_b32 v[12:13], v78 offset0:81 offset1:89
	ds_read2_b32 v[16:17], v78 offset0:146 offset1:154
	ds_read2_b32 v[18:19], v78 offset0:211 offset1:219
	s_waitcnt lgkmcnt(3)
	s_nop 1
	s_waitcnt lgkmcnt(2)
; #define LAS __attribute__((address_space(3)))
; __device__ __forceinline__ unsigned pk2(float lo, float hi) { return f2bf(lo) | (f2bf(hi) << 16); }
;     ...
; #pragma unroll
;         for (int j = 0; j < 8; ++j) { const int n = (lane >> 3) + 8 * j; const LAS float* sp = scr + (8 * c8) * 65 + n;
;             v4u o; o.x = pk2(sp[0 * 65], sp[1 * 65]); o.y = pk2(sp[2 * 65], sp[3 * 65]); o.z = pk2(sp[4 * 65], sp[5 * 65]); o.w = pk2(sp[6 * 65], sp[7 * 65]);
;             *(v4u*)(WT + (size_t)(d0 + n) * K + k0 + 8 * c8) = o; }
	s_nop 0
	ds_read2_b32 v[20:21], v30 offset0:20 offset1:28
	s_nop 1
	ds_read2_b32 v[22:23], v30 offset0:85 offset1:93
	v_cvt_pk_bf16_f32 v8, v14, v12
	s_waitcnt lgkmcnt(3)
	s_nop 1
	s_waitcnt lgkmcnt(2)
	s_nop 0
	ds_read2_b32 v[24:25], v30 offset0:150 offset1:158
	s_nop 1
	ds_read2_b32 v[26:27], v30 offset0:215 offset1:223
	v_cvt_pk_bf16_f32 v9, v16, v18
	s_waitcnt lgkmcnt(3)
	s_nop 1
	s_waitcnt lgkmcnt(2)
	s_nop 2
	v_cvt_pk_bf16_f32 v10, v20, v22
	s_waitcnt lgkmcnt(1)
	s_nop 0
	v_add_u32_e32 v28, 16, v6
	s_nop 0
	s_waitcnt lgkmcnt(0)
	s_nop 0
	v_ashrrev_i32_e32 v29, 31, v28
	s_nop 1
	v_lshlrev_b64 v[28:29], 12, v[28:29]
	v_cvt_pk_bf16_f32 v11, v24, v26
	v_lshl_add_u64 v[28:29], v[4:5], 0, v[28:29]
	s_nop 0
	global_store_dwordx4 v[28:29], v[8:11], off
	s_nop 3
	v_cvt_pk_bf16_f32 v8, v15, v13
	s_nop 4
	v_cvt_pk_bf16_f32 v9, v17, v19
	s_nop 4
	v_cvt_pk_bf16_f32 v10, v21, v23
	s_nop 0
	v_add_u32_e32 v12, 24, v6
	s_nop 1
	v_ashrrev_i32_e32 v13, 31, v12
	s_nop 1
	v_lshlrev_b64 v[12:13], 12, v[12:13]
	v_cvt_pk_bf16_f32 v11, v25, v27
	ds_read2_b32 v[14:15], v78 offset0:32 offset1:40
	v_lshl_add_u64 v[12:13], v[4:5], 0, v[12:13]
	global_store_dwordx4 v[12:13], v[8:11], off
	ds_read2_b32 v[12:13], v78 offset0:97 offset1:105
	ds_read2_b32 v[16:17], v78 offset0:162 offset1:170
	ds_read2_b32 v[18:19], v78 offset0:227 offset1:235
	s_waitcnt lgkmcnt(3)
	s_nop 1
	s_waitcnt lgkmcnt(2)
	s_nop 0
	ds_read2_b32 v[20:21], v30 offset0:36 offset1:44
	s_nop 1
	ds_read2_b32 v[22:23], v30 offset0:101 offset1:109
	v_cvt_pk_bf16_f32 v8, v14, v12
	s_waitcnt lgkmcnt(3)
	s_nop 1
	s_waitcnt lgkmcnt(2)
	s_nop 0
	ds_read2_b32 v[24:25], v30 offset0:166 offset1:174
	s_nop 1
	ds_read2_b32 v[26:27], v30 offset0:231 offset1:239
	v_cvt_pk_bf16_f32 v9, v16, v18
	s_waitcnt lgkmcnt(3)
	s_nop 1
	s_waitcnt lgkmcnt(2)
	s_nop 2
	v_cvt_pk_bf16_f32 v10, v20, v22
	s_waitcnt lgkmcnt(1)
	s_nop 0
	v_add_u32_e32 v28, 32, v6
	s_nop 0
	s_waitcnt lgkmcnt(0)
	s_nop 0
	v_ashrrev_i32_e32 v29, 31, v28
	s_nop 1
	v_lshlrev_b64 v[28:29], 12, v[28:29]
	v_cvt_pk_bf16_f32 v11, v24, v26
	v_lshl_add_u64 v[28:29], v[4:5], 0, v[28:29]
	s_nop 0
	global_store_dwordx4 v[28:29], v[8:11], off
	s_nop 3
	v_cvt_pk_bf16_f32 v8, v15, v13
	s_nop 4
	v_cvt_pk_bf16_f32 v9, v17, v19
	s_nop 4
	v_cvt_pk_bf16_f32 v10, v21, v23
	s_nop 0
	v_add_u32_e32 v12, 40, v6
	s_nop 1
	v_ashrrev_i32_e32 v13, 31, v12
	s_nop 1
	v_lshlrev_b64 v[12:13], 12, v[12:13]
	v_cvt_pk_bf16_f32 v11, v25, v27
	ds_read2_b32 v[14:15], v78 offset0:48 offset1:56
	v_lshl_add_u64 v[12:13], v[4:5], 0, v[12:13]
	global_store_dwordx4 v[12:13], v[8:11], off
	ds_read2_b32 v[12:13], v78 offset0:113 offset1:121
	ds_read2_b32 v[16:17], v78 offset0:178 offset1:186
	ds_read2_b32 v[18:19], v78 offset0:243 offset1:251
	s_waitcnt lgkmcnt(3)
	s_nop 1
	s_waitcnt lgkmcnt(2)
	s_nop 0
	ds_read2_b32 v[20:21], v30 offset0:52 offset1:60
	s_nop 1
	ds_read2_b32 v[22:23], v30 offset0:117 offset1:125
	v_cvt_pk_bf16_f32 v8, v14, v12
	s_waitcnt lgkmcnt(3)
	s_nop 1
	s_waitcnt lgkmcnt(2)
	s_nop 0
	ds_read2_b32 v[24:25], v30 offset0:182 offset1:190
	s_nop 1
	ds_read2_b32 v[26:27], v30 offset0:247 offset1:255
	v_cvt_pk_bf16_f32 v9, v16, v18
	s_waitcnt lgkmcnt(3)
	s_nop 1
	s_waitcnt lgkmcnt(2)
	s_nop 2
	v_cvt_pk_bf16_f32 v10, v20, v22
	s_waitcnt lgkmcnt(1)
	s_nop 0
	v_add_u32_e32 v28, 48, v6
	s_nop 0
	s_waitcnt lgkmcnt(0)
	s_nop 0
	v_ashrrev_i32_e32 v29, 31, v28
	s_nop 1
	v_lshlrev_b64 v[28:29], 12, v[28:29]
	v_cvt_pk_bf16_f32 v11, v24, v26
	v_lshl_add_u64 v[28:29], v[4:5], 0, v[28:29]
	s_nop 0
	global_store_dwordx4 v[28:29], v[8:11], off
	s_nop 3
	v_cvt_pk_bf16_f32 v8, v15, v13
	s_nop 4
	v_cvt_pk_bf16_f32 v9, v17, v19
	s_nop 4
	v_cvt_pk_bf16_f32 v10, v21, v23
	s_nop 4
	v_add_u32_e32 v6, 56, v6
	v_cvt_pk_bf16_f32 v11, v25, v27
	v_ashrrev_i32_e32 v7, 31, v6
	v_lshlrev_b64 v[6:7], 12, v[6:7]
	v_lshl_add_u64 v[4:5], v[4:5], 0, v[6:7]
	global_store_dwordx4 v[4:5], v[8:11], off
	s_waitcnt lgkmcnt(0)
	s_add_i32 s13, s13, s86
	s_add_i32 s14, s14, s15
	s_cmpk_lt_i32 s13, 0x200
	s_cbranch_scc0 .LBB0_3277

; #define LAS __attribute__((address_space(3)))
; #define LDS_WAIT() asm volatile("s_waitcnt lgkmcnt(0)" ::: "memory")
; __device__ __forceinline__ unsigned pk2(float lo, float hi) { return f2bf(lo) | (f2bf(hi) << 16); }
;     ...
;         for (int i = 0; i < 16; ++i) { LAS float* d = scr + (4 * i + kr) * 65 + nq; d[0] = v[i].x; d[1] = v[i].y; d[2] = v[i].z; d[3] = v[i].w; }
;         LDS_WAIT(); asm volatile("" ::: "memory");
;         const int c8 = lane & 7; int d0 = n0;
;         if (ffnmap) { const int bj = n0 >= FFH ? 1 : 0, chn = n0 - FFH * bj; d0 = 256 * (chn >> 7) + 128 * bj + (chn & 127); }
; #pragma unroll
;         for (int j = 0; j < 8; ++j) { const int n = (lane >> 3) + 8 * j; const LAS float* sp = scr + (8 * c8) * 65 + n;
;             v4u o; o.x = pk2(sp[0 * 65], sp[1 * 65]); o.y = pk2(sp[2 * 65], sp[3 * 65]); o.z = pk2(sp[4 * 65], sp[5 * 65]); o.w = pk2(sp[6 * 65], sp[7 * 65]);
;             *(v4u*)(WT + (size_t)(d0 + n) * K + k0 + 8 * c8) = o; }
.LBB0_3279:
	s_or_b64 exec, exec, s[8:9]
	s_waitcnt vmcnt(0)
	ds_write2_b32 v79, v4, v5 offset1:1
	ds_write2_b32 v79, v6, v7 offset0:2 offset1:3
	v_add_u32_e32 v4, 0x410, v79
	ds_write2_b32 v4, v12, v13 offset1:1
	v_add_u32_e32 v4, 0x418, v79
	ds_write2_b32 v4, v14, v15 offset1:1
	v_add_u32_e32 v4, 0x820, v79
	ds_write2_b32 v4, v8, v9 offset1:1
	v_add_u32_e32 v4, 0x828, v79
	ds_write2_b32 v4, v10, v11 offset1:1
	v_add_u32_e32 v4, 0xc30, v79
	ds_write2_b32 v4, v20, v21 offset1:1
	v_add_u32_e32 v4, 0xc38, v79
	ds_write2_b32 v4, v22, v23 offset1:1
	v_add_u32_e32 v4, 0x1040, v79
	ds_write2_b32 v4, v16, v17 offset1:1
	v_add_u32_e32 v4, 0x1048, v79
	ds_write2_b32 v4, v18, v19 offset1:1
	v_add_u32_e32 v4, 0x1450, v79
	ds_write2_b32 v4, v28, v29 offset1:1
	v_add_u32_e32 v4, 0x1458, v79
	ds_write2_b32 v4, v30, v31 offset1:1
	v_add_u32_e32 v4, 0x1860, v79
	ds_write2_b32 v4, v24, v25 offset1:1
	v_add_u32_e32 v4, 0x1868, v79
	ds_write2_b32 v4, v26, v27 offset1:1
	v_add_u32_e32 v4, 0x1c70, v79
	ds_write2_b32 v4, v36, v37 offset1:1
	v_add_u32_e32 v4, 0x1c78, v79
	ds_write2_b32 v4, v38, v39 offset1:1
	v_add_u32_e32 v4, 0x2080, v79
	ds_write2_b32 v4, v32, v33 offset1:1
	v_add_u32_e32 v4, 0x2088, v79
	ds_write2_b32 v4, v34, v35 offset1:1
	v_add_u32_e32 v4, 0x2490, v79
	ds_write2_b32 v4, v44, v45 offset1:1
	v_add_u32_e32 v4, 0x2498, v79
	ds_write2_b32 v4, v46, v47 offset1:1
	v_add_u32_e32 v4, 0x28a0, v79
	ds_write2_b32 v4, v40, v41 offset1:1
	v_add_u32_e32 v4, 0x28a8, v79
	ds_write2_b32 v4, v42, v43 offset1:1
	v_add_u32_e32 v4, 0x2cb0, v79
	ds_write2_b32 v4, v52, v53 offset1:1
	v_add_u32_e32 v4, 0x2cb8, v79
	ds_write2_b32 v4, v54, v55 offset1:1
	v_add_u32_e32 v4, 0x30c0, v79
	ds_write2_b32 v4, v48, v49 offset1:1
	v_add_u32_e32 v4, 0x30c8, v79
	ds_write2_b32 v4, v50, v51 offset1:1
	v_add_u32_e32 v4, 0x34d0, v79
	ds_write2_b32 v4, v60, v61 offset1:1
	v_add_u32_e32 v4, 0x34d8, v79
	ds_write2_b32 v4, v62, v63 offset1:1
	v_add_u32_e32 v4, 0x38e0, v79
	ds_write2_b32 v4, v56, v57 offset1:1
	v_add_u32_e32 v4, 0x38e8, v79
	ds_write2_b32 v4, v58, v59 offset1:1
	v_add_u32_e32 v4, 0x3cf0, v79
	ds_write2_b32 v4, v64, v65 offset1:1
	v_add_u32_e32 v4, 0x3cf8, v79
	ds_write2_b32 v4, v66, v67 offset1:1
	s_waitcnt lgkmcnt(0)
	ds_read2_b32 v[12:13], v78 offset1:8
	ds_read2_b32 v[14:15], v78 offset0:65 offset1:73
	ds_read2_b32 v[16:17], v78 offset0:130 offset1:138
	ds_read2_b32 v[18:19], v78 offset0:195 offset1:203
	v_add_u32_e32 v30, 0x400, v78
	s_waitcnt lgkmcnt(3)
	s_nop 1
	s_waitcnt lgkmcnt(2)
	s_nop 0
	ds_read2_b32 v[20:21], v30 offset0:4 offset1:12
	s_nop 1
	ds_read2_b32 v[22:23], v30 offset0:69 offset1:77
	v_cvt_pk_bf16_f32 v8, v12, v14
	s_waitcnt lgkmcnt(3)
	s_nop 1
	s_waitcnt lgkmcnt(2)
	s_nop 0
	ds_read2_b32 v[24:25], v30 offset0:134 offset1:142
	s_nop 1
	ds_read2_b32 v[26:27], v30 offset0:199 offset1:207
	v_cvt_pk_bf16_f32 v9, v16, v18
	s_waitcnt lgkmcnt(3)
	s_nop 1
	s_waitcnt lgkmcnt(2)
	s_nop 2
	v_cvt_pk_bf16_f32 v10, v20, v22
	s_waitcnt lgkmcnt(1)
	s_nop 1
	s_waitcnt lgkmcnt(0)
	s_nop 2
	s_add_i32 s18, s18, s14
	v_cvt_pk_bf16_f32 v11, v24, v26
	v_add_u32_e32 v6, s18, v77
	s_ashr_i32 s7, s6, 31
	v_ashrrev_i32_e32 v7, 31, v6
	v_lshl_add_u64 v[4:5], s[6:7], 1, v[70:71]
	v_lshlrev_b64 v[28:29], 10, v[6:7]
	v_lshl_add_u64 v[28:29], v[4:5], 0, v[28:29]
	s_nop 0
	global_store_dwordx4 v[28:29], v[8:11], off
	s_nop 3
	v_cvt_pk_bf16_f32 v8, v13, v15
	s_nop 4
	v_cvt_pk_bf16_f32 v9, v17, v19
	s_nop 4
	v_cvt_pk_bf16_f32 v10, v21, v23
	s_nop 0
	v_add_u32_e32 v12, 8, v6
	s_nop 1
	v_ashrrev_i32_e32 v13, 31, v12
	s_nop 1
	v_lshlrev_b64 v[12:13], 10, v[12:13]
	v_cvt_pk_bf16_f32 v11, v25, v27
	ds_read2_b32 v[14:15], v78 offset0:16 offset1:24
	v_lshl_add_u64 v[12:13], v[4:5], 0, v[12:13]
	global_store_dwordx4 v[12:13], v[8:11], off
	ds_read2_b32 v[12:13], v78 offset0:81 offset1:89
	ds_read2_b32 v[16:17], v78 offset0:146 offset1:154
	ds_read2_b32 v[18:19], v78 offset0:211 offset1:219
	s_waitcnt lgkmcnt(3)
	s_nop 1
	s_waitcnt lgkmcnt(2)
; #define LAS __attribute__((address_space(3)))
; __device__ __forceinline__ unsigned pk2(float lo, float hi) { return f2bf(lo) | (f2bf(hi) << 16); }
;     ...
; #pragma unroll
;         for (int j = 0; j < 8; ++j) { const int n = (lane >> 3) + 8 * j; const LAS float* sp = scr + (8 * c8) * 65 + n;
;             v4u o; o.x = pk2(sp[0 * 65], sp[1 * 65]); o.y = pk2(sp[2 * 65], sp[3 * 65]); o.z = pk2(sp[4 * 65], sp[5 * 65]); o.w = pk2(sp[6 * 65], sp[7 * 65]);
;             *(v4u*)(WT + (size_t)(d0 + n) * K + k0 + 8 * c8) = o; }
	s_nop 0
	ds_read2_b32 v[20:21], v30 offset0:20 offset1:28
	s_nop 1
	ds_read2_b32 v[22:23], v30 offset0:85 offset1:93
	v_cvt_pk_bf16_f32 v8, v14, v12
	s_waitcnt lgkmcnt(3)
	s_nop 1
	s_waitcnt lgkmcnt(2)
	s_nop 0
	ds_read2_b32 v[24:25], v30 offset0:150 offset1:158
	s_nop 1
	ds_read2_b32 v[26:27], v30 offset0:215 offset1:223
	v_cvt_pk_bf16_f32 v9, v16, v18
	s_waitcnt lgkmcnt(3)
	s_nop 1
	s_waitcnt lgkmcnt(2)
	s_nop 2
	v_cvt_pk_bf16_f32 v10, v20, v22
	s_waitcnt lgkmcnt(1)
	s_nop 0
	v_add_u32_e32 v28, 16, v6
	s_nop 0
	s_waitcnt lgkmcnt(0)
	s_nop 0
	v_ashrrev_i32_e32 v29, 31, v28
	s_nop 1
	v_lshlrev_b64 v[28:29], 10, v[28:29]
	v_cvt_pk_bf16_f32 v11, v24, v26
	v_lshl_add_u64 v[28:29], v[4:5], 0, v[28:29]
	s_nop 0
	global_store_dwordx4 v[28:29], v[8:11], off
	s_nop 3
	v_cvt_pk_bf16_f32 v8, v15, v13
	s_nop 4
	v_cvt_pk_bf16_f32 v9, v17, v19
	s_nop 4
	v_cvt_pk_bf16_f32 v10, v21, v23
	s_nop 0
	v_add_u32_e32 v12, 24, v6
	s_nop 1
	v_ashrrev_i32_e32 v13, 31, v12
	s_nop 1
	v_lshlrev_b64 v[12:13], 10, v[12:13]
	v_cvt_pk_bf16_f32 v11, v25, v27
	ds_read2_b32 v[14:15], v78 offset0:32 offset1:40
	v_lshl_add_u64 v[12:13], v[4:5], 0, v[12:13]
	global_store_dwordx4 v[12:13], v[8:11], off
	ds_read2_b32 v[12:13], v78 offset0:97 offset1:105
	ds_read2_b32 v[16:17], v78 offset0:162 offset1:170
	ds_read2_b32 v[18:19], v78 offset0:227 offset1:235
	s_waitcnt lgkmcnt(3)
	s_nop 1
	s_waitcnt lgkmcnt(2)
	s_nop 0
	ds_read2_b32 v[20:21], v30 offset0:36 offset1:44
	s_nop 1
	ds_read2_b32 v[22:23], v30 offset0:101 offset1:109
	v_cvt_pk_bf16_f32 v8, v14, v12
	s_waitcnt lgkmcnt(3)
	s_nop 1
	s_waitcnt lgkmcnt(2)
	s_nop 0
	ds_read2_b32 v[24:25], v30 offset0:166 offset1:174
	s_nop 1
	ds_read2_b32 v[26:27], v30 offset0:231 offset1:239
	v_cvt_pk_bf16_f32 v9, v16, v18
	s_waitcnt lgkmcnt(3)
	s_nop 1
	s_waitcnt lgkmcnt(2)
	s_nop 2
	v_cvt_pk_bf16_f32 v10, v20, v22
	s_waitcnt lgkmcnt(1)
	s_nop 0
	v_add_u32_e32 v28, 32, v6
	s_nop 0
	s_waitcnt lgkmcnt(0)
	s_nop 0
	v_ashrrev_i32_e32 v29, 31, v28
	s_nop 1
	v_lshlrev_b64 v[28:29], 10, v[28:29]
	v_cvt_pk_bf16_f32 v11, v24, v26
	v_lshl_add_u64 v[28:29], v[4:5], 0, v[28:29]
	s_nop 0
	global_store_dwordx4 v[28:29], v[8:11], off
	s_nop 3
	v_cvt_pk_bf16_f32 v8, v15, v13
	s_nop 4
	v_cvt_pk_bf16_f32 v9, v17, v19
	s_nop 4
	v_cvt_pk_bf16_f32 v10, v21, v23
	s_nop 0
	v_add_u32_e32 v12, 40, v6
	s_nop 1
	v_ashrrev_i32_e32 v13, 31, v12
	s_nop 1
	v_lshlrev_b64 v[12:13], 10, v[12:13]
	v_cvt_pk_bf16_f32 v11, v25, v27
	ds_read2_b32 v[14:15], v78 offset0:48 offset1:56
	v_lshl_add_u64 v[12:13], v[4:5], 0, v[12:13]
	global_store_dwordx4 v[12:13], v[8:11], off
	ds_read2_b32 v[12:13], v78 offset0:113 offset1:121
	ds_read2_b32 v[16:17], v78 offset0:178 offset1:186
	ds_read2_b32 v[18:19], v78 offset0:243 offset1:251
	s_waitcnt lgkmcnt(3)
	s_nop 1
	s_waitcnt lgkmcnt(2)
	s_nop 0
	ds_read2_b32 v[20:21], v30 offset0:52 offset1:60
	s_nop 1
	ds_read2_b32 v[22:23], v30 offset0:117 offset1:125
	v_cvt_pk_bf16_f32 v8, v14, v12
	s_waitcnt lgkmcnt(3)
	s_nop 1
	s_waitcnt lgkmcnt(2)
	s_nop 0
	ds_read2_b32 v[24:25], v30 offset0:182 offset1:190
	s_nop 1
	ds_read2_b32 v[26:27], v30 offset0:247 offset1:255
	v_cvt_pk_bf16_f32 v9, v16, v18
	s_waitcnt lgkmcnt(3)
	s_nop 1
	s_waitcnt lgkmcnt(2)
	s_nop 2
	v_cvt_pk_bf16_f32 v10, v20, v22
	s_waitcnt lgkmcnt(1)
	s_nop 0
	v_add_u32_e32 v28, 48, v6
	s_nop 0
	s_waitcnt lgkmcnt(0)
	s_nop 0
	v_ashrrev_i32_e32 v29, 31, v28
	s_nop 1
	v_lshlrev_b64 v[28:29], 10, v[28:29]
	v_cvt_pk_bf16_f32 v11, v24, v26
	v_lshl_add_u64 v[28:29], v[4:5], 0, v[28:29]
	s_nop 0
	global_store_dwordx4 v[28:29], v[8:11], off
	s_nop 3
	v_cvt_pk_bf16_f32 v8, v15, v13
	s_nop 4
	v_cvt_pk_bf16_f32 v9, v17, v19
	s_nop 4
	v_cvt_pk_bf16_f32 v10, v21, v23
	s_nop 4
	v_add_u32_e32 v6, 56, v6
	v_cvt_pk_bf16_f32 v11, v25, v27
	v_ashrrev_i32_e32 v7, 31, v6
	v_lshlrev_b64 v[6:7], 10, v[6:7]
	v_lshl_add_u64 v[4:5], v[4:5], 0, v[6:7]
	global_store_dwordx4 v[4:5], v[8:11], off
	s_waitcnt lgkmcnt(0)
	s_add_i32 s13, s13, s86
	s_add_i32 s14, s14, s15
	s_cmpk_lt_i32 s13, 0x100
	s_cbranch_scc0 .LBB0_3312

; #define LAS __attribute__((address_space(3)))
; #define LDS_WAIT() asm volatile("s_waitcnt lgkmcnt(0)" ::: "memory")
;     ...
;         const int kb = it / nblk, nb = it % nblk, k0 = 64 * kb, n0 = 64 * nb, nq = (lane & 15) * 4, kr = lane >> 4; const bool ok = (n0 + nq) < N;
;         f32x4 v[16];
; #pragma unroll
;         for (int i = 0; i < 16; ++i) v[i] = ok ? __builtin_nontemporal_load((const f32x4*)(W + (size_t)(k0 + 4 * i + kr) * N + n0 + nq)) : (f32x4){0.f, 0.f, 0.f, 0.f};
;         if (gain) {
; #pragma unroll
;             for (int i = 0; i < 16; ++i) v[i] *= gain[k0 + 4 * i + kr]; }
; #pragma unroll
;         for (int i = 0; i < 16; ++i) { LAS float* d = scr + (4 * i + kr) * 65 + nq; d[0] = v[i].x; d[1] = v[i].y; d[2] = v[i].z; d[3] = v[i].w; }
;         LDS_WAIT(); asm volatile("" ::: "memory");
;         const int c8 = lane & 7; int d0 = n0;
;         if (ffnmap) { const int bj = n0 >= FFH ? 1 : 0, chn = n0 - FFH * bj; d0 = 256 * (chn >> 7) + 128 * bj + (chn & 127); }
.LBB0_3373:
	s_or_b64 exec, exec, s[12:13]
	v_ashrrev_i32_e32 v73, 31, v72
	v_lshl_add_u64 v[114:115], v[72:73], 2, s[6:7]
	global_load_dword v72, v[114:115], off
	s_mulk_i32 s22, 0xff50
	s_add_i32 s11, s21, s22
	s_cmpk_gt_i32 s11, 0x57
	s_cselect_b32 s11, 0xffffea00, 0
	s_cselect_b32 s12, 0x80, 0
	s_add_i32 s11, s11, s16
	s_add_i32 s11, s11, s9
	s_lshl_b32 s9, s11, 1
	s_and_b32 s10, s10, 64
	s_and_b32 s9, s9, 0xffffff00
	s_or_b32 s10, s10, s12
	s_or_b32 s10, s10, s9
	s_ashr_i32 s9, s8, 31
	s_add_i32 s21, s21, s15
	s_add_i32 s16, s16, s17
	s_cmpk_lt_i32 s21, 0x1600
	s_waitcnt vmcnt(0)
	v_pk_mul_f32 v[100:101], v[4:5], v[72:73] op_sel_hi:[1,0]
	global_load_dword v4, v[114:115], off offset:16
	v_pk_mul_f32 v[98:99], v[6:7], v[72:73] op_sel_hi:[1,0]
	global_load_dword v6, v[114:115], off offset:128
	s_waitcnt vmcnt(1)
	v_pk_mul_f32 v[90:91], v[14:15], v[4:5] op_sel_hi:[1,0]
	v_pk_mul_f32 v[96:97], v[12:13], v[4:5] op_sel_hi:[1,0]
	global_load_dword v4, v[114:115], off offset:32
	global_load_dword v14, v[114:115], off offset:160
	s_waitcnt vmcnt(1)
	v_pk_mul_f32 v[86:87], v[10:11], v[4:5] op_sel_hi:[1,0]
	v_pk_mul_f32 v[92:93], v[8:9], v[4:5] op_sel_hi:[1,0]
	global_load_dword v4, v[114:115], off offset:48
	global_load_dword v10, v[114:115], off offset:144
	s_waitcnt vmcnt(2)
	v_pk_mul_f32 v[12:13], v[46:47], v[14:15] op_sel_hi:[1,0]
	v_pk_mul_f32 v[14:15], v[44:45], v[14:15] op_sel_hi:[1,0]
	s_waitcnt vmcnt(1)
	v_pk_mul_f32 v[82:83], v[22:23], v[4:5] op_sel_hi:[1,0]
	v_pk_mul_f32 v[88:89], v[20:21], v[4:5] op_sel_hi:[1,0]
	global_load_dword v4, v[114:115], off offset:64
	global_load_dword v22, v[114:115], off offset:192
	s_waitcnt vmcnt(1)
	v_pk_mul_f32 v[78:79], v[18:19], v[4:5] op_sel_hi:[1,0]
	v_pk_mul_f32 v[84:85], v[16:17], v[4:5] op_sel_hi:[1,0]
	global_load_dword v4, v[114:115], off offset:80
	global_load_dword v18, v[114:115], off offset:176
	s_waitcnt vmcnt(2)
	v_pk_mul_f32 v[20:21], v[54:55], v[22:23] op_sel_hi:[1,0]
	v_pk_mul_f32 v[22:23], v[52:53], v[22:23] op_sel_hi:[1,0]
	s_waitcnt vmcnt(1)
	v_pk_mul_f32 v[74:75], v[30:31], v[4:5] op_sel_hi:[1,0]
	v_pk_mul_f32 v[80:81], v[28:29], v[4:5] op_sel_hi:[1,0]
	global_load_dword v4, v[114:115], off offset:96
	global_load_dword v30, v[114:115], off offset:224
	s_waitcnt vmcnt(2)
	v_pk_mul_f32 v[16:17], v[58:59], v[18:19] op_sel_hi:[1,0]
	v_pk_mul_f32 v[18:19], v[56:57], v[18:19] op_sel_hi:[1,0]
	s_waitcnt vmcnt(1)
	v_pk_mul_f32 v[72:73], v[26:27], v[4:5] op_sel_hi:[1,0]
	v_pk_mul_f32 v[76:77], v[24:25], v[4:5] op_sel_hi:[1,0]
	global_load_dword v4, v[114:115], off offset:112
	global_load_dword v26, v[114:115], off offset:208
	s_waitcnt vmcnt(2)
	v_pk_mul_f32 v[28:29], v[62:63], v[30:31] op_sel_hi:[1,0]
	v_pk_mul_f32 v[30:31], v[60:61], v[30:31] op_sel_hi:[1,0]
	s_waitcnt vmcnt(1)
	v_pk_mul_f32 v[38:39], v[38:39], v[4:5] op_sel_hi:[1,0]
	v_pk_mul_f32 v[36:37], v[36:37], v[4:5] op_sel_hi:[1,0]
	v_pk_mul_f32 v[4:5], v[34:35], v[6:7] op_sel_hi:[1,0]
	v_pk_mul_f32 v[6:7], v[32:33], v[6:7] op_sel_hi:[1,0]
	v_lshl_add_u64 v[32:33], v[94:95], 2, s[6:7]
	global_load_dword v34, v[32:33], off
	ds_write2_b32 v112, v100, v101 offset1:1
	ds_write2_b32 v112, v98, v99 offset0:2 offset1:3
	v_pk_mul_f32 v[8:9], v[50:51], v[10:11] op_sel_hi:[1,0]
	v_pk_mul_f32 v[10:11], v[48:49], v[10:11] op_sel_hi:[1,0]
	s_waitcnt vmcnt(1)
	v_pk_mul_f32 v[24:25], v[66:67], v[26:27] op_sel_hi:[1,0]
	v_pk_mul_f32 v[26:27], v[64:65], v[26:27] op_sel_hi:[1,0]
	s_waitcnt vmcnt(0)
	v_pk_mul_f32 v[32:33], v[42:43], v[34:35] op_sel_hi:[1,0]
	v_pk_mul_f32 v[34:35], v[40:41], v[34:35] op_sel_hi:[1,0]
	v_add_u32_e32 v40, 0x410, v112
	ds_write2_b32 v40, v96, v97 offset1:1
	v_add_u32_e32 v40, 0x418, v112
	ds_write2_b32 v40, v90, v91 offset1:1
	v_add_u32_e32 v40, 0x820, v112
	ds_write2_b32 v40, v92, v93 offset1:1
	v_add_u32_e32 v40, 0x828, v112
	ds_write2_b32 v40, v86, v87 offset1:1
	v_add_u32_e32 v40, 0xc30, v112
	ds_write2_b32 v40, v88, v89 offset1:1
	v_add_u32_e32 v40, 0xc38, v112
	ds_write2_b32 v40, v82, v83 offset1:1
	v_add_u32_e32 v40, 0x1040, v112
	ds_write2_b32 v40, v84, v85 offset1:1
	v_add_u32_e32 v40, 0x1048, v112
	ds_write2_b32 v40, v78, v79 offset1:1
	v_add_u32_e32 v40, 0x1450, v112
	ds_write2_b32 v40, v80, v81 offset1:1
	v_add_u32_e32 v40, 0x1458, v112
	ds_write2_b32 v40, v74, v75 offset1:1
	v_add_u32_e32 v40, 0x1860, v112
	ds_write2_b32 v40, v76, v77 offset1:1
	v_add_u32_e32 v40, 0x1868, v112
	ds_write2_b32 v40, v72, v73 offset1:1
	v_add_u32_e32 v40, 0x1c70, v112
	ds_write2_b32 v40, v36, v37 offset1:1
	v_add_u32_e32 v36, 0x1c78, v112
	ds_write2_b32 v36, v38, v39 offset1:1
	v_add_u32_e32 v36, 0x2080, v112
	ds_write2_b32 v36, v6, v7 offset1:1
	v_add_u32_e32 v6, 0x2088, v112
	ds_write2_b32 v6, v4, v5 offset1:1
	v_add_u32_e32 v4, 0x2490, v112
	ds_write2_b32 v4, v10, v11 offset1:1
	v_add_u32_e32 v4, 0x2498, v112
	ds_write2_b32 v4, v8, v9 offset1:1
	v_add_u32_e32 v4, 0x28a0, v112
	ds_write2_b32 v4, v14, v15 offset1:1
	v_add_u32_e32 v4, 0x28a8, v112
	ds_write2_b32 v4, v12, v13 offset1:1
	v_add_u32_e32 v4, 0x2cb0, v112
	ds_write2_b32 v4, v18, v19 offset1:1
	v_add_u32_e32 v4, 0x2cb8, v112
	ds_write2_b32 v4, v16, v17 offset1:1
	v_add_u32_e32 v4, 0x30c0, v112
	ds_write2_b32 v4, v22, v23 offset1:1
	v_add_u32_e32 v4, 0x30c8, v112
	ds_write2_b32 v4, v20, v21 offset1:1
	v_add_u32_e32 v4, 0x34d0, v112
	ds_write2_b32 v4, v26, v27 offset1:1
	v_add_u32_e32 v4, 0x34d8, v112
	ds_write2_b32 v4, v24, v25 offset1:1
	v_add_u32_e32 v4, 0x38e0, v112
	ds_write2_b32 v4, v30, v31 offset1:1
	v_add_u32_e32 v4, 0x38e8, v112
	ds_write2_b32 v4, v28, v29 offset1:1
	v_add_u32_e32 v4, 0x3cf0, v112
	ds_write2_b32 v4, v34, v35 offset1:1
	v_add_u32_e32 v4, 0x3cf8, v112
	ds_write2_b32 v4, v32, v33 offset1:1
	s_waitcnt lgkmcnt(0)
; #define LAS __attribute__((address_space(3)))
; __device__ __forceinline__ unsigned pk2(float lo, float hi) { return f2bf(lo) | (f2bf(hi) << 16); }
;     ...
; #pragma unroll
;         for (int j = 0; j < 8; ++j) { const int n = (lane >> 3) + 8 * j; const LAS float* sp = scr + (8 * c8) * 65 + n;
;             v4u o; o.x = pk2(sp[0 * 65], sp[1 * 65]); o.y = pk2(sp[2 * 65], sp[3 * 65]); o.z = pk2(sp[4 * 65], sp[5 * 65]); o.w = pk2(sp[6 * 65], sp[7 * 65]);
;             *(v4u*)(WT + (size_t)(d0 + n) * K + k0 + 8 * c8) = o; }
	ds_read2_b32 v[6:7], v104 offset0:65 offset1:73
	ds_read2_b32 v[12:13], v104 offset1:8
	ds_read2_b32 v[14:15], v104 offset0:130 offset1:138
	ds_read2_b32 v[16:17], v104 offset0:195 offset1:203
	v_or_b32_e32 v26, s10, v103
	v_ashrrev_i32_e32 v27, 31, v26
	s_waitcnt lgkmcnt(3)
	s_nop 0
	s_waitcnt lgkmcnt(2)
	s_nop 3
	v_cvt_pk_bf16_f32 v8, v12, v6
	s_waitcnt lgkmcnt(1)
	s_nop 1
	s_waitcnt lgkmcnt(0)
	s_nop 2
	v_cvt_pk_bf16_f32 v9, v14, v16
	v_add_u32_e32 v6, 0x400, v104
	ds_read2_b32 v[18:19], v6 offset0:4 offset1:12
	ds_read2_b32 v[20:21], v6 offset0:69 offset1:77
	ds_read2_b32 v[22:23], v6 offset0:134 offset1:142
	ds_read2_b32 v[24:25], v6 offset0:199 offset1:207
	v_lshl_add_u64 v[4:5], s[8:9], 1, v[70:71]
	v_lshlrev_b64 v[26:27], 12, v[26:27]
	s_waitcnt lgkmcnt(3)
	s_nop 1
	s_waitcnt lgkmcnt(2)
	s_nop 2
	v_cvt_pk_bf16_f32 v10, v18, v20
	s_waitcnt lgkmcnt(1)
	s_nop 1
	s_waitcnt lgkmcnt(0)
	s_nop 2
	v_cvt_pk_bf16_f32 v11, v22, v24
	v_lshl_add_u64 v[26:27], v[4:5], 0, v[26:27]
	global_store_dwordx4 v[26:27], v[8:11], off
	v_or_b32_e32 v12, s10, v105
	v_or_b32_e32 v28, s10, v106
	s_nop 4
	v_cvt_pk_bf16_f32 v8, v13, v7
	s_nop 4
	v_cvt_pk_bf16_f32 v9, v15, v17
	s_nop 4
	v_cvt_pk_bf16_f32 v10, v19, v21
	s_nop 2
	v_ashrrev_i32_e32 v13, 31, v12
	s_nop 1
	v_lshlrev_b64 v[12:13], 12, v[12:13]
	v_cvt_pk_bf16_f32 v11, v23, v25
	v_lshl_add_u64 v[12:13], v[4:5], 0, v[12:13]
	global_store_dwordx4 v[12:13], v[8:11], off
	ds_read2_b32 v[12:13], v104 offset0:81 offset1:89
	ds_read2_b32 v[14:15], v104 offset0:16 offset1:24
	ds_read2_b32 v[16:17], v104 offset0:146 offset1:154
	ds_read2_b32 v[18:19], v104 offset0:211 offset1:219
	ds_read2_b32 v[20:21], v6 offset0:20 offset1:28
	ds_read2_b32 v[22:23], v6 offset0:85 offset1:93
	ds_read2_b32 v[24:25], v6 offset0:150 offset1:158
	ds_read2_b32 v[26:27], v6 offset0:215 offset1:223
	s_waitcnt lgkmcnt(7)
	s_nop 0
	s_waitcnt lgkmcnt(6)
	s_nop 3
	v_cvt_pk_bf16_f32 v8, v14, v12
	s_waitcnt lgkmcnt(5)
	s_nop 1
	s_waitcnt lgkmcnt(4)
	s_nop 2
	v_cvt_pk_bf16_f32 v9, v16, v18
	s_waitcnt lgkmcnt(3)
	s_nop 1
	s_waitcnt lgkmcnt(2)
	s_nop 2
	v_cvt_pk_bf16_f32 v10, v20, v22
	s_waitcnt lgkmcnt(1)
	s_nop 1
	s_waitcnt lgkmcnt(0)
	s_nop 0
	v_ashrrev_i32_e32 v29, 31, v28
	s_nop 1
	v_lshlrev_b64 v[28:29], 12, v[28:29]
	v_cvt_pk_bf16_f32 v11, v24, v26
	v_lshl_add_u64 v[28:29], v[4:5], 0, v[28:29]
	s_nop 0
	global_store_dwordx4 v[28:29], v[8:11], off
	s_nop 3
	v_cvt_pk_bf16_f32 v8, v15, v13
	s_nop 4
	v_cvt_pk_bf16_f32 v9, v17, v19
	s_nop 4
	v_cvt_pk_bf16_f32 v10, v21, v23
	s_nop 0
	v_or_b32_e32 v12, s10, v107
	s_nop 1
	v_ashrrev_i32_e32 v13, 31, v12
	s_nop 1
	v_lshlrev_b64 v[12:13], 12, v[12:13]
	v_cvt_pk_bf16_f32 v11, v25, v27
	v_lshl_add_u64 v[12:13], v[4:5], 0, v[12:13]
	global_store_dwordx4 v[12:13], v[8:11], off
	ds_read2_b32 v[12:13], v104 offset0:97 offset1:105
	ds_read2_b32 v[14:15], v104 offset0:32 offset1:40
	ds_read2_b32 v[16:17], v104 offset0:162 offset1:170
	ds_read2_b32 v[18:19], v104 offset0:227 offset1:235
	ds_read2_b32 v[20:21], v6 offset0:36 offset1:44
	ds_read2_b32 v[22:23], v6 offset0:101 offset1:109
	ds_read2_b32 v[24:25], v6 offset0:166 offset1:174
	ds_read2_b32 v[26:27], v6 offset0:231 offset1:239
	s_waitcnt lgkmcnt(7)
	s_nop 0
	s_waitcnt lgkmcnt(6)
	s_nop 3
	v_cvt_pk_bf16_f32 v8, v14, v12
	s_waitcnt lgkmcnt(5)
	s_nop 1
	s_waitcnt lgkmcnt(4)
	s_nop 2
	v_cvt_pk_bf16_f32 v9, v16, v18
	s_waitcnt lgkmcnt(3)
	s_nop 1
	s_waitcnt lgkmcnt(2)
	s_nop 2
	v_cvt_pk_bf16_f32 v10, v20, v22
	s_waitcnt lgkmcnt(1)
	s_nop 0
	v_or_b32_e32 v28, s10, v108
	s_nop 0
	s_waitcnt lgkmcnt(0)
	s_nop 0
	v_ashrrev_i32_e32 v29, 31, v28
	s_nop 1
	v_lshlrev_b64 v[28:29], 12, v[28:29]
	v_cvt_pk_bf16_f32 v11, v24, v26
	v_lshl_add_u64 v[28:29], v[4:5], 0, v[28:29]
	s_nop 0
	global_store_dwordx4 v[28:29], v[8:11], off
	s_nop 3
	v_cvt_pk_bf16_f32 v8, v15, v13
	s_nop 4
	v_cvt_pk_bf16_f32 v9, v17, v19
	s_nop 4
	v_cvt_pk_bf16_f32 v10, v21, v23
	s_nop 0
	v_or_b32_e32 v12, s10, v109
	s_nop 1
	v_ashrrev_i32_e32 v13, 31, v12
	s_nop 1
	v_lshlrev_b64 v[12:13], 12, v[12:13]
	v_cvt_pk_bf16_f32 v11, v25, v27
	v_lshl_add_u64 v[12:13], v[4:5], 0, v[12:13]
	global_store_dwordx4 v[12:13], v[8:11], off
	ds_read2_b32 v[12:13], v104 offset0:48 offset1:56
	ds_read2_b32 v[14:15], v104 offset0:113 offset1:121
	ds_read2_b32 v[16:17], v104 offset0:178 offset1:186
	ds_read2_b32 v[18:19], v104 offset0:243 offset1:251
	ds_read2_b32 v[20:21], v6 offset0:52 offset1:60
	ds_read2_b32 v[22:23], v6 offset0:117 offset1:125
	ds_read2_b32 v[24:25], v6 offset0:182 offset1:190
	ds_read2_b32 v[26:27], v6 offset0:247 offset1:255
	s_waitcnt lgkmcnt(7)
	s_nop 1
	s_waitcnt lgkmcnt(6)
	s_nop 2
	v_cvt_pk_bf16_f32 v8, v12, v14
	s_waitcnt lgkmcnt(5)
	s_nop 1
	s_waitcnt lgkmcnt(4)
	s_nop 2
	v_cvt_pk_bf16_f32 v9, v16, v18
	s_waitcnt lgkmcnt(3)
	s_nop 1
	s_waitcnt lgkmcnt(2)
	s_nop 2
	s_waitcnt lgkmcnt(1)
	s_nop 0
	v_cvt_pk_bf16_f32 v10, v20, v22
	s_nop 0
	s_waitcnt lgkmcnt(0)
	s_nop 2
	v_cvt_pk_bf16_f32 v11, v24, v26
	v_or_b32_e32 v6, s10, v110
	v_ashrrev_i32_e32 v7, 31, v6
	v_lshlrev_b64 v[6:7], 12, v[6:7]
	v_lshl_add_u64 v[6:7], v[4:5], 0, v[6:7]
	global_store_dwordx4 v[6:7], v[8:11], off
	s_nop 4
	v_cvt_pk_bf16_f32 v6, v13, v15
	s_nop 4
	v_cvt_pk_bf16_f32 v7, v17, v19
	s_nop 4
	v_cvt_pk_bf16_f32 v8, v21, v23
	s_nop 4
	v_cvt_pk_bf16_f32 v9, v25, v27
	v_or_b32_e32 v10, s10, v111
	v_ashrrev_i32_e32 v11, 31, v10
	v_lshlrev_b64 v[10:11], 12, v[10:11]
	v_lshl_add_u64 v[4:5], v[4:5], 0, v[10:11]
	global_store_dwordx4 v[4:5], v[6:9], off
	s_waitcnt lgkmcnt(0)
	s_cbranch_scc0 .LBB0_3406

; #define LAS __attribute__((address_space(3)))
; #define LDS_WAIT() asm volatile("s_waitcnt lgkmcnt(0)" ::: "memory")
; __device__ __forceinline__ unsigned pk2(float lo, float hi) { return f2bf(lo) | (f2bf(hi) << 16); }
;     ...
;         for (int i = 0; i < 16; ++i) { LAS float* d = scr + (4 * i + kr) * 65 + nq; d[0] = v[i].x; d[1] = v[i].y; d[2] = v[i].z; d[3] = v[i].w; }
;         LDS_WAIT(); asm volatile("" ::: "memory");
;         const int c8 = lane & 7; int d0 = n0;
;         if (ffnmap) { const int bj = n0 >= FFH ? 1 : 0, chn = n0 - FFH * bj; d0 = 256 * (chn >> 7) + 128 * bj + (chn & 127); }
; #pragma unroll
;         for (int j = 0; j < 8; ++j) { const int n = (lane >> 3) + 8 * j; const LAS float* sp = scr + (8 * c8) * 65 + n;
;             v4u o; o.x = pk2(sp[0 * 65], sp[1 * 65]); o.y = pk2(sp[2 * 65], sp[3 * 65]); o.z = pk2(sp[4 * 65], sp[5 * 65]); o.w = pk2(sp[6 * 65], sp[7 * 65]);
;             *(v4u*)(WT + (size_t)(d0 + n) * K + k0 + 8 * c8) = o; }
.LBB0_3408:
	s_or_b64 exec, exec, s[8:9]
	s_waitcnt vmcnt(0)
	ds_write2_b32 v79, v4, v5 offset1:1
	ds_write2_b32 v79, v6, v7 offset0:2 offset1:3
	v_add_u32_e32 v4, 0x410, v79
	ds_write2_b32 v4, v12, v13 offset1:1
	v_add_u32_e32 v4, 0x418, v79
	ds_write2_b32 v4, v14, v15 offset1:1
	v_add_u32_e32 v4, 0x820, v79
	ds_write2_b32 v4, v8, v9 offset1:1
	v_add_u32_e32 v4, 0x828, v79
	ds_write2_b32 v4, v10, v11 offset1:1
	v_add_u32_e32 v4, 0xc30, v79
	ds_write2_b32 v4, v20, v21 offset1:1
	v_add_u32_e32 v4, 0xc38, v79
	ds_write2_b32 v4, v22, v23 offset1:1
	v_add_u32_e32 v4, 0x1040, v79
	ds_write2_b32 v4, v16, v17 offset1:1
	v_add_u32_e32 v4, 0x1048, v79
	ds_write2_b32 v4, v18, v19 offset1:1
	v_add_u32_e32 v4, 0x1450, v79
	ds_write2_b32 v4, v28, v29 offset1:1
	v_add_u32_e32 v4, 0x1458, v79
	ds_write2_b32 v4, v30, v31 offset1:1
	v_add_u32_e32 v4, 0x1860, v79
	ds_write2_b32 v4, v24, v25 offset1:1
	v_add_u32_e32 v4, 0x1868, v79
	ds_write2_b32 v4, v26, v27 offset1:1
	v_add_u32_e32 v4, 0x1c70, v79
	ds_write2_b32 v4, v36, v37 offset1:1
	v_add_u32_e32 v4, 0x1c78, v79
	ds_write2_b32 v4, v38, v39 offset1:1
	v_add_u32_e32 v4, 0x2080, v79
	ds_write2_b32 v4, v32, v33 offset1:1
	v_add_u32_e32 v4, 0x2088, v79
	ds_write2_b32 v4, v34, v35 offset1:1
	v_add_u32_e32 v4, 0x2490, v79
	ds_write2_b32 v4, v44, v45 offset1:1
	v_add_u32_e32 v4, 0x2498, v79
	ds_write2_b32 v4, v46, v47 offset1:1
	v_add_u32_e32 v4, 0x28a0, v79
	ds_write2_b32 v4, v40, v41 offset1:1
	v_add_u32_e32 v4, 0x28a8, v79
	ds_write2_b32 v4, v42, v43 offset1:1
	v_add_u32_e32 v4, 0x2cb0, v79
	ds_write2_b32 v4, v52, v53 offset1:1
	v_add_u32_e32 v4, 0x2cb8, v79
	ds_write2_b32 v4, v54, v55 offset1:1
	v_add_u32_e32 v4, 0x30c0, v79
	ds_write2_b32 v4, v48, v49 offset1:1
	v_add_u32_e32 v4, 0x30c8, v79
	ds_write2_b32 v4, v50, v51 offset1:1
	v_add_u32_e32 v4, 0x34d0, v79
	ds_write2_b32 v4, v60, v61 offset1:1
	v_add_u32_e32 v4, 0x34d8, v79
	ds_write2_b32 v4, v62, v63 offset1:1
	v_add_u32_e32 v4, 0x38e0, v79
	ds_write2_b32 v4, v56, v57 offset1:1
	v_add_u32_e32 v4, 0x38e8, v79
	ds_write2_b32 v4, v58, v59 offset1:1
	v_add_u32_e32 v4, 0x3cf0, v79
	ds_write2_b32 v4, v64, v65 offset1:1
	v_add_u32_e32 v4, 0x3cf8, v79
	ds_write2_b32 v4, v66, v67 offset1:1
	s_waitcnt lgkmcnt(0)
	ds_read2_b32 v[12:13], v77 offset1:8
	ds_read2_b32 v[14:15], v77 offset0:65 offset1:73
	ds_read2_b32 v[16:17], v77 offset0:130 offset1:138
	ds_read2_b32 v[18:19], v77 offset0:195 offset1:203
	v_add_u32_e32 v30, 0x400, v77
	s_waitcnt lgkmcnt(3)
	s_nop 1
	s_waitcnt lgkmcnt(2)
	s_nop 0
	ds_read2_b32 v[20:21], v30 offset0:4 offset1:12
	s_nop 1
	ds_read2_b32 v[22:23], v30 offset0:69 offset1:77
	v_cvt_pk_bf16_f32 v8, v12, v14
	s_waitcnt lgkmcnt(3)
	s_nop 1
	s_waitcnt lgkmcnt(2)
	s_nop 0
	ds_read2_b32 v[24:25], v30 offset0:134 offset1:142
	s_nop 1
	ds_read2_b32 v[26:27], v30 offset0:199 offset1:207
	v_cvt_pk_bf16_f32 v9, v16, v18
	s_waitcnt lgkmcnt(3)
	s_nop 1
	s_waitcnt lgkmcnt(2)
	s_nop 2
	v_cvt_pk_bf16_f32 v10, v20, v22
	s_waitcnt lgkmcnt(1)
	s_nop 1
	s_waitcnt lgkmcnt(0)
	s_nop 2
	s_mul_i32 s16, s16, 0xfea00000
	s_ashr_i32 s7, s6, 31
	v_cvt_pk_bf16_f32 v11, v24, v26
	v_add_u32_e32 v6, s16, v78
	v_lshl_add_u64 v[4:5], s[6:7], 1, v[70:71]
	v_ashrrev_i32_e32 v7, 31, v6
	v_lshl_add_u64 v[28:29], v[4:5], 0, v[6:7]
	s_nop 0
	global_store_dwordx4 v[28:29], v[8:11], off
	s_nop 3
	v_cvt_pk_bf16_f32 v8, v13, v15
	s_nop 4
	v_cvt_pk_bf16_f32 v9, v17, v19
	s_nop 4
	v_cvt_pk_bf16_f32 v10, v21, v23
	s_nop 2
	v_add_u32_e32 v12, 0x16000, v6
	s_nop 1
	v_ashrrev_i32_e32 v13, 31, v12
	v_cvt_pk_bf16_f32 v11, v25, v27
	ds_read2_b32 v[14:15], v77 offset0:16 offset1:24
	v_lshl_add_u64 v[12:13], v[4:5], 0, v[12:13]
	global_store_dwordx4 v[12:13], v[8:11], off
	ds_read2_b32 v[12:13], v77 offset0:81 offset1:89
	ds_read2_b32 v[16:17], v77 offset0:146 offset1:154
	ds_read2_b32 v[18:19], v77 offset0:211 offset1:219
	s_waitcnt lgkmcnt(3)
; #define LAS __attribute__((address_space(3)))
; #define LDS_WAIT() asm volatile("s_waitcnt lgkmcnt(0)" ::: "memory")
; __device__ __forceinline__ unsigned pk2(float lo, float hi) { return f2bf(lo) | (f2bf(hi) << 16); }
;     ...
;         for (int j = 0; j < 8; ++j) { const int n = (lane >> 3) + 8 * j; const LAS float* sp = scr + (8 * c8) * 65 + n;
;             v4u o; o.x = pk2(sp[0 * 65], sp[1 * 65]); o.y = pk2(sp[2 * 65], sp[3 * 65]); o.z = pk2(sp[4 * 65], sp[5 * 65]); o.w = pk2(sp[6 * 65], sp[7 * 65]);
;             *(v4u*)(WT + (size_t)(d0 + n) * K + k0 + 8 * c8) = o; }
;         LDS_WAIT(); asm volatile("" ::: "memory");
	s_nop 1
	s_waitcnt lgkmcnt(2)
	s_nop 0
	ds_read2_b32 v[20:21], v30 offset0:20 offset1:28
	s_nop 1
	ds_read2_b32 v[22:23], v30 offset0:85 offset1:93
	v_cvt_pk_bf16_f32 v8, v14, v12
	s_waitcnt lgkmcnt(3)
	s_nop 1
	s_waitcnt lgkmcnt(2)
	s_nop 0
	ds_read2_b32 v[24:25], v30 offset0:150 offset1:158
	s_nop 1
	ds_read2_b32 v[26:27], v30 offset0:215 offset1:223
	v_cvt_pk_bf16_f32 v9, v16, v18
	s_waitcnt lgkmcnt(3)
	s_nop 1
	s_waitcnt lgkmcnt(2)
	s_nop 2
	v_cvt_pk_bf16_f32 v10, v20, v22
	s_waitcnt lgkmcnt(1)
	s_nop 1
	s_waitcnt lgkmcnt(0)
	s_nop 0
	v_add_u32_e32 v28, 0x2c000, v6
	s_nop 1
	v_ashrrev_i32_e32 v29, 31, v28
	v_cvt_pk_bf16_f32 v11, v24, v26
	v_lshl_add_u64 v[28:29], v[4:5], 0, v[28:29]
	s_nop 0
	global_store_dwordx4 v[28:29], v[8:11], off
	s_nop 3
	v_cvt_pk_bf16_f32 v8, v15, v13
	s_nop 4
	v_cvt_pk_bf16_f32 v9, v17, v19
	s_nop 4
	v_cvt_pk_bf16_f32 v10, v21, v23
	s_nop 2
	v_add_u32_e32 v12, 0x42000, v6
	s_nop 1
	v_ashrrev_i32_e32 v13, 31, v12
	v_cvt_pk_bf16_f32 v11, v25, v27
	ds_read2_b32 v[14:15], v77 offset0:32 offset1:40
	v_lshl_add_u64 v[12:13], v[4:5], 0, v[12:13]
	global_store_dwordx4 v[12:13], v[8:11], off
	ds_read2_b32 v[12:13], v77 offset0:97 offset1:105
	ds_read2_b32 v[16:17], v77 offset0:162 offset1:170
	ds_read2_b32 v[18:19], v77 offset0:227 offset1:235
	s_waitcnt lgkmcnt(3)
	s_nop 1
	s_waitcnt lgkmcnt(2)
	s_nop 0
	ds_read2_b32 v[20:21], v30 offset0:36 offset1:44
	s_nop 1
	ds_read2_b32 v[22:23], v30 offset0:101 offset1:109
	v_cvt_pk_bf16_f32 v8, v14, v12
	s_waitcnt lgkmcnt(3)
	s_nop 1
	s_waitcnt lgkmcnt(2)
	s_nop 0
	ds_read2_b32 v[24:25], v30 offset0:166 offset1:174
	s_nop 1
	ds_read2_b32 v[26:27], v30 offset0:231 offset1:239
	v_cvt_pk_bf16_f32 v9, v16, v18
	s_waitcnt lgkmcnt(3)
	s_nop 1
	s_waitcnt lgkmcnt(2)
	s_nop 2
	v_cvt_pk_bf16_f32 v10, v20, v22
	s_waitcnt lgkmcnt(1)
	s_nop 1
	s_waitcnt lgkmcnt(0)
	s_nop 0
	v_add_u32_e32 v28, 0x58000, v6
	s_nop 1
	v_ashrrev_i32_e32 v29, 31, v28
	v_cvt_pk_bf16_f32 v11, v24, v26
	v_lshl_add_u64 v[28:29], v[4:5], 0, v[28:29]
	s_nop 0
	global_store_dwordx4 v[28:29], v[8:11], off
	s_nop 3
	v_cvt_pk_bf16_f32 v8, v15, v13
	s_nop 4
	v_cvt_pk_bf16_f32 v9, v17, v19
	s_nop 4
	v_cvt_pk_bf16_f32 v10, v21, v23
	s_nop 2
	v_add_u32_e32 v12, 0x6e000, v6
	s_nop 1
	v_ashrrev_i32_e32 v13, 31, v12
	v_cvt_pk_bf16_f32 v11, v25, v27
	ds_read2_b32 v[14:15], v77 offset0:48 offset1:56
	v_lshl_add_u64 v[12:13], v[4:5], 0, v[12:13]
	global_store_dwordx4 v[12:13], v[8:11], off
	ds_read2_b32 v[12:13], v77 offset0:113 offset1:121
	ds_read2_b32 v[16:17], v77 offset0:178 offset1:186
	ds_read2_b32 v[18:19], v77 offset0:243 offset1:251
	s_waitcnt lgkmcnt(3)
	s_nop 1
	s_waitcnt lgkmcnt(2)
	s_nop 0
	ds_read2_b32 v[20:21], v30 offset0:52 offset1:60
	s_nop 1
	ds_read2_b32 v[22:23], v30 offset0:117 offset1:125
	v_cvt_pk_bf16_f32 v8, v14, v12
	s_waitcnt lgkmcnt(3)
	s_nop 1
	s_waitcnt lgkmcnt(2)
	s_nop 0
	ds_read2_b32 v[24:25], v30 offset0:182 offset1:190
	s_nop 1
	ds_read2_b32 v[26:27], v30 offset0:247 offset1:255
	v_cvt_pk_bf16_f32 v9, v16, v18
	s_waitcnt lgkmcnt(3)
	s_nop 1
	s_waitcnt lgkmcnt(2)
	s_nop 2
	v_cvt_pk_bf16_f32 v10, v20, v22
	s_waitcnt lgkmcnt(1)
	s_nop 1
	s_waitcnt lgkmcnt(0)
	s_nop 0
	v_add_u32_e32 v28, 0x84000, v6
	s_nop 1
	v_ashrrev_i32_e32 v29, 31, v28
	v_cvt_pk_bf16_f32 v11, v24, v26
	v_lshl_add_u64 v[28:29], v[4:5], 0, v[28:29]
	s_nop 0
	global_store_dwordx4 v[28:29], v[8:11], off
	s_nop 3
	v_cvt_pk_bf16_f32 v8, v15, v13
	s_nop 4
	v_cvt_pk_bf16_f32 v9, v17, v19
	s_nop 4
	v_cvt_pk_bf16_f32 v10, v21, v23
	s_nop 4
	v_add_u32_e32 v6, 0x9a000, v6
	v_cvt_pk_bf16_f32 v11, v25, v27
	v_ashrrev_i32_e32 v7, 31, v6
	v_lshl_add_u64 v[4:5], v[4:5], 0, v[6:7]
	global_store_dwordx4 v[4:5], v[8:11], off
	s_waitcnt lgkmcnt(0)
	s_add_i32 s14, s14, s15
	s_add_i32 s10, s10, s11
	s_mul_i32 s6, s15, 0xb0000
	s_cmpk_lt_i32 s14, 0xb00
	v_add_u32_e32 v78, s6, v78
	s_cbranch_scc0 .LBB0_3441

; __device__ __forceinline__ void sgu_ln(const Ctx& c, bf16* P, const float* g) {
;     for (int row = c.gw; row < MT; row += c.NGW) {
;         v4u* vr = (v4u*)(P + (size_t)row * 8192 + 4096) + c.lane;
;         float v[8][8]; float s = 0.f;
; #pragma unroll
;         for (int j = 0; j < 8; ++j) { const v4u y = vr[64 * j];
; #pragma unroll
;             for (int k = 0; k < 4; ++k) { v[j][2 * k] = bflo(y[k]); v[j][2 * k + 1] = bfhi(y[k]); s += v[j][2 * k] + v[j][2 * k + 1]; } }
;         const float mu = wave_sum(s) * (1.f / 4096.f); float q = 0.f;
.LBB0_3519:
	global_load_dwordx4 v[72:75], v[66:67], off
	global_load_dwordx4 v[76:79], v[66:67], off offset:1024
	global_load_dwordx4 v[80:83], v[66:67], off offset:2048
	global_load_dwordx4 v[84:87], v[66:67], off offset:3072
	v_add_co_u32_e32 v70, vcc, s8, v66
	s_add_i32 s11, s11, s86
	s_nop 0
	v_addc_co_u32_e32 v71, vcc, 0, v67, vcc
	global_load_dwordx4 v[88:91], v[70:71], off offset:3072
	global_load_dwordx4 v[92:95], v[70:71], off
	global_load_dwordx4 v[96:99], v[70:71], off offset:1024
	global_load_dwordx4 v[100:103], v[70:71], off offset:2048
	s_cmpk_lt_i32 s11, 0x4000
	s_waitcnt vmcnt(7)
	v_lshlrev_b32_e32 v113, 16, v73
	v_lshlrev_b32_e32 v112, 16, v72
	v_and_b32_e32 v73, 0xffff0000, v73
	v_and_b32_e32 v72, 0xffff0000, v72
	v_pk_add_f32 v[128:129], v[112:113], v[72:73]
	v_lshlrev_b32_e32 v115, 16, v75
	v_lshlrev_b32_e32 v114, 16, v74
	v_and_b32_e32 v75, 0xffff0000, v75
	v_and_b32_e32 v74, 0xffff0000, v74
	v_add_f32_e32 v104, 0, v128
	v_pk_add_f32 v[130:131], v[114:115], v[74:75]
	v_add_f32_e32 v104, v129, v104
	s_waitcnt vmcnt(6)
	v_lshlrev_b32_e32 v117, 16, v77
	v_lshlrev_b32_e32 v116, 16, v76
	v_and_b32_e32 v77, 0xffff0000, v77
	v_and_b32_e32 v76, 0xffff0000, v76
	v_add_f32_e32 v104, v130, v104
	v_pk_add_f32 v[132:133], v[116:117], v[76:77]
	v_add_f32_e32 v104, v131, v104
	v_lshlrev_b32_e32 v119, 16, v79
	v_lshlrev_b32_e32 v118, 16, v78
	v_and_b32_e32 v79, 0xffff0000, v79
	v_and_b32_e32 v78, 0xffff0000, v78
	v_add_f32_e32 v104, v132, v104
	v_pk_add_f32 v[134:135], v[118:119], v[78:79]
	v_add_f32_e32 v104, v133, v104
	s_waitcnt vmcnt(5)
	v_lshlrev_b32_e32 v121, 16, v81
	v_lshlrev_b32_e32 v120, 16, v80
	v_and_b32_e32 v81, 0xffff0000, v81
	v_and_b32_e32 v80, 0xffff0000, v80
	v_add_f32_e32 v104, v134, v104
	v_pk_add_f32 v[136:137], v[120:121], v[80:81]
	v_add_f32_e32 v104, v135, v104
	v_lshlrev_b32_e32 v123, 16, v83
	v_lshlrev_b32_e32 v122, 16, v82
	v_and_b32_e32 v83, 0xffff0000, v83
	v_and_b32_e32 v82, 0xffff0000, v82
	v_add_f32_e32 v104, v136, v104
	v_pk_add_f32 v[138:139], v[122:123], v[82:83]
	v_add_f32_e32 v104, v137, v104
	s_waitcnt vmcnt(4)
	v_lshlrev_b32_e32 v125, 16, v85
	v_lshlrev_b32_e32 v124, 16, v84
	v_and_b32_e32 v85, 0xffff0000, v85
	v_and_b32_e32 v84, 0xffff0000, v84
	v_add_f32_e32 v104, v138, v104
	v_pk_add_f32 v[140:141], v[124:125], v[84:85]
	v_add_f32_e32 v104, v139, v104
	v_lshlrev_b32_e32 v127, 16, v87
	v_lshlrev_b32_e32 v126, 16, v86
	v_and_b32_e32 v87, 0xffff0000, v87
	v_and_b32_e32 v86, 0xffff0000, v86
	v_add_f32_e32 v104, v140, v104
	v_pk_add_f32 v[142:143], v[126:127], v[86:87]
	v_add_f32_e32 v104, v141, v104
	s_waitcnt vmcnt(3)
	v_lshlrev_b32_e32 v145, 16, v89
	v_lshlrev_b32_e32 v144, 16, v88
	v_and_b32_e32 v147, 0xffff0000, v89
	v_and_b32_e32 v146, 0xffff0000, v88
	v_lshlrev_b32_e32 v149, 16, v91
	v_lshlrev_b32_e32 v148, 16, v90
	v_and_b32_e32 v151, 0xffff0000, v91
	v_and_b32_e32 v150, 0xffff0000, v90
	s_waitcnt vmcnt(2)
	v_lshlrev_b32_e32 v89, 16, v93
	v_lshlrev_b32_e32 v88, 16, v92
	v_and_b32_e32 v91, 0xffff0000, v93
	v_and_b32_e32 v90, 0xffff0000, v92
	v_add_f32_e32 v104, v142, v104
	v_pk_add_f32 v[128:129], v[88:89], v[90:91]
	v_add_f32_e32 v104, v143, v104
	v_lshlrev_b32_e32 v93, 16, v95
	v_lshlrev_b32_e32 v92, 16, v94
	v_and_b32_e32 v95, 0xffff0000, v95
	v_and_b32_e32 v94, 0xffff0000, v94
	v_add_f32_e32 v104, v128, v104
	v_pk_add_f32 v[160:161], v[92:93], v[94:95]
	v_add_f32_e32 v104, v129, v104
	s_waitcnt vmcnt(1)
	v_lshlrev_b32_e32 v153, 16, v97
	v_lshlrev_b32_e32 v152, 16, v96
	v_and_b32_e32 v155, 0xffff0000, v97
	v_and_b32_e32 v154, 0xffff0000, v96
	v_add_f32_e32 v104, v160, v104
	v_pk_add_f32 v[162:163], v[152:153], v[154:155]
	v_add_f32_e32 v104, v161, v104
	v_lshlrev_b32_e32 v157, 16, v99
	v_lshlrev_b32_e32 v156, 16, v98
	v_and_b32_e32 v159, 0xffff0000, v99
	v_and_b32_e32 v158, 0xffff0000, v98
	v_add_f32_e32 v104, v162, v104
	v_add_f32_e32 v104, v163, v104
	v_pk_add_f32 v[128:129], v[156:157], v[158:159]
	s_waitcnt vmcnt(0)
	v_and_b32_e32 v131, 0xffff0000, v101
	v_add_f32_e32 v104, v128, v104
	v_add_f32_e32 v104, v129, v104
	v_lshlrev_b32_e32 v129, 16, v101
	v_lshlrev_b32_e32 v128, 16, v100
	v_and_b32_e32 v130, 0xffff0000, v100
	v_pk_add_f32 v[100:101], v[128:129], v[130:131]
	v_lshlrev_b32_e32 v133, 16, v103
	v_add_f32_e32 v100, v100, v104
	v_lshlrev_b32_e32 v132, 16, v102
	v_and_b32_e32 v135, 0xffff0000, v103
	v_and_b32_e32 v134, 0xffff0000, v102
	v_add_f32_e32 v104, v101, v100
	v_pk_add_f32 v[100:101], v[132:133], v[134:135]
	v_pk_add_f32 v[96:97], v[144:145], v[146:147]
	v_add_f32_e32 v100, v100, v104
	v_add_f32_e32 v100, v101, v100
	v_add_f32_e32 v96, v96, v100
	v_pk_add_f32 v[98:99], v[148:149], v[150:151]
	v_add_f32_e32 v96, v97, v96
	v_add_f32_e32 v96, v98, v96
	v_add_f32_e32 v96, v99, v96
	ds_bpermute_b32 v97, v3, v96
	s_waitcnt lgkmcnt(0)
	v_add_f32_e32 v96, v96, v97
	ds_bpermute_b32 v97, v105, v96
	s_waitcnt lgkmcnt(0)
	v_add_f32_e32 v96, v96, v97
	ds_bpermute_b32 v97, v106, v96
	s_waitcnt lgkmcnt(0)
	v_add_f32_e32 v96, v96, v97
	ds_bpermute_b32 v97, v107, v96
	s_waitcnt lgkmcnt(0)
	v_add_f32_e32 v96, v96, v97
	ds_bpermute_b32 v97, v108, v96
	s_waitcnt lgkmcnt(0)
	v_add_f32_e32 v96, v96, v97
	ds_bpermute_b32 v97, v109, v96
	s_waitcnt lgkmcnt(0)
; __device__ __forceinline__ void sgu_ln(const Ctx& c, bf16* P, const float* g) {
;     ...
;         const float mu = wave_sum(s) * (1.f / 4096.f); float q = 0.f;
; #pragma unroll
;         for (int j = 0; j < 8; ++j)
; #pragma unroll
;             for (int k = 0; k < 8; ++k) { v[j][k] -= mu; q += v[j][k] * v[j][k]; }
;         const float rs = rsqrtf(wave_sum(q) * (1.f / 4096.f) + EPS);
	v_add_f32_e32 v96, v96, v97
	v_mul_f32_e32 v104, 0x39800000, v96
	v_pk_add_f32 v[112:113], v[112:113], v[104:105] op_sel_hi:[1,0] neg_lo:[0,1] neg_hi:[0,1]
	v_pk_add_f32 v[136:137], v[72:73], v[104:105] op_sel_hi:[1,0] neg_lo:[0,1] neg_hi:[0,1]
	v_pk_mul_f32 v[160:161], v[112:113], v[112:113]
	v_pk_mul_f32 v[162:163], v[136:137], v[136:137]
	v_pk_add_f32 v[114:115], v[114:115], v[104:105] op_sel_hi:[1,0] neg_lo:[0,1] neg_hi:[0,1]
	v_pk_add_f32 v[138:139], v[74:75], v[104:105] op_sel_hi:[1,0] neg_lo:[0,1] neg_hi:[0,1]
	v_pk_add_f32 v[116:117], v[116:117], v[104:105] op_sel_hi:[1,0] neg_lo:[0,1] neg_hi:[0,1]
	v_pk_add_f32 v[140:141], v[76:77], v[104:105] op_sel_hi:[1,0] neg_lo:[0,1] neg_hi:[0,1]
	v_pk_add_f32 v[118:119], v[118:119], v[104:105] op_sel_hi:[1,0] neg_lo:[0,1] neg_hi:[0,1]
	v_pk_add_f32 v[142:143], v[78:79], v[104:105] op_sel_hi:[1,0] neg_lo:[0,1] neg_hi:[0,1]
	v_pk_add_f32 v[120:121], v[120:121], v[104:105] op_sel_hi:[1,0] neg_lo:[0,1] neg_hi:[0,1]
	v_pk_add_f32 v[180:181], v[80:81], v[104:105] op_sel_hi:[1,0] neg_lo:[0,1] neg_hi:[0,1]
	v_pk_add_f32 v[122:123], v[122:123], v[104:105] op_sel_hi:[1,0] neg_lo:[0,1] neg_hi:[0,1]
	v_pk_add_f32 v[186:187], v[82:83], v[104:105] op_sel_hi:[1,0] neg_lo:[0,1] neg_hi:[0,1]
	v_pk_add_f32 v[124:125], v[124:125], v[104:105] op_sel_hi:[1,0] neg_lo:[0,1] neg_hi:[0,1]
	v_pk_add_f32 v[192:193], v[84:85], v[104:105] op_sel_hi:[1,0] neg_lo:[0,1] neg_hi:[0,1]
	v_pk_add_f32 v[126:127], v[126:127], v[104:105] op_sel_hi:[1,0] neg_lo:[0,1] neg_hi:[0,1]
	v_pk_add_f32 v[198:199], v[86:87], v[104:105] op_sel_hi:[1,0] neg_lo:[0,1] neg_hi:[0,1]
	v_pk_add_f32 v[96:97], v[88:89], v[104:105] op_sel_hi:[1,0] neg_lo:[0,1] neg_hi:[0,1]
	v_pk_add_f32 v[98:99], v[90:91], v[104:105] op_sel_hi:[1,0] neg_lo:[0,1] neg_hi:[0,1]
	v_pk_add_f32 v[100:101], v[92:93], v[104:105] op_sel_hi:[1,0] neg_lo:[0,1] neg_hi:[0,1]
	v_pk_add_f32 v[102:103], v[94:95], v[104:105] op_sel_hi:[1,0] neg_lo:[0,1] neg_hi:[0,1]
	v_pk_add_f32 v[88:89], v[152:153], v[104:105] op_sel_hi:[1,0] neg_lo:[0,1] neg_hi:[0,1]
	v_pk_add_f32 v[90:91], v[154:155], v[104:105] op_sel_hi:[1,0] neg_lo:[0,1] neg_hi:[0,1]
	v_pk_add_f32 v[92:93], v[156:157], v[104:105] op_sel_hi:[1,0] neg_lo:[0,1] neg_hi:[0,1]
	v_pk_add_f32 v[94:95], v[158:159], v[104:105] op_sel_hi:[1,0] neg_lo:[0,1] neg_hi:[0,1]
	v_pk_add_f32 v[80:81], v[128:129], v[104:105] op_sel_hi:[1,0] neg_lo:[0,1] neg_hi:[0,1]
	v_pk_add_f32 v[82:83], v[130:131], v[104:105] op_sel_hi:[1,0] neg_lo:[0,1] neg_hi:[0,1]
	v_pk_add_f32 v[84:85], v[132:133], v[104:105] op_sel_hi:[1,0] neg_lo:[0,1] neg_hi:[0,1]
	v_pk_add_f32 v[86:87], v[134:135], v[104:105] op_sel_hi:[1,0] neg_lo:[0,1] neg_hi:[0,1]
	v_pk_add_f32 v[74:75], v[144:145], v[104:105] op_sel_hi:[1,0] neg_lo:[0,1] neg_hi:[0,1]
	v_pk_add_f32 v[76:77], v[146:147], v[104:105] op_sel_hi:[1,0] neg_lo:[0,1] neg_hi:[0,1]
	v_pk_add_f32 v[78:79], v[148:149], v[104:105] op_sel_hi:[1,0] neg_lo:[0,1] neg_hi:[0,1]
	v_pk_add_f32 v[72:73], v[150:151], v[104:105] op_sel_hi:[1,0] neg_lo:[0,1] neg_hi:[0,1]
	v_add_f32_e32 v104, v160, v162
	v_add_f32_e32 v104, v161, v104
	v_pk_mul_f32 v[166:167], v[114:115], v[114:115]
	v_add_f32_e32 v104, v163, v104
	v_pk_mul_f32 v[168:169], v[138:139], v[138:139]
	v_add_f32_e32 v104, v166, v104
	v_add_f32_e32 v104, v168, v104
	v_add_f32_e32 v104, v167, v104
	v_pk_mul_f32 v[170:171], v[116:117], v[116:117]
	v_add_f32_e32 v104, v169, v104
	v_pk_mul_f32 v[172:173], v[140:141], v[140:141]
	v_add_f32_e32 v104, v170, v104
	v_add_f32_e32 v104, v172, v104
	v_add_f32_e32 v104, v171, v104
	v_pk_mul_f32 v[174:175], v[118:119], v[118:119]
	v_add_f32_e32 v104, v173, v104
	v_pk_mul_f32 v[176:177], v[142:143], v[142:143]
	v_add_f32_e32 v104, v174, v104
	v_add_f32_e32 v104, v176, v104
	v_add_f32_e32 v104, v175, v104
	v_pk_mul_f32 v[178:179], v[120:121], v[120:121]
	v_add_f32_e32 v104, v177, v104
	v_pk_mul_f32 v[182:183], v[180:181], v[180:181]
	v_add_f32_e32 v104, v178, v104
	v_add_f32_e32 v104, v182, v104
	v_add_f32_e32 v104, v179, v104
	v_pk_mul_f32 v[184:185], v[122:123], v[122:123]
	v_add_f32_e32 v104, v183, v104
	v_pk_mul_f32 v[188:189], v[186:187], v[186:187]
	v_add_f32_e32 v104, v184, v104
	v_add_f32_e32 v104, v188, v104
	v_add_f32_e32 v104, v185, v104
	v_pk_mul_f32 v[190:191], v[124:125], v[124:125]
	v_add_f32_e32 v104, v189, v104
	v_pk_mul_f32 v[194:195], v[192:193], v[192:193]
	v_add_f32_e32 v104, v190, v104
	v_add_f32_e32 v104, v194, v104
	v_add_f32_e32 v104, v191, v104
	v_pk_mul_f32 v[196:197], v[126:127], v[126:127]
	v_add_f32_e32 v104, v195, v104
	v_pk_mul_f32 v[200:201], v[198:199], v[198:199]
	v_add_f32_e32 v104, v196, v104
	v_add_f32_e32 v104, v200, v104
	v_add_f32_e32 v104, v197, v104
	v_pk_mul_f32 v[202:203], v[96:97], v[96:97]
	v_add_f32_e32 v104, v201, v104
	v_pk_mul_f32 v[204:205], v[98:99], v[98:99]
	v_add_f32_e32 v104, v202, v104
	v_add_f32_e32 v104, v204, v104
	v_add_f32_e32 v104, v203, v104
	v_pk_mul_f32 v[206:207], v[100:101], v[100:101]
	v_add_f32_e32 v104, v205, v104
	v_pk_mul_f32 v[208:209], v[102:103], v[102:103]
	v_add_f32_e32 v104, v206, v104
	v_add_f32_e32 v104, v208, v104
	v_add_f32_e32 v104, v207, v104
	v_pk_mul_f32 v[152:153], v[88:89], v[88:89]
	v_add_f32_e32 v104, v209, v104
	v_pk_mul_f32 v[154:155], v[90:91], v[90:91]
	v_add_f32_e32 v104, v152, v104
	v_add_f32_e32 v104, v154, v104
	v_add_f32_e32 v104, v153, v104
	v_pk_mul_f32 v[156:157], v[92:93], v[92:93]
	v_add_f32_e32 v104, v155, v104
	v_pk_mul_f32 v[158:159], v[94:95], v[94:95]
	v_add_f32_e32 v104, v156, v104
	v_add_f32_e32 v104, v158, v104
	v_add_f32_e32 v104, v157, v104
	v_pk_mul_f32 v[128:129], v[80:81], v[80:81]
	v_add_f32_e32 v104, v159, v104
	v_pk_mul_f32 v[130:131], v[82:83], v[82:83]
	v_add_f32_e32 v104, v128, v104
	v_add_f32_e32 v104, v130, v104
	v_add_f32_e32 v104, v129, v104
	v_pk_mul_f32 v[132:133], v[84:85], v[84:85]
	v_add_f32_e32 v104, v131, v104
	v_pk_mul_f32 v[134:135], v[86:87], v[86:87]
	v_add_f32_e32 v104, v132, v104
	v_add_f32_e32 v104, v134, v104
	v_add_f32_e32 v104, v133, v104
	v_pk_mul_f32 v[144:145], v[74:75], v[74:75]
	v_add_f32_e32 v104, v135, v104
	v_pk_mul_f32 v[146:147], v[76:77], v[76:77]
	v_add_f32_e32 v104, v144, v104
	v_add_f32_e32 v104, v146, v104
	v_mov_b32_e32 v148, v72
	v_mov_b32_e32 v149, v78
	v_add_f32_e32 v104, v145, v104
	v_pk_mul_f32 v[148:149], v[148:149], v[148:149]
	v_add_f32_e32 v104, v147, v104
	v_mov_b32_e32 v150, v73
	v_mov_b32_e32 v151, v79
	v_add_f32_e32 v104, v149, v104
	v_pk_mul_f32 v[150:151], v[150:151], v[150:151]
	v_add_f32_e32 v104, v148, v104
	v_add_f32_e32 v104, v151, v104
	v_add_f32_e32 v104, v150, v104
	ds_bpermute_b32 v111, v3, v104
	s_waitcnt lgkmcnt(0)
; __device__ __forceinline__ unsigned pk2(float lo, float hi) { return f2bf(lo) | (f2bf(hi) << 16); }
; __device__ __forceinline__ void sgu_ln(const Ctx& c, bf16* P, const float* g) {
;     ...
;         const float rs = rsqrtf(wave_sum(q) * (1.f / 4096.f) + EPS);
; #pragma unroll
;         for (int j = 0; j < 8; ++j) { const float* gg = g + (c.lane + 64 * j) * 8; const f32x4 g0 = *(CF4)gg, g1 = *(CF4)(gg + 4);
;             v4u w; w.x = pk2(v[j][0] * rs * g0.x, v[j][1] * rs * g0.y); w.y = pk2(v[j][2] * rs * g0.z, v[j][3] * rs * g0.w); w.z = pk2(v[j][4] * rs * g1.x, v[j][5] * rs * g1.y); w.w = pk2(v[j][6] * rs * g1.z, v[j][7] * rs * g1.w);
;             vr[64 * j] = w; }
	v_add_f32_e32 v104, v104, v111
	ds_bpermute_b32 v111, v105, v104
	s_waitcnt lgkmcnt(0)
	v_add_f32_e32 v104, v104, v111
	ds_bpermute_b32 v111, v106, v104
	s_waitcnt lgkmcnt(0)
	v_add_f32_e32 v104, v104, v111
	ds_bpermute_b32 v111, v107, v104
	s_waitcnt lgkmcnt(0)
	v_add_f32_e32 v104, v104, v111
	ds_bpermute_b32 v111, v108, v104
	s_waitcnt lgkmcnt(0)
	v_add_f32_e32 v104, v104, v111
	ds_bpermute_b32 v111, v109, v104
	s_waitcnt lgkmcnt(0)
	v_add_f32_e32 v104, v104, v111
	v_fmamk_f32 v104, v104, 0x39800000, v110
	v_mul_f32_e32 v111, 0x4b800000, v104
	v_cmp_gt_f32_e32 vcc, s12, v104
	s_nop 1
	v_cndmask_b32_e32 v104, v104, v111, vcc
	v_rsq_f32_e32 v104, v104
	s_nop 0
	v_mul_f32_e32 v111, 0x45800000, v104
	v_cndmask_b32_e32 v104, v104, v111, vcc
	v_pk_mul_f32 v[128:129], v[136:137], v[104:105] op_sel_hi:[1,0]
	v_pk_mul_f32 v[130:131], v[138:139], v[104:105] op_sel_hi:[1,0]
	v_pk_mul_f32 v[112:113], v[112:113], v[104:105] op_sel_hi:[1,0]
	v_pk_mul_f32 v[128:129], v[68:69], v[128:129]
	v_pk_mul_f32 v[114:115], v[114:115], v[104:105] op_sel_hi:[1,0]
	v_pk_mul_f32 v[130:131], v[6:7], v[130:131]
	v_pk_mul_f32 v[112:113], v[4:5], v[112:113]
	v_pk_mul_f32 v[114:115], v[8:9], v[114:115]
	v_bfe_u32 v111, v131, 16, 1
	s_nop 5
	v_add3_u32 v111, v131, v111, s10
	s_nop 2
	v_bfe_u32 v134, v115, 16, 1
	v_add3_u32 v115, v115, v134, s10
	s_nop 5
	v_lshrrev_b32_e32 v115, 16, v115
	v_and_or_b32 v115, v111, s9, v115
	v_cvt_pk_bf16_f32 v114, v114, v130
	v_cvt_pk_bf16_f32 v113, v113, v129
	v_cvt_pk_bf16_f32 v112, v112, v128
	global_store_dwordx4 v[66:67], v[112:115], off
	v_pk_mul_f32 v[98:99], v[98:99], v[104:105] op_sel_hi:[1,0]
	v_pk_mul_f32 v[102:103], v[102:103], v[104:105] op_sel_hi:[1,0]
	v_pk_mul_f32 v[112:113], v[116:117], v[104:105] op_sel_hi:[1,0]
	v_pk_mul_f32 v[114:115], v[140:141], v[104:105] op_sel_hi:[1,0]
	v_pk_mul_f32 v[116:117], v[118:119], v[104:105] op_sel_hi:[1,0]
	v_pk_mul_f32 v[118:119], v[142:143], v[104:105] op_sel_hi:[1,0]
	v_pk_mul_f32 v[114:115], v[10:11], v[114:115]
	v_pk_mul_f32 v[118:119], v[14:15], v[118:119]
	v_pk_mul_f32 v[112:113], v[12:13], v[112:113]
	v_pk_mul_f32 v[116:117], v[16:17], v[116:117]
	v_bfe_u32 v111, v119, 16, 1
	v_bfe_u32 v128, v118, 16, 1
	v_bfe_u32 v129, v115, 16, 1
	v_bfe_u32 v130, v114, 16, 1
	v_add3_u32 v130, v114, v130, s10
	v_add3_u32 v129, v115, v129, s10
	v_add3_u32 v114, v118, v128, s10
	v_add3_u32 v111, v119, v111, s10
	v_bfe_u32 v115, v112, 16, 1
	v_bfe_u32 v118, v113, 16, 1
	v_bfe_u32 v119, v116, 16, 1
	v_bfe_u32 v128, v117, 16, 1
	v_add3_u32 v117, v117, v128, s10
	v_add3_u32 v116, v116, v119, s10
	v_add3_u32 v113, v113, v118, s10
	v_add3_u32 v112, v112, v115, s10
	v_lshrrev_b32_e32 v112, 16, v112
	v_lshrrev_b32_e32 v113, 16, v113
	v_lshrrev_b32_e32 v116, 16, v116
	v_lshrrev_b32_e32 v115, 16, v117
	v_and_or_b32 v115, v111, s9, v115
	v_and_or_b32 v114, v114, s9, v116
	v_and_or_b32 v113, v129, s9, v113
	v_and_or_b32 v112, v130, s9, v112
	global_store_dwordx4 v[66:67], v[112:115], off offset:1024
	v_pk_mul_f32 v[118:119], v[186:187], v[104:105] op_sel_hi:[1,0]
	v_pk_mul_f32 v[116:117], v[122:123], v[104:105] op_sel_hi:[1,0]
	v_pk_mul_f32 v[114:115], v[180:181], v[104:105] op_sel_hi:[1,0]
	v_pk_mul_f32 v[112:113], v[120:121], v[104:105] op_sel_hi:[1,0]
	v_pk_mul_f32 v[114:115], v[18:19], v[114:115]
	v_pk_mul_f32 v[118:119], v[22:23], v[118:119]
	v_pk_mul_f32 v[112:113], v[20:21], v[112:113]
	v_pk_mul_f32 v[116:117], v[24:25], v[116:117]
	v_bfe_u32 v111, v119, 16, 1
	v_bfe_u32 v120, v118, 16, 1
	v_bfe_u32 v121, v115, 16, 1
	v_bfe_u32 v122, v114, 16, 1
	v_add3_u32 v122, v114, v122, s10
	v_add3_u32 v121, v115, v121, s10
	v_add3_u32 v114, v118, v120, s10
	v_add3_u32 v111, v119, v111, s10
	v_bfe_u32 v115, v112, 16, 1
	v_bfe_u32 v118, v113, 16, 1
	v_bfe_u32 v119, v116, 16, 1
	v_bfe_u32 v120, v117, 16, 1
	v_add3_u32 v117, v117, v120, s10
	v_add3_u32 v116, v116, v119, s10
	v_add3_u32 v113, v113, v118, s10
	v_add3_u32 v112, v112, v115, s10
	v_lshrrev_b32_e32 v112, 16, v112
	v_lshrrev_b32_e32 v113, 16, v113
	v_lshrrev_b32_e32 v116, 16, v116
	v_lshrrev_b32_e32 v115, 16, v117
	v_and_or_b32 v115, v111, s9, v115
	v_and_or_b32 v114, v114, s9, v116
	v_and_or_b32 v113, v121, s9, v113
	v_and_or_b32 v112, v122, s9, v112
	global_store_dwordx4 v[66:67], v[112:115], off offset:2048
	v_pk_mul_f32 v[118:119], v[198:199], v[104:105] op_sel_hi:[1,0]
	v_pk_mul_f32 v[116:117], v[126:127], v[104:105] op_sel_hi:[1,0]
	v_pk_mul_f32 v[114:115], v[192:193], v[104:105] op_sel_hi:[1,0]
	v_pk_mul_f32 v[112:113], v[124:125], v[104:105] op_sel_hi:[1,0]
	v_pk_mul_f32 v[114:115], v[26:27], v[114:115]
	v_pk_mul_f32 v[118:119], v[30:31], v[118:119]
	v_pk_mul_f32 v[112:113], v[28:29], v[112:113]
	v_pk_mul_f32 v[116:117], v[32:33], v[116:117]
	v_bfe_u32 v111, v119, 16, 1
	v_bfe_u32 v120, v118, 16, 1
	v_bfe_u32 v121, v115, 16, 1
	v_bfe_u32 v122, v114, 16, 1
	v_add3_u32 v122, v114, v122, s10
	v_add3_u32 v121, v115, v121, s10
	v_add3_u32 v114, v118, v120, s10
	v_add3_u32 v111, v119, v111, s10
	v_bfe_u32 v115, v112, 16, 1
	v_bfe_u32 v118, v113, 16, 1
	v_bfe_u32 v119, v116, 16, 1
; __device__ __forceinline__ unsigned pk2(float lo, float hi) { return f2bf(lo) | (f2bf(hi) << 16); }
; __device__ __forceinline__ void sgu_ln(const Ctx& c, bf16* P, const float* g) {
;     ...
; #pragma unroll
;         for (int j = 0; j < 8; ++j) { const float* gg = g + (c.lane + 64 * j) * 8; const f32x4 g0 = *(CF4)gg, g1 = *(CF4)(gg + 4);
;             v4u w; w.x = pk2(v[j][0] * rs * g0.x, v[j][1] * rs * g0.y); w.y = pk2(v[j][2] * rs * g0.z, v[j][3] * rs * g0.w); w.z = pk2(v[j][4] * rs * g1.x, v[j][5] * rs * g1.y); w.w = pk2(v[j][6] * rs * g1.z, v[j][7] * rs * g1.w);
;             vr[64 * j] = w; }
	v_bfe_u32 v120, v117, 16, 1
	v_add3_u32 v117, v117, v120, s10
	v_add3_u32 v116, v116, v119, s10
	v_add3_u32 v113, v113, v118, s10
	v_add3_u32 v112, v112, v115, s10
	v_lshrrev_b32_e32 v112, 16, v112
	v_lshrrev_b32_e32 v113, 16, v113
	v_lshrrev_b32_e32 v116, 16, v116
	v_lshrrev_b32_e32 v115, 16, v117
	v_and_or_b32 v115, v111, s9, v115
	v_and_or_b32 v114, v114, s9, v116
	v_and_or_b32 v113, v121, s9, v113
	v_and_or_b32 v112, v122, s9, v112
	v_pk_mul_f32 v[96:97], v[96:97], v[104:105] op_sel_hi:[1,0]
	v_pk_mul_f32 v[98:99], v[34:35], v[98:99]
	v_pk_mul_f32 v[100:101], v[100:101], v[104:105] op_sel_hi:[1,0]
	v_pk_mul_f32 v[102:103], v[38:39], v[102:103]
	global_store_dwordx4 v[66:67], v[112:115], off offset:3072
	v_pk_mul_f32 v[96:97], v[36:37], v[96:97]
	v_pk_mul_f32 v[100:101], v[40:41], v[100:101]
	v_bfe_u32 v111, v103, 16, 1
	v_bfe_u32 v112, v102, 16, 1
	v_bfe_u32 v113, v99, 16, 1
	v_bfe_u32 v114, v98, 16, 1
	v_add3_u32 v114, v98, v114, s10
	v_add3_u32 v113, v99, v113, s10
	v_add3_u32 v98, v102, v112, s10
	v_add3_u32 v99, v103, v111, s10
	v_bfe_u32 v102, v96, 16, 1
	v_bfe_u32 v103, v97, 16, 1
	v_bfe_u32 v111, v100, 16, 1
	v_bfe_u32 v112, v101, 16, 1
	v_add3_u32 v101, v101, v112, s10
	v_add3_u32 v100, v100, v111, s10
	v_add3_u32 v97, v97, v103, s10
	v_add3_u32 v96, v96, v102, s10
	v_lshrrev_b32_e32 v96, 16, v96
	v_lshrrev_b32_e32 v97, 16, v97
	v_lshrrev_b32_e32 v100, 16, v100
	v_lshrrev_b32_e32 v101, 16, v101
	v_pk_mul_f32 v[90:91], v[90:91], v[104:105] op_sel_hi:[1,0]
	v_pk_mul_f32 v[94:95], v[94:95], v[104:105] op_sel_hi:[1,0]
	v_and_or_b32 v99, v99, s9, v101
	v_and_or_b32 v98, v98, s9, v100
	v_and_or_b32 v97, v113, s9, v97
	v_and_or_b32 v96, v114, s9, v96
	v_pk_mul_f32 v[88:89], v[88:89], v[104:105] op_sel_hi:[1,0]
	v_pk_mul_f32 v[90:91], v[42:43], v[90:91]
	v_pk_mul_f32 v[92:93], v[92:93], v[104:105] op_sel_hi:[1,0]
	v_pk_mul_f32 v[94:95], v[50:51], v[94:95]
	global_store_dwordx4 v[70:71], v[96:99], off
	v_pk_mul_f32 v[88:89], v[48:49], v[88:89]
	v_pk_mul_f32 v[92:93], v[44:45], v[92:93]
	v_bfe_u32 v96, v95, 16, 1
	v_bfe_u32 v97, v94, 16, 1
	v_bfe_u32 v98, v91, 16, 1
	v_bfe_u32 v99, v90, 16, 1
	v_add3_u32 v99, v90, v99, s10
	v_add3_u32 v98, v91, v98, s10
	v_add3_u32 v90, v94, v97, s10
	v_add3_u32 v91, v95, v96, s10
	v_bfe_u32 v94, v88, 16, 1
	v_bfe_u32 v95, v89, 16, 1
	v_bfe_u32 v96, v92, 16, 1
	v_bfe_u32 v97, v93, 16, 1
	v_add3_u32 v93, v93, v97, s10
	v_add3_u32 v92, v92, v96, s10
	v_add3_u32 v89, v89, v95, s10
	v_add3_u32 v88, v88, v94, s10
	v_lshrrev_b32_e32 v88, 16, v88
	v_lshrrev_b32_e32 v89, 16, v89
	v_lshrrev_b32_e32 v92, 16, v92
	v_lshrrev_b32_e32 v93, 16, v93
	v_pk_mul_f32 v[82:83], v[82:83], v[104:105] op_sel_hi:[1,0]
	v_pk_mul_f32 v[86:87], v[86:87], v[104:105] op_sel_hi:[1,0]
	v_and_or_b32 v91, v91, s9, v93
	v_and_or_b32 v90, v90, s9, v92
	v_and_or_b32 v89, v98, s9, v89
	v_and_or_b32 v88, v99, s9, v88
	v_pk_mul_f32 v[80:81], v[80:81], v[104:105] op_sel_hi:[1,0]
	v_pk_mul_f32 v[82:83], v[46:47], v[82:83]
	v_pk_mul_f32 v[84:85], v[84:85], v[104:105] op_sel_hi:[1,0]
	v_pk_mul_f32 v[86:87], v[54:55], v[86:87]
	global_store_dwordx4 v[70:71], v[88:91], off offset:1024
	v_pk_mul_f32 v[80:81], v[52:53], v[80:81]
	v_pk_mul_f32 v[84:85], v[56:57], v[84:85]
	v_bfe_u32 v88, v87, 16, 1
	v_bfe_u32 v89, v86, 16, 1
	v_bfe_u32 v90, v83, 16, 1
	v_bfe_u32 v91, v82, 16, 1
	v_add3_u32 v91, v82, v91, s10
	v_add3_u32 v90, v83, v90, s10
	v_add3_u32 v82, v86, v89, s10
	v_add3_u32 v83, v87, v88, s10
	v_bfe_u32 v86, v80, 16, 1
	v_bfe_u32 v87, v81, 16, 1
	v_bfe_u32 v88, v84, 16, 1
	v_bfe_u32 v89, v85, 16, 1
	v_add3_u32 v85, v85, v89, s10
	v_add3_u32 v84, v84, v88, s10
	v_add3_u32 v81, v81, v87, s10
	v_add3_u32 v80, v80, v86, s10
	v_lshrrev_b32_e32 v80, 16, v80
	v_lshrrev_b32_e32 v81, 16, v81
	v_lshrrev_b32_e32 v84, 16, v84
	v_lshrrev_b32_e32 v85, 16, v85
	v_pk_mul_f32 v[76:77], v[76:77], v[104:105] op_sel_hi:[1,0]
	v_pk_mul_f32 v[72:73], v[72:73], v[104:105] op_sel_hi:[1,0]
	v_and_or_b32 v83, v83, s9, v85
	v_and_or_b32 v82, v82, s9, v84
	v_and_or_b32 v81, v90, s9, v81
	v_and_or_b32 v80, v91, s9, v80
	v_pk_mul_f32 v[74:75], v[74:75], v[104:105] op_sel_hi:[1,0]
	v_pk_mul_f32 v[76:77], v[58:59], v[76:77]
	v_pk_mul_f32 v[78:79], v[78:79], v[104:105] op_sel_hi:[1,0]
	v_pk_mul_f32 v[72:73], v[62:63], v[72:73]
	global_store_dwordx4 v[70:71], v[80:83], off offset:2048
	v_pk_mul_f32 v[74:75], v[60:61], v[74:75]
	v_pk_mul_f32 v[78:79], v[64:65], v[78:79]
	s_nop 1
	v_bfe_u32 v82, v77, 16, 1
	v_bfe_u32 v83, v76, 16, 1
	v_add3_u32 v76, v76, v83, s10
	v_add3_u32 v77, v77, v82, s10
	s_nop 1
	v_bfe_u32 v80, v74, 16, 1
	v_bfe_u32 v81, v75, 16, 1
	s_nop 3
	v_add3_u32 v75, v75, v81, s10
	v_add3_u32 v74, v74, v80, s10
	v_lshrrev_b32_e32 v80, 16, v74
	v_lshrrev_b32_e32 v81, 16, v75
	s_nop 1
	v_cvt_pk_bf16_f32 v75, v79, v73
	v_cvt_pk_bf16_f32 v74, v78, v72
	v_and_or_b32 v73, v77, s9, v81
	v_and_or_b32 v72, v76, s9, v80
	v_lshl_add_u64 v[66:67], v[66:67], 0, s[6:7]
	global_store_dwordx4 v[70:71], v[72:75], off offset:3072
	s_cbranch_scc1 .LBB0_3519
	s_mov_b64 s[4:5], s[20:21]

; #define LAS __attribute__((address_space(3)))
; __device__ __forceinline__ unsigned pk2(float lo, float hi) { return f2bf(lo) | (f2bf(hi) << 16); }
; __device__ __forceinline__ void sgu_spatial_mfma(const Ctx& c, const bf16* P, const float* Wsp, const float* bsp, bf16* ACT) {
;     ...
;             for (int dt = 0; dt < 16; ++dt) {
;                 f32x4 acc = (f32x4){0.f, 0.f, 0.f, 0.f};
; #pragma unroll
;                 for (int ks = 0; ks < 4; ++ks) if (ks < nks) {
;                     const s16x4 a0 = __builtin_amdgcn_ds_read_tr16_b64_v4i16((LAS s16x4*)(vb + ks * 32 * RS + dt * 32)), a1 = __builtin_amdgcn_ds_read_tr16_b64_v4i16((LAS s16x4*)(vb + ks * 32 * RS + 4 * RS + dt * 32));
;                     bf16x8 af; af[0] = a0[0]; af[1] = a0[1]; af[2] = a0[2]; af[3] = a0[3]; af[4] = a1[0]; af[5] = a1[1]; af[6] = a1[2]; af[7] = a1[3];
;                     acc = __builtin_amdgcn_mfma_f32_16x16x32_bf16(af, Wf[ks], acc, 0, 0, 0); }
;                 const size_t col = (size_t)g * 512 + 256 * half + 16 * dt + 4 * lg;
;                 const v2u uu = uv[dt];
;                 v2u o; o.x = pk2(bflo(uu.x) * (acc[0] + bb), bfhi(uu.x) * (acc[1] + bb)); o.y = pk2(bflo(uu.y) * (acc[2] + bb), bfhi(uu.y) * (acc[3] + bb));
;                 *(v2u*)(ACT + (row0 + t) * 4096 + col) = o;
.LBB0_3587:
	s_nop 7
	v_mov_b32_e32 v116, v20
	v_mov_b32_e32 v117, v22
	s_waitcnt vmcnt(15)
	v_lshlrev_b32_e32 v115, 16, v61
	v_lshlrev_b32_e32 v114, 16, v60
	v_pk_add_f32 v[116:117], v[56:57], v[116:117] op_sel_hi:[0,1]
	v_mov_b32_e32 v22, v21
	v_pk_mul_f32 v[114:115], v[116:117], v[114:115]
	v_and_b32_e32 v61, 0xffff0000, v61
	v_and_b32_e32 v60, 0xffff0000, v60
	v_pk_add_f32 v[20:21], v[56:57], v[22:23] op_sel_hi:[0,1]
	v_pk_mul_f32 v[60:61], v[20:21], v[60:61]
	s_nop 5
	ds_read_b64_tr_b16 v[20:21], v90 offset:32
	ds_read_b64_tr_b16 v[22:23], v90 offset:2144
	s_nop 0
	s_waitcnt lgkmcnt(0)
	v_mfma_f32_16x16x32_bf16 v[20:23], v[20:23], v[16:19], 0
	s_nop 0
	s_or_b32 s82, s82, s96
	s_nop 1
	v_cvt_pk_bf16_f32 v115, v115, v61
	v_cvt_pk_bf16_f32 v114, v114, v60
	v_lshl_add_u64 v[60:61], s[82:83], 1, v[38:39]
	s_and_b64 vcc, exec, s[70:71]
	global_store_dwordx2 v[60:61], v[114:115], off
	s_cbranch_vccz .LBB0_3648
	s_and_b64 vcc, exec, s[68:69]
	s_cbranch_vccz .LBB0_3649

; __device__ __forceinline__ void postnorm(const Ctx& c, const bf16* MF, bf16* XB, float* RS, const float* gpost, float* OUT) {
;     for (int row = c.gw; row < MT; row += c.NGW) {
;         const v4u* mr = (const v4u*)(MF + (size_t)row * DM) + c.lane; v4u* xr = (v4u*)(XB + (size_t)row * DM) + c.lane;
;         v4u mv[4], xv[4]; float v[4][8]; float s = 0.f;
; #pragma unroll
;         for (int j = 0; j < 4; ++j) { mv[j] = mr[64 * j]; xv[j] = xr[64 * j]; }
; #pragma unroll
;         for (int j = 0; j < 4; ++j)
; #pragma unroll
;             for (int k = 0; k < 4; ++k) { v[j][2 * k] = bflo(mv[j][k]); v[j][2 * k + 1] = bfhi(mv[j][k]); s += v[j][2 * k] * v[j][2 * k] + v[j][2 * k + 1] * v[j][2 * k + 1]; }
;         const float rs = rsqrtf(wave_sum(s) * (1.f / DM) + EPS);
.LBB0_3812:
	v_readlane_b32 s10, v253, 0
	v_readlane_b32 s11, v253, 1
	s_nop 1
	v_lshl_add_u64 v[34:35], s[10:11], 0, v[36:37]
	v_add_co_u32_e32 v58, vcc, 0xd400000, v34
	s_nop 1
	v_addc_co_u32_e32 v59, vcc, 0, v35, vcc
	s_waitcnt lgkmcnt(0)
	global_load_dwordx4 v[46:49], v[58:59], off
	global_load_dwordx4 v[50:53], v[58:59], off offset:1024
	global_load_dwordx4 v[54:57], v[58:59], off offset:2048
	s_nop 0
	global_load_dwordx4 v[58:61], v[58:59], off offset:3072
	v_add_co_u32_e32 v34, vcc, 0x9400000, v34
	s_waitcnt vmcnt(3)
	v_lshlrev_b32_e32 v79, 16, v47
	v_addc_co_u32_e32 v35, vcc, 0, v35, vcc
	global_load_dwordx4 v[62:65], v[34:35], off
	global_load_dwordx4 v[66:69], v[34:35], off offset:1024
	global_load_dwordx4 v[70:73], v[34:35], off offset:2048
	global_load_dwordx4 v[74:77], v[34:35], off offset:3072
	v_lshlrev_b32_e32 v78, 16, v46
	v_and_b32_e32 v47, 0xffff0000, v47
	v_and_b32_e32 v46, 0xffff0000, v46
	v_lshlrev_b32_e32 v81, 16, v49
	v_lshlrev_b32_e32 v80, 16, v48
	v_and_b32_e32 v49, 0xffff0000, v49
	v_and_b32_e32 v48, 0xffff0000, v48
	v_pk_mul_f32 v[94:95], v[46:47], v[46:47]
	v_pk_mul_f32 v[98:99], v[48:49], v[48:49]
	v_pk_fma_f32 v[94:95], v[78:79], v[78:79], v[94:95]
	s_waitcnt vmcnt(6)
	v_lshlrev_b32_e32 v83, 16, v51
	v_lshlrev_b32_e32 v82, 16, v50
	v_and_b32_e32 v51, 0xffff0000, v51
	v_and_b32_e32 v50, 0xffff0000, v50
	v_pk_fma_f32 v[98:99], v[80:81], v[80:81], v[98:99]
	v_add_f32_e32 v94, v94, v95
	v_pk_mul_f32 v[102:103], v[50:51], v[50:51]
	v_add_f32_e32 v94, v98, v94
	v_lshlrev_b32_e32 v85, 16, v53
	v_lshlrev_b32_e32 v84, 16, v52
	v_and_b32_e32 v53, 0xffff0000, v53
	v_and_b32_e32 v52, 0xffff0000, v52
	v_pk_fma_f32 v[102:103], v[82:83], v[82:83], v[102:103]
	v_add_f32_e32 v94, v99, v94
	v_pk_mul_f32 v[104:105], v[52:53], v[52:53]
	v_add_f32_e32 v94, v102, v94
	s_waitcnt vmcnt(5)
	v_lshlrev_b32_e32 v87, 16, v55
	v_lshlrev_b32_e32 v86, 16, v54
	v_and_b32_e32 v55, 0xffff0000, v55
	v_and_b32_e32 v54, 0xffff0000, v54
	v_pk_fma_f32 v[104:105], v[84:85], v[84:85], v[104:105]
	v_add_f32_e32 v94, v103, v94
	v_pk_mul_f32 v[106:107], v[54:55], v[54:55]
	v_add_f32_e32 v94, v104, v94
	v_lshlrev_b32_e32 v89, 16, v57
	v_lshlrev_b32_e32 v88, 16, v56
	v_and_b32_e32 v57, 0xffff0000, v57
	v_and_b32_e32 v56, 0xffff0000, v56
	v_pk_fma_f32 v[106:107], v[86:87], v[86:87], v[106:107]
	v_add_f32_e32 v94, v105, v94
	v_pk_mul_f32 v[108:109], v[56:57], v[56:57]
	v_add_f32_e32 v94, v106, v94
	s_waitcnt vmcnt(4)
	v_lshlrev_b32_e32 v91, 16, v59
	v_lshlrev_b32_e32 v90, 16, v58
	v_and_b32_e32 v59, 0xffff0000, v59
	v_and_b32_e32 v58, 0xffff0000, v58
	v_pk_fma_f32 v[108:109], v[88:89], v[88:89], v[108:109]
	v_add_f32_e32 v94, v107, v94
	v_pk_mul_f32 v[110:111], v[58:59], v[58:59]
	v_add_f32_e32 v94, v108, v94
	v_lshlrev_b32_e32 v93, 16, v61
	v_lshlrev_b32_e32 v92, 16, v60
	v_and_b32_e32 v61, 0xffff0000, v61
	v_and_b32_e32 v60, 0xffff0000, v60
	v_pk_fma_f32 v[110:111], v[90:91], v[90:91], v[110:111]
	v_add_f32_e32 v94, v109, v94
	v_pk_mul_f32 v[112:113], v[60:61], v[60:61]
	v_add_f32_e32 v94, v110, v94
	v_pk_fma_f32 v[112:113], v[92:93], v[92:93], v[112:113]
	v_add_f32_e32 v94, v111, v94
	v_add_f32_e32 v94, v112, v94
	v_add_f32_e32 v94, v113, v94
	ds_bpermute_b32 v98, v40, v94
	s_waitcnt lgkmcnt(0)
	v_add_f32_e32 v98, v94, v98
	ds_bpermute_b32 v102, v41, v98
	s_waitcnt lgkmcnt(0)
	v_add_f32_e32 v102, v98, v102
	ds_bpermute_b32 v104, v42, v102
	s_waitcnt vmcnt(3)
	v_lshlrev_b32_e32 v97, 16, v63
	v_lshlrev_b32_e32 v96, 16, v62
	v_and_b32_e32 v63, 0xffff0000, v63
	s_waitcnt lgkmcnt(0)
	v_add_f32_e32 v104, v102, v104
	ds_bpermute_b32 v106, v43, v104
	v_and_b32_e32 v62, 0xffff0000, v62
	v_lshlrev_b32_e32 v101, 16, v65
	v_lshlrev_b32_e32 v100, 16, v64
	v_and_b32_e32 v65, 0xffff0000, v65
	s_waitcnt lgkmcnt(0)
	v_add_f32_e32 v106, v104, v106
	ds_bpermute_b32 v108, v44, v106
	v_and_b32_e32 v64, 0xffff0000, v64
	s_waitcnt vmcnt(0)
	v_lshlrev_b32_e32 v109, 16, v77
	v_and_b32_e32 v77, 0xffff0000, v77
	v_lshlrev_b32_e32 v95, 16, v67
	s_waitcnt lgkmcnt(0)
	v_add_f32_e32 v108, v106, v108
	ds_bpermute_b32 v110, v45, v108
	v_lshlrev_b32_e32 v94, 16, v66
	v_and_b32_e32 v67, 0xffff0000, v67
	v_and_b32_e32 v66, 0xffff0000, v66
	v_lshlrev_b32_e32 v99, 16, v69
	s_waitcnt lgkmcnt(0)
; __device__ __forceinline__ unsigned pk2(float lo, float hi) { return f2bf(lo) | (f2bf(hi) << 16); }
; __device__ __forceinline__ void postnorm(const Ctx& c, const bf16* MF, bf16* XB, float* RS, const float* gpost, float* OUT) {
;     ...
;         const float rs = rsqrtf(wave_sum(s) * (1.f / DM) + EPS);
;         float s2 = 0.f;
; #pragma unroll
;         for (int j = 0; j < 4; ++j) { const float* gp = gpost + (c.lane + 64 * j) * 8; const f32x4 g0 = *(CF4)gp, g1 = *(CF4)(gp + 4);
; #pragma unroll
;             for (int k = 0; k < 4; ++k) { const float ga = (k < 2) ? g0[2 * k] : g1[2 * k - 4], gb = (k < 2) ? g0[2 * k + 1] : g1[2 * k - 3];
;                 v[j][2 * k] = bflo(xv[j][k]) + v[j][2 * k] * rs * ga; v[j][2 * k + 1] = bfhi(xv[j][k]) + v[j][2 * k + 1] * rs * gb;
;                 s2 += v[j][2 * k] * v[j][2 * k] + v[j][2 * k + 1] * v[j][2 * k + 1]; } }
;         if (OUT) {
; #pragma unroll
;             for (int j = 0; j < 4; ++j) { float* op = OUT + (size_t)row * DM + (c.lane + 64 * j) * 8; *(f32x4*)op = (f32x4){v[j][0], v[j][1], v[j][2], v[j][3]}; *(f32x4*)(op + 4) = (f32x4){v[j][4], v[j][5], v[j][6], v[j][7]}; }
;         } else {
; #pragma unroll
;             for (int j = 0; j < 4; ++j) { v4u o; o.x = pk2(v[j][0], v[j][1]); o.y = pk2(v[j][2], v[j][3]); o.z = pk2(v[j][4], v[j][5]); o.w = pk2(v[j][6], v[j][7]); xr[64 * j] = o; }
;             const float rs2 = rsqrtf(wave_sum(s2) * (1.f / DM) + EPS); if (c.lane == 0) RS[row] = rs2;
	v_add_f32_e32 v108, v108, v110
	v_fmamk_f32 v108, v108, 0x3a000000, v3
	v_mul_f32_e32 v110, 0x4b800000, v108
	v_cmp_gt_f32_e32 vcc, s15, v108
	v_lshlrev_b32_e32 v98, 16, v68
	v_and_b32_e32 v69, 0xffff0000, v69
	v_cndmask_b32_e32 v108, v108, v110, vcc
	v_rsq_f32_e32 v110, v108
	v_lshlrev_b32_e32 v108, 16, v76
	v_and_b32_e32 v76, 0xffff0000, v76
	v_and_b32_e32 v68, 0xffff0000, v68
	v_mul_f32_e32 v111, 0x45800000, v110
	v_cndmask_b32_e32 v110, v110, v111, vcc
	v_pk_mul_f32 v[46:47], v[110:111], v[46:47] op_sel_hi:[0,1]
	v_pk_mul_f32 v[78:79], v[110:111], v[78:79] op_sel_hi:[0,1]
	v_pk_mul_f32 v[48:49], v[110:111], v[48:49] op_sel_hi:[0,1]
	v_pk_fma_f32 v[46:47], v[38:39], v[46:47], v[62:63]
	v_pk_mul_f32 v[60:61], v[110:111], v[60:61] op_sel_hi:[0,1]
	v_pk_mul_f32 v[80:81], v[110:111], v[80:81] op_sel_hi:[0,1]
	v_pk_fma_f32 v[78:79], v[4:5], v[78:79], v[96:97]
	v_pk_fma_f32 v[48:49], v[6:7], v[48:49], v[64:65]
	v_pk_fma_f32 v[60:61], v[30:31], v[60:61], v[76:77]
	v_pk_mul_f32 v[76:77], v[46:47], v[46:47]
	v_pk_mul_f32 v[50:51], v[110:111], v[50:51] op_sel_hi:[0,1]
	v_pk_fma_f32 v[62:63], v[8:9], v[80:81], v[100:101]
	v_pk_fma_f32 v[76:77], v[78:79], v[78:79], v[76:77]
	v_pk_mul_f32 v[80:81], v[48:49], v[48:49]
	v_pk_mul_f32 v[82:83], v[110:111], v[82:83] op_sel_hi:[0,1]
	v_pk_fma_f32 v[50:51], v[10:11], v[50:51], v[66:67]
	v_pk_fma_f32 v[80:81], v[62:63], v[62:63], v[80:81]
	v_add_f32_e32 v76, v76, v77
	v_pk_fma_f32 v[64:65], v[12:13], v[82:83], v[94:95]
	v_pk_mul_f32 v[82:83], v[50:51], v[50:51]
	v_add_f32_e32 v76, v80, v76
	v_pk_fma_f32 v[82:83], v[64:65], v[64:65], v[82:83]
	v_add_f32_e32 v76, v81, v76
	v_add_f32_e32 v76, v82, v76
	s_nop 2
	v_bfe_u32 v82, v46, 16, 1
	v_pk_mul_f32 v[52:53], v[110:111], v[52:53] op_sel_hi:[0,1]
	v_add3_u32 v46, v46, v82, s16
	s_nop 2
	v_bfe_u32 v77, v78, 16, 1
	s_nop 2
	v_pk_mul_f32 v[84:85], v[110:111], v[84:85] op_sel_hi:[0,1]
	v_pk_fma_f32 v[52:53], v[14:15], v[52:53], v[68:69]
	s_nop 2
	v_add3_u32 v77, v78, v77, s16
	v_lshlrev_b32_e32 v103, 16, v71
	v_lshlrev_b32_e32 v102, 16, v70
	v_and_b32_e32 v71, 0xffff0000, v71
	v_and_b32_e32 v70, 0xffff0000, v70
	v_pk_fma_f32 v[66:67], v[16:17], v[84:85], v[98:99]
	v_pk_mul_f32 v[54:55], v[110:111], v[54:55] op_sel_hi:[0,1]
	v_pk_mul_f32 v[84:85], v[52:53], v[52:53]
	v_lshrrev_b32_e32 v77, 16, v77
	s_nop 2
	v_pk_mul_f32 v[68:69], v[110:111], v[86:87] op_sel_hi:[0,1]
	v_pk_fma_f32 v[54:55], v[18:19], v[54:55], v[70:71]
	v_pk_fma_f32 v[84:85], v[66:67], v[66:67], v[84:85]
	v_add_f32_e32 v76, v83, v76
	v_cvt_pk_bf16_f32 v49, v63, v49
	v_cvt_pk_bf16_f32 v48, v62, v48
	v_cvt_pk_bf16_f32 v47, v79, v47
	v_and_or_b32 v46, v46, s12, v77
	v_lshlrev_b32_e32 v105, 16, v73
	v_lshlrev_b32_e32 v104, 16, v72
	v_and_b32_e32 v73, 0xffff0000, v73
	v_and_b32_e32 v72, 0xffff0000, v72
	v_pk_fma_f32 v[68:69], v[20:21], v[68:69], v[102:103]
	v_pk_mul_f32 v[56:57], v[110:111], v[56:57] op_sel_hi:[0,1]
	v_pk_mul_f32 v[86:87], v[54:55], v[54:55]
	v_add_f32_e32 v76, v84, v76
	global_store_dwordx4 v[34:35], v[46:49], off
	v_pk_mul_f32 v[70:71], v[110:111], v[88:89] op_sel_hi:[0,1]
	v_pk_fma_f32 v[56:57], v[22:23], v[56:57], v[72:73]
	s_nop 3
	v_pk_fma_f32 v[86:87], v[68:69], v[68:69], v[86:87]
	v_add_f32_e32 v76, v85, v76
	s_nop 7
	v_lshlrev_b32_e32 v107, 16, v75
	v_lshlrev_b32_e32 v106, 16, v74
	v_and_b32_e32 v75, 0xffff0000, v75
	v_and_b32_e32 v74, 0xffff0000, v74
	v_pk_fma_f32 v[70:71], v[24:25], v[70:71], v[104:105]
	v_pk_mul_f32 v[58:59], v[110:111], v[58:59] op_sel_hi:[0,1]
	v_pk_mul_f32 v[88:89], v[56:57], v[56:57]
	v_add_f32_e32 v76, v86, v76
	s_nop 3
	v_pk_mul_f32 v[72:73], v[110:111], v[90:91] op_sel_hi:[0,1]
	v_pk_fma_f32 v[58:59], v[26:27], v[58:59], v[74:75]
	v_pk_fma_f32 v[88:89], v[70:71], v[70:71], v[88:89]
	v_add_f32_e32 v76, v87, v76
	s_nop 3
	v_pk_fma_f32 v[72:73], v[28:29], v[72:73], v[106:107]
	v_pk_mul_f32 v[90:91], v[58:59], v[58:59]
	v_add_f32_e32 v76, v88, v76
	v_cvt_pk_bf16_f32 v49, v67, v53
	v_cvt_pk_bf16_f32 v48, v66, v52
	v_cvt_pk_bf16_f32 v47, v65, v51
	v_cvt_pk_bf16_f32 v46, v64, v50
	v_pk_mul_f32 v[74:75], v[110:111], v[92:93] op_sel_hi:[0,1]
	v_pk_fma_f32 v[90:91], v[72:73], v[72:73], v[90:91]
	v_add_f32_e32 v76, v89, v76
	global_store_dwordx4 v[34:35], v[46:49], off offset:1024
	v_pk_fma_f32 v[74:75], v[32:33], v[74:75], v[108:109]
	v_pk_mul_f32 v[92:93], v[60:61], v[60:61]
	s_nop 1
	v_add_f32_e32 v76, v90, v76
	s_nop 5
	v_pk_fma_f32 v[92:93], v[74:75], v[74:75], v[92:93]
	v_add_f32_e32 v76, v91, v76
	s_nop 5
	v_add_f32_e32 v76, v92, v76
	s_nop 5
	v_add_f32_e32 v76, v93, v76
	v_cvt_pk_bf16_f32 v49, v71, v57
	v_cvt_pk_bf16_f32 v48, v70, v56
	v_cvt_pk_bf16_f32 v47, v69, v55
	v_cvt_pk_bf16_f32 v46, v68, v54
	global_store_dwordx4 v[34:35], v[46:49], off offset:2048
	ds_bpermute_b32 v47, v40, v76
	s_nop 3
	s_waitcnt lgkmcnt(0)
	v_add_f32_e32 v47, v76, v47
	ds_bpermute_b32 v50, v41, v47
	s_nop 3
	s_waitcnt lgkmcnt(0)
	v_add_f32_e32 v47, v47, v50
	ds_bpermute_b32 v50, v42, v47
	s_nop 1
	v_cvt_pk_bf16_f32 v51, v75, v61
	s_nop 0
	s_waitcnt lgkmcnt(0)
	v_add_f32_e32 v47, v47, v50
	ds_bpermute_b32 v50, v43, v47
	s_nop 3
	s_waitcnt lgkmcnt(0)
	v_add_f32_e32 v47, v47, v50
	ds_bpermute_b32 v50, v44, v47
	s_nop 3
	s_waitcnt lgkmcnt(0)
	v_add_f32_e32 v46, v47, v50
	ds_bpermute_b32 v47, v45, v46
	s_nop 0
	v_cvt_pk_bf16_f32 v50, v74, v60
	v_cvt_pk_bf16_f32 v49, v73, v59
	v_cvt_pk_bf16_f32 v48, v72, v58
	global_store_dwordx4 v[34:35], v[48:51], off offset:3072
	s_and_saveexec_b64 s[10:11], s[0:1]
	s_cbranch_execz .LBB0_3811
	s_waitcnt lgkmcnt(0)
	v_add_f32_e32 v34, v46, v47
	v_fmamk_f32 v34, v34, 0x3a000000, v3
	v_mul_f32_e32 v35, 0x4b800000, v34
	v_cmp_gt_f32_e32 vcc, s15, v34
	v_readlane_b32 s18, v253, 0
	v_readlane_b32 s19, v253, 1
	v_cndmask_b32_e32 v34, v34, v35, vcc
	v_rsq_f32_e32 v34, v34
	s_add_u32 s18, s18, s13
	s_addc_u32 s19, s19, s14
	v_mul_f32_e32 v35, 0x45800000, v34
	v_cndmask_b32_e32 v34, v34, v35, vcc
	global_store_dword v251, v34, s[18:19]
	s_branch .LBB0_3811

; #define LAS __attribute__((address_space(3)))
; #define LDS_WAIT() asm volatile("s_waitcnt lgkmcnt(0)" ::: "memory")
;     ...
;         const int kb = it / nblk, nb = it % nblk, k0 = 64 * kb, n0 = 64 * nb, nq = (lane & 15) * 4, kr = lane >> 4; const bool ok = (n0 + nq) < N;
;         f32x4 v[16];
; #pragma unroll
;         for (int i = 0; i < 16; ++i) v[i] = ok ? __builtin_nontemporal_load((const f32x4*)(W + (size_t)(k0 + 4 * i + kr) * N + n0 + nq)) : (f32x4){0.f, 0.f, 0.f, 0.f};
;         if (gain) {
; #pragma unroll
;             for (int i = 0; i < 16; ++i) v[i] *= gain[k0 + 4 * i + kr]; }
; #pragma unroll
;         for (int i = 0; i < 16; ++i) { LAS float* d = scr + (4 * i + kr) * 65 + nq; d[0] = v[i].x; d[1] = v[i].y; d[2] = v[i].z; d[3] = v[i].w; }
;         LDS_WAIT(); asm volatile("" ::: "memory");
.LBB0_3980:
	s_or_b64 exec, exec, s[8:9]
	v_lshl_add_u64 v[76:77], v[76:77], 2, s[0:1]
	global_load_dword v78, v[76:77], off
	global_load_dword v86, v[76:77], off offset:16
	global_load_dword v88, v[76:77], off offset:32
	global_load_dword v90, v[76:77], off offset:48
	global_load_dword v94, v[76:77], off offset:64
	global_load_dword v96, v[76:77], off offset:80
	global_load_dword v98, v[76:77], off offset:96
	global_load_dword v100, v[76:77], off offset:112
	global_load_dword v102, v[76:77], off offset:128
	global_load_dword v104, v[76:77], off offset:144
	global_load_dword v106, v[76:77], off offset:160
	global_load_dword v108, v[76:77], off offset:176
	global_load_dword v110, v[76:77], off offset:192
	global_load_dword v112, v[76:77], off offset:208
	s_nop 0
	global_load_dword v76, v[76:77], off offset:224
	v_lshl_add_u64 v[80:81], v[80:81], 2, s[0:1]
	global_load_dword v80, v[80:81], off
	v_add_u32_e32 v79, 0x418, v93
	v_add_u32_e32 v87, 0xc30, v93
	v_add_u32_e32 v89, 0xc38, v93
	v_add_u32_e32 v91, 0x1040, v93
	v_add_u32_e32 v95, 0x1048, v93
	v_add_u32_e32 v97, 0x1450, v93
	v_add_u32_e32 v99, 0x1458, v93
	v_add_u32_e32 v101, 0x1860, v93
	v_add_u32_e32 v103, 0x1868, v93
	v_add_u32_e32 v105, 0x1c70, v93
	v_add_u32_e32 v77, 0x410, v93
	v_add_u32_e32 v81, 0x820, v93
	v_add_u32_e32 v85, 0x828, v93
	v_add_u32_e32 v107, 0x1c78, v93
	s_waitcnt vmcnt(0)
	v_add_u32_e32 v109, 0x2080, v93
	v_add_u32_e32 v111, 0x2088, v93
	s_add_i32 s19, s19, s17
	s_ashr_i32 s7, s6, 31
	s_add_i32 s18, s18, s13
	s_add_i32 s17, s17, s14
	s_cmpk_lt_i32 s18, 0x400
	v_pk_mul_f32 v[4:5], v[4:5], v[78:79] op_sel_hi:[1,0]
	v_pk_mul_f32 v[6:7], v[6:7], v[78:79] op_sel_hi:[1,0]
	v_pk_mul_f32 v[14:15], v[14:15], v[86:87] op_sel_hi:[1,0]
	v_pk_mul_f32 v[12:13], v[12:13], v[86:87] op_sel_hi:[1,0]
	v_pk_mul_f32 v[10:11], v[10:11], v[88:89] op_sel_hi:[1,0]
	v_pk_mul_f32 v[8:9], v[8:9], v[88:89] op_sel_hi:[1,0]
	v_pk_mul_f32 v[22:23], v[22:23], v[90:91] op_sel_hi:[1,0]
	v_pk_mul_f32 v[20:21], v[20:21], v[90:91] op_sel_hi:[1,0]
	v_pk_mul_f32 v[18:19], v[18:19], v[94:95] op_sel_hi:[1,0]
	v_pk_mul_f32 v[16:17], v[16:17], v[94:95] op_sel_hi:[1,0]
	v_pk_mul_f32 v[30:31], v[30:31], v[96:97] op_sel_hi:[1,0]
	v_pk_mul_f32 v[28:29], v[28:29], v[96:97] op_sel_hi:[1,0]
	v_pk_mul_f32 v[26:27], v[26:27], v[98:99] op_sel_hi:[1,0]
	v_pk_mul_f32 v[24:25], v[24:25], v[98:99] op_sel_hi:[1,0]
	v_pk_mul_f32 v[38:39], v[38:39], v[100:101] op_sel_hi:[1,0]
	v_pk_mul_f32 v[36:37], v[36:37], v[100:101] op_sel_hi:[1,0]
	v_pk_mul_f32 v[34:35], v[34:35], v[102:103] op_sel_hi:[1,0]
	v_pk_mul_f32 v[32:33], v[32:33], v[102:103] op_sel_hi:[1,0]
	v_pk_mul_f32 v[44:45], v[44:45], v[104:105] op_sel_hi:[1,0]
	ds_write2_b32 v93, v4, v5 offset1:1
	ds_write2_b32 v93, v6, v7 offset0:2 offset1:3
	ds_write2_b32 v77, v12, v13 offset1:1
	ds_write2_b32 v79, v14, v15 offset1:1
	ds_write2_b32 v81, v8, v9 offset1:1
	ds_write2_b32 v85, v10, v11 offset1:1
	ds_write2_b32 v87, v20, v21 offset1:1
	ds_write2_b32 v89, v22, v23 offset1:1
	ds_write2_b32 v91, v16, v17 offset1:1
	ds_write2_b32 v95, v18, v19 offset1:1
	ds_write2_b32 v97, v28, v29 offset1:1
	ds_write2_b32 v99, v30, v31 offset1:1
	ds_write2_b32 v101, v24, v25 offset1:1
	ds_write2_b32 v103, v26, v27 offset1:1
	ds_write2_b32 v105, v36, v37 offset1:1
	ds_write2_b32 v107, v38, v39 offset1:1
	ds_write2_b32 v109, v32, v33 offset1:1
	ds_write2_b32 v111, v34, v35 offset1:1
	v_add_u32_e32 v4, 0x2490, v93
	v_pk_mul_f32 v[46:47], v[46:47], v[104:105] op_sel_hi:[1,0]
	ds_write2_b32 v4, v44, v45 offset1:1
	v_add_u32_e32 v4, 0x2498, v93
	v_pk_mul_f32 v[40:41], v[40:41], v[106:107] op_sel_hi:[1,0]
	ds_write2_b32 v4, v46, v47 offset1:1
	v_add_u32_e32 v4, 0x28a0, v93
	v_pk_mul_f32 v[42:43], v[42:43], v[106:107] op_sel_hi:[1,0]
	ds_write2_b32 v4, v40, v41 offset1:1
	v_add_u32_e32 v4, 0x28a8, v93
	v_pk_mul_f32 v[52:53], v[52:53], v[108:109] op_sel_hi:[1,0]
	ds_write2_b32 v4, v42, v43 offset1:1
	v_add_u32_e32 v4, 0x2cb0, v93
	v_pk_mul_f32 v[54:55], v[54:55], v[108:109] op_sel_hi:[1,0]
	ds_write2_b32 v4, v52, v53 offset1:1
	v_add_u32_e32 v4, 0x2cb8, v93
	v_pk_mul_f32 v[48:49], v[48:49], v[110:111] op_sel_hi:[1,0]
	ds_write2_b32 v4, v54, v55 offset1:1
	v_add_u32_e32 v4, 0x30c0, v93
	v_pk_mul_f32 v[50:51], v[50:51], v[110:111] op_sel_hi:[1,0]
	ds_write2_b32 v4, v48, v49 offset1:1
	v_add_u32_e32 v4, 0x30c8, v93
	v_pk_mul_f32 v[60:61], v[60:61], v[112:113] op_sel_hi:[1,0]
	ds_write2_b32 v4, v50, v51 offset1:1
	v_add_u32_e32 v4, 0x34d0, v93
	v_pk_mul_f32 v[62:63], v[62:63], v[112:113] op_sel_hi:[1,0]
	ds_write2_b32 v4, v60, v61 offset1:1
	v_add_u32_e32 v4, 0x34d8, v93
	v_pk_mul_f32 v[56:57], v[56:57], v[76:77] op_sel_hi:[1,0]
	ds_write2_b32 v4, v62, v63 offset1:1
	v_add_u32_e32 v4, 0x38e0, v93
	v_pk_mul_f32 v[58:59], v[58:59], v[76:77] op_sel_hi:[1,0]
	ds_write2_b32 v4, v56, v57 offset1:1
	v_add_u32_e32 v4, 0x38e8, v93
	v_pk_mul_f32 v[64:65], v[64:65], v[80:81] op_sel_hi:[1,0]
	ds_write2_b32 v4, v58, v59 offset1:1
	v_add_u32_e32 v4, 0x3cf0, v93
	v_pk_mul_f32 v[66:67], v[66:67], v[80:81] op_sel_hi:[1,0]
	ds_write2_b32 v4, v64, v65 offset1:1
	v_add_u32_e32 v4, 0x3cf8, v93
	ds_write2_b32 v4, v66, v67 offset1:1
	s_waitcnt lgkmcnt(0)
	ds_read2_b32 v[12:13], v92 offset1:8
	ds_read2_b32 v[14:15], v92 offset0:65 offset1:73
	ds_read2_b32 v[16:17], v92 offset0:130 offset1:138
	ds_read2_b32 v[18:19], v92 offset0:195 offset1:203
	v_add_u32_e32 v30, 0x400, v92
	s_waitcnt lgkmcnt(3)
; #define LAS __attribute__((address_space(3)))
; #define LDS_WAIT() asm volatile("s_waitcnt lgkmcnt(0)" ::: "memory")
; __device__ __forceinline__ unsigned pk2(float lo, float hi) { return f2bf(lo) | (f2bf(hi) << 16); }
;     ...
;         const int c8 = lane & 7; int d0 = n0;
;         if (ffnmap) { const int bj = n0 >= FFH ? 1 : 0, chn = n0 - FFH * bj; d0 = 256 * (chn >> 7) + 128 * bj + (chn & 127); }
; #pragma unroll
;         for (int j = 0; j < 8; ++j) { const int n = (lane >> 3) + 8 * j; const LAS float* sp = scr + (8 * c8) * 65 + n;
;             v4u o; o.x = pk2(sp[0 * 65], sp[1 * 65]); o.y = pk2(sp[2 * 65], sp[3 * 65]); o.z = pk2(sp[4 * 65], sp[5 * 65]); o.w = pk2(sp[6 * 65], sp[7 * 65]);
;             *(v4u*)(WT + (size_t)(d0 + n) * K + k0 + 8 * c8) = o; }
;         LDS_WAIT(); asm volatile("" ::: "memory");
	s_nop 1
	s_waitcnt lgkmcnt(2)
	s_nop 0
	ds_read2_b32 v[20:21], v30 offset0:4 offset1:12
	s_nop 1
	ds_read2_b32 v[22:23], v30 offset0:69 offset1:77
	v_cvt_pk_bf16_f32 v8, v12, v14
	s_waitcnt lgkmcnt(3)
	s_nop 1
	s_waitcnt lgkmcnt(2)
	s_nop 0
	ds_read2_b32 v[24:25], v30 offset0:134 offset1:142
	s_nop 1
	ds_read2_b32 v[26:27], v30 offset0:199 offset1:207
	v_cvt_pk_bf16_f32 v9, v16, v18
	s_waitcnt lgkmcnt(3)
	s_nop 1
	s_waitcnt lgkmcnt(2)
	s_nop 2
	v_cvt_pk_bf16_f32 v10, v20, v22
	s_waitcnt lgkmcnt(1)
	s_nop 1
	s_waitcnt lgkmcnt(0)
	s_nop 2
	v_cvt_pk_bf16_f32 v11, v24, v26
	v_add_u32_e32 v6, s19, v82
	v_ashrrev_i32_e32 v7, 31, v6
	v_lshl_add_u64 v[4:5], s[6:7], 1, v[74:75]
	v_lshlrev_b64 v[28:29], 12, v[6:7]
	v_lshl_add_u64 v[28:29], v[4:5], 0, v[28:29]
	s_nop 0
	global_store_dwordx4 v[28:29], v[8:11], off
	s_nop 3
	v_cvt_pk_bf16_f32 v8, v13, v15
	s_nop 4
	v_cvt_pk_bf16_f32 v9, v17, v19
	s_nop 4
	v_cvt_pk_bf16_f32 v10, v21, v23
	s_nop 0
	v_add_u32_e32 v12, 8, v6
	s_nop 1
	v_ashrrev_i32_e32 v13, 31, v12
	s_nop 1
	v_lshlrev_b64 v[12:13], 12, v[12:13]
	v_cvt_pk_bf16_f32 v11, v25, v27
	ds_read2_b32 v[14:15], v92 offset0:16 offset1:24
	v_lshl_add_u64 v[12:13], v[4:5], 0, v[12:13]
	global_store_dwordx4 v[12:13], v[8:11], off
	ds_read2_b32 v[12:13], v92 offset0:81 offset1:89
	ds_read2_b32 v[16:17], v92 offset0:146 offset1:154
	ds_read2_b32 v[18:19], v92 offset0:211 offset1:219
	s_waitcnt lgkmcnt(3)
	s_nop 1
	s_waitcnt lgkmcnt(2)
	s_nop 0
	ds_read2_b32 v[20:21], v30 offset0:20 offset1:28
	s_nop 1
	ds_read2_b32 v[22:23], v30 offset0:85 offset1:93
	v_cvt_pk_bf16_f32 v8, v14, v12
	s_waitcnt lgkmcnt(3)
	s_nop 1
	s_waitcnt lgkmcnt(2)
	s_nop 0
	ds_read2_b32 v[24:25], v30 offset0:150 offset1:158
	s_nop 1
	ds_read2_b32 v[26:27], v30 offset0:215 offset1:223
	v_cvt_pk_bf16_f32 v9, v16, v18
	s_waitcnt lgkmcnt(3)
	s_nop 1
	s_waitcnt lgkmcnt(2)
	s_nop 2
	v_cvt_pk_bf16_f32 v10, v20, v22
	s_waitcnt lgkmcnt(1)
	s_nop 0
	v_add_u32_e32 v28, 16, v6
	s_nop 0
	s_waitcnt lgkmcnt(0)
	s_nop 0
	v_ashrrev_i32_e32 v29, 31, v28
	s_nop 1
	v_lshlrev_b64 v[28:29], 12, v[28:29]
	v_cvt_pk_bf16_f32 v11, v24, v26
	v_lshl_add_u64 v[28:29], v[4:5], 0, v[28:29]
	s_nop 0
	global_store_dwordx4 v[28:29], v[8:11], off
	s_nop 3
	v_cvt_pk_bf16_f32 v8, v15, v13
	s_nop 4
	v_cvt_pk_bf16_f32 v9, v17, v19
	s_nop 4
	v_cvt_pk_bf16_f32 v10, v21, v23
	s_nop 0
	v_add_u32_e32 v12, 24, v6
	s_nop 1
	v_ashrrev_i32_e32 v13, 31, v12
	s_nop 1
	v_lshlrev_b64 v[12:13], 12, v[12:13]
	v_cvt_pk_bf16_f32 v11, v25, v27
	ds_read2_b32 v[14:15], v92 offset0:32 offset1:40
	v_lshl_add_u64 v[12:13], v[4:5], 0, v[12:13]
	global_store_dwordx4 v[12:13], v[8:11], off
	ds_read2_b32 v[12:13], v92 offset0:97 offset1:105
	ds_read2_b32 v[16:17], v92 offset0:162 offset1:170
	ds_read2_b32 v[18:19], v92 offset0:227 offset1:235
	s_waitcnt lgkmcnt(3)
	s_nop 1
	s_waitcnt lgkmcnt(2)
	s_nop 0
	ds_read2_b32 v[20:21], v30 offset0:36 offset1:44
	s_nop 1
	ds_read2_b32 v[22:23], v30 offset0:101 offset1:109
	v_cvt_pk_bf16_f32 v8, v14, v12
	s_waitcnt lgkmcnt(3)
	s_nop 1
	s_waitcnt lgkmcnt(2)
	s_nop 0
	ds_read2_b32 v[24:25], v30 offset0:166 offset1:174
	s_nop 1
	ds_read2_b32 v[26:27], v30 offset0:231 offset1:239
	v_cvt_pk_bf16_f32 v9, v16, v18
	s_waitcnt lgkmcnt(3)
	s_nop 1
	s_waitcnt lgkmcnt(2)
	s_nop 2
	v_cvt_pk_bf16_f32 v10, v20, v22
	s_waitcnt lgkmcnt(1)
	s_nop 0
	v_add_u32_e32 v28, 32, v6
	s_nop 0
	s_waitcnt lgkmcnt(0)
	s_nop 0
	v_ashrrev_i32_e32 v29, 31, v28
	s_nop 1
	v_lshlrev_b64 v[28:29], 12, v[28:29]
	v_cvt_pk_bf16_f32 v11, v24, v26
	v_lshl_add_u64 v[28:29], v[4:5], 0, v[28:29]
	s_nop 0
	global_store_dwordx4 v[28:29], v[8:11], off
	s_nop 3
	v_cvt_pk_bf16_f32 v8, v15, v13
	s_nop 4
	v_cvt_pk_bf16_f32 v9, v17, v19
	s_nop 4
	v_cvt_pk_bf16_f32 v10, v21, v23
	s_nop 0
	v_add_u32_e32 v12, 40, v6
	s_nop 1
	v_ashrrev_i32_e32 v13, 31, v12
	s_nop 1
	v_lshlrev_b64 v[12:13], 12, v[12:13]
	v_cvt_pk_bf16_f32 v11, v25, v27
	ds_read2_b32 v[14:15], v92 offset0:48 offset1:56
	v_lshl_add_u64 v[12:13], v[4:5], 0, v[12:13]
	global_store_dwordx4 v[12:13], v[8:11], off
	ds_read2_b32 v[12:13], v92 offset0:113 offset1:121
	ds_read2_b32 v[16:17], v92 offset0:178 offset1:186
	ds_read2_b32 v[18:19], v92 offset0:243 offset1:251
	s_waitcnt lgkmcnt(3)
	s_nop 1
	s_waitcnt lgkmcnt(2)
	s_nop 0
	ds_read2_b32 v[20:21], v30 offset0:52 offset1:60
	s_nop 1
	ds_read2_b32 v[22:23], v30 offset0:117 offset1:125
	v_cvt_pk_bf16_f32 v8, v14, v12
	s_waitcnt lgkmcnt(3)
	s_nop 1
	s_waitcnt lgkmcnt(2)
	s_nop 0
	ds_read2_b32 v[24:25], v30 offset0:182 offset1:190
	s_nop 1
	ds_read2_b32 v[26:27], v30 offset0:247 offset1:255
	v_cvt_pk_bf16_f32 v9, v16, v18
	s_waitcnt lgkmcnt(3)
	s_nop 1
	s_waitcnt lgkmcnt(2)
	s_nop 2
	v_cvt_pk_bf16_f32 v10, v20, v22
	s_waitcnt lgkmcnt(1)
	s_nop 0
	v_add_u32_e32 v28, 48, v6
	s_nop 0
	s_waitcnt lgkmcnt(0)
	s_nop 0
	v_ashrrev_i32_e32 v29, 31, v28
	s_nop 1
	v_lshlrev_b64 v[28:29], 12, v[28:29]
	v_cvt_pk_bf16_f32 v11, v24, v26
	v_lshl_add_u64 v[28:29], v[4:5], 0, v[28:29]
	s_nop 0
	global_store_dwordx4 v[28:29], v[8:11], off
	s_nop 3
	v_cvt_pk_bf16_f32 v8, v15, v13
	s_nop 4
	v_cvt_pk_bf16_f32 v9, v17, v19
	s_nop 4
	v_cvt_pk_bf16_f32 v10, v21, v23
	s_nop 4
	v_add_u32_e32 v6, 56, v6
	v_cvt_pk_bf16_f32 v11, v25, v27
	v_ashrrev_i32_e32 v7, 31, v6
	v_lshlrev_b64 v[6:7], 12, v[6:7]
	v_lshl_add_u64 v[4:5], v[4:5], 0, v[6:7]
	global_store_dwordx4 v[4:5], v[8:11], off
	s_waitcnt lgkmcnt(0)
	s_cbranch_scc0 .LBB0_4013

; #define LAS __attribute__((address_space(3)))
; #define LDS_WAIT() asm volatile("s_waitcnt lgkmcnt(0)" ::: "memory")
; __device__ __forceinline__ unsigned pk2(float lo, float hi) { return f2bf(lo) | (f2bf(hi) << 16); }
;     ...
;         for (int i = 0; i < 16; ++i) { LAS float* d = scr + (4 * i + kr) * 65 + nq; d[0] = v[i].x; d[1] = v[i].y; d[2] = v[i].z; d[3] = v[i].w; }
;         LDS_WAIT(); asm volatile("" ::: "memory");
;         const int c8 = lane & 7; int d0 = n0;
;         if (ffnmap) { const int bj = n0 >= FFH ? 1 : 0, chn = n0 - FFH * bj; d0 = 256 * (chn >> 7) + 128 * bj + (chn & 127); }
; #pragma unroll
;         for (int j = 0; j < 8; ++j) { const int n = (lane >> 3) + 8 * j; const LAS float* sp = scr + (8 * c8) * 65 + n;
;             v4u o; o.x = pk2(sp[0 * 65], sp[1 * 65]); o.y = pk2(sp[2 * 65], sp[3 * 65]); o.z = pk2(sp[4 * 65], sp[5 * 65]); o.w = pk2(sp[6 * 65], sp[7 * 65]);
;             *(v4u*)(WT + (size_t)(d0 + n) * K + k0 + 8 * c8) = o; }
.LBB0_4014:
	s_or_b64 exec, exec, s[6:7]
	s_waitcnt vmcnt(0)
	ds_write2_b32 v93, v4, v5 offset1:1
	ds_write2_b32 v93, v6, v7 offset0:2 offset1:3
	v_add_u32_e32 v4, 0x410, v93
	ds_write2_b32 v4, v12, v13 offset1:1
	v_add_u32_e32 v4, 0x418, v93
	ds_write2_b32 v4, v14, v15 offset1:1
	v_add_u32_e32 v4, 0x820, v93
	ds_write2_b32 v4, v8, v9 offset1:1
	v_add_u32_e32 v4, 0x828, v93
	ds_write2_b32 v4, v10, v11 offset1:1
	v_add_u32_e32 v4, 0xc30, v93
	ds_write2_b32 v4, v20, v21 offset1:1
	v_add_u32_e32 v4, 0xc38, v93
	ds_write2_b32 v4, v22, v23 offset1:1
	v_add_u32_e32 v4, 0x1040, v93
	ds_write2_b32 v4, v16, v17 offset1:1
	v_add_u32_e32 v4, 0x1048, v93
	ds_write2_b32 v4, v18, v19 offset1:1
	v_add_u32_e32 v4, 0x1450, v93
	ds_write2_b32 v4, v28, v29 offset1:1
	v_add_u32_e32 v4, 0x1458, v93
	ds_write2_b32 v4, v30, v31 offset1:1
	v_add_u32_e32 v4, 0x1860, v93
	ds_write2_b32 v4, v24, v25 offset1:1
	v_add_u32_e32 v4, 0x1868, v93
	ds_write2_b32 v4, v26, v27 offset1:1
	v_add_u32_e32 v4, 0x1c70, v93
	ds_write2_b32 v4, v36, v37 offset1:1
	v_add_u32_e32 v4, 0x1c78, v93
	ds_write2_b32 v4, v38, v39 offset1:1
	v_add_u32_e32 v4, 0x2080, v93
	ds_write2_b32 v4, v32, v33 offset1:1
	v_add_u32_e32 v4, 0x2088, v93
	ds_write2_b32 v4, v34, v35 offset1:1
	v_add_u32_e32 v4, 0x2490, v93
	ds_write2_b32 v4, v44, v45 offset1:1
	v_add_u32_e32 v4, 0x2498, v93
	ds_write2_b32 v4, v46, v47 offset1:1
	v_add_u32_e32 v4, 0x28a0, v93
	ds_write2_b32 v4, v40, v41 offset1:1
	v_add_u32_e32 v4, 0x28a8, v93
	ds_write2_b32 v4, v42, v43 offset1:1
	v_add_u32_e32 v4, 0x2cb0, v93
	ds_write2_b32 v4, v52, v53 offset1:1
	v_add_u32_e32 v4, 0x2cb8, v93
	ds_write2_b32 v4, v54, v55 offset1:1
	v_add_u32_e32 v4, 0x30c0, v93
	ds_write2_b32 v4, v48, v49 offset1:1
	v_add_u32_e32 v4, 0x30c8, v93
	ds_write2_b32 v4, v50, v51 offset1:1
	v_add_u32_e32 v4, 0x34d0, v93
	ds_write2_b32 v4, v60, v61 offset1:1
	v_add_u32_e32 v4, 0x34d8, v93
	ds_write2_b32 v4, v62, v63 offset1:1
	v_add_u32_e32 v4, 0x38e0, v93
	ds_write2_b32 v4, v56, v57 offset1:1
	v_add_u32_e32 v4, 0x38e8, v93
	ds_write2_b32 v4, v58, v59 offset1:1
	v_add_u32_e32 v4, 0x3cf0, v93
	ds_write2_b32 v4, v64, v65 offset1:1
	v_add_u32_e32 v4, 0x3cf8, v93
	ds_write2_b32 v4, v66, v67 offset1:1
	s_waitcnt lgkmcnt(0)
	ds_read2_b32 v[12:13], v92 offset1:8
	ds_read2_b32 v[14:15], v92 offset0:65 offset1:73
	ds_read2_b32 v[16:17], v92 offset0:130 offset1:138
	ds_read2_b32 v[18:19], v92 offset0:195 offset1:203
	v_add_u32_e32 v30, 0x400, v92
	s_waitcnt lgkmcnt(3)
	s_nop 1
	s_waitcnt lgkmcnt(2)
	s_nop 0
	ds_read2_b32 v[20:21], v30 offset0:4 offset1:12
	s_nop 1
	ds_read2_b32 v[22:23], v30 offset0:69 offset1:77
	v_cvt_pk_bf16_f32 v8, v12, v14
	s_waitcnt lgkmcnt(3)
	s_nop 1
	s_waitcnt lgkmcnt(2)
	s_nop 0
	ds_read2_b32 v[24:25], v30 offset0:134 offset1:142
	s_nop 1
	ds_read2_b32 v[26:27], v30 offset0:199 offset1:207
	v_cvt_pk_bf16_f32 v9, v16, v18
	s_waitcnt lgkmcnt(3)
	s_nop 1
	s_waitcnt lgkmcnt(2)
	s_nop 2
	v_cvt_pk_bf16_f32 v10, v20, v22
	s_waitcnt lgkmcnt(1)
	s_nop 1
	s_waitcnt lgkmcnt(0)
	s_nop 2
	s_add_i32 s17, s17, s11
	v_cvt_pk_bf16_f32 v11, v24, v26
	v_add_u32_e32 v6, s17, v82
	s_ashr_i32 s1, s0, 31
	v_ashrrev_i32_e32 v7, 31, v6
	v_lshl_add_u64 v[4:5], s[0:1], 1, v[74:75]
	v_lshlrev_b64 v[28:29], 12, v[6:7]
	v_lshl_add_u64 v[28:29], v[4:5], 0, v[28:29]
	s_nop 0
	global_store_dwordx4 v[28:29], v[8:11], off
	s_nop 3
	v_cvt_pk_bf16_f32 v8, v13, v15
	s_nop 4
	v_cvt_pk_bf16_f32 v9, v17, v19
	s_nop 4
	v_cvt_pk_bf16_f32 v10, v21, v23
	s_nop 0
	v_add_u32_e32 v12, 8, v6
	s_nop 1
	v_ashrrev_i32_e32 v13, 31, v12
	s_nop 1
	v_lshlrev_b64 v[12:13], 12, v[12:13]
	v_cvt_pk_bf16_f32 v11, v25, v27
	ds_read2_b32 v[14:15], v92 offset0:16 offset1:24
	v_lshl_add_u64 v[12:13], v[4:5], 0, v[12:13]
	global_store_dwordx4 v[12:13], v[8:11], off
	ds_read2_b32 v[12:13], v92 offset0:81 offset1:89
	ds_read2_b32 v[16:17], v92 offset0:146 offset1:154
	ds_read2_b32 v[18:19], v92 offset0:211 offset1:219
	s_waitcnt lgkmcnt(3)
	s_nop 1
	s_waitcnt lgkmcnt(2)
; #define LAS __attribute__((address_space(3)))
; #define LDS_WAIT() asm volatile("s_waitcnt lgkmcnt(0)" ::: "memory")
; __device__ __forceinline__ unsigned pk2(float lo, float hi) { return f2bf(lo) | (f2bf(hi) << 16); }
;     ...
;         for (int j = 0; j < 8; ++j) { const int n = (lane >> 3) + 8 * j; const LAS float* sp = scr + (8 * c8) * 65 + n;
;             v4u o; o.x = pk2(sp[0 * 65], sp[1 * 65]); o.y = pk2(sp[2 * 65], sp[3 * 65]); o.z = pk2(sp[4 * 65], sp[5 * 65]); o.w = pk2(sp[6 * 65], sp[7 * 65]);
;             *(v4u*)(WT + (size_t)(d0 + n) * K + k0 + 8 * c8) = o; }
;         LDS_WAIT(); asm volatile("" ::: "memory");
	s_nop 0
	ds_read2_b32 v[20:21], v30 offset0:20 offset1:28
	s_nop 1
	ds_read2_b32 v[22:23], v30 offset0:85 offset1:93
	v_cvt_pk_bf16_f32 v8, v14, v12
	s_waitcnt lgkmcnt(3)
	s_nop 1
	s_waitcnt lgkmcnt(2)
	s_nop 0
	ds_read2_b32 v[24:25], v30 offset0:150 offset1:158
	s_nop 1
	ds_read2_b32 v[26:27], v30 offset0:215 offset1:223
	v_cvt_pk_bf16_f32 v9, v16, v18
	s_waitcnt lgkmcnt(3)
	s_nop 1
	s_waitcnt lgkmcnt(2)
	s_nop 2
	v_cvt_pk_bf16_f32 v10, v20, v22
	s_waitcnt lgkmcnt(1)
	s_nop 0
	v_add_u32_e32 v28, 16, v6
	s_nop 0
	s_waitcnt lgkmcnt(0)
	s_nop 0
	v_ashrrev_i32_e32 v29, 31, v28
	s_nop 1
	v_lshlrev_b64 v[28:29], 12, v[28:29]
	v_cvt_pk_bf16_f32 v11, v24, v26
	v_lshl_add_u64 v[28:29], v[4:5], 0, v[28:29]
	s_nop 0
	global_store_dwordx4 v[28:29], v[8:11], off
	s_nop 3
	v_cvt_pk_bf16_f32 v8, v15, v13
	s_nop 4
	v_cvt_pk_bf16_f32 v9, v17, v19
	s_nop 4
	v_cvt_pk_bf16_f32 v10, v21, v23
	s_nop 0
	v_add_u32_e32 v12, 24, v6
	s_nop 1
	v_ashrrev_i32_e32 v13, 31, v12
	s_nop 1
	v_lshlrev_b64 v[12:13], 12, v[12:13]
	v_cvt_pk_bf16_f32 v11, v25, v27
	ds_read2_b32 v[14:15], v92 offset0:32 offset1:40
	v_lshl_add_u64 v[12:13], v[4:5], 0, v[12:13]
	global_store_dwordx4 v[12:13], v[8:11], off
	ds_read2_b32 v[12:13], v92 offset0:97 offset1:105
	ds_read2_b32 v[16:17], v92 offset0:162 offset1:170
	ds_read2_b32 v[18:19], v92 offset0:227 offset1:235
	s_waitcnt lgkmcnt(3)
	s_nop 1
	s_waitcnt lgkmcnt(2)
	s_nop 0
	ds_read2_b32 v[20:21], v30 offset0:36 offset1:44
	s_nop 1
	ds_read2_b32 v[22:23], v30 offset0:101 offset1:109
	v_cvt_pk_bf16_f32 v8, v14, v12
	s_waitcnt lgkmcnt(3)
	s_nop 1
	s_waitcnt lgkmcnt(2)
	s_nop 0
	ds_read2_b32 v[24:25], v30 offset0:166 offset1:174
	s_nop 1
	ds_read2_b32 v[26:27], v30 offset0:231 offset1:239
	v_cvt_pk_bf16_f32 v9, v16, v18
	s_waitcnt lgkmcnt(3)
	s_nop 1
	s_waitcnt lgkmcnt(2)
	s_nop 2
	v_cvt_pk_bf16_f32 v10, v20, v22
	s_waitcnt lgkmcnt(1)
	s_nop 0
	v_add_u32_e32 v28, 32, v6
	s_nop 0
	s_waitcnt lgkmcnt(0)
	s_nop 0
	v_ashrrev_i32_e32 v29, 31, v28
	s_nop 1
	v_lshlrev_b64 v[28:29], 12, v[28:29]
	v_cvt_pk_bf16_f32 v11, v24, v26
	v_lshl_add_u64 v[28:29], v[4:5], 0, v[28:29]
	s_nop 0
	global_store_dwordx4 v[28:29], v[8:11], off
	s_nop 3
	v_cvt_pk_bf16_f32 v8, v15, v13
	s_nop 4
	v_cvt_pk_bf16_f32 v9, v17, v19
	s_nop 4
	v_cvt_pk_bf16_f32 v10, v21, v23
	s_nop 0
	v_add_u32_e32 v12, 40, v6
	s_nop 1
	v_ashrrev_i32_e32 v13, 31, v12
	s_nop 1
	v_lshlrev_b64 v[12:13], 12, v[12:13]
	v_cvt_pk_bf16_f32 v11, v25, v27
	ds_read2_b32 v[14:15], v92 offset0:48 offset1:56
	v_lshl_add_u64 v[12:13], v[4:5], 0, v[12:13]
	global_store_dwordx4 v[12:13], v[8:11], off
	ds_read2_b32 v[12:13], v92 offset0:113 offset1:121
	ds_read2_b32 v[16:17], v92 offset0:178 offset1:186
	ds_read2_b32 v[18:19], v92 offset0:243 offset1:251
	s_waitcnt lgkmcnt(3)
	s_nop 1
	s_waitcnt lgkmcnt(2)
	s_nop 0
	ds_read2_b32 v[20:21], v30 offset0:52 offset1:60
	s_nop 1
	ds_read2_b32 v[22:23], v30 offset0:117 offset1:125
	v_cvt_pk_bf16_f32 v8, v14, v12
	s_waitcnt lgkmcnt(3)
	s_nop 1
	s_waitcnt lgkmcnt(2)
	s_nop 0
	ds_read2_b32 v[24:25], v30 offset0:182 offset1:190
	s_nop 1
	ds_read2_b32 v[26:27], v30 offset0:247 offset1:255
	v_cvt_pk_bf16_f32 v9, v16, v18
	s_waitcnt lgkmcnt(3)
	s_nop 1
	s_waitcnt lgkmcnt(2)
	s_nop 2
	v_cvt_pk_bf16_f32 v10, v20, v22
	s_waitcnt lgkmcnt(1)
	s_nop 0
	v_add_u32_e32 v28, 48, v6
	s_nop 0
	s_waitcnt lgkmcnt(0)
	s_nop 0
	v_ashrrev_i32_e32 v29, 31, v28
	s_nop 1
	v_lshlrev_b64 v[28:29], 12, v[28:29]
	v_cvt_pk_bf16_f32 v11, v24, v26
	v_lshl_add_u64 v[28:29], v[4:5], 0, v[28:29]
	s_nop 0
	global_store_dwordx4 v[28:29], v[8:11], off
	s_nop 3
	v_cvt_pk_bf16_f32 v8, v15, v13
	s_nop 4
	v_cvt_pk_bf16_f32 v9, v17, v19
	s_nop 4
	v_cvt_pk_bf16_f32 v10, v21, v23
	s_nop 4
	v_add_u32_e32 v6, 56, v6
	v_cvt_pk_bf16_f32 v11, v25, v27
	v_ashrrev_i32_e32 v7, 31, v6
	v_lshlrev_b64 v[6:7], 12, v[6:7]
	v_lshl_add_u64 v[4:5], v[4:5], 0, v[6:7]
	global_store_dwordx4 v[4:5], v[8:11], off
	s_waitcnt lgkmcnt(0)
	s_add_i32 s16, s16, s13
	s_add_i32 s11, s11, s14
	s_cmpk_lt_i32 s16, 0x400
	s_cbranch_scc0 .LBB0_4047

; #define LAS __attribute__((address_space(3)))
; #define LDS_WAIT() asm volatile("s_waitcnt lgkmcnt(0)" ::: "memory")
; __device__ __forceinline__ unsigned pk2(float lo, float hi) { return f2bf(lo) | (f2bf(hi) << 16); }
;     ...
;         for (int i = 0; i < 16; ++i) { LAS float* d = scr + (4 * i + kr) * 65 + nq; d[0] = v[i].x; d[1] = v[i].y; d[2] = v[i].z; d[3] = v[i].w; }
;         LDS_WAIT(); asm volatile("" ::: "memory");
;         const int c8 = lane & 7; int d0 = n0;
;         if (ffnmap) { const int bj = n0 >= FFH ? 1 : 0, chn = n0 - FFH * bj; d0 = 256 * (chn >> 7) + 128 * bj + (chn & 127); }
; #pragma unroll
;         for (int j = 0; j < 8; ++j) { const int n = (lane >> 3) + 8 * j; const LAS float* sp = scr + (8 * c8) * 65 + n;
;             v4u o; o.x = pk2(sp[0 * 65], sp[1 * 65]); o.y = pk2(sp[2 * 65], sp[3 * 65]); o.z = pk2(sp[4 * 65], sp[5 * 65]); o.w = pk2(sp[6 * 65], sp[7 * 65]);
;             *(v4u*)(WT + (size_t)(d0 + n) * K + k0 + 8 * c8) = o; }
.LBB0_4052:
	s_or_b64 exec, exec, s[10:11]
	s_waitcnt vmcnt(0)
	ds_write2_b32 v84, v8, v9 offset1:1
	ds_write2_b32 v84, v10, v11 offset0:2 offset1:3
	v_add_u32_e32 v8, 0x410, v84
	ds_write2_b32 v8, v4, v5 offset1:1
	v_add_u32_e32 v4, 0x418, v84
	ds_write2_b32 v4, v6, v7 offset1:1
	v_add_u32_e32 v4, 0x820, v84
	ds_write2_b32 v4, v16, v17 offset1:1
	v_add_u32_e32 v4, 0x828, v84
	ds_write2_b32 v4, v18, v19 offset1:1
	v_add_u32_e32 v4, 0xc30, v84
	ds_write2_b32 v4, v12, v13 offset1:1
	v_add_u32_e32 v4, 0xc38, v84
	ds_write2_b32 v4, v14, v15 offset1:1
	v_add_u32_e32 v4, 0x1040, v84
	ds_write2_b32 v4, v24, v25 offset1:1
	v_add_u32_e32 v4, 0x1048, v84
	ds_write2_b32 v4, v26, v27 offset1:1
	v_add_u32_e32 v4, 0x1450, v84
	ds_write2_b32 v4, v20, v21 offset1:1
	v_add_u32_e32 v4, 0x1458, v84
	ds_write2_b32 v4, v22, v23 offset1:1
	v_add_u32_e32 v4, 0x1860, v84
	ds_write2_b32 v4, v32, v33 offset1:1
	v_add_u32_e32 v4, 0x1868, v84
	ds_write2_b32 v4, v34, v35 offset1:1
	v_add_u32_e32 v4, 0x1c70, v84
	ds_write2_b32 v4, v28, v29 offset1:1
	v_add_u32_e32 v4, 0x1c78, v84
	ds_write2_b32 v4, v30, v31 offset1:1
	v_add_u32_e32 v4, 0x2080, v84
	ds_write2_b32 v4, v40, v41 offset1:1
	v_add_u32_e32 v4, 0x2088, v84
	ds_write2_b32 v4, v42, v43 offset1:1
	v_add_u32_e32 v4, 0x2490, v84
	ds_write2_b32 v4, v36, v37 offset1:1
	v_add_u32_e32 v4, 0x2498, v84
	ds_write2_b32 v4, v38, v39 offset1:1
	v_add_u32_e32 v4, 0x28a0, v84
	ds_write2_b32 v4, v48, v49 offset1:1
	v_add_u32_e32 v4, 0x28a8, v84
	ds_write2_b32 v4, v50, v51 offset1:1
	v_add_u32_e32 v4, 0x2cb0, v84
	ds_write2_b32 v4, v44, v45 offset1:1
	v_add_u32_e32 v4, 0x2cb8, v84
	ds_write2_b32 v4, v46, v47 offset1:1
	v_add_u32_e32 v4, 0x30c0, v84
	ds_write2_b32 v4, v56, v57 offset1:1
	v_add_u32_e32 v4, 0x30c8, v84
	ds_write2_b32 v4, v58, v59 offset1:1
	v_add_u32_e32 v4, 0x34d0, v84
	ds_write2_b32 v4, v52, v53 offset1:1
	v_add_u32_e32 v4, 0x34d8, v84
	ds_write2_b32 v4, v54, v55 offset1:1
	v_add_u32_e32 v4, 0x38e0, v84
	ds_write2_b32 v4, v64, v65 offset1:1
	v_add_u32_e32 v4, 0x38e8, v84
	ds_write2_b32 v4, v66, v67 offset1:1
	v_add_u32_e32 v4, 0x3cf0, v84
	ds_write2_b32 v4, v60, v61 offset1:1
	v_add_u32_e32 v4, 0x3cf8, v84
	ds_write2_b32 v4, v62, v63 offset1:1
	s_waitcnt lgkmcnt(0)
	ds_read2_b32 v[6:7], v73 offset1:65
	s_ashr_i32 s9, s8, 31
	v_lshl_add_u64 v[4:5], s[8:9], 1, v[76:77]
	s_add_i32 s8, s20, s6
	s_add_i32 s19, s19, s13
	s_waitcnt lgkmcnt(0)
	s_nop 1
	ds_read2_b32 v[8:9], v73 offset0:130 offset1:195
	s_nop 2
	v_cvt_pk_bf16_f32 v6, v6, v7
	s_waitcnt lgkmcnt(0)
	v_bfe_u32 v7, v8, 16, 1
	v_add3_u32 v7, v8, v7, s16
	v_add_u32_e32 v8, 0x400, v73
	ds_read2_b32 v[10:11], v8 offset0:4 offset1:69
	v_bfe_u32 v12, v9, 16, 1
	v_lshrrev_b32_e32 v7, 16, v7
	v_add3_u32 v9, v9, v12, s16
	ds_read2_b32 v[12:13], v8 offset0:134 offset1:199
	v_and_or_b32 v7, v9, s17, v7
	s_waitcnt lgkmcnt(1)
	s_nop 4
	v_cvt_pk_bf16_f32 v8, v10, v11
	s_waitcnt lgkmcnt(0)
	s_nop 4
	v_cvt_pk_bf16_f32 v9, v12, v13
	v_add_u32_e32 v10, s8, v82
	ds_read2_b32 v[12:13], v83 offset1:65
	v_ashrrev_i32_e32 v11, 31, v10
	v_lshlrev_b64 v[10:11], 10, v[10:11]
	v_lshl_add_u64 v[10:11], v[4:5], 0, v[10:11]
	global_store_dwordx4 v[10:11], v[6:9], off
	ds_read2_b32 v[8:9], v83 offset0:130 offset1:195
	s_add_i32 s6, s6, s15
	s_waitcnt lgkmcnt(1)
	s_nop 4
	v_cvt_pk_bf16_f32 v6, v12, v13
	s_waitcnt lgkmcnt(0)
	v_bfe_u32 v7, v8, 16, 1
	v_add3_u32 v7, v8, v7, s16
	v_add_u32_e32 v8, 0x400, v83
	ds_read2_b32 v[10:11], v8 offset0:4 offset1:69
	v_bfe_u32 v12, v9, 16, 1
	v_lshrrev_b32_e32 v7, 16, v7
	v_add3_u32 v9, v9, v12, s16
	ds_read2_b32 v[12:13], v8 offset0:134 offset1:199
	v_and_or_b32 v7, v9, s17, v7
	s_waitcnt lgkmcnt(1)
	s_nop 4
	v_cvt_pk_bf16_f32 v8, v10, v11
	s_waitcnt lgkmcnt(0)
	s_nop 4
	v_cvt_pk_bf16_f32 v9, v12, v13
	v_add_u32_e32 v10, s8, v85
	ds_read2_b32 v[12:13], v92 offset1:65
	v_ashrrev_i32_e32 v11, 31, v10
	v_lshlrev_b64 v[10:11], 10, v[10:11]
	v_lshl_add_u64 v[10:11], v[4:5], 0, v[10:11]
	global_store_dwordx4 v[10:11], v[6:9], off
	ds_read2_b32 v[8:9], v92 offset0:130 offset1:195
	s_cmp_lt_i32 s19, 64
	s_waitcnt lgkmcnt(1)
	s_nop 4
	v_cvt_pk_bf16_f32 v6, v12, v13
	s_waitcnt lgkmcnt(0)
	v_bfe_u32 v7, v8, 16, 1
	v_add3_u32 v7, v8, v7, s16
	v_add_u32_e32 v8, 0x400, v92
	ds_read2_b32 v[10:11], v8 offset0:4 offset1:69
	v_bfe_u32 v12, v9, 16, 1
	v_lshrrev_b32_e32 v7, 16, v7
	v_add3_u32 v9, v9, v12, s16
	ds_read2_b32 v[12:13], v8 offset0:134 offset1:199
	v_and_or_b32 v7, v9, s17, v7
	s_waitcnt lgkmcnt(1)
; #define LAS __attribute__((address_space(3)))
; #define LDS_WAIT() asm volatile("s_waitcnt lgkmcnt(0)" ::: "memory")
; __device__ __forceinline__ unsigned pk2(float lo, float hi) { return f2bf(lo) | (f2bf(hi) << 16); }
;     ...
;         for (int j = 0; j < 8; ++j) { const int n = (lane >> 3) + 8 * j; const LAS float* sp = scr + (8 * c8) * 65 + n;
;             v4u o; o.x = pk2(sp[0 * 65], sp[1 * 65]); o.y = pk2(sp[2 * 65], sp[3 * 65]); o.z = pk2(sp[4 * 65], sp[5 * 65]); o.w = pk2(sp[6 * 65], sp[7 * 65]);
;             *(v4u*)(WT + (size_t)(d0 + n) * K + k0 + 8 * c8) = o; }
;         LDS_WAIT(); asm volatile("" ::: "memory");
	s_nop 4
	v_cvt_pk_bf16_f32 v8, v10, v11
	s_waitcnt lgkmcnt(0)
	s_nop 4
	v_cvt_pk_bf16_f32 v9, v12, v13
	v_add_u32_e32 v10, s8, v86
	ds_read2_b32 v[12:13], v93 offset1:65
	v_ashrrev_i32_e32 v11, 31, v10
	v_lshlrev_b64 v[10:11], 10, v[10:11]
	v_lshl_add_u64 v[10:11], v[4:5], 0, v[10:11]
	global_store_dwordx4 v[10:11], v[6:9], off
	ds_read2_b32 v[8:9], v93 offset0:130 offset1:195
	s_waitcnt lgkmcnt(1)
	s_nop 4
	v_cvt_pk_bf16_f32 v6, v12, v13
	s_waitcnt lgkmcnt(0)
	v_bfe_u32 v7, v8, 16, 1
	v_add3_u32 v7, v8, v7, s16
	v_add_u32_e32 v8, 0x400, v93
	ds_read2_b32 v[10:11], v8 offset0:4 offset1:69
	v_bfe_u32 v12, v9, 16, 1
	v_lshrrev_b32_e32 v7, 16, v7
	v_add3_u32 v9, v9, v12, s16
	ds_read2_b32 v[12:13], v8 offset0:134 offset1:199
	v_and_or_b32 v7, v9, s17, v7
	s_waitcnt lgkmcnt(1)
	s_nop 4
	v_cvt_pk_bf16_f32 v8, v10, v11
	s_waitcnt lgkmcnt(0)
	s_nop 4
	v_cvt_pk_bf16_f32 v9, v12, v13
	v_add_u32_e32 v10, s8, v87
	ds_read2_b32 v[12:13], v94 offset1:65
	v_ashrrev_i32_e32 v11, 31, v10
	v_lshlrev_b64 v[10:11], 10, v[10:11]
	v_lshl_add_u64 v[10:11], v[4:5], 0, v[10:11]
	global_store_dwordx4 v[10:11], v[6:9], off
	ds_read2_b32 v[8:9], v94 offset0:130 offset1:195
	s_waitcnt lgkmcnt(1)
	s_nop 4
	v_cvt_pk_bf16_f32 v6, v12, v13
	s_waitcnt lgkmcnt(0)
	v_bfe_u32 v7, v8, 16, 1
	v_add3_u32 v7, v8, v7, s16
	v_add_u32_e32 v8, 0x400, v94
	ds_read2_b32 v[10:11], v8 offset0:4 offset1:69
	v_bfe_u32 v12, v9, 16, 1
	v_lshrrev_b32_e32 v7, 16, v7
	v_add3_u32 v9, v9, v12, s16
	ds_read2_b32 v[12:13], v8 offset0:134 offset1:199
	v_and_or_b32 v7, v9, s17, v7
	s_waitcnt lgkmcnt(1)
	s_nop 4
	v_cvt_pk_bf16_f32 v8, v10, v11
	s_waitcnt lgkmcnt(0)
	s_nop 4
	v_cvt_pk_bf16_f32 v9, v12, v13
	v_add_u32_e32 v10, s8, v88
	ds_read2_b32 v[12:13], v95 offset1:65
	v_ashrrev_i32_e32 v11, 31, v10
	v_lshlrev_b64 v[10:11], 10, v[10:11]
	v_lshl_add_u64 v[10:11], v[4:5], 0, v[10:11]
	global_store_dwordx4 v[10:11], v[6:9], off
	ds_read2_b32 v[8:9], v95 offset0:130 offset1:195
	s_waitcnt lgkmcnt(1)
	s_nop 4
	v_cvt_pk_bf16_f32 v6, v12, v13
	s_waitcnt lgkmcnt(0)
	v_bfe_u32 v7, v8, 16, 1
	v_add3_u32 v7, v8, v7, s16
	v_add_u32_e32 v8, 0x400, v95
	ds_read2_b32 v[10:11], v8 offset0:4 offset1:69
	v_bfe_u32 v12, v9, 16, 1
	v_lshrrev_b32_e32 v7, 16, v7
	v_add3_u32 v9, v9, v12, s16
	ds_read2_b32 v[12:13], v8 offset0:134 offset1:199
	v_and_or_b32 v7, v9, s17, v7
	s_waitcnt lgkmcnt(1)
	s_nop 4
	v_cvt_pk_bf16_f32 v8, v10, v11
	s_waitcnt lgkmcnt(0)
	s_nop 4
	v_cvt_pk_bf16_f32 v9, v12, v13
	v_add_u32_e32 v10, s8, v89
	ds_read2_b32 v[12:13], v96 offset1:65
	v_ashrrev_i32_e32 v11, 31, v10
	v_lshlrev_b64 v[10:11], 10, v[10:11]
	v_lshl_add_u64 v[10:11], v[4:5], 0, v[10:11]
	global_store_dwordx4 v[10:11], v[6:9], off
	ds_read2_b32 v[8:9], v96 offset0:130 offset1:195
	s_waitcnt lgkmcnt(1)
	s_nop 4
	v_cvt_pk_bf16_f32 v6, v12, v13
	s_waitcnt lgkmcnt(0)
	v_bfe_u32 v7, v8, 16, 1
	v_add3_u32 v7, v8, v7, s16
	v_add_u32_e32 v8, 0x400, v96
	ds_read2_b32 v[10:11], v8 offset0:4 offset1:69
	v_bfe_u32 v12, v9, 16, 1
	v_lshrrev_b32_e32 v7, 16, v7
	v_add3_u32 v9, v9, v12, s16
	ds_read2_b32 v[12:13], v8 offset0:134 offset1:199
	v_and_or_b32 v7, v9, s17, v7
	s_waitcnt lgkmcnt(1)
	s_nop 4
	v_cvt_pk_bf16_f32 v8, v10, v11
	s_waitcnt lgkmcnt(0)
	s_nop 4
	v_cvt_pk_bf16_f32 v9, v12, v13
	v_add_u32_e32 v10, s8, v90
	ds_read2_b32 v[12:13], v97 offset1:65
	v_ashrrev_i32_e32 v11, 31, v10
	v_lshlrev_b64 v[10:11], 10, v[10:11]
	v_lshl_add_u64 v[10:11], v[4:5], 0, v[10:11]
	global_store_dwordx4 v[10:11], v[6:9], off
	ds_read2_b32 v[8:9], v97 offset0:130 offset1:195
	s_waitcnt lgkmcnt(1)
	s_nop 4
	v_cvt_pk_bf16_f32 v6, v12, v13
	s_waitcnt lgkmcnt(0)
	v_bfe_u32 v7, v8, 16, 1
	v_add3_u32 v7, v8, v7, s16
	v_add_u32_e32 v8, 0x400, v97
	ds_read2_b32 v[10:11], v8 offset0:4 offset1:69
	v_bfe_u32 v12, v9, 16, 1
	v_lshrrev_b32_e32 v7, 16, v7
	v_add3_u32 v9, v9, v12, s16
	ds_read2_b32 v[12:13], v8 offset0:134 offset1:199
	v_and_or_b32 v7, v9, s17, v7
	s_waitcnt lgkmcnt(1)
	s_nop 4
	v_cvt_pk_bf16_f32 v8, v10, v11
	s_waitcnt lgkmcnt(0)
	s_nop 4
	v_cvt_pk_bf16_f32 v9, v12, v13
	v_add_u32_e32 v10, s8, v91
	v_ashrrev_i32_e32 v11, 31, v10
	v_lshlrev_b64 v[10:11], 10, v[10:11]
	v_lshl_add_u64 v[4:5], v[4:5], 0, v[10:11]
	global_store_dwordx4 v[4:5], v[6:9], off
	s_waitcnt lgkmcnt(0)
	s_cbranch_scc0 .LBB0_4049

; __device__ __forceinline__ unsigned pk2(float lo, float hi) { return f2bf(lo) | (f2bf(hi) << 16); }
; __device__ __forceinline__ void xa_attn_fa(const Ctx& c, const bf16* Q, const bf16* KV, const bf16* XVT, bf16* Oo) {
;     ...
; #pragma unroll
;         for (int mi = 0; mi < 2; ++mi) { float lt = l[mi]; lt += __shfl_xor(lt, 16); lt += __shfl_xor(lt, 32); const float il = 1.f / lt;
; #pragma unroll
;             for (int dt = 0; dt < 8; ++dt) { const f32x4 o = O[dt][mi] * il; v2u w; w.x = pk2(o[0], o[1]); w.y = pk2(o[2], o[3]);
;                 *(v2u*)(Oo + grow[mi] * 512 + hd * 128 + 16 * dt + 4 * lg) = w; } }
.LBB0_4141:
	v_mul_f32_e32 v4, 0x3e800000, v128
	ds_bpermute_b32 v4, v167, v4
	s_lshl_b32 s8, s21, 1
	v_lshl_add_u64 v[6:7], v[172:173], 0, s[8:9]
	v_lshl_add_u64 v[30:31], v[6:7], 0, v[188:189]
	v_mul_f32_e32 v52, 0x3e800000, v28
	s_waitcnt lgkmcnt(0)
	v_fmac_f32_e32 v4, 0x3e800000, v128
	ds_bpermute_b32 v29, v194, v4
	v_lshl_add_u64 v[6:7], v[6:7], 0, v[186:187]
	s_add_i32 s20, s20, s33
	s_cmpk_lt_i32 s20, 0x100
	s_waitcnt lgkmcnt(0)
	v_add_f32_e32 v4, v4, v29
	v_div_scale_f32 v29, s[10:11], v4, v4, 1.0
	v_rcp_f32_e32 v48, v29
	v_div_scale_f32 v49, vcc, 1.0, v4, 1.0
	v_fma_f32 v50, -v29, v48, 1.0
	v_fmac_f32_e32 v48, v50, v48
	v_mul_f32_e32 v50, v49, v48
	v_fma_f32 v51, -v29, v50, v49
	v_fmac_f32_e32 v50, v51, v48
	v_fma_f32 v29, -v29, v50, v49
	v_div_fmas_f32 v29, v29, v48, v50
	v_div_fixup_f32 v4, v29, v4, 1.0
	v_pk_mul_f32 v[50:51], v[120:121], v[4:5] op_sel_hi:[1,0]
	v_pk_mul_f32 v[48:49], v[122:123], v[4:5] op_sel_hi:[1,0]
	s_nop 4
	v_cvt_pk_bf16_f32 v50, v50, v51
	s_nop 4
	v_cvt_pk_bf16_f32 v51, v48, v49
	global_store_dwordx2 v[30:31], v[50:51], off
	v_pk_mul_f32 v[50:51], v[116:117], v[4:5] op_sel_hi:[1,0]
	v_pk_mul_f32 v[48:49], v[118:119], v[4:5] op_sel_hi:[1,0]
	s_nop 4
	v_cvt_pk_bf16_f32 v50, v50, v51
	s_nop 4
	v_cvt_pk_bf16_f32 v51, v48, v49
	global_store_dwordx2 v[30:31], v[50:51], off offset:32
	v_pk_mul_f32 v[50:51], v[112:113], v[4:5] op_sel_hi:[1,0]
	v_pk_mul_f32 v[48:49], v[114:115], v[4:5] op_sel_hi:[1,0]
	s_nop 4
	v_cvt_pk_bf16_f32 v50, v50, v51
	s_nop 4
	v_cvt_pk_bf16_f32 v51, v48, v49
	global_store_dwordx2 v[30:31], v[50:51], off offset:64
	v_pk_mul_f32 v[50:51], v[92:93], v[4:5] op_sel_hi:[1,0]
	v_pk_mul_f32 v[48:49], v[94:95], v[4:5] op_sel_hi:[1,0]
	s_nop 4
	v_cvt_pk_bf16_f32 v50, v50, v51
	s_nop 4
	v_cvt_pk_bf16_f32 v51, v48, v49
	global_store_dwordx2 v[30:31], v[50:51], off offset:96
	v_pk_mul_f32 v[50:51], v[88:89], v[4:5] op_sel_hi:[1,0]
	v_pk_mul_f32 v[48:49], v[90:91], v[4:5] op_sel_hi:[1,0]
	s_nop 4
	v_cvt_pk_bf16_f32 v50, v50, v51
	s_nop 4
	v_cvt_pk_bf16_f32 v51, v48, v49
	global_store_dwordx2 v[30:31], v[50:51], off offset:128
	v_pk_mul_f32 v[50:51], v[84:85], v[4:5] op_sel_hi:[1,0]
	v_pk_mul_f32 v[48:49], v[86:87], v[4:5] op_sel_hi:[1,0]
	s_nop 4
	v_cvt_pk_bf16_f32 v50, v50, v51
	s_nop 4
	v_cvt_pk_bf16_f32 v51, v48, v49
	global_store_dwordx2 v[30:31], v[50:51], off offset:160
	v_pk_mul_f32 v[50:51], v[64:65], v[4:5] op_sel_hi:[1,0]
	v_pk_mul_f32 v[48:49], v[66:67], v[4:5] op_sel_hi:[1,0]
	s_nop 4
	v_cvt_pk_bf16_f32 v50, v50, v51
	s_nop 4
	v_cvt_pk_bf16_f32 v51, v48, v49
	ds_bpermute_b32 v29, v167, v52
	v_pk_mul_f32 v[44:45], v[44:45], v[4:5] op_sel_hi:[1,0]
	v_pk_mul_f32 v[46:47], v[46:47], v[4:5] op_sel_hi:[1,0]
	s_nop 4
	s_waitcnt lgkmcnt(0)
	v_fmac_f32_e32 v29, 0x3e800000, v28
	v_cvt_pk_bf16_f32 v44, v44, v45
	ds_bpermute_b32 v4, v194, v29
	v_bfe_u32 v28, v46, 16, 1
	v_add3_u32 v28, v46, v28, s18
	v_bfe_u32 v45, v47, 16, 1
	v_lshrrev_b32_e32 v28, 16, v28
	s_waitcnt lgkmcnt(0)
	v_add_f32_e32 v4, v29, v4
	v_div_scale_f32 v29, s[10:11], v4, v4, 1.0
	v_rcp_f32_e32 v46, v29
	v_add3_u32 v45, v47, v45, s18
	v_and_or_b32 v45, v45, s19, v28
	global_store_dwordx2 v[30:31], v[50:51], off offset:192
	v_fma_f32 v28, -v29, v46, 1.0
	v_fmac_f32_e32 v46, v28, v46
	v_div_scale_f32 v28, vcc, 1.0, v4, 1.0
	global_store_dwordx2 v[30:31], v[44:45], off offset:224
	v_mul_f32_e32 v30, v28, v46
	v_fma_f32 v31, -v29, v30, v28
	v_fmac_f32_e32 v30, v31, v46
	v_fma_f32 v28, -v29, v30, v28
	v_div_fmas_f32 v28, v28, v46, v30
	v_div_fixup_f32 v4, v28, v4, 1.0
	v_pk_mul_f32 v[30:31], v[40:41], v[4:5] op_sel_hi:[1,0]
	v_pk_mul_f32 v[28:29], v[42:43], v[4:5] op_sel_hi:[1,0]
	s_nop 4
	v_cvt_pk_bf16_f32 v30, v30, v31
	s_nop 4
	v_cvt_pk_bf16_f32 v31, v28, v29
	global_store_dwordx2 v[6:7], v[30:31], off
	v_pk_mul_f32 v[30:31], v[36:37], v[4:5] op_sel_hi:[1,0]
	v_pk_mul_f32 v[28:29], v[38:39], v[4:5] op_sel_hi:[1,0]
	s_nop 4
	v_cvt_pk_bf16_f32 v30, v30, v31
	s_nop 4
	v_cvt_pk_bf16_f32 v31, v28, v29
	global_store_dwordx2 v[6:7], v[30:31], off offset:32
	v_pk_mul_f32 v[30:31], v[32:33], v[4:5] op_sel_hi:[1,0]
	v_pk_mul_f32 v[28:29], v[34:35], v[4:5] op_sel_hi:[1,0]
	s_nop 4
	v_cvt_pk_bf16_f32 v30, v30, v31
	s_nop 4
	v_pk_mul_f32 v[24:25], v[24:25], v[4:5] op_sel_hi:[1,0]
	v_cvt_pk_bf16_f32 v31, v28, v29
	s_nop 2
	v_pk_mul_f32 v[26:27], v[26:27], v[4:5] op_sel_hi:[1,0]
	s_nop 1
	v_cvt_pk_bf16_f32 v24, v24, v25
	s_nop 4
	v_cvt_pk_bf16_f32 v25, v26, v27
	v_pk_mul_f32 v[20:21], v[20:21], v[4:5] op_sel_hi:[1,0]
	global_store_dwordx2 v[6:7], v[24:25], off offset:96
	s_nop 2
	v_pk_mul_f32 v[22:23], v[22:23], v[4:5] op_sel_hi:[1,0]
	s_nop 1
	v_cvt_pk_bf16_f32 v20, v20, v21
	s_nop 4
	v_cvt_pk_bf16_f32 v21, v22, v23
	v_pk_mul_f32 v[16:17], v[16:17], v[4:5] op_sel_hi:[1,0]
	global_store_dwordx2 v[6:7], v[20:21], off offset:128
	s_nop 2
	v_pk_mul_f32 v[18:19], v[18:19], v[4:5] op_sel_hi:[1,0]
	s_nop 1
	v_cvt_pk_bf16_f32 v16, v16, v17
	s_nop 4
	v_cvt_pk_bf16_f32 v17, v18, v19
	v_pk_mul_f32 v[12:13], v[12:13], v[4:5] op_sel_hi:[1,0]
	v_pk_mul_f32 v[8:9], v[8:9], v[4:5] op_sel_hi:[1,0]
	global_store_dwordx2 v[6:7], v[16:17], off offset:160
	v_pk_mul_f32 v[14:15], v[14:15], v[4:5] op_sel_hi:[1,0]
	s_nop 0
	v_pk_mul_f32 v[10:11], v[10:11], v[4:5] op_sel_hi:[1,0]
	s_nop 7
	s_nop 0
	v_cvt_pk_bf16_f32 v12, v12, v13
	s_nop 0
	v_cvt_pk_bf16_f32 v8, v8, v9
	v_bfe_u32 v4, v10, 16, 1
	s_nop 1
	v_add3_u32 v4, v10, v4, s18
	v_bfe_u32 v9, v11, 16, 1
	s_nop 1
	v_lshrrev_b32_e32 v4, 16, v4
	v_add3_u32 v9, v11, v9, s18
	v_cvt_pk_bf16_f32 v13, v14, v15
	v_and_or_b32 v9, v9, s19, v4
	global_store_dwordx2 v[6:7], v[30:31], off offset:64
	global_store_dwordx2 v[6:7], v[12:13], off offset:192
	global_store_dwordx2 v[6:7], v[8:9], off offset:224
	s_cbranch_scc0 .LBB0_4153

; __device__ __forceinline__ unsigned pk2(float lo, float hi) { return f2bf(lo) | (f2bf(hi) << 16); }
; __device__ __forceinline__ float silu_fast(float x) { return x * __builtin_amdgcn_rcpf(1.f + __builtin_amdgcn_exp2f(-1.4426950408889634f * x)); }
; __device__ __forceinline__ float dpp_shr1(float x) { return __builtin_bit_cast(float, __builtin_amdgcn_update_dpp(0, __builtin_bit_cast(int, x), 0x111, 0xf, 0xf, true)); }
;     __device__ __forceinline__ void operator()(const f32x4 (&acc)[2][2][4][2], const pg8::Unit& u, int wr, int wc, int fr, int fq) const {
;     ...
;             const int cc = ch0 + 4 * n;
;             const f32x4 wg0 = *(CF4)(cw + cc), wg1 = *(CF4)(cw + FF2 + cc), wg2 = *(CF4)(cw + 2 * FF2 + cc), wv0 = *(CF4)(cw + FFH + cc), wv1 = *(CF4)(cw + FF2 + FFH + cc), wv2 = *(CF4)(cw + 2 * FF2 + FFH + cc);
;             const f32x4 bg = *(CF4)(cb + cc), bv = *(CF4)(cb + FFH + cc);
; #pragma unroll
;             for (int jj = 0; jj < 4; ++jj) {
;                 float g2 = dpp_shr1(g[6][jj]), g1 = dpp_shr1(g[7][jj]), v2 = dpp_shr1(v[6][jj]), v1 = dpp_shr1(v[7][jj]);
; #pragma unroll
;                 for (int e = 0; e < 8; ++e) { const float g0 = g[e][jj], v0 = v[e][jj];
;                     const float cg = bg[jj] + wg0[jj] * g2 + wg1[jj] * g1 + wg2[jj] * g0, cv = bv[jj] + wv0[jj] * v2 + wv1[jj] * v1 + wv2[jj] * v0;
;                     g[e][jj] = silu_fast(cg) * cv; g2 = g1; g1 = g0; v2 = v1; v1 = v0; } }
; #pragma unroll
;             for (int e = 0; e < 8; ++e) { v2u w; w.x = pk2(g[e][0], g[e][1]); w.y = pk2(g[e][2], g[e][3]); *(v2u*)(ACT + (size_t)(tok0 + e) * FFH + cc) = w; }
.LBB0_4346:
	s_or_b64 exec, exec, s[34:35]
	v_or_b32_e32 v38, 4, v132
	v_ashrrev_i32_e32 v39, 31, v38
	v_lshlrev_b64 v[64:65], 2, v[38:39]
	v_lshl_add_u64 v[38:39], s[6:7], 0, v[64:65]
	v_lshl_add_u64 v[44:45], s[18:19], 0, v[64:65]
	v_lshl_add_u64 v[66:67], s[8:9], 0, v[64:65]
	global_load_dwordx4 v[52:55], v[38:39], off
	v_lshl_add_u64 v[48:49], s[20:21], 0, v[64:65]
	global_load_dwordx4 v[44:47], v[44:45], off
	v_lshl_add_u64 v[38:39], s[12:13], 0, v[64:65]
	global_load_dwordx4 v[68:71], v[66:67], off
	global_load_dwordx4 v[56:59], v[38:39], off
	v_mov_b32_dpp v106, v88 row_shr:1 row_mask:0xf bank_mask:0xf bound_ctrl:1
	global_load_dwordx4 v[48:51], v[48:49], off
	v_lshl_add_u64 v[38:39], s[14:15], 0, v[64:65]
	global_load_dwordx4 v[60:63], v[38:39], off
	v_lshl_add_u64 v[38:39], s[16:17], 0, v[64:65]
	global_load_dwordx4 v[38:41], v[38:39], off
	v_lshl_add_u64 v[64:65], s[22:23], 0, v[64:65]
	global_load_dwordx4 v[64:67], v[64:65], off
	v_mov_b32_dpp v107, v89 row_shr:1 row_mask:0xf bank_mask:0xf bound_ctrl:1
	v_mov_b32_dpp v138, v94 row_shr:1 row_mask:0xf bank_mask:0xf bound_ctrl:1
	v_mov_b32_dpp v139, v95 row_shr:1 row_mask:0xf bank_mask:0xf bound_ctrl:1
	v_mov_b32_dpp v160, v86 row_shr:1 row_mask:0xf bank_mask:0xf bound_ctrl:1
	v_mov_b32_dpp v161, v87 row_shr:1 row_mask:0xf bank_mask:0xf bound_ctrl:1
	v_mov_b32_dpp v136, v90 row_shr:1 row_mask:0xf bank_mask:0xf bound_ctrl:1
	v_mov_b32_dpp v137, v91 row_shr:1 row_mask:0xf bank_mask:0xf bound_ctrl:1
	v_mov_b32_dpp v158, v82 row_shr:1 row_mask:0xf bank_mask:0xf bound_ctrl:1
	v_mov_b32_dpp v162, v72 row_shr:1 row_mask:0xf bank_mask:0xf bound_ctrl:1
	v_mov_b32_dpp v159, v83 row_shr:1 row_mask:0xf bank_mask:0xf bound_ctrl:1
	v_mov_b32_dpp v163, v73 row_shr:1 row_mask:0xf bank_mask:0xf bound_ctrl:1
	v_mov_b32_dpp v134, v84 row_shr:1 row_mask:0xf bank_mask:0xf bound_ctrl:1
	v_mov_b32_dpp v132, v74 row_shr:1 row_mask:0xf bank_mask:0xf bound_ctrl:1
	v_mov_b32_dpp v135, v85 row_shr:1 row_mask:0xf bank_mask:0xf bound_ctrl:1
	v_mov_b32_dpp v133, v75 row_shr:1 row_mask:0xf bank_mask:0xf bound_ctrl:1
	s_andn2_b64 vcc, exec, s[0:1]
	s_mov_b32 s61, s24
	s_mov_b32 s34, s26
	s_mov_b64 s[38:39], s[30:31]
	s_mov_b64 s[36:37], s[28:29]
	s_waitcnt vmcnt(0)
	v_mov_b32_e32 v98, v52
	v_mov_b32_e32 v99, v54
	v_mov_b32_e32 v54, v53
	v_mov_b32_e32 v102, v68
	v_mov_b32_e32 v103, v70
	v_pk_fma_f32 v[110:111], v[98:99], v[106:107], v[102:103]
	v_mov_b32_e32 v106, v56
	v_mov_b32_e32 v107, v58
	v_pk_fma_f32 v[168:169], v[106:107], v[138:139], v[110:111]
	v_mov_b32_e32 v110, v60
	v_mov_b32_e32 v111, v62
	v_pk_fma_f32 v[168:169], v[130:131], v[110:111], v[168:169]
	v_mov_b32_e32 v70, v69
	v_mul_f32_e32 v52, 0xbfb8aa3b, v168
	v_exp_f32_e32 v52, v52
	v_mov_b32_e32 v58, v57
	v_mov_b32_e32 v62, v61
	v_mov_b32_e32 v60, v44
	v_add_f32_e32 v52, 1.0, v52
	v_rcp_f32_e32 v170, v52
	v_pk_fma_f32 v[52:53], v[54:55], v[160:161], v[70:71]
	v_mov_b32_e32 v56, v64
	v_pk_fma_f32 v[52:53], v[58:59], v[136:137], v[52:53]
	v_mov_b32_e32 v57, v66
	v_pk_fma_f32 v[160:161], v[126:127], v[62:63], v[52:53]
	v_mov_b32_e32 v53, v40
	v_mul_f32_e32 v52, 0xbfb8aa3b, v160
	v_exp_f32_e32 v52, v52
	v_mul_f32_e32 v44, 0xbfb8aa3b, v161
	v_exp_f32_e32 v44, v44
	v_mov_b32_e32 v40, v39
	v_add_f32_e32 v52, 1.0, v52
	v_rcp_f32_e32 v172, v52
	v_mov_b32_e32 v52, v38
	v_mul_f32_e32 v38, 0xbfb8aa3b, v169
	v_exp_f32_e32 v38, v38
	v_add_f32_e32 v44, 1.0, v44
	v_rcp_f32_e32 v173, v44
	v_mov_b32_e32 v66, v65
	v_add_f32_e32 v38, 1.0, v38
	v_pk_fma_f32 v[68:69], v[52:53], v[158:159], v[56:57]
	v_mov_b32_e32 v61, v46
	v_rcp_f32_e32 v171, v38
	v_pk_fma_f32 v[38:39], v[40:41], v[162:163], v[66:67]
	v_mov_b32_e32 v46, v45
	v_pk_fma_f32 v[158:159], v[60:61], v[134:135], v[68:69]
	v_mov_b32_e32 v69, v50
	v_pk_fma_f32 v[38:39], v[46:47], v[132:133], v[38:39]
	v_mov_b32_e32 v50, v49
	v_pk_fma_f32 v[38:39], v[122:123], v[50:51], v[38:39]
	v_pk_mul_f32 v[44:45], v[160:161], v[172:173]
	v_mov_b32_e32 v68, v48
	v_pk_mul_f32 v[38:39], v[38:39], v[44:45]
	v_pk_fma_f32 v[158:159], v[124:125], v[68:69], v[158:159]
	v_pk_mul_f32 v[168:169], v[168:169], v[170:171]
	s_nop 1
	v_pk_mul_f32 v[158:159], v[158:159], v[168:169]
	s_nop 1
	v_pk_fma_f32 v[48:49], v[54:55], v[136:137], v[70:71]
	s_nop 0
	v_pk_fma_f32 v[48:49], v[126:127], v[58:59], v[48:49]
	s_nop 1
	v_pk_fma_f32 v[48:49], v[118:119], v[62:63], v[48:49]
	s_nop 0
	v_cvt_pk_bf16_f32 v38, v158, v38
	v_mul_f32_e32 v45, 0xbfb8aa3b, v48
	s_nop 1
	v_exp_f32_e32 v45, v45
	v_cvt_pk_bf16_f32 v39, v159, v39
	global_store_dwordx2 v[112:113], v[38:39], off offset:8
	v_pk_fma_f32 v[38:39], v[98:99], v[138:139], v[102:103]
	v_add_f32_e32 v45, 1.0, v45
	v_pk_fma_f32 v[38:39], v[130:131], v[106:107], v[38:39]
	v_rcp_f32_e32 v64, v45
	v_pk_fma_f32 v[38:39], v[114:115], v[110:111], v[38:39]
	v_mul_f32_e32 v65, 0xbfb8aa3b, v49
	v_mul_f32_e32 v44, 0xbfb8aa3b, v38
	v_mul_f32_e32 v45, 0xbfb8aa3b, v39
	v_exp_f32_e32 v44, v44
	v_exp_f32_e32 v45, v45
	v_exp_f32_e32 v65, v65
	v_pk_fma_f32 v[112:113], v[52:53], v[134:135], v[56:57]
	v_add_f32_e32 v44, 1.0, v44
	v_add_f32_e32 v45, 1.0, v45
	v_rcp_f32_e32 v44, v44
	v_rcp_f32_e32 v45, v45
	v_add_f32_e32 v65, 1.0, v65
	v_rcp_f32_e32 v65, v65
	v_pk_fma_f32 v[112:113], v[124:125], v[60:61], v[112:113]
	v_pk_mul_f32 v[38:39], v[38:39], v[44:45]
	v_pk_fma_f32 v[44:45], v[40:41], v[132:133], v[66:67]
	v_pk_fma_f32 v[112:113], v[116:117], v[68:69], v[112:113]
	v_pk_fma_f32 v[44:45], v[122:123], v[46:47], v[44:45]
	v_pk_mul_f32 v[38:39], v[112:113], v[38:39]
	v_pk_fma_f32 v[44:45], v[120:121], v[50:51], v[44:45]
	v_pk_mul_f32 v[48:49], v[48:49], v[64:65]
	s_nop 0
	v_pk_mul_f32 v[44:45], v[44:45], v[48:49]
	s_nop 7
; __device__ __forceinline__ unsigned pk2(float lo, float hi) { return f2bf(lo) | (f2bf(hi) << 16); }
; __device__ __forceinline__ float silu_fast(float x) { return x * __builtin_amdgcn_rcpf(1.f + __builtin_amdgcn_exp2f(-1.4426950408889634f * x)); }
; __device__ __forceinline__ float dpp_shr1(float x) { return __builtin_bit_cast(float, __builtin_amdgcn_update_dpp(0, __builtin_bit_cast(int, x), 0x111, 0xf, 0xf, true)); }
;     __device__ __forceinline__ void operator()(const f32x4 (&acc)[2][2][4][2], const pg8::Unit& u, int wr, int wc, int fr, int fq) const {
;     ...
; #pragma unroll
;             for (int jj = 0; jj < 4; ++jj) {
;                 float g2 = dpp_shr1(g[6][jj]), g1 = dpp_shr1(g[7][jj]), v2 = dpp_shr1(v[6][jj]), v1 = dpp_shr1(v[7][jj]);
; #pragma unroll
;                 for (int e = 0; e < 8; ++e) { const float g0 = g[e][jj], v0 = v[e][jj];
;                     const float cg = bg[jj] + wg0[jj] * g2 + wg1[jj] * g1 + wg2[jj] * g0, cv = bv[jj] + wv0[jj] * v2 + wv1[jj] * v1 + wv2[jj] * v0;
;                     g[e][jj] = silu_fast(cg) * cv; g2 = g1; g1 = g0; v2 = v1; v1 = v0; } }
; #pragma unroll
;             for (int e = 0; e < 8; ++e) { v2u w; w.x = pk2(g[e][0], g[e][1]); w.y = pk2(g[e][2], g[e][3]); *(v2u*)(ACT + (size_t)(tok0 + e) * FFH + cc) = w; }
	s_nop 1
	v_cvt_pk_bf16_f32 v39, v39, v45
	v_cvt_pk_bf16_f32 v38, v38, v44
	v_mov_b32_e32 v44, v33
	v_mov_b32_e32 v45, v35
	v_mov_b32_e32 v33, v34
	v_pk_fma_f32 v[34:35], v[126:127], v[54:55], v[70:71]
	v_pk_mul_f32 v[44:45], v[44:45], v[128:129]
	v_pk_fma_f32 v[34:35], v[118:119], v[58:59], v[34:35]
	global_store_dwordx2 v[108:109], v[38:39], off offset:8
	v_pk_fma_f32 v[34:35], v[44:45], v[62:63], v[34:35]
	v_mov_b32_e32 v39, v31
	v_mul_f32_e32 v31, 0xbfb8aa3b, v34
	v_exp_f32_e32 v31, v31
	v_mov_b32_e32 v38, v29
	v_mov_b32_e32 v29, v30
	v_pk_mul_f32 v[48:49], v[28:29], v[128:129]
	v_pk_fma_f32 v[28:29], v[130:131], v[98:99], v[102:103]
	v_pk_mul_f32 v[32:33], v[32:33], v[128:129]
	v_pk_fma_f32 v[28:29], v[114:115], v[106:107], v[28:29]
	v_add_f32_e32 v31, 1.0, v31
	v_pk_fma_f32 v[28:29], v[32:33], v[110:111], v[28:29]
	v_rcp_f32_e32 v64, v31
	v_mul_f32_e32 v30, 0xbfb8aa3b, v28
	v_mul_f32_e32 v31, 0xbfb8aa3b, v29
	v_exp_f32_e32 v30, v30
	v_exp_f32_e32 v31, v31
	v_mul_f32_e32 v65, 0xbfb8aa3b, v35
	v_exp_f32_e32 v65, v65
	v_add_f32_e32 v30, 1.0, v30
	v_add_f32_e32 v31, 1.0, v31
	v_rcp_f32_e32 v30, v30
	v_rcp_f32_e32 v31, v31
	v_add_f32_e32 v65, 1.0, v65
	v_rcp_f32_e32 v65, v65
	v_pk_fma_f32 v[108:109], v[124:125], v[52:53], v[56:57]
	v_pk_mul_f32 v[28:29], v[28:29], v[30:31]
	v_pk_fma_f32 v[108:109], v[116:117], v[60:61], v[108:109]
	v_pk_fma_f32 v[30:31], v[122:123], v[40:41], v[66:67]
	v_pk_mul_f32 v[38:39], v[38:39], v[128:129]
	v_pk_fma_f32 v[108:109], v[48:49], v[68:69], v[108:109]
	v_pk_fma_f32 v[30:31], v[120:121], v[46:47], v[30:31]
	v_pk_mul_f32 v[28:29], v[108:109], v[28:29]
	v_pk_fma_f32 v[30:31], v[38:39], v[50:51], v[30:31]
	v_pk_mul_f32 v[34:35], v[34:35], v[64:65]
	s_nop 0
	v_pk_mul_f32 v[30:31], v[30:31], v[34:35]
	s_nop 7
	s_nop 1
	v_cvt_pk_bf16_f32 v29, v29, v31
	v_cvt_pk_bf16_f32 v28, v28, v30
	v_mov_b32_e32 v30, v25
	v_mov_b32_e32 v31, v27
	v_pk_fma_f32 v[34:35], v[118:119], v[54:55], v[70:71]
	v_pk_mul_f32 v[30:31], v[30:31], v[42:43]
	v_pk_fma_f32 v[34:35], v[44:45], v[58:59], v[34:35]
	v_mov_b32_e32 v25, v26
	v_pk_fma_f32 v[34:35], v[30:31], v[62:63], v[34:35]
	global_store_dwordx2 v[104:105], v[28:29], off offset:8
	v_mul_f32_e32 v65, 0xbfb8aa3b, v34
	v_exp_f32_e32 v65, v65
	v_mov_b32_e32 v28, v21
	v_mov_b32_e32 v29, v23
	v_mov_b32_e32 v21, v22
	v_pk_mul_f32 v[22:23], v[24:25], v[42:43]
	v_pk_fma_f32 v[24:25], v[114:115], v[98:99], v[102:103]
	v_add_f32_e32 v65, 1.0, v65
	v_pk_fma_f32 v[24:25], v[32:33], v[106:107], v[24:25]
	v_rcp_f32_e32 v104, v65
	v_pk_fma_f32 v[24:25], v[22:23], v[110:111], v[24:25]
	v_pk_fma_f32 v[26:27], v[116:117], v[52:53], v[56:57]
	v_mul_f32_e32 v64, 0xbfb8aa3b, v24
	v_mul_f32_e32 v65, 0xbfb8aa3b, v25
	v_exp_f32_e32 v64, v64
	v_exp_f32_e32 v65, v65
	v_pk_mul_f32 v[20:21], v[20:21], v[42:43]
	v_pk_fma_f32 v[26:27], v[48:49], v[60:61], v[26:27]
	v_add_f32_e32 v64, 1.0, v64
	v_add_f32_e32 v65, 1.0, v65
	v_rcp_f32_e32 v64, v64
	v_rcp_f32_e32 v65, v65
	v_pk_mul_f32 v[28:29], v[28:29], v[42:43]
	v_pk_fma_f32 v[42:43], v[120:121], v[40:41], v[66:67]
	v_pk_fma_f32 v[26:27], v[20:21], v[68:69], v[26:27]
	v_pk_mul_f32 v[24:25], v[24:25], v[64:65]
	s_nop 0
	v_pk_mul_f32 v[24:25], v[26:27], v[24:25]
	v_pk_fma_f32 v[26:27], v[38:39], v[46:47], v[42:43]
	v_mul_f32_e32 v42, 0xbfb8aa3b, v35
	v_exp_f32_e32 v42, v42
	v_pk_fma_f32 v[26:27], v[28:29], v[50:51], v[26:27]
	v_add_f32_e32 v42, 1.0, v42
	v_rcp_f32_e32 v105, v42
	s_nop 0
	v_pk_mul_f32 v[34:35], v[34:35], v[104:105]
	s_nop 0
	v_pk_mul_f32 v[26:27], v[26:27], v[34:35]
	s_nop 7
	s_nop 1
	v_cvt_pk_bf16_f32 v25, v25, v27
	v_cvt_pk_bf16_f32 v24, v24, v26
	v_mov_b32_e32 v26, v17
	v_mov_b32_e32 v27, v19
	v_mov_b32_e32 v17, v18
	v_pk_fma_f32 v[18:19], v[44:45], v[54:55], v[70:71]
	v_pk_mul_f32 v[26:27], v[26:27], v[92:93]
	v_pk_fma_f32 v[18:19], v[30:31], v[58:59], v[18:19]
	global_store_dwordx2 v[100:101], v[24:25], off offset:8
	v_mov_b32_e32 v24, v13
	v_mov_b32_e32 v13, v14
	v_pk_fma_f32 v[18:19], v[26:27], v[62:63], v[18:19]
	v_pk_mul_f32 v[34:35], v[12:13], v[92:93]
	v_pk_fma_f32 v[12:13], v[32:33], v[98:99], v[102:103]
	v_pk_fma_f32 v[32:33], v[38:39], v[40:41], v[66:67]
	v_mul_f32_e32 v39, 0xbfb8aa3b, v18
	v_exp_f32_e32 v39, v39
	v_pk_mul_f32 v[16:17], v[16:17], v[92:93]
	v_pk_fma_f32 v[12:13], v[22:23], v[106:107], v[12:13]
	v_mov_b32_e32 v25, v15
	v_pk_fma_f32 v[12:13], v[16:17], v[110:111], v[12:13]
	v_add_f32_e32 v39, 1.0, v39
	v_mul_f32_e32 v38, 0xbfb8aa3b, v12
	v_rcp_f32_e32 v42, v39
	v_mul_f32_e32 v39, 0xbfb8aa3b, v13
	v_exp_f32_e32 v38, v38
	v_exp_f32_e32 v39, v39
	v_pk_fma_f32 v[14:15], v[48:49], v[52:53], v[56:57]
	v_pk_mul_f32 v[24:25], v[24:25], v[92:93]
	v_add_f32_e32 v38, 1.0, v38
	v_add_f32_e32 v39, 1.0, v39
	v_rcp_f32_e32 v38, v38
	v_rcp_f32_e32 v39, v39
	v_pk_fma_f32 v[14:15], v[20:21], v[60:61], v[14:15]
	v_pk_mul_f32 v[12:13], v[12:13], v[38:39]
	v_pk_fma_f32 v[14:15], v[34:35], v[68:69], v[14:15]
	s_nop 0
	v_pk_mul_f32 v[12:13], v[14:15], v[12:13]
	v_pk_fma_f32 v[14:15], v[28:29], v[46:47], v[32:33]
	v_mul_f32_e32 v32, 0xbfb8aa3b, v19
	v_exp_f32_e32 v32, v32
	v_pk_fma_f32 v[14:15], v[24:25], v[50:51], v[14:15]
	v_add_f32_e32 v32, 1.0, v32
	v_rcp_f32_e32 v43, v32
	s_nop 0
	v_pk_mul_f32 v[18:19], v[18:19], v[42:43]
	s_nop 0
	v_pk_mul_f32 v[14:15], v[14:15], v[18:19]
; __device__ __forceinline__ unsigned pk2(float lo, float hi) { return f2bf(lo) | (f2bf(hi) << 16); }
; __device__ __forceinline__ float silu_fast(float x) { return x * __builtin_amdgcn_rcpf(1.f + __builtin_amdgcn_exp2f(-1.4426950408889634f * x)); }
; __device__ __forceinline__ float dpp_shr1(float x) { return __builtin_bit_cast(float, __builtin_amdgcn_update_dpp(0, __builtin_bit_cast(int, x), 0x111, 0xf, 0xf, true)); }
;     __device__ __forceinline__ void operator()(const f32x4 (&acc)[2][2][4][2], const pg8::Unit& u, int wr, int wc, int fr, int fq) const {
;     ...
; #pragma unroll
;             for (int jj = 0; jj < 4; ++jj) {
;                 float g2 = dpp_shr1(g[6][jj]), g1 = dpp_shr1(g[7][jj]), v2 = dpp_shr1(v[6][jj]), v1 = dpp_shr1(v[7][jj]);
; #pragma unroll
;                 for (int e = 0; e < 8; ++e) { const float g0 = g[e][jj], v0 = v[e][jj];
;                     const float cg = bg[jj] + wg0[jj] * g2 + wg1[jj] * g1 + wg2[jj] * g0, cv = bv[jj] + wv0[jj] * v2 + wv1[jj] * v1 + wv2[jj] * v0;
;                     g[e][jj] = silu_fast(cg) * cv; g2 = g1; g1 = g0; v2 = v1; v1 = v0; } }
; #pragma unroll
;             for (int e = 0; e < 8; ++e) { v2u w; w.x = pk2(g[e][0], g[e][1]); w.y = pk2(g[e][2], g[e][3]); *(v2u*)(ACT + (size_t)(tok0 + e) * FFH + cc) = w; }
	s_nop 7
	s_nop 1
	v_cvt_pk_bf16_f32 v13, v13, v15
	v_cvt_pk_bf16_f32 v12, v12, v14
	v_mov_b32_e32 v14, v9
	v_mov_b32_e32 v15, v11
	v_pk_fma_f32 v[18:19], v[30:31], v[54:55], v[70:71]
	v_pk_mul_f32 v[14:15], v[14:15], v[36:37]
	v_pk_fma_f32 v[18:19], v[26:27], v[58:59], v[18:19]
	v_mov_b32_e32 v9, v10
	v_pk_fma_f32 v[18:19], v[14:15], v[62:63], v[18:19]
	global_store_dwordx2 v[96:97], v[12:13], off offset:8
	v_mov_b32_e32 v12, v5
	v_mov_b32_e32 v13, v7
	v_mov_b32_e32 v5, v6
	v_pk_mul_f32 v[6:7], v[8:9], v[36:37]
	v_pk_fma_f32 v[8:9], v[22:23], v[98:99], v[102:103]
	v_mul_f32_e32 v23, 0xbfb8aa3b, v18
	v_exp_f32_e32 v23, v23
	v_pk_fma_f32 v[8:9], v[16:17], v[106:107], v[8:9]
	v_pk_fma_f32 v[10:11], v[20:21], v[52:53], v[56:57]
	v_pk_fma_f32 v[8:9], v[6:7], v[110:111], v[8:9]
	v_add_f32_e32 v23, 1.0, v23
	v_pk_fma_f32 v[20:21], v[28:29], v[40:41], v[66:67]
	v_mul_f32_e32 v22, 0xbfb8aa3b, v8
	v_rcp_f32_e32 v28, v23
	v_mul_f32_e32 v23, 0xbfb8aa3b, v9
	v_exp_f32_e32 v22, v22
	v_exp_f32_e32 v23, v23
	v_pk_mul_f32 v[4:5], v[4:5], v[36:37]
	v_pk_fma_f32 v[10:11], v[34:35], v[60:61], v[10:11]
	v_add_f32_e32 v22, 1.0, v22
	v_add_f32_e32 v23, 1.0, v23
	v_rcp_f32_e32 v22, v22
	v_rcp_f32_e32 v23, v23
	v_pk_fma_f32 v[10:11], v[4:5], v[68:69], v[10:11]
	v_pk_mul_f32 v[12:13], v[12:13], v[36:37]
	v_pk_mul_f32 v[8:9], v[8:9], v[22:23]
	s_nop 0
	v_pk_mul_f32 v[8:9], v[10:11], v[8:9]
	v_pk_fma_f32 v[10:11], v[24:25], v[46:47], v[20:21]
	v_mul_f32_e32 v20, 0xbfb8aa3b, v19
	v_exp_f32_e32 v20, v20
	v_pk_fma_f32 v[10:11], v[12:13], v[50:51], v[10:11]
	v_add_f32_e32 v20, 1.0, v20
	v_rcp_f32_e32 v29, v20
	s_nop 0
	v_pk_mul_f32 v[18:19], v[18:19], v[28:29]
	s_nop 0
	v_pk_mul_f32 v[10:11], v[10:11], v[18:19]
	s_nop 7
	s_nop 1
	v_cvt_pk_bf16_f32 v9, v9, v11
	v_cvt_pk_bf16_f32 v8, v8, v10
	global_store_dwordx2 v[80:81], v[8:9], off offset:8
	v_pk_fma_f32 v[8:9], v[16:17], v[98:99], v[102:103]
	v_pk_fma_f32 v[16:17], v[26:27], v[54:55], v[70:71]
	v_pk_fma_f32 v[8:9], v[6:7], v[106:107], v[8:9]
	v_pk_fma_f32 v[16:17], v[14:15], v[58:59], v[16:17]
	v_pk_fma_f32 v[8:9], v[88:89], v[110:111], v[8:9]
	v_pk_fma_f32 v[16:17], v[86:87], v[62:63], v[16:17]
	v_mul_f32_e32 v20, 0xbfb8aa3b, v8
	v_mul_f32_e32 v21, 0xbfb8aa3b, v16
	v_exp_f32_e32 v21, v21
	v_exp_f32_e32 v20, v20
	v_pk_fma_f32 v[10:11], v[34:35], v[52:53], v[56:57]
	v_pk_fma_f32 v[18:19], v[24:25], v[40:41], v[66:67]
	v_add_f32_e32 v21, 1.0, v21
	v_rcp_f32_e32 v22, v21
	v_mul_f32_e32 v21, 0xbfb8aa3b, v9
	v_exp_f32_e32 v21, v21
	v_add_f32_e32 v20, 1.0, v20
	v_rcp_f32_e32 v20, v20
	v_pk_fma_f32 v[10:11], v[4:5], v[60:61], v[10:11]
	v_add_f32_e32 v21, 1.0, v21
	v_rcp_f32_e32 v21, v21
	v_pk_fma_f32 v[10:11], v[82:83], v[68:69], v[10:11]
	v_pk_fma_f32 v[6:7], v[6:7], v[98:99], v[102:103]
	v_pk_fma_f32 v[4:5], v[4:5], v[52:53], v[56:57]
	v_pk_mul_f32 v[8:9], v[8:9], v[20:21]
	v_pk_fma_f32 v[6:7], v[88:89], v[106:107], v[6:7]
	v_pk_mul_f32 v[8:9], v[10:11], v[8:9]
	v_pk_fma_f32 v[10:11], v[12:13], v[46:47], v[18:19]
	v_mul_f32_e32 v18, 0xbfb8aa3b, v17
	v_exp_f32_e32 v18, v18
	v_pk_fma_f32 v[10:11], v[72:73], v[50:51], v[10:11]
	v_pk_fma_f32 v[6:7], v[94:95], v[110:111], v[6:7]
	v_pk_fma_f32 v[4:5], v[82:83], v[60:61], v[4:5]
	v_add_f32_e32 v18, 1.0, v18
	v_rcp_f32_e32 v23, v18
	v_pk_fma_f32 v[4:5], v[84:85], v[68:69], v[4:5]
	v_pk_mul_f32 v[16:17], v[16:17], v[22:23]
	s_nop 0
	v_pk_mul_f32 v[10:11], v[10:11], v[16:17]
	s_nop 7
	s_nop 1
	v_cvt_pk_bf16_f32 v9, v9, v11
	v_cvt_pk_bf16_f32 v8, v8, v10
	v_pk_fma_f32 v[10:11], v[14:15], v[54:55], v[70:71]
	global_store_dwordx2 v[78:79], v[8:9], off offset:8
	v_pk_fma_f32 v[10:11], v[86:87], v[58:59], v[10:11]
	v_mul_f32_e32 v8, 0xbfb8aa3b, v6
	v_pk_fma_f32 v[10:11], v[90:91], v[62:63], v[10:11]
	v_exp_f32_e32 v8, v8
	v_mul_f32_e32 v9, 0xbfb8aa3b, v10
	v_exp_f32_e32 v9, v9
	v_add_f32_e32 v8, 1.0, v8
	v_rcp_f32_e32 v8, v8
	v_add_f32_e32 v9, 1.0, v9
	v_rcp_f32_e32 v14, v9
	v_mul_f32_e32 v9, 0xbfb8aa3b, v7
	v_exp_f32_e32 v9, v9
	s_nop 0
	v_add_f32_e32 v9, 1.0, v9
	v_rcp_f32_e32 v9, v9
	s_nop 0
	v_pk_mul_f32 v[6:7], v[6:7], v[8:9]
	v_mul_f32_e32 v8, 0xbfb8aa3b, v11
	v_exp_f32_e32 v8, v8
	v_pk_mul_f32 v[4:5], v[4:5], v[6:7]
	v_pk_fma_f32 v[6:7], v[12:13], v[40:41], v[66:67]
	v_add_f32_e32 v8, 1.0, v8
	v_rcp_f32_e32 v15, v8
	v_pk_fma_f32 v[6:7], v[72:73], v[46:47], v[6:7]
	v_pk_mul_f32 v[8:9], v[10:11], v[14:15]
	v_pk_fma_f32 v[6:7], v[74:75], v[50:51], v[6:7]
	s_nop 0
	v_pk_mul_f32 v[6:7], v[6:7], v[8:9]
	v_and_b32_sdwa v8, v5, v234 dst_sel:DWORD dst_unused:UNUSED_PAD src0_sel:WORD_1 src1_sel:DWORD
	v_and_b32_sdwa v9, v4, v234 dst_sel:DWORD dst_unused:UNUSED_PAD src0_sel:WORD_1 src1_sel:DWORD
	v_add3_u32 v4, v4, v9, s59
	v_add3_u32 v5, v5, v8, s59
	v_and_b32_sdwa v8, v7, v234 dst_sel:DWORD dst_unused:UNUSED_PAD src0_sel:WORD_1 src1_sel:DWORD
	v_and_b32_sdwa v9, v6, v234 dst_sel:DWORD dst_unused:UNUSED_PAD src0_sel:WORD_1 src1_sel:DWORD
	v_add3_u32 v7, v7, v8, s59
	v_add3_u32 v6, v6, v9, s59
	v_and_b32_e32 v7, 0xffff0000, v7
	v_and_b32_e32 v6, 0xffff0000, v6
	v_or_b32_sdwa v5, v7, v5 dst_sel:DWORD dst_unused:UNUSED_PAD src0_sel:DWORD src1_sel:WORD_1
	v_or_b32_sdwa v4, v6, v4 dst_sel:DWORD dst_unused:UNUSED_PAD src0_sel:DWORD src1_sel:WORD_1
	global_store_dwordx2 v[76:77], v[4:5], off offset:8
	s_cbranch_vccz .LBB0_4365

; #define PG8_STAGE(bufoff, gbase, voff) do { _Pragma("unroll") for (int _i = 0; _i < 2; ++_i) \
;         __builtin_amdgcn_global_load_lds((const unsigned*)((const char*)(gbase) + (voff)[_i]), (LAS unsigned*)(lds + (bufoff) + ldsw + _i * 8192), 16, 0, 0); } while (0)
; #define PG8_LDA(dst, b, h) do { _Pragma("unroll") for (int m = 0; m < 4; ++m) _Pragma("unroll") for (int k = 0; k < 2; ++k) dst[m][k] = *(const LAS bf16x8*)(lds + PG8_SA(b, h) + aoff + m * 2048 + k * 1024); } while (0)
; #define PG8_LDB(dst, b, h) do { _Pragma("unroll") for (int n = 0; n < 2; ++n) _Pragma("unroll") for (int k = 0; k < 2; ++k) dst[n][k] = *(const LAS bf16x8*)(lds + PG8_SB(b, h) + boff + n * 2048 + k * 1024); } while (0)
; #define PG8_MMA(ai, bj, At, Bt) do { __builtin_amdgcn_s_setprio(1); _Pragma("unroll") for (int m = 0; m < 4; ++m) _Pragma("unroll") for (int n = 0; n < 2; ++n) _Pragma("unroll") for (int k = 0; k < 2; ++k) \
;         acc[ai][bj][m][n] = __builtin_amdgcn_mfma_f32_16x16x32_bf16(Bt[n][k], At[m][k], acc[ai][bj][m][n], 0, 0, 0); __builtin_amdgcn_s_setprio(0); } while (0)
; #define PG8_WAIT_V(n) asm volatile("s_waitcnt vmcnt(" #n ")" ::: "memory")
; #define PG8_WAIT_L(n) asm volatile("s_waitcnt lgkmcnt(" #n ")" ::: "memory")
; #define PG8_BAR __builtin_amdgcn_s_barrier()
; #define PG8_SCHED __builtin_amdgcn_sched_barrier(0)
; template <class PT, class Epi>
; __device__ __forceinline__ void gemm_phase_once(LAS unsigned char* lds, const PT& S, const Epi& E, bool epi_on) {
;     ...
;             PG8_LDB(B0, 0, 0); PG8_SCHED; PG8_LDA(At, 0, 0); PG8_STAGE(PG8_SA(1, 1), a1 + hstepA, voffA);
;             PG8_WAIT_L(8); PG8_BAR; PG8_WAIT_L(0); PG8_MMA(0, 0, At, B0); PG8_BAR; PG8_SCHED;
;             PG8_LDB(B1, 0, 1); PG8_STAGE(PG8_SB(0, 0), b2, voffB);
;             PG8_BAR; PG8_WAIT_L(0); PG8_MMA(0, 1, At, B1); PG8_BAR;
;             PG8_LDA(At, 0, 1); PG8_STAGE(PG8_SA(0, 0), a2, voffA);
;             PG8_BAR; PG8_WAIT_L(0); PG8_MMA(1, 0, At, B0); PG8_BAR; PG8_SCHED;
;             PG8_STAGE(PG8_SB(0, 1), b2 + hstepB, voffB);
;             PG8_WAIT_V(6); PG8_BAR; PG8_MMA(1, 1, At, B1); PG8_BAR;
.LBB0_4350:
	ds_read_b128 v[36:39], v228
	ds_read_b128 v[40:43], v228 offset:1024
	ds_read_b128 v[158:161], v228 offset:2048
	ds_read_b128 v[168:171], v228 offset:3072
	s_add_u32 s38, s36, 0x100
	s_addc_u32 s39, s37, 0
	s_cmp_eq_u32 s65, 28
	s_cselect_b32 s43, s27, s39
	s_cselect_b32 s42, s35, s38
	s_cselect_b32 s41, s25, s64
	s_cselect_b32 s40, s62, s63
	v_lshl_add_u64 v[162:163], s[36:37], 0, v[150:151]
	s_add_i32 m0, s49, 0xc000
	ds_read_b128 v[172:175], v229
	ds_read_b128 v[176:179], v229 offset:1024
	ds_read_b128 v[180:183], v229 offset:2048
	ds_read_b128 v[184:187], v229 offset:3072
	ds_read_b128 v[188:191], v229 offset:4096
	ds_read_b128 v[192:195], v229 offset:5120
	ds_read_b128 v[196:199], v229 offset:6144
	ds_read_b128 v[200:203], v229 offset:7168
	global_load_lds_dwordx4 v[162:163], off
	v_lshl_add_u64 v[162:163], s[36:37], 0, v[152:153]
	s_add_i32 m0, s49, 0xe000
	s_nop 0
	global_load_lds_dwordx4 v[162:163], off
	s_waitcnt lgkmcnt(8)
	s_barrier
	s_waitcnt lgkmcnt(0)
	s_setprio 1
	s_waitcnt lgkmcnt(0)
	v_mfma_f32_16x16x32_bf16 v[132:135], v[36:39], v[172:175], v[132:135]
	v_mfma_f32_16x16x32_bf16 v[72:75], v[158:161], v[172:175], v[72:75]
	v_mfma_f32_16x16x32_bf16 v[124:127], v[36:39], v[180:183], v[124:127]
	v_mfma_f32_16x16x32_bf16 v[68:71], v[158:161], v[180:183], v[68:71]
	v_mfma_f32_16x16x32_bf16 v[104:107], v[36:39], v[188:191], v[104:107]
	v_mfma_f32_16x16x32_bf16 v[32:35], v[158:161], v[188:191], v[32:35]
	v_mfma_f32_16x16x32_bf16 v[100:103], v[36:39], v[196:199], v[100:103]
	v_mfma_f32_16x16x32_bf16 v[24:27], v[158:161], v[196:199], v[24:27]
	v_mfma_f32_16x16x32_bf16 v[132:135], v[40:43], v[176:179], v[132:135]
	v_mfma_f32_16x16x32_bf16 v[72:75], v[168:171], v[176:179], v[72:75]
	v_mfma_f32_16x16x32_bf16 v[124:127], v[40:43], v[184:187], v[124:127]
	v_mfma_f32_16x16x32_bf16 v[68:71], v[168:171], v[184:187], v[68:71]
	v_mfma_f32_16x16x32_bf16 v[104:107], v[40:43], v[192:195], v[104:107]
	v_mfma_f32_16x16x32_bf16 v[32:35], v[168:171], v[192:195], v[32:35]
	v_mfma_f32_16x16x32_bf16 v[100:103], v[40:43], v[200:203], v[100:103]
	v_mfma_f32_16x16x32_bf16 v[24:27], v[168:171], v[200:203], v[24:27]
	s_setprio 0
	s_barrier
	s_add_i32 s36, s57, s46
	v_lshl_add_u64 v[162:163], s[40:41], 0, v[146:147]
	s_mov_b32 m0, s36
	ds_read_b128 v[204:207], v233
	ds_read_b128 v[208:211], v233 offset:1024
	ds_read_b128 v[212:215], v233 offset:2048
	ds_read_b128 v[216:219], v233 offset:3072
	global_load_lds_dwordx4 v[162:163], off
	v_lshl_add_u64 v[220:221], s[40:41], 0, v[140:141]
	s_add_i32 m0, s36, 0x2000
	s_nop 0
	global_load_lds_dwordx4 v[220:221], off
	s_barrier
	s_waitcnt lgkmcnt(0)
	s_setprio 1
	s_waitcnt lgkmcnt(0)
	v_mfma_f32_16x16x32_bf16 v[120:123], v[204:207], v[172:175], v[120:123]
	v_mfma_f32_16x16x32_bf16 v[64:67], v[212:215], v[172:175], v[64:67]
	v_mfma_f32_16x16x32_bf16 v[116:119], v[204:207], v[180:183], v[116:119]
	v_mfma_f32_16x16x32_bf16 v[60:63], v[212:215], v[180:183], v[60:63]
	v_mfma_f32_16x16x32_bf16 v[96:99], v[204:207], v[188:191], v[96:99]
	v_mfma_f32_16x16x32_bf16 v[28:31], v[212:215], v[188:191], v[28:31]
	v_mfma_f32_16x16x32_bf16 v[92:95], v[204:207], v[196:199], v[92:95]
	v_mfma_f32_16x16x32_bf16 v[20:23], v[212:215], v[196:199], v[20:23]
	v_mfma_f32_16x16x32_bf16 v[120:123], v[208:211], v[176:179], v[120:123]
	v_mfma_f32_16x16x32_bf16 v[64:67], v[216:219], v[176:179], v[64:67]
	v_mfma_f32_16x16x32_bf16 v[116:119], v[208:211], v[184:187], v[116:119]
	v_mfma_f32_16x16x32_bf16 v[60:63], v[216:219], v[184:187], v[60:63]
	v_mfma_f32_16x16x32_bf16 v[96:99], v[208:211], v[192:195], v[96:99]
	v_mfma_f32_16x16x32_bf16 v[28:31], v[216:219], v[192:195], v[28:31]
	v_mfma_f32_16x16x32_bf16 v[92:95], v[208:211], v[200:203], v[92:95]
	v_mfma_f32_16x16x32_bf16 v[20:23], v[216:219], v[200:203], v[20:23]
	s_setprio 0
	s_mov_b32 m0, s49
	v_lshl_add_u64 v[222:223], s[42:43], 0, v[142:143]
	s_barrier
	ds_read_b128 v[172:175], v229 offset:16384
	ds_read_b128 v[176:179], v229 offset:17408
	ds_read_b128 v[180:183], v229 offset:18432
	ds_read_b128 v[184:187], v229 offset:19456
	ds_read_b128 v[188:191], v229 offset:20480
	ds_read_b128 v[192:195], v229 offset:21504
	ds_read_b128 v[196:199], v229 offset:22528
	ds_read_b128 v[200:203], v229 offset:23552
	global_load_lds_dwordx4 v[222:223], off
	v_lshl_add_u64 v[224:225], s[42:43], 0, v[144:145]
	s_mov_b32 m0, s50
	s_nop 0
	global_load_lds_dwordx4 v[224:225], off
	s_barrier
	s_waitcnt lgkmcnt(0)
	s_setprio 1
	s_waitcnt lgkmcnt(0)
	v_mfma_f32_16x16x32_bf16 v[88:91], v[36:39], v[172:175], v[88:91]
	v_mfma_f32_16x16x32_bf16 v[16:19], v[158:161], v[172:175], v[16:19]
	v_mfma_f32_16x16x32_bf16 v[84:87], v[36:39], v[180:183], v[84:87]
	v_mfma_f32_16x16x32_bf16 v[8:11], v[158:161], v[180:183], v[8:11]
	v_mfma_f32_16x16x32_bf16 v[136:139], v[36:39], v[188:191], v[136:139]
	v_mfma_f32_16x16x32_bf16 v[56:59], v[158:161], v[188:191], v[56:59]
	v_mfma_f32_16x16x32_bf16 v[36:39], v[36:39], v[196:199], v[112:115]
	v_mfma_f32_16x16x32_bf16 v[88:91], v[40:43], v[176:179], v[88:91]
	v_mfma_f32_16x16x32_bf16 v[16:19], v[168:171], v[176:179], v[16:19]
	v_mfma_f32_16x16x32_bf16 v[84:87], v[40:43], v[184:187], v[84:87]
	v_mfma_f32_16x16x32_bf16 v[8:11], v[168:171], v[184:187], v[8:11]
	v_mfma_f32_16x16x32_bf16 v[136:139], v[40:43], v[192:195], v[136:139]
	v_mfma_f32_16x16x32_bf16 v[56:59], v[168:171], v[192:195], v[56:59]
	v_mfma_f32_16x16x32_bf16 v[36:39], v[40:43], v[200:203], v[36:39]
	v_mfma_f32_16x16x32_bf16 v[40:43], v[158:161], v[196:199], v[52:55]
	v_mfma_f32_16x16x32_bf16 v[40:43], v[168:171], v[200:203], v[40:43]
	s_setprio 0
	s_barrier
; #define PG8_STAGE(bufoff, gbase, voff) do { _Pragma("unroll") for (int _i = 0; _i < 2; ++_i) \
;         __builtin_amdgcn_global_load_lds((const unsigned*)((const char*)(gbase) + (voff)[_i]), (LAS unsigned*)(lds + (bufoff) + ldsw + _i * 8192), 16, 0, 0); } while (0)
; #define PG8_LDA(dst, b, h) do { _Pragma("unroll") for (int m = 0; m < 4; ++m) _Pragma("unroll") for (int k = 0; k < 2; ++k) dst[m][k] = *(const LAS bf16x8*)(lds + PG8_SA(b, h) + aoff + m * 2048 + k * 1024); } while (0)
; #define PG8_LDB(dst, b, h) do { _Pragma("unroll") for (int n = 0; n < 2; ++n) _Pragma("unroll") for (int k = 0; k < 2; ++k) dst[n][k] = *(const LAS bf16x8*)(lds + PG8_SB(b, h) + boff + n * 2048 + k * 1024); } while (0)
; #define PG8_MMA(ai, bj, At, Bt) do { __builtin_amdgcn_s_setprio(1); _Pragma("unroll") for (int m = 0; m < 4; ++m) _Pragma("unroll") for (int n = 0; n < 2; ++n) _Pragma("unroll") for (int k = 0; k < 2; ++k) \
;         acc[ai][bj][m][n] = __builtin_amdgcn_mfma_f32_16x16x32_bf16(Bt[n][k], At[m][k], acc[ai][bj][m][n], 0, 0, 0); __builtin_amdgcn_s_setprio(0); } while (0)
; #define PG8_WAIT_V(n) asm volatile("s_waitcnt vmcnt(" #n ")" ::: "memory")
; #define PG8_WAIT_L(n) asm volatile("s_waitcnt lgkmcnt(" #n ")" ::: "memory")
; #define PG8_BAR __builtin_amdgcn_s_barrier()
; #define PG8_SCHED __builtin_amdgcn_sched_barrier(0)
; template <class PT, class Epi>
; __device__ __forceinline__ void gemm_phase_once(LAS unsigned char* lds, const PT& S, const Epi& E, bool epi_on) {
;     ...
;             PG8_STAGE(PG8_SB(0, 1), b2 + hstepB, voffB);
;             PG8_WAIT_V(6); PG8_BAR; PG8_MMA(1, 1, At, B1); PG8_BAR;
;             PG8_LDB(B0, 1, 0); PG8_SCHED; PG8_LDA(At, 1, 0); PG8_STAGE(PG8_SA(0, 1), a2 + hstepA, voffA);
;             PG8_WAIT_L(8); PG8_BAR; PG8_WAIT_L(0); PG8_MMA(0, 0, At, B0); PG8_BAR; PG8_SCHED;
;             PG8_LDB(B1, 1, 1); PG8_STAGE(PG8_SB(1, 0), b3, voffB);
;             PG8_BAR; PG8_WAIT_L(0); PG8_MMA(0, 1, At, B1); PG8_BAR;
;             PG8_LDA(At, 1, 1); PG8_STAGE(PG8_SA(1, 0), a3, voffA);
;             PG8_BAR; PG8_WAIT_L(0); PG8_MMA(1, 0, At, B0); PG8_BAR; PG8_SCHED;
	s_add_u32 s36, s40, 0x80000
	s_addc_u32 s37, s41, 0
	s_add_i32 s66, s58, s46
	v_lshl_add_u64 v[52:53], s[36:37], 0, v[146:147]
	s_mov_b32 m0, s66
	s_nop 0
	global_load_lds_dwordx4 v[52:53], off
	v_lshl_add_u64 v[52:53], s[36:37], 0, v[140:141]
	s_add_i32 m0, s66, 0x2000
	s_nop 0
	global_load_lds_dwordx4 v[52:53], off
	s_waitcnt vmcnt(6)
	s_barrier
	s_setprio 1
	v_mfma_f32_16x16x32_bf16 v[52:55], v[204:207], v[172:175], v[80:83]
	v_mfma_f32_16x16x32_bf16 v[80:83], v[208:211], v[176:179], v[52:55]
	v_mfma_f32_16x16x32_bf16 v[52:55], v[204:207], v[180:183], v[76:79]
	v_mfma_f32_16x16x32_bf16 v[76:79], v[208:211], v[184:187], v[52:55]
	v_mfma_f32_16x16x32_bf16 v[52:55], v[204:207], v[188:191], v[128:131]
	v_mfma_f32_16x16x32_bf16 v[12:15], v[212:215], v[172:175], v[12:15]
	v_mfma_f32_16x16x32_bf16 v[4:7], v[212:215], v[180:183], v[4:7]
	v_mfma_f32_16x16x32_bf16 v[128:131], v[208:211], v[192:195], v[52:55]
	v_mfma_f32_16x16x32_bf16 v[48:51], v[212:215], v[188:191], v[48:51]
	v_mfma_f32_16x16x32_bf16 v[52:55], v[204:207], v[196:199], v[108:111]
	v_mfma_f32_16x16x32_bf16 v[44:47], v[212:215], v[196:199], v[44:47]
	v_mfma_f32_16x16x32_bf16 v[12:15], v[216:219], v[176:179], v[12:15]
	v_mfma_f32_16x16x32_bf16 v[4:7], v[216:219], v[184:187], v[4:7]
	v_mfma_f32_16x16x32_bf16 v[48:51], v[216:219], v[192:195], v[48:51]
	v_mfma_f32_16x16x32_bf16 v[108:111], v[208:211], v[200:203], v[52:55]
	v_mfma_f32_16x16x32_bf16 v[44:47], v[216:219], v[200:203], v[44:47]
	s_setprio 0
	s_add_i32 s66, 0, 0x18000
	v_add_u32_e32 v165, s66, v167
	s_barrier
	ds_read_b128 v[52:55], v165
	ds_read_b128 v[112:115], v165 offset:1024
	ds_read_b128 v[158:161], v165 offset:2048
	ds_read_b128 v[168:171], v165 offset:3072
	s_add_u32 s36, s42, 0x4000
	s_addc_u32 s37, s43, 0
	s_mov_b32 m0, s51
	v_lshl_add_u64 v[204:205], s[36:37], 0, v[142:143]
	ds_read_b128 v[172:175], v229 offset:32768
	ds_read_b128 v[176:179], v229 offset:33792
	ds_read_b128 v[180:183], v229 offset:34816
	ds_read_b128 v[184:187], v229 offset:35840
	ds_read_b128 v[188:191], v229 offset:36864
	ds_read_b128 v[192:195], v229 offset:37888
	ds_read_b128 v[196:199], v229 offset:38912
	ds_read_b128 v[200:203], v229 offset:39936
	global_load_lds_dwordx4 v[204:205], off
	v_lshl_add_u64 v[204:205], s[36:37], 0, v[144:145]
	s_mov_b32 m0, s52
	s_nop 0
	global_load_lds_dwordx4 v[204:205], off
	s_waitcnt lgkmcnt(8)
	s_barrier
	s_waitcnt lgkmcnt(0)
	s_setprio 1
	s_waitcnt lgkmcnt(0)
	v_mfma_f32_16x16x32_bf16 v[132:135], v[52:55], v[172:175], v[132:135]
	v_mfma_f32_16x16x32_bf16 v[72:75], v[158:161], v[172:175], v[72:75]
	v_mfma_f32_16x16x32_bf16 v[124:127], v[52:55], v[180:183], v[124:127]
	v_mfma_f32_16x16x32_bf16 v[68:71], v[158:161], v[180:183], v[68:71]
	v_mfma_f32_16x16x32_bf16 v[104:107], v[52:55], v[188:191], v[104:107]
	v_mfma_f32_16x16x32_bf16 v[32:35], v[158:161], v[188:191], v[32:35]
	v_mfma_f32_16x16x32_bf16 v[100:103], v[52:55], v[196:199], v[100:103]
	v_mfma_f32_16x16x32_bf16 v[24:27], v[158:161], v[196:199], v[24:27]
	v_mfma_f32_16x16x32_bf16 v[132:135], v[112:115], v[176:179], v[132:135]
	v_mfma_f32_16x16x32_bf16 v[72:75], v[168:171], v[176:179], v[72:75]
	v_mfma_f32_16x16x32_bf16 v[124:127], v[112:115], v[184:187], v[124:127]
	v_mfma_f32_16x16x32_bf16 v[68:71], v[168:171], v[184:187], v[68:71]
	v_mfma_f32_16x16x32_bf16 v[104:107], v[112:115], v[192:195], v[104:107]
	v_mfma_f32_16x16x32_bf16 v[32:35], v[168:171], v[192:195], v[32:35]
	v_mfma_f32_16x16x32_bf16 v[100:103], v[112:115], v[200:203], v[100:103]
	v_mfma_f32_16x16x32_bf16 v[24:27], v[168:171], v[200:203], v[24:27]
	s_setprio 0
	s_barrier
	s_add_i32 s42, 0, 0x1c000
	s_add_i32 s36, s66, s46
	v_add_u32_e32 v165, s42, v167
	v_lshl_add_u64 v[162:163], v[162:163], 0, s[10:11]
	s_mov_b32 m0, s36
	ds_read_b128 v[204:207], v165
	ds_read_b128 v[208:211], v165 offset:1024
	ds_read_b128 v[212:215], v165 offset:2048
	ds_read_b128 v[216:219], v165 offset:3072
	global_load_lds_dwordx4 v[162:163], off
	v_lshl_add_u64 v[162:163], v[220:221], 0, s[10:11]
	s_add_i32 m0, s36, 0x2000
	s_nop 0
	global_load_lds_dwordx4 v[162:163], off
	s_barrier
	s_waitcnt lgkmcnt(0)
	s_setprio 1
	s_waitcnt lgkmcnt(0)
	v_mfma_f32_16x16x32_bf16 v[120:123], v[204:207], v[172:175], v[120:123]
	v_mfma_f32_16x16x32_bf16 v[64:67], v[212:215], v[172:175], v[64:67]
	v_mfma_f32_16x16x32_bf16 v[116:119], v[204:207], v[180:183], v[116:119]
	v_mfma_f32_16x16x32_bf16 v[60:63], v[212:215], v[180:183], v[60:63]
	v_mfma_f32_16x16x32_bf16 v[96:99], v[204:207], v[188:191], v[96:99]
	v_mfma_f32_16x16x32_bf16 v[28:31], v[212:215], v[188:191], v[28:31]
	v_mfma_f32_16x16x32_bf16 v[92:95], v[204:207], v[196:199], v[92:95]
	v_mfma_f32_16x16x32_bf16 v[20:23], v[212:215], v[196:199], v[20:23]
	v_mfma_f32_16x16x32_bf16 v[120:123], v[208:211], v[176:179], v[120:123]
	v_mfma_f32_16x16x32_bf16 v[64:67], v[216:219], v[176:179], v[64:67]
	v_mfma_f32_16x16x32_bf16 v[116:119], v[208:211], v[184:187], v[116:119]
	v_mfma_f32_16x16x32_bf16 v[60:63], v[216:219], v[184:187], v[60:63]
	v_mfma_f32_16x16x32_bf16 v[96:99], v[208:211], v[192:195], v[96:99]
	v_mfma_f32_16x16x32_bf16 v[28:31], v[216:219], v[192:195], v[28:31]
	v_mfma_f32_16x16x32_bf16 v[92:95], v[208:211], v[200:203], v[92:95]
	v_mfma_f32_16x16x32_bf16 v[20:23], v[216:219], v[200:203], v[20:23]
	s_setprio 0
	s_mov_b32 m0, s54
	v_lshl_add_u64 v[162:163], v[222:223], 0, s[10:11]
	s_barrier
	ds_read_b128 v[172:175], v229 offset:49152
	ds_read_b128 v[176:179], v229 offset:50176
	ds_read_b128 v[180:183], v229 offset:51200
	ds_read_b128 v[184:187], v229 offset:52224
	ds_read_b128 v[188:191], v229 offset:53248
	ds_read_b128 v[192:195], v229 offset:54272
	ds_read_b128 v[196:199], v229 offset:55296
	ds_read_b128 v[200:203], v229 offset:56320
	global_load_lds_dwordx4 v[162:163], off
	v_lshl_add_u64 v[162:163], v[224:225], 0, s[10:11]
	s_mov_b32 m0, s55
	s_nop 0
	global_load_lds_dwordx4 v[162:163], off
	s_barrier
; __device__ __forceinline__ unsigned pk2(float lo, float hi) { return f2bf(lo) | (f2bf(hi) << 16); }
; #define PG8_STAGE(bufoff, gbase, voff) do { _Pragma("unroll") for (int _i = 0; _i < 2; ++_i) \
;         __builtin_amdgcn_global_load_lds((const unsigned*)((const char*)(gbase) + (voff)[_i]), (LAS unsigned*)(lds + (bufoff) + ldsw + _i * 8192), 16, 0, 0); } while (0)
; template <class PT, class Epi>
; __device__ __forceinline__ void gemm_phase_once(LAS unsigned char* lds, const PT& S, const Epi& E, bool epi_on) {
;     ...
;             PG8_BAR; PG8_WAIT_L(0); PG8_MMA(0, 1, At, B1); PG8_BAR;
;             PG8_LDA(At, 1, 1); PG8_STAGE(PG8_SA(1, 0), a3, voffA);
;             PG8_BAR; PG8_WAIT_L(0); PG8_MMA(1, 0, At, B0); PG8_BAR; PG8_SCHED;
;             PG8_STAGE(PG8_SB(1, 1), b3 + hstepB, voffB);
;             PG8_WAIT_V(6); PG8_BAR; PG8_MMA(1, 1, At, B1); PG8_BAR;
;     __device__ __forceinline__ void operator()(const f32x4 (&acc)[2][2][4][2], const pg8::Unit& u, int wr, int wc, int fr, int fq) const {
;         const int ch0 = 128 * u.pn + 32 * wc + 8 * fq, tok0 = 256 * u.pm + 128 * wr + 8 * fr;
;         const f32x4 r0 = *(const f32x4*)(RS + tok0), r1 = *(const f32x4*)(RS + tok0 + 4);
;         bf16* hb = HALO + ((size_t)((u.pm * 44 + u.pn) * 2 + wr) * 4) * 256 + 32 * wc + 8 * fq;
; #pragma unroll
;         for (int n = 0; n < 2; ++n) {
;             float g[8][4], v[8][4];
; #pragma unroll
;             for (int e = 0; e < 8; ++e) { const float rs = (e < 4) ? r0[e & 3] : r1[e & 3];
; #pragma unroll
;                 for (int jj = 0; jj < 4; ++jj) { g[e][jj] = acc[e >> 2][0][e & 3][n][jj] * rs; v[e][jj] = acc[e >> 2][1][e & 3][n][jj] * rs; } }
;             if (fr == 0) {
; #pragma unroll
;                 for (int q = 0; q < 2; ++q) { v2u a, b; a.x = pk2(g[q][0], g[q][1]); a.y = pk2(g[q][2], g[q][3]); b.x = pk2(v[q][0], v[q][1]); b.y = pk2(v[q][2], v[q][3]);
;                     *(v2u*)(hb + (size_t)q * 256 + 4 * n) = a; *(v2u*)(hb + (size_t)q * 256 + 128 + 4 * n) = b; } }
;             if (fr == 15) {
; #pragma unroll
;                 for (int q = 0; q < 2; ++q) { v2u a, b; a.x = pk2(g[6 + q][0], g[6 + q][1]); a.y = pk2(g[6 + q][2], g[6 + q][3]); b.x = pk2(v[6 + q][0], v[6 + q][1]); b.y = pk2(v[6 + q][2], v[6 + q][3]);
;                     *(v2u*)(hb + (size_t)(2 + q) * 256 + 4 * n) = a; *(v2u*)(hb + (size_t)(2 + q) * 256 + 128 + 4 * n) = b; } }
	s_waitcnt lgkmcnt(0)
	s_setprio 1
	s_waitcnt lgkmcnt(0)
	v_mfma_f32_16x16x32_bf16 v[88:91], v[52:55], v[172:175], v[88:91]
	v_mfma_f32_16x16x32_bf16 v[84:87], v[52:55], v[180:183], v[84:87]
	v_mfma_f32_16x16x32_bf16 v[136:139], v[52:55], v[188:191], v[136:139]
	v_mfma_f32_16x16x32_bf16 v[36:39], v[52:55], v[196:199], v[36:39]
	v_mfma_f32_16x16x32_bf16 v[88:91], v[112:115], v[176:179], v[88:91]
	v_mfma_f32_16x16x32_bf16 v[16:19], v[158:161], v[172:175], v[16:19]
	v_mfma_f32_16x16x32_bf16 v[84:87], v[112:115], v[184:187], v[84:87]
	v_mfma_f32_16x16x32_bf16 v[8:11], v[158:161], v[180:183], v[8:11]
	v_mfma_f32_16x16x32_bf16 v[136:139], v[112:115], v[192:195], v[136:139]
	v_mfma_f32_16x16x32_bf16 v[56:59], v[158:161], v[188:191], v[56:59]
	v_mfma_f32_16x16x32_bf16 v[112:115], v[112:115], v[200:203], v[36:39]
	v_mfma_f32_16x16x32_bf16 v[36:39], v[158:161], v[196:199], v[40:43]
	v_mfma_f32_16x16x32_bf16 v[16:19], v[168:171], v[176:179], v[16:19]
	v_mfma_f32_16x16x32_bf16 v[8:11], v[168:171], v[184:187], v[8:11]
	v_mfma_f32_16x16x32_bf16 v[56:59], v[168:171], v[192:195], v[56:59]
	v_mfma_f32_16x16x32_bf16 v[52:55], v[168:171], v[200:203], v[36:39]
	s_setprio 0
	s_barrier
	s_add_u32 s36, s40, 0x80080
	s_addc_u32 s37, s41, 0
	s_add_i32 s40, s42, s46
	v_lshl_add_u64 v[36:37], s[36:37], 0, v[146:147]
	s_mov_b32 m0, s40
	s_nop 0
	global_load_lds_dwordx4 v[36:37], off
	v_lshl_add_u64 v[36:37], s[36:37], 0, v[140:141]
	s_add_i32 m0, s40, 0x2000
	s_nop 0
	global_load_lds_dwordx4 v[36:37], off
	s_waitcnt vmcnt(6)
	s_barrier
	s_setprio 1
	v_mfma_f32_16x16x32_bf16 v[36:39], v[204:207], v[172:175], v[80:83]
	v_mfma_f32_16x16x32_bf16 v[80:83], v[208:211], v[176:179], v[36:39]
	v_mfma_f32_16x16x32_bf16 v[36:39], v[204:207], v[180:183], v[76:79]
	v_mfma_f32_16x16x32_bf16 v[76:79], v[208:211], v[184:187], v[36:39]
	v_mfma_f32_16x16x32_bf16 v[36:39], v[204:207], v[188:191], v[128:131]
	v_mfma_f32_16x16x32_bf16 v[128:131], v[208:211], v[192:195], v[36:39]
	v_mfma_f32_16x16x32_bf16 v[36:39], v[212:215], v[188:191], v[48:51]
	v_mfma_f32_16x16x32_bf16 v[48:51], v[216:219], v[192:195], v[36:39]
	v_mfma_f32_16x16x32_bf16 v[36:39], v[204:207], v[196:199], v[108:111]
	v_mfma_f32_16x16x32_bf16 v[12:15], v[212:215], v[172:175], v[12:15]
	v_mfma_f32_16x16x32_bf16 v[4:7], v[212:215], v[180:183], v[4:7]
	v_mfma_f32_16x16x32_bf16 v[108:111], v[208:211], v[200:203], v[36:39]
	v_mfma_f32_16x16x32_bf16 v[36:39], v[212:215], v[196:199], v[44:47]
	v_mfma_f32_16x16x32_bf16 v[12:15], v[216:219], v[176:179], v[12:15]
	v_mfma_f32_16x16x32_bf16 v[4:7], v[216:219], v[184:187], v[4:7]
	v_mfma_f32_16x16x32_bf16 v[44:47], v[216:219], v[200:203], v[36:39]
	s_setprio 0
	s_add_i32 s65, s65, 2
	s_add_u32 s63, s63, 0x100
	s_addc_u32 s64, s64, 0
	s_cmp_lt_u32 s65, 30
	s_mov_b64 s[36:37], s[38:39]
	s_barrier
	s_cbranch_scc1 .LBB0_4350
	v_lshl_add_u32 v160, s34, 8, v226
	v_ashrrev_i32_e32 v161, 31, v160
	v_lshl_add_u64 v[40:41], v[160:161], 2, s[90:91]
	global_load_dwordx4 v[36:39], v[40:41], off offset:16
	s_nop 0
	global_load_dwordx4 v[40:43], v[40:41], off
	s_mul_i32 s25, s34, 44
	s_add_i32 s25, s25, s61
	s_lshl_b32 s25, s25, 1
	s_add_i32 s34, s25, s45
	s_ashr_i32 s35, s34, 31
	v_mov_b32_e32 v162, v136
	v_mov_b32_e32 v163, v138
	s_lshl_b64 s[34:35], s[34:35], 11
	v_mov_b32_e32 v138, v137
	v_lshl_add_u64 v[158:159], v[148:149], 0, s[34:35]
	v_cmp_lt_i32_e32 vcc, 14, v3
	s_mov_b64 s[34:35], 0
	s_waitcnt vmcnt(0)
	v_pk_mul_f32 v[168:169], v[162:163], v[38:39] op_sel_hi:[1,0]
	v_mov_b32_e32 v162, v128
	v_mov_b32_e32 v163, v130
	v_mov_b32_e32 v130, v129
	v_pk_mul_f32 v[162:163], v[162:163], v[38:39] op_sel_hi:[1,0]
	v_pk_mul_f32 v[136:137], v[138:139], v[38:39] op_sel_hi:[1,0]
	v_pk_mul_f32 v[130:131], v[130:131], v[38:39] op_sel_hi:[1,0]
	s_and_saveexec_b64 s[36:37], vcc
	s_xor_b64 s[36:37], exec, s[36:37]
	s_cbranch_execz .LBB0_4353
	s_nop 7
	s_nop 1
	v_cvt_pk_bf16_f32 v139, v169, v137
	v_cvt_pk_bf16_f32 v138, v168, v136
	s_nop 7
	s_nop 1
	s_mov_b64 s[34:35], exec
	v_cvt_pk_bf16_f32 v129, v163, v131
	v_cvt_pk_bf16_f32 v128, v162, v130
	global_store_dwordx2 v[158:159], v[138:139], off offset:1024
.LBB0_4353:
	s_or_saveexec_b64 s[36:37], s[36:37]
	v_mov_b32_e32 v138, v132
	v_mov_b32_e32 v139, v134
	v_pk_mul_f32 v[190:191], v[138:139], v[40:41] op_sel_hi:[1,0]
	v_mov_b32_e32 v138, v120
	v_mov_b32_e32 v139, v122
	v_mov_b32_e32 v122, v121
	v_mov_b32_e32 v120, v124
	v_mov_b32_e32 v121, v126
	v_pk_mul_f32 v[182:183], v[120:121], v[40:41] op_sel:[0,1]
	v_mov_b32_e32 v120, v116
	v_mov_b32_e32 v121, v118
	v_mov_b32_e32 v118, v117
	v_mov_b32_e32 v116, v112
	v_mov_b32_e32 v117, v114
	v_mov_b32_e32 v112, v39
	v_mov_b32_e32 v134, v133
	v_pk_mul_f32 v[170:171], v[116:117], v[112:113] op_sel_hi:[1,0]
	v_mov_b32_e32 v116, v108
	v_mov_b32_e32 v117, v110
	v_mov_b32_e32 v114, v113
	v_mov_b32_e32 v110, v109
	v_pk_mul_f32 v[188:189], v[138:139], v[40:41] op_sel_hi:[1,0]
	v_pk_mul_f32 v[192:193], v[134:135], v[40:41] op_sel_hi:[1,0]
	v_mov_b32_e32 v126, v125
	v_pk_mul_f32 v[134:135], v[116:117], v[112:113] op_sel_hi:[1,0]
	v_pk_mul_f32 v[172:173], v[114:115], v[112:113] op_sel_hi:[1,0]
	v_pk_mul_f32 v[138:139], v[110:111], v[112:113] op_sel_hi:[1,0]
	v_pk_mul_f32 v[186:187], v[122:123], v[40:41] op_sel_hi:[1,0]
	v_pk_mul_f32 v[180:181], v[120:121], v[40:41] op_sel:[0,1]
	v_pk_mul_f32 v[184:185], v[126:127], v[40:41] op_sel:[0,1]
	v_pk_mul_f32 v[178:179], v[118:119], v[40:41] op_sel:[0,1]
	v_mov_b64_e32 v[116:117], 0x500
	v_mov_b64_e32 v[110:111], 0x600
	v_mov_b64_e32 v[108:109], 0x700
	v_mov_b64_e32 v[120:121], v[170:171]
	v_mov_b64_e32 v[118:119], v[172:173]
	v_mov_b64_e32 v[112:113], v[134:135]
	v_mov_b64_e32 v[114:115], v[138:139]
	s_xor_b64 exec, exec, s[36:37]
	s_cbranch_execz .LBB0_4357
	v_cmp_eq_u32_e32 vcc, 0, v3
	s_mov_b64 s[40:41], s[34:35]
	s_and_saveexec_b64 s[38:39], vcc
	s_cbranch_execz .LBB0_4356
	s_nop 7
	s_nop 3
	v_cvt_pk_bf16_f32 v109, v191, v193
	v_cvt_pk_bf16_f32 v108, v190, v192
	s_nop 7
	v_cvt_pk_bf16_f32 v129, v189, v187
	v_cvt_pk_bf16_f32 v128, v188, v186
	s_or_b64 s[40:41], s[34:35], exec
	global_store_dwordx2 v[158:159], v[108:109], off

; __device__ __forceinline__ unsigned pk2(float lo, float hi) { return f2bf(lo) | (f2bf(hi) << 16); }
;     __device__ __forceinline__ void operator()(const f32x4 (&acc)[2][2][4][2], const pg8::Unit& u, int wr, int wc, int fr, int fq) const {
;     ...
;             if (fr == 0) {
; #pragma unroll
;                 for (int q = 0; q < 2; ++q) { v2u a, b; a.x = pk2(g[q][0], g[q][1]); a.y = pk2(g[q][2], g[q][3]); b.x = pk2(v[q][0], v[q][1]); b.y = pk2(v[q][2], v[q][3]);
;                     *(v2u*)(hb + (size_t)q * 256 + 4 * n) = a; *(v2u*)(hb + (size_t)q * 256 + 128 + 4 * n) = b; } }
;             if (fr == 15) {
; #pragma unroll
;                 for (int q = 0; q < 2; ++q) { v2u a, b; a.x = pk2(g[6 + q][0], g[6 + q][1]); a.y = pk2(g[6 + q][2], g[6 + q][3]); b.x = pk2(v[6 + q][0], v[6 + q][1]); b.y = pk2(v[6 + q][2], v[6 + q][3]);
;                     *(v2u*)(hb + (size_t)(2 + q) * 256 + 4 * n) = a; *(v2u*)(hb + (size_t)(2 + q) * 256 + 128 + 4 * n) = b; } }
;             const int cc = ch0 + 4 * n;
;             const f32x4 wg0 = *(CF4)(cw + cc), wg1 = *(CF4)(cw + FF2 + cc), wg2 = *(CF4)(cw + 2 * FF2 + cc), wv0 = *(CF4)(cw + FFH + cc), wv1 = *(CF4)(cw + FF2 + FFH + cc), wv2 = *(CF4)(cw + 2 * FF2 + FFH + cc);
;             const f32x4 bg = *(CF4)(cb + cc), bv = *(CF4)(cb + FFH + cc);
.LBB0_4357:
	s_or_b64 exec, exec, s[36:37]
	s_and_saveexec_b64 s[36:37], s[34:35]
	s_cbranch_execz .LBB0_4359
	v_lshl_add_u64 v[116:117], v[158:159], 0, v[116:117]
	global_store_dwordx2 v[116:117], v[128:129], off
	v_and_b32_sdwa v116, v121, v234 dst_sel:DWORD dst_unused:UNUSED_PAD src0_sel:WORD_1 src1_sel:DWORD
	s_nop 1
	v_add3_u32 v116, v121, v116, s59
	v_and_b32_sdwa v117, v119, v234 dst_sel:DWORD dst_unused:UNUSED_PAD src0_sel:WORD_1 src1_sel:DWORD
	s_nop 0
	v_add3_u32 v117, v119, v117, s59
	s_nop 0
	v_and_b32_e32 v117, 0xffff0000, v117
	s_nop 0
	v_or_b32_sdwa v117, v117, v116 dst_sel:DWORD dst_unused:UNUSED_PAD src0_sel:DWORD src1_sel:WORD_1
	v_cvt_pk_bf16_f32 v116, v120, v118
	s_nop 7
	s_nop 1
	v_cvt_pk_bf16_f32 v113, v113, v115
	v_cvt_pk_bf16_f32 v112, v112, v114
	v_lshl_add_u64 v[110:111], v[158:159], 0, v[110:111]
	v_lshl_add_u64 v[108:109], v[158:159], 0, v[108:109]
	global_store_dwordx2 v[110:111], v[116:117], off
	global_store_dwordx2 v[108:109], v[112:113], off
.LBB0_4359:
	s_or_b64 exec, exec, s[36:37]
	v_lshl_or_b32 v132, s61, 7, v227
	v_ashrrev_i32_e32 v133, 31, v132
	v_lshlrev_b64 v[194:195], 2, v[132:133]
	v_lshl_add_u64 v[108:109], s[6:7], 0, v[194:195]
	v_lshl_add_u64 v[112:113], s[8:9], 0, v[194:195]
	global_load_dwordx4 v[108:111], v[108:109], off
	v_mov_b32_e32 v166, v43
	global_load_dwordx4 v[116:119], v[112:113], off
	v_lshl_add_u64 v[112:113], s[12:13], 0, v[194:195]
	global_load_dwordx4 v[120:123], v[112:113], off
	v_lshl_add_u64 v[112:113], s[14:15], 0, v[194:195]
	global_load_dwordx4 v[124:127], v[112:113], off
	v_mov_b32_e32 v112, v104
	v_mov_b32_e32 v113, v106
	v_pk_mul_f32 v[224:225], v[112:113], v[42:43] op_sel_hi:[1,0]
	v_mov_b32_e32 v112, v96
	v_mov_b32_e32 v113, v98
	v_mov_b32_e32 v98, v97
	v_lshl_add_u64 v[96:97], s[16:17], 0, v[194:195]
	v_pk_mul_f32 v[218:219], v[98:99], v[42:43] op_sel_hi:[1,0]
	global_load_dwordx4 v[96:99], v[96:97], off
	v_pk_mul_f32 v[220:221], v[112:113], v[42:43] op_sel_hi:[1,0]
	v_mov_b32_e32 v106, v105
	v_mov_b32_e32 v112, v100
	v_mov_b32_e32 v113, v102
	v_lshl_add_u64 v[104:105], s[22:23], 0, v[194:195]
	v_pk_mul_f32 v[222:223], v[106:107], v[42:43] op_sel_hi:[1,0]
	global_load_dwordx4 v[104:107], v[104:105], off
	v_pk_mul_f32 v[214:215], v[112:113], v[166:167] op_sel_hi:[1,0]
	v_lshl_add_u64 v[112:113], s[18:19], 0, v[194:195]
	global_load_dwordx4 v[112:115], v[112:113], off
	v_mov_b32_e32 v102, v101
	v_lshl_add_u64 v[100:101], s[20:21], 0, v[194:195]
	v_pk_mul_f32 v[216:217], v[102:103], v[166:167] op_sel_hi:[1,0]
	global_load_dwordx4 v[100:103], v[100:101], off
	v_mov_b32_e32 v199, v94
	v_mov_b32_e32 v94, v93
	v_mov_b32_e32 v196, v36
	v_mov_b32_e32 v197, v37
	v_pk_mul_f32 v[206:207], v[94:95], v[166:167] op_sel_hi:[1,0]
	v_mov_b32_e32 v94, v88
	v_mov_b32_e32 v95, v90
	v_pk_mul_f32 v[202:203], v[94:95], v[196:197] op_sel_hi:[1,0]
	v_mov_b32_e32 v94, v80
	v_mov_b32_e32 v95, v82
	v_mov_b32_e32 v82, v81
	v_mov_b32_e32 v80, v84
	v_mov_b32_e32 v81, v86
	v_mov_b32_e32 v90, v89
	v_pk_mul_f32 v[88:89], v[80:81], v[196:197] op_sel:[0,1]
	v_mov_b32_e32 v81, v78
	v_mov_b32_e32 v86, v85
	v_mov_b32_e32 v78, v77
	v_pk_mul_f32 v[194:195], v[94:95], v[196:197] op_sel_hi:[1,0]
	v_mov_b32_e32 v80, v76
	v_pk_mul_f32 v[84:85], v[86:87], v[196:197] op_sel:[0,1]
	v_pk_mul_f32 v[76:77], v[78:79], v[196:197] op_sel:[0,1]
	v_mov_b32_dpp v78, v168 row_shr:1 row_mask:0xf bank_mask:0xf bound_ctrl:1
	v_mov_b32_dpp v79, v169 row_shr:1 row_mask:0xf bank_mask:0xf bound_ctrl:1
	v_mov_b32_e32 v198, v92
	v_pk_mul_f32 v[200:201], v[90:91], v[196:197] op_sel_hi:[1,0]
	v_pk_mul_f32 v[90:91], v[82:83], v[196:197] op_sel_hi:[1,0]
	v_pk_mul_f32 v[82:83], v[80:81], v[196:197] op_sel:[0,1]
	v_mov_b32_dpp v80, v170 row_shr:1 row_mask:0xf bank_mask:0xf bound_ctrl:1
	v_mov_b32_dpp v81, v171 row_shr:1 row_mask:0xf bank_mask:0xf bound_ctrl:1
	v_pk_mul_f32 v[208:209], v[198:199], v[166:167] op_sel_hi:[1,0]
	v_mov_b32_dpp v210, v136 row_shr:1 row_mask:0xf bank_mask:0xf bound_ctrl:1
	v_mov_b32_dpp v211, v137 row_shr:1 row_mask:0xf bank_mask:0xf bound_ctrl:1
	v_mov_b32_dpp v238, v172 row_shr:1 row_mask:0xf bank_mask:0xf bound_ctrl:1
	v_mov_b32_dpp v239, v173 row_shr:1 row_mask:0xf bank_mask:0xf bound_ctrl:1
	v_mov_b32_dpp v204, v162 row_shr:1 row_mask:0xf bank_mask:0xf bound_ctrl:1
	v_mov_b32_dpp v205, v163 row_shr:1 row_mask:0xf bank_mask:0xf bound_ctrl:1
	v_mov_b32_dpp v236, v134 row_shr:1 row_mask:0xf bank_mask:0xf bound_ctrl:1
	v_mov_b32_dpp v237, v135 row_shr:1 row_mask:0xf bank_mask:0xf bound_ctrl:1
	v_mov_b32_dpp v212, v130 row_shr:1 row_mask:0xf bank_mask:0xf bound_ctrl:1
	v_mov_b32_dpp v213, v131 row_shr:1 row_mask:0xf bank_mask:0xf bound_ctrl:1
	v_mov_b32_dpp v240, v138 row_shr:1 row_mask:0xf bank_mask:0xf bound_ctrl:1
	v_mov_b32_dpp v241, v139 row_shr:1 row_mask:0xf bank_mask:0xf bound_ctrl:1
	v_mov_b32_e32 v174, v40
	v_mov_b32_e32 v175, v40
	v_mov_b32_e32 v40, v41
	v_mov_b32_e32 v176, v38
	v_mov_b32_e32 v177, v38
	v_mov_b32_e32 v38, v39
	v_mov_b32_e32 v128, v42
	s_waitcnt vmcnt(0)
; __device__ __forceinline__ unsigned pk2(float lo, float hi) { return f2bf(lo) | (f2bf(hi) << 16); }
; __device__ __forceinline__ float silu_fast(float x) { return x * __builtin_amdgcn_rcpf(1.f + __builtin_amdgcn_exp2f(-1.4426950408889634f * x)); }
; __device__ __forceinline__ float dpp_shr1(float x) { return __builtin_bit_cast(float, __builtin_amdgcn_update_dpp(0, __builtin_bit_cast(int, x), 0x111, 0xf, 0xf, true)); }
;     __device__ __forceinline__ void operator()(const f32x4 (&acc)[2][2][4][2], const pg8::Unit& u, int wr, int wc, int fr, int fq) const {
;     ...
;             for (int jj = 0; jj < 4; ++jj) {
;                 float g2 = dpp_shr1(g[6][jj]), g1 = dpp_shr1(g[7][jj]), v2 = dpp_shr1(v[6][jj]), v1 = dpp_shr1(v[7][jj]);
; #pragma unroll
;                 for (int e = 0; e < 8; ++e) { const float g0 = g[e][jj], v0 = v[e][jj];
;                     const float cg = bg[jj] + wg0[jj] * g2 + wg1[jj] * g1 + wg2[jj] * g0, cv = bv[jj] + wv0[jj] * v2 + wv1[jj] * v1 + wv2[jj] * v0;
;                     g[e][jj] = silu_fast(cg) * cv; g2 = g1; g1 = g0; v2 = v1; v1 = v0; } }
; #pragma unroll
;             for (int e = 0; e < 8; ++e) { v2u w; w.x = pk2(g[e][0], g[e][1]); w.y = pk2(g[e][2], g[e][3]); *(v2u*)(ACT + (size_t)(tok0 + e) * FFH + cc) = w; }
	v_mov_b32_e32 v86, v108
	v_mov_b32_e32 v87, v110
	v_mov_b32_e32 v94, v116
	v_mov_b32_e32 v95, v118
	v_pk_fma_f32 v[78:79], v[86:87], v[78:79], v[94:95]
	v_mov_b32_e32 v196, v120
	v_mov_b32_e32 v197, v122
	v_pk_fma_f32 v[78:79], v[196:197], v[80:81], v[78:79]
	v_mov_b32_e32 v198, v124
	v_mov_b32_e32 v199, v126
	v_pk_fma_f32 v[78:79], v[190:191], v[198:199], v[78:79]
	v_mov_b32_e32 v110, v109
	v_mul_f32_e32 v108, 0xbfb8aa3b, v78
	v_mov_b32_e32 v118, v117
	v_exp_f32_e32 v116, v108
	v_pk_fma_f32 v[108:109], v[110:111], v[210:211], v[118:119]
	v_mov_b32_e32 v122, v121
	v_pk_fma_f32 v[108:109], v[122:123], v[238:239], v[108:109]
	v_mov_b32_e32 v126, v125
	v_pk_fma_f32 v[108:109], v[192:193], v[126:127], v[108:109]
	v_add_f32_e32 v116, 1.0, v116
	v_mul_f32_e32 v117, 0xbfb8aa3b, v108
	v_exp_f32_e32 v117, v117
	v_rcp_f32_e32 v210, v116
	v_mov_b32_e32 v120, v104
	v_mov_b32_e32 v121, v106
	v_add_f32_e32 v116, 1.0, v117
	v_rcp_f32_e32 v242, v116
	v_mov_b32_e32 v116, v96
	v_mul_f32_e32 v96, 0xbfb8aa3b, v79
	v_exp_f32_e32 v96, v96
	v_mov_b32_e32 v117, v98
	v_pk_fma_f32 v[124:125], v[116:117], v[204:205], v[120:121]
	v_mov_b32_e32 v204, v112
	v_add_f32_e32 v96, 1.0, v96
	v_mov_b32_e32 v205, v114
	v_rcp_f32_e32 v211, v96
	v_mul_f32_e32 v96, 0xbfb8aa3b, v109
	v_pk_fma_f32 v[244:245], v[204:205], v[236:237], v[124:125]
	v_mov_b32_e32 v124, v100
	v_exp_f32_e32 v100, v96
	v_mov_b32_e32 v98, v97
	v_mov_b32_e32 v106, v105
	v_mov_b32_e32 v125, v102
	v_add_f32_e32 v100, 1.0, v100
	v_rcp_f32_e32 v243, v100
	v_pk_fma_f32 v[96:97], v[98:99], v[212:213], v[106:107]
	v_mov_b32_e32 v114, v113
	v_pk_fma_f32 v[244:245], v[188:189], v[124:125], v[244:245]
	v_pk_mul_f32 v[78:79], v[78:79], v[210:211]
	v_pk_fma_f32 v[96:97], v[114:115], v[240:241], v[96:97]
	v_mov_b32_e32 v102, v101
	v_pk_mul_f32 v[78:79], v[244:245], v[78:79]
	v_pk_fma_f32 v[96:97], v[186:187], v[102:103], v[96:97]
	v_pk_mul_f32 v[100:101], v[108:109], v[242:243]
	v_pk_fma_f32 v[80:81], v[86:87], v[80:81], v[94:95]
	v_pk_mul_f32 v[96:97], v[96:97], v[100:101]
	s_nop 7
	s_nop 1
	v_mov_b64_e32 v[210:211], s[78:79]
	v_pk_fma_f32 v[80:81], v[190:191], v[196:197], v[80:81]
	v_cvt_pk_bf16_f32 v79, v79, v97
	v_cvt_pk_bf16_f32 v78, v78, v96
	v_mad_i64_i32 v[96:97], s[34:35], v160, s60, v[210:211]
	v_lshlrev_b64 v[212:213], 1, v[132:133]
	v_pk_fma_f32 v[80:81], v[182:183], v[198:199], v[80:81]
	v_lshl_add_u64 v[112:113], v[96:97], 0, v[212:213]
	v_mul_f32_e32 v96, 0xbfb8aa3b, v80
	v_exp_f32_e32 v100, v96
	v_pk_fma_f32 v[96:97], v[110:111], v[238:239], v[118:119]
	global_store_dwordx2 v[112:113], v[78:79], off
	v_pk_fma_f32 v[96:97], v[192:193], v[122:123], v[96:97]
	v_add_f32_e32 v78, 1.0, v100
	v_pk_fma_f32 v[96:97], v[184:185], v[126:127], v[96:97]
	v_mul_f32_e32 v100, 0xbfb8aa3b, v81
	v_mul_f32_e32 v101, 0xbfb8aa3b, v96
	v_exp_f32_e32 v101, v101
	v_rcp_f32_e32 v78, v78
	v_pk_fma_f32 v[104:105], v[116:117], v[236:237], v[120:121]
	v_mov_b32_e32 v129, v42
	v_add_f32_e32 v79, 1.0, v101
	v_exp_f32_e32 v101, v100
	v_rcp_f32_e32 v100, v79
	v_pk_fma_f32 v[104:105], v[188:189], v[204:205], v[104:105]
	v_mov_b32_e32 v42, v43
	v_add_f32_e32 v79, 1.0, v101
	v_mul_f32_e32 v101, 0xbfb8aa3b, v97
	v_rcp_f32_e32 v79, v79
	v_exp_f32_e32 v101, v101
	v_pk_fma_f32 v[104:105], v[180:181], v[124:125], v[104:105]
	v_mov_b32_e32 v92, v36
	v_pk_mul_f32 v[78:79], v[80:81], v[78:79]
	v_add_f32_e32 v80, 1.0, v101
	v_rcp_f32_e32 v101, v80
	v_pk_fma_f32 v[80:81], v[98:99], v[240:241], v[106:107]
	v_pk_mul_f32 v[78:79], v[104:105], v[78:79]
	v_pk_fma_f32 v[80:81], v[186:187], v[114:115], v[80:81]
	v_pk_mul_f32 v[96:97], v[96:97], v[100:101]
	v_pk_fma_f32 v[80:81], v[178:179], v[102:103], v[80:81]
	v_pk_fma_f32 v[104:105], v[188:189], v[116:117], v[120:121]
	v_pk_mul_f32 v[80:81], v[80:81], v[96:97]
	s_nop 7
	s_nop 1
	v_cvt_pk_bf16_f32 v78, v78, v80
	v_or_b32_e32 v80, 1, v160
	v_cvt_pk_bf16_f32 v79, v79, v81
	v_mad_i64_i32 v[80:81], s[34:35], v80, s60, v[210:211]
	v_lshl_add_u64 v[108:109], v[80:81], 0, v[212:213]
	v_pk_fma_f32 v[80:81], v[190:191], v[86:87], v[94:95]
	global_store_dwordx2 v[108:109], v[78:79], off
	v_pk_fma_f32 v[80:81], v[182:183], v[196:197], v[80:81]
	v_pk_fma_f32 v[104:105], v[180:181], v[204:205], v[104:105]
	v_pk_fma_f32 v[80:81], v[224:225], v[198:199], v[80:81]
	v_pk_fma_f32 v[104:105], v[220:221], v[124:125], v[104:105]
	v_mul_f32_e32 v96, 0xbfb8aa3b, v80
	v_exp_f32_e32 v100, v96
	v_pk_fma_f32 v[96:97], v[192:193], v[110:111], v[118:119]
	v_pk_fma_f32 v[180:181], v[180:181], v[116:117], v[120:121]
	v_pk_fma_f32 v[96:97], v[184:185], v[122:123], v[96:97]
	v_add_f32_e32 v78, 1.0, v100
	v_pk_fma_f32 v[96:97], v[222:223], v[126:127], v[96:97]
	v_mul_f32_e32 v100, 0xbfb8aa3b, v81
	v_mul_f32_e32 v101, 0xbfb8aa3b, v96
	v_exp_f32_e32 v101, v101
	v_rcp_f32_e32 v78, v78
	v_pk_fma_f32 v[180:181], v[220:221], v[204:205], v[180:181]
	v_mov_b32_e32 v93, v36
	v_add_f32_e32 v79, 1.0, v101
	v_exp_f32_e32 v101, v100
	v_rcp_f32_e32 v100, v79
	v_pk_fma_f32 v[180:181], v[208:209], v[124:125], v[180:181]
	v_mov_b32_e32 v36, v37
	v_add_f32_e32 v79, 1.0, v101
	v_mul_f32_e32 v101, 0xbfb8aa3b, v97
	v_rcp_f32_e32 v79, v79
	v_exp_f32_e32 v101, v101
	v_cmp_gt_i32_e32 vcc, 15, v3
	s_mov_b64 s[36:37], -1
	v_pk_mul_f32 v[78:79], v[80:81], v[78:79]
	v_add_f32_e32 v80, 1.0, v101
	v_rcp_f32_e32 v101, v80
	v_pk_fma_f32 v[80:81], v[186:187], v[98:99], v[106:107]
	v_pk_mul_f32 v[78:79], v[104:105], v[78:79]
	v_pk_fma_f32 v[80:81], v[178:179], v[114:115], v[80:81]
	v_pk_mul_f32 v[96:97], v[96:97], v[100:101]
	v_pk_fma_f32 v[80:81], v[218:219], v[102:103], v[80:81]
	s_nop 0
	v_pk_mul_f32 v[80:81], v[80:81], v[96:97]
	s_nop 7
	s_nop 1
; __device__ __forceinline__ unsigned pk2(float lo, float hi) { return f2bf(lo) | (f2bf(hi) << 16); }
; __device__ __forceinline__ float silu_fast(float x) { return x * __builtin_amdgcn_rcpf(1.f + __builtin_amdgcn_exp2f(-1.4426950408889634f * x)); }
; __device__ __forceinline__ float dpp_shr1(float x) { return __builtin_bit_cast(float, __builtin_amdgcn_update_dpp(0, __builtin_bit_cast(int, x), 0x111, 0xf, 0xf, true)); }
;     __device__ __forceinline__ void operator()(const f32x4 (&acc)[2][2][4][2], const pg8::Unit& u, int wr, int wc, int fr, int fq) const {
;     ...
;             for (int jj = 0; jj < 4; ++jj) {
;                 float g2 = dpp_shr1(g[6][jj]), g1 = dpp_shr1(g[7][jj]), v2 = dpp_shr1(v[6][jj]), v1 = dpp_shr1(v[7][jj]);
; #pragma unroll
;                 for (int e = 0; e < 8; ++e) { const float g0 = g[e][jj], v0 = v[e][jj];
;                     const float cg = bg[jj] + wg0[jj] * g2 + wg1[jj] * g1 + wg2[jj] * g0, cv = bv[jj] + wv0[jj] * v2 + wv1[jj] * v1 + wv2[jj] * v0;
;                     g[e][jj] = silu_fast(cg) * cv; g2 = g1; g1 = g0; v2 = v1; v1 = v0; } }
; #pragma unroll
;             for (int e = 0; e < 8; ++e) { v2u w; w.x = pk2(g[e][0], g[e][1]); w.y = pk2(g[e][2], g[e][3]); *(v2u*)(ACT + (size_t)(tok0 + e) * FFH + cc) = w; }
	v_cvt_pk_bf16_f32 v78, v78, v80
	v_or_b32_e32 v80, 2, v160
	v_cvt_pk_bf16_f32 v79, v79, v81
	v_mad_i64_i32 v[80:81], s[34:35], v80, s60, v[210:211]
	v_lshl_add_u64 v[104:105], v[80:81], 0, v[212:213]
	v_pk_fma_f32 v[80:81], v[182:183], v[86:87], v[94:95]
	global_store_dwordx2 v[104:105], v[78:79], off
	v_pk_fma_f32 v[80:81], v[224:225], v[196:197], v[80:81]
	v_pk_fma_f32 v[182:183], v[208:209], v[116:117], v[120:121]
	v_pk_fma_f32 v[80:81], v[214:215], v[198:199], v[80:81]
	v_pk_fma_f32 v[182:183], v[194:195], v[204:205], v[182:183]
	v_mul_f32_e32 v96, 0xbfb8aa3b, v80
	v_exp_f32_e32 v100, v96
	v_pk_fma_f32 v[96:97], v[184:185], v[110:111], v[118:119]
	v_pk_fma_f32 v[182:183], v[82:83], v[124:125], v[182:183]
	v_pk_fma_f32 v[96:97], v[222:223], v[122:123], v[96:97]
	v_add_f32_e32 v78, 1.0, v100
	v_pk_fma_f32 v[96:97], v[216:217], v[126:127], v[96:97]
	v_mul_f32_e32 v100, 0xbfb8aa3b, v81
	v_mul_f32_e32 v101, 0xbfb8aa3b, v96
	v_exp_f32_e32 v101, v101
	v_rcp_f32_e32 v78, v78
	v_pk_fma_f32 v[184:185], v[194:195], v[116:117], v[120:121]
	v_add_f32_e32 v79, 1.0, v101
	v_exp_f32_e32 v101, v100
	v_rcp_f32_e32 v100, v79
	v_pk_fma_f32 v[184:185], v[82:83], v[204:205], v[184:185]
	v_pk_fma_f32 v[82:83], v[82:83], v[116:117], v[120:121]
	v_add_f32_e32 v79, 1.0, v101
	v_mul_f32_e32 v101, 0xbfb8aa3b, v97
	v_rcp_f32_e32 v79, v79
	v_exp_f32_e32 v101, v101
	v_pk_fma_f32 v[184:185], v[162:163], v[124:125], v[184:185]
	v_pk_fma_f32 v[82:83], v[162:163], v[204:205], v[82:83]
	v_pk_mul_f32 v[78:79], v[80:81], v[78:79]
	v_add_f32_e32 v80, 1.0, v101
	v_rcp_f32_e32 v101, v80
	v_pk_fma_f32 v[80:81], v[178:179], v[98:99], v[106:107]
	v_pk_mul_f32 v[78:79], v[180:181], v[78:79]
	v_pk_fma_f32 v[80:81], v[218:219], v[114:115], v[80:81]
	v_pk_mul_f32 v[96:97], v[96:97], v[100:101]
	v_pk_fma_f32 v[80:81], v[206:207], v[102:103], v[80:81]
	v_pk_fma_f32 v[180:181], v[220:221], v[116:117], v[120:121]
	v_pk_mul_f32 v[80:81], v[80:81], v[96:97]
	s_nop 7
	s_nop 1
	v_cvt_pk_bf16_f32 v78, v78, v80
	v_or_b32_e32 v80, 3, v160
	v_cvt_pk_bf16_f32 v79, v79, v81
	v_mad_i64_i32 v[80:81], s[34:35], v80, s60, v[210:211]
	v_lshl_add_u64 v[100:101], v[80:81], 0, v[212:213]
	v_pk_fma_f32 v[80:81], v[224:225], v[86:87], v[94:95]
	global_store_dwordx2 v[100:101], v[78:79], off
	v_pk_fma_f32 v[80:81], v[214:215], v[196:197], v[80:81]
	v_pk_fma_f32 v[180:181], v[208:209], v[204:205], v[180:181]
	v_pk_fma_f32 v[80:81], v[202:203], v[198:199], v[80:81]
	v_pk_fma_f32 v[180:181], v[194:195], v[124:125], v[180:181]
	v_mul_f32_e32 v96, 0xbfb8aa3b, v80
	v_exp_f32_e32 v133, v96
	v_pk_fma_f32 v[96:97], v[222:223], v[110:111], v[118:119]
	v_pk_fma_f32 v[82:83], v[134:135], v[124:125], v[82:83]
	v_pk_fma_f32 v[96:97], v[216:217], v[122:123], v[96:97]
	v_add_f32_e32 v78, 1.0, v133
	v_pk_fma_f32 v[96:97], v[200:201], v[126:127], v[96:97]
	v_mul_f32_e32 v133, 0xbfb8aa3b, v81
	v_mul_f32_e32 v161, 0xbfb8aa3b, v96
	v_exp_f32_e32 v161, v161
	v_exp_f32_e32 v133, v133
	v_rcp_f32_e32 v78, v78
	v_add_f32_e32 v79, 1.0, v161
	v_rcp_f32_e32 v178, v79
	v_add_f32_e32 v79, 1.0, v133
	v_mul_f32_e32 v133, 0xbfb8aa3b, v97
	v_rcp_f32_e32 v79, v79
	v_exp_f32_e32 v133, v133
	v_pk_mul_f32 v[78:79], v[80:81], v[78:79]
	v_add_f32_e32 v80, 1.0, v133
	v_rcp_f32_e32 v179, v80
	v_pk_fma_f32 v[80:81], v[218:219], v[98:99], v[106:107]
	v_pk_mul_f32 v[78:79], v[180:181], v[78:79]
	v_pk_fma_f32 v[80:81], v[206:207], v[114:115], v[80:81]
	v_pk_mul_f32 v[96:97], v[96:97], v[178:179]
	v_pk_fma_f32 v[80:81], v[90:91], v[102:103], v[80:81]
	v_pk_fma_f32 v[178:179], v[216:217], v[110:111], v[118:119]
	v_pk_mul_f32 v[80:81], v[80:81], v[96:97]
	s_nop 7
	s_nop 1
	v_cvt_pk_bf16_f32 v78, v78, v80
	v_or_b32_e32 v80, 4, v160
	v_cvt_pk_bf16_f32 v79, v79, v81
	v_mad_i64_i32 v[80:81], s[34:35], v80, s60, v[210:211]
	v_lshl_add_u64 v[96:97], v[80:81], 0, v[212:213]
	v_pk_fma_f32 v[80:81], v[214:215], v[86:87], v[94:95]
	v_pk_fma_f32 v[178:179], v[200:201], v[122:123], v[178:179]
	v_pk_fma_f32 v[80:81], v[202:203], v[196:197], v[80:81]
	v_pk_fma_f32 v[178:179], v[84:85], v[126:127], v[178:179]
	v_pk_fma_f32 v[80:81], v[88:89], v[198:199], v[80:81]
	v_mul_f32_e32 v161, 0xbfb8aa3b, v178
	v_mul_f32_e32 v133, 0xbfb8aa3b, v80
	v_exp_f32_e32 v133, v133
	v_exp_f32_e32 v161, v161
	global_store_dwordx2 v[96:97], v[78:79], off
	v_add_f32_e32 v78, 1.0, v133
	v_mul_f32_e32 v133, 0xbfb8aa3b, v81
	v_exp_f32_e32 v133, v133
	v_add_f32_e32 v79, 1.0, v161
	v_rcp_f32_e32 v180, v79
	v_rcp_f32_e32 v78, v78
	v_add_f32_e32 v79, 1.0, v133
	v_mul_f32_e32 v133, 0xbfb8aa3b, v179
	v_rcp_f32_e32 v79, v79
	v_exp_f32_e32 v133, v133
	v_pk_mul_f32 v[78:79], v[80:81], v[78:79]
	v_add_f32_e32 v80, 1.0, v133
	v_rcp_f32_e32 v181, v80
	v_pk_fma_f32 v[80:81], v[206:207], v[98:99], v[106:107]
	v_pk_mul_f32 v[78:79], v[182:183], v[78:79]
	v_pk_fma_f32 v[80:81], v[90:91], v[114:115], v[80:81]
	v_pk_mul_f32 v[178:179], v[178:179], v[180:181]
	v_pk_fma_f32 v[80:81], v[76:77], v[102:103], v[80:81]
	s_nop 0
	v_pk_mul_f32 v[80:81], v[80:81], v[178:179]
	v_pk_fma_f32 v[178:179], v[202:203], v[86:87], v[94:95]
	s_nop 0
	v_pk_fma_f32 v[178:179], v[88:89], v[196:197], v[178:179]
	s_nop 3
	v_pk_fma_f32 v[178:179], v[168:169], v[198:199], v[178:179]
	s_nop 1
	v_mul_f32_e32 v133, 0xbfb8aa3b, v178
	s_nop 0
	v_exp_f32_e32 v133, v133
	v_pk_fma_f32 v[180:181], v[200:201], v[110:111], v[118:119]
	s_nop 0
	v_cvt_pk_bf16_f32 v78, v78, v80
	v_or_b32_e32 v80, 5, v160
	v_pk_fma_f32 v[180:181], v[84:85], v[122:123], v[180:181]
	v_cvt_pk_bf16_f32 v79, v79, v81
	v_mad_i64_i32 v[80:81], s[34:35], v80, s60, v[210:211]
	v_pk_fma_f32 v[180:181], v[136:137], v[126:127], v[180:181]
	v_lshl_add_u64 v[80:81], v[80:81], 0, v[212:213]
; __device__ __forceinline__ unsigned pk2(float lo, float hi) { return f2bf(lo) | (f2bf(hi) << 16); }
; __device__ __forceinline__ float silu_fast(float x) { return x * __builtin_amdgcn_rcpf(1.f + __builtin_amdgcn_exp2f(-1.4426950408889634f * x)); }
; __device__ __forceinline__ float dpp_shr1(float x) { return __builtin_bit_cast(float, __builtin_amdgcn_update_dpp(0, __builtin_bit_cast(int, x), 0x111, 0xf, 0xf, true)); }
;     __device__ __forceinline__ void operator()(const f32x4 (&acc)[2][2][4][2], const pg8::Unit& u, int wr, int wc, int fr, int fq) const {
;     ...
;             for (int e = 0; e < 8; ++e) { const float rs = (e < 4) ? r0[e & 3] : r1[e & 3];
; #pragma unroll
;                 for (int jj = 0; jj < 4; ++jj) { g[e][jj] = acc[e >> 2][0][e & 3][n][jj] * rs; v[e][jj] = acc[e >> 2][1][e & 3][n][jj] * rs; } }
;             if (fr == 0) {
; #pragma unroll
;                 for (int q = 0; q < 2; ++q) { v2u a, b; a.x = pk2(g[q][0], g[q][1]); a.y = pk2(g[q][2], g[q][3]); b.x = pk2(v[q][0], v[q][1]); b.y = pk2(v[q][2], v[q][3]);
;                     *(v2u*)(hb + (size_t)q * 256 + 4 * n) = a; *(v2u*)(hb + (size_t)q * 256 + 128 + 4 * n) = b; } }
;             if (fr == 15) {
; #pragma unroll
;                 for (int q = 0; q < 2; ++q) { v2u a, b; a.x = pk2(g[6 + q][0], g[6 + q][1]); a.y = pk2(g[6 + q][2], g[6 + q][3]); b.x = pk2(v[6 + q][0], v[6 + q][1]); b.y = pk2(v[6 + q][2], v[6 + q][3]);
;                     *(v2u*)(hb + (size_t)(2 + q) * 256 + 4 * n) = a; *(v2u*)(hb + (size_t)(2 + q) * 256 + 128 + 4 * n) = b; } }
;     ...
;             for (int jj = 0; jj < 4; ++jj) {
;                 float g2 = dpp_shr1(g[6][jj]), g1 = dpp_shr1(g[7][jj]), v2 = dpp_shr1(v[6][jj]), v1 = dpp_shr1(v[7][jj]);
; #pragma unroll
;                 for (int e = 0; e < 8; ++e) { const float g0 = g[e][jj], v0 = v[e][jj];
;                     const float cg = bg[jj] + wg0[jj] * g2 + wg1[jj] * g1 + wg2[jj] * g0, cv = bv[jj] + wv0[jj] * v2 + wv1[jj] * v1 + wv2[jj] * v0;
;                     g[e][jj] = silu_fast(cg) * cv; g2 = g1; g1 = g0; v2 = v1; v1 = v0; } }
; #pragma unroll
;             for (int e = 0; e < 8; ++e) { v2u w; w.x = pk2(g[e][0], g[e][1]); w.y = pk2(g[e][2], g[e][3]); *(v2u*)(ACT + (size_t)(tok0 + e) * FFH + cc) = w; }
	v_mul_f32_e32 v161, 0xbfb8aa3b, v180
	v_exp_f32_e32 v161, v161
	global_store_dwordx2 v[80:81], v[78:79], off
	v_add_f32_e32 v78, 1.0, v133
	v_mul_f32_e32 v133, 0xbfb8aa3b, v179
	v_exp_f32_e32 v133, v133
	v_add_f32_e32 v79, 1.0, v161
	v_rcp_f32_e32 v182, v79
	v_rcp_f32_e32 v78, v78
	v_add_f32_e32 v79, 1.0, v133
	v_mul_f32_e32 v133, 0xbfb8aa3b, v181
	v_exp_f32_e32 v133, v133
	v_rcp_f32_e32 v79, v79
	v_pk_fma_f32 v[90:91], v[90:91], v[98:99], v[106:107]
	v_pk_fma_f32 v[84:85], v[84:85], v[110:111], v[118:119]
	v_add_f32_e32 v133, 1.0, v133
	v_rcp_f32_e32 v183, v133
	v_pk_mul_f32 v[78:79], v[178:179], v[78:79]
	v_pk_fma_f32 v[90:91], v[76:77], v[114:115], v[90:91]
	v_pk_mul_f32 v[78:79], v[184:185], v[78:79]
	v_pk_fma_f32 v[90:91], v[130:131], v[102:103], v[90:91]
	v_pk_mul_f32 v[178:179], v[180:181], v[182:183]
	s_nop 0
	v_pk_mul_f32 v[90:91], v[90:91], v[178:179]
	s_nop 7
	s_nop 0
	v_cvt_pk_bf16_f32 v90, v78, v90
	v_or_b32_e32 v78, 6, v160
	v_pk_fma_f32 v[86:87], v[88:89], v[86:87], v[94:95]
	v_pk_fma_f32 v[84:85], v[136:137], v[122:123], v[84:85]
	v_cvt_pk_bf16_f32 v91, v79, v91
	v_mad_i64_i32 v[78:79], s[34:35], v78, s60, v[210:211]
	v_pk_fma_f32 v[86:87], v[168:169], v[196:197], v[86:87]
	v_pk_fma_f32 v[84:85], v[172:173], v[126:127], v[84:85]
	v_lshl_add_u64 v[78:79], v[78:79], 0, v[212:213]
	v_pk_fma_f32 v[86:87], v[170:171], v[198:199], v[86:87]
	v_mul_f32_e32 v89, 0xbfb8aa3b, v84
	v_mul_f32_e32 v88, 0xbfb8aa3b, v86
	v_exp_f32_e32 v89, v89
	global_store_dwordx2 v[78:79], v[90:91], off
	v_mul_f32_e32 v90, 0xbfb8aa3b, v87
	v_exp_f32_e32 v88, v88
	v_exp_f32_e32 v91, v90
	v_add_f32_e32 v89, 1.0, v89
	v_rcp_f32_e32 v90, v89
	v_add_f32_e32 v88, 1.0, v88
	v_add_f32_e32 v89, 1.0, v91
	v_rcp_f32_e32 v88, v88
	v_rcp_f32_e32 v89, v89
	v_mul_f32_e32 v91, 0xbfb8aa3b, v85
	v_exp_f32_e32 v91, v91
	v_pk_fma_f32 v[76:77], v[76:77], v[98:99], v[106:107]
	v_pk_mul_f32 v[86:87], v[86:87], v[88:89]
	v_pk_fma_f32 v[76:77], v[130:131], v[114:115], v[76:77]
	v_pk_mul_f32 v[82:83], v[82:83], v[86:87]
	v_add_f32_e32 v86, 1.0, v91
	v_rcp_f32_e32 v91, v86
	v_pk_fma_f32 v[76:77], v[138:139], v[102:103], v[76:77]
	v_pk_mul_f32 v[84:85], v[84:85], v[90:91]
	s_nop 0
	v_pk_mul_f32 v[76:77], v[76:77], v[84:85]
	s_nop 7
	s_nop 1
	v_cvt_pk_bf16_f32 v82, v82, v76
	v_or_b32_e32 v76, 7, v160
	v_cvt_pk_bf16_f32 v83, v83, v77
	v_mad_i64_i32 v[76:77], s[34:35], v76, s60, v[210:211]
	v_lshl_add_u64 v[76:77], v[76:77], 0, v[212:213]
	global_store_dwordx2 v[76:77], v[82:83], off
	v_mov_b32_e32 v82, v72
	v_mov_b32_e32 v83, v74
	v_pk_mul_f32 v[130:131], v[82:83], v[174:175]
	v_mov_b32_e32 v82, v64
	v_mov_b32_e32 v83, v66
	v_mov_b32_e32 v66, v65
	v_mov_b32_e32 v64, v68
	v_mov_b32_e32 v65, v70
	v_pk_mul_f32 v[114:115], v[64:65], v[40:41]
	v_mov_b32_e32 v64, v60
	v_mov_b32_e32 v65, v62
	v_mov_b32_e32 v70, v69
	v_mov_b32_e32 v62, v61
	v_pk_mul_f32 v[116:117], v[64:65], v[40:41]
	v_pk_mul_f32 v[118:119], v[70:71], v[40:41]
	v_pk_mul_f32 v[120:121], v[62:63], v[40:41]
	v_mov_b32_e32 v40, v56
	v_mov_b32_e32 v41, v58
	v_pk_mul_f32 v[88:89], v[40:41], v[176:177]
	v_mov_b32_e32 v40, v48
	v_mov_b32_e32 v41, v50
	v_pk_mul_f32 v[124:125], v[82:83], v[174:175]
	v_pk_mul_f32 v[82:83], v[40:41], v[176:177]
	v_mov_b32_e32 v40, v52
	v_mov_b32_e32 v41, v54
	v_mov_b32_e32 v74, v73
	v_mov_b32_e32 v58, v57
	v_mov_b32_e32 v50, v49
	v_pk_mul_f32 v[94:95], v[40:41], v[38:39]
	v_mov_b32_e32 v40, v44
	v_mov_b32_e32 v41, v46
	v_mov_b32_e32 v54, v53
	v_mov_b32_e32 v46, v45
	v_pk_mul_f32 v[126:127], v[74:75], v[174:175]
	v_pk_mul_f32 v[86:87], v[58:59], v[176:177]
	v_pk_mul_f32 v[72:73], v[50:51], v[176:177]
	v_pk_mul_f32 v[84:85], v[40:41], v[38:39]
	v_pk_mul_f32 v[90:91], v[54:55], v[38:39]
	v_pk_mul_f32 v[74:75], v[46:47], v[38:39]
	v_pk_mul_f32 v[122:123], v[66:67], v[174:175]
	v_mov_b64_e32 v[44:45], 0x408
	v_mov_b64_e32 v[46:47], 0x508
	v_mov_b64_e32 v[38:39], 0x608
	v_mov_b64_e32 v[40:41], 0x708
	v_mov_b64_e32 v[54:55], v[94:95]
	v_mov_b64_e32 v[52:53], v[90:91]
	v_mov_b64_e32 v[50:51], v[84:85]
	v_mov_b64_e32 v[48:49], v[74:75]
	v_mov_b64_e32 v[62:63], v[88:89]
	v_mov_b64_e32 v[60:61], v[86:87]
	v_mov_b64_e32 v[58:59], v[82:83]
	v_mov_b64_e32 v[56:57], v[72:73]
	s_and_saveexec_b64 s[34:35], vcc
	s_cbranch_execz .LBB0_4363
	v_cmp_eq_u32_e32 vcc, 0, v3
	s_mov_b64 s[36:37], 0
	v_mov_b64_e32 v[44:45], 0x408
	v_mov_b64_e32 v[46:47], 0x508
	v_mov_b64_e32 v[38:39], 0x608
	v_mov_b64_e32 v[40:41], 0x708
	s_and_saveexec_b64 s[38:39], vcc
	s_mov_b64 s[36:37], exec
	v_mov_b64_e32 v[44:45], 8
	v_mov_b64_e32 v[46:47], 0x108
	v_mov_b64_e32 v[38:39], 0x208
	v_mov_b64_e32 v[40:41], 0x308
	s_or_b64 exec, exec, s[38:39]
	s_orn2_b64 s[36:37], s[36:37], exec
	v_mov_b64_e32 v[54:55], v[114:115]
	v_mov_b64_e32 v[52:53], v[118:119]
	v_mov_b64_e32 v[50:51], v[116:117]
	v_mov_b64_e32 v[48:49], v[120:121]
	v_mov_b64_e32 v[62:63], v[130:131]
	v_mov_b64_e32 v[60:61], v[126:127]
	v_mov_b64_e32 v[58:59], v[124:125]
	v_mov_b64_e32 v[56:57], v[122:123]
.LBB0_4363:
	s_or_b64 exec, exec, s[34:35]
	s_and_saveexec_b64 s[34:35], s[36:37]
	s_cbranch_execz .LBB0_4346
	s_nop 7
	s_nop 1
	v_cvt_pk_bf16_f32 v61, v63, v61
	v_cvt_pk_bf16_f32 v60, v62, v60
	s_nop 7
	s_nop 1
	v_lshl_add_u64 v[44:45], v[158:159], 0, v[44:45]
	v_cvt_pk_bf16_f32 v57, v59, v57
	v_cvt_pk_bf16_f32 v56, v58, v56
	global_store_dwordx2 v[44:45], v[60:61], off
	v_lshl_add_u64 v[44:45], v[158:159], 0, v[46:47]
	global_store_dwordx2 v[44:45], v[56:57], off
	s_nop 7
	s_nop 1
	v_cvt_pk_bf16_f32 v45, v55, v53
	v_cvt_pk_bf16_f32 v44, v54, v52
	v_and_b32_sdwa v46, v51, v234 dst_sel:DWORD dst_unused:UNUSED_PAD src0_sel:WORD_1 src1_sel:DWORD
	s_nop 1
	v_add3_u32 v46, v51, v46, s59
	v_and_b32_sdwa v47, v49, v234 dst_sel:DWORD dst_unused:UNUSED_PAD src0_sel:WORD_1 src1_sel:DWORD
	s_nop 0
	v_add3_u32 v47, v49, v47, s59
	s_nop 0
	v_and_b32_e32 v47, 0xffff0000, v47
	s_nop 0
	v_lshl_add_u64 v[38:39], v[158:159], 0, v[38:39]
	v_or_b32_sdwa v47, v47, v46 dst_sel:DWORD dst_unused:UNUSED_PAD src0_sel:DWORD src1_sel:WORD_1
	v_cvt_pk_bf16_f32 v46, v50, v48
	global_store_dwordx2 v[38:39], v[44:45], off
	v_lshl_add_u64 v[38:39], v[158:159], 0, v[40:41]
	global_store_dwordx2 v[38:39], v[46:47], off
	s_branch .LBB0_4346

; __device__ __forceinline__ void ffn_fixup(const Ctx& c, const bf16* HALO, const float* cw, const float* cb, bf16* ACT) {
;     for (int it = c.vcu * 512 + c.tid; it < 64 * 44 * 2 * 16; it += c.G * 512) {
;         const int cg8 = it & 15, wr = (it >> 4) & 1, tile = it >> 5, pm = tile / 44, pn = tile % 44, ch0 = 128 * pn + 8 * cg8;
;         const bf16* cur = HALO + ((size_t)(tile * 2 + wr) * 4) * 256 + 8 * cg8;
;         const bool hasprev = wr == 1 || (pm & 15) != 0; const bf16* prv = wr == 1 ? HALO + ((size_t)(tile * 2) * 4 + 2) * 256 + 8 * cg8 : HALO + ((size_t)((tile - 44) * 2 + 1) * 4 + 2) * 256 + 8 * cg8;
;         const v4u z4 = (v4u){0u, 0u, 0u, 0u};
;         const v4u cg0 = *(const v4u*)cur, cv0 = *(const v4u*)(cur + 128), cg1 = *(const v4u*)(cur + 256), cv1 = *(const v4u*)(cur + 256 + 128);
;         const v4u pg2 = hasprev ? *(const v4u*)prv : z4, pv2 = hasprev ? *(const v4u*)(prv + 128) : z4, pg3 = hasprev ? *(const v4u*)(prv + 256) : z4, pv3 = hasprev ? *(const v4u*)(prv + 256 + 128) : z4;
;         float oa[8], ob[8];
; #pragma unroll
;         for (int j = 0; j < 8; ++j) { const int q = j >> 1; const bool hi = j & 1;
;             const float wg0 = cw[ch0 + j], wg1 = cw[FF2 + ch0 + j], wg2 = cw[2 * FF2 + ch0 + j], wv0 = cw[FFH + ch0 + j], wv1 = cw[FF2 + FFH + ch0 + j], wv2 = cw[2 * FF2 + FFH + ch0 + j], bg = cb[ch0 + j], bv = cb[FFH + ch0 + j];
;             const float gA2 = hi ? bfhi(pg2[q]) : bflo(pg2[q]), gA1 = hi ? bfhi(pg3[q]) : bflo(pg3[q]), gA0 = hi ? bfhi(cg0[q]) : bflo(cg0[q]), gB0 = hi ? bfhi(cg1[q]) : bflo(cg1[q]);
;             const float vA2 = hi ? bfhi(pv2[q]) : bflo(pv2[q]), vA1 = hi ? bfhi(pv3[q]) : bflo(pv3[q]), vA0 = hi ? bfhi(cv0[q]) : bflo(cv0[q]), vB0 = hi ? bfhi(cv1[q]) : bflo(cv1[q]);
.LBB0_4425:
	s_or_b64 exec, exec, s[0:1]
	v_mul_lo_u32 v26, v24, 44
	v_sub_u32_e32 v25, v25, v26
	v_lshl_or_b32 v94, v25, 7, v28
	v_ashrrev_i32_e32 v95, 31, v94
	v_lshlrev_b64 v[26:27], 2, v[94:95]
	v_lshl_add_u64 v[42:43], s[10:11], 0, v[26:27]
	s_mov_b64 s[0:1], 0xb000
	v_lshl_add_u64 v[28:29], v[42:43], 0, s[0:1]
	s_mov_b64 s[0:1], 0x16000
	v_lshl_add_u64 v[36:37], v[42:43], 0, s[0:1]
	s_mov_b64 s[0:1], 0x5800
	v_lshl_add_u64 v[38:39], v[26:27], 0, s[0:1]
	v_lshl_add_u64 v[44:45], s[12:13], 0, v[26:27]
	v_ashrrev_i32_e32 v25, 31, v24
	v_lshl_add_u64 v[34:35], s[10:11], 0, v[38:39]
	v_lshl_add_u64 v[48:49], s[12:13], 0, v[38:39]
	s_waitcnt vmcnt(0)
	v_lshlrev_b32_e32 v39, 16, v13
	v_lshlrev_b32_e32 v38, 16, v12
	v_and_b32_e32 v131, 0xffff0000, v13
	v_and_b32_e32 v130, 0xffff0000, v12
	v_lshlrev_b32_e32 v123, 16, v15
	v_lshlrev_b32_e32 v122, 16, v14
	v_and_b32_e32 v121, 0xffff0000, v15
	v_and_b32_e32 v120, 0xffff0000, v14
	v_lshlrev_b64 v[102:103], 8, v[24:25]
	global_load_dwordx4 v[12:15], v[42:43], off offset:16
	global_load_dwordx4 v[60:63], v[42:43], off
	global_load_dwordx4 v[24:27], v[44:45], off offset:16
	global_load_dwordx4 v[64:67], v[44:45], off
	s_mov_b64 s[0:1], 0x10800
	v_lshl_add_u64 v[32:33], v[42:43], 0, s[0:1]
	s_mov_b64 s[0:1], 0x1b800
	v_lshl_add_u64 v[40:41], v[42:43], 0, s[0:1]
	s_mov_b32 s0, 0xb000
	v_lshlrev_b32_e32 v114, 16, v18
	v_and_b32_e32 v104, 0xffff0000, v18
	v_add_co_u32_e32 v18, vcc, s0, v42
	v_lshlrev_b32_e32 v115, 16, v19
	v_and_b32_e32 v105, 0xffff0000, v19
	v_addc_co_u32_e32 v19, vcc, 0, v43, vcc
	v_lshl_or_b32 v88, v30, 7, v102
	global_load_dwordx4 v[68:71], v[18:19], off
	s_nop 0
	global_load_dwordx4 v[28:31], v[28:29], off offset:16
	v_add_co_u32_e32 v18, vcc, s16, v42
	v_lshlrev_b32_e32 v126, 16, v16
	s_nop 0
	v_addc_co_u32_e32 v19, vcc, 0, v43, vcc
	v_and_b32_e32 v124, 0xffff0000, v16
	v_lshlrev_b32_e32 v127, 16, v17
	v_and_b32_e32 v125, 0xffff0000, v17
	v_lshlrev_b32_e32 v98, 16, v20
	v_lshlrev_b32_e32 v99, 16, v21
	v_lshlrev_b32_e32 v101, 16, v57
	v_lshlrev_b32_e32 v100, 16, v56
	s_mov_b32 s0, 0x10000
	v_and_b32_e32 v96, 0xffff0000, v20
	v_and_b32_e32 v97, 0xffff0000, v21
	v_lshlrev_b32_e32 v92, 16, v22
	v_and_b32_e32 v90, 0xffff0000, v22
	v_lshlrev_b32_e32 v93, 16, v23
	v_and_b32_e32 v91, 0xffff0000, v23
	v_and_b32_e32 v129, 0xffff0000, v57
	v_and_b32_e32 v128, 0xffff0000, v56
	v_lshlrev_b32_e32 v106, 16, v76
	v_lshlrev_b32_e32 v107, 16, v77
	v_lshlrev_b32_e32 v109, 16, v53
	v_lshlrev_b32_e32 v108, 16, v52
	v_and_b32_e32 v53, 0xffff0000, v53
	v_and_b32_e32 v52, 0xffff0000, v52
	v_add_u32_e32 v3, s17, v3
	v_add_u32_e32 v134, s18, v134
	s_waitcnt vmcnt(0)
	v_mov_b32_e32 v110, v60
	v_mov_b32_e32 v111, v62
	v_mov_b32_e32 v112, v64
	v_mov_b32_e32 v113, v66
	v_pk_fma_f32 v[16:17], v[110:111], v[38:39], v[112:113]
	global_load_dwordx4 v[80:83], v[18:19], off
	s_nop 0
	global_load_dwordx4 v[36:39], v[36:37], off offset:16
	v_mov_b32_e32 v62, v61
	v_mov_b32_e32 v66, v65
	v_pk_fma_f32 v[56:57], v[62:63], v[130:131], v[66:67]
	v_pk_fma_f32 v[62:63], v[62:63], v[96:97], v[66:67]
	v_mov_b32_e32 v116, v68
	v_mov_b32_e32 v117, v70
	v_pk_fma_f32 v[16:17], v[116:117], v[98:99], v[16:17]
	v_mov_b32_e32 v70, v69
	v_pk_fma_f32 v[56:57], v[70:71], v[96:97], v[56:57]
	v_pk_fma_f32 v[62:63], v[70:71], v[128:129], v[62:63]
	s_waitcnt vmcnt(0)
	v_mov_b32_e32 v118, v80
	v_mov_b32_e32 v119, v82
	v_pk_fma_f32 v[132:133], v[118:119], v[100:101], v[16:17]
	v_mov_b32_e32 v82, v81
	v_mul_f32_e32 v16, 0xbfb8aa3b, v132
	v_exp_f32_e32 v60, v16
	global_load_dwordx4 v[16:19], v[34:35], off offset:16
	s_waitcnt lgkmcnt(0)
	global_load_dwordx4 v[44:47], v[34:35], off
	global_load_dwordx4 v[20:23], v[48:49], off offset:16
	s_nop 0
	global_load_dwordx4 v[48:51], v[48:49], off
	v_add_co_u32_e32 v34, vcc, s0, v42
	s_mov_b32 s0, 0x1b000
	s_nop 0
	v_addc_co_u32_e32 v35, vcc, 0, v43, vcc
	v_add_co_u32_e32 v42, vcc, s0, v42
	global_load_dwordx4 v[72:75], v[34:35], off offset:2048
	s_nop 0
	global_load_dwordx4 v[32:35], v[32:33], off offset:16
	v_addc_co_u32_e32 v43, vcc, 0, v43, vcc
	global_load_dwordx4 v[84:87], v[42:43], off offset:2048
	s_nop 0
	global_load_dwordx4 v[40:43], v[40:41], off offset:16
	v_mul_f32_e32 v61, 0xbfb8aa3b, v133
	v_exp_f32_e32 v61, v61
	v_pk_fma_f32 v[68:69], v[82:83], v[128:129], v[56:57]
	v_and_b32_e32 v57, 0xffff0000, v77
	v_mul_f32_e32 v56, 0xbfb8aa3b, v68
	v_pk_add_f32 v[60:61], v[60:61], 1.0 op_sel_hi:[1,0]
	v_exp_f32_e32 v136, v56
	v_div_scale_f32 v64, s[0:1], v61, v61, 1.0
	v_rcp_f32_e32 v65, v64
	v_and_b32_e32 v56, 0xffff0000, v76
	v_fma_f32 v76, -v64, v65, 1.0
	v_fmac_f32_e32 v65, v76, v65
	v_div_scale_f32 v76, vcc, 1.0, v61, 1.0
	v_mul_f32_e32 v77, v76, v65
	v_fma_f32 v80, -v64, v77, v76
	v_fmac_f32_e32 v77, v80, v65
	v_fma_f32 v64, -v64, v77, v76
	v_div_fmas_f32 v64, v64, v65, v77
	v_div_fixup_f32 v61, v64, v61, 1.0
	v_div_scale_f32 v64, s[0:1], v60, v60, 1.0
	v_rcp_f32_e32 v65, v64
	s_waitcnt vmcnt(3)
	v_mov_b32_e32 v81, v74
	v_fma_f32 v76, -v64, v65, 1.0
	v_fmac_f32_e32 v65, v76, v65
	v_div_scale_f32 v76, vcc, 1.0, v60, 1.0
	v_mul_f32_e32 v77, v76, v65
	v_fma_f32 v80, -v64, v77, v76
	v_fmac_f32_e32 v77, v80, v65
	v_fma_f32 v64, -v64, v77, v76
	v_div_fmas_f32 v64, v64, v65, v77
	v_div_fixup_f32 v60, v64, v60, 1.0
	v_mov_b32_e32 v64, v44
	v_mul_f32_e32 v44, 0xbfb8aa3b, v69
	v_mov_b32_e32 v65, v46
	v_mov_b32_e32 v76, v48
	v_mov_b32_e32 v77, v50
	v_exp_f32_e32 v137, v44
	v_pk_fma_f32 v[126:127], v[64:65], v[126:127], v[76:77]
	v_mov_b32_e32 v80, v72
	v_pk_fma_f32 v[130:131], v[80:81], v[106:107], v[126:127]
	s_waitcnt vmcnt(1)
; __device__ __forceinline__ unsigned pk2(float lo, float hi) { return f2bf(lo) | (f2bf(hi) << 16); }
; __device__ __forceinline__ float siluf_(float x) { return x * sigmoidf_(x); }
; __device__ __forceinline__ void ffn_fixup(const Ctx& c, const bf16* HALO, const float* cw, const float* cb, bf16* ACT) {
;     ...
;         for (int j = 0; j < 8; ++j) { const int q = j >> 1; const bool hi = j & 1;
;             const float wg0 = cw[ch0 + j], wg1 = cw[FF2 + ch0 + j], wg2 = cw[2 * FF2 + ch0 + j], wv0 = cw[FFH + ch0 + j], wv1 = cw[FF2 + FFH + ch0 + j], wv2 = cw[2 * FF2 + FFH + ch0 + j], bg = cb[ch0 + j], bv = cb[FFH + ch0 + j];
;             const float gA2 = hi ? bfhi(pg2[q]) : bflo(pg2[q]), gA1 = hi ? bfhi(pg3[q]) : bflo(pg3[q]), gA0 = hi ? bfhi(cg0[q]) : bflo(cg0[q]), gB0 = hi ? bfhi(cg1[q]) : bflo(cg1[q]);
;             const float vA2 = hi ? bfhi(pv2[q]) : bflo(pv2[q]), vA1 = hi ? bfhi(pv3[q]) : bflo(pv3[q]), vA0 = hi ? bfhi(cv0[q]) : bflo(cv0[q]), vB0 = hi ? bfhi(cv1[q]) : bflo(cv1[q]);
;             oa[j] = siluf_(bg + wg0 * gA2 + wg1 * gA1 + wg2 * gA0) * (bv + wv0 * vA2 + wv1 * vA1 + wv2 * vA0);
;             ob[j] = siluf_(bg + wg0 * gA1 + wg1 * gA0 + wg2 * gB0) * (bv + wv0 * vA1 + wv1 * vA0 + wv2 * vB0); }
;         const size_t tok = (size_t)256 * pm + 128 * wr;
;         v4u w; w.x = pk2(oa[0], oa[1]); w.y = pk2(oa[2], oa[3]); w.z = pk2(oa[4], oa[5]); w.w = pk2(oa[6], oa[7]); *(v4u*)(ACT + tok * FFH + ch0) = w;
	v_mov_b32_e32 v126, v84
	v_mov_b32_e32 v127, v86
	v_pk_mul_f32 v[60:61], v[132:133], v[60:61]
	v_pk_fma_f32 v[130:131], v[126:127], v[108:109], v[130:131]
	v_mov_b32_e32 v74, v73
	v_pk_mul_f32 v[130:131], v[130:131], v[60:61]
	v_pk_add_f32 v[60:61], v[136:137], 1.0 op_sel_hi:[1,0]
	v_mov_b32_e32 v86, v85
	v_div_scale_f32 v44, s[0:1], v61, v61, 1.0
	v_rcp_f32_e32 v46, v44
	v_mov_b32_e32 v73, v26
	v_mov_b32_e32 v84, v28
	v_mov_b32_e32 v85, v30
	v_fma_f32 v48, -v44, v46, 1.0
	v_fmac_f32_e32 v46, v48, v46
	v_div_scale_f32 v48, vcc, 1.0, v61, 1.0
	v_mul_f32_e32 v50, v48, v46
	v_fma_f32 v72, -v44, v50, v48
	v_fmac_f32_e32 v50, v72, v46
	v_fma_f32 v44, -v44, v50, v48
	v_div_fmas_f32 v44, v44, v46, v50
	v_div_fixup_f32 v61, v44, v61, 1.0
	v_div_scale_f32 v44, s[0:1], v60, v60, 1.0
	v_rcp_f32_e32 v46, v44
	v_mov_b32_e32 v30, v29
	v_mov_b32_e32 v26, v25
	v_and_b32_e32 v25, 0xffff0000, v55
	v_fma_f32 v48, -v44, v46, 1.0
	v_fmac_f32_e32 v46, v48, v46
	v_div_scale_f32 v48, vcc, 1.0, v60, 1.0
	v_mul_f32_e32 v50, v48, v46
	v_fma_f32 v72, -v44, v50, v48
	v_fmac_f32_e32 v50, v72, v46
	v_fma_f32 v44, -v44, v50, v48
	v_div_fmas_f32 v44, v44, v46, v50
	v_mov_b32_e32 v46, v45
	v_mov_b32_e32 v50, v49
	v_div_fixup_f32 v60, v44, v60, 1.0
	v_pk_fma_f32 v[44:45], v[46:47], v[124:125], v[50:51]
	v_pk_mul_f32 v[60:61], v[68:69], v[60:61]
	v_pk_fma_f32 v[44:45], v[74:75], v[56:57], v[44:45]
	v_mov_b32_e32 v68, v12
	v_pk_fma_f32 v[44:45], v[86:87], v[52:53], v[44:45]
	v_mov_b32_e32 v69, v14
	v_mov_b32_e32 v72, v24
	v_pk_mul_f32 v[124:125], v[44:45], v[60:61]
	v_pk_fma_f32 v[44:45], v[68:69], v[122:123], v[72:73]
	v_lshlrev_b32_e32 v61, 16, v59
	v_lshlrev_b32_e32 v60, 16, v58
	v_pk_fma_f32 v[44:45], v[84:85], v[92:93], v[44:45]
	v_mov_b32_e32 v122, v36
	v_mov_b32_e32 v123, v38
	v_pk_fma_f32 v[132:133], v[122:123], v[60:61], v[44:45]
	v_mov_b32_e32 v38, v37
	v_mul_f32_e32 v12, 0xbfb8aa3b, v132
	v_mul_f32_e32 v29, 0xbfb8aa3b, v133
	v_exp_f32_e32 v28, v12
	v_exp_f32_e32 v29, v29
	v_mov_b32_e32 v14, v13
	v_pk_fma_f32 v[12:13], v[14:15], v[120:121], v[26:27]
	v_lshlrev_b32_e32 v48, 16, v54
	v_pk_add_f32 v[28:29], v[28:29], 1.0 op_sel_hi:[1,0]
	v_and_b32_e32 v59, 0xffff0000, v59
	v_div_scale_f32 v36, s[0:1], v29, v29, 1.0
	v_rcp_f32_e32 v37, v36
	v_and_b32_e32 v58, 0xffff0000, v58
	v_pk_fma_f32 v[12:13], v[30:31], v[90:91], v[12:13]
	v_and_b32_e32 v24, 0xffff0000, v54
	v_fma_f32 v54, -v36, v37, 1.0
	v_pk_fma_f32 v[120:121], v[38:39], v[58:59], v[12:13]
	v_fmac_f32_e32 v37, v54, v37
	v_div_scale_f32 v54, vcc, 1.0, v29, 1.0
	v_lshlrev_b32_e32 v49, 16, v55
	v_mul_f32_e32 v12, 0xbfb8aa3b, v120
	v_mul_f32_e32 v55, v54, v37
	v_lshlrev_b32_e32 v44, 16, v78
	v_exp_f32_e32 v136, v12
	v_and_b32_e32 v12, 0xffff0000, v78
	v_fma_f32 v78, -v36, v55, v54
	v_fmac_f32_e32 v55, v78, v37
	v_fma_f32 v36, -v36, v55, v54
	v_div_fmas_f32 v36, v36, v37, v55
	v_div_fixup_f32 v29, v36, v29, 1.0
	v_div_scale_f32 v36, s[0:1], v28, v28, 1.0
	v_rcp_f32_e32 v37, v36
	v_lshlrev_b32_e32 v45, 16, v79
	v_and_b32_e32 v13, 0xffff0000, v79
	v_pk_fma_f32 v[14:15], v[14:15], v[90:91], v[26:27]
	v_fma_f32 v54, -v36, v37, 1.0
	v_fmac_f32_e32 v37, v54, v37
	v_div_scale_f32 v54, vcc, 1.0, v28, 1.0
	v_mul_f32_e32 v55, v54, v37
	v_fma_f32 v78, -v36, v55, v54
	v_fmac_f32_e32 v55, v78, v37
	v_fma_f32 v36, -v36, v55, v54
	v_div_fmas_f32 v36, v36, v37, v55
	v_div_fixup_f32 v28, v36, v28, 1.0
	v_pk_mul_f32 v[132:133], v[132:133], v[28:29]
	v_mov_b32_e32 v28, v16
	v_mul_f32_e32 v16, 0xbfb8aa3b, v121
	v_mov_b32_e32 v29, v18
	v_mov_b32_e32 v36, v20
	v_mov_b32_e32 v37, v22
	v_exp_f32_e32 v137, v16
	v_pk_fma_f32 v[78:79], v[28:29], v[114:115], v[36:37]
	v_mov_b32_e32 v54, v32
	v_mov_b32_e32 v55, v34
	v_pk_fma_f32 v[114:115], v[54:55], v[44:45], v[78:79]
	s_waitcnt vmcnt(0)
	v_mov_b32_e32 v78, v40
	v_mov_b32_e32 v79, v42
	v_pk_fma_f32 v[114:115], v[78:79], v[48:49], v[114:115]
	v_mov_b32_e32 v34, v33
	v_pk_mul_f32 v[114:115], v[114:115], v[132:133]
	v_pk_add_f32 v[132:133], v[136:137], 1.0 op_sel_hi:[1,0]
	v_mov_b32_e32 v42, v41
	v_div_scale_f32 v16, s[0:1], v133, v133, 1.0
	v_rcp_f32_e32 v18, v16
	s_nop 2
	v_fma_f32 v20, -v16, v18, 1.0
	v_fmac_f32_e32 v18, v20, v18
	v_div_scale_f32 v20, vcc, 1.0, v133, 1.0
	v_mul_f32_e32 v22, v20, v18
	v_fma_f32 v32, -v16, v22, v20
	v_fmac_f32_e32 v22, v32, v18
	v_fma_f32 v16, -v16, v22, v20
	v_div_fmas_f32 v16, v16, v18, v22
	v_div_fixup_f32 v133, v16, v133, 1.0
	v_div_scale_f32 v16, s[0:1], v132, v132, 1.0
	v_rcp_f32_e32 v18, v16
	s_nop 2
	v_fma_f32 v20, -v16, v18, 1.0
	v_fmac_f32_e32 v18, v20, v18
	v_div_scale_f32 v20, vcc, 1.0, v132, 1.0
	v_mul_f32_e32 v22, v20, v18
	v_fma_f32 v32, -v16, v22, v20
	v_fmac_f32_e32 v22, v32, v18
	v_fma_f32 v16, -v16, v22, v20
	v_div_fmas_f32 v16, v16, v18, v22
	v_mov_b32_e32 v18, v17
	v_mov_b32_e32 v22, v21
	v_div_fixup_f32 v132, v16, v132, 1.0
	v_pk_fma_f32 v[16:17], v[18:19], v[104:105], v[22:23]
	v_pk_mul_f32 v[120:121], v[120:121], v[132:133]
	v_pk_fma_f32 v[16:17], v[34:35], v[12:13], v[16:17]
	s_nop 0
	v_pk_fma_f32 v[16:17], v[42:43], v[24:25], v[16:17]
	s_nop 0
	v_pk_mul_f32 v[16:17], v[16:17], v[120:121]
	s_nop 7
	s_nop 3
	v_cvt_pk_bf16_f32 v131, v131, v125
	v_cvt_pk_bf16_f32 v130, v130, v124
	v_cvt_pk_bf16_f32 v133, v115, v17
	v_cvt_pk_bf16_f32 v132, v114, v16
	v_lshlrev_b32_e32 v21, 16, v9
	v_lshlrev_b32_e32 v20, 16, v8
	v_lshlrev_b32_e32 v33, 16, v5
	v_lshlrev_b32_e32 v32, 16, v4
	v_and_b32_e32 v9, 0xffff0000, v9
	v_and_b32_e32 v8, 0xffff0000, v8
	v_and_b32_e32 v41, 0xffff0000, v5
	v_and_b32_e32 v40, 0xffff0000, v4
	v_pk_fma_f32 v[4:5], v[110:111], v[98:99], v[112:113]
	v_pk_fma_f32 v[8:9], v[82:83], v[8:9], v[62:63]
	v_pk_fma_f32 v[4:5], v[116:117], v[100:101], v[4:5]
; __device__ __forceinline__ unsigned pk2(float lo, float hi) { return f2bf(lo) | (f2bf(hi) << 16); }
; __device__ __forceinline__ float siluf_(float x) { return x * sigmoidf_(x); }
; __device__ __forceinline__ void ffn_fixup(const Ctx& c, const bf16* HALO, const float* cw, const float* cb, bf16* ACT) {
;     ...
;         for (int j = 0; j < 8; ++j) { const int q = j >> 1; const bool hi = j & 1;
;             const float wg0 = cw[ch0 + j], wg1 = cw[FF2 + ch0 + j], wg2 = cw[2 * FF2 + ch0 + j], wv0 = cw[FFH + ch0 + j], wv1 = cw[FF2 + FFH + ch0 + j], wv2 = cw[2 * FF2 + FFH + ch0 + j], bg = cb[ch0 + j], bv = cb[FFH + ch0 + j];
;             const float gA2 = hi ? bfhi(pg2[q]) : bflo(pg2[q]), gA1 = hi ? bfhi(pg3[q]) : bflo(pg3[q]), gA0 = hi ? bfhi(cg0[q]) : bflo(cg0[q]), gB0 = hi ? bfhi(cg1[q]) : bflo(cg1[q]);
;             const float vA2 = hi ? bfhi(pv2[q]) : bflo(pv2[q]), vA1 = hi ? bfhi(pv3[q]) : bflo(pv3[q]), vA0 = hi ? bfhi(cv0[q]) : bflo(cv0[q]), vB0 = hi ? bfhi(cv1[q]) : bflo(cv1[q]);
;             oa[j] = siluf_(bg + wg0 * gA2 + wg1 * gA1 + wg2 * gA0) * (bv + wv0 * vA2 + wv1 * vA1 + wv2 * vA0);
;             ob[j] = siluf_(bg + wg0 * gA1 + wg1 * gA0 + wg2 * gB0) * (bv + wv0 * vA1 + wv1 * vA0 + wv2 * vB0); }
;         const size_t tok = (size_t)256 * pm + 128 * wr;
;         v4u w; w.x = pk2(oa[0], oa[1]); w.y = pk2(oa[2], oa[3]); w.z = pk2(oa[4], oa[5]); w.w = pk2(oa[6], oa[7]); *(v4u*)(ACT + tok * FFH + ch0) = w;
;         w.x = pk2(ob[0], ob[1]); w.y = pk2(ob[2], ob[3]); w.z = pk2(ob[4], ob[5]); w.w = pk2(ob[6], ob[7]); *(v4u*)(ACT + (tok + 1) * FFH + ch0) = w;
	v_pk_fma_f32 v[14:15], v[30:31], v[58:59], v[14:15]
	v_pk_fma_f32 v[4:5], v[118:119], v[20:21], v[4:5]
	v_mul_f32_e32 v21, 0xbfb8aa3b, v8
	v_mul_f32_e32 v20, 0xbfb8aa3b, v4
	v_exp_f32_e32 v62, v21
	v_mul_f32_e32 v21, 0xbfb8aa3b, v5
	v_exp_f32_e32 v20, v20
	v_exp_f32_e32 v21, v21
	v_pk_fma_f32 v[12:13], v[18:19], v[12:13], v[22:23]
	v_mov_b64_e32 v[16:17], s[78:79]
	v_pk_fma_f32 v[12:13], v[34:35], v[24:25], v[12:13]
	v_pk_add_f32 v[20:21], v[20:21], 1.0 op_sel_hi:[1,0]
	v_mad_u64_u32 v[16:17], s[0:1], v88, s21, v[16:17]
	v_div_scale_f32 v63, s[0:1], v21, v21, 1.0
	v_rcp_f32_e32 v66, v63
	v_mad_i32_i24 v17, v103, s21, v17
	v_lshl_add_u64 v[16:17], v[94:95], 1, v[16:17]
	global_store_dwordx4 v[16:17], v[130:133], off
	v_fma_f32 v67, -v63, v66, 1.0
	v_fmac_f32_e32 v66, v67, v66
	v_div_scale_f32 v67, vcc, 1.0, v21, 1.0
	v_mul_f32_e32 v70, v67, v66
	v_fma_f32 v71, -v63, v70, v67
	v_fmac_f32_e32 v70, v71, v66
	v_fma_f32 v63, -v63, v70, v67
	v_div_fmas_f32 v63, v63, v66, v70
	v_div_fixup_f32 v21, v63, v21, 1.0
	v_div_scale_f32 v63, s[0:1], v20, v20, 1.0
	v_rcp_f32_e32 v66, v63
	s_nop 0
	v_fma_f32 v67, -v63, v66, 1.0
	v_fmac_f32_e32 v66, v67, v66
	v_div_scale_f32 v67, vcc, 1.0, v20, 1.0
	v_mul_f32_e32 v70, v67, v66
	v_fma_f32 v71, -v63, v70, v67
	v_fmac_f32_e32 v70, v71, v66
	v_fma_f32 v63, -v63, v70, v67
	v_div_fmas_f32 v63, v63, v66, v70
	v_div_fixup_f32 v20, v63, v20, 1.0
	v_pk_mul_f32 v[4:5], v[4:5], v[20:21]
	v_pk_fma_f32 v[20:21], v[64:65], v[106:107], v[76:77]
	s_nop 0
	v_pk_fma_f32 v[20:21], v[80:81], v[108:109], v[20:21]
	s_nop 0
	v_pk_fma_f32 v[20:21], v[126:127], v[32:33], v[20:21]
	s_nop 0
	v_pk_mul_f32 v[4:5], v[20:21], v[4:5]
	v_mul_f32_e32 v20, 0xbfb8aa3b, v9
	v_exp_f32_e32 v63, v20
	s_nop 0
	v_pk_add_f32 v[20:21], v[62:63], 1.0 op_sel_hi:[1,0]
	s_nop 0
	v_div_scale_f32 v32, s[0:1], v21, v21, 1.0
	v_rcp_f32_e32 v33, v32
	s_nop 0
	v_fma_f32 v62, -v32, v33, 1.0
	v_fmac_f32_e32 v33, v62, v33
	v_div_scale_f32 v62, vcc, 1.0, v21, 1.0
	v_mul_f32_e32 v63, v62, v33
	v_fma_f32 v64, -v32, v63, v62
	v_fmac_f32_e32 v63, v64, v33
	v_fma_f32 v32, -v32, v63, v62
	v_div_fmas_f32 v32, v32, v33, v63
	v_div_fixup_f32 v21, v32, v21, 1.0
	v_div_scale_f32 v32, s[0:1], v20, v20, 1.0
	v_rcp_f32_e32 v33, v32
	s_nop 0
	v_fma_f32 v62, -v32, v33, 1.0
	v_fmac_f32_e32 v33, v62, v33
	v_div_scale_f32 v62, vcc, 1.0, v20, 1.0
	v_mul_f32_e32 v63, v62, v33
	v_fma_f32 v64, -v32, v63, v62
	v_fmac_f32_e32 v63, v64, v33
	v_fma_f32 v32, -v32, v63, v62
	v_div_fmas_f32 v32, v32, v33, v63
	v_div_fixup_f32 v20, v32, v20, 1.0
	v_pk_mul_f32 v[8:9], v[8:9], v[20:21]
	v_pk_fma_f32 v[20:21], v[46:47], v[56:57], v[50:51]
	v_lshlrev_b32_e32 v33, 16, v7
	v_pk_fma_f32 v[20:21], v[74:75], v[52:53], v[20:21]
	v_lshlrev_b32_e32 v32, 16, v6
	v_pk_fma_f32 v[20:21], v[86:87], v[40:41], v[20:21]
	v_pk_fma_f32 v[40:41], v[68:69], v[92:93], v[72:73]
	v_pk_mul_f32 v[8:9], v[20:21], v[8:9]
	v_lshlrev_b32_e32 v21, 16, v11
	v_lshlrev_b32_e32 v20, 16, v10
	v_pk_fma_f32 v[40:41], v[84:85], v[60:61], v[40:41]
	v_and_b32_e32 v11, 0xffff0000, v11
	v_and_b32_e32 v10, 0xffff0000, v10
	v_pk_fma_f32 v[20:21], v[122:123], v[20:21], v[40:41]
	v_pk_fma_f32 v[10:11], v[38:39], v[10:11], v[14:15]
	v_mul_f32_e32 v40, 0xbfb8aa3b, v20
	v_mul_f32_e32 v15, 0xbfb8aa3b, v21
	v_exp_f32_e32 v40, v40
	v_exp_f32_e32 v41, v15
	v_mul_f32_e32 v14, 0xbfb8aa3b, v10
	v_exp_f32_e32 v14, v14
	v_and_b32_e32 v7, 0xffff0000, v7
	v_pk_add_f32 v[26:27], v[40:41], 1.0 op_sel_hi:[1,0]
	v_and_b32_e32 v6, 0xffff0000, v6
	v_div_scale_f32 v15, s[0:1], v27, v27, 1.0
	v_rcp_f32_e32 v30, v15
	v_pk_fma_f32 v[6:7], v[42:43], v[6:7], v[12:13]
	v_fma_f32 v31, -v15, v30, 1.0
	v_fmac_f32_e32 v30, v31, v30
	v_div_scale_f32 v31, vcc, 1.0, v27, 1.0
	v_mul_f32_e32 v38, v31, v30
	v_fma_f32 v39, -v15, v38, v31
	v_fmac_f32_e32 v38, v39, v30
	v_fma_f32 v15, -v15, v38, v31
	v_div_fmas_f32 v15, v15, v30, v38
	v_div_fixup_f32 v27, v15, v27, 1.0
	v_div_scale_f32 v15, s[0:1], v26, v26, 1.0
	v_rcp_f32_e32 v30, v15
	s_nop 0
	v_fma_f32 v31, -v15, v30, 1.0
	v_fmac_f32_e32 v30, v31, v30
	v_div_scale_f32 v31, vcc, 1.0, v26, 1.0
	v_mul_f32_e32 v38, v31, v30
	v_fma_f32 v39, -v15, v38, v31
	v_fmac_f32_e32 v38, v39, v30
	v_fma_f32 v15, -v15, v38, v31
	v_div_fmas_f32 v15, v15, v30, v38
	v_div_fixup_f32 v26, v15, v26, 1.0
	v_mul_f32_e32 v15, 0xbfb8aa3b, v11
	v_exp_f32_e32 v15, v15
	v_pk_mul_f32 v[20:21], v[20:21], v[26:27]
	v_pk_fma_f32 v[26:27], v[28:29], v[44:45], v[36:37]
	v_pk_add_f32 v[14:15], v[14:15], 1.0 op_sel_hi:[1,0]
	v_pk_fma_f32 v[26:27], v[54:55], v[48:49], v[26:27]
	s_nop 0
	v_pk_fma_f32 v[26:27], v[78:79], v[32:33], v[26:27]
	s_nop 0
	v_pk_mul_f32 v[20:21], v[26:27], v[20:21]
	v_div_scale_f32 v26, s[0:1], v15, v15, 1.0
	v_rcp_f32_e32 v27, v26
	s_nop 0
	v_fma_f32 v28, -v26, v27, 1.0
	v_fmac_f32_e32 v27, v28, v27
	v_div_scale_f32 v28, vcc, 1.0, v15, 1.0
	v_mul_f32_e32 v29, v28, v27
	v_fma_f32 v30, -v26, v29, v28
	v_fmac_f32_e32 v29, v30, v27
	v_fma_f32 v26, -v26, v29, v28
	v_div_fmas_f32 v26, v26, v27, v29
	v_div_fixup_f32 v15, v26, v15, 1.0
	v_div_scale_f32 v26, s[0:1], v14, v14, 1.0
	v_rcp_f32_e32 v27, v26
	s_mov_b32 s0, 0x15fff
	v_fma_f32 v28, -v26, v27, 1.0
	v_fmac_f32_e32 v27, v28, v27
	v_div_scale_f32 v28, vcc, 1.0, v14, 1.0
	v_mul_f32_e32 v29, v28, v27
	v_fma_f32 v30, -v26, v29, v28
	v_fmac_f32_e32 v29, v30, v27
	v_fma_f32 v26, -v26, v29, v28
	v_div_fmas_f32 v26, v26, v27, v29
	v_div_fixup_f32 v14, v26, v14, 1.0
	v_pk_mul_f32 v[10:11], v[10:11], v[14:15]
	s_nop 0
	v_pk_mul_f32 v[6:7], v[6:7], v[10:11]
	s_nop 6
	v_bfe_u32 v12, v7, 16, 1
	v_bfe_u32 v13, v6, 16, 1
	s_nop 1
	v_add3_u32 v6, v6, v13, s20
	v_add3_u32 v7, v7, v12, s20
	v_bfe_u32 v12, v20, 16, 1
	v_bfe_u32 v13, v21, 16, 1
	s_nop 0
	v_cvt_pk_bf16_f32 v4, v4, v8
	v_add_co_u32_e32 v8, vcc, 0x2000, v16
	v_add3_u32 v10, v21, v13, s20
	v_add3_u32 v11, v20, v12, s20
	v_cvt_pk_bf16_f32 v5, v5, v9
	v_addc_co_u32_e32 v9, vcc, 0, v17, vcc
	v_lshrrev_b32_e32 v11, 16, v11
	v_lshrrev_b32_e32 v10, 16, v10
	v_cmp_lt_i32_e32 vcc, s0, v3
	v_and_or_b32 v7, v7, s19, v10
	v_and_or_b32 v6, v6, s19, v11
	s_or_b64 s[14:15], vcc, s[14:15]
	global_store_dwordx4 v[8:9], v[4:7], off offset:3072
	s_andn2_b64 exec, exec, s[14:15]
	s_cbranch_execz .LBB0_4434

; __device__ __forceinline__ void postnorm(const Ctx& c, const bf16* MF, bf16* XB, float* RS, const float* gpost, float* OUT) {
;     for (int row = c.gw; row < MT; row += c.NGW) {
;         const v4u* mr = (const v4u*)(MF + (size_t)row * DM) + c.lane; v4u* xr = (v4u*)(XB + (size_t)row * DM) + c.lane;
;         v4u mv[4], xv[4]; float v[4][8]; float s = 0.f;
; #pragma unroll
;         for (int j = 0; j < 4; ++j) { mv[j] = mr[64 * j]; xv[j] = xr[64 * j]; }
; #pragma unroll
;         for (int j = 0; j < 4; ++j)
; #pragma unroll
;             for (int k = 0; k < 4; ++k) { v[j][2 * k] = bflo(mv[j][k]); v[j][2 * k + 1] = bfhi(mv[j][k]); s += v[j][2 * k] * v[j][2 * k] + v[j][2 * k + 1] * v[j][2 * k + 1]; }
;         const float rs = rsqrtf(wave_sum(s) * (1.f / DM) + EPS);
.LBB0_4571:
	v_readlane_b32 s8, v253, 0
	v_readlane_b32 s9, v253, 1
	s_nop 1
	v_lshl_add_u64 v[34:35], s[8:9], 0, v[36:37]
	v_add_co_u32_e32 v58, vcc, 0xd400000, v34
	s_nop 1
	v_addc_co_u32_e32 v59, vcc, 0, v35, vcc
	s_waitcnt lgkmcnt(0)
	global_load_dwordx4 v[46:49], v[58:59], off
	global_load_dwordx4 v[50:53], v[58:59], off offset:1024
	global_load_dwordx4 v[54:57], v[58:59], off offset:2048
	s_nop 0
	global_load_dwordx4 v[58:61], v[58:59], off offset:3072
	v_add_co_u32_e32 v34, vcc, 0x9400000, v34
	s_waitcnt vmcnt(3)
	v_lshlrev_b32_e32 v79, 16, v47
	v_addc_co_u32_e32 v35, vcc, 0, v35, vcc
	global_load_dwordx4 v[62:65], v[34:35], off
	global_load_dwordx4 v[66:69], v[34:35], off offset:1024
	global_load_dwordx4 v[70:73], v[34:35], off offset:2048
	global_load_dwordx4 v[74:77], v[34:35], off offset:3072
	v_lshlrev_b32_e32 v78, 16, v46
	v_and_b32_e32 v47, 0xffff0000, v47
	v_and_b32_e32 v46, 0xffff0000, v46
	v_lshlrev_b32_e32 v81, 16, v49
	v_lshlrev_b32_e32 v80, 16, v48
	v_and_b32_e32 v49, 0xffff0000, v49
	v_and_b32_e32 v48, 0xffff0000, v48
	v_pk_mul_f32 v[94:95], v[46:47], v[46:47]
	v_pk_mul_f32 v[98:99], v[48:49], v[48:49]
	v_pk_fma_f32 v[94:95], v[78:79], v[78:79], v[94:95]
	s_waitcnt vmcnt(6)
	v_lshlrev_b32_e32 v83, 16, v51
	v_lshlrev_b32_e32 v82, 16, v50
	v_and_b32_e32 v51, 0xffff0000, v51
	v_and_b32_e32 v50, 0xffff0000, v50
	v_pk_fma_f32 v[98:99], v[80:81], v[80:81], v[98:99]
	v_add_f32_e32 v94, v94, v95
	v_pk_mul_f32 v[102:103], v[50:51], v[50:51]
	v_add_f32_e32 v94, v98, v94
	v_lshlrev_b32_e32 v85, 16, v53
	v_lshlrev_b32_e32 v84, 16, v52
	v_and_b32_e32 v53, 0xffff0000, v53
	v_and_b32_e32 v52, 0xffff0000, v52
	v_pk_fma_f32 v[102:103], v[82:83], v[82:83], v[102:103]
	v_add_f32_e32 v94, v99, v94
	v_pk_mul_f32 v[104:105], v[52:53], v[52:53]
	v_add_f32_e32 v94, v102, v94
	s_waitcnt vmcnt(5)
	v_lshlrev_b32_e32 v87, 16, v55
	v_lshlrev_b32_e32 v86, 16, v54
	v_and_b32_e32 v55, 0xffff0000, v55
	v_and_b32_e32 v54, 0xffff0000, v54
	v_pk_fma_f32 v[104:105], v[84:85], v[84:85], v[104:105]
	v_add_f32_e32 v94, v103, v94
	v_pk_mul_f32 v[106:107], v[54:55], v[54:55]
	v_add_f32_e32 v94, v104, v94
	v_lshlrev_b32_e32 v89, 16, v57
	v_lshlrev_b32_e32 v88, 16, v56
	v_and_b32_e32 v57, 0xffff0000, v57
	v_and_b32_e32 v56, 0xffff0000, v56
	v_pk_fma_f32 v[106:107], v[86:87], v[86:87], v[106:107]
	v_add_f32_e32 v94, v105, v94
	v_pk_mul_f32 v[108:109], v[56:57], v[56:57]
	v_add_f32_e32 v94, v106, v94
	s_waitcnt vmcnt(4)
	v_lshlrev_b32_e32 v91, 16, v59
	v_lshlrev_b32_e32 v90, 16, v58
	v_and_b32_e32 v59, 0xffff0000, v59
	v_and_b32_e32 v58, 0xffff0000, v58
	v_pk_fma_f32 v[108:109], v[88:89], v[88:89], v[108:109]
	v_add_f32_e32 v94, v107, v94
	v_pk_mul_f32 v[110:111], v[58:59], v[58:59]
	v_add_f32_e32 v94, v108, v94
	v_lshlrev_b32_e32 v93, 16, v61
	v_lshlrev_b32_e32 v92, 16, v60
	v_and_b32_e32 v61, 0xffff0000, v61
	v_and_b32_e32 v60, 0xffff0000, v60
	v_pk_fma_f32 v[110:111], v[90:91], v[90:91], v[110:111]
	v_add_f32_e32 v94, v109, v94
	v_pk_mul_f32 v[112:113], v[60:61], v[60:61]
	v_add_f32_e32 v94, v110, v94
	v_pk_fma_f32 v[112:113], v[92:93], v[92:93], v[112:113]
	v_add_f32_e32 v94, v111, v94
	v_add_f32_e32 v94, v112, v94
	v_add_f32_e32 v94, v113, v94
	ds_bpermute_b32 v98, v40, v94
	s_waitcnt lgkmcnt(0)
	v_add_f32_e32 v98, v94, v98
	ds_bpermute_b32 v102, v41, v98
	s_waitcnt lgkmcnt(0)
	v_add_f32_e32 v102, v98, v102
	ds_bpermute_b32 v104, v42, v102
	s_waitcnt vmcnt(3)
	v_lshlrev_b32_e32 v97, 16, v63
	v_lshlrev_b32_e32 v96, 16, v62
	v_and_b32_e32 v63, 0xffff0000, v63
	s_waitcnt lgkmcnt(0)
	v_add_f32_e32 v104, v102, v104
	ds_bpermute_b32 v106, v43, v104
	v_and_b32_e32 v62, 0xffff0000, v62
	v_lshlrev_b32_e32 v101, 16, v65
	v_lshlrev_b32_e32 v100, 16, v64
	v_and_b32_e32 v65, 0xffff0000, v65
	s_waitcnt lgkmcnt(0)
	v_add_f32_e32 v106, v104, v106
	ds_bpermute_b32 v108, v44, v106
	v_and_b32_e32 v64, 0xffff0000, v64
	s_waitcnt vmcnt(0)
	v_lshlrev_b32_e32 v109, 16, v77
	v_and_b32_e32 v77, 0xffff0000, v77
	v_lshlrev_b32_e32 v95, 16, v67
	s_waitcnt lgkmcnt(0)
	v_add_f32_e32 v108, v106, v108
	ds_bpermute_b32 v110, v45, v108
	v_lshlrev_b32_e32 v94, 16, v66
	v_and_b32_e32 v67, 0xffff0000, v67
	v_and_b32_e32 v66, 0xffff0000, v66
	v_lshlrev_b32_e32 v99, 16, v69
	s_waitcnt lgkmcnt(0)
; __device__ __forceinline__ unsigned pk2(float lo, float hi) { return f2bf(lo) | (f2bf(hi) << 16); }
; __device__ __forceinline__ void postnorm(const Ctx& c, const bf16* MF, bf16* XB, float* RS, const float* gpost, float* OUT) {
;     ...
;         const float rs = rsqrtf(wave_sum(s) * (1.f / DM) + EPS);
;         float s2 = 0.f;
; #pragma unroll
;         for (int j = 0; j < 4; ++j) { const float* gp = gpost + (c.lane + 64 * j) * 8; const f32x4 g0 = *(CF4)gp, g1 = *(CF4)(gp + 4);
; #pragma unroll
;             for (int k = 0; k < 4; ++k) { const float ga = (k < 2) ? g0[2 * k] : g1[2 * k - 4], gb = (k < 2) ? g0[2 * k + 1] : g1[2 * k - 3];
;                 v[j][2 * k] = bflo(xv[j][k]) + v[j][2 * k] * rs * ga; v[j][2 * k + 1] = bfhi(xv[j][k]) + v[j][2 * k + 1] * rs * gb;
;                 s2 += v[j][2 * k] * v[j][2 * k] + v[j][2 * k + 1] * v[j][2 * k + 1]; } }
;         if (OUT) {
; #pragma unroll
;             for (int j = 0; j < 4; ++j) { float* op = OUT + (size_t)row * DM + (c.lane + 64 * j) * 8; *(f32x4*)op = (f32x4){v[j][0], v[j][1], v[j][2], v[j][3]}; *(f32x4*)(op + 4) = (f32x4){v[j][4], v[j][5], v[j][6], v[j][7]}; }
;         } else {
; #pragma unroll
;             for (int j = 0; j < 4; ++j) { v4u o; o.x = pk2(v[j][0], v[j][1]); o.y = pk2(v[j][2], v[j][3]); o.z = pk2(v[j][4], v[j][5]); o.w = pk2(v[j][6], v[j][7]); xr[64 * j] = o; }
;             const float rs2 = rsqrtf(wave_sum(s2) * (1.f / DM) + EPS); if (c.lane == 0) RS[row] = rs2;
	v_add_f32_e32 v108, v108, v110
	v_fmamk_f32 v108, v108, 0x3a000000, v3
	v_mul_f32_e32 v110, 0x4b800000, v108
	v_cmp_gt_f32_e32 vcc, s13, v108
	v_lshlrev_b32_e32 v98, 16, v68
	v_and_b32_e32 v69, 0xffff0000, v69
	v_cndmask_b32_e32 v108, v108, v110, vcc
	v_rsq_f32_e32 v110, v108
	v_lshlrev_b32_e32 v108, 16, v76
	v_and_b32_e32 v76, 0xffff0000, v76
	v_and_b32_e32 v68, 0xffff0000, v68
	v_mul_f32_e32 v111, 0x45800000, v110
	v_cndmask_b32_e32 v110, v110, v111, vcc
	v_pk_mul_f32 v[46:47], v[110:111], v[46:47] op_sel_hi:[0,1]
	v_pk_mul_f32 v[78:79], v[110:111], v[78:79] op_sel_hi:[0,1]
	v_pk_mul_f32 v[48:49], v[110:111], v[48:49] op_sel_hi:[0,1]
	v_pk_fma_f32 v[46:47], v[38:39], v[46:47], v[62:63]
	v_pk_mul_f32 v[60:61], v[110:111], v[60:61] op_sel_hi:[0,1]
	v_pk_mul_f32 v[80:81], v[110:111], v[80:81] op_sel_hi:[0,1]
	v_pk_fma_f32 v[78:79], v[4:5], v[78:79], v[96:97]
	v_pk_fma_f32 v[48:49], v[6:7], v[48:49], v[64:65]
	v_pk_fma_f32 v[60:61], v[30:31], v[60:61], v[76:77]
	v_pk_mul_f32 v[76:77], v[46:47], v[46:47]
	v_pk_mul_f32 v[50:51], v[110:111], v[50:51] op_sel_hi:[0,1]
	v_pk_fma_f32 v[62:63], v[8:9], v[80:81], v[100:101]
	v_pk_fma_f32 v[76:77], v[78:79], v[78:79], v[76:77]
	v_pk_mul_f32 v[80:81], v[48:49], v[48:49]
	v_pk_mul_f32 v[82:83], v[110:111], v[82:83] op_sel_hi:[0,1]
	v_pk_fma_f32 v[50:51], v[10:11], v[50:51], v[66:67]
	v_pk_fma_f32 v[80:81], v[62:63], v[62:63], v[80:81]
	v_add_f32_e32 v76, v76, v77
	v_pk_fma_f32 v[64:65], v[12:13], v[82:83], v[94:95]
	v_pk_mul_f32 v[82:83], v[50:51], v[50:51]
	v_add_f32_e32 v76, v80, v76
	v_pk_fma_f32 v[82:83], v[64:65], v[64:65], v[82:83]
	v_add_f32_e32 v76, v81, v76
	v_add_f32_e32 v76, v82, v76
	s_nop 2
	v_bfe_u32 v82, v46, 16, 1
	v_pk_mul_f32 v[52:53], v[110:111], v[52:53] op_sel_hi:[0,1]
	v_add3_u32 v46, v46, v82, s14
	s_nop 2
	v_bfe_u32 v77, v78, 16, 1
	s_nop 2
	v_pk_mul_f32 v[84:85], v[110:111], v[84:85] op_sel_hi:[0,1]
	v_pk_fma_f32 v[52:53], v[14:15], v[52:53], v[68:69]
	s_nop 2
	v_add3_u32 v77, v78, v77, s14
	v_lshlrev_b32_e32 v103, 16, v71
	v_lshlrev_b32_e32 v102, 16, v70
	v_and_b32_e32 v71, 0xffff0000, v71
	v_and_b32_e32 v70, 0xffff0000, v70
	v_pk_fma_f32 v[66:67], v[16:17], v[84:85], v[98:99]
	v_pk_mul_f32 v[54:55], v[110:111], v[54:55] op_sel_hi:[0,1]
	v_pk_mul_f32 v[84:85], v[52:53], v[52:53]
	v_lshrrev_b32_e32 v77, 16, v77
	s_nop 2
	v_pk_mul_f32 v[68:69], v[110:111], v[86:87] op_sel_hi:[0,1]
	v_pk_fma_f32 v[54:55], v[18:19], v[54:55], v[70:71]
	v_pk_fma_f32 v[84:85], v[66:67], v[66:67], v[84:85]
	v_add_f32_e32 v76, v83, v76
	v_cvt_pk_bf16_f32 v49, v63, v49
	v_cvt_pk_bf16_f32 v48, v62, v48
	v_cvt_pk_bf16_f32 v47, v79, v47
	v_and_or_b32 v46, v46, s10, v77
	v_lshlrev_b32_e32 v105, 16, v73
	v_lshlrev_b32_e32 v104, 16, v72
	v_and_b32_e32 v73, 0xffff0000, v73
	v_and_b32_e32 v72, 0xffff0000, v72
	v_pk_fma_f32 v[68:69], v[20:21], v[68:69], v[102:103]
	v_pk_mul_f32 v[56:57], v[110:111], v[56:57] op_sel_hi:[0,1]
	v_pk_mul_f32 v[86:87], v[54:55], v[54:55]
	v_add_f32_e32 v76, v84, v76
	global_store_dwordx4 v[34:35], v[46:49], off
	v_pk_mul_f32 v[70:71], v[110:111], v[88:89] op_sel_hi:[0,1]
	v_pk_fma_f32 v[56:57], v[22:23], v[56:57], v[72:73]
	s_nop 3
	v_pk_fma_f32 v[86:87], v[68:69], v[68:69], v[86:87]
	v_add_f32_e32 v76, v85, v76
	s_nop 7
	v_lshlrev_b32_e32 v107, 16, v75
	v_lshlrev_b32_e32 v106, 16, v74
	v_and_b32_e32 v75, 0xffff0000, v75
	v_and_b32_e32 v74, 0xffff0000, v74
	v_pk_fma_f32 v[70:71], v[24:25], v[70:71], v[104:105]
	v_pk_mul_f32 v[58:59], v[110:111], v[58:59] op_sel_hi:[0,1]
	v_pk_mul_f32 v[88:89], v[56:57], v[56:57]
	v_add_f32_e32 v76, v86, v76
	s_nop 3
	v_pk_mul_f32 v[72:73], v[110:111], v[90:91] op_sel_hi:[0,1]
	v_pk_fma_f32 v[58:59], v[26:27], v[58:59], v[74:75]
	v_pk_fma_f32 v[88:89], v[70:71], v[70:71], v[88:89]
	v_add_f32_e32 v76, v87, v76
	s_nop 3
	v_pk_fma_f32 v[72:73], v[28:29], v[72:73], v[106:107]
	v_pk_mul_f32 v[90:91], v[58:59], v[58:59]
	v_add_f32_e32 v76, v88, v76
	v_cvt_pk_bf16_f32 v49, v67, v53
	v_cvt_pk_bf16_f32 v48, v66, v52
	v_cvt_pk_bf16_f32 v47, v65, v51
	v_cvt_pk_bf16_f32 v46, v64, v50
	v_pk_mul_f32 v[74:75], v[110:111], v[92:93] op_sel_hi:[0,1]
	v_pk_fma_f32 v[90:91], v[72:73], v[72:73], v[90:91]
	v_add_f32_e32 v76, v89, v76
	global_store_dwordx4 v[34:35], v[46:49], off offset:1024
	v_pk_fma_f32 v[74:75], v[32:33], v[74:75], v[108:109]
	v_pk_mul_f32 v[92:93], v[60:61], v[60:61]
	s_nop 1
	v_add_f32_e32 v76, v90, v76
	s_nop 5
	v_pk_fma_f32 v[92:93], v[74:75], v[74:75], v[92:93]
	v_add_f32_e32 v76, v91, v76
	s_nop 5
	v_add_f32_e32 v76, v92, v76
	s_nop 5
	v_add_f32_e32 v76, v93, v76
	v_cvt_pk_bf16_f32 v49, v71, v57
	v_cvt_pk_bf16_f32 v48, v70, v56
	v_cvt_pk_bf16_f32 v47, v69, v55
	v_cvt_pk_bf16_f32 v46, v68, v54
	global_store_dwordx4 v[34:35], v[46:49], off offset:2048
	ds_bpermute_b32 v47, v40, v76
	s_nop 3
	s_waitcnt lgkmcnt(0)
	v_add_f32_e32 v47, v76, v47
	ds_bpermute_b32 v50, v41, v47
	s_nop 3
	s_waitcnt lgkmcnt(0)
	v_add_f32_e32 v47, v47, v50
	ds_bpermute_b32 v50, v42, v47
	s_nop 1
	v_cvt_pk_bf16_f32 v51, v75, v61
	s_nop 0
	s_waitcnt lgkmcnt(0)
	v_add_f32_e32 v47, v47, v50
	ds_bpermute_b32 v50, v43, v47
	s_nop 3
	s_waitcnt lgkmcnt(0)
	v_add_f32_e32 v47, v47, v50
	ds_bpermute_b32 v50, v44, v47
	s_nop 3
	s_waitcnt lgkmcnt(0)
	v_add_f32_e32 v46, v47, v50
	ds_bpermute_b32 v47, v45, v46
	s_nop 0
	v_cvt_pk_bf16_f32 v50, v74, v60
	v_cvt_pk_bf16_f32 v49, v73, v59
	v_cvt_pk_bf16_f32 v48, v72, v58
	global_store_dwordx4 v[34:35], v[48:51], off offset:3072
	s_and_saveexec_b64 s[8:9], s[0:1]
	s_cbranch_execz .LBB0_4570
	s_waitcnt lgkmcnt(0)
	v_add_f32_e32 v34, v46, v47
	v_fmamk_f32 v34, v34, 0x3a000000, v3
	v_mul_f32_e32 v35, 0x4b800000, v34
	v_cmp_gt_f32_e32 vcc, s13, v34
	v_readlane_b32 s16, v253, 0
	v_readlane_b32 s17, v253, 1
	v_cndmask_b32_e32 v34, v34, v35, vcc
	v_rsq_f32_e32 v34, v34
	s_add_u32 s16, s16, s11
	s_addc_u32 s17, s17, s12
	v_mul_f32_e32 v35, 0x45800000, v34
	v_cndmask_b32_e32 v34, v34, v35, vcc
	global_store_dword v251, v34, s[16:17]
	s_branch .LBB0_4570

; #define LAS __attribute__((address_space(3)))
; #define LDS_WAIT() asm volatile("s_waitcnt lgkmcnt(0)" ::: "memory")
;     ...
;     for (int it = gw0; it < items; it += ngw) {
;         const int kb = it / nblk, nb = it % nblk, k0 = 64 * kb, n0 = 64 * nb, nq = (lane & 15) * 4, kr = lane >> 4; const bool ok = (n0 + nq) < N;
;         f32x4 v[16];
; #pragma unroll
;         for (int i = 0; i < 16; ++i) v[i] = ok ? __builtin_nontemporal_load((const f32x4*)(W + (size_t)(k0 + 4 * i + kr) * N + n0 + nq)) : (f32x4){0.f, 0.f, 0.f, 0.f};
;         if (gain) {
; #pragma unroll
;             for (int i = 0; i < 16; ++i) v[i] *= gain[k0 + 4 * i + kr]; }
; #pragma unroll
;         for (int i = 0; i < 16; ++i) { LAS float* d = scr + (4 * i + kr) * 65 + nq; d[0] = v[i].x; d[1] = v[i].y; d[2] = v[i].z; d[3] = v[i].w; }
;         LDS_WAIT(); asm volatile("" ::: "memory");
.LBB0_4576:
	s_or_b64 exec, exec, s[8:9]
	v_lshl_add_u64 v[72:73], v[72:73], 2, s[2:3]
	global_load_dword v74, v[72:73], off
	global_load_dword v82, v[72:73], off offset:16
	global_load_dword v84, v[72:73], off offset:32
	global_load_dword v86, v[72:73], off offset:48
	global_load_dword v88, v[72:73], off offset:64
	global_load_dword v90, v[72:73], off offset:80
	global_load_dword v92, v[72:73], off offset:96
	global_load_dword v94, v[72:73], off offset:112
	global_load_dword v96, v[72:73], off offset:128
	global_load_dword v98, v[72:73], off offset:144
	global_load_dword v100, v[72:73], off offset:160
	global_load_dword v102, v[72:73], off offset:176
	global_load_dword v104, v[72:73], off offset:192
	global_load_dword v106, v[72:73], off offset:208
	s_nop 0
	global_load_dword v72, v[72:73], off offset:224
	v_lshl_add_u64 v[76:77], v[76:77], 2, s[2:3]
	global_load_dword v76, v[76:77], off
	v_add_u32_e32 v75, 0x418, v81
	v_add_u32_e32 v83, 0x828, v81
	v_add_u32_e32 v85, 0xc30, v81
	v_add_u32_e32 v87, 0xc38, v81
	v_add_u32_e32 v89, 0x1040, v81
	v_add_u32_e32 v91, 0x1048, v81
	v_add_u32_e32 v93, 0x1450, v81
	v_add_u32_e32 v95, 0x1458, v81
	s_waitcnt vmcnt(0)
	v_add_u32_e32 v97, 0x1860, v81
	v_add_u32_e32 v99, 0x1868, v81
	v_add_u32_e32 v73, 0x410, v81
	v_add_u32_e32 v77, 0x820, v81
	v_add_u32_e32 v101, 0x1c70, v81
	v_add_u32_e32 v103, 0x1c78, v81
	v_add_u32_e32 v105, 0x2080, v81
	v_add_u32_e32 v107, 0x2088, v81
	s_add_i32 s16, s16, s10
	s_ashr_i32 s7, s6, 31
	s_add_i32 s15, s15, s86
	s_add_i32 s10, s10, s11
	s_cmpk_lt_i32 s15, 0x100
	v_pk_mul_f32 v[4:5], v[4:5], v[74:75] op_sel_hi:[1,0]
	v_pk_mul_f32 v[6:7], v[6:7], v[74:75] op_sel_hi:[1,0]
	v_pk_mul_f32 v[14:15], v[14:15], v[82:83] op_sel_hi:[1,0]
	v_pk_mul_f32 v[12:13], v[12:13], v[82:83] op_sel_hi:[1,0]
	v_pk_mul_f32 v[10:11], v[10:11], v[84:85] op_sel_hi:[1,0]
	v_pk_mul_f32 v[8:9], v[8:9], v[84:85] op_sel_hi:[1,0]
	v_pk_mul_f32 v[22:23], v[22:23], v[86:87] op_sel_hi:[1,0]
	v_pk_mul_f32 v[20:21], v[20:21], v[86:87] op_sel_hi:[1,0]
	v_pk_mul_f32 v[18:19], v[18:19], v[88:89] op_sel_hi:[1,0]
	v_pk_mul_f32 v[16:17], v[16:17], v[88:89] op_sel_hi:[1,0]
	v_pk_mul_f32 v[30:31], v[30:31], v[90:91] op_sel_hi:[1,0]
	v_pk_mul_f32 v[28:29], v[28:29], v[90:91] op_sel_hi:[1,0]
	v_pk_mul_f32 v[26:27], v[26:27], v[92:93] op_sel_hi:[1,0]
	v_pk_mul_f32 v[24:25], v[24:25], v[92:93] op_sel_hi:[1,0]
	v_pk_mul_f32 v[38:39], v[38:39], v[94:95] op_sel_hi:[1,0]
	v_pk_mul_f32 v[36:37], v[36:37], v[94:95] op_sel_hi:[1,0]
	v_pk_mul_f32 v[34:35], v[34:35], v[96:97] op_sel_hi:[1,0]
	v_pk_mul_f32 v[32:33], v[32:33], v[96:97] op_sel_hi:[1,0]
	v_pk_mul_f32 v[44:45], v[44:45], v[98:99] op_sel_hi:[1,0]
	ds_write2_b32 v81, v4, v5 offset1:1
	ds_write2_b32 v81, v6, v7 offset0:2 offset1:3
	ds_write2_b32 v73, v12, v13 offset1:1
	ds_write2_b32 v75, v14, v15 offset1:1
	ds_write2_b32 v77, v8, v9 offset1:1
	ds_write2_b32 v83, v10, v11 offset1:1
	ds_write2_b32 v85, v20, v21 offset1:1
	ds_write2_b32 v87, v22, v23 offset1:1
	ds_write2_b32 v89, v16, v17 offset1:1
	ds_write2_b32 v91, v18, v19 offset1:1
	ds_write2_b32 v93, v28, v29 offset1:1
	ds_write2_b32 v95, v30, v31 offset1:1
	ds_write2_b32 v97, v24, v25 offset1:1
	ds_write2_b32 v99, v26, v27 offset1:1
	ds_write2_b32 v101, v36, v37 offset1:1
	ds_write2_b32 v103, v38, v39 offset1:1
	ds_write2_b32 v105, v32, v33 offset1:1
	ds_write2_b32 v107, v34, v35 offset1:1
	v_add_u32_e32 v4, 0x2490, v81
	v_pk_mul_f32 v[46:47], v[46:47], v[98:99] op_sel_hi:[1,0]
	ds_write2_b32 v4, v44, v45 offset1:1
	v_add_u32_e32 v4, 0x2498, v81
	v_pk_mul_f32 v[40:41], v[40:41], v[100:101] op_sel_hi:[1,0]
	ds_write2_b32 v4, v46, v47 offset1:1
	v_add_u32_e32 v4, 0x28a0, v81
	v_pk_mul_f32 v[42:43], v[42:43], v[100:101] op_sel_hi:[1,0]
	ds_write2_b32 v4, v40, v41 offset1:1
	v_add_u32_e32 v4, 0x28a8, v81
	v_pk_mul_f32 v[52:53], v[52:53], v[102:103] op_sel_hi:[1,0]
	ds_write2_b32 v4, v42, v43 offset1:1
	v_add_u32_e32 v4, 0x2cb0, v81
	v_pk_mul_f32 v[54:55], v[54:55], v[102:103] op_sel_hi:[1,0]
	ds_write2_b32 v4, v52, v53 offset1:1
	v_add_u32_e32 v4, 0x2cb8, v81
	v_pk_mul_f32 v[48:49], v[48:49], v[104:105] op_sel_hi:[1,0]
	ds_write2_b32 v4, v54, v55 offset1:1
	v_add_u32_e32 v4, 0x30c0, v81
	v_pk_mul_f32 v[50:51], v[50:51], v[104:105] op_sel_hi:[1,0]
	ds_write2_b32 v4, v48, v49 offset1:1
	v_add_u32_e32 v4, 0x30c8, v81
	v_pk_mul_f32 v[60:61], v[60:61], v[106:107] op_sel_hi:[1,0]
	ds_write2_b32 v4, v50, v51 offset1:1
	v_add_u32_e32 v4, 0x34d0, v81
	v_pk_mul_f32 v[62:63], v[62:63], v[106:107] op_sel_hi:[1,0]
	ds_write2_b32 v4, v60, v61 offset1:1
	v_add_u32_e32 v4, 0x34d8, v81
	v_pk_mul_f32 v[56:57], v[56:57], v[72:73] op_sel_hi:[1,0]
	ds_write2_b32 v4, v62, v63 offset1:1
	v_add_u32_e32 v4, 0x38e0, v81
	v_pk_mul_f32 v[58:59], v[58:59], v[72:73] op_sel_hi:[1,0]
	ds_write2_b32 v4, v56, v57 offset1:1
	v_add_u32_e32 v4, 0x38e8, v81
	v_pk_mul_f32 v[64:65], v[64:65], v[76:77] op_sel_hi:[1,0]
	ds_write2_b32 v4, v58, v59 offset1:1
	v_add_u32_e32 v4, 0x3cf0, v81
	v_pk_mul_f32 v[66:67], v[66:67], v[76:77] op_sel_hi:[1,0]
	ds_write2_b32 v4, v64, v65 offset1:1
	v_add_u32_e32 v4, 0x3cf8, v81
	ds_write2_b32 v4, v66, v67 offset1:1
	s_waitcnt lgkmcnt(0)
	ds_read2_b32 v[12:13], v80 offset1:8
	ds_read2_b32 v[14:15], v80 offset0:65 offset1:73
	ds_read2_b32 v[16:17], v80 offset0:130 offset1:138
	ds_read2_b32 v[18:19], v80 offset0:195 offset1:203
	v_add_u32_e32 v30, 0x400, v80
	s_waitcnt lgkmcnt(3)
; #define LAS __attribute__((address_space(3)))
; #define LDS_WAIT() asm volatile("s_waitcnt lgkmcnt(0)" ::: "memory")
; __device__ __forceinline__ unsigned pk2(float lo, float hi) { return f2bf(lo) | (f2bf(hi) << 16); }
;     ...
;         const int c8 = lane & 7; int d0 = n0;
;         if (ffnmap) { const int bj = n0 >= FFH ? 1 : 0, chn = n0 - FFH * bj; d0 = 256 * (chn >> 7) + 128 * bj + (chn & 127); }
; #pragma unroll
;         for (int j = 0; j < 8; ++j) { const int n = (lane >> 3) + 8 * j; const LAS float* sp = scr + (8 * c8) * 65 + n;
;             v4u o; o.x = pk2(sp[0 * 65], sp[1 * 65]); o.y = pk2(sp[2 * 65], sp[3 * 65]); o.z = pk2(sp[4 * 65], sp[5 * 65]); o.w = pk2(sp[6 * 65], sp[7 * 65]);
;             *(v4u*)(WT + (size_t)(d0 + n) * K + k0 + 8 * c8) = o; }
;         LDS_WAIT(); asm volatile("" ::: "memory");
	s_nop 1
	s_waitcnt lgkmcnt(2)
	s_nop 0
	ds_read2_b32 v[20:21], v30 offset0:4 offset1:12
	s_nop 1
	ds_read2_b32 v[22:23], v30 offset0:69 offset1:77
	v_cvt_pk_bf16_f32 v8, v12, v14
	s_waitcnt lgkmcnt(3)
	s_nop 1
	s_waitcnt lgkmcnt(2)
	s_nop 0
	ds_read2_b32 v[24:25], v30 offset0:134 offset1:142
	s_nop 1
	ds_read2_b32 v[26:27], v30 offset0:199 offset1:207
	v_cvt_pk_bf16_f32 v9, v16, v18
	s_waitcnt lgkmcnt(3)
	s_nop 1
	s_waitcnt lgkmcnt(2)
	s_nop 2
	v_cvt_pk_bf16_f32 v10, v20, v22
	s_waitcnt lgkmcnt(1)
	s_nop 1
	s_waitcnt lgkmcnt(0)
	s_nop 2
	v_cvt_pk_bf16_f32 v11, v24, v26
	v_add_u32_e32 v6, s16, v79
	v_ashrrev_i32_e32 v7, 31, v6
	v_lshl_add_u64 v[4:5], s[6:7], 1, v[70:71]
	v_lshlrev_b64 v[28:29], 12, v[6:7]
	v_lshl_add_u64 v[28:29], v[4:5], 0, v[28:29]
	s_nop 0
	global_store_dwordx4 v[28:29], v[8:11], off
	s_nop 3
	v_cvt_pk_bf16_f32 v8, v13, v15
	s_nop 4
	v_cvt_pk_bf16_f32 v9, v17, v19
	s_nop 4
	v_cvt_pk_bf16_f32 v10, v21, v23
	s_nop 0
	v_add_u32_e32 v12, 8, v6
	s_nop 1
	v_ashrrev_i32_e32 v13, 31, v12
	s_nop 1
	v_lshlrev_b64 v[12:13], 12, v[12:13]
	v_cvt_pk_bf16_f32 v11, v25, v27
	ds_read2_b32 v[14:15], v80 offset0:16 offset1:24
	v_lshl_add_u64 v[12:13], v[4:5], 0, v[12:13]
	global_store_dwordx4 v[12:13], v[8:11], off
	ds_read2_b32 v[12:13], v80 offset0:81 offset1:89
	ds_read2_b32 v[16:17], v80 offset0:146 offset1:154
	ds_read2_b32 v[18:19], v80 offset0:211 offset1:219
	s_waitcnt lgkmcnt(3)
	s_nop 1
	s_waitcnt lgkmcnt(2)
	s_nop 0
	ds_read2_b32 v[20:21], v30 offset0:20 offset1:28
	s_nop 1
	ds_read2_b32 v[22:23], v30 offset0:85 offset1:93
	v_cvt_pk_bf16_f32 v8, v14, v12
	s_waitcnt lgkmcnt(3)
	s_nop 1
	s_waitcnt lgkmcnt(2)
	s_nop 0
	ds_read2_b32 v[24:25], v30 offset0:150 offset1:158
	s_nop 1
	ds_read2_b32 v[26:27], v30 offset0:215 offset1:223
	v_cvt_pk_bf16_f32 v9, v16, v18
	s_waitcnt lgkmcnt(3)
	s_nop 1
	s_waitcnt lgkmcnt(2)
	s_nop 2
	v_cvt_pk_bf16_f32 v10, v20, v22
	s_waitcnt lgkmcnt(1)
	s_nop 0
	v_add_u32_e32 v28, 16, v6
	s_nop 0
	s_waitcnt lgkmcnt(0)
	s_nop 0
	v_ashrrev_i32_e32 v29, 31, v28
	s_nop 1
	v_lshlrev_b64 v[28:29], 12, v[28:29]
	v_cvt_pk_bf16_f32 v11, v24, v26
	v_lshl_add_u64 v[28:29], v[4:5], 0, v[28:29]
	s_nop 0
	global_store_dwordx4 v[28:29], v[8:11], off
	s_nop 3
	v_cvt_pk_bf16_f32 v8, v15, v13
	s_nop 4
	v_cvt_pk_bf16_f32 v9, v17, v19
	s_nop 4
	v_cvt_pk_bf16_f32 v10, v21, v23
	s_nop 0
	v_add_u32_e32 v12, 24, v6
	s_nop 1
	v_ashrrev_i32_e32 v13, 31, v12
	s_nop 1
	v_lshlrev_b64 v[12:13], 12, v[12:13]
	v_cvt_pk_bf16_f32 v11, v25, v27
	ds_read2_b32 v[14:15], v80 offset0:32 offset1:40
	v_lshl_add_u64 v[12:13], v[4:5], 0, v[12:13]
	global_store_dwordx4 v[12:13], v[8:11], off
	ds_read2_b32 v[12:13], v80 offset0:97 offset1:105
	ds_read2_b32 v[16:17], v80 offset0:162 offset1:170
	ds_read2_b32 v[18:19], v80 offset0:227 offset1:235
	s_waitcnt lgkmcnt(3)
	s_nop 1
	s_waitcnt lgkmcnt(2)
	s_nop 0
	ds_read2_b32 v[20:21], v30 offset0:36 offset1:44
	s_nop 1
	ds_read2_b32 v[22:23], v30 offset0:101 offset1:109
	v_cvt_pk_bf16_f32 v8, v14, v12
	s_waitcnt lgkmcnt(3)
	s_nop 1
	s_waitcnt lgkmcnt(2)
	s_nop 0
	ds_read2_b32 v[24:25], v30 offset0:166 offset1:174
	s_nop 1
	ds_read2_b32 v[26:27], v30 offset0:231 offset1:239
	v_cvt_pk_bf16_f32 v9, v16, v18
	s_waitcnt lgkmcnt(3)
	s_nop 1
	s_waitcnt lgkmcnt(2)
	s_nop 2
	v_cvt_pk_bf16_f32 v10, v20, v22
	s_waitcnt lgkmcnt(1)
	s_nop 0
	v_add_u32_e32 v28, 32, v6
	s_nop 0
	s_waitcnt lgkmcnt(0)
	s_nop 0
	v_ashrrev_i32_e32 v29, 31, v28
	s_nop 1
	v_lshlrev_b64 v[28:29], 12, v[28:29]
	v_cvt_pk_bf16_f32 v11, v24, v26
	v_lshl_add_u64 v[28:29], v[4:5], 0, v[28:29]
	s_nop 0
	global_store_dwordx4 v[28:29], v[8:11], off
	s_nop 3
	v_cvt_pk_bf16_f32 v8, v15, v13
	s_nop 4
	v_cvt_pk_bf16_f32 v9, v17, v19
	s_nop 4
	v_cvt_pk_bf16_f32 v10, v21, v23
	s_nop 0
	v_add_u32_e32 v12, 40, v6
	s_nop 1
	v_ashrrev_i32_e32 v13, 31, v12
	s_nop 1
	v_lshlrev_b64 v[12:13], 12, v[12:13]
	v_cvt_pk_bf16_f32 v11, v25, v27
	ds_read2_b32 v[14:15], v80 offset0:48 offset1:56
	v_lshl_add_u64 v[12:13], v[4:5], 0, v[12:13]
	global_store_dwordx4 v[12:13], v[8:11], off
	ds_read2_b32 v[12:13], v80 offset0:113 offset1:121
	ds_read2_b32 v[16:17], v80 offset0:178 offset1:186
	ds_read2_b32 v[18:19], v80 offset0:243 offset1:251
	s_waitcnt lgkmcnt(3)
	s_nop 1
	s_waitcnt lgkmcnt(2)
	s_nop 0
	ds_read2_b32 v[20:21], v30 offset0:52 offset1:60
	s_nop 1
	ds_read2_b32 v[22:23], v30 offset0:117 offset1:125
	v_cvt_pk_bf16_f32 v8, v14, v12
	s_waitcnt lgkmcnt(3)
	s_nop 1
	s_waitcnt lgkmcnt(2)
	s_nop 0
	ds_read2_b32 v[24:25], v30 offset0:182 offset1:190
	s_nop 1
	ds_read2_b32 v[26:27], v30 offset0:247 offset1:255
	v_cvt_pk_bf16_f32 v9, v16, v18
	s_waitcnt lgkmcnt(3)
	s_nop 1
	s_waitcnt lgkmcnt(2)
	s_nop 2
	v_cvt_pk_bf16_f32 v10, v20, v22
	s_waitcnt lgkmcnt(1)
	s_nop 0
	v_add_u32_e32 v28, 48, v6
	s_nop 0
	s_waitcnt lgkmcnt(0)
	s_nop 0
	v_ashrrev_i32_e32 v29, 31, v28
	s_nop 1
	v_lshlrev_b64 v[28:29], 12, v[28:29]
	v_cvt_pk_bf16_f32 v11, v24, v26
	v_lshl_add_u64 v[28:29], v[4:5], 0, v[28:29]
	s_nop 0
	global_store_dwordx4 v[28:29], v[8:11], off
	s_nop 3
	v_cvt_pk_bf16_f32 v8, v15, v13
	s_nop 4
	v_cvt_pk_bf16_f32 v9, v17, v19
	s_nop 4
	v_cvt_pk_bf16_f32 v10, v21, v23
	s_nop 4
	v_add_u32_e32 v6, 56, v6
	v_cvt_pk_bf16_f32 v11, v25, v27
	v_ashrrev_i32_e32 v7, 31, v6
	v_lshlrev_b64 v[6:7], 12, v[6:7]
	v_lshl_add_u64 v[4:5], v[4:5], 0, v[6:7]
	global_store_dwordx4 v[4:5], v[8:11], off
	s_waitcnt lgkmcnt(0)
	s_cbranch_scc0 .LBB0_4609

; #define LAS __attribute__((address_space(3)))
; #define LDS_WAIT() asm volatile("s_waitcnt lgkmcnt(0)" ::: "memory")
; __device__ __forceinline__ unsigned pk2(float lo, float hi) { return f2bf(lo) | (f2bf(hi) << 16); }
;     ...
;         for (int i = 0; i < 16; ++i) { LAS float* d = scr + (4 * i + kr) * 65 + nq; d[0] = v[i].x; d[1] = v[i].y; d[2] = v[i].z; d[3] = v[i].w; }
;         LDS_WAIT(); asm volatile("" ::: "memory");
;         const int c8 = lane & 7; int d0 = n0;
;         if (ffnmap) { const int bj = n0 >= FFH ? 1 : 0, chn = n0 - FFH * bj; d0 = 256 * (chn >> 7) + 128 * bj + (chn & 127); }
; #pragma unroll
;         for (int j = 0; j < 8; ++j) { const int n = (lane >> 3) + 8 * j; const LAS float* sp = scr + (8 * c8) * 65 + n;
;             v4u o; o.x = pk2(sp[0 * 65], sp[1 * 65]); o.y = pk2(sp[2 * 65], sp[3 * 65]); o.z = pk2(sp[4 * 65], sp[5 * 65]); o.w = pk2(sp[6 * 65], sp[7 * 65]);
;             *(v4u*)(WT + (size_t)(d0 + n) * K + k0 + 8 * c8) = o; }
.LBB0_4611:
	s_or_b64 exec, exec, s[6:7]
	s_waitcnt vmcnt(0)
	ds_write2_b32 v79, v4, v5 offset1:1
	ds_write2_b32 v79, v6, v7 offset0:2 offset1:3
	v_add_u32_e32 v4, 0x410, v79
	ds_write2_b32 v4, v12, v13 offset1:1
	v_add_u32_e32 v4, 0x418, v79
	ds_write2_b32 v4, v14, v15 offset1:1
	v_add_u32_e32 v4, 0x820, v79
	ds_write2_b32 v4, v8, v9 offset1:1
	v_add_u32_e32 v4, 0x828, v79
	ds_write2_b32 v4, v10, v11 offset1:1
	v_add_u32_e32 v4, 0xc30, v79
	ds_write2_b32 v4, v20, v21 offset1:1
	v_add_u32_e32 v4, 0xc38, v79
	ds_write2_b32 v4, v22, v23 offset1:1
	v_add_u32_e32 v4, 0x1040, v79
	ds_write2_b32 v4, v16, v17 offset1:1
	v_add_u32_e32 v4, 0x1048, v79
	ds_write2_b32 v4, v18, v19 offset1:1
	v_add_u32_e32 v4, 0x1450, v79
	ds_write2_b32 v4, v28, v29 offset1:1
	v_add_u32_e32 v4, 0x1458, v79
	ds_write2_b32 v4, v30, v31 offset1:1
	v_add_u32_e32 v4, 0x1860, v79
	ds_write2_b32 v4, v24, v25 offset1:1
	v_add_u32_e32 v4, 0x1868, v79
	ds_write2_b32 v4, v26, v27 offset1:1
	v_add_u32_e32 v4, 0x1c70, v79
	ds_write2_b32 v4, v36, v37 offset1:1
	v_add_u32_e32 v4, 0x1c78, v79
	ds_write2_b32 v4, v38, v39 offset1:1
	v_add_u32_e32 v4, 0x2080, v79
	ds_write2_b32 v4, v32, v33 offset1:1
	v_add_u32_e32 v4, 0x2088, v79
	ds_write2_b32 v4, v34, v35 offset1:1
	v_add_u32_e32 v4, 0x2490, v79
	ds_write2_b32 v4, v44, v45 offset1:1
	v_add_u32_e32 v4, 0x2498, v79
	ds_write2_b32 v4, v46, v47 offset1:1
	v_add_u32_e32 v4, 0x28a0, v79
	ds_write2_b32 v4, v40, v41 offset1:1
	v_add_u32_e32 v4, 0x28a8, v79
	ds_write2_b32 v4, v42, v43 offset1:1
	v_add_u32_e32 v4, 0x2cb0, v79
	ds_write2_b32 v4, v52, v53 offset1:1
	v_add_u32_e32 v4, 0x2cb8, v79
	ds_write2_b32 v4, v54, v55 offset1:1
	v_add_u32_e32 v4, 0x30c0, v79
	ds_write2_b32 v4, v48, v49 offset1:1
	v_add_u32_e32 v4, 0x30c8, v79
	ds_write2_b32 v4, v50, v51 offset1:1
	v_add_u32_e32 v4, 0x34d0, v79
	ds_write2_b32 v4, v60, v61 offset1:1
	v_add_u32_e32 v4, 0x34d8, v79
	ds_write2_b32 v4, v62, v63 offset1:1
	v_add_u32_e32 v4, 0x38e0, v79
	ds_write2_b32 v4, v56, v57 offset1:1
	v_add_u32_e32 v4, 0x38e8, v79
	ds_write2_b32 v4, v58, v59 offset1:1
	v_add_u32_e32 v4, 0x3cf0, v79
	ds_write2_b32 v4, v64, v65 offset1:1
	v_add_u32_e32 v4, 0x3cf8, v79
	ds_write2_b32 v4, v66, v67 offset1:1
	s_waitcnt lgkmcnt(0)
	ds_read2_b32 v[12:13], v78 offset1:8
	ds_read2_b32 v[14:15], v78 offset0:65 offset1:73
	ds_read2_b32 v[16:17], v78 offset0:130 offset1:138
	ds_read2_b32 v[18:19], v78 offset0:195 offset1:203
	v_add_u32_e32 v30, 0x400, v78
	s_waitcnt lgkmcnt(3)
	s_nop 1
	s_waitcnt lgkmcnt(2)
	s_nop 0
	ds_read2_b32 v[20:21], v30 offset0:4 offset1:12
	s_nop 1
	ds_read2_b32 v[22:23], v30 offset0:69 offset1:77
	v_cvt_pk_bf16_f32 v8, v12, v14
	s_waitcnt lgkmcnt(3)
	s_nop 1
	s_waitcnt lgkmcnt(2)
	s_nop 0
	ds_read2_b32 v[24:25], v30 offset0:134 offset1:142
	s_nop 1
	ds_read2_b32 v[26:27], v30 offset0:199 offset1:207
	v_cvt_pk_bf16_f32 v9, v16, v18
	s_waitcnt lgkmcnt(3)
	s_nop 1
	s_waitcnt lgkmcnt(2)
	s_nop 2
	v_cvt_pk_bf16_f32 v10, v20, v22
	s_waitcnt lgkmcnt(1)
	s_nop 1
	s_waitcnt lgkmcnt(0)
	s_nop 2
	s_add_i32 s17, s17, s12
	v_cvt_pk_bf16_f32 v11, v24, v26
	v_add_u32_e32 v6, s17, v77
	s_ashr_i32 s3, s2, 31
	v_ashrrev_i32_e32 v7, 31, v6
	v_lshl_add_u64 v[4:5], s[2:3], 1, v[70:71]
	v_lshlrev_b64 v[28:29], 12, v[6:7]
	v_lshl_add_u64 v[28:29], v[4:5], 0, v[28:29]
	s_nop 0
	global_store_dwordx4 v[28:29], v[8:11], off
	s_nop 3
	v_cvt_pk_bf16_f32 v8, v13, v15
	s_nop 4
	v_cvt_pk_bf16_f32 v9, v17, v19
	s_nop 4
	v_cvt_pk_bf16_f32 v10, v21, v23
	s_nop 0
	v_add_u32_e32 v12, 8, v6
	s_nop 1
	v_ashrrev_i32_e32 v13, 31, v12
	s_nop 1
	v_lshlrev_b64 v[12:13], 12, v[12:13]
	v_cvt_pk_bf16_f32 v11, v25, v27
	ds_read2_b32 v[14:15], v78 offset0:16 offset1:24
	v_lshl_add_u64 v[12:13], v[4:5], 0, v[12:13]
	global_store_dwordx4 v[12:13], v[8:11], off
	ds_read2_b32 v[12:13], v78 offset0:81 offset1:89
	ds_read2_b32 v[16:17], v78 offset0:146 offset1:154
	ds_read2_b32 v[18:19], v78 offset0:211 offset1:219
	s_waitcnt lgkmcnt(3)
	s_nop 1
	s_waitcnt lgkmcnt(2)
; #define LAS __attribute__((address_space(3)))
; #define LDS_WAIT() asm volatile("s_waitcnt lgkmcnt(0)" ::: "memory")
; __device__ __forceinline__ unsigned pk2(float lo, float hi) { return f2bf(lo) | (f2bf(hi) << 16); }
;     ...
;         const int c8 = lane & 7; int d0 = n0;
;         if (ffnmap) { const int bj = n0 >= FFH ? 1 : 0, chn = n0 - FFH * bj; d0 = 256 * (chn >> 7) + 128 * bj + (chn & 127); }
; #pragma unroll
;         for (int j = 0; j < 8; ++j) { const int n = (lane >> 3) + 8 * j; const LAS float* sp = scr + (8 * c8) * 65 + n;
;             v4u o; o.x = pk2(sp[0 * 65], sp[1 * 65]); o.y = pk2(sp[2 * 65], sp[3 * 65]); o.z = pk2(sp[4 * 65], sp[5 * 65]); o.w = pk2(sp[6 * 65], sp[7 * 65]);
;             *(v4u*)(WT + (size_t)(d0 + n) * K + k0 + 8 * c8) = o; }
;         LDS_WAIT(); asm volatile("" ::: "memory");
	s_nop 0
	ds_read2_b32 v[20:21], v30 offset0:20 offset1:28
	s_nop 1
	ds_read2_b32 v[22:23], v30 offset0:85 offset1:93
	v_cvt_pk_bf16_f32 v8, v14, v12
	s_waitcnt lgkmcnt(3)
	s_nop 1
	s_waitcnt lgkmcnt(2)
	s_nop 0
	ds_read2_b32 v[24:25], v30 offset0:150 offset1:158
	s_nop 1
	ds_read2_b32 v[26:27], v30 offset0:215 offset1:223
	v_cvt_pk_bf16_f32 v9, v16, v18
	s_waitcnt lgkmcnt(3)
	s_nop 1
	s_waitcnt lgkmcnt(2)
	s_nop 2
	v_cvt_pk_bf16_f32 v10, v20, v22
	s_waitcnt lgkmcnt(1)
	s_nop 0
	v_add_u32_e32 v28, 16, v6
	s_nop 0
	s_waitcnt lgkmcnt(0)
	s_nop 0
	v_ashrrev_i32_e32 v29, 31, v28
	s_nop 1
	v_lshlrev_b64 v[28:29], 12, v[28:29]
	v_cvt_pk_bf16_f32 v11, v24, v26
	v_lshl_add_u64 v[28:29], v[4:5], 0, v[28:29]
	s_nop 0
	global_store_dwordx4 v[28:29], v[8:11], off
	s_nop 3
	v_cvt_pk_bf16_f32 v8, v15, v13
	s_nop 4
	v_cvt_pk_bf16_f32 v9, v17, v19
	s_nop 4
	v_cvt_pk_bf16_f32 v10, v21, v23
	s_nop 0
	v_add_u32_e32 v12, 24, v6
	s_nop 1
	v_ashrrev_i32_e32 v13, 31, v12
	s_nop 1
	v_lshlrev_b64 v[12:13], 12, v[12:13]
	v_cvt_pk_bf16_f32 v11, v25, v27
	ds_read2_b32 v[14:15], v78 offset0:32 offset1:40
	v_lshl_add_u64 v[12:13], v[4:5], 0, v[12:13]
	global_store_dwordx4 v[12:13], v[8:11], off
	ds_read2_b32 v[12:13], v78 offset0:97 offset1:105
	ds_read2_b32 v[16:17], v78 offset0:162 offset1:170
	ds_read2_b32 v[18:19], v78 offset0:227 offset1:235
	s_waitcnt lgkmcnt(3)
	s_nop 1
	s_waitcnt lgkmcnt(2)
	s_nop 0
	ds_read2_b32 v[20:21], v30 offset0:36 offset1:44
	s_nop 1
	ds_read2_b32 v[22:23], v30 offset0:101 offset1:109
	v_cvt_pk_bf16_f32 v8, v14, v12
	s_waitcnt lgkmcnt(3)
	s_nop 1
	s_waitcnt lgkmcnt(2)
	s_nop 0
	ds_read2_b32 v[24:25], v30 offset0:166 offset1:174
	s_nop 1
	ds_read2_b32 v[26:27], v30 offset0:231 offset1:239
	v_cvt_pk_bf16_f32 v9, v16, v18
	s_waitcnt lgkmcnt(3)
	s_nop 1
	s_waitcnt lgkmcnt(2)
	s_nop 2
	v_cvt_pk_bf16_f32 v10, v20, v22
	s_waitcnt lgkmcnt(1)
	s_nop 0
	v_add_u32_e32 v28, 32, v6
	s_nop 0
	s_waitcnt lgkmcnt(0)
	s_nop 0
	v_ashrrev_i32_e32 v29, 31, v28
	s_nop 1
	v_lshlrev_b64 v[28:29], 12, v[28:29]
	v_cvt_pk_bf16_f32 v11, v24, v26
	v_lshl_add_u64 v[28:29], v[4:5], 0, v[28:29]
	s_nop 0
	global_store_dwordx4 v[28:29], v[8:11], off
	s_nop 3
	v_cvt_pk_bf16_f32 v8, v15, v13
	s_nop 4
	v_cvt_pk_bf16_f32 v9, v17, v19
	s_nop 4
	v_cvt_pk_bf16_f32 v10, v21, v23
	s_nop 0
	v_add_u32_e32 v12, 40, v6
	s_nop 1
	v_ashrrev_i32_e32 v13, 31, v12
	s_nop 1
	v_lshlrev_b64 v[12:13], 12, v[12:13]
	v_cvt_pk_bf16_f32 v11, v25, v27
	ds_read2_b32 v[14:15], v78 offset0:48 offset1:56
	v_lshl_add_u64 v[12:13], v[4:5], 0, v[12:13]
	global_store_dwordx4 v[12:13], v[8:11], off
	ds_read2_b32 v[12:13], v78 offset0:113 offset1:121
	ds_read2_b32 v[16:17], v78 offset0:178 offset1:186
	ds_read2_b32 v[18:19], v78 offset0:243 offset1:251
	s_waitcnt lgkmcnt(3)
	s_nop 1
	s_waitcnt lgkmcnt(2)
	s_nop 0
	ds_read2_b32 v[20:21], v30 offset0:52 offset1:60
	s_nop 1
	ds_read2_b32 v[22:23], v30 offset0:117 offset1:125
	v_cvt_pk_bf16_f32 v8, v14, v12
	s_waitcnt lgkmcnt(3)
	s_nop 1
	s_waitcnt lgkmcnt(2)
	s_nop 0
	ds_read2_b32 v[24:25], v30 offset0:182 offset1:190
	s_nop 1
	ds_read2_b32 v[26:27], v30 offset0:247 offset1:255
	v_cvt_pk_bf16_f32 v9, v16, v18
	s_waitcnt lgkmcnt(3)
	s_nop 1
	s_waitcnt lgkmcnt(2)
	s_nop 2
	v_cvt_pk_bf16_f32 v10, v20, v22
	s_waitcnt lgkmcnt(1)
	s_nop 0
	v_add_u32_e32 v28, 48, v6
	s_nop 0
	s_waitcnt lgkmcnt(0)
	s_nop 0
	v_ashrrev_i32_e32 v29, 31, v28
	s_nop 1
	v_lshlrev_b64 v[28:29], 12, v[28:29]
	v_cvt_pk_bf16_f32 v11, v24, v26
	v_lshl_add_u64 v[28:29], v[4:5], 0, v[28:29]
	s_nop 0
	global_store_dwordx4 v[28:29], v[8:11], off
	s_nop 3
	v_cvt_pk_bf16_f32 v8, v15, v13
	s_nop 4
	v_cvt_pk_bf16_f32 v9, v17, v19
	s_nop 4
	v_cvt_pk_bf16_f32 v10, v21, v23
	s_nop 4
	v_add_u32_e32 v6, 56, v6
	v_cvt_pk_bf16_f32 v11, v25, v27
	v_ashrrev_i32_e32 v7, 31, v6
	v_lshlrev_b64 v[6:7], 12, v[6:7]
	v_lshl_add_u64 v[4:5], v[4:5], 0, v[6:7]
	global_store_dwordx4 v[4:5], v[8:11], off
	s_waitcnt lgkmcnt(0)
	s_add_i32 s11, s11, s86
	s_add_i32 s12, s12, s13
	s_cmpk_lt_i32 s11, 0x200
	s_cbranch_scc0 .LBB0_4644

; #define LAS __attribute__((address_space(3)))
; #define LDS_WAIT() asm volatile("s_waitcnt lgkmcnt(0)" ::: "memory")
; __device__ __forceinline__ unsigned pk2(float lo, float hi) { return f2bf(lo) | (f2bf(hi) << 16); }
;     ...
;         for (int i = 0; i < 16; ++i) { LAS float* d = scr + (4 * i + kr) * 65 + nq; d[0] = v[i].x; d[1] = v[i].y; d[2] = v[i].z; d[3] = v[i].w; }
;         LDS_WAIT(); asm volatile("" ::: "memory");
;         const int c8 = lane & 7; int d0 = n0;
;         if (ffnmap) { const int bj = n0 >= FFH ? 1 : 0, chn = n0 - FFH * bj; d0 = 256 * (chn >> 7) + 128 * bj + (chn & 127); }
; #pragma unroll
;         for (int j = 0; j < 8; ++j) { const int n = (lane >> 3) + 8 * j; const LAS float* sp = scr + (8 * c8) * 65 + n;
;             v4u o; o.x = pk2(sp[0 * 65], sp[1 * 65]); o.y = pk2(sp[2 * 65], sp[3 * 65]); o.z = pk2(sp[4 * 65], sp[5 * 65]); o.w = pk2(sp[6 * 65], sp[7 * 65]);
;             *(v4u*)(WT + (size_t)(d0 + n) * K + k0 + 8 * c8) = o; }
.LBB0_4646:
	s_or_b64 exec, exec, s[6:7]
	s_waitcnt vmcnt(0)
	ds_write2_b32 v79, v4, v5 offset1:1
	ds_write2_b32 v79, v6, v7 offset0:2 offset1:3
	v_add_u32_e32 v4, 0x410, v79
	ds_write2_b32 v4, v12, v13 offset1:1
	v_add_u32_e32 v4, 0x418, v79
	ds_write2_b32 v4, v14, v15 offset1:1
	v_add_u32_e32 v4, 0x820, v79
	ds_write2_b32 v4, v8, v9 offset1:1
	v_add_u32_e32 v4, 0x828, v79
	ds_write2_b32 v4, v10, v11 offset1:1
	v_add_u32_e32 v4, 0xc30, v79
	ds_write2_b32 v4, v20, v21 offset1:1
	v_add_u32_e32 v4, 0xc38, v79
	ds_write2_b32 v4, v22, v23 offset1:1
	v_add_u32_e32 v4, 0x1040, v79
	ds_write2_b32 v4, v16, v17 offset1:1
	v_add_u32_e32 v4, 0x1048, v79
	ds_write2_b32 v4, v18, v19 offset1:1
	v_add_u32_e32 v4, 0x1450, v79
	ds_write2_b32 v4, v28, v29 offset1:1
	v_add_u32_e32 v4, 0x1458, v79
	ds_write2_b32 v4, v30, v31 offset1:1
	v_add_u32_e32 v4, 0x1860, v79
	ds_write2_b32 v4, v24, v25 offset1:1
	v_add_u32_e32 v4, 0x1868, v79
	ds_write2_b32 v4, v26, v27 offset1:1
	v_add_u32_e32 v4, 0x1c70, v79
	ds_write2_b32 v4, v36, v37 offset1:1
	v_add_u32_e32 v4, 0x1c78, v79
	ds_write2_b32 v4, v38, v39 offset1:1
	v_add_u32_e32 v4, 0x2080, v79
	ds_write2_b32 v4, v32, v33 offset1:1
	v_add_u32_e32 v4, 0x2088, v79
	ds_write2_b32 v4, v34, v35 offset1:1
	v_add_u32_e32 v4, 0x2490, v79
	ds_write2_b32 v4, v44, v45 offset1:1
	v_add_u32_e32 v4, 0x2498, v79
	ds_write2_b32 v4, v46, v47 offset1:1
	v_add_u32_e32 v4, 0x28a0, v79
	ds_write2_b32 v4, v40, v41 offset1:1
	v_add_u32_e32 v4, 0x28a8, v79
	ds_write2_b32 v4, v42, v43 offset1:1
	v_add_u32_e32 v4, 0x2cb0, v79
	ds_write2_b32 v4, v52, v53 offset1:1
	v_add_u32_e32 v4, 0x2cb8, v79
	ds_write2_b32 v4, v54, v55 offset1:1
	v_add_u32_e32 v4, 0x30c0, v79
	ds_write2_b32 v4, v48, v49 offset1:1
	v_add_u32_e32 v4, 0x30c8, v79
	ds_write2_b32 v4, v50, v51 offset1:1
	v_add_u32_e32 v4, 0x34d0, v79
	ds_write2_b32 v4, v60, v61 offset1:1
	v_add_u32_e32 v4, 0x34d8, v79
	ds_write2_b32 v4, v62, v63 offset1:1
	v_add_u32_e32 v4, 0x38e0, v79
	ds_write2_b32 v4, v56, v57 offset1:1
	v_add_u32_e32 v4, 0x38e8, v79
	ds_write2_b32 v4, v58, v59 offset1:1
	v_add_u32_e32 v4, 0x3cf0, v79
	ds_write2_b32 v4, v64, v65 offset1:1
	v_add_u32_e32 v4, 0x3cf8, v79
	ds_write2_b32 v4, v66, v67 offset1:1
	s_waitcnt lgkmcnt(0)
	ds_read2_b32 v[12:13], v78 offset1:8
	ds_read2_b32 v[14:15], v78 offset0:65 offset1:73
	ds_read2_b32 v[16:17], v78 offset0:130 offset1:138
	ds_read2_b32 v[18:19], v78 offset0:195 offset1:203
	v_add_u32_e32 v30, 0x400, v78
	s_waitcnt lgkmcnt(3)
	s_nop 1
	s_waitcnt lgkmcnt(2)
	s_nop 0
	ds_read2_b32 v[20:21], v30 offset0:4 offset1:12
	s_nop 1
	ds_read2_b32 v[22:23], v30 offset0:69 offset1:77
	v_cvt_pk_bf16_f32 v8, v12, v14
	s_waitcnt lgkmcnt(3)
	s_nop 1
	s_waitcnt lgkmcnt(2)
	s_nop 0
	ds_read2_b32 v[24:25], v30 offset0:134 offset1:142
	s_nop 1
	ds_read2_b32 v[26:27], v30 offset0:199 offset1:207
	v_cvt_pk_bf16_f32 v9, v16, v18
	s_waitcnt lgkmcnt(3)
	s_nop 1
	s_waitcnt lgkmcnt(2)
	s_nop 2
	v_cvt_pk_bf16_f32 v10, v20, v22
	s_waitcnt lgkmcnt(1)
	s_nop 1
	s_waitcnt lgkmcnt(0)
	s_nop 2
	s_add_i32 s17, s17, s12
	v_cvt_pk_bf16_f32 v11, v24, v26
	v_add_u32_e32 v6, s17, v77
	s_ashr_i32 s3, s2, 31
	v_ashrrev_i32_e32 v7, 31, v6
	v_lshl_add_u64 v[4:5], s[2:3], 1, v[70:71]
	v_lshlrev_b64 v[28:29], 10, v[6:7]
	v_lshl_add_u64 v[28:29], v[4:5], 0, v[28:29]
	s_nop 0
	global_store_dwordx4 v[28:29], v[8:11], off
	s_nop 3
	v_cvt_pk_bf16_f32 v8, v13, v15
	s_nop 4
	v_cvt_pk_bf16_f32 v9, v17, v19
	s_nop 4
	v_cvt_pk_bf16_f32 v10, v21, v23
	s_nop 0
	v_add_u32_e32 v12, 8, v6
	s_nop 1
	v_ashrrev_i32_e32 v13, 31, v12
	s_nop 1
	v_lshlrev_b64 v[12:13], 10, v[12:13]
	v_cvt_pk_bf16_f32 v11, v25, v27
	ds_read2_b32 v[14:15], v78 offset0:16 offset1:24
	v_lshl_add_u64 v[12:13], v[4:5], 0, v[12:13]
	global_store_dwordx4 v[12:13], v[8:11], off
	ds_read2_b32 v[12:13], v78 offset0:81 offset1:89
	ds_read2_b32 v[16:17], v78 offset0:146 offset1:154
	ds_read2_b32 v[18:19], v78 offset0:211 offset1:219
	s_waitcnt lgkmcnt(3)
	s_nop 1
	s_waitcnt lgkmcnt(2)
; #define LAS __attribute__((address_space(3)))
; #define LDS_WAIT() asm volatile("s_waitcnt lgkmcnt(0)" ::: "memory")
; __device__ __forceinline__ unsigned pk2(float lo, float hi) { return f2bf(lo) | (f2bf(hi) << 16); }
;     ...
;         const int c8 = lane & 7; int d0 = n0;
;         if (ffnmap) { const int bj = n0 >= FFH ? 1 : 0, chn = n0 - FFH * bj; d0 = 256 * (chn >> 7) + 128 * bj + (chn & 127); }
; #pragma unroll
;         for (int j = 0; j < 8; ++j) { const int n = (lane >> 3) + 8 * j; const LAS float* sp = scr + (8 * c8) * 65 + n;
;             v4u o; o.x = pk2(sp[0 * 65], sp[1 * 65]); o.y = pk2(sp[2 * 65], sp[3 * 65]); o.z = pk2(sp[4 * 65], sp[5 * 65]); o.w = pk2(sp[6 * 65], sp[7 * 65]);
;             *(v4u*)(WT + (size_t)(d0 + n) * K + k0 + 8 * c8) = o; }
;         LDS_WAIT(); asm volatile("" ::: "memory");
	s_nop 0
	ds_read2_b32 v[20:21], v30 offset0:20 offset1:28
	s_nop 1
	ds_read2_b32 v[22:23], v30 offset0:85 offset1:93
	v_cvt_pk_bf16_f32 v8, v14, v12
	s_waitcnt lgkmcnt(3)
	s_nop 1
	s_waitcnt lgkmcnt(2)
	s_nop 0
	ds_read2_b32 v[24:25], v30 offset0:150 offset1:158
	s_nop 1
	ds_read2_b32 v[26:27], v30 offset0:215 offset1:223
	v_cvt_pk_bf16_f32 v9, v16, v18
	s_waitcnt lgkmcnt(3)
	s_nop 1
	s_waitcnt lgkmcnt(2)
	s_nop 2
	v_cvt_pk_bf16_f32 v10, v20, v22
	s_waitcnt lgkmcnt(1)
	s_nop 0
	v_add_u32_e32 v28, 16, v6
	s_nop 0
	s_waitcnt lgkmcnt(0)
	s_nop 0
	v_ashrrev_i32_e32 v29, 31, v28
	s_nop 1
	v_lshlrev_b64 v[28:29], 10, v[28:29]
	v_cvt_pk_bf16_f32 v11, v24, v26
	v_lshl_add_u64 v[28:29], v[4:5], 0, v[28:29]
	s_nop 0
	global_store_dwordx4 v[28:29], v[8:11], off
	s_nop 3
	v_cvt_pk_bf16_f32 v8, v15, v13
	s_nop 4
	v_cvt_pk_bf16_f32 v9, v17, v19
	s_nop 4
	v_cvt_pk_bf16_f32 v10, v21, v23
	s_nop 0
	v_add_u32_e32 v12, 24, v6
	s_nop 1
	v_ashrrev_i32_e32 v13, 31, v12
	s_nop 1
	v_lshlrev_b64 v[12:13], 10, v[12:13]
	v_cvt_pk_bf16_f32 v11, v25, v27
	ds_read2_b32 v[14:15], v78 offset0:32 offset1:40
	v_lshl_add_u64 v[12:13], v[4:5], 0, v[12:13]
	global_store_dwordx4 v[12:13], v[8:11], off
	ds_read2_b32 v[12:13], v78 offset0:97 offset1:105
	ds_read2_b32 v[16:17], v78 offset0:162 offset1:170
	ds_read2_b32 v[18:19], v78 offset0:227 offset1:235
	s_waitcnt lgkmcnt(3)
	s_nop 1
	s_waitcnt lgkmcnt(2)
	s_nop 0
	ds_read2_b32 v[20:21], v30 offset0:36 offset1:44
	s_nop 1
	ds_read2_b32 v[22:23], v30 offset0:101 offset1:109
	v_cvt_pk_bf16_f32 v8, v14, v12
	s_waitcnt lgkmcnt(3)
	s_nop 1
	s_waitcnt lgkmcnt(2)
	s_nop 0
	ds_read2_b32 v[24:25], v30 offset0:166 offset1:174
	s_nop 1
	ds_read2_b32 v[26:27], v30 offset0:231 offset1:239
	v_cvt_pk_bf16_f32 v9, v16, v18
	s_waitcnt lgkmcnt(3)
	s_nop 1
	s_waitcnt lgkmcnt(2)
	s_nop 2
	v_cvt_pk_bf16_f32 v10, v20, v22
	s_waitcnt lgkmcnt(1)
	s_nop 0
	v_add_u32_e32 v28, 32, v6
	s_nop 0
	s_waitcnt lgkmcnt(0)
	s_nop 0
	v_ashrrev_i32_e32 v29, 31, v28
	s_nop 1
	v_lshlrev_b64 v[28:29], 10, v[28:29]
	v_cvt_pk_bf16_f32 v11, v24, v26
	v_lshl_add_u64 v[28:29], v[4:5], 0, v[28:29]
	s_nop 0
	global_store_dwordx4 v[28:29], v[8:11], off
	s_nop 3
	v_cvt_pk_bf16_f32 v8, v15, v13
	s_nop 4
	v_cvt_pk_bf16_f32 v9, v17, v19
	s_nop 4
	v_cvt_pk_bf16_f32 v10, v21, v23
	s_nop 0
	v_add_u32_e32 v12, 40, v6
	s_nop 1
	v_ashrrev_i32_e32 v13, 31, v12
	s_nop 1
	v_lshlrev_b64 v[12:13], 10, v[12:13]
	v_cvt_pk_bf16_f32 v11, v25, v27
	ds_read2_b32 v[14:15], v78 offset0:48 offset1:56
	v_lshl_add_u64 v[12:13], v[4:5], 0, v[12:13]
	global_store_dwordx4 v[12:13], v[8:11], off
	ds_read2_b32 v[12:13], v78 offset0:113 offset1:121
	ds_read2_b32 v[16:17], v78 offset0:178 offset1:186
	ds_read2_b32 v[18:19], v78 offset0:243 offset1:251
	s_waitcnt lgkmcnt(3)
	s_nop 1
	s_waitcnt lgkmcnt(2)
	s_nop 0
	ds_read2_b32 v[20:21], v30 offset0:52 offset1:60
	s_nop 1
	ds_read2_b32 v[22:23], v30 offset0:117 offset1:125
	v_cvt_pk_bf16_f32 v8, v14, v12
	s_waitcnt lgkmcnt(3)
	s_nop 1
	s_waitcnt lgkmcnt(2)
	s_nop 0
	ds_read2_b32 v[24:25], v30 offset0:182 offset1:190
	s_nop 1
	ds_read2_b32 v[26:27], v30 offset0:247 offset1:255
	v_cvt_pk_bf16_f32 v9, v16, v18
	s_waitcnt lgkmcnt(3)
	s_nop 1
	s_waitcnt lgkmcnt(2)
	s_nop 2
	v_cvt_pk_bf16_f32 v10, v20, v22
	s_waitcnt lgkmcnt(1)
	s_nop 0
	v_add_u32_e32 v28, 48, v6
	s_nop 0
	s_waitcnt lgkmcnt(0)
	s_nop 0
	v_ashrrev_i32_e32 v29, 31, v28
	s_nop 1
	v_lshlrev_b64 v[28:29], 10, v[28:29]
	v_cvt_pk_bf16_f32 v11, v24, v26
	v_lshl_add_u64 v[28:29], v[4:5], 0, v[28:29]
	s_nop 0
	global_store_dwordx4 v[28:29], v[8:11], off
	s_nop 3
	v_cvt_pk_bf16_f32 v8, v15, v13
	s_nop 4
	v_cvt_pk_bf16_f32 v9, v17, v19
	s_nop 4
	v_cvt_pk_bf16_f32 v10, v21, v23
	s_nop 4
	v_add_u32_e32 v6, 56, v6
	v_cvt_pk_bf16_f32 v11, v25, v27
	v_ashrrev_i32_e32 v7, 31, v6
	v_lshlrev_b64 v[6:7], 10, v[6:7]
	v_lshl_add_u64 v[4:5], v[4:5], 0, v[6:7]
	global_store_dwordx4 v[4:5], v[8:11], off
	s_waitcnt lgkmcnt(0)
	s_add_i32 s11, s11, s86
	s_add_i32 s12, s12, s13
	s_cmpk_lt_i32 s11, 0x100
	s_cbranch_scc0 .LBB0_4679

; #define LAS __attribute__((address_space(3)))
; #define LDS_WAIT() asm volatile("s_waitcnt lgkmcnt(0)" ::: "memory")
; __device__ __forceinline__ unsigned pk2(float lo, float hi) { return f2bf(lo) | (f2bf(hi) << 16); }
;     ...
;         for (int i = 0; i < 16; ++i) { LAS float* d = scr + (4 * i + kr) * 65 + nq; d[0] = v[i].x; d[1] = v[i].y; d[2] = v[i].z; d[3] = v[i].w; }
;         LDS_WAIT(); asm volatile("" ::: "memory");
;         const int c8 = lane & 7; int d0 = n0;
;         if (ffnmap) { const int bj = n0 >= FFH ? 1 : 0, chn = n0 - FFH * bj; d0 = 256 * (chn >> 7) + 128 * bj + (chn & 127); }
; #pragma unroll
;         for (int j = 0; j < 8; ++j) { const int n = (lane >> 3) + 8 * j; const LAS float* sp = scr + (8 * c8) * 65 + n;
;             v4u o; o.x = pk2(sp[0 * 65], sp[1 * 65]); o.y = pk2(sp[2 * 65], sp[3 * 65]); o.z = pk2(sp[4 * 65], sp[5 * 65]); o.w = pk2(sp[6 * 65], sp[7 * 65]);
;             *(v4u*)(WT + (size_t)(d0 + n) * K + k0 + 8 * c8) = o; }
.LBB0_4775:
	s_or_b64 exec, exec, s[6:7]
	s_waitcnt vmcnt(0)
	ds_write2_b32 v79, v4, v5 offset1:1
	ds_write2_b32 v79, v6, v7 offset0:2 offset1:3
	v_add_u32_e32 v4, 0x410, v79
	ds_write2_b32 v4, v12, v13 offset1:1
	v_add_u32_e32 v4, 0x418, v79
	ds_write2_b32 v4, v14, v15 offset1:1
	v_add_u32_e32 v4, 0x820, v79
	ds_write2_b32 v4, v8, v9 offset1:1
	v_add_u32_e32 v4, 0x828, v79
	ds_write2_b32 v4, v10, v11 offset1:1
	v_add_u32_e32 v4, 0xc30, v79
	ds_write2_b32 v4, v20, v21 offset1:1
	v_add_u32_e32 v4, 0xc38, v79
	ds_write2_b32 v4, v22, v23 offset1:1
	v_add_u32_e32 v4, 0x1040, v79
	ds_write2_b32 v4, v16, v17 offset1:1
	v_add_u32_e32 v4, 0x1048, v79
	ds_write2_b32 v4, v18, v19 offset1:1
	v_add_u32_e32 v4, 0x1450, v79
	ds_write2_b32 v4, v28, v29 offset1:1
	v_add_u32_e32 v4, 0x1458, v79
	ds_write2_b32 v4, v30, v31 offset1:1
	v_add_u32_e32 v4, 0x1860, v79
	ds_write2_b32 v4, v24, v25 offset1:1
	v_add_u32_e32 v4, 0x1868, v79
	ds_write2_b32 v4, v26, v27 offset1:1
	v_add_u32_e32 v4, 0x1c70, v79
	ds_write2_b32 v4, v36, v37 offset1:1
	v_add_u32_e32 v4, 0x1c78, v79
	ds_write2_b32 v4, v38, v39 offset1:1
	v_add_u32_e32 v4, 0x2080, v79
	ds_write2_b32 v4, v32, v33 offset1:1
	v_add_u32_e32 v4, 0x2088, v79
	ds_write2_b32 v4, v34, v35 offset1:1
	v_add_u32_e32 v4, 0x2490, v79
	ds_write2_b32 v4, v44, v45 offset1:1
	v_add_u32_e32 v4, 0x2498, v79
	ds_write2_b32 v4, v46, v47 offset1:1
	v_add_u32_e32 v4, 0x28a0, v79
	ds_write2_b32 v4, v40, v41 offset1:1
	v_add_u32_e32 v4, 0x28a8, v79
	ds_write2_b32 v4, v42, v43 offset1:1
	v_add_u32_e32 v4, 0x2cb0, v79
	ds_write2_b32 v4, v52, v53 offset1:1
	v_add_u32_e32 v4, 0x2cb8, v79
	ds_write2_b32 v4, v54, v55 offset1:1
	v_add_u32_e32 v4, 0x30c0, v79
	ds_write2_b32 v4, v48, v49 offset1:1
	v_add_u32_e32 v4, 0x30c8, v79
	ds_write2_b32 v4, v50, v51 offset1:1
	v_add_u32_e32 v4, 0x34d0, v79
	ds_write2_b32 v4, v60, v61 offset1:1
	v_add_u32_e32 v4, 0x34d8, v79
	ds_write2_b32 v4, v62, v63 offset1:1
	v_add_u32_e32 v4, 0x38e0, v79
	ds_write2_b32 v4, v56, v57 offset1:1
	v_add_u32_e32 v4, 0x38e8, v79
	ds_write2_b32 v4, v58, v59 offset1:1
	v_add_u32_e32 v4, 0x3cf0, v79
	ds_write2_b32 v4, v64, v65 offset1:1
	v_add_u32_e32 v4, 0x3cf8, v79
	ds_write2_b32 v4, v66, v67 offset1:1
	s_waitcnt lgkmcnt(0)
	ds_read2_b32 v[12:13], v77 offset1:8
	ds_read2_b32 v[14:15], v77 offset0:65 offset1:73
	ds_read2_b32 v[16:17], v77 offset0:130 offset1:138
	ds_read2_b32 v[18:19], v77 offset0:195 offset1:203
	v_add_u32_e32 v30, 0x400, v77
	s_waitcnt lgkmcnt(3)
	s_nop 1
	s_waitcnt lgkmcnt(2)
	s_nop 0
	ds_read2_b32 v[20:21], v30 offset0:4 offset1:12
	s_nop 1
	ds_read2_b32 v[22:23], v30 offset0:69 offset1:77
	v_cvt_pk_bf16_f32 v8, v12, v14
	s_waitcnt lgkmcnt(3)
	s_nop 1
	s_waitcnt lgkmcnt(2)
	s_nop 0
	ds_read2_b32 v[24:25], v30 offset0:134 offset1:142
	s_nop 1
	ds_read2_b32 v[26:27], v30 offset0:199 offset1:207
	v_cvt_pk_bf16_f32 v9, v16, v18
	s_waitcnt lgkmcnt(3)
	s_nop 1
	s_waitcnt lgkmcnt(2)
	s_nop 2
	v_cvt_pk_bf16_f32 v10, v20, v22
	s_waitcnt lgkmcnt(1)
	s_nop 1
	s_waitcnt lgkmcnt(0)
	s_nop 2
	s_mul_i32 s20, s20, 0xfea00000
	s_ashr_i32 s1, s0, 31
	v_cvt_pk_bf16_f32 v11, v24, v26
	v_add_u32_e32 v6, s20, v78
	v_lshl_add_u64 v[4:5], s[0:1], 1, v[70:71]
	v_ashrrev_i32_e32 v7, 31, v6
	v_lshl_add_u64 v[28:29], v[4:5], 0, v[6:7]
	s_nop 0
	global_store_dwordx4 v[28:29], v[8:11], off
	s_nop 3
	v_cvt_pk_bf16_f32 v8, v13, v15
	s_nop 4
	v_cvt_pk_bf16_f32 v9, v17, v19
	s_nop 4
	v_cvt_pk_bf16_f32 v10, v21, v23
	s_nop 2
	v_add_u32_e32 v12, 0x16000, v6
	s_nop 1
	v_ashrrev_i32_e32 v13, 31, v12
	v_cvt_pk_bf16_f32 v11, v25, v27
	ds_read2_b32 v[14:15], v77 offset0:16 offset1:24
	v_lshl_add_u64 v[12:13], v[4:5], 0, v[12:13]
	global_store_dwordx4 v[12:13], v[8:11], off
	ds_read2_b32 v[12:13], v77 offset0:81 offset1:89
	ds_read2_b32 v[16:17], v77 offset0:146 offset1:154
	ds_read2_b32 v[18:19], v77 offset0:211 offset1:219
	s_waitcnt lgkmcnt(3)
; #define LAS __attribute__((address_space(3)))
; #define LDS_WAIT() asm volatile("s_waitcnt lgkmcnt(0)" ::: "memory")
; __device__ __forceinline__ unsigned pk2(float lo, float hi) { return f2bf(lo) | (f2bf(hi) << 16); }
;     ...
;         const int c8 = lane & 7; int d0 = n0;
;         if (ffnmap) { const int bj = n0 >= FFH ? 1 : 0, chn = n0 - FFH * bj; d0 = 256 * (chn >> 7) + 128 * bj + (chn & 127); }
; #pragma unroll
;         for (int j = 0; j < 8; ++j) { const int n = (lane >> 3) + 8 * j; const LAS float* sp = scr + (8 * c8) * 65 + n;
;             v4u o; o.x = pk2(sp[0 * 65], sp[1 * 65]); o.y = pk2(sp[2 * 65], sp[3 * 65]); o.z = pk2(sp[4 * 65], sp[5 * 65]); o.w = pk2(sp[6 * 65], sp[7 * 65]);
;             *(v4u*)(WT + (size_t)(d0 + n) * K + k0 + 8 * c8) = o; }
;         LDS_WAIT(); asm volatile("" ::: "memory");
	s_nop 1
	s_waitcnt lgkmcnt(2)
	s_nop 0
	ds_read2_b32 v[20:21], v30 offset0:20 offset1:28
	s_nop 1
	ds_read2_b32 v[22:23], v30 offset0:85 offset1:93
	v_cvt_pk_bf16_f32 v8, v14, v12
	s_waitcnt lgkmcnt(3)
	s_nop 1
	s_waitcnt lgkmcnt(2)
	s_nop 0
	ds_read2_b32 v[24:25], v30 offset0:150 offset1:158
	s_nop 1
	ds_read2_b32 v[26:27], v30 offset0:215 offset1:223
	v_cvt_pk_bf16_f32 v9, v16, v18
	s_waitcnt lgkmcnt(3)
	s_nop 1
	s_waitcnt lgkmcnt(2)
	s_nop 2
	v_cvt_pk_bf16_f32 v10, v20, v22
	s_waitcnt lgkmcnt(1)
	s_nop 1
	s_waitcnt lgkmcnt(0)
	s_nop 0
	v_add_u32_e32 v28, 0x2c000, v6
	s_nop 1
	v_ashrrev_i32_e32 v29, 31, v28
	v_cvt_pk_bf16_f32 v11, v24, v26
	v_lshl_add_u64 v[28:29], v[4:5], 0, v[28:29]
	s_nop 0
	global_store_dwordx4 v[28:29], v[8:11], off
	s_nop 3
	v_cvt_pk_bf16_f32 v8, v15, v13
	s_nop 4
	v_cvt_pk_bf16_f32 v9, v17, v19
	s_nop 4
	v_cvt_pk_bf16_f32 v10, v21, v23
	s_nop 2
	v_add_u32_e32 v12, 0x42000, v6
	s_nop 1
	v_ashrrev_i32_e32 v13, 31, v12
	v_cvt_pk_bf16_f32 v11, v25, v27
	ds_read2_b32 v[14:15], v77 offset0:32 offset1:40
	v_lshl_add_u64 v[12:13], v[4:5], 0, v[12:13]
	global_store_dwordx4 v[12:13], v[8:11], off
	ds_read2_b32 v[12:13], v77 offset0:97 offset1:105
	ds_read2_b32 v[16:17], v77 offset0:162 offset1:170
	ds_read2_b32 v[18:19], v77 offset0:227 offset1:235
	s_waitcnt lgkmcnt(3)
	s_nop 1
	s_waitcnt lgkmcnt(2)
	s_nop 0
	ds_read2_b32 v[20:21], v30 offset0:36 offset1:44
	s_nop 1
	ds_read2_b32 v[22:23], v30 offset0:101 offset1:109
	v_cvt_pk_bf16_f32 v8, v14, v12
	s_waitcnt lgkmcnt(3)
	s_nop 1
	s_waitcnt lgkmcnt(2)
	s_nop 0
	ds_read2_b32 v[24:25], v30 offset0:166 offset1:174
	s_nop 1
	ds_read2_b32 v[26:27], v30 offset0:231 offset1:239
	v_cvt_pk_bf16_f32 v9, v16, v18
	s_waitcnt lgkmcnt(3)
	s_nop 1
	s_waitcnt lgkmcnt(2)
	s_nop 2
	v_cvt_pk_bf16_f32 v10, v20, v22
	s_waitcnt lgkmcnt(1)
	s_nop 1
	s_waitcnt lgkmcnt(0)
	s_nop 0
	v_add_u32_e32 v28, 0x58000, v6
	s_nop 1
	v_ashrrev_i32_e32 v29, 31, v28
	v_cvt_pk_bf16_f32 v11, v24, v26
	v_lshl_add_u64 v[28:29], v[4:5], 0, v[28:29]
	s_nop 0
	global_store_dwordx4 v[28:29], v[8:11], off
	s_nop 3
	v_cvt_pk_bf16_f32 v8, v15, v13
	s_nop 4
	v_cvt_pk_bf16_f32 v9, v17, v19
	s_nop 4
	v_cvt_pk_bf16_f32 v10, v21, v23
	s_nop 2
	v_add_u32_e32 v12, 0x6e000, v6
	s_nop 1
	v_ashrrev_i32_e32 v13, 31, v12
	v_cvt_pk_bf16_f32 v11, v25, v27
	ds_read2_b32 v[14:15], v77 offset0:48 offset1:56
	v_lshl_add_u64 v[12:13], v[4:5], 0, v[12:13]
	global_store_dwordx4 v[12:13], v[8:11], off
	ds_read2_b32 v[12:13], v77 offset0:113 offset1:121
	ds_read2_b32 v[16:17], v77 offset0:178 offset1:186
	ds_read2_b32 v[18:19], v77 offset0:243 offset1:251
	s_waitcnt lgkmcnt(3)
	s_nop 1
	s_waitcnt lgkmcnt(2)
	s_nop 0
	ds_read2_b32 v[20:21], v30 offset0:52 offset1:60
	s_nop 1
	ds_read2_b32 v[22:23], v30 offset0:117 offset1:125
	v_cvt_pk_bf16_f32 v8, v14, v12
	s_waitcnt lgkmcnt(3)
	s_nop 1
	s_waitcnt lgkmcnt(2)
	s_nop 0
	ds_read2_b32 v[24:25], v30 offset0:182 offset1:190
	s_nop 1
	ds_read2_b32 v[26:27], v30 offset0:247 offset1:255
	v_cvt_pk_bf16_f32 v9, v16, v18
	s_waitcnt lgkmcnt(3)
	s_nop 1
	s_waitcnt lgkmcnt(2)
	s_nop 2
	v_cvt_pk_bf16_f32 v10, v20, v22
	s_waitcnt lgkmcnt(1)
	s_nop 1
	s_waitcnt lgkmcnt(0)
	s_nop 0
	v_add_u32_e32 v28, 0x84000, v6
	s_nop 1
	v_ashrrev_i32_e32 v29, 31, v28
	v_cvt_pk_bf16_f32 v11, v24, v26
	v_lshl_add_u64 v[28:29], v[4:5], 0, v[28:29]
	s_nop 0
	global_store_dwordx4 v[28:29], v[8:11], off
	s_nop 3
	v_cvt_pk_bf16_f32 v8, v15, v13
	s_nop 4
	v_cvt_pk_bf16_f32 v9, v17, v19
	s_nop 4
	v_cvt_pk_bf16_f32 v10, v21, v23
	s_nop 4
	v_add_u32_e32 v6, 0x9a000, v6
	v_cvt_pk_bf16_f32 v11, v25, v27
	v_ashrrev_i32_e32 v7, 31, v6
	v_lshl_add_u64 v[4:5], v[4:5], 0, v[6:7]
	global_store_dwordx4 v[4:5], v[8:11], off
	s_waitcnt lgkmcnt(0)
	s_add_i32 s16, s16, s17
	s_add_i32 s9, s9, s10
	s_cmpk_lt_i32 s16, 0xb00
	v_add_u32_e32 v78, s8, v78
	s_cbranch_scc0 .LBB0_4808

; __device__ __forceinline__ unsigned pk2(float lo, float hi) { return f2bf(lo) | (f2bf(hi) << 16); }
; template <int MODE, class MaskF> ...
;     ...
;     if constexpr (MODE == 0) { l[0] = OL[0][0] * 0.25f; l[1] = OL[1][0] * 0.25f; }
; __device__ __forceinline__ void xa_attn_fa(const Ctx& c, const bf16* Q, const bf16* KV, const bf16* XVT, bf16* Oo) {
;     ...
;         for (int mi = 0; mi < 2; ++mi) { float lt = l[mi]; lt += __shfl_xor(lt, 16); lt += __shfl_xor(lt, 32); const float il = 1.f / lt;
; #pragma unroll
;             for (int dt = 0; dt < 8; ++dt) { const f32x4 o = O[dt][mi] * il; v2u w; w.x = pk2(o[0], o[1]); w.y = pk2(o[2], o[3]);
;                 *(v2u*)(Oo + grow[mi] * 512 + hd * 128 + 16 * dt + 4 * lg) = w; } }
.LBB0_5374:
	v_mul_f32_e32 v2, 0x3e800000, v126
	ds_bpermute_b32 v2, v192, v2
	s_lshl_b32 s8, s21, 1
	v_lshl_add_u64 v[4:5], v[170:171], 0, s[8:9]
	v_lshl_add_u64 v[28:29], v[4:5], 0, v[186:187]
	v_mul_f32_e32 v50, 0x3e800000, v26
	s_waitcnt lgkmcnt(0)
	v_fmac_f32_e32 v2, 0x3e800000, v126
	ds_bpermute_b32 v27, v193, v2
	v_lshl_add_u64 v[4:5], v[4:5], 0, v[184:185]
	s_add_i32 s20, s20, s33
	s_cmpk_lt_i32 s20, 0x100
	s_waitcnt lgkmcnt(0)
	v_add_f32_e32 v2, v2, v27
	v_div_scale_f32 v27, s[10:11], v2, v2, 1.0
	v_rcp_f32_e32 v46, v27
	v_div_scale_f32 v47, vcc, 1.0, v2, 1.0
	v_fma_f32 v48, -v27, v46, 1.0
	v_fmac_f32_e32 v46, v48, v46
	v_mul_f32_e32 v48, v47, v46
	v_fma_f32 v49, -v27, v48, v47
	v_fmac_f32_e32 v48, v49, v46
	v_fma_f32 v27, -v27, v48, v47
	v_div_fmas_f32 v27, v27, v46, v48
	v_div_fixup_f32 v2, v27, v2, 1.0
	v_pk_mul_f32 v[48:49], v[118:119], v[2:3] op_sel_hi:[1,0]
	v_pk_mul_f32 v[46:47], v[120:121], v[2:3] op_sel_hi:[1,0]
	s_nop 4
	v_cvt_pk_bf16_f32 v48, v48, v49
	s_nop 4
	v_cvt_pk_bf16_f32 v49, v46, v47
	global_store_dwordx2 v[28:29], v[48:49], off
	v_pk_mul_f32 v[48:49], v[114:115], v[2:3] op_sel_hi:[1,0]
	v_pk_mul_f32 v[46:47], v[116:117], v[2:3] op_sel_hi:[1,0]
	s_nop 4
	v_cvt_pk_bf16_f32 v48, v48, v49
	s_nop 4
	v_cvt_pk_bf16_f32 v49, v46, v47
	global_store_dwordx2 v[28:29], v[48:49], off offset:32
	v_pk_mul_f32 v[48:49], v[110:111], v[2:3] op_sel_hi:[1,0]
	v_pk_mul_f32 v[46:47], v[112:113], v[2:3] op_sel_hi:[1,0]
	s_nop 4
	v_cvt_pk_bf16_f32 v48, v48, v49
	s_nop 4
	v_cvt_pk_bf16_f32 v49, v46, v47
	global_store_dwordx2 v[28:29], v[48:49], off offset:64
	v_pk_mul_f32 v[48:49], v[90:91], v[2:3] op_sel_hi:[1,0]
	v_pk_mul_f32 v[46:47], v[92:93], v[2:3] op_sel_hi:[1,0]
	s_nop 4
	v_cvt_pk_bf16_f32 v48, v48, v49
	s_nop 4
	v_cvt_pk_bf16_f32 v49, v46, v47
	global_store_dwordx2 v[28:29], v[48:49], off offset:96
	v_pk_mul_f32 v[48:49], v[86:87], v[2:3] op_sel_hi:[1,0]
	v_pk_mul_f32 v[46:47], v[88:89], v[2:3] op_sel_hi:[1,0]
	s_nop 4
	v_cvt_pk_bf16_f32 v48, v48, v49
	s_nop 4
	v_cvt_pk_bf16_f32 v49, v46, v47
	global_store_dwordx2 v[28:29], v[48:49], off offset:128
	v_pk_mul_f32 v[48:49], v[82:83], v[2:3] op_sel_hi:[1,0]
	v_pk_mul_f32 v[46:47], v[84:85], v[2:3] op_sel_hi:[1,0]
	s_nop 4
	v_cvt_pk_bf16_f32 v48, v48, v49
	s_nop 4
	v_cvt_pk_bf16_f32 v49, v46, v47
	global_store_dwordx2 v[28:29], v[48:49], off offset:160
	v_pk_mul_f32 v[48:49], v[62:63], v[2:3] op_sel_hi:[1,0]
	v_pk_mul_f32 v[46:47], v[64:65], v[2:3] op_sel_hi:[1,0]
	s_nop 4
	v_cvt_pk_bf16_f32 v48, v48, v49
	s_nop 4
	v_cvt_pk_bf16_f32 v49, v46, v47
	ds_bpermute_b32 v27, v192, v50
	v_pk_mul_f32 v[42:43], v[42:43], v[2:3] op_sel_hi:[1,0]
	v_pk_mul_f32 v[44:45], v[44:45], v[2:3] op_sel_hi:[1,0]
	s_nop 4
	s_waitcnt lgkmcnt(0)
	v_fmac_f32_e32 v27, 0x3e800000, v26
	v_cvt_pk_bf16_f32 v42, v42, v43
	ds_bpermute_b32 v2, v193, v27
	v_bfe_u32 v26, v44, 16, 1
	v_add3_u32 v26, v44, v26, s18
	v_bfe_u32 v43, v45, 16, 1
	v_lshrrev_b32_e32 v26, 16, v26
	s_waitcnt lgkmcnt(0)
	v_add_f32_e32 v2, v27, v2
	v_div_scale_f32 v27, s[10:11], v2, v2, 1.0
	v_rcp_f32_e32 v44, v27
	v_add3_u32 v43, v45, v43, s18
	v_and_or_b32 v43, v43, s19, v26
	global_store_dwordx2 v[28:29], v[48:49], off offset:192
	v_fma_f32 v26, -v27, v44, 1.0
	v_fmac_f32_e32 v44, v26, v44
	v_div_scale_f32 v26, vcc, 1.0, v2, 1.0
	global_store_dwordx2 v[28:29], v[42:43], off offset:224
	v_mul_f32_e32 v28, v26, v44
	v_fma_f32 v29, -v27, v28, v26
	v_fmac_f32_e32 v28, v29, v44
	v_fma_f32 v26, -v27, v28, v26
	v_div_fmas_f32 v26, v26, v44, v28
	v_div_fixup_f32 v2, v26, v2, 1.0
	v_pk_mul_f32 v[28:29], v[38:39], v[2:3] op_sel_hi:[1,0]
	v_pk_mul_f32 v[26:27], v[40:41], v[2:3] op_sel_hi:[1,0]
	s_nop 4
	v_cvt_pk_bf16_f32 v28, v28, v29
	s_nop 4
	v_cvt_pk_bf16_f32 v29, v26, v27
	global_store_dwordx2 v[4:5], v[28:29], off
	v_pk_mul_f32 v[28:29], v[34:35], v[2:3] op_sel_hi:[1,0]
	v_pk_mul_f32 v[26:27], v[36:37], v[2:3] op_sel_hi:[1,0]
	s_nop 4
	v_cvt_pk_bf16_f32 v28, v28, v29
	s_nop 4
	v_cvt_pk_bf16_f32 v29, v26, v27
	global_store_dwordx2 v[4:5], v[28:29], off offset:32
	v_pk_mul_f32 v[28:29], v[30:31], v[2:3] op_sel_hi:[1,0]
	v_pk_mul_f32 v[26:27], v[32:33], v[2:3] op_sel_hi:[1,0]
	s_nop 4
	v_cvt_pk_bf16_f32 v28, v28, v29
	s_nop 4
	v_pk_mul_f32 v[22:23], v[22:23], v[2:3] op_sel_hi:[1,0]
	v_cvt_pk_bf16_f32 v29, v26, v27
	s_nop 2
	v_pk_mul_f32 v[24:25], v[24:25], v[2:3] op_sel_hi:[1,0]
	s_nop 1
	v_cvt_pk_bf16_f32 v22, v22, v23
	s_nop 4
	v_cvt_pk_bf16_f32 v23, v24, v25
	v_pk_mul_f32 v[18:19], v[18:19], v[2:3] op_sel_hi:[1,0]
	global_store_dwordx2 v[4:5], v[22:23], off offset:96
	s_nop 2
	v_pk_mul_f32 v[20:21], v[20:21], v[2:3] op_sel_hi:[1,0]
	s_nop 1
	v_cvt_pk_bf16_f32 v18, v18, v19
	s_nop 4
	v_cvt_pk_bf16_f32 v19, v20, v21
	v_pk_mul_f32 v[14:15], v[14:15], v[2:3] op_sel_hi:[1,0]
	global_store_dwordx2 v[4:5], v[18:19], off offset:128
	s_nop 2
	v_pk_mul_f32 v[16:17], v[16:17], v[2:3] op_sel_hi:[1,0]
	s_nop 1
	v_cvt_pk_bf16_f32 v14, v14, v15
	s_nop 4
	v_cvt_pk_bf16_f32 v15, v16, v17
	v_pk_mul_f32 v[10:11], v[10:11], v[2:3] op_sel_hi:[1,0]
	v_pk_mul_f32 v[6:7], v[6:7], v[2:3] op_sel_hi:[1,0]
	global_store_dwordx2 v[4:5], v[14:15], off offset:160
	v_pk_mul_f32 v[12:13], v[12:13], v[2:3] op_sel_hi:[1,0]
	s_nop 0
	v_pk_mul_f32 v[8:9], v[8:9], v[2:3] op_sel_hi:[1,0]
	s_nop 7
	s_nop 0
	v_cvt_pk_bf16_f32 v10, v10, v11
	s_nop 0
	v_cvt_pk_bf16_f32 v6, v6, v7
	s_nop 7
	s_nop 0
	v_cvt_pk_bf16_f32 v11, v12, v13
	v_cvt_pk_bf16_f32 v7, v8, v9
	global_store_dwordx2 v[4:5], v[28:29], off offset:64
	global_store_dwordx2 v[4:5], v[10:11], off offset:192
	global_store_dwordx2 v[4:5], v[6:7], off offset:224
	s_cbranch_scc0 .LBB0_5386

; __device__ __forceinline__ void postnorm(const Ctx& c, const bf16* MF, bf16* XB, float* RS, const float* gpost, float* OUT) {
;     for (int row = c.gw; row < MT; row += c.NGW) {
;         const v4u* mr = (const v4u*)(MF + (size_t)row * DM) + c.lane; v4u* xr = (v4u*)(XB + (size_t)row * DM) + c.lane;
;         v4u mv[4], xv[4]; float v[4][8]; float s = 0.f;
; #pragma unroll
;         for (int j = 0; j < 4; ++j) { mv[j] = mr[64 * j]; xv[j] = xr[64 * j]; }
; #pragma unroll
;         for (int j = 0; j < 4; ++j)
; #pragma unroll
;             for (int k = 0; k < 4; ++k) { v[j][2 * k] = bflo(mv[j][k]); v[j][2 * k + 1] = bfhi(mv[j][k]); s += v[j][2 * k] * v[j][2 * k] + v[j][2 * k + 1] * v[j][2 * k + 1]; }
;         const float rs = rsqrtf(wave_sum(s) * (1.f / DM) + EPS);
.LBB0_5518:
	v_readlane_b32 s4, v253, 0
	v_readlane_b32 s5, v253, 1
	s_nop 1
	v_lshl_add_u64 v[32:33], s[4:5], 0, v[34:35]
	v_add_co_u32_e32 v58, vcc, 0xd400000, v32
	s_nop 1
	v_addc_co_u32_e32 v59, vcc, 0, v33, vcc
	s_waitcnt lgkmcnt(0)
	global_load_dwordx4 v[46:49], v[58:59], off
	global_load_dwordx4 v[50:53], v[58:59], off offset:1024
	global_load_dwordx4 v[54:57], v[58:59], off offset:2048
	s_nop 0
	global_load_dwordx4 v[58:61], v[58:59], off offset:3072
	v_add_co_u32_e32 v32, vcc, 0x9400000, v32
	s_waitcnt vmcnt(3)
	v_lshlrev_b32_e32 v79, 16, v47
	v_addc_co_u32_e32 v33, vcc, 0, v33, vcc
	global_load_dwordx4 v[62:65], v[32:33], off
	global_load_dwordx4 v[66:69], v[32:33], off offset:1024
	global_load_dwordx4 v[70:73], v[32:33], off offset:2048
	global_load_dwordx4 v[74:77], v[32:33], off offset:3072
	v_lshlrev_b32_e32 v78, 16, v46
	v_and_b32_e32 v47, 0xffff0000, v47
	v_and_b32_e32 v46, 0xffff0000, v46
	v_lshlrev_b32_e32 v81, 16, v49
	v_lshlrev_b32_e32 v80, 16, v48
	v_and_b32_e32 v49, 0xffff0000, v49
	v_and_b32_e32 v48, 0xffff0000, v48
	v_pk_mul_f32 v[94:95], v[46:47], v[46:47]
	v_pk_mul_f32 v[98:99], v[48:49], v[48:49]
	v_pk_fma_f32 v[94:95], v[78:79], v[78:79], v[94:95]
	s_waitcnt vmcnt(6)
	v_lshlrev_b32_e32 v83, 16, v51
	v_lshlrev_b32_e32 v82, 16, v50
	v_and_b32_e32 v51, 0xffff0000, v51
	v_and_b32_e32 v50, 0xffff0000, v50
	v_pk_fma_f32 v[98:99], v[80:81], v[80:81], v[98:99]
	v_add_f32_e32 v45, v94, v95
	v_pk_mul_f32 v[102:103], v[50:51], v[50:51]
	v_add_f32_e32 v45, v98, v45
	v_lshlrev_b32_e32 v85, 16, v53
	v_lshlrev_b32_e32 v84, 16, v52
	v_and_b32_e32 v53, 0xffff0000, v53
	v_and_b32_e32 v52, 0xffff0000, v52
	v_pk_fma_f32 v[102:103], v[82:83], v[82:83], v[102:103]
	v_add_f32_e32 v45, v99, v45
	v_pk_mul_f32 v[104:105], v[52:53], v[52:53]
	v_add_f32_e32 v45, v102, v45
	s_waitcnt vmcnt(5)
	v_lshlrev_b32_e32 v87, 16, v55
	v_lshlrev_b32_e32 v86, 16, v54
	v_and_b32_e32 v55, 0xffff0000, v55
	v_and_b32_e32 v54, 0xffff0000, v54
	v_pk_fma_f32 v[104:105], v[84:85], v[84:85], v[104:105]
	v_add_f32_e32 v45, v103, v45
	v_pk_mul_f32 v[106:107], v[54:55], v[54:55]
	v_add_f32_e32 v45, v104, v45
	v_lshlrev_b32_e32 v89, 16, v57
	v_lshlrev_b32_e32 v88, 16, v56
	v_and_b32_e32 v57, 0xffff0000, v57
	v_and_b32_e32 v56, 0xffff0000, v56
	v_pk_fma_f32 v[106:107], v[86:87], v[86:87], v[106:107]
	v_add_f32_e32 v45, v105, v45
	v_pk_mul_f32 v[108:109], v[56:57], v[56:57]
	v_add_f32_e32 v45, v106, v45
	s_waitcnt vmcnt(4)
	v_lshlrev_b32_e32 v91, 16, v59
	v_lshlrev_b32_e32 v90, 16, v58
	v_and_b32_e32 v59, 0xffff0000, v59
	v_and_b32_e32 v58, 0xffff0000, v58
	v_pk_fma_f32 v[108:109], v[88:89], v[88:89], v[108:109]
	v_add_f32_e32 v45, v107, v45
	v_pk_mul_f32 v[110:111], v[58:59], v[58:59]
	v_add_f32_e32 v45, v108, v45
	v_lshlrev_b32_e32 v93, 16, v61
	v_lshlrev_b32_e32 v92, 16, v60
	v_and_b32_e32 v61, 0xffff0000, v61
	v_and_b32_e32 v60, 0xffff0000, v60
	v_pk_fma_f32 v[110:111], v[90:91], v[90:91], v[110:111]
	v_add_f32_e32 v45, v109, v45
	v_pk_mul_f32 v[112:113], v[60:61], v[60:61]
	v_add_f32_e32 v45, v110, v45
	v_pk_fma_f32 v[112:113], v[92:93], v[92:93], v[112:113]
	v_add_f32_e32 v45, v111, v45
	v_add_f32_e32 v45, v112, v45
	v_add_f32_e32 v45, v113, v45
	ds_bpermute_b32 v94, v39, v45
	s_waitcnt lgkmcnt(0)
	v_add_f32_e32 v45, v45, v94
	ds_bpermute_b32 v98, v40, v45
	s_waitcnt lgkmcnt(0)
	v_add_f32_e32 v45, v45, v98
	ds_bpermute_b32 v102, v41, v45
	s_waitcnt vmcnt(3)
	v_lshlrev_b32_e32 v97, 16, v63
	v_lshlrev_b32_e32 v96, 16, v62
	v_and_b32_e32 v63, 0xffff0000, v63
	s_waitcnt lgkmcnt(0)
	v_add_f32_e32 v45, v45, v102
	ds_bpermute_b32 v104, v42, v45
	v_and_b32_e32 v62, 0xffff0000, v62
	v_lshlrev_b32_e32 v101, 16, v65
	v_lshlrev_b32_e32 v100, 16, v64
	v_and_b32_e32 v65, 0xffff0000, v65
	s_waitcnt lgkmcnt(0)
	v_add_f32_e32 v45, v45, v104
	ds_bpermute_b32 v106, v43, v45
	v_and_b32_e32 v64, 0xffff0000, v64
	s_waitcnt vmcnt(0)
	v_lshlrev_b32_e32 v109, 16, v77
	v_and_b32_e32 v77, 0xffff0000, v77
	v_lshlrev_b32_e32 v95, 16, v67
	s_waitcnt lgkmcnt(0)
	v_add_f32_e32 v45, v45, v106
	ds_bpermute_b32 v108, v44, v45
	v_lshlrev_b32_e32 v94, 16, v66
	v_and_b32_e32 v67, 0xffff0000, v67
	v_and_b32_e32 v66, 0xffff0000, v66
	v_lshlrev_b32_e32 v99, 16, v69
	s_waitcnt lgkmcnt(0)
; __device__ __forceinline__ unsigned pk2(float lo, float hi) { return f2bf(lo) | (f2bf(hi) << 16); }
; __device__ __forceinline__ void postnorm(const Ctx& c, const bf16* MF, bf16* XB, float* RS, const float* gpost, float* OUT) {
;     ...
;         const float rs = rsqrtf(wave_sum(s) * (1.f / DM) + EPS);
;         float s2 = 0.f;
; #pragma unroll
;         for (int j = 0; j < 4; ++j) { const float* gp = gpost + (c.lane + 64 * j) * 8; const f32x4 g0 = *(CF4)gp, g1 = *(CF4)(gp + 4);
; #pragma unroll
;             for (int k = 0; k < 4; ++k) { const float ga = (k < 2) ? g0[2 * k] : g1[2 * k - 4], gb = (k < 2) ? g0[2 * k + 1] : g1[2 * k - 3];
;                 v[j][2 * k] = bflo(xv[j][k]) + v[j][2 * k] * rs * ga; v[j][2 * k + 1] = bfhi(xv[j][k]) + v[j][2 * k + 1] * rs * gb;
;                 s2 += v[j][2 * k] * v[j][2 * k] + v[j][2 * k + 1] * v[j][2 * k + 1]; } }
;         if (OUT) {
; #pragma unroll
;             for (int j = 0; j < 4; ++j) { float* op = OUT + (size_t)row * DM + (c.lane + 64 * j) * 8; *(f32x4*)op = (f32x4){v[j][0], v[j][1], v[j][2], v[j][3]}; *(f32x4*)(op + 4) = (f32x4){v[j][4], v[j][5], v[j][6], v[j][7]}; }
;         } else {
; #pragma unroll
;             for (int j = 0; j < 4; ++j) { v4u o; o.x = pk2(v[j][0], v[j][1]); o.y = pk2(v[j][2], v[j][3]); o.z = pk2(v[j][4], v[j][5]); o.w = pk2(v[j][6], v[j][7]); xr[64 * j] = o; }
;             const float rs2 = rsqrtf(wave_sum(s2) * (1.f / DM) + EPS); if (c.lane == 0) RS[row] = rs2;
	v_add_f32_e32 v45, v45, v108
	v_fmamk_f32 v45, v45, 0x3a000000, v38
	v_mul_f32_e32 v108, 0x4b800000, v45
	v_cmp_gt_f32_e32 vcc, s15, v45
	v_lshlrev_b32_e32 v98, 16, v68
	v_and_b32_e32 v69, 0xffff0000, v69
	v_cndmask_b32_e32 v45, v45, v108, vcc
	v_rsq_f32_e32 v45, v45
	v_lshlrev_b32_e32 v108, 16, v76
	v_and_b32_e32 v76, 0xffff0000, v76
	v_and_b32_e32 v68, 0xffff0000, v68
	v_mul_f32_e32 v110, 0x45800000, v45
	v_cndmask_b32_e32 v110, v45, v110, vcc
	v_pk_mul_f32 v[46:47], v[110:111], v[46:47] op_sel_hi:[0,1]
	v_pk_mul_f32 v[78:79], v[110:111], v[78:79] op_sel_hi:[0,1]
	v_pk_mul_f32 v[48:49], v[110:111], v[48:49] op_sel_hi:[0,1]
	v_pk_fma_f32 v[46:47], v[36:37], v[46:47], v[62:63]
	v_pk_mul_f32 v[60:61], v[110:111], v[60:61] op_sel_hi:[0,1]
	v_pk_mul_f32 v[80:81], v[110:111], v[80:81] op_sel_hi:[0,1]
	v_pk_fma_f32 v[78:79], v[2:3], v[78:79], v[96:97]
	v_pk_fma_f32 v[48:49], v[4:5], v[48:49], v[64:65]
	v_pk_fma_f32 v[60:61], v[28:29], v[60:61], v[76:77]
	v_pk_mul_f32 v[76:77], v[46:47], v[46:47]
	v_pk_fma_f32 v[62:63], v[6:7], v[80:81], v[100:101]
	v_pk_fma_f32 v[76:77], v[78:79], v[78:79], v[76:77]
	v_pk_mul_f32 v[80:81], v[48:49], v[48:49]
	v_add_f32_e32 v45, v76, v77
	v_pk_fma_f32 v[80:81], v[62:63], v[62:63], v[80:81]
	v_pk_mul_f32 v[50:51], v[110:111], v[50:51] op_sel_hi:[0,1]
	v_add_f32_e32 v45, v80, v45
	v_pk_mul_f32 v[82:83], v[110:111], v[82:83] op_sel_hi:[0,1]
	v_pk_fma_f32 v[50:51], v[8:9], v[50:51], v[66:67]
	v_add_f32_e32 v45, v81, v45
	s_nop 3
	v_pk_mul_f32 v[52:53], v[110:111], v[52:53] op_sel_hi:[0,1]
	v_pk_fma_f32 v[64:65], v[10:11], v[82:83], v[94:95]
	v_pk_mul_f32 v[82:83], v[50:51], v[50:51]
	s_nop 7
	v_pk_mul_f32 v[84:85], v[110:111], v[84:85] op_sel_hi:[0,1]
	v_pk_fma_f32 v[52:53], v[12:13], v[52:53], v[68:69]
	v_pk_fma_f32 v[82:83], v[64:65], v[64:65], v[82:83]
	s_nop 3
	v_lshlrev_b32_e32 v103, 16, v71
	v_lshlrev_b32_e32 v102, 16, v70
	v_and_b32_e32 v71, 0xffff0000, v71
	v_and_b32_e32 v70, 0xffff0000, v70
	v_pk_fma_f32 v[66:67], v[14:15], v[84:85], v[98:99]
	v_pk_mul_f32 v[54:55], v[110:111], v[54:55] op_sel_hi:[0,1]
	v_pk_mul_f32 v[84:85], v[52:53], v[52:53]
	v_add_f32_e32 v45, v82, v45
	s_nop 3
	v_pk_mul_f32 v[68:69], v[110:111], v[86:87] op_sel_hi:[0,1]
	v_pk_fma_f32 v[54:55], v[16:17], v[54:55], v[70:71]
	v_pk_fma_f32 v[84:85], v[66:67], v[66:67], v[84:85]
	v_add_f32_e32 v45, v83, v45
	v_cvt_pk_bf16_f32 v49, v63, v49
	v_cvt_pk_bf16_f32 v48, v62, v48
	v_cvt_pk_bf16_f32 v47, v79, v47
	v_cvt_pk_bf16_f32 v46, v78, v46
	v_lshlrev_b32_e32 v105, 16, v73
	v_lshlrev_b32_e32 v104, 16, v72
	v_and_b32_e32 v73, 0xffff0000, v73
	v_and_b32_e32 v72, 0xffff0000, v72
	v_pk_fma_f32 v[68:69], v[18:19], v[68:69], v[102:103]
	v_pk_mul_f32 v[56:57], v[110:111], v[56:57] op_sel_hi:[0,1]
	v_pk_mul_f32 v[86:87], v[54:55], v[54:55]
	v_add_f32_e32 v45, v84, v45
	global_store_dwordx4 v[32:33], v[46:49], off
	v_pk_mul_f32 v[70:71], v[110:111], v[88:89] op_sel_hi:[0,1]
	v_pk_fma_f32 v[56:57], v[20:21], v[56:57], v[72:73]
	s_nop 3
	v_pk_fma_f32 v[86:87], v[68:69], v[68:69], v[86:87]
	v_add_f32_e32 v45, v85, v45
	s_nop 7
	v_lshlrev_b32_e32 v107, 16, v75
	v_lshlrev_b32_e32 v106, 16, v74
	v_and_b32_e32 v75, 0xffff0000, v75
	v_and_b32_e32 v74, 0xffff0000, v74
	v_pk_fma_f32 v[70:71], v[22:23], v[70:71], v[104:105]
	v_pk_mul_f32 v[58:59], v[110:111], v[58:59] op_sel_hi:[0,1]
	v_pk_mul_f32 v[88:89], v[56:57], v[56:57]
	v_add_f32_e32 v45, v86, v45
	s_nop 3
	v_pk_mul_f32 v[72:73], v[110:111], v[90:91] op_sel_hi:[0,1]
	v_pk_fma_f32 v[58:59], v[24:25], v[58:59], v[74:75]
	v_pk_fma_f32 v[88:89], v[70:71], v[70:71], v[88:89]
	v_add_f32_e32 v45, v87, v45
	s_nop 3
	v_pk_fma_f32 v[72:73], v[26:27], v[72:73], v[106:107]
	v_pk_mul_f32 v[90:91], v[58:59], v[58:59]
	v_add_f32_e32 v45, v88, v45
	v_cvt_pk_bf16_f32 v49, v67, v53
	v_cvt_pk_bf16_f32 v48, v66, v52
	v_cvt_pk_bf16_f32 v47, v65, v51
	v_cvt_pk_bf16_f32 v46, v64, v50
	v_pk_mul_f32 v[74:75], v[110:111], v[92:93] op_sel_hi:[0,1]
	v_pk_fma_f32 v[90:91], v[72:73], v[72:73], v[90:91]
	v_add_f32_e32 v45, v89, v45
	global_store_dwordx4 v[32:33], v[46:49], off offset:1024
	v_pk_fma_f32 v[74:75], v[30:31], v[74:75], v[108:109]
	v_pk_mul_f32 v[92:93], v[60:61], v[60:61]
	s_nop 1
	v_add_f32_e32 v45, v90, v45
	s_nop 5
	v_pk_fma_f32 v[92:93], v[74:75], v[74:75], v[92:93]
	v_add_f32_e32 v45, v91, v45
	s_nop 5
	v_add_f32_e32 v45, v92, v45
	s_nop 5
	v_add_f32_e32 v45, v93, v45
	v_cvt_pk_bf16_f32 v49, v71, v57
	v_cvt_pk_bf16_f32 v48, v70, v56
	v_cvt_pk_bf16_f32 v47, v69, v55
	v_cvt_pk_bf16_f32 v46, v68, v54
	global_store_dwordx4 v[32:33], v[46:49], off offset:2048
	ds_bpermute_b32 v47, v39, v45
	s_nop 3
	s_waitcnt lgkmcnt(0)
	v_add_f32_e32 v45, v45, v47
	ds_bpermute_b32 v47, v40, v45
	s_nop 3
	s_waitcnt lgkmcnt(0)
	v_add_f32_e32 v45, v45, v47
	ds_bpermute_b32 v47, v41, v45
	s_nop 0
	v_cvt_pk_bf16_f32 v51, v75, v61
	s_nop 1
	s_waitcnt lgkmcnt(0)
	v_add_f32_e32 v45, v45, v47
	ds_bpermute_b32 v47, v42, v45
	s_nop 3
	s_waitcnt lgkmcnt(0)
	v_add_f32_e32 v45, v45, v47
	ds_bpermute_b32 v47, v43, v45
	s_nop 3
	s_waitcnt lgkmcnt(0)
	v_add_f32_e32 v45, v45, v47
	ds_bpermute_b32 v46, v44, v45
	s_nop 0
	v_cvt_pk_bf16_f32 v50, v74, v60
	v_cvt_pk_bf16_f32 v49, v73, v59
	v_cvt_pk_bf16_f32 v48, v72, v58
	global_store_dwordx4 v[32:33], v[48:51], off offset:3072
	s_and_saveexec_b64 s[10:11], s[0:1]
	s_cbranch_execz .LBB0_5517
	s_waitcnt lgkmcnt(0)
	v_add_f32_e32 v32, v45, v46
	v_fmamk_f32 v32, v32, 0x3a000000, v38
	v_mul_f32_e32 v33, 0x4b800000, v32
	v_cmp_gt_f32_e32 vcc, s15, v32
	v_readlane_b32 s4, v253, 0
	v_readlane_b32 s5, v253, 1
	v_cndmask_b32_e32 v32, v32, v33, vcc
	v_rsq_f32_e32 v32, v32
	s_add_u32 s18, s4, s13
	s_addc_u32 s19, s5, s14
	v_mul_f32_e32 v33, 0x45800000, v32
	v_cndmask_b32_e32 v32, v32, v33, vcc
	global_store_dword v251, v32, s[18:19]
	s_branch .LBB0_5517

; #define PG8_STAGE(bufoff, gbase, voff) do { _Pragma("unroll") for (int _i = 0; _i < 2; ++_i) \
;         __builtin_amdgcn_global_load_lds((const unsigned*)((const char*)(gbase) + (voff)[_i]), (LAS unsigned*)(lds + (bufoff) + ldsw + _i * 8192), 16, 0, 0); } while (0)
; #define PG8_LDA(dst, b, h) do { _Pragma("unroll") for (int m = 0; m < 4; ++m) _Pragma("unroll") for (int k = 0; k < 2; ++k) dst[m][k] = *(const LAS bf16x8*)(lds + PG8_SA(b, h) + aoff + m * 2048 + k * 1024); } while (0)
; #define PG8_LDB(dst, b, h) do { _Pragma("unroll") for (int n = 0; n < 2; ++n) _Pragma("unroll") for (int k = 0; k < 2; ++k) dst[n][k] = *(const LAS bf16x8*)(lds + PG8_SB(b, h) + boff + n * 2048 + k * 1024); } while (0)
; #define PG8_MMA(ai, bj, At, Bt) do { __builtin_amdgcn_s_setprio(1); _Pragma("unroll") for (int m = 0; m < 4; ++m) _Pragma("unroll") for (int n = 0; n < 2; ++n) _Pragma("unroll") for (int k = 0; k < 2; ++k) \
;         acc[ai][bj][m][n] = __builtin_amdgcn_mfma_f32_16x16x32_bf16(Bt[n][k], At[m][k], acc[ai][bj][m][n], 0, 0, 0); __builtin_amdgcn_s_setprio(0); } while (0)
; #define PG8_WAIT_V(n) asm volatile("s_waitcnt vmcnt(" #n ")" ::: "memory")
; #define PG8_WAIT_L(n) asm volatile("s_waitcnt lgkmcnt(" #n ")" ::: "memory")
; #define PG8_BAR __builtin_amdgcn_s_barrier()
; #define PG8_SCHED __builtin_amdgcn_sched_barrier(0)
; template <class PT, class Epi>
; __device__ __forceinline__ void gemm_phase_once(LAS unsigned char* lds, const PT& S, const Epi& E, bool epi_on) {
;     ...
;             PG8_LDB(B0, 0, 0); PG8_SCHED; PG8_LDA(At, 0, 0); PG8_STAGE(PG8_SA(1, 1), a1 + hstepA, voffA);
;             PG8_WAIT_L(8); PG8_BAR; PG8_WAIT_L(0); PG8_MMA(0, 0, At, B0); PG8_BAR; PG8_SCHED;
;             PG8_LDB(B1, 0, 1); PG8_STAGE(PG8_SB(0, 0), b2, voffB);
;             PG8_BAR; PG8_WAIT_L(0); PG8_MMA(0, 1, At, B1); PG8_BAR;
;             PG8_LDA(At, 0, 1); PG8_STAGE(PG8_SA(0, 0), a2, voffA);
;             PG8_BAR; PG8_WAIT_L(0); PG8_MMA(1, 0, At, B0); PG8_BAR; PG8_SCHED;
;             PG8_STAGE(PG8_SB(0, 1), b2 + hstepB, voffB);
;             PG8_WAIT_V(6); PG8_BAR; PG8_MMA(1, 1, At, B1); PG8_BAR;
;             PG8_LDB(B0, 1, 0); PG8_SCHED; PG8_LDA(At, 1, 0); PG8_STAGE(PG8_SA(0, 1), a2 + hstepA, voffA);
;             PG8_WAIT_L(8); PG8_BAR; PG8_WAIT_L(0); PG8_MMA(0, 0, At, B0); PG8_BAR; PG8_SCHED;
.LBB0_5583:
	ds_read_b128 v[58:61], v231
	ds_read_b128 v[70:73], v231 offset:1024
	ds_read_b128 v[156:159], v231 offset:2048
	ds_read_b128 v[160:163], v231 offset:3072
	s_add_u32 s38, s36, 0x100
	s_addc_u32 s39, s37, 0
	s_cmp_eq_u32 s65, 28
	s_cselect_b32 s43, s27, s39
	s_cselect_b32 s42, s35, s38
	s_cselect_b32 s41, s25, s64
	s_cselect_b32 s40, s62, s63
	v_lshl_add_u64 v[200:201], s[36:37], 0, v[148:149]
	s_add_i32 m0, s49, 0xc000
	ds_read_b128 v[168:171], v232
	ds_read_b128 v[172:175], v232 offset:1024
	ds_read_b128 v[176:179], v232 offset:2048
	ds_read_b128 v[180:183], v232 offset:3072
	ds_read_b128 v[184:187], v232 offset:4096
	ds_read_b128 v[188:191], v232 offset:5120
	ds_read_b128 v[192:195], v232 offset:6144
	ds_read_b128 v[196:199], v232 offset:7168
	global_load_lds_dwordx4 v[200:201], off
	v_lshl_add_u64 v[200:201], s[36:37], 0, v[150:151]
	s_add_i32 m0, s49, 0xe000
	s_nop 0
	global_load_lds_dwordx4 v[200:201], off
	s_waitcnt lgkmcnt(8)
	s_barrier
	s_waitcnt lgkmcnt(0)
	s_setprio 1
	s_waitcnt lgkmcnt(0)
	v_mfma_f32_16x16x32_bf16 v[134:137], v[58:61], v[168:171], v[134:137]
	v_mfma_f32_16x16x32_bf16 v[66:69], v[156:159], v[168:171], v[66:69]
	v_mfma_f32_16x16x32_bf16 v[126:129], v[58:61], v[176:179], v[126:129]
	v_mfma_f32_16x16x32_bf16 v[62:65], v[156:159], v[176:179], v[62:65]
	v_mfma_f32_16x16x32_bf16 v[102:105], v[58:61], v[184:187], v[102:105]
	v_mfma_f32_16x16x32_bf16 v[30:33], v[156:159], v[184:187], v[30:33]
	v_mfma_f32_16x16x32_bf16 v[98:101], v[58:61], v[192:195], v[98:101]
	v_mfma_f32_16x16x32_bf16 v[22:25], v[156:159], v[192:195], v[22:25]
	v_mfma_f32_16x16x32_bf16 v[134:137], v[70:73], v[172:175], v[134:137]
	v_mfma_f32_16x16x32_bf16 v[66:69], v[160:163], v[172:175], v[66:69]
	v_mfma_f32_16x16x32_bf16 v[126:129], v[70:73], v[180:183], v[126:129]
	v_mfma_f32_16x16x32_bf16 v[62:65], v[160:163], v[180:183], v[62:65]
	v_mfma_f32_16x16x32_bf16 v[102:105], v[70:73], v[188:191], v[102:105]
	v_mfma_f32_16x16x32_bf16 v[30:33], v[160:163], v[188:191], v[30:33]
	v_mfma_f32_16x16x32_bf16 v[98:101], v[70:73], v[196:199], v[98:101]
	v_mfma_f32_16x16x32_bf16 v[22:25], v[160:163], v[196:199], v[22:25]
	s_setprio 0
	s_barrier
	s_add_i32 s36, s57, s46
	v_lshl_add_u64 v[216:217], s[40:41], 0, v[144:145]
	s_mov_b32 m0, s36
	ds_read_b128 v[200:203], v233
	ds_read_b128 v[204:207], v233 offset:1024
	ds_read_b128 v[208:211], v233 offset:2048
	ds_read_b128 v[212:215], v233 offset:3072
	global_load_lds_dwordx4 v[216:217], off
	v_lshl_add_u64 v[218:219], s[40:41], 0, v[138:139]
	s_add_i32 m0, s36, 0x2000
	s_nop 0
	global_load_lds_dwordx4 v[218:219], off
	s_barrier
	s_waitcnt lgkmcnt(0)
	s_setprio 1
	s_waitcnt lgkmcnt(0)
	v_mfma_f32_16x16x32_bf16 v[122:125], v[200:203], v[168:171], v[122:125]
	v_mfma_f32_16x16x32_bf16 v[54:57], v[208:211], v[168:171], v[54:57]
	v_mfma_f32_16x16x32_bf16 v[114:117], v[200:203], v[176:179], v[114:117]
	v_mfma_f32_16x16x32_bf16 v[50:53], v[208:211], v[176:179], v[50:53]
	v_mfma_f32_16x16x32_bf16 v[94:97], v[200:203], v[184:187], v[94:97]
	v_mfma_f32_16x16x32_bf16 v[26:29], v[208:211], v[184:187], v[26:29]
	v_mfma_f32_16x16x32_bf16 v[90:93], v[200:203], v[192:195], v[90:93]
	v_mfma_f32_16x16x32_bf16 v[18:21], v[208:211], v[192:195], v[18:21]
	v_mfma_f32_16x16x32_bf16 v[122:125], v[204:207], v[172:175], v[122:125]
	v_mfma_f32_16x16x32_bf16 v[54:57], v[212:215], v[172:175], v[54:57]
	v_mfma_f32_16x16x32_bf16 v[114:117], v[204:207], v[180:183], v[114:117]
	v_mfma_f32_16x16x32_bf16 v[50:53], v[212:215], v[180:183], v[50:53]
	v_mfma_f32_16x16x32_bf16 v[94:97], v[204:207], v[188:191], v[94:97]
	v_mfma_f32_16x16x32_bf16 v[26:29], v[212:215], v[188:191], v[26:29]
	v_mfma_f32_16x16x32_bf16 v[90:93], v[204:207], v[196:199], v[90:93]
	v_mfma_f32_16x16x32_bf16 v[18:21], v[212:215], v[196:199], v[18:21]
	s_setprio 0
	s_mov_b32 m0, s49
	v_lshl_add_u64 v[220:221], s[42:43], 0, v[140:141]
	s_barrier
	ds_read_b128 v[168:171], v232 offset:16384
	ds_read_b128 v[172:175], v232 offset:17408
	ds_read_b128 v[176:179], v232 offset:18432
	ds_read_b128 v[180:183], v232 offset:19456
	ds_read_b128 v[184:187], v232 offset:20480
	ds_read_b128 v[188:191], v232 offset:21504
	ds_read_b128 v[192:195], v232 offset:22528
	ds_read_b128 v[196:199], v232 offset:23552
	global_load_lds_dwordx4 v[220:221], off
	v_lshl_add_u64 v[222:223], s[42:43], 0, v[142:143]
	s_mov_b32 m0, s50
	s_nop 0
	global_load_lds_dwordx4 v[222:223], off
	s_barrier
	s_waitcnt lgkmcnt(0)
	s_setprio 1
	s_waitcnt lgkmcnt(0)
	v_mfma_f32_16x16x32_bf16 v[86:89], v[58:61], v[168:171], v[86:89]
	v_mfma_f32_16x16x32_bf16 v[14:17], v[156:159], v[168:171], v[14:17]
	v_mfma_f32_16x16x32_bf16 v[82:85], v[58:61], v[176:179], v[82:85]
	v_mfma_f32_16x16x32_bf16 v[6:9], v[156:159], v[176:179], v[6:9]
	v_mfma_f32_16x16x32_bf16 v[130:133], v[58:61], v[184:187], v[130:133]
	v_mfma_f32_16x16x32_bf16 v[46:49], v[156:159], v[184:187], v[46:49]
	v_mfma_f32_16x16x32_bf16 v[42:45], v[156:159], v[192:195], v[42:45]
	v_mfma_f32_16x16x32_bf16 v[86:89], v[70:73], v[172:175], v[86:89]
	v_mfma_f32_16x16x32_bf16 v[14:17], v[160:163], v[172:175], v[14:17]
	v_mfma_f32_16x16x32_bf16 v[82:85], v[70:73], v[180:183], v[82:85]
	v_mfma_f32_16x16x32_bf16 v[6:9], v[160:163], v[180:183], v[6:9]
	v_mfma_f32_16x16x32_bf16 v[130:133], v[70:73], v[188:191], v[130:133]
	v_mfma_f32_16x16x32_bf16 v[46:49], v[160:163], v[188:191], v[46:49]
	v_mfma_f32_16x16x32_bf16 v[58:61], v[58:61], v[192:195], v[110:113]
	v_mfma_f32_16x16x32_bf16 v[42:45], v[160:163], v[196:199], v[42:45]
	v_mfma_f32_16x16x32_bf16 v[58:61], v[70:73], v[196:199], v[58:61]
	s_setprio 0
	s_barrier
; #define PG8_STAGE(bufoff, gbase, voff) do { _Pragma("unroll") for (int _i = 0; _i < 2; ++_i) \
;         __builtin_amdgcn_global_load_lds((const unsigned*)((const char*)(gbase) + (voff)[_i]), (LAS unsigned*)(lds + (bufoff) + ldsw + _i * 8192), 16, 0, 0); } while (0)
; #define PG8_LDA(dst, b, h) do { _Pragma("unroll") for (int m = 0; m < 4; ++m) _Pragma("unroll") for (int k = 0; k < 2; ++k) dst[m][k] = *(const LAS bf16x8*)(lds + PG8_SA(b, h) + aoff + m * 2048 + k * 1024); } while (0)
; #define PG8_LDB(dst, b, h) do { _Pragma("unroll") for (int n = 0; n < 2; ++n) _Pragma("unroll") for (int k = 0; k < 2; ++k) dst[n][k] = *(const LAS bf16x8*)(lds + PG8_SB(b, h) + boff + n * 2048 + k * 1024); } while (0)
; #define PG8_WAIT_V(n) asm volatile("s_waitcnt vmcnt(" #n ")" ::: "memory")
; #define PG8_WAIT_L(n) asm volatile("s_waitcnt lgkmcnt(" #n ")" ::: "memory")
; #define PG8_BAR __builtin_amdgcn_s_barrier()
; #define PG8_SCHED __builtin_amdgcn_sched_barrier(0)
; template <class PT, class Epi>
; __device__ __forceinline__ void gemm_phase_once(LAS unsigned char* lds, const PT& S, const Epi& E, bool epi_on) {
;     ...
;             PG8_LDB(B0, 0, 0); PG8_SCHED; PG8_LDA(At, 0, 0); PG8_STAGE(PG8_SA(1, 1), a1 + hstepA, voffA);
;             PG8_WAIT_L(8); PG8_BAR; PG8_WAIT_L(0); PG8_MMA(0, 0, At, B0); PG8_BAR; PG8_SCHED;
;             PG8_LDB(B1, 0, 1); PG8_STAGE(PG8_SB(0, 0), b2, voffB);
;             PG8_BAR; PG8_WAIT_L(0); PG8_MMA(0, 1, At, B1); PG8_BAR;
;             PG8_LDA(At, 0, 1); PG8_STAGE(PG8_SA(0, 0), a2, voffA);
;             PG8_BAR; PG8_WAIT_L(0); PG8_MMA(1, 0, At, B0); PG8_BAR; PG8_SCHED;
;             PG8_STAGE(PG8_SB(0, 1), b2 + hstepB, voffB);
;             PG8_WAIT_V(6); PG8_BAR; PG8_MMA(1, 1, At, B1); PG8_BAR;
;             PG8_LDB(B0, 1, 0); PG8_SCHED; PG8_LDA(At, 1, 0); PG8_STAGE(PG8_SA(0, 1), a2 + hstepA, voffA);
;             PG8_WAIT_L(8); PG8_BAR; PG8_WAIT_L(0); PG8_MMA(0, 0, At, B0); PG8_BAR; PG8_SCHED;
;             PG8_LDB(B1, 1, 1); PG8_STAGE(PG8_SB(1, 0), b3, voffB);
;             PG8_BAR; PG8_WAIT_L(0); PG8_MMA(0, 1, At, B1); PG8_BAR;
;             PG8_LDA(At, 1, 1); PG8_STAGE(PG8_SA(1, 0), a3, voffA);
;             PG8_BAR; PG8_WAIT_L(0); PG8_MMA(1, 0, At, B0); PG8_BAR; PG8_SCHED;
;             PG8_STAGE(PG8_SB(1, 1), b3 + hstepB, voffB);
;             PG8_WAIT_V(6); PG8_BAR; PG8_MMA(1, 1, At, B1); PG8_BAR;
	s_add_u32 s36, s40, 0x80000
	s_addc_u32 s37, s41, 0
	s_add_i32 s66, s58, s46
	v_lshl_add_u64 v[70:71], s[36:37], 0, v[144:145]
	s_mov_b32 m0, s66
	s_nop 0
	global_load_lds_dwordx4 v[70:71], off
	v_lshl_add_u64 v[70:71], s[36:37], 0, v[138:139]
	s_add_i32 m0, s66, 0x2000
	s_nop 0
	global_load_lds_dwordx4 v[70:71], off
	s_waitcnt vmcnt(6)
	s_barrier
	s_setprio 1
	v_mfma_f32_16x16x32_bf16 v[70:73], v[200:203], v[168:171], v[78:81]
	v_mfma_f32_16x16x32_bf16 v[78:81], v[200:203], v[184:187], v[118:121]
	v_mfma_f32_16x16x32_bf16 v[10:13], v[208:211], v[168:171], v[10:13]
	v_mfma_f32_16x16x32_bf16 v[74:77], v[200:203], v[176:179], v[74:77]
	v_mfma_f32_16x16x32_bf16 v[2:5], v[208:211], v[176:179], v[2:5]
	v_mfma_f32_16x16x32_bf16 v[118:121], v[204:207], v[188:191], v[78:81]
	v_mfma_f32_16x16x32_bf16 v[38:41], v[208:211], v[184:187], v[38:41]
	v_mfma_f32_16x16x32_bf16 v[78:81], v[200:203], v[192:195], v[106:109]
	v_mfma_f32_16x16x32_bf16 v[34:37], v[208:211], v[192:195], v[34:37]
	v_mfma_f32_16x16x32_bf16 v[10:13], v[212:215], v[172:175], v[10:13]
	v_mfma_f32_16x16x32_bf16 v[74:77], v[204:207], v[180:183], v[74:77]
	v_mfma_f32_16x16x32_bf16 v[2:5], v[212:215], v[180:183], v[2:5]
	v_mfma_f32_16x16x32_bf16 v[38:41], v[212:215], v[188:191], v[38:41]
	v_mfma_f32_16x16x32_bf16 v[106:109], v[204:207], v[196:199], v[78:81]
	v_mfma_f32_16x16x32_bf16 v[34:37], v[212:215], v[196:199], v[34:37]
	v_mfma_f32_16x16x32_bf16 v[70:73], v[204:207], v[172:175], v[70:73]
	s_setprio 0
	s_add_i32 s66, 0, 0x18000
	v_add_u32_e32 v160, s66, v228
	s_barrier
	ds_read_b128 v[78:81], v160
	ds_read_b128 v[110:113], v160 offset:1024
	ds_read_b128 v[156:159], v160 offset:2048
	ds_read_b128 v[160:163], v160 offset:3072
	s_add_u32 s36, s42, 0x4000
	s_addc_u32 s37, s43, 0
	s_mov_b32 m0, s51
	v_lshl_add_u64 v[200:201], s[36:37], 0, v[140:141]
	ds_read_b128 v[168:171], v232 offset:32768
	ds_read_b128 v[172:175], v232 offset:33792
	ds_read_b128 v[176:179], v232 offset:34816
	ds_read_b128 v[180:183], v232 offset:35840
	ds_read_b128 v[184:187], v232 offset:36864
	ds_read_b128 v[188:191], v232 offset:37888
	ds_read_b128 v[192:195], v232 offset:38912
	ds_read_b128 v[196:199], v232 offset:39936
	global_load_lds_dwordx4 v[200:201], off
	v_lshl_add_u64 v[200:201], s[36:37], 0, v[142:143]
	s_mov_b32 m0, s52
	s_nop 0
	global_load_lds_dwordx4 v[200:201], off
	s_waitcnt lgkmcnt(8)
	s_barrier
	s_waitcnt lgkmcnt(0)
	s_setprio 1
	s_waitcnt lgkmcnt(0)
	v_mfma_f32_16x16x32_bf16 v[134:137], v[78:81], v[168:171], v[134:137]
	v_mfma_f32_16x16x32_bf16 v[66:69], v[156:159], v[168:171], v[66:69]
	v_mfma_f32_16x16x32_bf16 v[126:129], v[78:81], v[176:179], v[126:129]
	v_mfma_f32_16x16x32_bf16 v[62:65], v[156:159], v[176:179], v[62:65]
	v_mfma_f32_16x16x32_bf16 v[102:105], v[78:81], v[184:187], v[102:105]
	v_mfma_f32_16x16x32_bf16 v[30:33], v[156:159], v[184:187], v[30:33]
	v_mfma_f32_16x16x32_bf16 v[98:101], v[78:81], v[192:195], v[98:101]
	v_mfma_f32_16x16x32_bf16 v[22:25], v[156:159], v[192:195], v[22:25]
	v_mfma_f32_16x16x32_bf16 v[134:137], v[110:113], v[172:175], v[134:137]
	v_mfma_f32_16x16x32_bf16 v[66:69], v[160:163], v[172:175], v[66:69]
	v_mfma_f32_16x16x32_bf16 v[126:129], v[110:113], v[180:183], v[126:129]
	v_mfma_f32_16x16x32_bf16 v[62:65], v[160:163], v[180:183], v[62:65]
	v_mfma_f32_16x16x32_bf16 v[102:105], v[110:113], v[188:191], v[102:105]
	v_mfma_f32_16x16x32_bf16 v[30:33], v[160:163], v[188:191], v[30:33]
	v_mfma_f32_16x16x32_bf16 v[98:101], v[110:113], v[196:199], v[98:101]
	v_mfma_f32_16x16x32_bf16 v[22:25], v[160:163], v[196:199], v[22:25]
	s_setprio 0
	s_barrier
	s_add_i32 s42, 0, 0x1c000
	s_add_i32 s36, s66, s46
	v_add_u32_e32 v165, s42, v228
	v_lshl_add_u64 v[216:217], v[216:217], 0, s[10:11]
	s_mov_b32 m0, s36
	ds_read_b128 v[200:203], v165
	ds_read_b128 v[204:207], v165 offset:1024
	ds_read_b128 v[208:211], v165 offset:2048
	ds_read_b128 v[212:215], v165 offset:3072
	global_load_lds_dwordx4 v[216:217], off
	v_lshl_add_u64 v[216:217], v[218:219], 0, s[10:11]
	s_add_i32 m0, s36, 0x2000
	s_nop 0
	global_load_lds_dwordx4 v[216:217], off
	s_barrier
	s_waitcnt lgkmcnt(0)
	s_setprio 1
	s_waitcnt lgkmcnt(0)
	v_mfma_f32_16x16x32_bf16 v[122:125], v[200:203], v[168:171], v[122:125]
	v_mfma_f32_16x16x32_bf16 v[54:57], v[208:211], v[168:171], v[54:57]
	v_mfma_f32_16x16x32_bf16 v[114:117], v[200:203], v[176:179], v[114:117]
	v_mfma_f32_16x16x32_bf16 v[50:53], v[208:211], v[176:179], v[50:53]
	v_mfma_f32_16x16x32_bf16 v[94:97], v[200:203], v[184:187], v[94:97]
	v_mfma_f32_16x16x32_bf16 v[26:29], v[208:211], v[184:187], v[26:29]
	v_mfma_f32_16x16x32_bf16 v[90:93], v[200:203], v[192:195], v[90:93]
	v_mfma_f32_16x16x32_bf16 v[18:21], v[208:211], v[192:195], v[18:21]
	v_mfma_f32_16x16x32_bf16 v[122:125], v[204:207], v[172:175], v[122:125]
	v_mfma_f32_16x16x32_bf16 v[54:57], v[212:215], v[172:175], v[54:57]
	v_mfma_f32_16x16x32_bf16 v[114:117], v[204:207], v[180:183], v[114:117]
	v_mfma_f32_16x16x32_bf16 v[50:53], v[212:215], v[180:183], v[50:53]
	v_mfma_f32_16x16x32_bf16 v[94:97], v[204:207], v[188:191], v[94:97]
	v_mfma_f32_16x16x32_bf16 v[26:29], v[212:215], v[188:191], v[26:29]
	v_mfma_f32_16x16x32_bf16 v[90:93], v[204:207], v[196:199], v[90:93]
	v_mfma_f32_16x16x32_bf16 v[18:21], v[212:215], v[196:199], v[18:21]
	s_setprio 0
	s_mov_b32 m0, s54
	v_lshl_add_u64 v[216:217], v[220:221], 0, s[10:11]
	s_barrier
	ds_read_b128 v[168:171], v232 offset:49152
	ds_read_b128 v[172:175], v232 offset:50176
	ds_read_b128 v[176:179], v232 offset:51200
	ds_read_b128 v[180:183], v232 offset:52224
	ds_read_b128 v[184:187], v232 offset:53248
	ds_read_b128 v[188:191], v232 offset:54272
	ds_read_b128 v[192:195], v232 offset:55296
	ds_read_b128 v[196:199], v232 offset:56320
	global_load_lds_dwordx4 v[216:217], off
	v_lshl_add_u64 v[216:217], v[222:223], 0, s[10:11]
	s_mov_b32 m0, s55
	s_nop 0
	global_load_lds_dwordx4 v[216:217], off
	s_barrier
; template <class PT, class Epi>
; __device__ __forceinline__ void gemm_phase_once(LAS unsigned char* lds, const PT& S, const Epi& E, bool epi_on) {
;     ...
;             PG8_WAIT_V(6); PG8_BAR; PG8_MMA(1, 1, At, B1); PG8_BAR;
;             PG8_LDB(B0, 1, 0); PG8_SCHED; PG8_LDA(At, 1, 0); PG8_STAGE(PG8_SA(0, 1), a2 + hstepA, voffA);
;             PG8_WAIT_L(8); PG8_BAR; PG8_WAIT_L(0); PG8_MMA(0, 0, At, B0); PG8_BAR; PG8_SCHED;
;             PG8_LDB(B1, 1, 1); PG8_STAGE(PG8_SB(1, 0), b3, voffB);
;             PG8_BAR; PG8_WAIT_L(0); PG8_MMA(0, 1, At, B1); PG8_BAR;
;             PG8_LDA(At, 1, 1); PG8_STAGE(PG8_SA(1, 0), a3, voffA);
;             PG8_BAR; PG8_WAIT_L(0); PG8_MMA(1, 0, At, B0); PG8_BAR; PG8_SCHED;
;             PG8_STAGE(PG8_SB(1, 1), b3 + hstepB, voffB);
;             PG8_WAIT_V(6); PG8_BAR; PG8_MMA(1, 1, At, B1); PG8_BAR;
;     __device__ __forceinline__ void operator()(const f32x4 (&acc)[2][2][4][2], const pg8::Unit& u, int wr, int wc, int fr, int fq) const {
;         const int ch0 = 128 * u.pn + 32 * wc + 8 * fq, tok0 = 256 * u.pm + 128 * wr + 8 * fr;
;         const f32x4 r0 = *(const f32x4*)(RS + tok0), r1 = *(const f32x4*)(RS + tok0 + 4);
;         bf16* hb = HALO + ((size_t)((u.pm * 44 + u.pn) * 2 + wr) * 4) * 256 + 32 * wc + 8 * fq;
; #pragma unroll
;         for (int n = 0; n < 2; ++n) {
;             float g[8][4], v[8][4];
; #pragma unroll
;             for (int e = 0; e < 8; ++e) { const float rs = (e < 4) ? r0[e & 3] : r1[e & 3];
; #pragma unroll
;                 for (int jj = 0; jj < 4; ++jj) { g[e][jj] = acc[e >> 2][0][e & 3][n][jj] * rs; v[e][jj] = acc[e >> 2][1][e & 3][n][jj] * rs; } }
;             if (fr == 0) {
; #pragma unroll
;                 for (int q = 0; q < 2; ++q) { v2u a, b; a.x = pk2(g[q][0], g[q][1]); a.y = pk2(g[q][2], g[q][3]); b.x = pk2(v[q][0], v[q][1]); b.y = pk2(v[q][2], v[q][3]);
;                     *(v2u*)(hb + (size_t)q * 256 + 4 * n) = a; *(v2u*)(hb + (size_t)q * 256 + 128 + 4 * n) = b; } }
;             if (fr == 15) {
; #pragma unroll
;                 for (int q = 0; q < 2; ++q) { v2u a, b; a.x = pk2(g[6 + q][0], g[6 + q][1]); a.y = pk2(g[6 + q][2], g[6 + q][3]); b.x = pk2(v[6 + q][0], v[6 + q][1]); b.y = pk2(v[6 + q][2], v[6 + q][3]);
;                     *(v2u*)(hb + (size_t)(2 + q) * 256 + 4 * n) = a; *(v2u*)(hb + (size_t)(2 + q) * 256 + 128 + 4 * n) = b; } }
	s_waitcnt lgkmcnt(0)
	s_setprio 1
	s_waitcnt lgkmcnt(0)
	v_mfma_f32_16x16x32_bf16 v[86:89], v[78:81], v[168:171], v[86:89]
	v_mfma_f32_16x16x32_bf16 v[14:17], v[156:159], v[168:171], v[14:17]
	v_mfma_f32_16x16x32_bf16 v[82:85], v[78:81], v[176:179], v[82:85]
	v_mfma_f32_16x16x32_bf16 v[6:9], v[156:159], v[176:179], v[6:9]
	v_mfma_f32_16x16x32_bf16 v[130:133], v[78:81], v[184:187], v[130:133]
	v_mfma_f32_16x16x32_bf16 v[46:49], v[156:159], v[184:187], v[46:49]
	v_mfma_f32_16x16x32_bf16 v[58:61], v[78:81], v[192:195], v[58:61]
	v_mfma_f32_16x16x32_bf16 v[42:45], v[156:159], v[192:195], v[42:45]
	v_mfma_f32_16x16x32_bf16 v[86:89], v[110:113], v[172:175], v[86:89]
	v_mfma_f32_16x16x32_bf16 v[14:17], v[160:163], v[172:175], v[14:17]
	v_mfma_f32_16x16x32_bf16 v[82:85], v[110:113], v[180:183], v[82:85]
	v_mfma_f32_16x16x32_bf16 v[6:9], v[160:163], v[180:183], v[6:9]
	v_mfma_f32_16x16x32_bf16 v[130:133], v[110:113], v[188:191], v[130:133]
	v_mfma_f32_16x16x32_bf16 v[46:49], v[160:163], v[188:191], v[46:49]
	v_mfma_f32_16x16x32_bf16 v[110:113], v[110:113], v[196:199], v[58:61]
	v_mfma_f32_16x16x32_bf16 v[42:45], v[160:163], v[196:199], v[42:45]
	s_setprio 0
	s_barrier
	s_add_u32 s36, s40, 0x80080
	s_addc_u32 s37, s41, 0
	s_add_i32 s40, s42, s46
	v_lshl_add_u64 v[58:59], s[36:37], 0, v[144:145]
	s_mov_b32 m0, s40
	s_nop 0
	global_load_lds_dwordx4 v[58:59], off
	v_lshl_add_u64 v[58:59], s[36:37], 0, v[138:139]
	s_add_i32 m0, s40, 0x2000
	s_nop 0
	global_load_lds_dwordx4 v[58:59], off
	s_waitcnt vmcnt(6)
	s_barrier
	s_setprio 1
	v_mfma_f32_16x16x32_bf16 v[58:61], v[200:203], v[168:171], v[70:73]
	v_mfma_f32_16x16x32_bf16 v[78:81], v[204:207], v[172:175], v[58:61]
	v_mfma_f32_16x16x32_bf16 v[58:61], v[200:203], v[176:179], v[74:77]
	v_mfma_f32_16x16x32_bf16 v[74:77], v[204:207], v[180:183], v[58:61]
	v_mfma_f32_16x16x32_bf16 v[58:61], v[200:203], v[184:187], v[118:121]
	v_mfma_f32_16x16x32_bf16 v[10:13], v[208:211], v[168:171], v[10:13]
	v_mfma_f32_16x16x32_bf16 v[2:5], v[208:211], v[176:179], v[2:5]
	v_mfma_f32_16x16x32_bf16 v[118:121], v[204:207], v[188:191], v[58:61]
	v_mfma_f32_16x16x32_bf16 v[38:41], v[208:211], v[184:187], v[38:41]
	v_mfma_f32_16x16x32_bf16 v[58:61], v[200:203], v[192:195], v[106:109]
	v_mfma_f32_16x16x32_bf16 v[34:37], v[208:211], v[192:195], v[34:37]
	v_mfma_f32_16x16x32_bf16 v[10:13], v[212:215], v[172:175], v[10:13]
	v_mfma_f32_16x16x32_bf16 v[2:5], v[212:215], v[180:183], v[2:5]
	v_mfma_f32_16x16x32_bf16 v[38:41], v[212:215], v[188:191], v[38:41]
	v_mfma_f32_16x16x32_bf16 v[106:109], v[204:207], v[196:199], v[58:61]
	v_mfma_f32_16x16x32_bf16 v[34:37], v[212:215], v[196:199], v[34:37]
	s_setprio 0
	s_add_i32 s65, s65, 2
	s_add_u32 s63, s63, 0x100
	s_addc_u32 s64, s64, 0
	s_cmp_lt_u32 s65, 30
	s_mov_b64 s[36:37], s[38:39]
	s_barrier
	s_cbranch_scc1 .LBB0_5583
	v_lshl_add_u32 v156, s34, 8, v229
	v_ashrrev_i32_e32 v157, 31, v156
	v_lshl_add_u64 v[70:71], v[156:157], 2, s[90:91]
	global_load_dwordx4 v[58:61], v[70:71], off offset:16
	s_nop 0
	global_load_dwordx4 v[70:73], v[70:71], off
	s_mul_i32 s25, s34, 44
	s_add_i32 s25, s25, s61
	s_lshl_b32 s25, s25, 1
	s_add_i32 s34, s25, s45
	s_ashr_i32 s35, s34, 31
	v_mov_b32_e32 v158, v130
	v_mov_b32_e32 v159, v132
	v_mov_b32_e32 v160, v118
	v_mov_b32_e32 v161, v120
	v_mov_b32_e32 v132, v131
	v_mov_b32_e32 v120, v119
	s_lshl_b64 s[34:35], s[34:35], 11
	v_cmp_lt_i32_e32 vcc, 14, v167
	v_lshl_add_u64 v[130:131], v[146:147], 0, s[34:35]
	s_mov_b64 s[34:35], 0
	s_waitcnt vmcnt(0)
	v_pk_mul_f32 v[162:163], v[158:159], v[60:61] op_sel_hi:[1,0]
	v_pk_mul_f32 v[158:159], v[160:161], v[60:61] op_sel_hi:[1,0]
	v_pk_mul_f32 v[160:161], v[132:133], v[60:61] op_sel_hi:[1,0]
	v_pk_mul_f32 v[132:133], v[120:121], v[60:61] op_sel_hi:[1,0]
	s_and_saveexec_b64 s[36:37], vcc
	s_xor_b64 s[36:37], exec, s[36:37]
	s_cbranch_execz .LBB0_5586
	s_nop 7
	s_nop 1
	v_cvt_pk_bf16_f32 v121, v163, v161
	v_cvt_pk_bf16_f32 v120, v162, v160
	s_nop 7
	s_nop 1
	s_mov_b64 s[34:35], exec
	v_cvt_pk_bf16_f32 v119, v159, v133
	v_cvt_pk_bf16_f32 v118, v158, v132
	global_store_dwordx2 v[130:131], v[120:121], off offset:1024
.LBB0_5586:
	s_or_saveexec_b64 s[36:37], s[36:37]
	v_mov_b32_e32 v120, v134
	v_mov_b32_e32 v121, v136
	v_pk_mul_f32 v[188:189], v[120:121], v[70:71] op_sel_hi:[1,0]
	v_mov_b32_e32 v120, v122
	v_mov_b32_e32 v121, v124
	v_pk_mul_f32 v[186:187], v[120:121], v[70:71] op_sel_hi:[1,0]
	v_mov_b32_e32 v120, v126
	v_mov_b32_e32 v121, v128
	v_pk_mul_f32 v[180:181], v[120:121], v[70:71] op_sel:[0,1]
	v_mov_b32_e32 v120, v114
	v_mov_b32_e32 v121, v116
	v_mov_b32_e32 v116, v115
	v_mov_b32_e32 v114, v110
	v_mov_b32_e32 v115, v112
	v_mov_b32_e32 v110, v61
	v_mov_b32_e32 v136, v135
	v_pk_mul_f32 v[168:169], v[114:115], v[110:111] op_sel_hi:[1,0]
	v_mov_b32_e32 v114, v106
	v_mov_b32_e32 v115, v108
	v_mov_b32_e32 v112, v111
	v_mov_b32_e32 v108, v107
	v_pk_mul_f32 v[190:191], v[136:137], v[70:71] op_sel_hi:[1,0]
	v_mov_b32_e32 v124, v123
	v_mov_b32_e32 v128, v127
	v_pk_mul_f32 v[134:135], v[114:115], v[110:111] op_sel_hi:[1,0]
	v_pk_mul_f32 v[170:171], v[112:113], v[110:111] op_sel_hi:[1,0]
	v_pk_mul_f32 v[136:137], v[108:109], v[110:111] op_sel_hi:[1,0]
	v_pk_mul_f32 v[184:185], v[124:125], v[70:71] op_sel_hi:[1,0]
	v_pk_mul_f32 v[178:179], v[120:121], v[70:71] op_sel:[0,1]
	v_pk_mul_f32 v[182:183], v[128:129], v[70:71] op_sel:[0,1]
	v_pk_mul_f32 v[176:177], v[116:117], v[70:71] op_sel:[0,1]
	v_mov_b64_e32 v[114:115], 0x500
	v_mov_b64_e32 v[108:109], 0x600
	v_mov_b64_e32 v[106:107], 0x700
	v_mov_b64_e32 v[120:121], v[168:169]
	v_mov_b64_e32 v[116:117], v[170:171]
	v_mov_b64_e32 v[110:111], v[134:135]
	v_mov_b64_e32 v[112:113], v[136:137]
	s_xor_b64 exec, exec, s[36:37]
	s_cbranch_execz .LBB0_5590
	v_cmp_eq_u32_e32 vcc, 0, v167
	s_mov_b64 s[40:41], s[34:35]
	s_and_saveexec_b64 s[38:39], vcc
	s_cbranch_execz .LBB0_5589
	s_nop 7
	s_nop 3
	v_cvt_pk_bf16_f32 v107, v189, v191
	v_cvt_pk_bf16_f32 v106, v188, v190
	s_nop 7
	v_cvt_pk_bf16_f32 v119, v187, v185
	v_cvt_pk_bf16_f32 v118, v186, v184
	s_or_b64 s[40:41], s[34:35], exec
	global_store_dwordx2 v[130:131], v[106:107], off

; __device__ __forceinline__ unsigned pk2(float lo, float hi) { return f2bf(lo) | (f2bf(hi) << 16); }
; __device__ __forceinline__ float dpp_shr1(float x) { return __builtin_bit_cast(float, __builtin_amdgcn_update_dpp(0, __builtin_bit_cast(int, x), 0x111, 0xf, 0xf, true)); }
;     __device__ __forceinline__ void operator()(const f32x4 (&acc)[2][2][4][2], const pg8::Unit& u, int wr, int wc, int fr, int fq) const {
;     ...
;             if (fr == 0) {
; #pragma unroll
;                 for (int q = 0; q < 2; ++q) { v2u a, b; a.x = pk2(g[q][0], g[q][1]); a.y = pk2(g[q][2], g[q][3]); b.x = pk2(v[q][0], v[q][1]); b.y = pk2(v[q][2], v[q][3]);
;                     *(v2u*)(hb + (size_t)q * 256 + 4 * n) = a; *(v2u*)(hb + (size_t)q * 256 + 128 + 4 * n) = b; } }
;             if (fr == 15) {
; #pragma unroll
;                 for (int q = 0; q < 2; ++q) { v2u a, b; a.x = pk2(g[6 + q][0], g[6 + q][1]); a.y = pk2(g[6 + q][2], g[6 + q][3]); b.x = pk2(v[6 + q][0], v[6 + q][1]); b.y = pk2(v[6 + q][2], v[6 + q][3]);
;                     *(v2u*)(hb + (size_t)(2 + q) * 256 + 4 * n) = a; *(v2u*)(hb + (size_t)(2 + q) * 256 + 128 + 4 * n) = b; } }
;             const int cc = ch0 + 4 * n;
;             const f32x4 wg0 = *(CF4)(cw + cc), wg1 = *(CF4)(cw + FF2 + cc), wg2 = *(CF4)(cw + 2 * FF2 + cc), wv0 = *(CF4)(cw + FFH + cc), wv1 = *(CF4)(cw + FF2 + FFH + cc), wv2 = *(CF4)(cw + 2 * FF2 + FFH + cc);
;             const f32x4 bg = *(CF4)(cb + cc), bv = *(CF4)(cb + FFH + cc);
; #pragma unroll
;             for (int jj = 0; jj < 4; ++jj) {
;                 float g2 = dpp_shr1(g[6][jj]), g1 = dpp_shr1(g[7][jj]), v2 = dpp_shr1(v[6][jj]), v1 = dpp_shr1(v[7][jj]);
.LBB0_5590:
	s_or_b64 exec, exec, s[36:37]
	s_and_saveexec_b64 s[36:37], s[34:35]
	s_cbranch_execz .LBB0_5592
	v_lshl_add_u64 v[114:115], v[130:131], 0, v[114:115]
	global_store_dwordx2 v[114:115], v[118:119], off
	s_nop 7
	s_nop 1
	v_cvt_pk_bf16_f32 v115, v121, v117
	v_cvt_pk_bf16_f32 v114, v120, v116
	s_nop 7
	s_nop 1
	v_cvt_pk_bf16_f32 v111, v111, v113
	v_cvt_pk_bf16_f32 v110, v110, v112
	v_lshl_add_u64 v[108:109], v[130:131], 0, v[108:109]
	v_lshl_add_u64 v[106:107], v[130:131], 0, v[106:107]
	global_store_dwordx2 v[108:109], v[114:115], off
	global_store_dwordx2 v[106:107], v[110:111], off
.LBB0_5592:
	s_or_b64 exec, exec, s[36:37]
	v_lshl_or_b32 v128, s61, 7, v230
	v_ashrrev_i32_e32 v129, 31, v128
	v_lshlrev_b64 v[192:193], 2, v[128:129]
	v_lshl_add_u64 v[106:107], s[6:7], 0, v[192:193]
	v_lshl_add_u64 v[110:111], s[8:9], 0, v[192:193]
	global_load_dwordx4 v[106:109], v[106:107], off
	v_mov_b32_e32 v166, v73
	global_load_dwordx4 v[114:117], v[110:111], off
	v_lshl_add_u64 v[110:111], s[12:13], 0, v[192:193]
	global_load_dwordx4 v[118:121], v[110:111], off
	v_lshl_add_u64 v[110:111], s[14:15], 0, v[192:193]
	global_load_dwordx4 v[122:125], v[110:111], off
	v_mov_b32_e32 v110, v102
	v_mov_b32_e32 v111, v104
	v_pk_mul_f32 v[226:227], v[110:111], v[72:73] op_sel_hi:[1,0]
	v_mov_b32_e32 v110, v94
	v_mov_b32_e32 v111, v96
	v_mov_b32_e32 v96, v95
	v_lshl_add_u64 v[94:95], s[16:17], 0, v[192:193]
	v_pk_mul_f32 v[220:221], v[96:97], v[72:73] op_sel_hi:[1,0]
	global_load_dwordx4 v[94:97], v[94:95], off
	v_pk_mul_f32 v[222:223], v[110:111], v[72:73] op_sel_hi:[1,0]
	v_mov_b32_e32 v104, v103
	v_mov_b32_e32 v110, v98
	v_mov_b32_e32 v111, v100
	v_lshl_add_u64 v[102:103], s[22:23], 0, v[192:193]
	v_pk_mul_f32 v[224:225], v[104:105], v[72:73] op_sel_hi:[1,0]
	global_load_dwordx4 v[102:105], v[102:103], off
	v_pk_mul_f32 v[216:217], v[110:111], v[166:167] op_sel_hi:[1,0]
	v_lshl_add_u64 v[110:111], s[18:19], 0, v[192:193]
	global_load_dwordx4 v[110:113], v[110:111], off
	v_mov_b32_e32 v100, v99
	v_lshl_add_u64 v[98:99], s[20:21], 0, v[192:193]
	v_pk_mul_f32 v[218:219], v[100:101], v[166:167] op_sel_hi:[1,0]
	global_load_dwordx4 v[98:101], v[98:99], off
	v_mov_b32_e32 v195, v92
	v_mov_b32_e32 v92, v91
	v_mov_b32_e32 v198, v58
	v_mov_b32_e32 v199, v59
	v_pk_mul_f32 v[212:213], v[92:93], v[166:167] op_sel_hi:[1,0]
	v_mov_b32_e32 v92, v86
	v_mov_b32_e32 v93, v88
	v_mov_b32_e32 v194, v90
	v_pk_mul_f32 v[210:211], v[92:93], v[198:199] op_sel_hi:[1,0]
	v_mov_b32_e32 v92, v78
	v_mov_b32_e32 v93, v80
	v_mov_b32_e32 v80, v79
	v_mov_b32_e32 v78, v82
	v_mov_b32_e32 v79, v84
	v_pk_mul_f32 v[214:215], v[194:195], v[166:167] op_sel_hi:[1,0]
	v_mov_b32_e32 v88, v87
	v_pk_mul_f32 v[194:195], v[78:79], v[198:199] op_sel:[0,1]
	v_mov_b32_e32 v78, v74
	v_mov_b32_e32 v79, v76
	v_mov_b32_e32 v84, v83
	v_mov_b32_e32 v76, v75
	v_pk_mul_f32 v[202:203], v[92:93], v[198:199] op_sel_hi:[1,0]
	v_pk_mul_f32 v[208:209], v[88:89], v[198:199] op_sel_hi:[1,0]
	v_pk_mul_f32 v[196:197], v[80:81], v[198:199] op_sel_hi:[1,0]
	v_pk_mul_f32 v[92:93], v[78:79], v[198:199] op_sel:[0,1]
	v_pk_mul_f32 v[192:193], v[84:85], v[198:199] op_sel:[0,1]
	v_pk_mul_f32 v[78:79], v[76:77], v[198:199] op_sel:[0,1]
	v_mov_b32_dpp v74, v162 row_shr:1 row_mask:0xf bank_mask:0xf bound_ctrl:1
	v_mov_b32_dpp v75, v163 row_shr:1 row_mask:0xf bank_mask:0xf bound_ctrl:1
	v_mov_b32_dpp v76, v168 row_shr:1 row_mask:0xf bank_mask:0xf bound_ctrl:1
	v_mov_b32_dpp v84, v160 row_shr:1 row_mask:0xf bank_mask:0xf bound_ctrl:1
	v_mov_b32_dpp v77, v169 row_shr:1 row_mask:0xf bank_mask:0xf bound_ctrl:1
	v_mov_b32_dpp v85, v161 row_shr:1 row_mask:0xf bank_mask:0xf bound_ctrl:1
	v_mov_b32_dpp v86, v170 row_shr:1 row_mask:0xf bank_mask:0xf bound_ctrl:1
	v_mov_b32_dpp v87, v171 row_shr:1 row_mask:0xf bank_mask:0xf bound_ctrl:1
	v_mov_b32_dpp v80, v158 row_shr:1 row_mask:0xf bank_mask:0xf bound_ctrl:1
	v_mov_b32_dpp v81, v159 row_shr:1 row_mask:0xf bank_mask:0xf bound_ctrl:1
	v_mov_b32_dpp v82, v134 row_shr:1 row_mask:0xf bank_mask:0xf bound_ctrl:1
	v_mov_b32_dpp v83, v135 row_shr:1 row_mask:0xf bank_mask:0xf bound_ctrl:1
	v_mov_b32_dpp v88, v132 row_shr:1 row_mask:0xf bank_mask:0xf bound_ctrl:1
	v_mov_b32_dpp v89, v133 row_shr:1 row_mask:0xf bank_mask:0xf bound_ctrl:1
	v_mov_b32_dpp v236, v136 row_shr:1 row_mask:0xf bank_mask:0xf bound_ctrl:1
	v_mov_b32_dpp v237, v137 row_shr:1 row_mask:0xf bank_mask:0xf bound_ctrl:1
	v_mov_b32_e32 v172, v70
	v_mov_b32_e32 v173, v70
	v_mov_b32_e32 v70, v71
	v_mov_b32_e32 v174, v60
	v_mov_b32_e32 v175, v60
	v_mov_b32_e32 v60, v61
	v_mov_b32_e32 v126, v72
	s_waitcnt vmcnt(0)
; __device__ __forceinline__ unsigned pk2(float lo, float hi) { return f2bf(lo) | (f2bf(hi) << 16); }
; __device__ __forceinline__ float silu_fast(float x) { return x * __builtin_amdgcn_rcpf(1.f + __builtin_amdgcn_exp2f(-1.4426950408889634f * x)); }
; __device__ __forceinline__ float dpp_shr1(float x) { return __builtin_bit_cast(float, __builtin_amdgcn_update_dpp(0, __builtin_bit_cast(int, x), 0x111, 0xf, 0xf, true)); }
;     __device__ __forceinline__ void operator()(const f32x4 (&acc)[2][2][4][2], const pg8::Unit& u, int wr, int wc, int fr, int fq) const {
;     ...
;             const int cc = ch0 + 4 * n;
;             const f32x4 wg0 = *(CF4)(cw + cc), wg1 = *(CF4)(cw + FF2 + cc), wg2 = *(CF4)(cw + 2 * FF2 + cc), wv0 = *(CF4)(cw + FFH + cc), wv1 = *(CF4)(cw + FF2 + FFH + cc), wv2 = *(CF4)(cw + 2 * FF2 + FFH + cc);
;             const f32x4 bg = *(CF4)(cb + cc), bv = *(CF4)(cb + FFH + cc);
; #pragma unroll
;             for (int jj = 0; jj < 4; ++jj) {
;                 float g2 = dpp_shr1(g[6][jj]), g1 = dpp_shr1(g[7][jj]), v2 = dpp_shr1(v[6][jj]), v1 = dpp_shr1(v[7][jj]);
; #pragma unroll
;                 for (int e = 0; e < 8; ++e) { const float g0 = g[e][jj], v0 = v[e][jj];
;                     const float cg = bg[jj] + wg0[jj] * g2 + wg1[jj] * g1 + wg2[jj] * g0, cv = bv[jj] + wv0[jj] * v2 + wv1[jj] * v1 + wv2[jj] * v0;
;                     g[e][jj] = silu_fast(cg) * cv; g2 = g1; g1 = g0; v2 = v1; v1 = v0; } }
; #pragma unroll
;             for (int e = 0; e < 8; ++e) { v2u w; w.x = pk2(g[e][0], g[e][1]); w.y = pk2(g[e][2], g[e][3]); *(v2u*)(ACT + (size_t)(tok0 + e) * FFH + cc) = w; }
	v_mov_b32_e32 v198, v106
	v_mov_b32_e32 v199, v108
	v_mov_b32_e32 v200, v114
	v_mov_b32_e32 v201, v116
	v_pk_fma_f32 v[74:75], v[198:199], v[74:75], v[200:201]
	v_mov_b32_e32 v204, v118
	v_mov_b32_e32 v205, v120
	v_mov_b32_e32 v108, v107
	v_mov_b32_e32 v116, v115
	v_pk_fma_f32 v[74:75], v[204:205], v[76:77], v[74:75]
	v_mov_b32_e32 v206, v122
	v_mov_b32_e32 v207, v124
	v_pk_fma_f32 v[84:85], v[108:109], v[84:85], v[116:117]
	v_mov_b32_e32 v120, v119
	v_pk_fma_f32 v[74:75], v[188:189], v[206:207], v[74:75]
	v_pk_fma_f32 v[84:85], v[120:121], v[86:87], v[84:85]
	v_mov_b32_e32 v124, v123
	v_mul_f32_e32 v106, 0xbfb8aa3b, v74
	v_pk_fma_f32 v[84:85], v[190:191], v[124:125], v[84:85]
	v_exp_f32_e32 v106, v106
	v_mul_f32_e32 v107, 0xbfb8aa3b, v84
	v_exp_f32_e32 v107, v107
	v_mov_b32_e32 v114, v102
	v_add_f32_e32 v106, 1.0, v106
	v_rcp_f32_e32 v238, v106
	v_add_f32_e32 v106, 1.0, v107
	v_rcp_f32_e32 v240, v106
	v_mov_b32_e32 v106, v94
	v_mul_f32_e32 v94, 0xbfb8aa3b, v75
	v_exp_f32_e32 v94, v94
	v_mov_b32_e32 v107, v96
	v_mov_b32_e32 v115, v104
	v_pk_fma_f32 v[80:81], v[106:107], v[80:81], v[114:115]
	v_add_f32_e32 v94, 1.0, v94
	v_rcp_f32_e32 v239, v94
	v_mov_b32_e32 v122, v110
	v_mov_b32_e32 v123, v112
	v_pk_fma_f32 v[80:81], v[122:123], v[82:83], v[80:81]
	v_mov_b32_e32 v118, v98
	v_mov_b32_e32 v119, v100
	v_pk_fma_f32 v[80:81], v[186:187], v[118:119], v[80:81]
	v_pk_mul_f32 v[74:75], v[74:75], v[238:239]
	v_mov_b32_e32 v96, v95
	v_pk_mul_f32 v[74:75], v[80:81], v[74:75]
	v_mul_f32_e32 v80, 0xbfb8aa3b, v85
	v_exp_f32_e32 v94, v80
	v_mov_b32_e32 v104, v103
	v_pk_fma_f32 v[80:81], v[96:97], v[88:89], v[104:105]
	v_mov_b32_e32 v112, v111
	v_add_f32_e32 v88, 1.0, v94
	v_rcp_f32_e32 v241, v88
	v_pk_fma_f32 v[80:81], v[112:113], v[236:237], v[80:81]
	v_mov_b32_e32 v100, v99
	v_pk_fma_f32 v[80:81], v[184:185], v[100:101], v[80:81]
	v_pk_mul_f32 v[84:85], v[84:85], v[240:241]
	v_pk_fma_f32 v[76:77], v[198:199], v[76:77], v[200:201]
	v_pk_mul_f32 v[80:81], v[80:81], v[84:85]
	s_nop 7
	s_nop 1
	v_mov_b64_e32 v[94:95], s[78:79]
	v_pk_fma_f32 v[76:77], v[188:189], v[204:205], v[76:77]
	v_cvt_pk_bf16_f32 v75, v75, v81
	v_cvt_pk_bf16_f32 v74, v74, v80
	v_mad_i64_i32 v[80:81], s[34:35], v156, s60, v[94:95]
	v_lshlrev_b64 v[98:99], 1, v[128:129]
	v_pk_fma_f32 v[76:77], v[180:181], v[206:207], v[76:77]
	v_lshl_add_u64 v[84:85], v[80:81], 0, v[98:99]
	v_mul_f32_e32 v80, 0xbfb8aa3b, v76
	v_exp_f32_e32 v88, v80
	v_pk_fma_f32 v[80:81], v[108:109], v[86:87], v[116:117]
	global_store_dwordx2 v[84:85], v[74:75], off
	v_pk_fma_f32 v[80:81], v[190:191], v[120:121], v[80:81]
	v_add_f32_e32 v74, 1.0, v88
	v_pk_fma_f32 v[80:81], v[182:183], v[124:125], v[80:81]
	v_rcp_f32_e32 v74, v74
	v_mul_f32_e32 v86, 0xbfb8aa3b, v80
	v_exp_f32_e32 v86, v86
	v_pk_fma_f32 v[82:83], v[106:107], v[82:83], v[114:115]
	v_pk_fma_f32 v[102:103], v[178:179], v[106:107], v[114:115]
	v_pk_fma_f32 v[82:83], v[186:187], v[122:123], v[82:83]
	v_add_f32_e32 v75, 1.0, v86
	v_mul_f32_e32 v86, 0xbfb8aa3b, v77
	v_exp_f32_e32 v87, v86
	v_rcp_f32_e32 v86, v75
	v_pk_fma_f32 v[82:83], v[178:179], v[118:119], v[82:83]
	v_pk_fma_f32 v[102:103], v[222:223], v[122:123], v[102:103]
	v_add_f32_e32 v75, 1.0, v87
	v_mul_f32_e32 v87, 0xbfb8aa3b, v81
	v_rcp_f32_e32 v75, v75
	v_exp_f32_e32 v87, v87
	v_pk_fma_f32 v[102:103], v[214:215], v[118:119], v[102:103]
	v_pk_fma_f32 v[110:111], v[222:223], v[106:107], v[114:115]
	v_pk_mul_f32 v[74:75], v[76:77], v[74:75]
	v_add_f32_e32 v76, 1.0, v87
	v_rcp_f32_e32 v87, v76
	v_pk_fma_f32 v[76:77], v[96:97], v[236:237], v[104:105]
	v_pk_mul_f32 v[74:75], v[82:83], v[74:75]
	v_pk_fma_f32 v[76:77], v[184:185], v[112:113], v[76:77]
	v_pk_mul_f32 v[80:81], v[80:81], v[86:87]
	v_pk_fma_f32 v[76:77], v[176:177], v[100:101], v[76:77]
	v_pk_fma_f32 v[86:87], v[186:187], v[106:107], v[114:115]
	v_pk_mul_f32 v[76:77], v[76:77], v[80:81]
	s_nop 7
	s_nop 1
	v_cvt_pk_bf16_f32 v74, v74, v76
	v_or_b32_e32 v76, 1, v156
	v_cvt_pk_bf16_f32 v75, v75, v77
	v_mad_i64_i32 v[76:77], s[34:35], v76, s60, v[94:95]
	v_lshl_add_u64 v[88:89], v[76:77], 0, v[98:99]
	v_pk_fma_f32 v[76:77], v[188:189], v[198:199], v[200:201]
	global_store_dwordx2 v[88:89], v[74:75], off
	v_pk_fma_f32 v[76:77], v[180:181], v[204:205], v[76:77]
	v_pk_fma_f32 v[86:87], v[178:179], v[122:123], v[86:87]
	v_pk_fma_f32 v[76:77], v[226:227], v[206:207], v[76:77]
	v_pk_fma_f32 v[86:87], v[222:223], v[118:119], v[86:87]
	v_mul_f32_e32 v80, 0xbfb8aa3b, v76
	v_exp_f32_e32 v82, v80
	v_pk_fma_f32 v[80:81], v[190:191], v[108:109], v[116:117]
	v_pk_fma_f32 v[110:111], v[214:215], v[122:123], v[110:111]
	v_pk_fma_f32 v[80:81], v[182:183], v[120:121], v[80:81]
	v_add_f32_e32 v74, 1.0, v82
	v_pk_fma_f32 v[80:81], v[224:225], v[124:125], v[80:81]
	v_mul_f32_e32 v82, 0xbfb8aa3b, v77
	v_mul_f32_e32 v83, 0xbfb8aa3b, v80
	v_exp_f32_e32 v83, v83
	v_rcp_f32_e32 v74, v74
	v_pk_fma_f32 v[110:111], v[202:203], v[118:119], v[110:111]
	v_pk_fma_f32 v[178:179], v[202:203], v[106:107], v[114:115]
	v_add_f32_e32 v75, 1.0, v83
	v_exp_f32_e32 v83, v82
	v_rcp_f32_e32 v82, v75
	v_pk_fma_f32 v[178:179], v[92:93], v[122:123], v[178:179]
	v_mov_b32_e32 v127, v72
	v_add_f32_e32 v75, 1.0, v83
	v_mul_f32_e32 v83, 0xbfb8aa3b, v81
	v_rcp_f32_e32 v75, v75
	v_exp_f32_e32 v83, v83
	v_pk_fma_f32 v[178:179], v[158:159], v[118:119], v[178:179]
	v_mov_b32_e32 v72, v73
	v_pk_mul_f32 v[74:75], v[76:77], v[74:75]
	v_add_f32_e32 v76, 1.0, v83
	v_rcp_f32_e32 v83, v76
	v_pk_fma_f32 v[76:77], v[184:185], v[96:97], v[104:105]
	v_pk_mul_f32 v[74:75], v[86:87], v[74:75]
	v_pk_fma_f32 v[76:77], v[176:177], v[112:113], v[76:77]
	v_pk_mul_f32 v[80:81], v[80:81], v[82:83]
; __device__ __forceinline__ unsigned pk2(float lo, float hi) { return f2bf(lo) | (f2bf(hi) << 16); }
; __device__ __forceinline__ float silu_fast(float x) { return x * __builtin_amdgcn_rcpf(1.f + __builtin_amdgcn_exp2f(-1.4426950408889634f * x)); }
; __device__ __forceinline__ float dpp_shr1(float x) { return __builtin_bit_cast(float, __builtin_amdgcn_update_dpp(0, __builtin_bit_cast(int, x), 0x111, 0xf, 0xf, true)); }
;     __device__ __forceinline__ void operator()(const f32x4 (&acc)[2][2][4][2], const pg8::Unit& u, int wr, int wc, int fr, int fq) const {
;     ...
;             for (int jj = 0; jj < 4; ++jj) {
;                 float g2 = dpp_shr1(g[6][jj]), g1 = dpp_shr1(g[7][jj]), v2 = dpp_shr1(v[6][jj]), v1 = dpp_shr1(v[7][jj]);
; #pragma unroll
;                 for (int e = 0; e < 8; ++e) { const float g0 = g[e][jj], v0 = v[e][jj];
;                     const float cg = bg[jj] + wg0[jj] * g2 + wg1[jj] * g1 + wg2[jj] * g0, cv = bv[jj] + wv0[jj] * v2 + wv1[jj] * v1 + wv2[jj] * v0;
;                     g[e][jj] = silu_fast(cg) * cv; g2 = g1; g1 = g0; v2 = v1; v1 = v0; } }
; #pragma unroll
;             for (int e = 0; e < 8; ++e) { v2u w; w.x = pk2(g[e][0], g[e][1]); w.y = pk2(g[e][2], g[e][3]); *(v2u*)(ACT + (size_t)(tok0 + e) * FFH + cc) = w; }
	v_pk_fma_f32 v[76:77], v[220:221], v[100:101], v[76:77]
	v_mov_b32_e32 v90, v58
	v_pk_mul_f32 v[76:77], v[76:77], v[80:81]
	s_nop 7
	s_nop 1
	v_cvt_pk_bf16_f32 v74, v74, v76
	v_or_b32_e32 v76, 2, v156
	v_cvt_pk_bf16_f32 v75, v75, v77
	v_mad_i64_i32 v[76:77], s[34:35], v76, s60, v[94:95]
	v_lshl_add_u64 v[86:87], v[76:77], 0, v[98:99]
	v_pk_fma_f32 v[76:77], v[180:181], v[198:199], v[200:201]
	global_store_dwordx2 v[86:87], v[74:75], off
	v_pk_fma_f32 v[76:77], v[226:227], v[204:205], v[76:77]
	v_mov_b32_e32 v91, v58
	v_pk_fma_f32 v[76:77], v[216:217], v[206:207], v[76:77]
	v_mov_b32_e32 v58, v59
	v_mul_f32_e32 v80, 0xbfb8aa3b, v76
	v_exp_f32_e32 v82, v80
	v_pk_fma_f32 v[80:81], v[182:183], v[108:109], v[116:117]
	v_cmp_gt_i32_e32 vcc, 15, v167
	v_pk_fma_f32 v[80:81], v[224:225], v[120:121], v[80:81]
	v_add_f32_e32 v74, 1.0, v82
	v_pk_fma_f32 v[80:81], v[218:219], v[124:125], v[80:81]
	v_mul_f32_e32 v82, 0xbfb8aa3b, v77
	v_mul_f32_e32 v83, 0xbfb8aa3b, v80
	v_exp_f32_e32 v83, v83
	v_rcp_f32_e32 v74, v74
	s_mov_b64 s[36:37], -1
	v_add_f32_e32 v75, 1.0, v83
	v_exp_f32_e32 v83, v82
	v_rcp_f32_e32 v82, v75
	v_add_f32_e32 v75, 1.0, v83
	v_mul_f32_e32 v83, 0xbfb8aa3b, v81
	v_rcp_f32_e32 v75, v75
	v_exp_f32_e32 v83, v83
	v_pk_mul_f32 v[74:75], v[76:77], v[74:75]
	v_add_f32_e32 v76, 1.0, v83
	v_rcp_f32_e32 v83, v76
	v_pk_fma_f32 v[76:77], v[176:177], v[96:97], v[104:105]
	v_pk_mul_f32 v[74:75], v[102:103], v[74:75]
	v_pk_fma_f32 v[76:77], v[220:221], v[112:113], v[76:77]
	v_pk_mul_f32 v[80:81], v[80:81], v[82:83]
	v_pk_fma_f32 v[76:77], v[212:213], v[100:101], v[76:77]
	v_pk_fma_f32 v[176:177], v[214:215], v[106:107], v[114:115]
	v_pk_mul_f32 v[76:77], v[76:77], v[80:81]
	s_nop 7
	s_nop 1
	v_cvt_pk_bf16_f32 v74, v74, v76
	v_or_b32_e32 v76, 3, v156
	v_cvt_pk_bf16_f32 v75, v75, v77
	v_mad_i64_i32 v[76:77], s[34:35], v76, s60, v[94:95]
	v_lshl_add_u64 v[82:83], v[76:77], 0, v[98:99]
	v_pk_fma_f32 v[76:77], v[226:227], v[198:199], v[200:201]
	global_store_dwordx2 v[82:83], v[74:75], off
	v_pk_fma_f32 v[76:77], v[216:217], v[204:205], v[76:77]
	v_pk_fma_f32 v[176:177], v[202:203], v[122:123], v[176:177]
	v_pk_fma_f32 v[76:77], v[210:211], v[206:207], v[76:77]
	v_pk_fma_f32 v[176:177], v[92:93], v[118:119], v[176:177]
	v_mul_f32_e32 v80, 0xbfb8aa3b, v76
	v_exp_f32_e32 v102, v80
	v_pk_fma_f32 v[80:81], v[224:225], v[108:109], v[116:117]
	v_pk_fma_f32 v[92:93], v[92:93], v[106:107], v[114:115]
	v_pk_fma_f32 v[80:81], v[218:219], v[120:121], v[80:81]
	v_add_f32_e32 v74, 1.0, v102
	v_pk_fma_f32 v[80:81], v[208:209], v[124:125], v[80:81]
	v_mul_f32_e32 v102, 0xbfb8aa3b, v77
	v_mul_f32_e32 v103, 0xbfb8aa3b, v80
	v_exp_f32_e32 v103, v103
	v_rcp_f32_e32 v74, v74
	v_pk_fma_f32 v[92:93], v[158:159], v[122:123], v[92:93]
	v_add_f32_e32 v75, 1.0, v103
	v_exp_f32_e32 v103, v102
	v_rcp_f32_e32 v102, v75
	v_pk_fma_f32 v[92:93], v[134:135], v[118:119], v[92:93]
	v_add_f32_e32 v75, 1.0, v103
	v_mul_f32_e32 v103, 0xbfb8aa3b, v81
	v_rcp_f32_e32 v75, v75
	v_exp_f32_e32 v103, v103
	v_pk_mul_f32 v[74:75], v[76:77], v[74:75]
	v_add_f32_e32 v76, 1.0, v103
	v_rcp_f32_e32 v103, v76
	v_pk_fma_f32 v[76:77], v[220:221], v[96:97], v[104:105]
	v_pk_mul_f32 v[74:75], v[110:111], v[74:75]
	v_pk_fma_f32 v[76:77], v[212:213], v[112:113], v[76:77]
	v_pk_mul_f32 v[80:81], v[80:81], v[102:103]
	v_pk_fma_f32 v[76:77], v[196:197], v[100:101], v[76:77]
	s_nop 0
	v_pk_mul_f32 v[76:77], v[76:77], v[80:81]
	s_nop 7
	s_nop 1
	v_cvt_pk_bf16_f32 v74, v74, v76
	v_or_b32_e32 v76, 4, v156
	v_cvt_pk_bf16_f32 v75, v75, v77
	v_mad_i64_i32 v[76:77], s[34:35], v76, s60, v[94:95]
	v_lshl_add_u64 v[80:81], v[76:77], 0, v[98:99]
	v_pk_fma_f32 v[76:77], v[216:217], v[198:199], v[200:201]
	global_store_dwordx2 v[80:81], v[74:75], off
	v_pk_fma_f32 v[76:77], v[210:211], v[204:205], v[76:77]
	s_nop 0
	v_pk_fma_f32 v[76:77], v[194:195], v[206:207], v[76:77]
	s_nop 0
	v_mul_f32_e32 v102, 0xbfb8aa3b, v76
	v_exp_f32_e32 v110, v102
	v_pk_fma_f32 v[102:103], v[218:219], v[108:109], v[116:117]
	v_add_f32_e32 v74, 1.0, v110
	v_pk_fma_f32 v[102:103], v[208:209], v[120:121], v[102:103]
	v_mul_f32_e32 v110, 0xbfb8aa3b, v77
	v_pk_fma_f32 v[102:103], v[192:193], v[124:125], v[102:103]
	v_rcp_f32_e32 v74, v74
	v_mul_f32_e32 v111, 0xbfb8aa3b, v102
	v_exp_f32_e32 v111, v111
	s_nop 0
	v_add_f32_e32 v75, 1.0, v111
	v_exp_f32_e32 v111, v110
	v_rcp_f32_e32 v110, v75
	v_add_f32_e32 v75, 1.0, v111
	v_mul_f32_e32 v111, 0xbfb8aa3b, v103
	v_rcp_f32_e32 v75, v75
	v_exp_f32_e32 v111, v111
	v_pk_mul_f32 v[74:75], v[76:77], v[74:75]
	v_add_f32_e32 v76, 1.0, v111
	v_rcp_f32_e32 v111, v76
	v_pk_fma_f32 v[76:77], v[212:213], v[96:97], v[104:105]
	v_pk_mul_f32 v[74:75], v[176:177], v[74:75]
	v_pk_fma_f32 v[76:77], v[196:197], v[112:113], v[76:77]
	v_pk_mul_f32 v[102:103], v[102:103], v[110:111]
	v_pk_fma_f32 v[76:77], v[78:79], v[100:101], v[76:77]
	s_nop 0
	v_pk_mul_f32 v[76:77], v[76:77], v[102:103]
	s_nop 7
	v_pk_fma_f32 v[102:103], v[210:211], v[198:199], v[200:201]
	s_nop 0
	v_pk_fma_f32 v[102:103], v[194:195], v[204:205], v[102:103]
	s_nop 0
	v_pk_fma_f32 v[102:103], v[162:163], v[206:207], v[102:103]
	v_cvt_pk_bf16_f32 v74, v74, v76
	v_mul_f32_e32 v110, 0xbfb8aa3b, v102
	v_exp_f32_e32 v129, v110
	v_pk_fma_f32 v[110:111], v[208:209], v[108:109], v[116:117]
	v_or_b32_e32 v76, 5, v156
	v_pk_fma_f32 v[110:111], v[192:193], v[120:121], v[110:111]
	v_cvt_pk_bf16_f32 v75, v75, v77
	v_mad_i64_i32 v[76:77], s[34:35], v76, s60, v[94:95]
	v_pk_fma_f32 v[110:111], v[160:161], v[124:125], v[110:111]
	v_lshl_add_u64 v[76:77], v[76:77], 0, v[98:99]
	v_mul_f32_e32 v157, 0xbfb8aa3b, v110
	v_exp_f32_e32 v157, v157
	global_store_dwordx2 v[76:77], v[74:75], off
; __device__ __forceinline__ unsigned pk2(float lo, float hi) { return f2bf(lo) | (f2bf(hi) << 16); }
;     __device__ __forceinline__ void operator()(const f32x4 (&acc)[2][2][4][2], const pg8::Unit& u, int wr, int wc, int fr, int fq) const {
;     ...
;         for (int n = 0; n < 2; ++n) {
;             float g[8][4], v[8][4];
; #pragma unroll
;             for (int e = 0; e < 8; ++e) { const float rs = (e < 4) ? r0[e & 3] : r1[e & 3];
; #pragma unroll
;                 for (int jj = 0; jj < 4; ++jj) { g[e][jj] = acc[e >> 2][0][e & 3][n][jj] * rs; v[e][jj] = acc[e >> 2][1][e & 3][n][jj] * rs; } }
;             if (fr == 0) {
; #pragma unroll
;                 for (int q = 0; q < 2; ++q) { v2u a, b; a.x = pk2(g[q][0], g[q][1]); a.y = pk2(g[q][2], g[q][3]); b.x = pk2(v[q][0], v[q][1]); b.y = pk2(v[q][2], v[q][3]);
;                     *(v2u*)(hb + (size_t)q * 256 + 4 * n) = a; *(v2u*)(hb + (size_t)q * 256 + 128 + 4 * n) = b; } }
;             if (fr == 15) {
; #pragma unroll
;                 for (int q = 0; q < 2; ++q) { v2u a, b; a.x = pk2(g[6 + q][0], g[6 + q][1]); a.y = pk2(g[6 + q][2], g[6 + q][3]); b.x = pk2(v[6 + q][0], v[6 + q][1]); b.y = pk2(v[6 + q][2], v[6 + q][3]);
;                     *(v2u*)(hb + (size_t)(2 + q) * 256 + 4 * n) = a; *(v2u*)(hb + (size_t)(2 + q) * 256 + 128 + 4 * n) = b; } }
;             const int cc = ch0 + 4 * n;
;             const f32x4 wg0 = *(CF4)(cw + cc), wg1 = *(CF4)(cw + FF2 + cc), wg2 = *(CF4)(cw + 2 * FF2 + cc), wv0 = *(CF4)(cw + FFH + cc), wv1 = *(CF4)(cw + FF2 + FFH + cc), wv2 = *(CF4)(cw + 2 * FF2 + FFH + cc);
;             const f32x4 bg = *(CF4)(cb + cc), bv = *(CF4)(cb + FFH + cc);
; #pragma unroll
;             for (int jj = 0; jj < 4; ++jj) {
;                 float g2 = dpp_shr1(g[6][jj]), g1 = dpp_shr1(g[7][jj]), v2 = dpp_shr1(v[6][jj]), v1 = dpp_shr1(v[7][jj]);
; #pragma unroll
;                 for (int e = 0; e < 8; ++e) { const float g0 = g[e][jj], v0 = v[e][jj];
;                     const float cg = bg[jj] + wg0[jj] * g2 + wg1[jj] * g1 + wg2[jj] * g0, cv = bv[jj] + wv0[jj] * v2 + wv1[jj] * v1 + wv2[jj] * v0;
;                     g[e][jj] = silu_fast(cg) * cv; g2 = g1; g1 = g0; v2 = v1; v1 = v0; } }
; #pragma unroll
;             for (int e = 0; e < 8; ++e) { v2u w; w.x = pk2(g[e][0], g[e][1]); w.y = pk2(g[e][2], g[e][3]); *(v2u*)(ACT + (size_t)(tok0 + e) * FFH + cc) = w; }
	v_add_f32_e32 v74, 1.0, v129
	v_mul_f32_e32 v129, 0xbfb8aa3b, v103
	v_exp_f32_e32 v129, v129
	v_add_f32_e32 v75, 1.0, v157
	v_rcp_f32_e32 v176, v75
	v_rcp_f32_e32 v74, v74
	v_add_f32_e32 v75, 1.0, v129
	v_mul_f32_e32 v129, 0xbfb8aa3b, v111
	v_rcp_f32_e32 v75, v75
	v_exp_f32_e32 v129, v129
	v_pk_fma_f32 v[108:109], v[192:193], v[108:109], v[116:117]
	v_pk_mul_f32 v[74:75], v[102:103], v[74:75]
	v_add_f32_e32 v102, 1.0, v129
	v_rcp_f32_e32 v177, v102
	v_pk_fma_f32 v[102:103], v[196:197], v[96:97], v[104:105]
	v_pk_mul_f32 v[74:75], v[178:179], v[74:75]
	v_pk_fma_f32 v[102:103], v[78:79], v[112:113], v[102:103]
	v_pk_mul_f32 v[110:111], v[110:111], v[176:177]
	v_pk_fma_f32 v[102:103], v[132:133], v[100:101], v[102:103]
	v_pk_fma_f32 v[108:109], v[160:161], v[120:121], v[108:109]
	v_pk_mul_f32 v[102:103], v[102:103], v[110:111]
	s_nop 3
	v_pk_fma_f32 v[108:109], v[170:171], v[124:125], v[108:109]
	s_nop 2
	v_mul_f32_e32 v116, 0xbfb8aa3b, v108
	s_nop 1
	v_exp_f32_e32 v116, v116
	s_nop 0
	v_cvt_pk_bf16_f32 v102, v74, v102
	v_or_b32_e32 v74, 6, v156
	v_pk_fma_f32 v[110:111], v[194:195], v[198:199], v[200:201]
	v_cvt_pk_bf16_f32 v103, v75, v103
	v_mad_i64_i32 v[74:75], s[34:35], v74, s60, v[94:95]
	v_pk_fma_f32 v[110:111], v[162:163], v[204:205], v[110:111]
	v_lshl_add_u64 v[74:75], v[74:75], 0, v[98:99]
	v_pk_fma_f32 v[110:111], v[168:169], v[206:207], v[110:111]
	global_store_dwordx2 v[74:75], v[102:103], off
	v_mul_f32_e32 v129, 0xbfb8aa3b, v110
	v_add_f32_e32 v103, 1.0, v116
	v_mul_f32_e32 v116, 0xbfb8aa3b, v111
	v_exp_f32_e32 v129, v129
	v_exp_f32_e32 v117, v116
	v_rcp_f32_e32 v116, v103
	v_mul_f32_e32 v106, 0xbfb8aa3b, v109
	v_add_f32_e32 v102, 1.0, v129
	v_add_f32_e32 v103, 1.0, v117
	v_rcp_f32_e32 v102, v102
	v_rcp_f32_e32 v103, v103
	v_exp_f32_e32 v106, v106
	v_pk_fma_f32 v[78:79], v[78:79], v[96:97], v[104:105]
	v_pk_mul_f32 v[102:103], v[110:111], v[102:103]
	s_nop 0
	v_pk_mul_f32 v[92:93], v[92:93], v[102:103]
	v_add_f32_e32 v102, 1.0, v106
	v_rcp_f32_e32 v117, v102
	v_pk_fma_f32 v[78:79], v[132:133], v[112:113], v[78:79]
	v_pk_mul_f32 v[96:97], v[108:109], v[116:117]
	v_pk_fma_f32 v[78:79], v[136:137], v[100:101], v[78:79]
	s_nop 0
	v_pk_mul_f32 v[78:79], v[78:79], v[96:97]
	s_nop 7
	s_nop 1
	v_cvt_pk_bf16_f32 v92, v92, v78
	v_or_b32_e32 v78, 7, v156
	v_cvt_pk_bf16_f32 v93, v93, v79
	v_mad_i64_i32 v[78:79], s[34:35], v78, s60, v[94:95]
	v_lshl_add_u64 v[78:79], v[78:79], 0, v[98:99]
	global_store_dwordx2 v[78:79], v[92:93], off
	v_mov_b32_e32 v92, v66
	v_mov_b32_e32 v93, v68
	v_pk_mul_f32 v[124:125], v[92:93], v[172:173]
	v_mov_b32_e32 v92, v54
	v_mov_b32_e32 v93, v56
	v_mov_b32_e32 v56, v55
	v_mov_b32_e32 v54, v62
	v_mov_b32_e32 v55, v64
	v_pk_mul_f32 v[116:117], v[54:55], v[70:71]
	v_mov_b32_e32 v54, v50
	v_mov_b32_e32 v55, v52
	v_mov_b32_e32 v52, v51
	v_mov_b32_e32 v50, v46
	v_mov_b32_e32 v51, v48
	v_pk_mul_f32 v[96:97], v[50:51], v[174:175]
	v_mov_b32_e32 v50, v38
	v_mov_b32_e32 v51, v40
	v_mov_b32_e32 v40, v39
	v_mov_b32_e32 v38, v42
	v_mov_b32_e32 v39, v44
	v_mov_b32_e32 v68, v67
	v_mov_b32_e32 v64, v63
	v_mov_b32_e32 v48, v47
	v_pk_mul_f32 v[100:101], v[38:39], v[60:61]
	v_mov_b32_e32 v38, v34
	v_mov_b32_e32 v39, v36
	v_mov_b32_e32 v44, v43
	v_mov_b32_e32 v36, v35
	v_pk_mul_f32 v[122:123], v[92:93], v[172:173]
	v_pk_mul_f32 v[132:133], v[68:69], v[172:173]
	v_pk_mul_f32 v[112:113], v[54:55], v[70:71]
	v_pk_mul_f32 v[114:115], v[64:65], v[70:71]
	v_pk_mul_f32 v[118:119], v[52:53], v[70:71]
	v_pk_mul_f32 v[70:71], v[50:51], v[174:175]
	v_pk_mul_f32 v[98:99], v[48:49], v[174:175]
	v_pk_mul_f32 v[68:69], v[40:41], v[174:175]
	v_pk_mul_f32 v[92:93], v[38:39], v[60:61]
	v_pk_mul_f32 v[102:103], v[44:45], v[60:61]
	v_pk_mul_f32 v[94:95], v[36:37], v[60:61]
	v_pk_mul_f32 v[120:121], v[56:57], v[172:173]
	v_mov_b64_e32 v[38:39], 0x408
	v_mov_b64_e32 v[40:41], 0x508
	v_mov_b64_e32 v[34:35], 0x608
	v_mov_b64_e32 v[36:37], 0x708
	v_mov_b64_e32 v[48:49], v[100:101]
	v_mov_b64_e32 v[46:47], v[102:103]
	v_mov_b64_e32 v[44:45], v[92:93]
	v_mov_b64_e32 v[42:43], v[94:95]
	v_mov_b64_e32 v[56:57], v[96:97]
	v_mov_b64_e32 v[54:55], v[98:99]
	v_mov_b64_e32 v[52:53], v[70:71]
	v_mov_b64_e32 v[50:51], v[68:69]
	s_and_saveexec_b64 s[34:35], vcc
	s_cbranch_execz .LBB0_5596
	v_cmp_eq_u32_e32 vcc, 0, v167
	s_mov_b64 s[36:37], 0
	v_mov_b64_e32 v[38:39], 0x408
	v_mov_b64_e32 v[40:41], 0x508
	v_mov_b64_e32 v[34:35], 0x608
	v_mov_b64_e32 v[36:37], 0x708
	s_and_saveexec_b64 s[38:39], vcc
	s_mov_b64 s[36:37], exec
	v_mov_b64_e32 v[38:39], 8
	v_mov_b64_e32 v[40:41], 0x108
	v_mov_b64_e32 v[34:35], 0x208
	v_mov_b64_e32 v[36:37], 0x308
	s_or_b64 exec, exec, s[38:39]
	s_orn2_b64 s[36:37], s[36:37], exec
	v_mov_b64_e32 v[48:49], v[116:117]
	v_mov_b64_e32 v[46:47], v[114:115]
	v_mov_b64_e32 v[44:45], v[112:113]
	v_mov_b64_e32 v[42:43], v[118:119]
	v_mov_b64_e32 v[56:57], v[124:125]
	v_mov_b64_e32 v[54:55], v[132:133]
	v_mov_b64_e32 v[52:53], v[122:123]
	v_mov_b64_e32 v[50:51], v[120:121]
.LBB0_5596:
	s_or_b64 exec, exec, s[34:35]
	s_and_saveexec_b64 s[34:35], s[36:37]
	s_cbranch_execz .LBB0_5579
	s_nop 7
	s_nop 1
	v_cvt_pk_bf16_f32 v55, v57, v55
	v_cvt_pk_bf16_f32 v54, v56, v54
	s_nop 7
	s_nop 1
	v_lshl_add_u64 v[38:39], v[130:131], 0, v[38:39]
	v_cvt_pk_bf16_f32 v51, v53, v51
	v_cvt_pk_bf16_f32 v50, v52, v50
	global_store_dwordx2 v[38:39], v[54:55], off
	v_lshl_add_u64 v[38:39], v[130:131], 0, v[40:41]
	global_store_dwordx2 v[38:39], v[50:51], off
	s_nop 7
	s_nop 1
	v_cvt_pk_bf16_f32 v39, v49, v47
	v_cvt_pk_bf16_f32 v38, v48, v46
	v_and_b32_sdwa v40, v45, v234 dst_sel:DWORD dst_unused:UNUSED_PAD src0_sel:WORD_1 src1_sel:DWORD
	s_nop 1
	v_add3_u32 v40, v45, v40, s59
	v_and_b32_sdwa v41, v43, v234 dst_sel:DWORD dst_unused:UNUSED_PAD src0_sel:WORD_1 src1_sel:DWORD
	s_nop 0
	v_add3_u32 v41, v43, v41, s59
	s_nop 0
	v_and_b32_e32 v41, 0xffff0000, v41
	s_nop 0
	v_lshl_add_u64 v[34:35], v[130:131], 0, v[34:35]
	v_or_b32_sdwa v41, v41, v40 dst_sel:DWORD dst_unused:UNUSED_PAD src0_sel:DWORD src1_sel:WORD_1
	v_cvt_pk_bf16_f32 v40, v44, v42
	global_store_dwordx2 v[34:35], v[38:39], off
	v_lshl_add_u64 v[34:35], v[130:131], 0, v[36:37]
	global_store_dwordx2 v[34:35], v[40:41], off
	s_branch .LBB0_5579

; __device__ __forceinline__ float siluf_(float x) { return x * sigmoidf_(x); }
; __device__ __forceinline__ void ffn_fixup(const Ctx& c, const bf16* HALO, const float* cw, const float* cb, bf16* ACT) {
;     ...
;         const int cg8 = it & 15, wr = (it >> 4) & 1, tile = it >> 5, pm = tile / 44, pn = tile % 44, ch0 = 128 * pn + 8 * cg8;
;         const bf16* cur = HALO + ((size_t)(tile * 2 + wr) * 4) * 256 + 8 * cg8;
;         const bool hasprev = wr == 1 || (pm & 15) != 0; const bf16* prv = wr == 1 ? HALO + ((size_t)(tile * 2) * 4 + 2) * 256 + 8 * cg8 : HALO + ((size_t)((tile - 44) * 2 + 1) * 4 + 2) * 256 + 8 * cg8;
;         const v4u z4 = (v4u){0u, 0u, 0u, 0u};
;         const v4u cg0 = *(const v4u*)cur, cv0 = *(const v4u*)(cur + 128), cg1 = *(const v4u*)(cur + 256), cv1 = *(const v4u*)(cur + 256 + 128);
;         const v4u pg2 = hasprev ? *(const v4u*)prv : z4, pv2 = hasprev ? *(const v4u*)(prv + 128) : z4, pg3 = hasprev ? *(const v4u*)(prv + 256) : z4, pv3 = hasprev ? *(const v4u*)(prv + 256 + 128) : z4;
;         float oa[8], ob[8];
; #pragma unroll
;         for (int j = 0; j < 8; ++j) { const int q = j >> 1; const bool hi = j & 1;
;             const float wg0 = cw[ch0 + j], wg1 = cw[FF2 + ch0 + j], wg2 = cw[2 * FF2 + ch0 + j], wv0 = cw[FFH + ch0 + j], wv1 = cw[FF2 + FFH + ch0 + j], wv2 = cw[2 * FF2 + FFH + ch0 + j], bg = cb[ch0 + j], bv = cb[FFH + ch0 + j];
;             const float gA2 = hi ? bfhi(pg2[q]) : bflo(pg2[q]), gA1 = hi ? bfhi(pg3[q]) : bflo(pg3[q]), gA0 = hi ? bfhi(cg0[q]) : bflo(cg0[q]), gB0 = hi ? bfhi(cg1[q]) : bflo(cg1[q]);
;             const float vA2 = hi ? bfhi(pv2[q]) : bflo(pv2[q]), vA1 = hi ? bfhi(pv3[q]) : bflo(pv3[q]), vA0 = hi ? bfhi(cv0[q]) : bflo(cv0[q]), vB0 = hi ? bfhi(cv1[q]) : bflo(cv1[q]);
;             oa[j] = siluf_(bg + wg0 * gA2 + wg1 * gA1 + wg2 * gA0) * (bv + wv0 * vA2 + wv1 * vA1 + wv2 * vA0);
;             ob[j] = siluf_(bg + wg0 * gA1 + wg1 * gA0 + wg2 * gB0) * (bv + wv0 * vA1 + wv1 * vA0 + wv2 * vB0); }
.LBB0_5658:
	s_or_b64 exec, exec, s[0:1]
	v_mul_lo_u32 v24, v22, 44
	v_sub_u32_e32 v23, v23, v24
	v_lshl_or_b32 v92, v23, 7, v26
	v_ashrrev_i32_e32 v93, 31, v92
	v_lshlrev_b64 v[24:25], 2, v[92:93]
	v_lshl_add_u64 v[40:41], s[8:9], 0, v[24:25]
	v_add_co_u32_e32 v26, vcc, s29, v40
	v_lshl_add_u64 v[30:31], s[10:11], 0, v[24:25]
	s_waitcnt lgkmcnt(0)
	global_load_dwordx4 v[46:49], v[40:41], off
	global_load_dwordx4 v[58:61], v[30:31], off
	v_addc_co_u32_e32 v27, vcc, 0, v41, vcc
	global_load_dwordx4 v[66:69], v[26:27], off
	v_add_co_u32_e32 v26, vcc, s24, v40
	s_waitcnt vmcnt(0)
	v_lshlrev_b32_e32 v113, 16, v11
	v_addc_co_u32_e32 v27, vcc, 0, v41, vcc
	global_load_dwordx4 v[74:77], v[26:27], off
	s_nop 0
	global_load_dwordx4 v[26:29], v[40:41], off offset:16
	s_nop 0
	global_load_dwordx4 v[30:33], v[30:31], off offset:16
	v_lshlrev_b32_e32 v112, 16, v10
	v_and_b32_e32 v123, 0xffff0000, v11
	v_and_b32_e32 v122, 0xffff0000, v10
	v_lshl_add_u64 v[10:11], v[24:25], 0, s[18:19]
	v_lshlrev_b32_e32 v118, 16, v14
	v_and_b32_e32 v120, 0xffff0000, v14
	v_lshlrev_b32_e32 v119, 16, v15
	v_and_b32_e32 v121, 0xffff0000, v15
	v_lshl_add_u64 v[14:15], s[8:9], 0, v[10:11]
	v_lshlrev_b32_e32 v100, 16, v18
	v_and_b32_e32 v98, 0xffff0000, v18
	v_lshlrev_b32_e32 v101, 16, v19
	v_and_b32_e32 v99, 0xffff0000, v19
	v_lshlrev_b32_e32 v116, 16, v16
	v_and_b32_e32 v104, 0xffff0000, v16
	v_lshlrev_b32_e32 v129, 16, v13
	v_lshlrev_b32_e32 v128, 16, v12
	v_lshlrev_b32_e32 v117, 16, v17
	v_and_b32_e32 v125, 0xffff0000, v13
	v_and_b32_e32 v124, 0xffff0000, v12
	v_and_b32_e32 v105, 0xffff0000, v17
	v_lshl_add_u64 v[18:19], s[10:11], 0, v[10:11]
	global_load_dwordx4 v[10:13], v[14:15], off offset:16
	global_load_dwordx4 v[50:53], v[14:15], off
	s_nop 0
	global_load_dwordx4 v[14:17], v[18:19], off offset:16
	global_load_dwordx4 v[54:57], v[18:19], off
	v_add_co_u32_e32 v18, vcc, s30, v40
	v_ashrrev_i32_e32 v23, 31, v22
	s_nop 0
	v_addc_co_u32_e32 v19, vcc, 0, v41, vcc
	global_load_dwordx4 v[62:65], v[18:19], off offset:2048
	v_add_co_u32_e32 v18, vcc, s31, v40
	v_lshlrev_b32_e32 v90, 16, v20
	s_nop 0
	v_addc_co_u32_e32 v19, vcc, 0, v41, vcc
	global_load_dwordx4 v[70:73], v[18:19], off offset:2048
	v_and_b32_e32 v88, 0xffff0000, v20
	v_lshlrev_b32_e32 v91, 16, v21
	v_and_b32_e32 v89, 0xffff0000, v21
	v_lshlrev_b64 v[106:107], 8, v[22:23]
	v_lshl_add_u64 v[18:19], v[40:41], 0, s[14:15]
	v_lshl_add_u64 v[20:21], v[40:41], 0, s[16:17]
	v_lshl_add_u64 v[22:23], v[40:41], 0, s[20:21]
	v_lshl_add_u64 v[24:25], v[40:41], 0, s[22:23]
	v_lshl_or_b32 v86, v38, 7, v106
	global_load_dwordx4 v[42:45], v[18:19], off offset:16
	global_load_dwordx4 v[38:41], v[20:21], off offset:16
	s_nop 0
	global_load_dwordx4 v[18:21], v[22:23], off offset:16
	s_nop 0
	global_load_dwordx4 v[22:25], v[24:25], off offset:16
	v_lshlrev_b32_e32 v103, 16, v79
	v_lshlrev_b32_e32 v102, 16, v78
	v_and_b32_e32 v79, 0xffff0000, v79
	v_and_b32_e32 v78, 0xffff0000, v78
	v_lshlrev_b32_e32 v94, 16, v82
	v_lshlrev_b32_e32 v95, 16, v83
	v_lshlrev_b32_e32 v97, 16, v35
	v_lshlrev_b32_e32 v96, 16, v34
	v_and_b32_e32 v35, 0xffff0000, v35
	v_and_b32_e32 v34, 0xffff0000, v34
	v_add_u32_e32 v1, s25, v1
	v_add_u32_e32 v126, s26, v126
	v_mov_b32_e32 v108, v46
	v_mov_b32_e32 v109, v48
	v_mov_b32_e32 v110, v58
	v_mov_b32_e32 v111, v60
	v_pk_fma_f32 v[130:131], v[108:109], v[112:113], v[110:111]
	v_mov_b32_e32 v112, v66
	v_mov_b32_e32 v113, v68
	v_pk_fma_f32 v[130:131], v[112:113], v[100:101], v[130:131]
	s_waitcnt vmcnt(12)
	v_mov_b32_e32 v114, v74
	v_mov_b32_e32 v115, v76
	v_pk_fma_f32 v[130:131], v[114:115], v[102:103], v[130:131]
	v_mov_b32_e32 v48, v47
	v_mul_f32_e32 v46, 0xbfb8aa3b, v130
	v_mov_b32_e32 v60, v59
	v_exp_f32_e32 v58, v46
	v_pk_fma_f32 v[46:47], v[48:49], v[122:123], v[60:61]
	v_mov_b32_e32 v68, v67
	v_pk_fma_f32 v[46:47], v[68:69], v[98:99], v[46:47]
	v_mov_b32_e32 v76, v75
	v_pk_fma_f32 v[122:123], v[76:77], v[78:79], v[46:47]
	v_mul_f32_e32 v46, 0xbfb8aa3b, v131
	v_exp_f32_e32 v59, v46
	v_mul_f32_e32 v46, 0xbfb8aa3b, v122
	v_exp_f32_e32 v132, v46
	v_and_b32_e32 v46, 0xffff0000, v82
	v_pk_add_f32 v[58:59], v[58:59], 1.0 op_sel_hi:[1,0]
	v_and_b32_e32 v47, 0xffff0000, v83
	v_div_scale_f32 v66, s[0:1], v59, v59, 1.0
	v_rcp_f32_e32 v67, v66
	v_pk_fma_f32 v[48:49], v[48:49], v[98:99], v[60:61]
	v_fma_f32 v74, -v66, v67, 1.0
	v_fmac_f32_e32 v67, v74, v67
	v_div_scale_f32 v74, vcc, 1.0, v59, 1.0
	v_mul_f32_e32 v75, v74, v67
	v_fma_f32 v82, -v66, v75, v74
	v_fmac_f32_e32 v75, v82, v67
	v_fma_f32 v66, -v66, v75, v74
	v_div_scale_f32 v74, s[0:1], v58, v58, 1.0
	v_rcp_f32_e32 v82, v74
	v_div_fmas_f32 v66, v66, v67, v75
	v_div_fixup_f32 v59, v66, v59, 1.0
	v_pk_fma_f32 v[48:49], v[68:69], v[78:79], v[48:49]
	v_fma_f32 v66, -v74, v82, 1.0
	v_fmac_f32_e32 v82, v66, v82
	v_div_scale_f32 v66, vcc, 1.0, v58, 1.0
	v_mul_f32_e32 v67, v66, v82
	v_fma_f32 v75, -v74, v67, v66
	v_fmac_f32_e32 v67, v75, v82
	v_fma_f32 v66, -v74, v67, v66
	v_div_fmas_f32 v66, v66, v82, v67
	v_div_fixup_f32 v58, v66, v58, 1.0
	s_waitcnt vmcnt(8)
	v_mov_b32_e32 v66, v50
	v_mul_f32_e32 v50, 0xbfb8aa3b, v123
	v_exp_f32_e32 v133, v50
	v_mov_b32_e32 v67, v52
	s_waitcnt vmcnt(6)
	v_mov_b32_e32 v74, v54
	v_mov_b32_e32 v75, v56
	v_pk_add_f32 v[132:133], v[132:133], 1.0 op_sel_hi:[1,0]
	v_pk_mul_f32 v[130:131], v[130:131], v[58:59]
	v_div_scale_f32 v50, s[0:1], v133, v133, 1.0
	v_rcp_f32_e32 v52, v50
	s_waitcnt vmcnt(5)
	v_mov_b32_e32 v58, v62
	v_pk_fma_f32 v[82:83], v[66:67], v[118:119], v[74:75]
	v_mov_b32_e32 v59, v64
	v_fma_f32 v54, -v50, v52, 1.0
	v_fmac_f32_e32 v52, v54, v52
	v_div_scale_f32 v54, vcc, 1.0, v133, 1.0
	v_mul_f32_e32 v56, v54, v52
	v_fma_f32 v62, -v50, v56, v54
	v_fmac_f32_e32 v56, v62, v52
	v_fma_f32 v50, -v50, v56, v54
	v_div_scale_f32 v54, s[0:1], v132, v132, 1.0
	v_rcp_f32_e32 v62, v54
	v_pk_fma_f32 v[118:119], v[58:59], v[94:95], v[82:83]
	s_waitcnt vmcnt(4)
; __device__ __forceinline__ unsigned pk2(float lo, float hi) { return f2bf(lo) | (f2bf(hi) << 16); }
; __device__ __forceinline__ float siluf_(float x) { return x * sigmoidf_(x); }
; __device__ __forceinline__ void ffn_fixup(const Ctx& c, const bf16* HALO, const float* cw, const float* cb, bf16* ACT) {
;     ...
;         for (int j = 0; j < 8; ++j) { const int q = j >> 1; const bool hi = j & 1;
;             const float wg0 = cw[ch0 + j], wg1 = cw[FF2 + ch0 + j], wg2 = cw[2 * FF2 + ch0 + j], wv0 = cw[FFH + ch0 + j], wv1 = cw[FF2 + FFH + ch0 + j], wv2 = cw[2 * FF2 + FFH + ch0 + j], bg = cb[ch0 + j], bv = cb[FFH + ch0 + j];
;             const float gA2 = hi ? bfhi(pg2[q]) : bflo(pg2[q]), gA1 = hi ? bfhi(pg3[q]) : bflo(pg3[q]), gA0 = hi ? bfhi(cg0[q]) : bflo(cg0[q]), gB0 = hi ? bfhi(cg1[q]) : bflo(cg1[q]);
;             const float vA2 = hi ? bfhi(pv2[q]) : bflo(pv2[q]), vA1 = hi ? bfhi(pv3[q]) : bflo(pv3[q]), vA0 = hi ? bfhi(cv0[q]) : bflo(cv0[q]), vB0 = hi ? bfhi(cv1[q]) : bflo(cv1[q]);
;             oa[j] = siluf_(bg + wg0 * gA2 + wg1 * gA1 + wg2 * gA0) * (bv + wv0 * vA2 + wv1 * vA1 + wv2 * vA0);
;             ob[j] = siluf_(bg + wg0 * gA1 + wg1 * gA0 + wg2 * gB0) * (bv + wv0 * vA1 + wv1 * vA0 + wv2 * vB0); }
;         const size_t tok = (size_t)256 * pm + 128 * wr;
;         v4u w; w.x = pk2(oa[0], oa[1]); w.y = pk2(oa[2], oa[3]); w.z = pk2(oa[4], oa[5]); w.w = pk2(oa[6], oa[7]); *(v4u*)(ACT + tok * FFH + ch0) = w;
;         w.x = pk2(ob[0], ob[1]); w.y = pk2(ob[2], ob[3]); w.z = pk2(ob[4], ob[5]); w.w = pk2(ob[6], ob[7]); *(v4u*)(ACT + (tok + 1) * FFH + ch0) = w;
	v_mov_b32_e32 v82, v70
	v_mov_b32_e32 v83, v72
	v_pk_fma_f32 v[118:119], v[82:83], v[96:97], v[118:119]
	v_div_fmas_f32 v50, v50, v52, v56
	v_pk_mul_f32 v[130:131], v[118:119], v[130:131]
	v_div_fixup_f32 v119, v50, v133, 1.0
	v_fma_f32 v50, -v54, v62, 1.0
	v_fmac_f32_e32 v62, v50, v62
	v_div_scale_f32 v50, vcc, 1.0, v132, 1.0
	v_mul_f32_e32 v52, v50, v62
	v_fma_f32 v56, -v54, v52, v50
	v_fmac_f32_e32 v52, v56, v62
	v_fma_f32 v50, -v54, v52, v50
	v_div_fmas_f32 v50, v50, v62, v52
	v_mov_b32_e32 v52, v51
	v_mov_b32_e32 v56, v55
	v_div_fixup_f32 v118, v50, v132, 1.0
	v_pk_fma_f32 v[50:51], v[52:53], v[120:121], v[56:57]
	v_mov_b32_e32 v64, v63
	v_pk_fma_f32 v[50:51], v[64:65], v[46:47], v[50:51]
	v_mov_b32_e32 v72, v71
	v_pk_mul_f32 v[118:119], v[122:123], v[118:119]
	v_pk_fma_f32 v[50:51], v[72:73], v[34:35], v[50:51]
	v_mov_b32_e32 v70, v26
	v_pk_mul_f32 v[132:133], v[50:51], v[118:119]
	v_mov_b32_e32 v71, v28
	v_mov_b32_e32 v118, v30
	v_mov_b32_e32 v119, v32
	v_pk_fma_f32 v[50:51], v[70:71], v[128:129], v[118:119]
	s_waitcnt vmcnt(3)
	v_mov_b32_e32 v120, v42
	v_mov_b32_e32 v121, v44
	v_lshlrev_b32_e32 v63, 16, v81
	v_lshlrev_b32_e32 v62, 16, v80
	v_pk_fma_f32 v[50:51], v[120:121], v[90:91], v[50:51]
	s_waitcnt vmcnt(2)
	v_mov_b32_e32 v122, v38
	v_mov_b32_e32 v123, v40
	v_pk_fma_f32 v[128:129], v[122:123], v[62:63], v[50:51]
	v_mov_b32_e32 v28, v27
	v_mul_f32_e32 v26, 0xbfb8aa3b, v128
	v_mov_b32_e32 v32, v31
	v_exp_f32_e32 v30, v26
	v_pk_fma_f32 v[26:27], v[28:29], v[124:125], v[32:33]
	v_mov_b32_e32 v44, v43
	v_and_b32_e32 v81, 0xffff0000, v81
	v_and_b32_e32 v80, 0xffff0000, v80
	v_pk_fma_f32 v[26:27], v[44:45], v[88:89], v[26:27]
	v_mov_b32_e32 v40, v39
	v_pk_fma_f32 v[124:125], v[40:41], v[80:81], v[26:27]
	v_mul_f32_e32 v26, 0xbfb8aa3b, v129
	v_exp_f32_e32 v31, v26
	v_lshlrev_b32_e32 v50, 16, v36
	v_lshlrev_b32_e32 v51, 16, v37
	v_mul_f32_e32 v26, 0xbfb8aa3b, v124
	v_pk_add_f32 v[38:39], v[30:31], 1.0 op_sel_hi:[1,0]
	v_and_b32_e32 v30, 0xffff0000, v36
	v_div_scale_f32 v42, s[0:1], v39, v39, 1.0
	v_rcp_f32_e32 v43, v42
	v_and_b32_e32 v31, 0xffff0000, v37
	v_lshlrev_b32_e32 v54, 16, v84
	v_exp_f32_e32 v134, v26
	v_fma_f32 v36, -v42, v43, 1.0
	v_fmac_f32_e32 v43, v36, v43
	v_div_scale_f32 v36, vcc, 1.0, v39, 1.0
	v_mul_f32_e32 v37, v36, v43
	v_and_b32_e32 v26, 0xffff0000, v84
	v_fma_f32 v84, -v42, v37, v36
	v_fmac_f32_e32 v37, v84, v43
	v_fma_f32 v36, -v42, v37, v36
	v_div_scale_f32 v42, s[0:1], v38, v38, 1.0
	v_rcp_f32_e32 v84, v42
	v_div_fmas_f32 v36, v36, v43, v37
	v_div_fixup_f32 v37, v36, v39, 1.0
	v_lshlrev_b32_e32 v55, 16, v85
	v_fma_f32 v36, -v42, v84, 1.0
	v_fmac_f32_e32 v84, v36, v84
	v_div_scale_f32 v36, vcc, 1.0, v38, 1.0
	v_mul_f32_e32 v39, v36, v84
	v_fma_f32 v43, -v42, v39, v36
	v_fmac_f32_e32 v39, v43, v84
	v_fma_f32 v36, -v42, v39, v36
	v_div_fmas_f32 v36, v36, v84, v39
	v_div_fixup_f32 v36, v36, v38, 1.0
	v_mov_b32_e32 v38, v10
	v_mul_f32_e32 v10, 0xbfb8aa3b, v125
	v_exp_f32_e32 v135, v10
	v_mov_b32_e32 v39, v12
	v_mov_b32_e32 v42, v14
	v_mov_b32_e32 v43, v16
	v_pk_add_f32 v[134:135], v[134:135], 1.0 op_sel_hi:[1,0]
	v_pk_mul_f32 v[128:129], v[128:129], v[36:37]
	v_div_scale_f32 v10, s[0:1], v135, v135, 1.0
	v_rcp_f32_e32 v12, v10
	s_waitcnt vmcnt(1)
	v_mov_b32_e32 v36, v18
	v_and_b32_e32 v27, 0xffff0000, v85
	v_pk_fma_f32 v[84:85], v[38:39], v[116:117], v[42:43]
	v_fma_f32 v14, -v10, v12, 1.0
	v_fmac_f32_e32 v12, v14, v12
	v_div_scale_f32 v14, vcc, 1.0, v135, 1.0
	v_mul_f32_e32 v16, v14, v12
	v_fma_f32 v18, -v10, v16, v14
	v_fmac_f32_e32 v16, v18, v12
	v_fma_f32 v10, -v10, v16, v14
	v_div_scale_f32 v14, s[0:1], v134, v134, 1.0
	v_rcp_f32_e32 v18, v14
	v_mov_b32_e32 v37, v20
	v_pk_fma_f32 v[116:117], v[36:37], v[54:55], v[84:85]
	s_waitcnt vmcnt(0)
	v_mov_b32_e32 v84, v22
	v_mov_b32_e32 v85, v24
	v_pk_fma_f32 v[116:117], v[84:85], v[50:51], v[116:117]
	v_div_fmas_f32 v10, v10, v12, v16
	v_pk_mul_f32 v[116:117], v[116:117], v[128:129]
	v_div_fixup_f32 v129, v10, v135, 1.0
	v_fma_f32 v10, -v14, v18, 1.0
	v_fmac_f32_e32 v18, v10, v18
	v_div_scale_f32 v10, vcc, 1.0, v134, 1.0
	v_mul_f32_e32 v12, v10, v18
	v_fma_f32 v16, -v14, v12, v10
	v_fmac_f32_e32 v12, v16, v18
	v_fma_f32 v10, -v14, v12, v10
	v_div_fmas_f32 v10, v10, v18, v12
	v_mov_b32_e32 v12, v11
	v_mov_b32_e32 v16, v15
	v_div_fixup_f32 v128, v10, v134, 1.0
	v_pk_fma_f32 v[10:11], v[12:13], v[104:105], v[16:17]
	v_mov_b32_e32 v20, v19
	v_pk_fma_f32 v[10:11], v[20:21], v[26:27], v[10:11]
	v_mov_b32_e32 v24, v23
	v_pk_mul_f32 v[124:125], v[124:125], v[128:129]
	v_pk_fma_f32 v[10:11], v[24:25], v[30:31], v[10:11]
	s_nop 0
	v_pk_mul_f32 v[10:11], v[10:11], v[124:125]
	s_nop 4
	v_bfe_u32 v18, v130, 16, 1
	v_bfe_u32 v19, v131, 16, 1
	s_nop 1
	v_bfe_u32 v14, v133, 16, 1
	v_bfe_u32 v15, v132, 16, 1
	v_add3_u32 v19, v131, v19, s34
	v_add3_u32 v18, v130, v18, s34
	s_nop 1
	v_add3_u32 v15, v132, v15, s34
	v_add3_u32 v14, v133, v14, s34
	v_lshrrev_b32_e32 v18, 16, v18
	v_lshrrev_b32_e32 v19, 16, v19
	v_cvt_pk_bf16_f32 v131, v117, v11
	v_cvt_pk_bf16_f32 v130, v116, v10
	v_pk_fma_f32 v[22:23], v[108:109], v[100:101], v[110:111]
	v_and_or_b32 v129, v14, s28, v19
	v_and_or_b32 v128, v15, s28, v18
	v_lshlrev_b32_e32 v15, 16, v7
	v_lshlrev_b32_e32 v14, 16, v6
	v_pk_fma_f32 v[22:23], v[112:113], v[102:103], v[22:23]
	v_and_b32_e32 v7, 0xffff0000, v7
	v_pk_fma_f32 v[14:15], v[114:115], v[14:15], v[22:23]
	v_and_b32_e32 v6, 0xffff0000, v6
	v_mul_f32_e32 v22, 0xbfb8aa3b, v14
	v_mul_f32_e32 v23, 0xbfb8aa3b, v15
	v_exp_f32_e32 v22, v22
	v_exp_f32_e32 v23, v23
	v_pk_fma_f32 v[6:7], v[76:77], v[6:7], v[48:49]
	v_lshlrev_b32_e32 v19, 16, v3
	v_mul_f32_e32 v48, 0xbfb8aa3b, v6
; __device__ __forceinline__ unsigned pk2(float lo, float hi) { return f2bf(lo) | (f2bf(hi) << 16); }
; __device__ __forceinline__ float siluf_(float x) { return x * sigmoidf_(x); }
; __device__ __forceinline__ void ffn_fixup(const Ctx& c, const bf16* HALO, const float* cw, const float* cb, bf16* ACT) {
;     ...
;         for (int j = 0; j < 8; ++j) { const int q = j >> 1; const bool hi = j & 1;
;             const float wg0 = cw[ch0 + j], wg1 = cw[FF2 + ch0 + j], wg2 = cw[2 * FF2 + ch0 + j], wv0 = cw[FFH + ch0 + j], wv1 = cw[FF2 + FFH + ch0 + j], wv2 = cw[2 * FF2 + FFH + ch0 + j], bg = cb[ch0 + j], bv = cb[FFH + ch0 + j];
;             const float gA2 = hi ? bfhi(pg2[q]) : bflo(pg2[q]), gA1 = hi ? bfhi(pg3[q]) : bflo(pg3[q]), gA0 = hi ? bfhi(cg0[q]) : bflo(cg0[q]), gB0 = hi ? bfhi(cg1[q]) : bflo(cg1[q]);
;             const float vA2 = hi ? bfhi(pv2[q]) : bflo(pv2[q]), vA1 = hi ? bfhi(pv3[q]) : bflo(pv3[q]), vA0 = hi ? bfhi(cv0[q]) : bflo(cv0[q]), vB0 = hi ? bfhi(cv1[q]) : bflo(cv1[q]);
;             oa[j] = siluf_(bg + wg0 * gA2 + wg1 * gA1 + wg2 * gA0) * (bv + wv0 * vA2 + wv1 * vA1 + wv2 * vA0);
;             ob[j] = siluf_(bg + wg0 * gA1 + wg1 * gA0 + wg2 * gB0) * (bv + wv0 * vA1 + wv1 * vA0 + wv2 * vB0); }
;         const size_t tok = (size_t)256 * pm + 128 * wr;
;         v4u w; w.x = pk2(oa[0], oa[1]); w.y = pk2(oa[2], oa[3]); w.z = pk2(oa[4], oa[5]); w.w = pk2(oa[6], oa[7]); *(v4u*)(ACT + tok * FFH + ch0) = w;
;         w.x = pk2(ob[0], ob[1]); w.y = pk2(ob[2], ob[3]); w.z = pk2(ob[4], ob[5]); w.w = pk2(ob[6], ob[7]); *(v4u*)(ACT + (tok + 1) * FFH + ch0) = w;
	v_pk_add_f32 v[22:23], v[22:23], 1.0 op_sel_hi:[1,0]
	v_exp_f32_e32 v48, v48
	v_div_scale_f32 v60, s[0:1], v23, v23, 1.0
	v_rcp_f32_e32 v61, v60
	v_lshlrev_b32_e32 v18, 16, v2
	v_and_b32_e32 v3, 0xffff0000, v3
	v_and_b32_e32 v2, 0xffff0000, v2
	v_fma_f32 v49, -v60, v61, 1.0
	v_fmac_f32_e32 v61, v49, v61
	v_div_scale_f32 v49, vcc, 1.0, v23, 1.0
	v_mul_f32_e32 v68, v49, v61
	v_fma_f32 v69, -v60, v68, v49
	v_fmac_f32_e32 v68, v69, v61
	v_fma_f32 v49, -v60, v68, v49
	v_div_scale_f32 v60, s[0:1], v22, v22, 1.0
	v_rcp_f32_e32 v69, v60
	v_div_fmas_f32 v49, v49, v61, v68
	v_div_fixup_f32 v23, v49, v23, 1.0
	v_pk_fma_f32 v[28:29], v[28:29], v[88:89], v[32:33]
	v_fma_f32 v49, -v60, v69, 1.0
	v_fmac_f32_e32 v69, v49, v69
	v_div_scale_f32 v49, vcc, 1.0, v22, 1.0
	v_mul_f32_e32 v61, v49, v69
	v_fma_f32 v68, -v60, v61, v49
	v_fmac_f32_e32 v61, v68, v69
	v_fma_f32 v49, -v60, v61, v49
	v_div_fmas_f32 v60, v49, v69, v61
	v_mul_f32_e32 v49, 0xbfb8aa3b, v7
	v_exp_f32_e32 v49, v49
	v_div_fixup_f32 v22, v60, v22, 1.0
	v_pk_mul_f32 v[14:15], v[14:15], v[22:23]
	v_pk_fma_f32 v[22:23], v[66:67], v[94:95], v[74:75]
	v_pk_add_f32 v[48:49], v[48:49], 1.0 op_sel_hi:[1,0]
	v_pk_fma_f32 v[22:23], v[58:59], v[96:97], v[22:23]
	v_div_scale_f32 v60, s[0:1], v49, v49, 1.0
	v_rcp_f32_e32 v61, v60
	v_pk_fma_f32 v[18:19], v[82:83], v[18:19], v[22:23]
	v_pk_fma_f32 v[28:29], v[44:45], v[80:81], v[28:29]
	v_pk_mul_f32 v[14:15], v[18:19], v[14:15]
	v_fma_f32 v18, -v60, v61, 1.0
	v_fmac_f32_e32 v61, v18, v61
	v_div_scale_f32 v18, vcc, 1.0, v49, 1.0
	v_mul_f32_e32 v19, v18, v61
	v_fma_f32 v22, -v60, v19, v18
	v_fmac_f32_e32 v19, v22, v61
	v_div_scale_f32 v22, s[0:1], v48, v48, 1.0
	v_rcp_f32_e32 v23, v22
	v_fma_f32 v18, -v60, v19, v18
	v_div_fmas_f32 v18, v18, v61, v19
	v_div_fixup_f32 v19, v18, v49, 1.0
	v_fma_f32 v18, -v22, v23, 1.0
	v_fmac_f32_e32 v23, v18, v23
	v_div_scale_f32 v18, vcc, 1.0, v48, 1.0
	v_mul_f32_e32 v49, v18, v23
	v_fma_f32 v58, -v22, v49, v18
	v_fmac_f32_e32 v49, v58, v23
	v_fma_f32 v18, -v22, v49, v18
	v_div_fmas_f32 v18, v18, v23, v49
	v_div_fixup_f32 v18, v18, v48, 1.0
	v_pk_mul_f32 v[6:7], v[6:7], v[18:19]
	v_pk_fma_f32 v[18:19], v[52:53], v[46:47], v[56:57]
	v_pk_fma_f32 v[22:23], v[70:71], v[90:91], v[118:119]
	v_pk_fma_f32 v[18:19], v[64:65], v[34:35], v[18:19]
	v_pk_fma_f32 v[22:23], v[120:121], v[62:63], v[22:23]
	v_pk_fma_f32 v[2:3], v[72:73], v[2:3], v[18:19]
	v_lshlrev_b32_e32 v19, 16, v5
	v_pk_mul_f32 v[2:3], v[2:3], v[6:7]
	v_lshlrev_b32_e32 v7, 16, v9
	v_lshlrev_b32_e32 v6, 16, v8
	v_pk_fma_f32 v[6:7], v[122:123], v[6:7], v[22:23]
	v_and_b32_e32 v9, 0xffff0000, v9
	v_mul_f32_e32 v22, 0xbfb8aa3b, v6
	v_mul_f32_e32 v23, 0xbfb8aa3b, v7
	v_exp_f32_e32 v22, v22
	v_exp_f32_e32 v23, v23
	v_and_b32_e32 v8, 0xffff0000, v8
	v_pk_fma_f32 v[8:9], v[40:41], v[8:9], v[28:29]
	v_lshlrev_b32_e32 v18, 16, v4
	v_pk_add_f32 v[22:23], v[22:23], 1.0 op_sel_hi:[1,0]
	v_mul_f32_e32 v28, 0xbfb8aa3b, v8
	v_div_scale_f32 v32, s[0:1], v23, v23, 1.0
	v_rcp_f32_e32 v33, v32
	v_exp_f32_e32 v28, v28
	v_pk_fma_f32 v[12:13], v[12:13], v[26:27], v[16:17]
	v_and_b32_e32 v5, 0xffff0000, v5
	v_fma_f32 v29, -v32, v33, 1.0
	v_fmac_f32_e32 v33, v29, v33
	v_div_scale_f32 v29, vcc, 1.0, v23, 1.0
	v_mul_f32_e32 v34, v29, v33
	v_fma_f32 v35, -v32, v34, v29
	v_fmac_f32_e32 v34, v35, v33
	v_fma_f32 v29, -v32, v34, v29
	v_div_scale_f32 v32, s[0:1], v22, v22, 1.0
	v_rcp_f32_e32 v35, v32
	v_div_fmas_f32 v29, v29, v33, v34
	v_div_fixup_f32 v23, v29, v23, 1.0
	v_and_b32_e32 v4, 0xffff0000, v4
	v_fma_f32 v29, -v32, v35, 1.0
	v_fmac_f32_e32 v35, v29, v35
	v_div_scale_f32 v29, vcc, 1.0, v22, 1.0
	v_mul_f32_e32 v33, v29, v35
	v_fma_f32 v34, -v32, v33, v29
	v_fmac_f32_e32 v33, v34, v35
	v_fma_f32 v29, -v32, v33, v29
	v_div_fmas_f32 v32, v29, v35, v33
	v_mul_f32_e32 v29, 0xbfb8aa3b, v9
	v_exp_f32_e32 v29, v29
	v_div_fixup_f32 v22, v32, v22, 1.0
	v_pk_mul_f32 v[6:7], v[6:7], v[22:23]
	v_pk_fma_f32 v[22:23], v[38:39], v[54:55], v[42:43]
	v_pk_add_f32 v[28:29], v[28:29], 1.0 op_sel_hi:[1,0]
	v_pk_fma_f32 v[22:23], v[36:37], v[50:51], v[22:23]
	v_div_scale_f32 v32, s[0:1], v29, v29, 1.0
	v_rcp_f32_e32 v33, v32
	v_pk_fma_f32 v[18:19], v[84:85], v[18:19], v[22:23]
	v_pk_fma_f32 v[12:13], v[20:21], v[30:31], v[12:13]
	v_pk_mul_f32 v[6:7], v[18:19], v[6:7]
	v_fma_f32 v18, -v32, v33, 1.0
	v_fmac_f32_e32 v33, v18, v33
	v_div_scale_f32 v18, vcc, 1.0, v29, 1.0
	v_mul_f32_e32 v19, v18, v33
	v_fma_f32 v22, -v32, v19, v18
	v_fmac_f32_e32 v19, v22, v33
	v_div_scale_f32 v22, s[0:1], v28, v28, 1.0
	v_rcp_f32_e32 v23, v22
	v_fma_f32 v18, -v32, v19, v18
	v_div_fmas_f32 v18, v18, v33, v19
	v_div_fixup_f32 v19, v18, v29, 1.0
	v_fma_f32 v18, -v22, v23, 1.0
	v_fmac_f32_e32 v23, v18, v23
	v_div_scale_f32 v18, vcc, 1.0, v28, 1.0
	v_mul_f32_e32 v29, v18, v23
	v_fma_f32 v32, -v22, v29, v18
	v_fmac_f32_e32 v29, v32, v23
	v_fma_f32 v18, -v22, v29, v18
	v_div_fmas_f32 v18, v18, v23, v29
	v_div_fixup_f32 v18, v18, v28, 1.0
	v_pk_mul_f32 v[8:9], v[8:9], v[18:19]
	v_pk_fma_f32 v[4:5], v[24:25], v[4:5], v[12:13]
	v_mov_b64_e32 v[10:11], s[78:79]
	v_pk_mul_f32 v[4:5], v[4:5], v[8:9]
	v_mad_u64_u32 v[10:11], s[0:1], v86, s35, v[10:11]
	s_nop 3
	v_mad_i32_i24 v11, v107, s35, v11
	s_nop 2
	v_lshl_add_u64 v[10:11], v[92:93], 1, v[10:11]
	s_nop 7
	s_nop 0
	v_cvt_pk_bf16_f32 v4, v6, v4
	v_add_co_u32_e32 v6, vcc, 0x2000, v10
	s_nop 1
	v_cvt_pk_bf16_f32 v5, v7, v5
	v_addc_co_u32_e32 v7, vcc, 0, v11, vcc
	s_nop 1
	v_cmp_lt_i32_e32 vcc, s36, v1
	v_cvt_pk_bf16_f32 v3, v15, v3
	v_cvt_pk_bf16_f32 v2, v14, v2
	s_or_b64 s[12:13], vcc, s[12:13]
	global_store_dwordx4 v[10:11], v[128:131], off
	global_store_dwordx4 v[6:7], v[2:5], off offset:3072
	s_andn2_b64 exec, exec, s[12:13]
	s_cbranch_execz .LBB0_5667

; __device__ __forceinline__ unsigned pk2(float lo, float hi) { return f2bf(lo) | (f2bf(hi) << 16); }
; __device__ __forceinline__ void postnorm(const Ctx& c, const bf16* MF, bf16* XB, float* RS, const float* gpost, float* OUT) {
;     ...
;         for (int j = 0; j < 4; ++j) { const float* gp = gpost + (c.lane + 64 * j) * 8; const f32x4 g0 = *(CF4)gp, g1 = *(CF4)(gp + 4);
; #pragma unroll
;             for (int k = 0; k < 4; ++k) { const float ga = (k < 2) ? g0[2 * k] : g1[2 * k - 4], gb = (k < 2) ? g0[2 * k + 1] : g1[2 * k - 3];
;                 v[j][2 * k] = bflo(xv[j][k]) + v[j][2 * k] * rs * ga; v[j][2 * k + 1] = bfhi(xv[j][k]) + v[j][2 * k + 1] * rs * gb;
;                 s2 += v[j][2 * k] * v[j][2 * k] + v[j][2 * k + 1] * v[j][2 * k + 1]; } }
;         if (OUT) {
; #pragma unroll
;             for (int j = 0; j < 4; ++j) { float* op = OUT + (size_t)row * DM + (c.lane + 64 * j) * 8; *(f32x4*)op = (f32x4){v[j][0], v[j][1], v[j][2], v[j][3]}; *(f32x4*)(op + 4) = (f32x4){v[j][4], v[j][5], v[j][6], v[j][7]}; }
;         } else {
; #pragma unroll
;             for (int j = 0; j < 4; ++j) { v4u o; o.x = pk2(v[j][0], v[j][1]); o.y = pk2(v[j][2], v[j][3]); o.z = pk2(v[j][4], v[j][5]); o.w = pk2(v[j][6], v[j][7]); xr[64 * j] = o; }
;             const float rs2 = rsqrtf(wave_sum(s2) * (1.f / DM) + EPS); if (c.lane == 0) RS[row] = rs2;
.LBB0_5807:
.LBB0_5808:
	v_lshl_add_u64 v[78:79], v[40:41], 0, s[10:11]
	v_lshl_add_u64 v[80:81], v[40:41], 0, s[12:13]
	v_lshl_add_u64 v[82:83], v[40:41], 0, s[14:15]
	v_lshl_add_u64 v[84:85], v[40:41], 0, s[16:17]
	v_pk_mul_f32 v[40:41], v[66:67], v[66:67]
	v_pk_mul_f32 v[86:87], v[68:69], v[68:69]
	v_pk_fma_f32 v[40:41], v[62:63], v[62:63], v[40:41]
	v_pk_fma_f32 v[86:87], v[64:65], v[64:65], v[86:87]
	v_add_f32_e32 v40, v40, v41
	v_add_f32_e32 v40, v86, v40
	v_add_f32_e32 v40, v87, v40
	v_bfe_u32 v41, v69, 16, 1
	s_nop 2
	v_pk_mul_f32 v[88:89], v[58:59], v[58:59]
	s_nop 2
	v_add3_u32 v41, v69, v41, s24
	s_nop 2
	v_bfe_u32 v87, v65, 16, 1
	v_pk_fma_f32 v[88:89], v[54:55], v[54:55], v[88:89]
	v_add3_u32 v65, v65, v87, s24
	s_nop 2
	v_pk_mul_f32 v[90:91], v[60:61], v[60:61]
	v_add_f32_e32 v40, v88, v40
	s_nop 2
	v_lshrrev_b32_e32 v65, 16, v65
	v_pk_fma_f32 v[90:91], v[56:57], v[56:57], v[90:91]
	v_add_f32_e32 v40, v89, v40
	v_and_or_b32 v65, v41, s22, v65
	v_cvt_pk_bf16_f32 v64, v64, v68
	v_cvt_pk_bf16_f32 v63, v63, v67
	v_cvt_pk_bf16_f32 v62, v62, v66
	v_pk_mul_f32 v[92:93], v[50:51], v[50:51]
	v_add_f32_e32 v40, v90, v40
	global_store_dwordx4 v[78:79], v[62:65], off
	v_bfe_u32 v41, v61, 16, 1
	v_pk_fma_f32 v[92:93], v[46:47], v[46:47], v[92:93]
	s_nop 2
	v_add_f32_e32 v40, v91, v40
	s_nop 2
	v_add3_u32 v41, v61, v41, s24
	s_nop 2
	v_bfe_u32 v64, v57, 16, 1
	v_pk_mul_f32 v[94:95], v[52:53], v[52:53]
	v_add_f32_e32 v40, v92, v40
	v_add3_u32 v57, v57, v64, s24
	s_nop 2
	v_pk_fma_f32 v[94:95], v[48:49], v[48:49], v[94:95]
	v_add_f32_e32 v40, v93, v40
	s_nop 2
	v_lshrrev_b32_e32 v57, 16, v57
	v_pk_mul_f32 v[96:97], v[42:43], v[42:43]
	v_add_f32_e32 v40, v94, v40
	v_and_or_b32 v57, v41, s22, v57
	v_cvt_pk_bf16_f32 v56, v56, v60
	v_cvt_pk_bf16_f32 v55, v55, v59
	v_cvt_pk_bf16_f32 v54, v54, v58
	v_pk_fma_f32 v[96:97], v[30:31], v[30:31], v[96:97]
	v_add_f32_e32 v40, v95, v40
	global_store_dwordx4 v[80:81], v[54:57], off
	v_bfe_u32 v41, v53, 16, 1
	v_pk_mul_f32 v[98:99], v[44:45], v[44:45]
	s_nop 2
	v_add_f32_e32 v40, v96, v40
	s_nop 2
	v_add3_u32 v41, v53, v41, s24
	s_nop 2
	v_bfe_u32 v56, v49, 16, 1
	v_pk_fma_f32 v[98:99], v[32:33], v[32:33], v[98:99]
	v_add_f32_e32 v40, v97, v40
	v_add3_u32 v49, v49, v56, s24
	s_nop 2
	v_add_f32_e32 v40, v98, v40
	s_nop 2
	v_lshrrev_b32_e32 v49, 16, v49
	v_add_f32_e32 v40, v99, v40
	v_and_or_b32 v49, v41, s22, v49
	v_cvt_pk_bf16_f32 v48, v48, v52
	v_cvt_pk_bf16_f32 v47, v47, v51
	v_cvt_pk_bf16_f32 v46, v46, v50
	global_store_dwordx4 v[82:83], v[46:49], off
	ds_bpermute_b32 v46, v70, v40
	v_bfe_u32 v41, v45, 16, 1
	v_bfe_u32 v49, v42, 16, 1
	v_add3_u32 v49, v42, v49, s24
	v_bfe_u32 v48, v43, 16, 1
	s_waitcnt lgkmcnt(0)
	v_add_f32_e32 v40, v40, v46
	ds_bpermute_b32 v42, v71, v40
	v_add3_u32 v46, v43, v48, s24
	v_bfe_u32 v43, v30, 16, 1
	v_add3_u32 v41, v45, v41, s24
	v_bfe_u32 v45, v31, 16, 1
	s_waitcnt lgkmcnt(0)
	v_add_f32_e32 v40, v40, v42
	ds_bpermute_b32 v42, v72, v40
	v_add3_u32 v30, v30, v43, s24
	v_add3_u32 v31, v31, v45, s24
	v_lshrrev_b32_e32 v45, 16, v30
	s_nop 0
	s_waitcnt lgkmcnt(0)
	v_add_f32_e32 v40, v40, v42
	ds_bpermute_b32 v42, v73, v40
	v_bfe_u32 v48, v33, 16, 1
	s_nop 1
	v_add3_u32 v33, v33, v48, s24
	s_waitcnt lgkmcnt(0)
	v_add_f32_e32 v30, v40, v42
	ds_bpermute_b32 v40, v74, v30
	s_nop 0
	v_lshrrev_b32_e32 v47, 16, v31
	v_lshrrev_b32_e32 v31, 16, v33
	v_and_or_b32 v43, v41, s22, v31
	s_waitcnt lgkmcnt(0)
	v_add_f32_e32 v30, v30, v40
	ds_bpermute_b32 v31, v75, v30
	s_nop 0
	v_cvt_pk_bf16_f32 v42, v32, v44
	v_and_or_b32 v41, v46, s22, v47
	v_and_or_b32 v40, v49, s22, v45
	global_store_dwordx4 v[84:85], v[40:43], off
	s_and_saveexec_b64 s[18:19], s[0:1]
	s_cbranch_execz .LBB0_5803
	s_waitcnt lgkmcnt(0)
	v_add_f32_e32 v30, v30, v31
	v_fmamk_f32 v30, v30, 0x3a000000, v76
	v_mul_f32_e32 v31, 0x4b800000, v30
	v_cmp_gt_f32_e32 vcc, s23, v30
	v_readlane_b32 s26, v253, 0
	v_readlane_b32 s27, v253, 1
	v_cndmask_b32_e32 v30, v30, v31, vcc
	v_rsq_f32_e32 v30, v30
	s_add_u32 s26, s26, s20
	s_addc_u32 s27, s27, s21
	v_mul_f32_e32 v31, 0x45800000, v30
	v_cndmask_b32_e32 v30, v30, v31, vcc
	global_store_dword v251, v30, s[26:27]
	s_branch .LBB0_5803
